# write-through (sc1) cache policy on all dwordx2/dwordx4 global stores so the grid barrier's L2 write-back has little left to flush
# speedup vs baseline: 1.0875x; 1.0065x over previous
.LBB0_7:
	s_or_b64 exec, exec, s[8:9]
	s_waitcnt vmcnt(0)
	ds_write2_b32 v40, v2, v3 offset1:1
	ds_write2_b32 v40, v4, v5 offset0:2 offset1:3
	v_add_u32_e32 v2, 0x420, v40
	ds_write2_b32 v2, v10, v11 offset1:1
	v_add_u32_e32 v2, 0x428, v40
	ds_write2_b32 v2, v12, v13 offset1:1
	v_add_u32_e32 v2, 0x840, v40
	ds_write2_b32 v2, v6, v7 offset1:1
	v_add_u32_e32 v2, 0x848, v40
	ds_write2_b32 v2, v8, v9 offset1:1
	v_add_u32_e32 v2, 0xc60, v40
	ds_write2_b32 v2, v18, v19 offset1:1
	v_add_u32_e32 v2, 0xc68, v40
	ds_write2_b32 v2, v20, v21 offset1:1
	v_add_u32_e32 v2, 0x1080, v40
	ds_write2_b32 v2, v14, v15 offset1:1
	v_add_u32_e32 v2, 0x1088, v40
	ds_write2_b32 v2, v16, v17 offset1:1
	v_add_u32_e32 v2, 0x14a0, v40
	ds_write2_b32 v2, v26, v27 offset1:1
	v_add_u32_e32 v2, 0x14a8, v40
	ds_write2_b32 v2, v28, v29 offset1:1
	v_add_u32_e32 v2, 0x18c0, v40
	ds_write2_b32 v2, v22, v23 offset1:1
	v_add_u32_e32 v2, 0x18c8, v40
	ds_write2_b32 v2, v24, v25 offset1:1
	v_add_u32_e32 v2, 0x1ce0, v40
	ds_write2_b32 v2, v30, v31 offset1:1
	v_add_u32_e32 v2, 0x1ce8, v40
	ds_write2_b32 v2, v32, v33 offset1:1
	s_waitcnt lgkmcnt(0)
	ds_read2_b32 v[6:7], v39 offset0:33 offset1:41
	ds_read2_b32 v[8:9], v39 offset1:8
	ds_read2_b32 v[10:11], v39 offset0:66 offset1:74
	ds_read2_b32 v[12:13], v39 offset0:99 offset1:107
	ds_read2_b32 v[14:15], v39 offset0:132 offset1:140
	ds_read2_b32 v[16:17], v39 offset0:165 offset1:173
	ds_read2_b32 v[18:19], v39 offset0:198 offset1:206
	ds_read2_b32 v[20:21], v39 offset0:231 offset1:239
	v_add_u32_e32 v24, s11, v38
	s_ashr_i32 s7, s6, 31
	v_ashrrev_i32_e32 v25, 31, v24
	v_lshl_add_u64 v[22:23], s[6:7], 1, v[34:35]
	v_lshlrev_b64 v[26:27], 11, v[24:25]
	s_waitcnt lgkmcnt(6)
	v_cvt_pk_bf16_f32 v2, v8, v6
	s_waitcnt lgkmcnt(4)
	v_cvt_pk_bf16_f32 v3, v10, v12
	s_waitcnt lgkmcnt(2)
	v_cvt_pk_bf16_f32 v4, v14, v16
	s_waitcnt lgkmcnt(0)
	v_cvt_pk_bf16_f32 v5, v18, v20
	v_lshl_add_u64 v[26:27], v[22:23], 0, v[26:27]
	v_add_u32_e32 v6, 8, v24
	global_store_dwordx4 v[26:27], v[2:5], off sc1
	s_add_i32 s0, s0, s34
	s_add_i32 s1, s1, s2
	v_cvt_pk_bf16_f32 v2, v9, v7
	v_ashrrev_i32_e32 v7, 31, v6
	v_cvt_pk_bf16_f32 v3, v11, v13
	v_cvt_pk_bf16_f32 v4, v15, v17
	v_cvt_pk_bf16_f32 v5, v19, v21
	v_lshlrev_b64 v[6:7], 11, v[6:7]
	ds_read2_b32 v[8:9], v39 offset0:49 offset1:57
	ds_read2_b32 v[10:11], v39 offset0:16 offset1:24
	ds_read2_b32 v[12:13], v39 offset0:82 offset1:90
	ds_read2_b32 v[14:15], v39 offset0:115 offset1:123
	ds_read2_b32 v[16:17], v39 offset0:148 offset1:156
	ds_read2_b32 v[18:19], v39 offset0:181 offset1:189
	ds_read2_b32 v[20:21], v39 offset0:214 offset1:222
	ds_read2_b32 v[26:27], v39 offset0:247 offset1:255
	v_lshl_add_u64 v[6:7], v[22:23], 0, v[6:7]
	global_store_dwordx4 v[6:7], v[2:5], off sc1
	v_add_u32_e32 v6, 16, v24
	v_ashrrev_i32_e32 v7, 31, v6
	v_lshlrev_b64 v[6:7], 11, v[6:7]
	s_waitcnt lgkmcnt(6)
	v_cvt_pk_bf16_f32 v2, v10, v8
	s_waitcnt lgkmcnt(4)
	v_cvt_pk_bf16_f32 v3, v12, v14
	s_waitcnt lgkmcnt(2)
	v_cvt_pk_bf16_f32 v4, v16, v18
	s_waitcnt lgkmcnt(0)
	v_cvt_pk_bf16_f32 v5, v20, v26
	v_lshl_add_u64 v[6:7], v[22:23], 0, v[6:7]
	global_store_dwordx4 v[6:7], v[2:5], off sc1
	v_add_u32_e32 v6, 24, v24
	v_ashrrev_i32_e32 v7, 31, v6
	v_lshlrev_b64 v[6:7], 11, v[6:7]
	v_cvt_pk_bf16_f32 v2, v11, v9
	v_cvt_pk_bf16_f32 v3, v13, v15
	v_cvt_pk_bf16_f32 v4, v17, v19
	v_cvt_pk_bf16_f32 v5, v21, v27
	v_lshl_add_u64 v[6:7], v[22:23], 0, v[6:7]
	global_store_dwordx4 v[6:7], v[2:5], off sc1
	s_waitcnt lgkmcnt(0)
	s_cmpk_lt_i32 s0, 0x600
	s_cbranch_scc0 .LBB0_24

.LBB0_26:
	s_or_b64 exec, exec, s[8:9]
	s_waitcnt vmcnt(0)
	ds_write2_b32 v44, v2, v3 offset1:1
	ds_write2_b32 v44, v4, v5 offset0:2 offset1:3
	v_add_u32_e32 v2, 0x420, v44
	ds_write2_b32 v2, v10, v11 offset1:1
	v_add_u32_e32 v2, 0x428, v44
	ds_write2_b32 v2, v12, v13 offset1:1
	v_add_u32_e32 v2, 0x840, v44
	ds_write2_b32 v2, v6, v7 offset1:1
	v_add_u32_e32 v2, 0x848, v44
	ds_write2_b32 v2, v8, v9 offset1:1
	v_add_u32_e32 v2, 0xc60, v44
	ds_write2_b32 v2, v18, v19 offset1:1
	v_add_u32_e32 v2, 0xc68, v44
	ds_write2_b32 v2, v20, v21 offset1:1
	v_add_u32_e32 v2, 0x1080, v44
	ds_write2_b32 v2, v14, v15 offset1:1
	v_add_u32_e32 v2, 0x1088, v44
	ds_write2_b32 v2, v16, v17 offset1:1
	v_add_u32_e32 v2, 0x14a0, v44
	ds_write2_b32 v2, v26, v27 offset1:1
	v_add_u32_e32 v2, 0x14a8, v44
	ds_write2_b32 v2, v28, v29 offset1:1
	v_add_u32_e32 v2, 0x18c0, v44
	ds_write2_b32 v2, v22, v23 offset1:1
	v_add_u32_e32 v2, 0x18c8, v44
	ds_write2_b32 v2, v24, v25 offset1:1
	v_add_u32_e32 v2, 0x1ce0, v44
	ds_write2_b32 v2, v30, v31 offset1:1
	v_add_u32_e32 v2, 0x1ce8, v44
	ds_write2_b32 v2, v32, v33 offset1:1
	s_waitcnt lgkmcnt(0)
	s_sub_i32 s3, 0, s3
	ds_read2_b32 v[6:7], v43 offset0:33 offset1:41
	ds_read2_b32 v[8:9], v43 offset1:8
	ds_read2_b32 v[10:11], v43 offset0:66 offset1:74
	ds_read2_b32 v[12:13], v43 offset0:99 offset1:107
	ds_read2_b32 v[14:15], v43 offset0:132 offset1:140
	ds_read2_b32 v[16:17], v43 offset0:165 offset1:173
	ds_read2_b32 v[18:19], v43 offset0:198 offset1:206
	ds_read2_b32 v[20:21], v43 offset0:231 offset1:239
	s_add_i32 s3, s3, s1
	v_add_u32_e32 v26, s3, v42
	s_ashr_i32 s7, s6, 31
	v_add_u32_e32 v34, 0xc00, v26
	v_lshl_add_u64 v[22:23], s[6:7], 1, v[36:37]
	v_lshlrev_b64 v[24:25], 11, v[34:35]
	s_waitcnt lgkmcnt(6)
	v_cvt_pk_bf16_f32 v2, v8, v6
	s_waitcnt lgkmcnt(4)
	v_cvt_pk_bf16_f32 v3, v10, v12
	s_waitcnt lgkmcnt(2)
	v_cvt_pk_bf16_f32 v4, v14, v16
	s_waitcnt lgkmcnt(0)
	v_cvt_pk_bf16_f32 v5, v18, v20
	v_lshl_add_u64 v[24:25], v[22:23], 0, v[24:25]
	global_store_dwordx4 v[24:25], v[2:5], off sc1
	v_add_u32_e32 v34, 0xc08, v26
	s_add_i32 s0, s0, s34
	v_cvt_pk_bf16_f32 v2, v9, v7
	v_cvt_pk_bf16_f32 v3, v11, v13
	v_cvt_pk_bf16_f32 v4, v15, v17
	v_cvt_pk_bf16_f32 v5, v19, v21
	ds_read2_b32 v[8:9], v43 offset0:49 offset1:57
	ds_read2_b32 v[10:11], v43 offset0:16 offset1:24
	ds_read2_b32 v[12:13], v43 offset0:82 offset1:90
	ds_read2_b32 v[14:15], v43 offset0:115 offset1:123
	ds_read2_b32 v[16:17], v43 offset0:148 offset1:156
	ds_read2_b32 v[18:19], v43 offset0:181 offset1:189
	ds_read2_b32 v[20:21], v43 offset0:214 offset1:222
	ds_read2_b32 v[24:25], v43 offset0:247 offset1:255
	v_lshlrev_b64 v[6:7], 11, v[34:35]
	v_lshl_add_u64 v[6:7], v[22:23], 0, v[6:7]
	v_add_u32_e32 v34, 0xc10, v26
	global_store_dwordx4 v[6:7], v[2:5], off sc1
	v_lshlrev_b64 v[6:7], 11, v[34:35]
	v_lshl_add_u64 v[6:7], v[22:23], 0, v[6:7]
	s_waitcnt lgkmcnt(6)
	v_cvt_pk_bf16_f32 v2, v10, v8
	s_waitcnt lgkmcnt(4)
	v_cvt_pk_bf16_f32 v3, v12, v14
	s_waitcnt lgkmcnt(2)
	v_cvt_pk_bf16_f32 v4, v16, v18
	s_waitcnt lgkmcnt(0)
	v_cvt_pk_bf16_f32 v5, v20, v24
	v_add_u32_e32 v34, 0xc18, v26
	global_store_dwordx4 v[6:7], v[2:5], off sc1
	v_lshlrev_b64 v[6:7], 11, v[34:35]
	v_lshl_add_u64 v[6:7], v[22:23], 0, v[6:7]
	v_cvt_pk_bf16_f32 v2, v11, v9
	v_cvt_pk_bf16_f32 v3, v13, v15
	v_cvt_pk_bf16_f32 v4, v17, v19
	v_cvt_pk_bf16_f32 v5, v21, v25
	global_store_dwordx4 v[6:7], v[2:5], off sc1
	s_waitcnt lgkmcnt(0)
	s_add_i32 s1, s1, s2
	s_cmpk_lt_i32 s0, 0x80
	s_cbranch_scc0 .LBB0_43

.LBB0_45:
	s_or_b64 exec, exec, s[8:9]
	s_waitcnt vmcnt(0)
	ds_write2_b32 v42, v2, v3 offset1:1
	ds_write2_b32 v42, v4, v5 offset0:2 offset1:3
	v_add_u32_e32 v2, 0x420, v42
	ds_write2_b32 v2, v10, v11 offset1:1
	v_add_u32_e32 v2, 0x428, v42
	ds_write2_b32 v2, v12, v13 offset1:1
	v_add_u32_e32 v2, 0x840, v42
	ds_write2_b32 v2, v6, v7 offset1:1
	v_add_u32_e32 v2, 0x848, v42
	ds_write2_b32 v2, v8, v9 offset1:1
	v_add_u32_e32 v2, 0xc60, v42
	ds_write2_b32 v2, v18, v19 offset1:1
	v_add_u32_e32 v2, 0xc68, v42
	ds_write2_b32 v2, v20, v21 offset1:1
	v_add_u32_e32 v2, 0x1080, v42
	ds_write2_b32 v2, v14, v15 offset1:1
	v_add_u32_e32 v2, 0x1088, v42
	ds_write2_b32 v2, v16, v17 offset1:1
	v_add_u32_e32 v2, 0x14a0, v42
	ds_write2_b32 v2, v26, v27 offset1:1
	v_add_u32_e32 v2, 0x14a8, v42
	ds_write2_b32 v2, v28, v29 offset1:1
	v_add_u32_e32 v2, 0x18c0, v42
	ds_write2_b32 v2, v22, v23 offset1:1
	v_add_u32_e32 v2, 0x18c8, v42
	ds_write2_b32 v2, v24, v25 offset1:1
	v_add_u32_e32 v2, 0x1ce0, v42
	ds_write2_b32 v2, v30, v31 offset1:1
	v_add_u32_e32 v2, 0x1ce8, v42
	ds_write2_b32 v2, v32, v33 offset1:1
	s_waitcnt lgkmcnt(0)
	s_sub_i32 s8, 0, s7
	ds_read2_b32 v[6:7], v41 offset0:33 offset1:41
	ds_read2_b32 v[8:9], v41 offset1:8
	ds_read2_b32 v[10:11], v41 offset0:66 offset1:74
	ds_read2_b32 v[12:13], v41 offset0:99 offset1:107
	ds_read2_b32 v[14:15], v41 offset0:132 offset1:140
	ds_read2_b32 v[16:17], v41 offset0:165 offset1:173
	ds_read2_b32 v[18:19], v41 offset0:198 offset1:206
	ds_read2_b32 v[20:21], v41 offset0:231 offset1:239
	s_add_i32 s8, s8, s1
	v_add_u32_e32 v24, s8, v40
	s_ashr_i32 s7, s6, 31
	v_ashrrev_i32_e32 v25, 31, v24
	v_lshl_add_u64 v[22:23], s[6:7], 1, v[34:35]
	v_lshlrev_b64 v[26:27], 11, v[24:25]
	s_waitcnt lgkmcnt(6)
	v_cvt_pk_bf16_f32 v2, v8, v6
	s_waitcnt lgkmcnt(4)
	v_cvt_pk_bf16_f32 v3, v10, v12
	s_waitcnt lgkmcnt(2)
	v_cvt_pk_bf16_f32 v4, v14, v16
	s_waitcnt lgkmcnt(0)
	v_cvt_pk_bf16_f32 v5, v18, v20
	v_lshl_add_u64 v[26:27], v[22:23], 0, v[26:27]
	v_add_u32_e32 v6, 8, v24
	global_store_dwordx4 v[26:27], v[2:5], off sc1
	s_add_i32 s0, s0, s34
	s_add_i32 s1, s1, s2
	v_cvt_pk_bf16_f32 v2, v9, v7
	v_ashrrev_i32_e32 v7, 31, v6
	v_cvt_pk_bf16_f32 v3, v11, v13
	v_cvt_pk_bf16_f32 v4, v15, v17
	v_cvt_pk_bf16_f32 v5, v19, v21
	v_lshlrev_b64 v[6:7], 11, v[6:7]
	ds_read2_b32 v[8:9], v41 offset0:49 offset1:57
	ds_read2_b32 v[10:11], v41 offset0:16 offset1:24
	ds_read2_b32 v[12:13], v41 offset0:82 offset1:90
	ds_read2_b32 v[14:15], v41 offset0:115 offset1:123
	ds_read2_b32 v[16:17], v41 offset0:148 offset1:156
	ds_read2_b32 v[18:19], v41 offset0:181 offset1:189
	ds_read2_b32 v[20:21], v41 offset0:214 offset1:222
	ds_read2_b32 v[26:27], v41 offset0:247 offset1:255
	v_lshl_add_u64 v[6:7], v[22:23], 0, v[6:7]
	global_store_dwordx4 v[6:7], v[2:5], off sc1
	v_add_u32_e32 v6, 16, v24
	v_ashrrev_i32_e32 v7, 31, v6
	v_lshlrev_b64 v[6:7], 11, v[6:7]
	s_waitcnt lgkmcnt(6)
	v_cvt_pk_bf16_f32 v2, v10, v8
	s_waitcnt lgkmcnt(4)
	v_cvt_pk_bf16_f32 v3, v12, v14
	s_waitcnt lgkmcnt(2)
	v_cvt_pk_bf16_f32 v4, v16, v18
	s_waitcnt lgkmcnt(0)
	v_cvt_pk_bf16_f32 v5, v20, v26
	v_lshl_add_u64 v[6:7], v[22:23], 0, v[6:7]
	global_store_dwordx4 v[6:7], v[2:5], off sc1
	v_add_u32_e32 v6, 24, v24
	v_ashrrev_i32_e32 v7, 31, v6
	v_lshlrev_b64 v[6:7], 11, v[6:7]
	v_cvt_pk_bf16_f32 v2, v11, v9
	v_cvt_pk_bf16_f32 v3, v13, v15
	v_cvt_pk_bf16_f32 v4, v17, v19
	v_cvt_pk_bf16_f32 v5, v21, v27
	v_lshl_add_u64 v[6:7], v[22:23], 0, v[6:7]
	global_store_dwordx4 v[6:7], v[2:5], off sc1
	s_waitcnt lgkmcnt(0)
	s_cmpk_lt_i32 s0, 0x200
	s_cbranch_scc0 .LBB0_62

.LBB0_77:
	v_mul_f32_e32 v61, v31, v31
	v_mul_f32_e32 v62, v33, v33
	v_fmac_f32_e32 v61, v30, v30
	v_fmac_f32_e32 v62, v32, v32
	v_add_f32_e32 v61, v61, v62
	v_mul_f32_e32 v62, v27, v27
	v_mul_f32_e32 v63, v29, v29
	v_fmac_f32_e32 v62, v26, v26
	v_fmac_f32_e32 v63, v28, v28
	v_add_f32_e32 v62, v62, v63
	v_add_f32_e32 v61, v61, v62
	v_mul_f32_e32 v62, v23, v23
	v_mul_f32_e32 v63, v25, v25
	v_fmac_f32_e32 v62, v22, v22
	v_fmac_f32_e32 v63, v24, v24
	v_add_f32_e32 v62, v62, v63
	v_add_f32_e32 v61, v62, v61
	v_mul_f32_e32 v62, v19, v19
	v_mul_f32_e32 v63, v21, v21
	v_fmac_f32_e32 v62, v18, v18
	v_fmac_f32_e32 v63, v20, v20
	v_add_f32_e32 v62, v62, v63
	v_add_f32_e32 v61, v62, v61
	ds_bpermute_b32 v62, v54, v61
	v_lshl_add_u64 v[52:53], v[52:53], 0, s[8:9]
	s_waitcnt lgkmcnt(0)
	v_add_f32_e32 v61, v61, v62
	ds_bpermute_b32 v62, v55, v61
	s_waitcnt lgkmcnt(0)
	v_add_f32_e32 v61, v61, v62
	ds_bpermute_b32 v62, v56, v61
	s_waitcnt lgkmcnt(0)
	v_add_f32_e32 v61, v61, v62
	ds_bpermute_b32 v62, v57, v61
	s_waitcnt lgkmcnt(0)
	v_add_f32_e32 v61, v61, v62
	ds_bpermute_b32 v62, v58, v61
	s_waitcnt lgkmcnt(0)
	v_add_f32_e32 v61, v61, v62
	ds_bpermute_b32 v62, v59, v61
	s_waitcnt lgkmcnt(0)
	v_add_f32_e32 v61, v61, v62
	v_fmamk_f32 v61, v61, 0x3a800000, v60
	v_mul_f32_e32 v62, 0x4b800000, v61
	v_cmp_gt_f32_e32 vcc, s0, v61
	s_nop 1
	v_cndmask_b32_e32 v61, v61, v62, vcc
	v_rsq_f32_e32 v61, v61
	s_nop 0
	v_mul_f32_e32 v62, 0x45800000, v61
	v_cndmask_b32_e32 v62, v61, v62, vcc
	v_pk_mul_f32 v[30:31], v[30:31], v[62:63] op_sel_hi:[1,0]
	v_pk_mul_f32 v[32:33], v[32:33], v[62:63] op_sel_hi:[1,0]
	v_pk_mul_f32 v[26:27], v[26:27], v[62:63] op_sel_hi:[1,0]
	v_pk_mul_f32 v[28:29], v[28:29], v[62:63] op_sel_hi:[1,0]
	v_pk_mul_f32 v[22:23], v[22:23], v[62:63] op_sel_hi:[1,0]
	v_pk_mul_f32 v[24:25], v[24:25], v[62:63] op_sel_hi:[1,0]
	v_pk_mul_f32 v[18:19], v[18:19], v[62:63] op_sel_hi:[1,0]
	v_pk_mul_f32 v[20:21], v[20:21], v[62:63] op_sel_hi:[1,0]
	v_pk_mul_f32 v[32:33], v[4:5], v[32:33]
	v_pk_mul_f32 v[30:31], v[2:3], v[30:31]
	v_pk_mul_f32 v[28:29], v[8:9], v[28:29]
	v_pk_mul_f32 v[26:27], v[6:7], v[26:27]
	v_pk_mul_f32 v[24:25], v[12:13], v[24:25]
	v_pk_mul_f32 v[22:23], v[10:11], v[22:23]
	v_pk_mul_f32 v[20:21], v[16:17], v[20:21]
	v_pk_mul_f32 v[18:19], v[14:15], v[18:19]
	v_cvt_pk_bf16_f32 v30, v30, v31
	v_cvt_pk_bf16_f32 v31, v32, v33
	v_cvt_pk_bf16_f32 v26, v26, v27
	v_cvt_pk_bf16_f32 v27, v28, v29
	v_cvt_pk_bf16_f32 v22, v22, v23
	v_cvt_pk_bf16_f32 v23, v24, v25
	v_cvt_pk_bf16_f32 v18, v18, v19
	v_cvt_pk_bf16_f32 v19, v20, v21
	global_store_dwordx2 v[50:51], v[30:31], off sc1
	global_store_dwordx2 v[50:51], v[26:27], off offset:512 sc1
	global_store_dwordx2 v[50:51], v[22:23], off offset:1024 sc1
	global_store_dwordx2 v[50:51], v[18:19], off offset:1536 sc1
	v_lshl_add_u64 v[50:51], v[50:51], 0, s[6:7]
	s_andn2_b64 vcc, exec, s[10:11]
	s_waitcnt vmcnt(7)
	v_mov_b32_e32 v30, v34
	v_mov_b32_e32 v31, v35
	v_mov_b32_e32 v32, v36
	v_mov_b32_e32 v33, v37
	s_waitcnt vmcnt(6)
	v_mov_b32_e32 v26, v38
	v_mov_b32_e32 v27, v39
	v_mov_b32_e32 v28, v40
	v_mov_b32_e32 v29, v41
	s_waitcnt vmcnt(5)
	v_mov_b32_e32 v22, v42
	v_mov_b32_e32 v23, v43
	v_mov_b32_e32 v24, v44
	v_mov_b32_e32 v25, v45
	s_waitcnt vmcnt(4)
	v_mov_b32_e32 v18, v46
	v_mov_b32_e32 v19, v47
	v_mov_b32_e32 v20, v48
	v_mov_b32_e32 v21, v49
	s_cbranch_vccz .LBB0_80

.LBB0_162:
	s_ashr_i32 s50, s81, 2
	s_ashr_i32 s51, s50, 31
	s_lshl_b64 s[50:51], s[50:51], 25
	s_add_u32 s50, s38, s50
	s_addc_u32 s51, s39, s51
	s_cmp_lt_u32 s81, 4
	s_cselect_b64 vcc, -1, 0
	s_lshl_b32 s8, s81, 8
	s_and_b32 s8, s8, 0x300
	v_or_b32_e32 v138, s8, v187
	v_cndmask_b32_e32 v170, 1.0, v195, vcc
	v_lshlrev_b32_e32 v138, 1, v138
	v_ashrrev_i32_e32 v169, 31, v168
	v_lshl_add_u64 v[174:175], s[50:51], 0, v[138:139]
	v_lshlrev_b64 v[172:173], 11, v[168:169]
	v_pk_mul_f32 v[128:129], v[170:171], v[128:129] op_sel_hi:[0,1]
	v_pk_mul_f32 v[126:127], v[170:171], v[126:127] op_sel_hi:[0,1]
	v_pk_mul_f32 v[176:177], v[170:171], v[124:125] op_sel_hi:[0,1]
	v_pk_mul_f32 v[124:125], v[170:171], v[122:123] op_sel_hi:[0,1]
	v_lshl_add_u64 v[172:173], v[174:175], 0, v[172:173]
	v_cvt_pk_bf16_f32 v122, v126, v127
	v_cvt_pk_bf16_f32 v123, v128, v129
	v_cvt_pk_bf16_f32 v124, v124, v125
	v_cvt_pk_bf16_f32 v125, v176, v177
	global_store_dwordx4 v[172:173], v[122:125], off sc1
	v_pk_mul_f32 v[116:117], v[170:171], v[116:117] op_sel_hi:[0,1]
	v_pk_mul_f32 v[114:115], v[170:171], v[114:115] op_sel_hi:[0,1]
	v_pk_mul_f32 v[122:123], v[170:171], v[108:109] op_sel_hi:[0,1]
	v_pk_mul_f32 v[108:109], v[170:171], v[106:107] op_sel_hi:[0,1]
	v_cvt_pk_bf16_f32 v106, v114, v115
	v_cvt_pk_bf16_f32 v107, v116, v117
	v_cvt_pk_bf16_f32 v108, v108, v109
	v_cvt_pk_bf16_f32 v109, v122, v123
	global_store_dwordx4 v[172:173], v[106:109], off offset:256 sc1
	v_pk_mul_f32 v[112:113], v[170:171], v[112:113] op_sel_hi:[0,1]
	v_pk_mul_f32 v[110:111], v[170:171], v[110:111] op_sel_hi:[0,1]
	v_or_b32_e32 v106, 16, v168
	v_ashrrev_i32_e32 v107, 31, v106
	v_lshlrev_b64 v[106:107], 11, v[106:107]
	v_lshl_add_u64 v[114:115], v[174:175], 0, v[106:107]
	v_pk_mul_f32 v[108:109], v[170:171], v[120:121] op_sel_hi:[0,1]
	v_pk_mul_f32 v[106:107], v[170:171], v[118:119] op_sel_hi:[0,1]
	v_cvt_pk_bf16_f32 v106, v106, v107
	v_cvt_pk_bf16_f32 v107, v108, v109
	v_cvt_pk_bf16_f32 v108, v110, v111
	v_cvt_pk_bf16_f32 v109, v112, v113
	global_store_dwordx4 v[114:115], v[106:109], off sc1
	v_pk_mul_f32 v[100:101], v[170:171], v[100:101] op_sel_hi:[0,1]
	v_pk_mul_f32 v[98:99], v[170:171], v[98:99] op_sel_hi:[0,1]
	v_pk_mul_f32 v[106:107], v[170:171], v[92:93] op_sel_hi:[0,1]
	v_pk_mul_f32 v[92:93], v[170:171], v[90:91] op_sel_hi:[0,1]
	v_cvt_pk_bf16_f32 v90, v98, v99
	v_cvt_pk_bf16_f32 v91, v100, v101
	v_cvt_pk_bf16_f32 v92, v92, v93
	v_cvt_pk_bf16_f32 v93, v106, v107
	global_store_dwordx4 v[114:115], v[90:93], off offset:256 sc1
	v_pk_mul_f32 v[96:97], v[170:171], v[96:97] op_sel_hi:[0,1]
	v_pk_mul_f32 v[94:95], v[170:171], v[94:95] op_sel_hi:[0,1]
	v_or_b32_e32 v90, 32, v168
	v_ashrrev_i32_e32 v91, 31, v90
	v_lshlrev_b64 v[90:91], 11, v[90:91]
	v_lshl_add_u64 v[98:99], v[174:175], 0, v[90:91]
	v_pk_mul_f32 v[92:93], v[170:171], v[104:105] op_sel_hi:[0,1]
	v_pk_mul_f32 v[90:91], v[170:171], v[102:103] op_sel_hi:[0,1]
	v_cvt_pk_bf16_f32 v90, v90, v91
	v_cvt_pk_bf16_f32 v91, v92, v93
	v_cvt_pk_bf16_f32 v92, v94, v95
	v_cvt_pk_bf16_f32 v93, v96, v97
	global_store_dwordx4 v[98:99], v[90:93], off sc1
	v_pk_mul_f32 v[84:85], v[170:171], v[84:85] op_sel_hi:[0,1]
	v_pk_mul_f32 v[82:83], v[170:171], v[82:83] op_sel_hi:[0,1]
	v_pk_mul_f32 v[90:91], v[170:171], v[76:77] op_sel_hi:[0,1]
	v_pk_mul_f32 v[76:77], v[170:171], v[74:75] op_sel_hi:[0,1]
	v_cvt_pk_bf16_f32 v74, v82, v83
	v_cvt_pk_bf16_f32 v75, v84, v85
	v_cvt_pk_bf16_f32 v76, v76, v77
	v_cvt_pk_bf16_f32 v77, v90, v91
	global_store_dwordx4 v[98:99], v[74:77], off offset:256 sc1
	v_pk_mul_f32 v[80:81], v[170:171], v[80:81] op_sel_hi:[0,1]
	v_pk_mul_f32 v[78:79], v[170:171], v[78:79] op_sel_hi:[0,1]
	v_or_b32_e32 v74, 48, v168
	v_ashrrev_i32_e32 v75, 31, v74
	v_lshlrev_b64 v[74:75], 11, v[74:75]
	v_lshl_add_u64 v[82:83], v[174:175], 0, v[74:75]
	v_pk_mul_f32 v[76:77], v[170:171], v[88:89] op_sel_hi:[0,1]
	v_pk_mul_f32 v[74:75], v[170:171], v[86:87] op_sel_hi:[0,1]
	v_cvt_pk_bf16_f32 v74, v74, v75
	v_cvt_pk_bf16_f32 v75, v76, v77
	v_cvt_pk_bf16_f32 v76, v78, v79
	v_cvt_pk_bf16_f32 v77, v80, v81
	global_store_dwordx4 v[82:83], v[74:77], off sc1
	v_pk_mul_f32 v[72:73], v[170:171], v[72:73] op_sel_hi:[0,1]
	v_pk_mul_f32 v[70:71], v[170:171], v[70:71] op_sel_hi:[0,1]
	v_pk_mul_f32 v[74:75], v[170:171], v[68:69] op_sel_hi:[0,1]
	v_pk_mul_f32 v[68:69], v[170:171], v[66:67] op_sel_hi:[0,1]
	v_cvt_pk_bf16_f32 v66, v70, v71
	v_cvt_pk_bf16_f32 v67, v72, v73
	v_cvt_pk_bf16_f32 v68, v68, v69
	v_cvt_pk_bf16_f32 v69, v74, v75
	v_pk_mul_f32 v[62:63], v[170:171], v[62:63] op_sel_hi:[0,1]
	s_mov_b32 s8, 0x40000
	global_store_dwordx4 v[82:83], v[66:69], off offset:256 sc1
	v_pk_mul_f32 v[64:65], v[170:171], v[64:65] op_sel_hi:[0,1]
	s_mov_b64 s[50:51], 0x40000
	v_pk_mul_f32 v[68:69], v[170:171], v[60:61] op_sel_hi:[0,1]
	v_pk_mul_f32 v[60:61], v[170:171], v[58:59] op_sel_hi:[0,1]
	v_cvt_pk_bf16_f32 v58, v62, v63
	v_add_co_u32_e32 v62, vcc, s8, v172
	v_cvt_pk_bf16_f32 v59, v64, v65
	v_cvt_pk_bf16_f32 v60, v60, v61
	v_cvt_pk_bf16_f32 v61, v68, v69
	v_addc_co_u32_e32 v63, vcc, 0, v173, vcc
	global_store_dwordx4 v[62:63], v[58:61], off sc1
	v_pk_mul_f32 v[52:53], v[170:171], v[52:53] op_sel_hi:[0,1]
	v_pk_mul_f32 v[50:51], v[170:171], v[50:51] op_sel_hi:[0,1]
	v_pk_mul_f32 v[58:59], v[170:171], v[44:45] op_sel_hi:[0,1]
	v_pk_mul_f32 v[44:45], v[170:171], v[42:43] op_sel_hi:[0,1]
	v_lshl_add_u64 v[66:67], v[172:173], 0, s[50:51]
	v_cvt_pk_bf16_f32 v42, v50, v51
	v_cvt_pk_bf16_f32 v43, v52, v53
	v_cvt_pk_bf16_f32 v44, v44, v45
	v_cvt_pk_bf16_f32 v45, v58, v59
	global_store_dwordx4 v[66:67], v[42:45], off offset:256 sc1
	v_pk_mul_f32 v[46:47], v[170:171], v[46:47] op_sel_hi:[0,1]
	v_pk_mul_f32 v[48:49], v[170:171], v[48:49] op_sel_hi:[0,1]
	v_pk_mul_f32 v[44:45], v[170:171], v[56:57] op_sel_hi:[0,1]
	v_pk_mul_f32 v[42:43], v[170:171], v[54:55] op_sel_hi:[0,1]
	v_cvt_pk_bf16_f32 v42, v42, v43
	v_cvt_pk_bf16_f32 v43, v44, v45
	v_cvt_pk_bf16_f32 v44, v46, v47
	v_add_co_u32_e32 v46, vcc, s76, v172
	v_cvt_pk_bf16_f32 v45, v48, v49
	s_nop 0
	v_addc_co_u32_e32 v47, vcc, 0, v173, vcc
	global_store_dwordx4 v[46:47], v[42:45], off sc1
	v_pk_mul_f32 v[36:37], v[170:171], v[36:37] op_sel_hi:[0,1]
	v_pk_mul_f32 v[34:35], v[170:171], v[34:35] op_sel_hi:[0,1]
	v_pk_mul_f32 v[42:43], v[170:171], v[28:29] op_sel_hi:[0,1]
	v_pk_mul_f32 v[28:29], v[170:171], v[26:27] op_sel_hi:[0,1]
	v_lshl_add_u64 v[50:51], v[172:173], 0, s[18:19]
	v_cvt_pk_bf16_f32 v26, v34, v35
	v_cvt_pk_bf16_f32 v27, v36, v37
	v_cvt_pk_bf16_f32 v28, v28, v29
	v_cvt_pk_bf16_f32 v29, v42, v43
	global_store_dwordx4 v[50:51], v[26:29], off offset:256 sc1
	v_pk_mul_f32 v[30:31], v[170:171], v[30:31] op_sel_hi:[0,1]
	s_mov_b32 s8, 0x50000
	v_pk_mul_f32 v[28:29], v[170:171], v[40:41] op_sel_hi:[0,1]
	v_pk_mul_f32 v[26:27], v[170:171], v[38:39] op_sel_hi:[0,1]
	v_pk_mul_f32 v[32:33], v[170:171], v[32:33] op_sel_hi:[0,1]
	v_cvt_pk_bf16_f32 v26, v26, v27
	v_cvt_pk_bf16_f32 v27, v28, v29
	v_cvt_pk_bf16_f32 v28, v30, v31
	v_add_co_u32_e32 v30, vcc, s8, v172
	v_cvt_pk_bf16_f32 v29, v32, v33
	s_nop 0
	v_addc_co_u32_e32 v31, vcc, 0, v173, vcc
	global_store_dwordx4 v[30:31], v[26:29], off sc1
	v_pk_mul_f32 v[20:21], v[170:171], v[20:21] op_sel_hi:[0,1]
	v_pk_mul_f32 v[18:19], v[170:171], v[18:19] op_sel_hi:[0,1]
	v_pk_mul_f32 v[26:27], v[170:171], v[12:13] op_sel_hi:[0,1]
	v_pk_mul_f32 v[12:13], v[170:171], v[10:11] op_sel_hi:[0,1]
	v_lshl_add_u64 v[34:35], v[172:173], 0, s[20:21]
	v_cvt_pk_bf16_f32 v10, v18, v19
	v_cvt_pk_bf16_f32 v11, v20, v21
	v_cvt_pk_bf16_f32 v12, v12, v13
	v_cvt_pk_bf16_f32 v13, v26, v27
	global_store_dwordx4 v[34:35], v[10:13], off offset:256 sc1
	v_pk_mul_f32 v[14:15], v[170:171], v[14:15] op_sel_hi:[0,1]
	v_pk_mul_f32 v[16:17], v[170:171], v[16:17] op_sel_hi:[0,1]
	v_pk_mul_f32 v[12:13], v[170:171], v[24:25] op_sel_hi:[0,1]
	v_pk_mul_f32 v[10:11], v[170:171], v[22:23] op_sel_hi:[0,1]
	v_cvt_pk_bf16_f32 v10, v10, v11
	v_cvt_pk_bf16_f32 v11, v12, v13
	v_cvt_pk_bf16_f32 v12, v14, v15
	v_add_co_u32_e32 v14, vcc, s77, v172
	v_cvt_pk_bf16_f32 v13, v16, v17
	s_nop 0
	v_addc_co_u32_e32 v15, vcc, 0, v173, vcc
	global_store_dwordx4 v[14:15], v[10:13], off sc1
	v_pk_mul_f32 v[8:9], v[170:171], v[8:9] op_sel_hi:[0,1]
	v_pk_mul_f32 v[6:7], v[170:171], v[6:7] op_sel_hi:[0,1]
	v_pk_mul_f32 v[10:11], v[170:171], v[4:5] op_sel_hi:[0,1]
	v_pk_mul_f32 v[4:5], v[170:171], v[2:3] op_sel_hi:[0,1]
	v_lshl_add_u64 v[18:19], v[172:173], 0, s[22:23]
	v_cvt_pk_bf16_f32 v2, v6, v7
	v_cvt_pk_bf16_f32 v3, v8, v9
	v_cvt_pk_bf16_f32 v4, v4, v5
	v_cvt_pk_bf16_f32 v5, v10, v11
	global_store_dwordx4 v[18:19], v[2:5], off offset:256 sc1
	s_andn2_b64 vcc, exec, s[6:7]
	s_mov_b64 s[6:7], -1
	s_cbranch_vccnz .LBB0_137

.LBB0_170:
	s_or_b64 exec, exec, s[8:9]
	s_waitcnt vmcnt(0)
	ds_write2_b32 v43, v2, v3 offset1:1
	ds_write2_b32 v43, v4, v5 offset0:2 offset1:3
	v_add_u32_e32 v2, 0x420, v43
	ds_write2_b32 v2, v10, v11 offset1:1
	v_add_u32_e32 v2, 0x428, v43
	ds_write2_b32 v2, v12, v13 offset1:1
	v_add_u32_e32 v2, 0x840, v43
	ds_write2_b32 v2, v6, v7 offset1:1
	v_add_u32_e32 v2, 0x848, v43
	ds_write2_b32 v2, v8, v9 offset1:1
	v_add_u32_e32 v2, 0xc60, v43
	ds_write2_b32 v2, v18, v19 offset1:1
	v_add_u32_e32 v2, 0xc68, v43
	ds_write2_b32 v2, v20, v21 offset1:1
	v_add_u32_e32 v2, 0x1080, v43
	ds_write2_b32 v2, v14, v15 offset1:1
	v_add_u32_e32 v2, 0x1088, v43
	ds_write2_b32 v2, v16, v17 offset1:1
	v_add_u32_e32 v2, 0x14a0, v43
	ds_write2_b32 v2, v26, v27 offset1:1
	v_add_u32_e32 v2, 0x14a8, v43
	ds_write2_b32 v2, v28, v29 offset1:1
	v_add_u32_e32 v2, 0x18c0, v43
	ds_write2_b32 v2, v22, v23 offset1:1
	v_add_u32_e32 v2, 0x18c8, v43
	ds_write2_b32 v2, v24, v25 offset1:1
	v_add_u32_e32 v2, 0x1ce0, v43
	ds_write2_b32 v2, v30, v31 offset1:1
	v_add_u32_e32 v2, 0x1ce8, v43
	ds_write2_b32 v2, v32, v33 offset1:1
	s_waitcnt lgkmcnt(0)
	s_sub_i32 s8, 0, s7
	ds_read2_b32 v[6:7], v42 offset0:33 offset1:41
	ds_read2_b32 v[8:9], v42 offset1:8
	ds_read2_b32 v[10:11], v42 offset0:66 offset1:74
	ds_read2_b32 v[12:13], v42 offset0:99 offset1:107
	ds_read2_b32 v[14:15], v42 offset0:132 offset1:140
	ds_read2_b32 v[16:17], v42 offset0:165 offset1:173
	ds_read2_b32 v[18:19], v42 offset0:198 offset1:206
	ds_read2_b32 v[20:21], v42 offset0:231 offset1:239
	s_add_i32 s8, s8, s2
	v_add_u32_e32 v24, s8, v41
	s_ashr_i32 s7, s6, 31
	v_ashrrev_i32_e32 v25, 31, v24
	v_lshl_add_u64 v[22:23], s[6:7], 1, v[34:35]
	v_lshlrev_b64 v[26:27], 11, v[24:25]
	s_waitcnt lgkmcnt(6)
	v_cvt_pk_bf16_f32 v2, v8, v6
	s_waitcnt lgkmcnt(4)
	v_cvt_pk_bf16_f32 v3, v10, v12
	s_waitcnt lgkmcnt(2)
	v_cvt_pk_bf16_f32 v4, v14, v16
	s_waitcnt lgkmcnt(0)
	v_cvt_pk_bf16_f32 v5, v18, v20
	v_lshl_add_u64 v[26:27], v[22:23], 0, v[26:27]
	v_add_u32_e32 v6, 8, v24
	global_store_dwordx4 v[26:27], v[2:5], off sc1
	s_add_i32 s6, s1, 0x600
	s_add_i32 s2, s2, 0xc000
	v_cvt_pk_bf16_f32 v2, v9, v7
	v_ashrrev_i32_e32 v7, 31, v6
	v_cvt_pk_bf16_f32 v3, v11, v13
	v_cvt_pk_bf16_f32 v4, v15, v17
	v_cvt_pk_bf16_f32 v5, v19, v21
	v_lshlrev_b64 v[6:7], 11, v[6:7]
	ds_read2_b32 v[8:9], v42 offset0:49 offset1:57
	ds_read2_b32 v[10:11], v42 offset0:16 offset1:24
	ds_read2_b32 v[12:13], v42 offset0:82 offset1:90
	ds_read2_b32 v[14:15], v42 offset0:115 offset1:123
	ds_read2_b32 v[16:17], v42 offset0:148 offset1:156
	ds_read2_b32 v[18:19], v42 offset0:181 offset1:189
	ds_read2_b32 v[20:21], v42 offset0:214 offset1:222
	ds_read2_b32 v[26:27], v42 offset0:247 offset1:255
	v_lshl_add_u64 v[6:7], v[22:23], 0, v[6:7]
	global_store_dwordx4 v[6:7], v[2:5], off sc1
	v_add_u32_e32 v6, 16, v24
	v_ashrrev_i32_e32 v7, 31, v6
	v_lshlrev_b64 v[6:7], 11, v[6:7]
	s_waitcnt lgkmcnt(6)
	v_cvt_pk_bf16_f32 v2, v10, v8
	s_waitcnt lgkmcnt(4)
	v_cvt_pk_bf16_f32 v3, v12, v14
	s_waitcnt lgkmcnt(2)
	v_cvt_pk_bf16_f32 v4, v16, v18
	s_waitcnt lgkmcnt(0)
	v_cvt_pk_bf16_f32 v5, v20, v26
	v_lshl_add_u64 v[6:7], v[22:23], 0, v[6:7]
	global_store_dwordx4 v[6:7], v[2:5], off sc1
	v_add_u32_e32 v6, 24, v24
	v_ashrrev_i32_e32 v7, 31, v6
	v_lshlrev_b64 v[6:7], 11, v[6:7]
	v_cvt_pk_bf16_f32 v2, v11, v9
	v_cvt_pk_bf16_f32 v3, v13, v15
	v_cvt_pk_bf16_f32 v4, v17, v19
	v_cvt_pk_bf16_f32 v5, v21, v27
	v_lshl_add_u64 v[6:7], v[22:23], 0, v[6:7]
	global_store_dwordx4 v[6:7], v[2:5], off sc1
	s_waitcnt lgkmcnt(0)
	s_cmpk_lt_i32 s1, 0x200
	s_mov_b32 s1, s6
	s_cbranch_scc0 .LBB0_187

.LBB0_189:
	s_or_b64 exec, exec, s[8:9]
	s_waitcnt vmcnt(0)
	ds_write2_b32 v43, v2, v3 offset1:1
	ds_write2_b32 v43, v4, v5 offset0:2 offset1:3
	v_add_u32_e32 v2, 0x420, v43
	ds_write2_b32 v2, v10, v11 offset1:1
	v_add_u32_e32 v2, 0x428, v43
	ds_write2_b32 v2, v12, v13 offset1:1
	v_add_u32_e32 v2, 0x840, v43
	ds_write2_b32 v2, v6, v7 offset1:1
	v_add_u32_e32 v2, 0x848, v43
	ds_write2_b32 v2, v8, v9 offset1:1
	v_add_u32_e32 v2, 0xc60, v43
	ds_write2_b32 v2, v18, v19 offset1:1
	v_add_u32_e32 v2, 0xc68, v43
	ds_write2_b32 v2, v20, v21 offset1:1
	v_add_u32_e32 v2, 0x1080, v43
	ds_write2_b32 v2, v14, v15 offset1:1
	v_add_u32_e32 v2, 0x1088, v43
	ds_write2_b32 v2, v16, v17 offset1:1
	v_add_u32_e32 v2, 0x14a0, v43
	ds_write2_b32 v2, v26, v27 offset1:1
	v_add_u32_e32 v2, 0x14a8, v43
	ds_write2_b32 v2, v28, v29 offset1:1
	v_add_u32_e32 v2, 0x18c0, v43
	ds_write2_b32 v2, v22, v23 offset1:1
	v_add_u32_e32 v2, 0x18c8, v43
	ds_write2_b32 v2, v24, v25 offset1:1
	v_add_u32_e32 v2, 0x1ce0, v43
	ds_write2_b32 v2, v30, v31 offset1:1
	v_add_u32_e32 v2, 0x1ce8, v43
	ds_write2_b32 v2, v32, v33 offset1:1
	s_waitcnt lgkmcnt(0)
	s_sub_i32 s3, 0, s3
	ds_read2_b32 v[6:7], v42 offset0:33 offset1:41
	ds_read2_b32 v[8:9], v42 offset1:8
	ds_read2_b32 v[10:11], v42 offset0:66 offset1:74
	ds_read2_b32 v[12:13], v42 offset0:99 offset1:107
	ds_read2_b32 v[14:15], v42 offset0:132 offset1:140
	ds_read2_b32 v[16:17], v42 offset0:165 offset1:173
	ds_read2_b32 v[18:19], v42 offset0:198 offset1:206
	ds_read2_b32 v[20:21], v42 offset0:231 offset1:239
	s_add_i32 s3, s3, s1
	v_add_u32_e32 v24, s3, v41
	s_ashr_i32 s7, s6, 31
	v_ashrrev_i32_e32 v25, 31, v24
	v_lshl_add_u64 v[22:23], s[6:7], 1, v[34:35]
	v_lshlrev_b64 v[26:27], 13, v[24:25]
	s_waitcnt lgkmcnt(6)
	v_cvt_pk_bf16_f32 v2, v8, v6
	s_waitcnt lgkmcnt(4)
	v_cvt_pk_bf16_f32 v3, v10, v12
	s_waitcnt lgkmcnt(2)
	v_cvt_pk_bf16_f32 v4, v14, v16
	s_waitcnt lgkmcnt(0)
	v_cvt_pk_bf16_f32 v5, v18, v20
	v_lshl_add_u64 v[26:27], v[22:23], 0, v[26:27]
	v_add_u32_e32 v6, 8, v24
	global_store_dwordx4 v[26:27], v[2:5], off sc1
	s_add_i32 s3, s0, 0x600
	s_add_i32 s1, s1, 0xc000
	v_cvt_pk_bf16_f32 v2, v9, v7
	v_ashrrev_i32_e32 v7, 31, v6
	v_cvt_pk_bf16_f32 v3, v11, v13
	v_cvt_pk_bf16_f32 v4, v15, v17
	v_cvt_pk_bf16_f32 v5, v19, v21
	v_lshlrev_b64 v[6:7], 13, v[6:7]
	ds_read2_b32 v[8:9], v42 offset0:49 offset1:57
	ds_read2_b32 v[10:11], v42 offset0:16 offset1:24
	ds_read2_b32 v[12:13], v42 offset0:82 offset1:90
	ds_read2_b32 v[14:15], v42 offset0:115 offset1:123
	ds_read2_b32 v[16:17], v42 offset0:148 offset1:156
	ds_read2_b32 v[18:19], v42 offset0:181 offset1:189
	ds_read2_b32 v[20:21], v42 offset0:214 offset1:222
	ds_read2_b32 v[26:27], v42 offset0:247 offset1:255
	v_lshl_add_u64 v[6:7], v[22:23], 0, v[6:7]
	global_store_dwordx4 v[6:7], v[2:5], off sc1
	v_add_u32_e32 v6, 16, v24
	v_ashrrev_i32_e32 v7, 31, v6
	v_lshlrev_b64 v[6:7], 13, v[6:7]
	s_waitcnt lgkmcnt(6)
	v_cvt_pk_bf16_f32 v2, v10, v8
	s_waitcnt lgkmcnt(4)
	v_cvt_pk_bf16_f32 v3, v12, v14
	s_waitcnt lgkmcnt(2)
	v_cvt_pk_bf16_f32 v4, v16, v18
	s_waitcnt lgkmcnt(0)
	v_cvt_pk_bf16_f32 v5, v20, v26
	v_lshl_add_u64 v[6:7], v[22:23], 0, v[6:7]
	global_store_dwordx4 v[6:7], v[2:5], off sc1
	v_add_u32_e32 v6, 24, v24
	v_ashrrev_i32_e32 v7, 31, v6
	v_lshlrev_b64 v[6:7], 13, v[6:7]
	v_cvt_pk_bf16_f32 v2, v11, v9
	v_cvt_pk_bf16_f32 v3, v13, v15
	v_cvt_pk_bf16_f32 v4, v17, v19
	v_cvt_pk_bf16_f32 v5, v21, v27
	v_lshl_add_u64 v[6:7], v[22:23], 0, v[6:7]
	global_store_dwordx4 v[6:7], v[2:5], off sc1
	s_waitcnt lgkmcnt(0)
	s_cmpk_lt_i32 s0, 0x200
	s_mov_b32 s0, s3
	s_cbranch_scc0 .LBB0_206

.LBB0_259:
	s_or_b64 exec, exec, s[22:23]
	v_lshl_add_u32 v40, v114, 2, s96
	s_waitcnt lgkmcnt(0)
	ds_read_b128 v[32:35], v40 offset:32896
	ds_read_b128 v[36:39], v40 offset:32928
	s_mov_b32 s81, s73
	s_waitcnt lgkmcnt(1)
	v_div_scale_f32 v41, s[20:21], v32, v32, 1.0
	v_rcp_f32_e32 v43, v41
	v_div_scale_f32 v42, vcc, 1.0, v32, 1.0
	v_div_scale_f32 v44, s[20:21], v33, v33, 1.0
	v_fma_f32 v46, -v41, v43, 1.0
	v_fmac_f32_e32 v43, v46, v43
	v_mul_f32_e32 v46, v42, v43
	v_rcp_f32_e32 v45, v44
	v_fma_f32 v47, -v41, v46, v42
	v_fmac_f32_e32 v46, v47, v43
	v_fma_f32 v41, -v41, v46, v42
	v_div_fmas_f32 v41, v41, v43, v46
	v_div_fixup_f32 v46, v41, v32, 1.0
	v_fma_f32 v32, -v44, v45, 1.0
	v_fmac_f32_e32 v45, v32, v45
	v_div_scale_f32 v32, vcc, 1.0, v33, 1.0
	v_mul_f32_e32 v41, v32, v45
	v_fma_f32 v42, -v44, v41, v32
	v_fmac_f32_e32 v41, v42, v45
	v_div_scale_f32 v42, s[20:21], v34, v34, 1.0
	v_rcp_f32_e32 v43, v42
	v_fma_f32 v32, -v44, v41, v32
	v_div_fmas_f32 v32, v32, v45, v41
	v_div_fixup_f32 v44, v32, v33, 1.0
	v_fma_f32 v32, -v42, v43, 1.0
	v_fmac_f32_e32 v43, v32, v43
	v_div_scale_f32 v32, vcc, 1.0, v34, 1.0
	v_mul_f32_e32 v33, v32, v43
	v_fma_f32 v41, -v42, v33, v32
	v_fmac_f32_e32 v33, v41, v43
	v_div_scale_f32 v41, s[20:21], v35, v35, 1.0
	v_fma_f32 v32, -v42, v33, v32
	v_rcp_f32_e32 v42, v41
	v_div_fmas_f32 v32, v32, v43, v33
	v_div_fixup_f32 v45, v32, v34, 1.0
	v_mul_f32_e32 v0, v0, v46
	v_fma_f32 v32, -v41, v42, 1.0
	v_fmac_f32_e32 v42, v32, v42
	v_div_scale_f32 v32, vcc, 1.0, v35, 1.0
	v_mul_f32_e32 v33, v32, v42
	v_fma_f32 v34, -v41, v33, v32
	v_fmac_f32_e32 v33, v34, v42
	s_waitcnt lgkmcnt(0)
	v_div_scale_f32 v34, s[20:21], v36, v36, 1.0
	v_fma_f32 v32, -v41, v33, v32
	v_rcp_f32_e32 v41, v34
	v_div_fmas_f32 v32, v32, v42, v33
	v_div_fixup_f32 v47, v32, v35, 1.0
	v_div_scale_f32 v42, s[20:21], v39, v39, 1.0
	v_fma_f32 v32, -v34, v41, 1.0
	v_fmac_f32_e32 v41, v32, v41
	v_div_scale_f32 v32, vcc, 1.0, v36, 1.0
	v_mul_f32_e32 v33, v32, v41
	v_fma_f32 v35, -v34, v33, v32
	v_fmac_f32_e32 v33, v35, v41
	v_fma_f32 v32, -v34, v33, v32
	v_div_scale_f32 v34, s[20:21], v37, v37, 1.0
	v_rcp_f32_e32 v35, v34
	v_div_fmas_f32 v32, v32, v41, v33
	v_div_fixup_f32 v36, v32, v36, 1.0
	v_rcp_f32_e32 v48, v42
	v_fma_f32 v32, -v34, v35, 1.0
	v_fmac_f32_e32 v35, v32, v35
	v_div_scale_f32 v32, vcc, 1.0, v37, 1.0
	v_mul_f32_e32 v33, v32, v35
	v_fma_f32 v41, -v34, v33, v32
	v_fmac_f32_e32 v33, v41, v35
	v_fma_f32 v32, -v34, v33, v32
	v_div_scale_f32 v34, s[20:21], v38, v38, 1.0
	v_rcp_f32_e32 v41, v34
	v_div_fmas_f32 v32, v32, v35, v33
	v_div_fixup_f32 v37, v32, v37, 1.0
	v_cvt_pk_bf16_f32 v0, v0, s0
	v_fma_f32 v32, -v34, v41, 1.0
	v_fmac_f32_e32 v41, v32, v41
	v_div_scale_f32 v32, vcc, 1.0, v38, 1.0
	v_mul_f32_e32 v33, v32, v41
	v_fma_f32 v35, -v34, v33, v32
	v_fmac_f32_e32 v33, v35, v41
	v_fma_f32 v32, -v34, v33, v32
	v_div_fmas_f32 v32, v32, v41, v33
	v_div_fixup_f32 v38, v32, v38, 1.0
	v_fma_f32 v32, -v42, v48, 1.0
	v_fmac_f32_e32 v48, v32, v48
	ds_read_b128 v[32:35], v40 offset:32960
	v_div_scale_f32 v41, vcc, 1.0, v39, 1.0
	v_mul_f32_e32 v49, v41, v48
	v_fma_f32 v43, -v42, v49, v41
	s_waitcnt lgkmcnt(0)
	v_div_scale_f32 v51, s[20:21], v32, v32, 1.0
	v_rcp_f32_e32 v52, v51
	v_fmac_f32_e32 v49, v43, v48
	v_fma_f32 v50, -v42, v49, v41
	v_div_fmas_f32 v48, v50, v48, v49
	v_div_fixup_f32 v39, v48, v39, 1.0
	v_fma_f32 v48, -v51, v52, 1.0
	v_fmac_f32_e32 v52, v48, v52
	v_div_scale_f32 v48, vcc, 1.0, v32, 1.0
	v_mul_f32_e32 v49, v48, v52
	v_fma_f32 v50, -v51, v49, v48
	v_fmac_f32_e32 v49, v50, v52
	v_div_scale_f32 v50, s[20:21], v33, v33, 1.0
	v_fma_f32 v48, -v51, v49, v48
	v_rcp_f32_e32 v51, v50
	v_div_fmas_f32 v48, v48, v52, v49
	v_div_fixup_f32 v32, v48, v32, 1.0
	ds_read_b128 v[40:43], v40 offset:32992
	v_fma_f32 v48, -v50, v51, 1.0
	v_fmac_f32_e32 v51, v48, v51
	v_div_scale_f32 v48, vcc, 1.0, v33, 1.0
	v_mul_f32_e32 v49, v48, v51
	v_fma_f32 v52, -v50, v49, v48
	v_fmac_f32_e32 v49, v52, v51
	v_fma_f32 v48, -v50, v49, v48
	v_div_scale_f32 v50, s[20:21], v34, v34, 1.0
	v_rcp_f32_e32 v52, v50
	v_div_fmas_f32 v48, v48, v51, v49
	v_div_fixup_f32 v33, v48, v33, 1.0
	v_fma_f32 v48, -v50, v52, 1.0
	v_fmac_f32_e32 v52, v48, v52
	v_div_scale_f32 v48, vcc, 1.0, v34, 1.0
	v_mul_f32_e32 v49, v48, v52
	v_fma_f32 v51, -v50, v49, v48
	v_fmac_f32_e32 v49, v51, v52
	v_fma_f32 v48, -v50, v49, v48
	v_div_scale_f32 v50, s[20:21], v35, v35, 1.0
	v_rcp_f32_e32 v51, v50
	v_div_fmas_f32 v48, v48, v52, v49
	v_div_fixup_f32 v34, v48, v34, 1.0
	v_fma_f32 v48, -v50, v51, 1.0
	v_fmac_f32_e32 v51, v48, v51
	v_div_scale_f32 v48, vcc, 1.0, v35, 1.0
	v_mul_f32_e32 v49, v48, v51
	v_fma_f32 v52, -v50, v49, v48
	v_fmac_f32_e32 v49, v52, v51
	v_fma_f32 v48, -v50, v49, v48
	s_waitcnt lgkmcnt(0)
	v_div_scale_f32 v50, s[20:21], v40, v40, 1.0
	v_rcp_f32_e32 v52, v50
	v_div_fmas_f32 v48, v48, v51, v49
	v_div_fixup_f32 v35, v48, v35, 1.0
	v_fma_f32 v48, -v50, v52, 1.0
	v_fmac_f32_e32 v52, v48, v52
	v_div_scale_f32 v48, vcc, 1.0, v40, 1.0
	v_mul_f32_e32 v49, v48, v52
	v_fma_f32 v51, -v50, v49, v48
	v_fmac_f32_e32 v49, v51, v52
	v_fma_f32 v48, -v50, v49, v48
	v_div_scale_f32 v50, s[20:21], v41, v41, 1.0
	v_rcp_f32_e32 v51, v50
	v_div_fmas_f32 v48, v48, v52, v49
	v_div_fixup_f32 v40, v48, v40, 1.0
	v_fma_f32 v48, -v50, v51, 1.0
	v_fmac_f32_e32 v51, v48, v51
	v_div_scale_f32 v48, vcc, 1.0, v41, 1.0
	v_mul_f32_e32 v49, v48, v51
	v_fma_f32 v52, -v50, v49, v48
	v_fmac_f32_e32 v49, v52, v51
	v_fma_f32 v48, -v50, v49, v48
	v_div_scale_f32 v50, s[20:21], v42, v42, 1.0
	v_rcp_f32_e32 v52, v50
	v_div_fmas_f32 v48, v48, v51, v49
	v_div_fixup_f32 v41, v48, v41, 1.0
	v_fma_f32 v48, -v50, v52, 1.0
	v_fmac_f32_e32 v52, v48, v52
	v_div_scale_f32 v48, vcc, 1.0, v42, 1.0
	v_mul_f32_e32 v49, v48, v52
	v_fma_f32 v51, -v50, v49, v48
	v_fmac_f32_e32 v49, v51, v52
	v_fma_f32 v48, -v50, v49, v48
	v_div_scale_f32 v50, s[20:21], v43, v43, 1.0
	v_rcp_f32_e32 v51, v50
	v_div_fmas_f32 v48, v48, v52, v49
	v_div_fixup_f32 v42, v48, v42, 1.0
	s_lshl_b64 s[20:21], s[80:81], 11
	v_fma_f32 v48, -v50, v51, 1.0
	v_fmac_f32_e32 v51, v48, v51
	v_div_scale_f32 v48, vcc, 1.0, v43, 1.0
	v_mul_f32_e32 v49, v48, v51
	v_fma_f32 v52, -v50, v49, v48
	v_fmac_f32_e32 v49, v52, v51
	v_fma_f32 v48, -v50, v49, v48
	v_div_fmas_f32 v48, v48, v51, v49
	v_div_fixup_f32 v43, v48, v43, 1.0
	v_lshlrev_b32_e32 v48, 9, v111
	v_lshlrev_b32_e32 v49, 1, v110
	v_add3_u32 v48, s31, v48, v49
	ds_write_b16 v48, v0 offset:34816
	v_mul_f32_e32 v0, v16, v46
	v_cvt_pk_bf16_f32 v0, v0, s0
	ds_write_b16 v48, v0 offset:34880
	v_mul_f32_e32 v0, v1, v44
	v_cvt_pk_bf16_f32 v0, v0, s0
	ds_write_b16 v48, v0 offset:34944
	v_mul_f32_e32 v0, v17, v44
	v_cvt_pk_bf16_f32 v0, v0, s0
	ds_write_b16 v48, v0 offset:35008
	v_mul_f32_e32 v0, v2, v45
	v_cvt_pk_bf16_f32 v0, v0, s0
	ds_write_b16 v48, v0 offset:35072
	v_mul_f32_e32 v0, v18, v45
	v_cvt_pk_bf16_f32 v0, v0, s0
	ds_write_b16 v48, v0 offset:35136
	v_mul_f32_e32 v0, v3, v47
	v_cvt_pk_bf16_f32 v0, v0, s0
	ds_write_b16 v48, v0 offset:35200
	v_mul_f32_e32 v0, v19, v47
	v_cvt_pk_bf16_f32 v0, v0, s0
	ds_write_b16 v48, v0 offset:35264
	v_mul_f32_e32 v0, v4, v36
	v_cvt_pk_bf16_f32 v0, v0, s0
	ds_write_b16 v48, v0 offset:35840
	v_mul_f32_e32 v0, v20, v36
	v_cvt_pk_bf16_f32 v0, v0, s0
	ds_write_b16 v48, v0 offset:35904
	v_mul_f32_e32 v0, v5, v37
	v_cvt_pk_bf16_f32 v0, v0, s0
	ds_write_b16 v48, v0 offset:35968
	v_mul_f32_e32 v0, v21, v37
	v_cvt_pk_bf16_f32 v0, v0, s0
	ds_write_b16 v48, v0 offset:36032
	v_mul_f32_e32 v0, v6, v38
	v_cvt_pk_bf16_f32 v0, v0, s0
	ds_write_b16 v48, v0 offset:36096
	v_mul_f32_e32 v0, v22, v38
	v_cvt_pk_bf16_f32 v0, v0, s0
	ds_write_b16 v48, v0 offset:36160
	v_mul_f32_e32 v0, v7, v39
	v_cvt_pk_bf16_f32 v0, v0, s0
	ds_write_b16 v48, v0 offset:36224
	v_mul_f32_e32 v0, v23, v39
	v_cvt_pk_bf16_f32 v0, v0, s0
	ds_write_b16 v48, v0 offset:36288
	v_mul_f32_e32 v0, v8, v32
	v_cvt_pk_bf16_f32 v0, v0, s0
	ds_write_b16 v48, v0 offset:36864
	v_mul_f32_e32 v0, v24, v32
	v_cvt_pk_bf16_f32 v0, v0, s0
	ds_write_b16 v48, v0 offset:36928
	v_mul_f32_e32 v0, v9, v33
	v_cvt_pk_bf16_f32 v0, v0, s0
	ds_write_b16 v48, v0 offset:36992
	v_mul_f32_e32 v0, v25, v33
	v_cvt_pk_bf16_f32 v0, v0, s0
	ds_write_b16 v48, v0 offset:37056
	v_mul_f32_e32 v0, v10, v34
	v_cvt_pk_bf16_f32 v0, v0, s0
	ds_write_b16 v48, v0 offset:37120
	v_mul_f32_e32 v0, v26, v34
	v_cvt_pk_bf16_f32 v0, v0, s0
	ds_write_b16 v48, v0 offset:37184
	v_mul_f32_e32 v0, v11, v35
	v_cvt_pk_bf16_f32 v0, v0, s0
	ds_write_b16 v48, v0 offset:37248
	v_mul_f32_e32 v0, v27, v35
	v_cvt_pk_bf16_f32 v0, v0, s0
	ds_write_b16 v48, v0 offset:37312
	v_mul_f32_e32 v0, v12, v40
	v_cvt_pk_bf16_f32 v0, v0, s0
	ds_write_b16 v48, v0 offset:37888
	v_mul_f32_e32 v0, v28, v40
	v_cvt_pk_bf16_f32 v0, v0, s0
	ds_write_b16 v48, v0 offset:37952
	v_mul_f32_e32 v0, v13, v41
	v_cvt_pk_bf16_f32 v0, v0, s0
	ds_write_b16 v48, v0 offset:38016
	v_mul_f32_e32 v0, v29, v41
	v_cvt_pk_bf16_f32 v0, v0, s0
	ds_write_b16 v48, v0 offset:38080
	v_mul_f32_e32 v0, v14, v42
	v_cvt_pk_bf16_f32 v0, v0, s0
	ds_write_b16 v48, v0 offset:38144
	v_mul_f32_e32 v0, v30, v42
	v_cvt_pk_bf16_f32 v0, v0, s0
	ds_write_b16 v48, v0 offset:38208
	v_mul_f32_e32 v0, v15, v43
	v_cvt_pk_bf16_f32 v0, v0, s0
	ds_write_b16 v48, v0 offset:38272
	v_mul_f32_e32 v0, v31, v43
	v_cvt_pk_bf16_f32 v0, v0, s0
	ds_write_b16 v48, v0 offset:38336
	v_lshlrev_b32_e32 v0, 1, v99
	v_and_b32_e32 v96, 0x70, v0
	v_lshrrev_b32_e32 v12, 3, v109
	v_add_u32_e32 v13, s31, v96
	s_add_u32 s20, s64, s20
	v_lshl_add_u32 v0, v12, 7, v13
	v_or_b32_e32 v14, 8, v12
	s_addc_u32 s21, s65, s21
	s_lshl_b32 s22, s44, 1
	ds_read_b128 v[0:3], v0 offset:34816
	v_lshl_add_u32 v4, v14, 7, v13
	s_add_u32 s20, s20, s22
	ds_read_b128 v[4:7], v4 offset:34816
	s_addc_u32 s21, s21, 0
	v_lshl_add_u64 v[8:9], s[20:21], 0, v[96:97]
	v_lshlrev_b32_e32 v96, 11, v12
	v_lshl_add_u64 v[10:11], v[8:9], 0, v[96:97]
	v_lshlrev_b32_e32 v96, 11, v14
	s_waitcnt lgkmcnt(1)
	global_store_dwordx4 v[10:11], v[0:3], off sc1
	s_mov_b64 s[20:21], 0
	s_nop 0
	v_lshl_add_u64 v[0:1], v[8:9], 0, v[96:97]
	s_waitcnt lgkmcnt(0)
	global_store_dwordx4 v[0:1], v[4:7], off sc1
	s_nop 1
	v_or_b32_e32 v4, 16, v12
	v_lshl_add_u32 v0, v4, 7, v13
	v_or_b32_e32 v12, 24, v12
	ds_read_b128 v[0:3], v0 offset:34816
	v_lshlrev_b32_e32 v96, 11, v4
	v_lshl_add_u32 v4, v12, 7, v13
	ds_read_b128 v[4:7], v4 offset:34816
	v_lshl_add_u64 v[10:11], v[8:9], 0, v[96:97]
	v_lshlrev_b32_e32 v96, 11, v12
	s_waitcnt lgkmcnt(1)
	global_store_dwordx4 v[10:11], v[0:3], off sc1
	s_nop 1
	v_lshl_add_u64 v[0:1], v[8:9], 0, v[96:97]
	s_waitcnt lgkmcnt(0)
	global_store_dwordx4 v[0:1], v[4:7], off sc1

.LBB0_317:
	s_or_b64 exec, exec, s[8:9]
	s_waitcnt vmcnt(0)
	ds_write2_b32 v41, v0, v1 offset1:1
	ds_write2_b32 v41, v2, v3 offset0:2 offset1:3
	v_add_u32_e32 v0, 0x420, v41
	ds_write2_b32 v0, v8, v9 offset1:1
	v_add_u32_e32 v0, 0x428, v41
	ds_write2_b32 v0, v10, v11 offset1:1
	v_add_u32_e32 v0, 0x840, v41
	ds_write2_b32 v0, v4, v5 offset1:1
	v_add_u32_e32 v0, 0x848, v41
	ds_write2_b32 v0, v6, v7 offset1:1
	v_add_u32_e32 v0, 0xc60, v41
	ds_write2_b32 v0, v16, v17 offset1:1
	v_add_u32_e32 v0, 0xc68, v41
	ds_write2_b32 v0, v18, v19 offset1:1
	v_add_u32_e32 v0, 0x1080, v41
	ds_write2_b32 v0, v12, v13 offset1:1
	v_add_u32_e32 v0, 0x1088, v41
	ds_write2_b32 v0, v14, v15 offset1:1
	v_add_u32_e32 v0, 0x14a0, v41
	ds_write2_b32 v0, v24, v25 offset1:1
	v_add_u32_e32 v0, 0x14a8, v41
	ds_write2_b32 v0, v26, v27 offset1:1
	v_add_u32_e32 v0, 0x18c0, v41
	ds_write2_b32 v0, v20, v21 offset1:1
	v_add_u32_e32 v0, 0x18c8, v41
	ds_write2_b32 v0, v22, v23 offset1:1
	v_add_u32_e32 v0, 0x1ce0, v41
	ds_write2_b32 v0, v28, v29 offset1:1
	v_add_u32_e32 v0, 0x1ce8, v41
	ds_write2_b32 v0, v30, v31 offset1:1
	s_waitcnt lgkmcnt(0)
	s_sub_i32 s8, 0, s7
	ds_read2_b32 v[4:5], v40 offset0:33 offset1:41
	ds_read2_b32 v[6:7], v40 offset1:8
	ds_read2_b32 v[8:9], v40 offset0:66 offset1:74
	ds_read2_b32 v[10:11], v40 offset0:99 offset1:107
	ds_read2_b32 v[12:13], v40 offset0:132 offset1:140
	ds_read2_b32 v[14:15], v40 offset0:165 offset1:173
	ds_read2_b32 v[16:17], v40 offset0:198 offset1:206
	ds_read2_b32 v[18:19], v40 offset0:231 offset1:239
	s_add_i32 s8, s8, s1
	v_add_u32_e32 v22, s8, v39
	s_ashr_i32 s7, s6, 31
	v_ashrrev_i32_e32 v23, 31, v22
	v_lshl_add_u64 v[20:21], s[6:7], 1, v[32:33]
	v_lshlrev_b64 v[24:25], 11, v[22:23]
	s_waitcnt lgkmcnt(6)
	v_cvt_pk_bf16_f32 v0, v6, v4
	s_waitcnt lgkmcnt(4)
	v_cvt_pk_bf16_f32 v1, v8, v10
	s_waitcnt lgkmcnt(2)
	v_cvt_pk_bf16_f32 v2, v12, v14
	s_waitcnt lgkmcnt(0)
	v_cvt_pk_bf16_f32 v3, v16, v18
	v_lshl_add_u64 v[24:25], v[20:21], 0, v[24:25]
	v_add_u32_e32 v4, 8, v22
	global_store_dwordx4 v[24:25], v[0:3], off sc1
	s_add_i32 s0, s0, s34
	s_add_i32 s1, s1, s2
	v_cvt_pk_bf16_f32 v0, v7, v5
	v_ashrrev_i32_e32 v5, 31, v4
	v_cvt_pk_bf16_f32 v1, v9, v11
	v_cvt_pk_bf16_f32 v2, v13, v15
	v_cvt_pk_bf16_f32 v3, v17, v19
	v_lshlrev_b64 v[4:5], 11, v[4:5]
	ds_read2_b32 v[6:7], v40 offset0:49 offset1:57
	ds_read2_b32 v[8:9], v40 offset0:16 offset1:24
	ds_read2_b32 v[10:11], v40 offset0:82 offset1:90
	ds_read2_b32 v[12:13], v40 offset0:115 offset1:123
	ds_read2_b32 v[14:15], v40 offset0:148 offset1:156
	ds_read2_b32 v[16:17], v40 offset0:181 offset1:189
	ds_read2_b32 v[18:19], v40 offset0:214 offset1:222
	ds_read2_b32 v[24:25], v40 offset0:247 offset1:255
	v_lshl_add_u64 v[4:5], v[20:21], 0, v[4:5]
	global_store_dwordx4 v[4:5], v[0:3], off sc1
	v_add_u32_e32 v4, 16, v22
	v_ashrrev_i32_e32 v5, 31, v4
	v_lshlrev_b64 v[4:5], 11, v[4:5]
	s_waitcnt lgkmcnt(6)
	v_cvt_pk_bf16_f32 v0, v8, v6
	s_waitcnt lgkmcnt(4)
	v_cvt_pk_bf16_f32 v1, v10, v12
	s_waitcnt lgkmcnt(2)
	v_cvt_pk_bf16_f32 v2, v14, v16
	s_waitcnt lgkmcnt(0)
	v_cvt_pk_bf16_f32 v3, v18, v24
	v_lshl_add_u64 v[4:5], v[20:21], 0, v[4:5]
	global_store_dwordx4 v[4:5], v[0:3], off sc1
	v_add_u32_e32 v4, 24, v22
	v_ashrrev_i32_e32 v5, 31, v4
	v_lshlrev_b64 v[4:5], 11, v[4:5]
	v_cvt_pk_bf16_f32 v0, v9, v7
	v_cvt_pk_bf16_f32 v1, v11, v13
	v_cvt_pk_bf16_f32 v2, v15, v17
	v_cvt_pk_bf16_f32 v3, v19, v25
	v_lshl_add_u64 v[4:5], v[20:21], 0, v[4:5]
	global_store_dwordx4 v[4:5], v[0:3], off sc1
	s_waitcnt lgkmcnt(0)
	s_cmpk_lt_i32 s0, 0x800
	s_cbranch_scc0 .LBB0_334

.LBB0_336:
	s_or_b64 exec, exec, s[8:9]
	s_waitcnt vmcnt(0)
	ds_write2_b32 v41, v0, v1 offset1:1
	ds_write2_b32 v41, v2, v3 offset0:2 offset1:3
	v_add_u32_e32 v0, 0x420, v41
	ds_write2_b32 v0, v8, v9 offset1:1
	v_add_u32_e32 v0, 0x428, v41
	ds_write2_b32 v0, v10, v11 offset1:1
	v_add_u32_e32 v0, 0x840, v41
	ds_write2_b32 v0, v4, v5 offset1:1
	v_add_u32_e32 v0, 0x848, v41
	ds_write2_b32 v0, v6, v7 offset1:1
	v_add_u32_e32 v0, 0xc60, v41
	ds_write2_b32 v0, v16, v17 offset1:1
	v_add_u32_e32 v0, 0xc68, v41
	ds_write2_b32 v0, v18, v19 offset1:1
	v_add_u32_e32 v0, 0x1080, v41
	ds_write2_b32 v0, v12, v13 offset1:1
	v_add_u32_e32 v0, 0x1088, v41
	ds_write2_b32 v0, v14, v15 offset1:1
	v_add_u32_e32 v0, 0x14a0, v41
	ds_write2_b32 v0, v24, v25 offset1:1
	v_add_u32_e32 v0, 0x14a8, v41
	ds_write2_b32 v0, v26, v27 offset1:1
	v_add_u32_e32 v0, 0x18c0, v41
	ds_write2_b32 v0, v20, v21 offset1:1
	v_add_u32_e32 v0, 0x18c8, v41
	ds_write2_b32 v0, v22, v23 offset1:1
	v_add_u32_e32 v0, 0x1ce0, v41
	ds_write2_b32 v0, v28, v29 offset1:1
	v_add_u32_e32 v0, 0x1ce8, v41
	ds_write2_b32 v0, v30, v31 offset1:1
	s_waitcnt lgkmcnt(0)
	s_sub_i32 s8, 0, s7
	ds_read2_b32 v[4:5], v40 offset0:33 offset1:41
	ds_read2_b32 v[6:7], v40 offset1:8
	ds_read2_b32 v[8:9], v40 offset0:66 offset1:74
	ds_read2_b32 v[10:11], v40 offset0:99 offset1:107
	ds_read2_b32 v[12:13], v40 offset0:132 offset1:140
	ds_read2_b32 v[14:15], v40 offset0:165 offset1:173
	ds_read2_b32 v[16:17], v40 offset0:198 offset1:206
	ds_read2_b32 v[18:19], v40 offset0:231 offset1:239
	s_add_i32 s8, s8, s1
	v_add_u32_e32 v22, s8, v39
	s_ashr_i32 s7, s6, 31
	v_ashrrev_i32_e32 v23, 31, v22
	v_lshl_add_u64 v[20:21], s[6:7], 1, v[32:33]
	v_lshlrev_b64 v[24:25], 13, v[22:23]
	s_waitcnt lgkmcnt(6)
	v_cvt_pk_bf16_f32 v0, v6, v4
	s_waitcnt lgkmcnt(4)
	v_cvt_pk_bf16_f32 v1, v8, v10
	s_waitcnt lgkmcnt(2)
	v_cvt_pk_bf16_f32 v2, v12, v14
	s_waitcnt lgkmcnt(0)
	v_cvt_pk_bf16_f32 v3, v16, v18
	v_lshl_add_u64 v[24:25], v[20:21], 0, v[24:25]
	v_add_u32_e32 v4, 8, v22
	global_store_dwordx4 v[24:25], v[0:3], off sc1
	s_add_i32 s0, s0, s34
	s_add_i32 s1, s1, s2
	v_cvt_pk_bf16_f32 v0, v7, v5
	v_ashrrev_i32_e32 v5, 31, v4
	v_cvt_pk_bf16_f32 v1, v9, v11
	v_cvt_pk_bf16_f32 v2, v13, v15
	v_cvt_pk_bf16_f32 v3, v17, v19
	v_lshlrev_b64 v[4:5], 13, v[4:5]
	ds_read2_b32 v[6:7], v40 offset0:49 offset1:57
	ds_read2_b32 v[8:9], v40 offset0:16 offset1:24
	ds_read2_b32 v[10:11], v40 offset0:82 offset1:90
	ds_read2_b32 v[12:13], v40 offset0:115 offset1:123
	ds_read2_b32 v[14:15], v40 offset0:148 offset1:156
	ds_read2_b32 v[16:17], v40 offset0:181 offset1:189
	ds_read2_b32 v[18:19], v40 offset0:214 offset1:222
	ds_read2_b32 v[24:25], v40 offset0:247 offset1:255
	v_lshl_add_u64 v[4:5], v[20:21], 0, v[4:5]
	global_store_dwordx4 v[4:5], v[0:3], off sc1
	v_add_u32_e32 v4, 16, v22
	v_ashrrev_i32_e32 v5, 31, v4
	v_lshlrev_b64 v[4:5], 13, v[4:5]
	s_waitcnt lgkmcnt(6)
	v_cvt_pk_bf16_f32 v0, v8, v6
	s_waitcnt lgkmcnt(4)
	v_cvt_pk_bf16_f32 v1, v10, v12
	s_waitcnt lgkmcnt(2)
	v_cvt_pk_bf16_f32 v2, v14, v16
	s_waitcnt lgkmcnt(0)
	v_cvt_pk_bf16_f32 v3, v18, v24
	v_lshl_add_u64 v[4:5], v[20:21], 0, v[4:5]
	global_store_dwordx4 v[4:5], v[0:3], off sc1
	v_add_u32_e32 v4, 24, v22
	v_ashrrev_i32_e32 v5, 31, v4
	v_lshlrev_b64 v[4:5], 13, v[4:5]
	v_cvt_pk_bf16_f32 v0, v9, v7
	v_cvt_pk_bf16_f32 v1, v11, v13
	v_cvt_pk_bf16_f32 v2, v15, v17
	v_cvt_pk_bf16_f32 v3, v19, v25
	v_lshl_add_u64 v[4:5], v[20:21], 0, v[4:5]
	global_store_dwordx4 v[4:5], v[0:3], off sc1
	s_waitcnt lgkmcnt(0)
	s_cmpk_lt_i32 s0, 0x800
	s_cbranch_scc0 .LBB0_353

.LBB0_425:
	v_lshl_or_b32 v140, s47, 8, v147
	v_lshl_add_u32 v144, s22, 8, v146
	v_ashrrev_i32_e32 v141, 31, v140
	v_or_b32_e32 v174, 16, v144
	v_or_b32_e32 v190, 32, v144
	v_or_b32_e32 v206, 48, v144
	v_lshlrev_b64 v[140:141], 2, v[140:141]
	v_ashrrev_i32_e32 v145, 31, v144
	v_ashrrev_i32_e32 v175, 31, v174
	v_ashrrev_i32_e32 v191, 31, v190
	v_ashrrev_i32_e32 v207, 31, v206
	v_lshl_add_u64 v[142:143], s[66:67], 0, v[140:141]
	v_lshlrev_b64 v[158:159], 12, v[144:145]
	v_lshlrev_b64 v[226:227], 12, v[174:175]
	v_lshlrev_b64 v[228:229], 12, v[190:191]
	v_lshlrev_b64 v[230:231], 12, v[206:207]
	v_lshl_add_u64 v[170:171], v[142:143], 0, v[158:159]
	v_lshl_add_u64 v[186:187], v[142:143], 0, v[226:227]
	v_lshl_add_u64 v[202:203], v[142:143], 0, v[228:229]
	v_lshl_add_u64 v[222:223], v[142:143], 0, v[230:231]
	global_load_dwordx4 v[154:157], v[170:171], off
	global_load_dwordx4 v[162:165], v[170:171], off offset:64
	global_load_dwordx4 v[166:169], v[170:171], off offset:512
	s_nop 0
	global_load_dwordx4 v[170:173], v[170:171], off offset:576
	s_nop 0
	global_load_dwordx4 v[174:177], v[186:187], off
	global_load_dwordx4 v[178:181], v[186:187], off offset:64
	global_load_dwordx4 v[182:185], v[186:187], off offset:512
	s_nop 0
	global_load_dwordx4 v[186:189], v[186:187], off offset:576
	s_nop 0
	global_load_dwordx4 v[190:193], v[202:203], off
	global_load_dwordx4 v[194:197], v[202:203], off offset:64
	global_load_dwordx4 v[198:201], v[202:203], off offset:512
	s_nop 0
	global_load_dwordx4 v[202:205], v[202:203], off offset:576
	s_nop 0
	global_load_dwordx4 v[206:209], v[222:223], off
	global_load_dwordx4 v[214:217], v[222:223], off offset:64
	global_load_dwordx4 v[218:221], v[222:223], off offset:512
	s_nop 0
	global_load_dwordx4 v[222:225], v[222:223], off offset:576
	v_lshl_add_u64 v[158:159], s[36:37], 0, v[158:159]
	v_lshl_add_u64 v[230:231], s[36:37], 0, v[230:231]
	v_lshl_add_u64 v[158:159], v[158:159], 0, v[140:141]
	v_lshl_add_u64 v[226:227], s[36:37], 0, v[226:227]
	v_lshl_add_u64 v[228:229], s[36:37], 0, v[228:229]
	v_lshl_add_u64 v[230:231], v[230:231], 0, v[140:141]
	v_lshl_add_u64 v[226:227], v[226:227], 0, v[140:141]
	v_lshl_add_u64 v[228:229], v[228:229], 0, v[140:141]
	s_andn2_b64 vcc, exec, s[4:5]
	s_mov_b64 s[4:5], -1
	s_waitcnt vmcnt(0)
	v_pk_add_f32 v[126:127], v[126:127], v[156:157]
	v_pk_add_f32 v[124:125], v[124:125], v[154:155]
	v_pk_add_f32 v[122:123], v[122:123], v[164:165]
	v_pk_add_f32 v[96:97], v[96:97], v[170:171]
	v_pk_add_f32 v[80:81], v[80:81], v[214:215]
	v_pk_add_f32 v[120:121], v[120:121], v[162:163]
	v_pk_add_f32 v[66:67], v[66:67], v[224:225]
	v_pk_add_f32 v[64:65], v[64:65], v[222:223]
	v_pk_add_f32 v[106:107], v[106:107], v[168:169]
	v_pk_add_f32 v[104:105], v[104:105], v[166:167]
	v_pk_add_f32 v[98:99], v[98:99], v[172:173]
	v_pk_add_f32 v[118:119], v[118:119], v[176:177]
	v_pk_add_f32 v[116:117], v[116:117], v[174:175]
	v_pk_add_f32 v[114:115], v[114:115], v[180:181]
	v_pk_add_f32 v[112:113], v[112:113], v[178:179]
	v_pk_add_f32 v[90:91], v[90:91], v[184:185]
	v_pk_add_f32 v[88:89], v[88:89], v[182:183]
	v_pk_add_f32 v[86:87], v[86:87], v[188:189]
	v_pk_add_f32 v[84:85], v[84:85], v[186:187]
	v_pk_add_f32 v[110:111], v[110:111], v[192:193]
	v_pk_add_f32 v[108:109], v[108:109], v[190:191]
	v_pk_add_f32 v[102:103], v[102:103], v[196:197]
	v_pk_add_f32 v[100:101], v[100:101], v[194:195]
	v_pk_add_f32 v[78:79], v[78:79], v[200:201]
	v_pk_add_f32 v[76:77], v[76:77], v[198:199]
	v_pk_add_f32 v[74:75], v[74:75], v[204:205]
	v_pk_add_f32 v[72:73], v[72:73], v[202:203]
	v_pk_add_f32 v[94:95], v[94:95], v[208:209]
	v_pk_add_f32 v[92:93], v[92:93], v[206:207]
	v_pk_add_f32 v[82:83], v[82:83], v[216:217]
	global_store_dwordx4 v[158:159], v[124:127], off sc1
	global_store_dwordx4 v[158:159], v[120:123], off offset:64 sc1
	global_store_dwordx4 v[158:159], v[104:107], off offset:512 sc1
	global_store_dwordx4 v[158:159], v[96:99], off offset:576 sc1
	global_store_dwordx4 v[226:227], v[116:119], off sc1
	global_store_dwordx4 v[226:227], v[112:115], off offset:64 sc1
	global_store_dwordx4 v[226:227], v[88:91], off offset:512 sc1
	global_store_dwordx4 v[226:227], v[84:87], off offset:576 sc1
	global_store_dwordx4 v[228:229], v[108:111], off sc1
	global_store_dwordx4 v[228:229], v[100:103], off offset:64 sc1
	global_store_dwordx4 v[228:229], v[76:79], off offset:512 sc1
	global_store_dwordx4 v[228:229], v[72:75], off offset:576 sc1
	global_store_dwordx4 v[230:231], v[92:95], off sc1
	global_store_dwordx4 v[230:231], v[80:83], off offset:64 sc1
	global_store_dwordx4 v[230:231], v[64:67], off offset:576 sc1
	v_add_u32_e32 v96, 0xa0, v144
	v_add_u32_e32 v80, 0x90, v144
	v_add_u32_e32 v64, 0x80, v144
	v_ashrrev_i32_e32 v65, 31, v64
	v_ashrrev_i32_e32 v81, 31, v80
	v_ashrrev_i32_e32 v97, 31, v96
	v_add_u32_e32 v112, 0xb0, v144
	v_pk_add_f32 v[70:71], v[70:71], v[220:221]
	v_pk_add_f32 v[68:69], v[68:69], v[218:219]
	v_lshlrev_b64 v[154:155], 12, v[64:65]
	v_lshlrev_b64 v[156:157], 12, v[80:81]
	v_lshlrev_b64 v[158:159], 12, v[96:97]
	v_ashrrev_i32_e32 v113, 31, v112
	global_store_dwordx4 v[230:231], v[68:71], off offset:512 sc1
	v_lshl_add_u64 v[76:77], v[142:143], 0, v[154:155]
	v_lshl_add_u64 v[92:93], v[142:143], 0, v[156:157]
	v_lshl_add_u64 v[108:109], v[142:143], 0, v[158:159]
	v_lshlrev_b64 v[144:145], 12, v[112:113]
	global_load_dwordx4 v[64:67], v[76:77], off
	global_load_dwordx4 v[68:71], v[76:77], off offset:64
	global_load_dwordx4 v[72:75], v[76:77], off offset:512
	s_nop 0
	global_load_dwordx4 v[76:79], v[76:77], off offset:576
	s_nop 0
	global_load_dwordx4 v[80:83], v[92:93], off
	global_load_dwordx4 v[84:87], v[92:93], off offset:64
	global_load_dwordx4 v[88:91], v[92:93], off offset:512
	s_nop 0
	global_load_dwordx4 v[92:95], v[92:93], off offset:576
	s_nop 0
	global_load_dwordx4 v[96:99], v[108:109], off
	global_load_dwordx4 v[100:103], v[108:109], off offset:64
	global_load_dwordx4 v[104:107], v[108:109], off offset:512
	s_nop 0
	global_load_dwordx4 v[108:111], v[108:109], off offset:576
	v_lshl_add_u64 v[124:125], v[142:143], 0, v[144:145]
	global_load_dwordx4 v[112:115], v[124:125], off
	global_load_dwordx4 v[116:119], v[124:125], off offset:64
	global_load_dwordx4 v[120:123], v[124:125], off offset:512
	s_nop 0
	global_load_dwordx4 v[124:127], v[124:125], off offset:576
	v_lshl_add_u64 v[142:143], s[36:37], 0, v[154:155]
	v_lshl_add_u64 v[154:155], s[36:37], 0, v[156:157]
	v_lshl_add_u64 v[156:157], s[36:37], 0, v[158:159]
	v_lshl_add_u64 v[144:145], s[36:37], 0, v[144:145]
	v_lshl_add_u64 v[142:143], v[142:143], 0, v[140:141]
	v_lshl_add_u64 v[154:155], v[154:155], 0, v[140:141]
	v_lshl_add_u64 v[156:157], v[156:157], 0, v[140:141]
	s_waitcnt vmcnt(15)
	v_pk_add_f32 v[62:63], v[62:63], v[66:67]
	v_pk_add_f32 v[60:61], v[60:61], v[64:65]
	s_waitcnt vmcnt(14)
	v_pk_add_f32 v[58:59], v[58:59], v[70:71]
	v_pk_add_f32 v[56:57], v[56:57], v[68:69]
	s_waitcnt vmcnt(13)
	v_pk_add_f32 v[42:43], v[42:43], v[74:75]
	s_waitcnt vmcnt(4)
	v_pk_add_f32 v[12:13], v[12:13], v[108:109]
	v_pk_add_f32 v[40:41], v[40:41], v[72:73]
	v_pk_add_f32 v[34:35], v[34:35], v[78:79]
	v_pk_add_f32 v[32:33], v[32:33], v[76:77]
	v_pk_add_f32 v[54:55], v[54:55], v[82:83]
	v_pk_add_f32 v[52:53], v[52:53], v[80:81]
	v_pk_add_f32 v[50:51], v[50:51], v[86:87]
	v_pk_add_f32 v[48:49], v[48:49], v[84:85]
	v_pk_add_f32 v[26:27], v[26:27], v[90:91]
	v_pk_add_f32 v[24:25], v[24:25], v[88:89]
	v_pk_add_f32 v[22:23], v[22:23], v[94:95]
	v_pk_add_f32 v[20:21], v[20:21], v[92:93]
	v_pk_add_f32 v[46:47], v[46:47], v[98:99]
	v_pk_add_f32 v[44:45], v[44:45], v[96:97]
	v_pk_add_f32 v[38:39], v[38:39], v[102:103]
	v_pk_add_f32 v[36:37], v[36:37], v[100:101]
	v_pk_add_f32 v[18:19], v[18:19], v[106:107]
	v_pk_add_f32 v[16:17], v[16:17], v[104:105]
	v_pk_add_f32 v[14:15], v[14:15], v[110:111]
	s_waitcnt vmcnt(3)
	v_pk_add_f32 v[30:31], v[30:31], v[114:115]
	v_pk_add_f32 v[28:29], v[28:29], v[112:113]
	global_store_dwordx4 v[142:143], v[60:63], off sc1
	global_store_dwordx4 v[142:143], v[56:59], off offset:64 sc1
	global_store_dwordx4 v[142:143], v[40:43], off offset:512 sc1
	global_store_dwordx4 v[142:143], v[32:35], off offset:576 sc1
	global_store_dwordx4 v[154:155], v[52:55], off sc1
	global_store_dwordx4 v[154:155], v[48:51], off offset:64 sc1
	global_store_dwordx4 v[154:155], v[24:27], off offset:512 sc1
	global_store_dwordx4 v[154:155], v[20:23], off offset:576 sc1
	global_store_dwordx4 v[156:157], v[44:47], off sc1
	global_store_dwordx4 v[156:157], v[36:39], off offset:64 sc1
	global_store_dwordx4 v[156:157], v[16:19], off offset:512 sc1
	global_store_dwordx4 v[156:157], v[12:15], off offset:576 sc1
	s_waitcnt vmcnt(14)
	v_pk_add_f32 v[10:11], v[10:11], v[118:119]
	v_pk_add_f32 v[8:9], v[8:9], v[116:117]
	v_lshl_add_u64 v[12:13], v[144:145], 0, v[140:141]
	s_waitcnt vmcnt(13)
	v_pk_add_f32 v[6:7], v[6:7], v[122:123]
	v_pk_add_f32 v[4:5], v[4:5], v[120:121]
	s_waitcnt vmcnt(12)
	v_pk_add_f32 v[2:3], v[2:3], v[126:127]
	v_pk_add_f32 v[0:1], v[0:1], v[124:125]
	global_store_dwordx4 v[12:13], v[28:31], off sc1
	global_store_dwordx4 v[12:13], v[8:11], off offset:64 sc1
	global_store_dwordx4 v[12:13], v[4:7], off offset:512 sc1
	global_store_dwordx4 v[12:13], v[0:3], off offset:576 sc1
	s_cbranch_vccnz .LBB0_414
	s_andn2_b64 vcc, exec, s[8:9]
	s_cbranch_vccnz .LBB0_413
	s_barrier
	s_branch .LBB0_413

.LBB0_483:
	v_mul_f32_e32 v59, v29, v29
	v_mul_f32_e32 v60, v31, v31
	v_fmac_f32_e32 v59, v28, v28
	v_fmac_f32_e32 v60, v30, v30
	v_add_f32_e32 v59, v59, v60
	v_mul_f32_e32 v60, v25, v25
	v_mul_f32_e32 v61, v27, v27
	v_fmac_f32_e32 v60, v24, v24
	v_fmac_f32_e32 v61, v26, v26
	v_add_f32_e32 v60, v60, v61
	v_add_f32_e32 v59, v59, v60
	v_mul_f32_e32 v60, v21, v21
	v_mul_f32_e32 v61, v23, v23
	v_fmac_f32_e32 v60, v20, v20
	v_fmac_f32_e32 v61, v22, v22
	v_add_f32_e32 v60, v60, v61
	v_add_f32_e32 v59, v60, v59
	v_mul_f32_e32 v60, v17, v17
	v_mul_f32_e32 v61, v19, v19
	v_fmac_f32_e32 v60, v16, v16
	v_fmac_f32_e32 v61, v18, v18
	v_add_f32_e32 v60, v60, v61
	v_add_f32_e32 v59, v60, v59
	ds_bpermute_b32 v60, v52, v59
	v_lshl_add_u64 v[50:51], v[50:51], 0, s[10:11]
	s_waitcnt lgkmcnt(0)
	v_add_f32_e32 v59, v59, v60
	ds_bpermute_b32 v60, v53, v59
	s_waitcnt lgkmcnt(0)
	v_add_f32_e32 v59, v59, v60
	ds_bpermute_b32 v60, v54, v59
	s_waitcnt lgkmcnt(0)
	v_add_f32_e32 v59, v59, v60
	ds_bpermute_b32 v60, v55, v59
	s_waitcnt lgkmcnt(0)
	v_add_f32_e32 v59, v59, v60
	ds_bpermute_b32 v60, v56, v59
	s_waitcnt lgkmcnt(0)
	v_add_f32_e32 v59, v59, v60
	ds_bpermute_b32 v60, v57, v59
	s_waitcnt lgkmcnt(0)
	v_add_f32_e32 v59, v59, v60
	v_fmamk_f32 v59, v59, 0x3a800000, v58
	v_mul_f32_e32 v60, 0x4b800000, v59
	v_cmp_gt_f32_e32 vcc, s0, v59
	s_nop 1
	v_cndmask_b32_e32 v59, v59, v60, vcc
	v_rsq_f32_e32 v59, v59
	s_nop 0
	v_mul_f32_e32 v60, 0x45800000, v59
	v_cndmask_b32_e32 v60, v59, v60, vcc
	v_pk_mul_f32 v[28:29], v[28:29], v[60:61] op_sel_hi:[1,0]
	v_pk_mul_f32 v[30:31], v[30:31], v[60:61] op_sel_hi:[1,0]
	v_pk_mul_f32 v[24:25], v[24:25], v[60:61] op_sel_hi:[1,0]
	v_pk_mul_f32 v[26:27], v[26:27], v[60:61] op_sel_hi:[1,0]
	v_pk_mul_f32 v[20:21], v[20:21], v[60:61] op_sel_hi:[1,0]
	v_pk_mul_f32 v[22:23], v[22:23], v[60:61] op_sel_hi:[1,0]
	v_pk_mul_f32 v[16:17], v[16:17], v[60:61] op_sel_hi:[1,0]
	v_pk_mul_f32 v[18:19], v[18:19], v[60:61] op_sel_hi:[1,0]
	v_pk_mul_f32 v[30:31], v[2:3], v[30:31]
	v_pk_mul_f32 v[28:29], v[0:1], v[28:29]
	v_pk_mul_f32 v[26:27], v[6:7], v[26:27]
	v_pk_mul_f32 v[24:25], v[4:5], v[24:25]
	v_pk_mul_f32 v[22:23], v[10:11], v[22:23]
	v_pk_mul_f32 v[20:21], v[8:9], v[20:21]
	v_pk_mul_f32 v[18:19], v[14:15], v[18:19]
	v_pk_mul_f32 v[16:17], v[12:13], v[16:17]
	v_cvt_pk_bf16_f32 v28, v28, v29
	v_cvt_pk_bf16_f32 v29, v30, v31
	v_cvt_pk_bf16_f32 v24, v24, v25
	v_cvt_pk_bf16_f32 v25, v26, v27
	v_cvt_pk_bf16_f32 v20, v20, v21
	v_cvt_pk_bf16_f32 v21, v22, v23
	v_cvt_pk_bf16_f32 v16, v16, v17
	v_cvt_pk_bf16_f32 v17, v18, v19
	global_store_dwordx2 v[48:49], v[28:29], off sc1
	global_store_dwordx2 v[48:49], v[24:25], off offset:512 sc1
	global_store_dwordx2 v[48:49], v[20:21], off offset:1024 sc1
	global_store_dwordx2 v[48:49], v[16:17], off offset:1536 sc1
	v_lshl_add_u64 v[48:49], v[48:49], 0, s[8:9]
	s_andn2_b64 vcc, exec, s[12:13]
	s_waitcnt vmcnt(7)
	v_mov_b32_e32 v28, v32
	v_mov_b32_e32 v29, v33
	v_mov_b32_e32 v30, v34
	v_mov_b32_e32 v31, v35
	s_waitcnt vmcnt(6)
	v_mov_b32_e32 v24, v36
	v_mov_b32_e32 v25, v37
	v_mov_b32_e32 v26, v38
	v_mov_b32_e32 v27, v39
	s_waitcnt vmcnt(5)
	v_mov_b32_e32 v20, v40
	v_mov_b32_e32 v21, v41
	v_mov_b32_e32 v22, v42
	v_mov_b32_e32 v23, v43
	s_waitcnt vmcnt(4)
	v_mov_b32_e32 v16, v44
	v_mov_b32_e32 v17, v45
	v_mov_b32_e32 v18, v46
	v_mov_b32_e32 v19, v47
	s_cbranch_vccz .LBB0_486

.LBB0_558:
	v_lshl_add_u32 v154, s24, 8, v146
	v_lshl_or_b32 v144, s48, 8, v147
	v_ashrrev_i32_e32 v155, 31, v154
	v_ashrrev_i32_e32 v145, 31, v144
	v_lshlrev_b64 v[156:157], 13, v[154:155]
	v_max_f32_e32 v120, v120, v120
	v_max_f32_e32 v121, v121, v121
	v_lshl_add_u64 v[156:157], s[38:39], 0, v[156:157]
	v_lshlrev_b64 v[158:159], 1, v[144:145]
	v_max_f32_e32 v120, 0, v120
	v_max_f32_e32 v121, 0, v121
	v_lshl_add_u64 v[144:145], v[156:157], 0, v[158:159]
	v_pk_mul_f32 v[156:157], v[120:121], v[120:121]
	v_max_f32_e32 v121, v122, v122
	v_max_f32_e32 v124, v124, v124
	v_max_f32_e32 v125, v125, v125
	v_max_f32_e32 v120, v126, v126
	v_max_f32_e32 v122, 0, v121
	v_max_f32_e32 v121, v127, v127
	v_max_f32_e32 v123, v123, v123
	v_max_f32_e32 v124, 0, v124
	v_max_f32_e32 v125, 0, v125
	v_max_f32_e32 v120, 0, v120
	v_max_f32_e32 v121, 0, v121
	v_max_f32_e32 v123, 0, v123
	v_pk_mul_f32 v[124:125], v[124:125], v[124:125]
	v_pk_mul_f32 v[126:127], v[120:121], v[120:121]
	v_pk_mul_f32 v[162:163], v[122:123], v[122:123]
	v_max_f32_e32 v112, v112, v112
	v_max_f32_e32 v113, v113, v113
	v_cvt_pk_bf16_f32 v120, v124, v125
	v_cvt_pk_bf16_f32 v121, v126, v127
	v_cvt_pk_bf16_f32 v122, v156, v157
	v_cvt_pk_bf16_f32 v123, v162, v163
	v_max_f32_e32 v112, 0, v112
	v_max_f32_e32 v113, 0, v113
	global_store_dwordx4 v[144:145], v[120:123], off sc1
	v_max_f32_e32 v116, v116, v116
	v_max_f32_e32 v117, v117, v117
	v_pk_mul_f32 v[120:121], v[112:113], v[112:113]
	v_max_f32_e32 v113, v114, v114
	v_max_f32_e32 v112, v118, v118
	v_max_f32_e32 v114, 0, v113
	v_max_f32_e32 v113, v119, v119
	v_max_f32_e32 v115, v115, v115
	v_max_f32_e32 v116, 0, v116
	v_max_f32_e32 v117, 0, v117
	v_max_f32_e32 v112, 0, v112
	v_max_f32_e32 v113, 0, v113
	v_max_f32_e32 v115, 0, v115
	v_pk_mul_f32 v[116:117], v[116:117], v[116:117]
	v_pk_mul_f32 v[118:119], v[112:113], v[112:113]
	v_pk_mul_f32 v[122:123], v[114:115], v[114:115]
	v_max_f32_e32 v104, v104, v104
	v_max_f32_e32 v105, v105, v105
	v_cvt_pk_bf16_f32 v112, v116, v117
	v_cvt_pk_bf16_f32 v113, v118, v119
	v_cvt_pk_bf16_f32 v114, v120, v121
	v_cvt_pk_bf16_f32 v115, v122, v123
	v_max_f32_e32 v104, 0, v104
	v_max_f32_e32 v105, 0, v105
	global_store_dwordx4 v[144:145], v[112:115], off offset:256 sc1
	v_max_f32_e32 v108, v108, v108
	v_max_f32_e32 v109, v109, v109
	v_or_b32_e32 v112, 16, v154
	v_pk_mul_f32 v[114:115], v[104:105], v[104:105]
	v_max_f32_e32 v105, v106, v106
	v_ashrrev_i32_e32 v113, 31, v112
	v_max_f32_e32 v104, v110, v110
	v_max_f32_e32 v106, 0, v105
	v_max_f32_e32 v105, v111, v111
	v_max_f32_e32 v107, v107, v107
	v_lshlrev_b64 v[112:113], 13, v[112:113]
	v_max_f32_e32 v108, 0, v108
	v_max_f32_e32 v109, 0, v109
	v_max_f32_e32 v104, 0, v104
	v_max_f32_e32 v105, 0, v105
	v_max_f32_e32 v107, 0, v107
	v_lshl_add_u64 v[112:113], s[38:39], 0, v[112:113]
	v_pk_mul_f32 v[108:109], v[108:109], v[108:109]
	v_pk_mul_f32 v[110:111], v[104:105], v[104:105]
	v_pk_mul_f32 v[116:117], v[106:107], v[106:107]
	v_max_f32_e32 v96, v96, v96
	v_max_f32_e32 v97, v97, v97
	v_lshl_add_u64 v[112:113], v[112:113], 0, v[158:159]
	v_cvt_pk_bf16_f32 v104, v108, v109
	v_cvt_pk_bf16_f32 v105, v110, v111
	v_cvt_pk_bf16_f32 v106, v114, v115
	v_cvt_pk_bf16_f32 v107, v116, v117
	v_max_f32_e32 v96, 0, v96
	v_max_f32_e32 v97, 0, v97
	global_store_dwordx4 v[112:113], v[104:107], off sc1
	v_max_f32_e32 v100, v100, v100
	v_max_f32_e32 v101, v101, v101
	v_pk_mul_f32 v[104:105], v[96:97], v[96:97]
	v_max_f32_e32 v97, v98, v98
	v_max_f32_e32 v96, v102, v102
	v_max_f32_e32 v98, 0, v97
	v_max_f32_e32 v97, v103, v103
	v_max_f32_e32 v99, v99, v99
	v_max_f32_e32 v100, 0, v100
	v_max_f32_e32 v101, 0, v101
	v_max_f32_e32 v96, 0, v96
	v_max_f32_e32 v97, 0, v97
	v_max_f32_e32 v99, 0, v99
	v_pk_mul_f32 v[100:101], v[100:101], v[100:101]
	v_pk_mul_f32 v[102:103], v[96:97], v[96:97]
	v_pk_mul_f32 v[106:107], v[98:99], v[98:99]
	v_max_f32_e32 v88, v88, v88
	v_max_f32_e32 v89, v89, v89
	v_cvt_pk_bf16_f32 v96, v100, v101
	v_cvt_pk_bf16_f32 v97, v102, v103
	v_cvt_pk_bf16_f32 v98, v104, v105
	v_cvt_pk_bf16_f32 v99, v106, v107
	v_max_f32_e32 v88, 0, v88
	v_max_f32_e32 v89, 0, v89
	global_store_dwordx4 v[112:113], v[96:99], off offset:256 sc1
	v_max_f32_e32 v92, v92, v92
	v_max_f32_e32 v93, v93, v93
	v_or_b32_e32 v96, 32, v154
	v_pk_mul_f32 v[98:99], v[88:89], v[88:89]
	v_max_f32_e32 v89, v90, v90
	v_ashrrev_i32_e32 v97, 31, v96
	v_max_f32_e32 v88, v94, v94
	v_max_f32_e32 v90, 0, v89
	v_max_f32_e32 v89, v95, v95
	v_max_f32_e32 v91, v91, v91
	v_lshlrev_b64 v[96:97], 13, v[96:97]
	v_max_f32_e32 v92, 0, v92
	v_max_f32_e32 v93, 0, v93
	v_max_f32_e32 v88, 0, v88
	v_max_f32_e32 v89, 0, v89
	v_max_f32_e32 v91, 0, v91
	v_lshl_add_u64 v[96:97], s[38:39], 0, v[96:97]
	v_pk_mul_f32 v[92:93], v[92:93], v[92:93]
	v_pk_mul_f32 v[94:95], v[88:89], v[88:89]
	v_pk_mul_f32 v[100:101], v[90:91], v[90:91]
	v_max_f32_e32 v80, v80, v80
	v_max_f32_e32 v81, v81, v81
	v_lshl_add_u64 v[96:97], v[96:97], 0, v[158:159]
	v_cvt_pk_bf16_f32 v88, v92, v93
	v_cvt_pk_bf16_f32 v89, v94, v95
	v_cvt_pk_bf16_f32 v90, v98, v99
	v_cvt_pk_bf16_f32 v91, v100, v101
	v_max_f32_e32 v80, 0, v80
	v_max_f32_e32 v81, 0, v81
	global_store_dwordx4 v[96:97], v[88:91], off sc1
	v_max_f32_e32 v84, v84, v84
	v_max_f32_e32 v85, v85, v85
	v_pk_mul_f32 v[88:89], v[80:81], v[80:81]
	v_max_f32_e32 v81, v82, v82
	v_max_f32_e32 v80, v86, v86
	v_max_f32_e32 v82, 0, v81
	v_max_f32_e32 v81, v87, v87
	v_max_f32_e32 v83, v83, v83
	v_max_f32_e32 v84, 0, v84
	v_max_f32_e32 v85, 0, v85
	v_max_f32_e32 v80, 0, v80
	v_max_f32_e32 v81, 0, v81
	v_max_f32_e32 v83, 0, v83
	v_pk_mul_f32 v[84:85], v[84:85], v[84:85]
	v_pk_mul_f32 v[86:87], v[80:81], v[80:81]
	v_pk_mul_f32 v[90:91], v[82:83], v[82:83]
	v_max_f32_e32 v72, v72, v72
	v_max_f32_e32 v73, v73, v73
	v_cvt_pk_bf16_f32 v80, v84, v85
	v_cvt_pk_bf16_f32 v81, v86, v87
	v_cvt_pk_bf16_f32 v82, v88, v89
	v_cvt_pk_bf16_f32 v83, v90, v91
	v_max_f32_e32 v72, 0, v72
	v_max_f32_e32 v73, 0, v73
	global_store_dwordx4 v[96:97], v[80:83], off offset:256 sc1
	v_max_f32_e32 v76, v76, v76
	v_max_f32_e32 v77, v77, v77
	v_or_b32_e32 v80, 48, v154
	v_pk_mul_f32 v[82:83], v[72:73], v[72:73]
	v_max_f32_e32 v73, v74, v74
	v_ashrrev_i32_e32 v81, 31, v80
	v_max_f32_e32 v72, v78, v78
	v_max_f32_e32 v74, 0, v73
	v_max_f32_e32 v73, v79, v79
	v_max_f32_e32 v75, v75, v75
	v_lshlrev_b64 v[80:81], 13, v[80:81]
	v_max_f32_e32 v76, 0, v76
	v_max_f32_e32 v77, 0, v77
	v_max_f32_e32 v72, 0, v72
	v_max_f32_e32 v73, 0, v73
	v_max_f32_e32 v75, 0, v75
	v_lshl_add_u64 v[80:81], s[38:39], 0, v[80:81]
	v_pk_mul_f32 v[76:77], v[76:77], v[76:77]
	v_pk_mul_f32 v[78:79], v[72:73], v[72:73]
	v_pk_mul_f32 v[84:85], v[74:75], v[74:75]
	v_max_f32_e32 v64, v64, v64
	v_max_f32_e32 v65, v65, v65
	v_lshl_add_u64 v[80:81], v[80:81], 0, v[158:159]
	v_cvt_pk_bf16_f32 v72, v76, v77
	v_cvt_pk_bf16_f32 v73, v78, v79
	v_cvt_pk_bf16_f32 v74, v82, v83
	v_cvt_pk_bf16_f32 v75, v84, v85
	v_max_f32_e32 v64, 0, v64
	v_max_f32_e32 v65, 0, v65
	global_store_dwordx4 v[80:81], v[72:75], off sc1
	v_max_f32_e32 v68, v68, v68
	v_max_f32_e32 v69, v69, v69
	v_pk_mul_f32 v[72:73], v[64:65], v[64:65]
	v_max_f32_e32 v65, v66, v66
	v_max_f32_e32 v64, v70, v70
	v_max_f32_e32 v66, 0, v65
	v_max_f32_e32 v65, v71, v71
	v_max_f32_e32 v67, v67, v67
	v_max_f32_e32 v68, 0, v68
	v_max_f32_e32 v69, 0, v69
	v_max_f32_e32 v64, 0, v64
	v_max_f32_e32 v65, 0, v65
	v_max_f32_e32 v67, 0, v67
	v_pk_mul_f32 v[68:69], v[68:69], v[68:69]
	v_pk_mul_f32 v[70:71], v[64:65], v[64:65]
	v_pk_mul_f32 v[74:75], v[66:67], v[66:67]
	v_max_f32_e32 v56, v56, v56
	v_max_f32_e32 v57, v57, v57
	v_cvt_pk_bf16_f32 v64, v68, v69
	v_cvt_pk_bf16_f32 v65, v70, v71
	v_cvt_pk_bf16_f32 v66, v72, v73
	v_cvt_pk_bf16_f32 v67, v74, v75
	v_max_f32_e32 v56, 0, v56
	v_max_f32_e32 v57, 0, v57
	global_store_dwordx4 v[80:81], v[64:67], off offset:256 sc1
	v_max_f32_e32 v60, v60, v60
	v_max_f32_e32 v61, v61, v61
	v_pk_mul_f32 v[66:67], v[56:57], v[56:57]
	v_max_f32_e32 v57, v58, v58
	v_max_f32_e32 v60, 0, v60
	v_max_f32_e32 v61, 0, v61
	v_max_f32_e32 v56, v62, v62
	v_max_f32_e32 v58, 0, v57
	v_max_f32_e32 v57, v63, v63
	v_max_f32_e32 v59, v59, v59
	v_pk_mul_f32 v[60:61], v[60:61], v[60:61]
	v_max_f32_e32 v56, 0, v56
	v_max_f32_e32 v57, 0, v57
	v_max_f32_e32 v59, 0, v59
	s_mov_b32 s17, 0x100000
	v_pk_mul_f32 v[62:63], v[56:57], v[56:57]
	v_pk_mul_f32 v[68:69], v[58:59], v[58:59]
	v_cvt_pk_bf16_f32 v56, v60, v61
	v_add_co_u32_e32 v60, vcc, s17, v144
	v_max_f32_e32 v48, v48, v48
	v_max_f32_e32 v49, v49, v49
	v_cvt_pk_bf16_f32 v57, v62, v63
	v_cvt_pk_bf16_f32 v58, v66, v67
	v_cvt_pk_bf16_f32 v59, v68, v69
	v_addc_co_u32_e32 v61, vcc, 0, v145, vcc
	v_max_f32_e32 v48, 0, v48
	v_max_f32_e32 v49, 0, v49
	global_store_dwordx4 v[60:61], v[56:59], off sc1
	v_max_f32_e32 v52, v52, v52
	v_max_f32_e32 v53, v53, v53
	v_pk_mul_f32 v[56:57], v[48:49], v[48:49]
	v_max_f32_e32 v49, v50, v50
	v_max_f32_e32 v48, v54, v54
	v_max_f32_e32 v50, 0, v49
	v_max_f32_e32 v49, v55, v55
	v_max_f32_e32 v51, v51, v51
	v_max_f32_e32 v52, 0, v52
	v_max_f32_e32 v53, 0, v53
	v_max_f32_e32 v48, 0, v48
	v_max_f32_e32 v49, 0, v49
	v_max_f32_e32 v51, 0, v51
	s_mov_b64 s[48:49], 0x100000
	v_pk_mul_f32 v[52:53], v[52:53], v[52:53]
	v_pk_mul_f32 v[54:55], v[48:49], v[48:49]
	v_pk_mul_f32 v[58:59], v[50:51], v[50:51]
	v_max_f32_e32 v40, v40, v40
	v_max_f32_e32 v41, v41, v41
	v_lshl_add_u64 v[64:65], v[144:145], 0, s[48:49]
	v_cvt_pk_bf16_f32 v48, v52, v53
	v_cvt_pk_bf16_f32 v49, v54, v55
	v_cvt_pk_bf16_f32 v50, v56, v57
	v_cvt_pk_bf16_f32 v51, v58, v59
	v_max_f32_e32 v40, 0, v40
	v_max_f32_e32 v41, 0, v41
	global_store_dwordx4 v[64:65], v[48:51], off offset:256 sc1
	v_max_f32_e32 v44, v44, v44
	v_max_f32_e32 v45, v45, v45
	v_pk_mul_f32 v[50:51], v[40:41], v[40:41]
	v_max_f32_e32 v41, v42, v42
	v_max_f32_e32 v44, 0, v44
	v_max_f32_e32 v45, 0, v45
	v_max_f32_e32 v40, v46, v46
	v_max_f32_e32 v42, 0, v41
	v_max_f32_e32 v41, v47, v47
	v_max_f32_e32 v43, v43, v43
	v_pk_mul_f32 v[44:45], v[44:45], v[44:45]
	v_max_f32_e32 v40, 0, v40
	v_max_f32_e32 v41, 0, v41
	v_max_f32_e32 v43, 0, v43
	s_mov_b32 s17, 0x120000
	v_pk_mul_f32 v[46:47], v[40:41], v[40:41]
	v_pk_mul_f32 v[52:53], v[42:43], v[42:43]
	v_cvt_pk_bf16_f32 v40, v44, v45
	v_add_co_u32_e32 v44, vcc, s17, v144
	v_max_f32_e32 v32, v32, v32
	v_max_f32_e32 v33, v33, v33
	v_cvt_pk_bf16_f32 v41, v46, v47
	v_cvt_pk_bf16_f32 v42, v50, v51
	v_cvt_pk_bf16_f32 v43, v52, v53
	v_addc_co_u32_e32 v45, vcc, 0, v145, vcc
	v_max_f32_e32 v32, 0, v32
	v_max_f32_e32 v33, 0, v33
	global_store_dwordx4 v[44:45], v[40:43], off sc1
	v_max_f32_e32 v36, v36, v36
	v_max_f32_e32 v37, v37, v37
	v_pk_mul_f32 v[40:41], v[32:33], v[32:33]
	v_max_f32_e32 v33, v34, v34
	v_max_f32_e32 v32, v38, v38
	v_max_f32_e32 v34, 0, v33
	v_max_f32_e32 v33, v39, v39
	v_max_f32_e32 v35, v35, v35
	v_max_f32_e32 v36, 0, v36
	v_max_f32_e32 v37, 0, v37
	v_max_f32_e32 v32, 0, v32
	v_max_f32_e32 v33, 0, v33
	v_max_f32_e32 v35, 0, v35
	s_mov_b64 s[48:49], 0x120000
	v_pk_mul_f32 v[36:37], v[36:37], v[36:37]
	v_pk_mul_f32 v[38:39], v[32:33], v[32:33]
	v_pk_mul_f32 v[42:43], v[34:35], v[34:35]
	v_max_f32_e32 v24, v24, v24
	v_max_f32_e32 v25, v25, v25
	v_lshl_add_u64 v[48:49], v[144:145], 0, s[48:49]
	v_cvt_pk_bf16_f32 v32, v36, v37
	v_cvt_pk_bf16_f32 v33, v38, v39
	v_cvt_pk_bf16_f32 v34, v40, v41
	v_cvt_pk_bf16_f32 v35, v42, v43
	v_max_f32_e32 v24, 0, v24
	v_max_f32_e32 v25, 0, v25
	global_store_dwordx4 v[48:49], v[32:35], off offset:256 sc1
	v_max_f32_e32 v28, v28, v28
	v_max_f32_e32 v29, v29, v29
	v_pk_mul_f32 v[34:35], v[24:25], v[24:25]
	v_max_f32_e32 v25, v26, v26
	v_max_f32_e32 v28, 0, v28
	v_max_f32_e32 v29, 0, v29
	v_max_f32_e32 v24, v30, v30
	v_max_f32_e32 v26, 0, v25
	v_max_f32_e32 v25, v31, v31
	v_max_f32_e32 v27, v27, v27
	v_pk_mul_f32 v[28:29], v[28:29], v[28:29]
	v_max_f32_e32 v24, 0, v24
	v_max_f32_e32 v25, 0, v25
	v_max_f32_e32 v27, 0, v27
	s_mov_b32 s17, 0x140000
	v_pk_mul_f32 v[30:31], v[24:25], v[24:25]
	v_pk_mul_f32 v[36:37], v[26:27], v[26:27]
	v_cvt_pk_bf16_f32 v24, v28, v29
	v_add_co_u32_e32 v28, vcc, s17, v144
	v_max_f32_e32 v16, v16, v16
	v_max_f32_e32 v17, v17, v17
	v_cvt_pk_bf16_f32 v25, v30, v31
	v_cvt_pk_bf16_f32 v26, v34, v35
	v_cvt_pk_bf16_f32 v27, v36, v37
	v_addc_co_u32_e32 v29, vcc, 0, v145, vcc
	v_max_f32_e32 v16, 0, v16
	v_max_f32_e32 v17, 0, v17
	global_store_dwordx4 v[28:29], v[24:27], off sc1
	v_max_f32_e32 v20, v20, v20
	v_max_f32_e32 v21, v21, v21
	v_pk_mul_f32 v[24:25], v[16:17], v[16:17]
	v_max_f32_e32 v17, v18, v18
	v_max_f32_e32 v16, v22, v22
	v_max_f32_e32 v18, 0, v17
	v_max_f32_e32 v17, v23, v23
	v_max_f32_e32 v19, v19, v19
	v_max_f32_e32 v20, 0, v20
	v_max_f32_e32 v21, 0, v21
	v_max_f32_e32 v16, 0, v16
	v_max_f32_e32 v17, 0, v17
	v_max_f32_e32 v19, 0, v19
	s_mov_b64 s[48:49], 0x140000
	v_pk_mul_f32 v[20:21], v[20:21], v[20:21]
	v_pk_mul_f32 v[22:23], v[16:17], v[16:17]
	v_pk_mul_f32 v[26:27], v[18:19], v[18:19]
	v_max_f32_e32 v8, v8, v8
	v_max_f32_e32 v9, v9, v9
	v_lshl_add_u64 v[32:33], v[144:145], 0, s[48:49]
	v_cvt_pk_bf16_f32 v16, v20, v21
	v_cvt_pk_bf16_f32 v17, v22, v23
	v_cvt_pk_bf16_f32 v18, v24, v25
	v_cvt_pk_bf16_f32 v19, v26, v27
	v_max_f32_e32 v8, 0, v8
	v_max_f32_e32 v9, 0, v9
	global_store_dwordx4 v[32:33], v[16:19], off offset:256 sc1
	v_max_f32_e32 v12, v12, v12
	v_max_f32_e32 v13, v13, v13
	v_pk_mul_f32 v[18:19], v[8:9], v[8:9]
	v_max_f32_e32 v9, v10, v10
	v_max_f32_e32 v12, 0, v12
	v_max_f32_e32 v13, 0, v13
	v_max_f32_e32 v8, v14, v14
	v_max_f32_e32 v10, 0, v9
	v_max_f32_e32 v9, v15, v15
	v_max_f32_e32 v11, v11, v11
	v_pk_mul_f32 v[12:13], v[12:13], v[12:13]
	v_max_f32_e32 v8, 0, v8
	v_max_f32_e32 v9, 0, v9
	v_max_f32_e32 v11, 0, v11
	v_pk_mul_f32 v[14:15], v[8:9], v[8:9]
	v_pk_mul_f32 v[20:21], v[10:11], v[10:11]
	v_cvt_pk_bf16_f32 v8, v12, v13
	v_add_co_u32_e32 v12, vcc, s45, v144
	v_max_f32_e32 v0, v0, v0
	v_max_f32_e32 v1, v1, v1
	v_cvt_pk_bf16_f32 v9, v14, v15
	v_cvt_pk_bf16_f32 v10, v18, v19
	v_cvt_pk_bf16_f32 v11, v20, v21
	v_addc_co_u32_e32 v13, vcc, 0, v145, vcc
	v_max_f32_e32 v0, 0, v0
	v_max_f32_e32 v1, 0, v1
	global_store_dwordx4 v[12:13], v[8:11], off sc1
	v_max_f32_e32 v4, v4, v4
	v_max_f32_e32 v5, v5, v5
	v_pk_mul_f32 v[8:9], v[0:1], v[0:1]
	v_max_f32_e32 v1, v2, v2
	v_max_f32_e32 v0, v6, v6
	v_max_f32_e32 v2, 0, v1
	v_max_f32_e32 v1, v7, v7
	v_max_f32_e32 v3, v3, v3
	v_max_f32_e32 v4, 0, v4
	v_max_f32_e32 v5, 0, v5
	v_max_f32_e32 v0, 0, v0
	v_max_f32_e32 v1, 0, v1
	v_max_f32_e32 v3, 0, v3
	s_mov_b64 s[48:49], 0x160000
	v_pk_mul_f32 v[4:5], v[4:5], v[4:5]
	v_pk_mul_f32 v[6:7], v[0:1], v[0:1]
	v_pk_mul_f32 v[10:11], v[2:3], v[2:3]
	v_lshl_add_u64 v[16:17], v[144:145], 0, s[48:49]
	v_cvt_pk_bf16_f32 v0, v4, v5
	v_cvt_pk_bf16_f32 v1, v6, v7
	v_cvt_pk_bf16_f32 v2, v8, v9
	v_cvt_pk_bf16_f32 v3, v10, v11
	s_andn2_b64 vcc, exec, s[4:5]
	s_mov_b64 s[4:5], -1
	global_store_dwordx4 v[16:17], v[0:3], off offset:256 sc1
	s_cbranch_vccnz .LBB0_547
	s_andn2_b64 vcc, exec, s[8:9]
	s_cbranch_vccnz .LBB0_546
	s_barrier
	s_branch .LBB0_546

.LBB0_634:
	v_lshl_or_b32 v140, s25, 8, v149
	v_ashrrev_i32_e32 v141, 31, v140
	v_lshl_add_u32 v144, s24, 8, v148
	v_lshlrev_b64 v[140:141], 2, v[140:141]
	v_ashrrev_i32_e32 v145, 31, v144
	v_lshl_add_u64 v[142:143], s[36:37], 0, v[140:141]
	v_lshlrev_b64 v[146:147], 12, v[144:145]
	v_or_b32_e32 v174, 16, v144
	v_lshl_add_u64 v[170:171], v[142:143], 0, v[146:147]
	v_ashrrev_i32_e32 v175, 31, v174
	global_load_dwordx4 v[156:159], v[170:171], off
	global_load_dwordx4 v[162:165], v[170:171], off offset:64
	global_load_dwordx4 v[166:169], v[170:171], off offset:512
	s_nop 0
	global_load_dwordx4 v[170:173], v[170:171], off offset:576
	v_lshlrev_b64 v[226:227], 12, v[174:175]
	v_or_b32_e32 v190, 32, v144
	v_lshl_add_u64 v[186:187], v[142:143], 0, v[226:227]
	v_ashrrev_i32_e32 v191, 31, v190
	v_or_b32_e32 v206, 48, v144
	global_load_dwordx4 v[174:177], v[186:187], off
	global_load_dwordx4 v[178:181], v[186:187], off offset:64
	global_load_dwordx4 v[182:185], v[186:187], off offset:512
	s_nop 0
	global_load_dwordx4 v[186:189], v[186:187], off offset:576
	v_lshlrev_b64 v[228:229], 12, v[190:191]
	v_ashrrev_i32_e32 v207, 31, v206
	v_lshl_add_u64 v[202:203], v[142:143], 0, v[228:229]
	v_lshlrev_b64 v[230:231], 12, v[206:207]
	global_load_dwordx4 v[190:193], v[202:203], off
	global_load_dwordx4 v[194:197], v[202:203], off offset:64
	global_load_dwordx4 v[198:201], v[202:203], off offset:512
	s_nop 0
	global_load_dwordx4 v[202:205], v[202:203], off offset:576
	v_lshl_add_u64 v[222:223], v[142:143], 0, v[230:231]
	global_load_dwordx4 v[206:209], v[222:223], off
	global_load_dwordx4 v[214:217], v[222:223], off offset:64
	global_load_dwordx4 v[218:221], v[222:223], off offset:512
	s_nop 0
	global_load_dwordx4 v[222:225], v[222:223], off offset:576
	v_lshl_add_u64 v[146:147], s[36:37], 0, v[146:147]
	v_lshl_add_u64 v[146:147], v[146:147], 0, v[140:141]
	s_mov_b64 s[24:25], -1
	s_andn2_b64 vcc, exec, s[6:7]
	s_waitcnt vmcnt(0)
	v_pk_add_f32 v[126:127], v[126:127], v[158:159]
	v_pk_add_f32 v[124:125], v[124:125], v[156:157]
	v_pk_add_f32 v[110:111], v[110:111], v[168:169]
	v_pk_add_f32 v[108:109], v[108:109], v[166:167]
	global_store_dwordx4 v[146:147], v[108:111], off offset:512 sc1
	v_pk_add_f32 v[102:103], v[102:103], v[172:173]
	v_pk_add_f32 v[100:101], v[100:101], v[170:171]
	v_lshl_add_u64 v[108:109], s[36:37], 0, v[226:227]
	v_lshl_add_u64 v[108:109], v[108:109], 0, v[140:141]
	v_pk_add_f32 v[94:95], v[94:95], v[184:185]
	v_pk_add_f32 v[92:93], v[92:93], v[182:183]
	global_store_dwordx4 v[108:109], v[92:95], off offset:512 sc1
	v_pk_add_f32 v[86:87], v[86:87], v[188:189]
	v_pk_add_f32 v[78:79], v[78:79], v[200:201]
	v_lshl_add_u64 v[92:93], s[36:37], 0, v[228:229]
	v_lshl_add_u64 v[92:93], v[92:93], 0, v[140:141]
	v_pk_add_f32 v[76:77], v[76:77], v[198:199]
	global_store_dwordx4 v[92:93], v[76:79], off offset:512 sc1
	v_pk_add_f32 v[66:67], v[66:67], v[224:225]
	v_pk_add_f32 v[64:65], v[64:65], v[222:223]
	v_lshl_add_u64 v[76:77], s[36:37], 0, v[230:231]
	v_lshl_add_u64 v[76:77], v[76:77], 0, v[140:141]
	v_pk_add_f32 v[84:85], v[84:85], v[186:187]
	v_pk_add_f32 v[74:75], v[74:75], v[204:205]
	v_pk_add_f32 v[72:73], v[72:73], v[202:203]
	global_store_dwordx4 v[76:77], v[64:67], off offset:576 sc1
	v_pk_add_f32 v[122:123], v[122:123], v[164:165]
	v_pk_add_f32 v[120:121], v[120:121], v[162:163]
	v_add_u32_e32 v64, 0x80, v144
	global_store_dwordx4 v[146:147], v[100:103], off offset:576 sc1
	global_store_dwordx4 v[108:109], v[84:87], off offset:576 sc1
	global_store_dwordx4 v[92:93], v[72:75], off offset:576 sc1
	v_pk_add_f32 v[102:103], v[118:119], v[176:177]
	v_pk_add_f32 v[100:101], v[116:117], v[174:175]
	v_pk_add_f32 v[86:87], v[106:107], v[192:193]
	v_pk_add_f32 v[84:85], v[104:105], v[190:191]
	v_pk_add_f32 v[74:75], v[90:91], v[208:209]
	v_pk_add_f32 v[72:73], v[88:89], v[206:207]
	v_ashrrev_i32_e32 v65, 31, v64
	global_store_dwordx4 v[146:147], v[124:127], off sc1
	global_store_dwordx4 v[146:147], v[120:123], off offset:64 sc1
	global_store_dwordx4 v[108:109], v[100:103], off sc1
	global_store_dwordx4 v[92:93], v[84:87], off sc1
	global_store_dwordx4 v[76:77], v[72:75], off sc1
	v_pk_add_f32 v[102:103], v[114:115], v[180:181]
	v_pk_add_f32 v[100:101], v[112:113], v[178:179]
	v_pk_add_f32 v[86:87], v[98:99], v[196:197]
	v_pk_add_f32 v[84:85], v[96:97], v[194:195]
	v_pk_add_f32 v[74:75], v[82:83], v[216:217]
	v_pk_add_f32 v[72:73], v[80:81], v[214:215]
	v_pk_add_f32 v[70:71], v[70:71], v[220:221]
	v_pk_add_f32 v[68:69], v[68:69], v[218:219]
	v_lshlrev_b64 v[146:147], 12, v[64:65]
	global_store_dwordx4 v[108:109], v[100:103], off offset:64 sc1
	global_store_dwordx4 v[92:93], v[84:87], off offset:64 sc1
	global_store_dwordx4 v[76:77], v[72:75], off offset:64 sc1
	global_store_dwordx4 v[76:77], v[68:71], off offset:512 sc1
	v_lshl_add_u64 v[64:65], v[142:143], 0, v[146:147]
	global_load_dwordx4 v[108:111], v[64:65], off
	global_load_dwordx4 v[104:107], v[64:65], off offset:64
	global_load_dwordx4 v[96:99], v[64:65], off offset:512
	global_load_dwordx4 v[84:87], v[64:65], off offset:576
	v_add_u32_e32 v64, 0x90, v144
	v_ashrrev_i32_e32 v65, 31, v64
	v_lshlrev_b64 v[126:127], 12, v[64:65]
	v_lshl_add_u64 v[64:65], v[142:143], 0, v[126:127]
	global_load_dwordx4 v[100:103], v[64:65], off
	global_load_dwordx4 v[88:91], v[64:65], off offset:64
	global_load_dwordx4 v[80:83], v[64:65], off offset:512
	global_load_dwordx4 v[72:75], v[64:65], off offset:576
	v_add_u32_e32 v64, 0xa0, v144
	v_ashrrev_i32_e32 v65, 31, v64
	v_lshlrev_b64 v[124:125], 12, v[64:65]
	v_add_u32_e32 v112, 0xb0, v144
	v_lshl_add_u64 v[64:65], v[142:143], 0, v[124:125]
	v_ashrrev_i32_e32 v113, 31, v112
	global_load_dwordx4 v[92:95], v[64:65], off
	global_load_dwordx4 v[76:79], v[64:65], off offset:64
	global_load_dwordx4 v[68:71], v[64:65], off offset:512
	s_nop 0
	global_load_dwordx4 v[64:67], v[64:65], off offset:576
	v_lshlrev_b64 v[144:145], 12, v[112:113]
	v_lshl_add_u64 v[116:117], v[142:143], 0, v[144:145]
	global_load_dwordx4 v[112:115], v[116:117], off
	global_load_dwordx4 v[156:159], v[116:117], off offset:64
	global_load_dwordx4 v[120:123], v[116:117], off offset:512
	s_nop 0
	global_load_dwordx4 v[116:119], v[116:117], off offset:576
	s_waitcnt vmcnt(15)
	v_pk_add_f32 v[60:61], v[60:61], v[108:109]
	v_lshl_add_u64 v[108:109], s[36:37], 0, v[146:147]
	v_lshl_add_u64 v[108:109], v[108:109], 0, v[140:141]
	s_waitcnt vmcnt(13)
	v_pk_add_f32 v[50:51], v[50:51], v[98:99]
	v_pk_add_f32 v[48:49], v[48:49], v[96:97]
	global_store_dwordx4 v[108:109], v[48:51], off offset:512 sc1
	s_waitcnt vmcnt(13)
	v_pk_add_f32 v[42:43], v[42:43], v[86:87]
	s_waitcnt vmcnt(10)
	v_pk_add_f32 v[34:35], v[34:35], v[82:83]
	v_lshl_add_u64 v[48:49], s[36:37], 0, v[126:127]
	v_lshl_add_u64 v[48:49], v[48:49], 0, v[140:141]
	v_pk_add_f32 v[32:33], v[32:33], v[80:81]
	global_store_dwordx4 v[48:49], v[32:35], off offset:512 sc1
	v_pk_add_f32 v[40:41], v[40:41], v[84:85]
	s_waitcnt vmcnt(10)
	v_pk_add_f32 v[26:27], v[26:27], v[74:75]
	v_lshl_add_u64 v[32:33], s[36:37], 0, v[124:125]
	v_lshl_add_u64 v[32:33], v[32:33], 0, v[140:141]
	s_waitcnt vmcnt(7)
	v_pk_add_f32 v[18:19], v[18:19], v[70:71]
	v_pk_add_f32 v[16:17], v[16:17], v[68:69]
	v_pk_add_f32 v[24:25], v[24:25], v[72:73]
	global_store_dwordx4 v[32:33], v[16:19], off offset:512 sc1
	s_waitcnt vmcnt(7)
	v_pk_add_f32 v[10:11], v[10:11], v[66:67]
	v_pk_add_f32 v[8:9], v[8:9], v[64:65]
	v_lshl_add_u64 v[16:17], s[36:37], 0, v[144:145]
	global_store_dwordx4 v[108:109], v[40:43], off offset:576 sc1
	global_store_dwordx4 v[48:49], v[24:27], off offset:576 sc1
	global_store_dwordx4 v[32:33], v[8:11], off offset:576 sc1
	v_pk_add_f32 v[42:43], v[54:55], v[102:103]
	v_pk_add_f32 v[40:41], v[52:53], v[100:101]
	v_pk_add_f32 v[26:27], v[38:39], v[94:95]
	v_pk_add_f32 v[24:25], v[36:37], v[92:93]
	s_waitcnt vmcnt(9)
	v_pk_add_f32 v[10:11], v[22:23], v[114:115]
	v_pk_add_f32 v[8:9], v[20:21], v[112:113]
	v_lshl_add_u64 v[16:17], v[16:17], 0, v[140:141]
	v_pk_add_f32 v[62:63], v[62:63], v[110:111]
	v_pk_add_f32 v[58:59], v[58:59], v[106:107]
	v_pk_add_f32 v[56:57], v[56:57], v[104:105]
	global_store_dwordx4 v[48:49], v[40:43], off sc1
	global_store_dwordx4 v[32:33], v[24:27], off sc1
	global_store_dwordx4 v[16:17], v[8:11], off sc1
	v_pk_add_f32 v[42:43], v[46:47], v[90:91]
	v_pk_add_f32 v[40:41], v[44:45], v[88:89]
	v_pk_add_f32 v[26:27], v[30:31], v[78:79]
	v_pk_add_f32 v[24:25], v[28:29], v[76:77]
	s_waitcnt vmcnt(11)
	v_pk_add_f32 v[10:11], v[14:15], v[158:159]
	v_pk_add_f32 v[8:9], v[12:13], v[156:157]
	s_waitcnt vmcnt(10)
	v_pk_add_f32 v[6:7], v[6:7], v[122:123]
	v_pk_add_f32 v[4:5], v[4:5], v[120:121]
	s_waitcnt vmcnt(9)
	v_pk_add_f32 v[2:3], v[2:3], v[118:119]
	v_pk_add_f32 v[0:1], v[0:1], v[116:117]
	global_store_dwordx4 v[108:109], v[60:63], off sc1
	global_store_dwordx4 v[108:109], v[56:59], off offset:64 sc1
	global_store_dwordx4 v[48:49], v[40:43], off offset:64 sc1
	global_store_dwordx4 v[32:33], v[24:27], off offset:64 sc1
	global_store_dwordx4 v[16:17], v[8:11], off offset:64 sc1
	global_store_dwordx4 v[16:17], v[4:7], off offset:512 sc1
	global_store_dwordx4 v[16:17], v[0:3], off offset:576 sc1
	s_cbranch_vccnz .LBB0_623
	s_andn2_b64 vcc, exec, s[8:9]
	s_cbranch_vccnz .LBB0_622
	s_barrier
	s_branch .LBB0_622

.LBB0_692:
	v_mul_f32_e32 v59, v29, v29
	v_mul_f32_e32 v60, v31, v31
	v_fmac_f32_e32 v59, v28, v28
	v_fmac_f32_e32 v60, v30, v30
	v_add_f32_e32 v59, v59, v60
	v_mul_f32_e32 v60, v25, v25
	v_mul_f32_e32 v61, v27, v27
	v_fmac_f32_e32 v60, v24, v24
	v_fmac_f32_e32 v61, v26, v26
	v_add_f32_e32 v60, v60, v61
	v_add_f32_e32 v59, v59, v60
	v_mul_f32_e32 v60, v21, v21
	v_mul_f32_e32 v61, v23, v23
	v_fmac_f32_e32 v60, v20, v20
	v_fmac_f32_e32 v61, v22, v22
	v_add_f32_e32 v60, v60, v61
	v_add_f32_e32 v59, v60, v59
	v_mul_f32_e32 v60, v17, v17
	v_mul_f32_e32 v61, v19, v19
	v_fmac_f32_e32 v60, v16, v16
	v_fmac_f32_e32 v61, v18, v18
	v_add_f32_e32 v60, v60, v61
	v_add_f32_e32 v59, v60, v59
	ds_bpermute_b32 v60, v52, v59
	v_lshl_add_u64 v[50:51], v[50:51], 0, s[12:13]
	s_waitcnt lgkmcnt(0)
	v_add_f32_e32 v59, v59, v60
	ds_bpermute_b32 v60, v53, v59
	s_waitcnt lgkmcnt(0)
	v_add_f32_e32 v59, v59, v60
	ds_bpermute_b32 v60, v54, v59
	s_waitcnt lgkmcnt(0)
	v_add_f32_e32 v59, v59, v60
	ds_bpermute_b32 v60, v55, v59
	s_waitcnt lgkmcnt(0)
	v_add_f32_e32 v59, v59, v60
	ds_bpermute_b32 v60, v56, v59
	s_waitcnt lgkmcnt(0)
	v_add_f32_e32 v59, v59, v60
	ds_bpermute_b32 v60, v57, v59
	s_waitcnt lgkmcnt(0)
	v_add_f32_e32 v59, v59, v60
	v_fmamk_f32 v59, v59, 0x3a800000, v58
	v_mul_f32_e32 v60, 0x4b800000, v59
	v_cmp_gt_f32_e32 vcc, s0, v59
	s_nop 1
	v_cndmask_b32_e32 v59, v59, v60, vcc
	v_rsq_f32_e32 v59, v59
	s_nop 0
	v_mul_f32_e32 v60, 0x45800000, v59
	v_cndmask_b32_e32 v60, v59, v60, vcc
	v_pk_mul_f32 v[28:29], v[28:29], v[60:61] op_sel_hi:[1,0]
	v_pk_mul_f32 v[30:31], v[30:31], v[60:61] op_sel_hi:[1,0]
	v_pk_mul_f32 v[24:25], v[24:25], v[60:61] op_sel_hi:[1,0]
	v_pk_mul_f32 v[26:27], v[26:27], v[60:61] op_sel_hi:[1,0]
	v_pk_mul_f32 v[20:21], v[20:21], v[60:61] op_sel_hi:[1,0]
	v_pk_mul_f32 v[22:23], v[22:23], v[60:61] op_sel_hi:[1,0]
	v_pk_mul_f32 v[16:17], v[16:17], v[60:61] op_sel_hi:[1,0]
	v_pk_mul_f32 v[18:19], v[18:19], v[60:61] op_sel_hi:[1,0]
	v_pk_mul_f32 v[30:31], v[2:3], v[30:31]
	v_pk_mul_f32 v[28:29], v[0:1], v[28:29]
	v_pk_mul_f32 v[26:27], v[6:7], v[26:27]
	v_pk_mul_f32 v[24:25], v[4:5], v[24:25]
	v_pk_mul_f32 v[22:23], v[10:11], v[22:23]
	v_pk_mul_f32 v[20:21], v[8:9], v[20:21]
	v_pk_mul_f32 v[18:19], v[14:15], v[18:19]
	v_pk_mul_f32 v[16:17], v[12:13], v[16:17]
	v_cvt_pk_bf16_f32 v28, v28, v29
	v_cvt_pk_bf16_f32 v29, v30, v31
	v_cvt_pk_bf16_f32 v24, v24, v25
	v_cvt_pk_bf16_f32 v25, v26, v27
	v_cvt_pk_bf16_f32 v20, v20, v21
	v_cvt_pk_bf16_f32 v21, v22, v23
	v_cvt_pk_bf16_f32 v16, v16, v17
	v_cvt_pk_bf16_f32 v17, v18, v19
	global_store_dwordx2 v[48:49], v[28:29], off sc1
	global_store_dwordx2 v[48:49], v[24:25], off offset:512 sc1
	global_store_dwordx2 v[48:49], v[20:21], off offset:1024 sc1
	global_store_dwordx2 v[48:49], v[16:17], off offset:1536 sc1
	v_lshl_add_u64 v[48:49], v[48:49], 0, s[8:9]
	s_andn2_b64 vcc, exec, s[14:15]
	s_waitcnt vmcnt(7)
	v_mov_b32_e32 v28, v32
	v_mov_b32_e32 v29, v33
	v_mov_b32_e32 v30, v34
	v_mov_b32_e32 v31, v35
	s_waitcnt vmcnt(6)
	v_mov_b32_e32 v24, v36
	v_mov_b32_e32 v25, v37
	v_mov_b32_e32 v26, v38
	v_mov_b32_e32 v27, v39
	s_waitcnt vmcnt(5)
	v_mov_b32_e32 v20, v40
	v_mov_b32_e32 v21, v41
	v_mov_b32_e32 v22, v42
	v_mov_b32_e32 v23, v43
	s_waitcnt vmcnt(4)
	v_mov_b32_e32 v16, v44
	v_mov_b32_e32 v17, v45
	v_mov_b32_e32 v18, v46
	v_mov_b32_e32 v19, v47
	s_cbranch_vccz .LBB0_695

.LBB0_699:
	s_or_b64 exec, exec, s[16:17]
	s_waitcnt vmcnt(0)
	ds_write2_b32 v43, v4, v5 offset1:1
	ds_write2_b32 v43, v6, v7 offset0:2 offset1:3
	v_add_u32_e32 v4, 0x420, v43
	ds_write2_b32 v4, v0, v1 offset1:1
	v_add_u32_e32 v0, 0x428, v43
	ds_write2_b32 v0, v2, v3 offset1:1
	v_add_u32_e32 v0, 0x840, v43
	ds_write2_b32 v0, v12, v13 offset1:1
	v_add_u32_e32 v0, 0x848, v43
	ds_write2_b32 v0, v14, v15 offset1:1
	v_add_u32_e32 v0, 0xc60, v43
	ds_write2_b32 v0, v8, v9 offset1:1
	v_add_u32_e32 v0, 0xc68, v43
	ds_write2_b32 v0, v10, v11 offset1:1
	v_add_u32_e32 v0, 0x1080, v43
	ds_write2_b32 v0, v20, v21 offset1:1
	v_add_u32_e32 v0, 0x1088, v43
	ds_write2_b32 v0, v22, v23 offset1:1
	v_add_u32_e32 v0, 0x14a0, v43
	ds_write2_b32 v0, v16, v17 offset1:1
	v_add_u32_e32 v0, 0x14a8, v43
	ds_write2_b32 v0, v18, v19 offset1:1
	v_add_u32_e32 v0, 0x18c0, v43
	ds_write2_b32 v0, v28, v29 offset1:1
	v_add_u32_e32 v0, 0x18c8, v43
	ds_write2_b32 v0, v30, v31 offset1:1
	v_add_u32_e32 v0, 0x1ce0, v43
	ds_write2_b32 v0, v24, v25 offset1:1
	v_add_u32_e32 v0, 0x1ce8, v43
	ds_write2_b32 v0, v26, v27 offset1:1
	s_waitcnt lgkmcnt(0)
	s_sub_i32 s5, 0, s5
	ds_read2_b32 v[4:5], v32 offset0:33 offset1:41
	ds_read2_b32 v[6:7], v32 offset1:8
	ds_read2_b32 v[8:9], v32 offset0:66 offset1:74
	ds_read2_b32 v[10:11], v32 offset0:99 offset1:107
	ds_read2_b32 v[12:13], v32 offset0:132 offset1:140
	ds_read2_b32 v[14:15], v32 offset0:165 offset1:173
	ds_read2_b32 v[16:17], v32 offset0:198 offset1:206
	ds_read2_b32 v[18:19], v32 offset0:231 offset1:239
	s_add_i32 s5, s5, s4
	v_add_u32_e32 v22, s5, v42
	s_ashr_i32 s15, s14, 31
	v_ashrrev_i32_e32 v23, 31, v22
	v_lshl_add_u64 v[20:21], s[14:15], 1, v[34:35]
	v_lshlrev_b64 v[24:25], 9, v[22:23]
	s_waitcnt lgkmcnt(6)
	v_cvt_pk_bf16_f32 v0, v6, v4
	s_waitcnt lgkmcnt(4)
	v_cvt_pk_bf16_f32 v1, v8, v10
	s_waitcnt lgkmcnt(2)
	v_cvt_pk_bf16_f32 v2, v12, v14
	s_waitcnt lgkmcnt(0)
	v_cvt_pk_bf16_f32 v3, v16, v18
	v_lshl_add_u64 v[24:25], v[20:21], 0, v[24:25]
	v_add_u32_e32 v4, 8, v22
	global_store_dwordx4 v[24:25], v[0:3], off sc1
	s_add_i32 s3, s3, s34
	v_add_u32_e32 v42, s51, v42
	v_cvt_pk_bf16_f32 v0, v7, v5
	v_ashrrev_i32_e32 v5, 31, v4
	v_cvt_pk_bf16_f32 v1, v9, v11
	v_cvt_pk_bf16_f32 v2, v13, v15
	v_cvt_pk_bf16_f32 v3, v17, v19
	v_lshlrev_b64 v[4:5], 9, v[4:5]
	ds_read2_b32 v[6:7], v32 offset0:49 offset1:57
	ds_read2_b32 v[8:9], v32 offset0:16 offset1:24
	ds_read2_b32 v[10:11], v32 offset0:82 offset1:90
	ds_read2_b32 v[12:13], v32 offset0:115 offset1:123
	ds_read2_b32 v[14:15], v32 offset0:148 offset1:156
	ds_read2_b32 v[16:17], v32 offset0:181 offset1:189
	ds_read2_b32 v[18:19], v32 offset0:214 offset1:222
	ds_read2_b32 v[24:25], v32 offset0:247 offset1:255
	v_lshl_add_u64 v[4:5], v[20:21], 0, v[4:5]
	global_store_dwordx4 v[4:5], v[0:3], off sc1
	v_add_u32_e32 v4, 16, v22
	v_ashrrev_i32_e32 v5, 31, v4
	v_lshlrev_b64 v[4:5], 9, v[4:5]
	s_waitcnt lgkmcnt(6)
	v_cvt_pk_bf16_f32 v0, v8, v6
	s_waitcnt lgkmcnt(4)
	v_cvt_pk_bf16_f32 v1, v10, v12
	s_waitcnt lgkmcnt(2)
	v_cvt_pk_bf16_f32 v2, v14, v16
	s_waitcnt lgkmcnt(0)
	v_cvt_pk_bf16_f32 v3, v18, v24
	v_lshl_add_u64 v[4:5], v[20:21], 0, v[4:5]
	global_store_dwordx4 v[4:5], v[0:3], off sc1
	v_add_u32_e32 v4, 24, v22
	v_ashrrev_i32_e32 v5, 31, v4
	v_lshlrev_b64 v[4:5], 9, v[4:5]
	v_cvt_pk_bf16_f32 v0, v9, v7
	v_cvt_pk_bf16_f32 v1, v11, v13
	v_cvt_pk_bf16_f32 v2, v15, v17
	v_cvt_pk_bf16_f32 v3, v19, v25
	v_lshl_add_u64 v[4:5], v[20:21], 0, v[4:5]
	global_store_dwordx4 v[4:5], v[0:3], off sc1
	s_waitcnt lgkmcnt(0)
	s_cmp_lt_i32 s3, 32
	v_add_u32_e32 v40, s51, v40
	s_cbranch_scc0 .LBB0_696

.LBB0_718:
	s_or_b64 exec, exec, s[12:13]
	s_waitcnt vmcnt(0)
	ds_write2_b32 v41, v0, v1 offset1:1
	ds_write2_b32 v41, v2, v3 offset0:2 offset1:3
	v_add_u32_e32 v0, 0x420, v41
	ds_write2_b32 v0, v8, v9 offset1:1
	v_add_u32_e32 v0, 0x428, v41
	ds_write2_b32 v0, v10, v11 offset1:1
	v_add_u32_e32 v0, 0x840, v41
	ds_write2_b32 v0, v4, v5 offset1:1
	v_add_u32_e32 v0, 0x848, v41
	ds_write2_b32 v0, v6, v7 offset1:1
	v_add_u32_e32 v0, 0xc60, v41
	ds_write2_b32 v0, v16, v17 offset1:1
	v_add_u32_e32 v0, 0xc68, v41
	ds_write2_b32 v0, v18, v19 offset1:1
	v_add_u32_e32 v0, 0x1080, v41
	ds_write2_b32 v0, v12, v13 offset1:1
	v_add_u32_e32 v0, 0x1088, v41
	ds_write2_b32 v0, v14, v15 offset1:1
	v_add_u32_e32 v0, 0x14a0, v41
	ds_write2_b32 v0, v24, v25 offset1:1
	v_add_u32_e32 v0, 0x14a8, v41
	ds_write2_b32 v0, v26, v27 offset1:1
	v_add_u32_e32 v0, 0x18c0, v41
	ds_write2_b32 v0, v20, v21 offset1:1
	v_add_u32_e32 v0, 0x18c8, v41
	ds_write2_b32 v0, v22, v23 offset1:1
	v_add_u32_e32 v0, 0x1ce0, v41
	ds_write2_b32 v0, v28, v29 offset1:1
	v_add_u32_e32 v0, 0x1ce8, v41
	ds_write2_b32 v0, v30, v31 offset1:1
	s_waitcnt lgkmcnt(0)
	s_sub_i32 s3, 0, s3
	ds_read2_b32 v[4:5], v40 offset0:33 offset1:41
	ds_read2_b32 v[6:7], v40 offset1:8
	ds_read2_b32 v[8:9], v40 offset0:66 offset1:74
	ds_read2_b32 v[10:11], v40 offset0:99 offset1:107
	ds_read2_b32 v[12:13], v40 offset0:132 offset1:140
	ds_read2_b32 v[14:15], v40 offset0:165 offset1:173
	ds_read2_b32 v[16:17], v40 offset0:198 offset1:206
	ds_read2_b32 v[18:19], v40 offset0:231 offset1:239
	s_add_i32 s3, s3, s1
	v_add_u32_e32 v22, s3, v39
	s_ashr_i32 s9, s8, 31
	v_ashrrev_i32_e32 v23, 31, v22
	v_lshl_add_u64 v[20:21], s[8:9], 1, v[32:33]
	v_lshlrev_b64 v[24:25], 11, v[22:23]
	s_waitcnt lgkmcnt(6)
	v_cvt_pk_bf16_f32 v0, v6, v4
	s_waitcnt lgkmcnt(4)
	v_cvt_pk_bf16_f32 v1, v8, v10
	s_waitcnt lgkmcnt(2)
	v_cvt_pk_bf16_f32 v2, v12, v14
	s_waitcnt lgkmcnt(0)
	v_cvt_pk_bf16_f32 v3, v16, v18
	v_lshl_add_u64 v[24:25], v[20:21], 0, v[24:25]
	v_add_u32_e32 v4, 8, v22
	global_store_dwordx4 v[24:25], v[0:3], off sc1
	s_add_i32 s0, s0, s34
	s_add_i32 s1, s1, s51
	v_cvt_pk_bf16_f32 v0, v7, v5
	v_ashrrev_i32_e32 v5, 31, v4
	v_cvt_pk_bf16_f32 v1, v9, v11
	v_cvt_pk_bf16_f32 v2, v13, v15
	v_cvt_pk_bf16_f32 v3, v17, v19
	v_lshlrev_b64 v[4:5], 11, v[4:5]
	ds_read2_b32 v[6:7], v40 offset0:49 offset1:57
	ds_read2_b32 v[8:9], v40 offset0:16 offset1:24
	ds_read2_b32 v[10:11], v40 offset0:82 offset1:90
	ds_read2_b32 v[12:13], v40 offset0:115 offset1:123
	ds_read2_b32 v[14:15], v40 offset0:148 offset1:156
	ds_read2_b32 v[16:17], v40 offset0:181 offset1:189
	ds_read2_b32 v[18:19], v40 offset0:214 offset1:222
	ds_read2_b32 v[24:25], v40 offset0:247 offset1:255
	v_lshl_add_u64 v[4:5], v[20:21], 0, v[4:5]
	global_store_dwordx4 v[4:5], v[0:3], off sc1
	v_add_u32_e32 v4, 16, v22
	v_ashrrev_i32_e32 v5, 31, v4
	v_lshlrev_b64 v[4:5], 11, v[4:5]
	s_waitcnt lgkmcnt(6)
	v_cvt_pk_bf16_f32 v0, v8, v6
	s_waitcnt lgkmcnt(4)
	v_cvt_pk_bf16_f32 v1, v10, v12
	s_waitcnt lgkmcnt(2)
	v_cvt_pk_bf16_f32 v2, v14, v16
	s_waitcnt lgkmcnt(0)
	v_cvt_pk_bf16_f32 v3, v18, v24
	v_lshl_add_u64 v[4:5], v[20:21], 0, v[4:5]
	global_store_dwordx4 v[4:5], v[0:3], off sc1
	v_add_u32_e32 v4, 24, v22
	v_ashrrev_i32_e32 v5, 31, v4
	v_lshlrev_b64 v[4:5], 11, v[4:5]
	v_cvt_pk_bf16_f32 v0, v9, v7
	v_cvt_pk_bf16_f32 v1, v11, v13
	v_cvt_pk_bf16_f32 v2, v15, v17
	v_cvt_pk_bf16_f32 v3, v19, v25
	v_lshl_add_u64 v[4:5], v[20:21], 0, v[4:5]
	global_store_dwordx4 v[4:5], v[0:3], off sc1
	s_waitcnt lgkmcnt(0)
	s_cmpk_lt_i32 s0, 0x800
	s_cbranch_scc0 .LBB0_735

.LBB0_737:
	s_or_b64 exec, exec, s[12:13]
	s_waitcnt vmcnt(0)
	ds_write2_b32 v41, v0, v1 offset1:1
	ds_write2_b32 v41, v2, v3 offset0:2 offset1:3
	v_add_u32_e32 v0, 0x420, v41
	ds_write2_b32 v0, v8, v9 offset1:1
	v_add_u32_e32 v0, 0x428, v41
	ds_write2_b32 v0, v10, v11 offset1:1
	v_add_u32_e32 v0, 0x840, v41
	ds_write2_b32 v0, v4, v5 offset1:1
	v_add_u32_e32 v0, 0x848, v41
	ds_write2_b32 v0, v6, v7 offset1:1
	v_add_u32_e32 v0, 0xc60, v41
	ds_write2_b32 v0, v16, v17 offset1:1
	v_add_u32_e32 v0, 0xc68, v41
	ds_write2_b32 v0, v18, v19 offset1:1
	v_add_u32_e32 v0, 0x1080, v41
	ds_write2_b32 v0, v12, v13 offset1:1
	v_add_u32_e32 v0, 0x1088, v41
	ds_write2_b32 v0, v14, v15 offset1:1
	v_add_u32_e32 v0, 0x14a0, v41
	ds_write2_b32 v0, v24, v25 offset1:1
	v_add_u32_e32 v0, 0x14a8, v41
	ds_write2_b32 v0, v26, v27 offset1:1
	v_add_u32_e32 v0, 0x18c0, v41
	ds_write2_b32 v0, v20, v21 offset1:1
	v_add_u32_e32 v0, 0x18c8, v41
	ds_write2_b32 v0, v22, v23 offset1:1
	v_add_u32_e32 v0, 0x1ce0, v41
	ds_write2_b32 v0, v28, v29 offset1:1
	v_add_u32_e32 v0, 0x1ce8, v41
	ds_write2_b32 v0, v30, v31 offset1:1
	s_waitcnt lgkmcnt(0)
	s_sub_i32 s3, 0, s3
	ds_read2_b32 v[4:5], v40 offset0:33 offset1:41
	ds_read2_b32 v[6:7], v40 offset1:8
	ds_read2_b32 v[8:9], v40 offset0:66 offset1:74
	ds_read2_b32 v[10:11], v40 offset0:99 offset1:107
	ds_read2_b32 v[12:13], v40 offset0:132 offset1:140
	ds_read2_b32 v[14:15], v40 offset0:165 offset1:173
	ds_read2_b32 v[16:17], v40 offset0:198 offset1:206
	ds_read2_b32 v[18:19], v40 offset0:231 offset1:239
	s_add_i32 s3, s3, s1
	v_add_u32_e32 v22, s3, v39
	s_ashr_i32 s9, s8, 31
	v_ashrrev_i32_e32 v23, 31, v22
	v_lshl_add_u64 v[20:21], s[8:9], 1, v[32:33]
	v_lshlrev_b64 v[24:25], 13, v[22:23]
	s_waitcnt lgkmcnt(6)
	v_cvt_pk_bf16_f32 v0, v6, v4
	s_waitcnt lgkmcnt(4)
	v_cvt_pk_bf16_f32 v1, v8, v10
	s_waitcnt lgkmcnt(2)
	v_cvt_pk_bf16_f32 v2, v12, v14
	s_waitcnt lgkmcnt(0)
	v_cvt_pk_bf16_f32 v3, v16, v18
	v_lshl_add_u64 v[24:25], v[20:21], 0, v[24:25]
	v_add_u32_e32 v4, 8, v22
	global_store_dwordx4 v[24:25], v[0:3], off sc1
	s_add_i32 s0, s0, s34
	s_add_i32 s1, s1, s51
	v_cvt_pk_bf16_f32 v0, v7, v5
	v_ashrrev_i32_e32 v5, 31, v4
	v_cvt_pk_bf16_f32 v1, v9, v11
	v_cvt_pk_bf16_f32 v2, v13, v15
	v_cvt_pk_bf16_f32 v3, v17, v19
	v_lshlrev_b64 v[4:5], 13, v[4:5]
	ds_read2_b32 v[6:7], v40 offset0:49 offset1:57
	ds_read2_b32 v[8:9], v40 offset0:16 offset1:24
	ds_read2_b32 v[10:11], v40 offset0:82 offset1:90
	ds_read2_b32 v[12:13], v40 offset0:115 offset1:123
	ds_read2_b32 v[14:15], v40 offset0:148 offset1:156
	ds_read2_b32 v[16:17], v40 offset0:181 offset1:189
	ds_read2_b32 v[18:19], v40 offset0:214 offset1:222
	ds_read2_b32 v[24:25], v40 offset0:247 offset1:255
	v_lshl_add_u64 v[4:5], v[20:21], 0, v[4:5]
	global_store_dwordx4 v[4:5], v[0:3], off sc1
	v_add_u32_e32 v4, 16, v22
	v_ashrrev_i32_e32 v5, 31, v4
	v_lshlrev_b64 v[4:5], 13, v[4:5]
	s_waitcnt lgkmcnt(6)
	v_cvt_pk_bf16_f32 v0, v8, v6
	s_waitcnt lgkmcnt(4)
	v_cvt_pk_bf16_f32 v1, v10, v12
	s_waitcnt lgkmcnt(2)
	v_cvt_pk_bf16_f32 v2, v14, v16
	s_waitcnt lgkmcnt(0)
	v_cvt_pk_bf16_f32 v3, v18, v24
	v_lshl_add_u64 v[4:5], v[20:21], 0, v[4:5]
	global_store_dwordx4 v[4:5], v[0:3], off sc1
	v_add_u32_e32 v4, 24, v22
	v_ashrrev_i32_e32 v5, 31, v4
	v_lshlrev_b64 v[4:5], 13, v[4:5]
	v_cvt_pk_bf16_f32 v0, v9, v7
	v_cvt_pk_bf16_f32 v1, v11, v13
	v_cvt_pk_bf16_f32 v2, v15, v17
	v_cvt_pk_bf16_f32 v3, v19, v25
	v_lshl_add_u64 v[4:5], v[20:21], 0, v[4:5]
	global_store_dwordx4 v[4:5], v[0:3], off sc1
	s_waitcnt lgkmcnt(0)
	s_cmpk_lt_i32 s0, 0x800
	s_cbranch_scc0 .LBB0_754

.LBB0_809:
	s_or_b64 exec, exec, s[20:21]
	v_and_b32_e32 v4, 0xf8, v57
	v_add_u32_e32 v57, s60, v61
	v_lshlrev_b32_e32 v48, 1, v4
	v_cmp_lt_i32_e32 vcc, s1, v57
	v_lshl_add_u64 v[4:5], v[10:11], 0, v[48:49]
	s_orn2_b64 s[20:21], vcc, exec
	global_store_dwordx4 v[4:5], v[0:3], off sc1

.LBB0_823:
	s_or_b64 exec, exec, s[18:19]
	v_and_b32_e32 v4, 0xf8, v61
	v_lshlrev_b32_e32 v48, 1, v4
	v_add_u32_e32 v61, s60, v57
	v_lshl_add_u64 v[4:5], v[12:13], 0, v[48:49]
	v_cmp_gt_i32_e32 vcc, s0, v61
	s_mov_b64 s[20:21], -1
	global_store_dwordx4 v[4:5], v[0:3], off sc1
	s_and_saveexec_b64 s[18:19], vcc
	s_cbranch_execz .LBB0_810
	v_bfe_u32 v0, v57, 5, 1
	v_ashrrev_i32_e32 v52, 7, v61
	v_and_or_b32 v50, v52, -2, v0
	v_cmp_lt_i32_e32 vcc, 1, v59
	s_and_saveexec_b64 s[2:3], vcc
	s_xor_b64 s[20:21], exec, s[2:3]
	s_cbranch_execz .LBB0_830
	v_max_i32_e32 v0, 4, v50
	v_max_i32_e32 v1, 5, v50
	v_max_i32_e32 v2, 6, v50
	v_max_i32_e32 v3, 7, v50
	v_cmp_lt_i32_e32 vcc, 2, v59
	v_add_u32_e32 v6, -4, v0
	v_add_u32_e32 v4, -5, v1
	v_add_u32_e32 v8, -6, v2
	v_add_u32_e32 v12, -7, v3
	s_and_saveexec_b64 s[2:3], vcc
	s_xor_b64 s[22:23], exec, s[2:3]
	s_cbranch_execz .LBB0_827
	v_readlane_b32 s2, v254, 6
	v_lshlrev_b32_e32 v48, 4, v55
	v_readlane_b32 s3, v254, 7
	v_max_i32_e32 v0, 1, v50
	v_mov_b32_e32 v13, v49
	v_lshl_add_u64 v[16:17], s[2:3], 0, v[48:49]
	v_max_i32_e32 v48, 0, v50
	v_lshlrev_b64 v[10:11], 11, v[48:49]
	v_add_u32_e32 v48, -1, v0
	v_max_i32_e32 v0, 2, v50
	v_lshlrev_b64 v[14:15], 11, v[48:49]
	v_add_u32_e32 v48, -2, v0
	v_lshlrev_b64 v[0:1], 11, v[12:13]
	v_max_i32_e32 v2, 3, v50
	v_lshl_add_u64 v[0:1], v[16:17], 0, v[0:1]
	v_lshlrev_b64 v[18:19], 11, v[48:49]
	global_load_dwordx4 v[66:69], v[0:1], off
	v_add_u32_e32 v48, -3, v2
	v_max_i32_e32 v0, 8, v50
	v_lshlrev_b64 v[12:13], 11, v[48:49]
	v_add_u32_e32 v48, -8, v0
	v_lshlrev_b64 v[0:1], 11, v[48:49]
	v_max_i32_e32 v5, 9, v50
	v_mov_b32_e32 v9, v49
	v_lshl_add_u64 v[0:1], v[16:17], 0, v[0:1]
	v_add_u32_e32 v48, -9, v5
	global_load_dwordx4 v[70:73], v[0:1], off
	v_lshlrev_b64 v[0:1], 11, v[8:9]
	v_lshl_add_u64 v[8:9], v[16:17], 0, v[10:11]
	v_lshlrev_b64 v[10:11], 11, v[48:49]
	v_lshl_add_u64 v[0:1], v[16:17], 0, v[0:1]
	v_lshl_add_u64 v[10:11], v[16:17], 0, v[10:11]
	global_load_dwordx4 v[0:3], v[0:1], off
	v_max_i32_e32 v5, 10, v50
	global_load_dwordx4 v[74:77], v[10:11], off
	v_lshl_add_u64 v[10:11], v[16:17], 0, v[14:15]
	v_add_u32_e32 v48, -10, v5
	global_load_dwordx4 v[28:31], v[8:9], off
	global_load_dwordx4 v[24:27], v[10:11], off
	v_lshl_add_u64 v[10:11], v[16:17], 0, v[12:13]
	v_lshlrev_b64 v[12:13], 11, v[48:49]
	v_lshl_add_u64 v[12:13], v[16:17], 0, v[12:13]
	v_lshl_add_u64 v[8:9], v[16:17], 0, v[18:19]
	global_load_dwordx4 v[78:81], v[12:13], off
	global_load_dwordx4 v[40:43], v[8:9], off
	global_load_dwordx4 v[32:35], v[10:11], off
	v_mov_b32_e32 v7, v49
	v_lshlrev_b64 v[6:7], 11, v[6:7]
	v_mov_b32_e32 v5, v49
	v_lshl_add_u64 v[6:7], v[16:17], 0, v[6:7]
	v_lshlrev_b64 v[4:5], 11, v[4:5]
	v_lshl_add_u64 v[4:5], v[16:17], 0, v[4:5]
	global_load_dwordx4 v[44:47], v[6:7], off
	global_load_dwordx4 v[36:39], v[4:5], off
	v_max_i32_e32 v4, 11, v50
	v_add_u32_e32 v48, -11, v4
	v_max_i32_e32 v8, 12, v50
	v_lshlrev_b64 v[4:5], 11, v[48:49]
	v_add_u32_e32 v48, -12, v8
	v_max_i32_e32 v10, 13, v50
	v_lshl_add_u64 v[4:5], v[16:17], 0, v[4:5]
	v_lshlrev_b64 v[8:9], 11, v[48:49]
	v_add_u32_e32 v48, -13, v10
	v_max_i32_e32 v18, 14, v50
	global_load_dwordx4 v[4:7], v[4:5], off
	v_lshlrev_b64 v[10:11], 11, v[48:49]
	v_add_u32_e32 v48, -14, v18
	v_max_i32_e32 v20, 15, v50
	v_lshl_add_u64 v[8:9], v[16:17], 0, v[8:9]
	v_lshl_add_u64 v[10:11], v[16:17], 0, v[10:11]
	v_lshlrev_b64 v[18:19], 11, v[48:49]
	v_add_u32_e32 v48, -15, v20
	global_load_dwordx4 v[12:15], v[8:9], off
	s_nop 0
	global_load_dwordx4 v[8:11], v[10:11], off
	v_lshlrev_b64 v[20:21], 11, v[48:49]
	v_lshl_add_u64 v[18:19], v[16:17], 0, v[18:19]
	v_lshl_add_u64 v[16:17], v[16:17], 0, v[20:21]
	global_load_dwordx4 v[20:23], v[18:19], off
	s_nop 0
	global_load_dwordx4 v[16:19], v[16:17], off
	v_cmp_gt_i32_e32 vcc, 0, v52
	v_min_i32_e32 v51, 15, v50
	v_add_u32_e32 v51, 1, v51
	v_cndmask_b32_e64 v48, 1.0, 0, vcc
	v_cmp_gt_i32_e32 vcc, 1, v50
	v_cvt_f32_i32_e32 v51, v51
	v_lshlrev_b32_e32 v57, 3, v55
	v_cndmask_b32_e64 v52, 1.0, 0, vcc
	v_cmp_gt_i32_e32 vcc, 2, v50
	v_div_scale_f32 v55, s[2:3], v51, v51, 1.0
	s_nop 0
	v_cndmask_b32_e64 v54, 1.0, 0, vcc
	v_cmp_gt_i32_e32 vcc, 3, v50
	v_rcp_f32_e32 v59, v55
	s_waitcnt vmcnt(15)
	v_lshlrev_b32_e32 v96, 16, v66
	v_cndmask_b32_e64 v56, 1.0, 0, vcc
	v_cmp_gt_i32_e32 vcc, 4, v50
	v_fma_f32 v63, -v55, v59, 1.0
	v_fmac_f32_e32 v59, v63, v59
	v_cndmask_b32_e64 v58, 1.0, 0, vcc
	v_cmp_gt_i32_e32 vcc, 5, v50
	v_and_b32_e32 v97, 0xffff0000, v66
	v_lshlrev_b32_e32 v98, 16, v67
	v_cndmask_b32_e64 v60, 1.0, 0, vcc
	v_cmp_gt_i32_e32 vcc, 6, v50
	s_waitcnt vmcnt(14)
	v_lshlrev_b32_e32 v100, 16, v70
	v_and_b32_e32 v101, 0xffff0000, v70
	v_cndmask_b32_e64 v62, 1.0, 0, vcc
	v_cmp_gt_i32_e32 vcc, 7, v50
	v_lshlrev_b32_e32 v102, 16, v71
	v_and_b32_e32 v103, 0xffff0000, v71
	v_cndmask_b32_e64 v64, 1.0, 0, vcc
	v_cmp_gt_i32_e32 vcc, 8, v50
	s_waitcnt vmcnt(12)
	v_lshlrev_b32_e32 v104, 16, v74
	v_and_b32_e32 v105, 0xffff0000, v74
	v_cndmask_b32_e64 v70, 1.0, 0, vcc
	v_cmp_gt_i32_e32 vcc, 9, v50
	v_lshlrev_b32_e32 v108, 16, v76
	s_waitcnt vmcnt(9)
	v_lshlrev_b32_e32 v114, 16, v80
	v_cndmask_b32_e64 v74, 1.0, 0, vcc
	v_cmp_gt_i32_e32 vcc, 10, v50
	v_and_b32_e32 v115, 0xffff0000, v80
	v_and_b32_e32 v109, 0xffff0000, v76
	v_cndmask_b32_e64 v86, 1.0, 0, vcc
	v_cmp_gt_i32_e32 vcc, 11, v50
	v_lshlrev_b32_e32 v110, 16, v78
	v_and_b32_e32 v111, 0xffff0000, v78
	v_cndmask_b32_e64 v80, 1.0, 0, vcc
	v_cmp_gt_i32_e32 vcc, 12, v50
	v_lshlrev_b32_e32 v116, 16, v28
	v_and_b32_e32 v117, 0xffff0000, v28
	v_cndmask_b32_e64 v76, 1.0, 0, vcc
	v_cmp_gt_i32_e32 vcc, 13, v50
	v_lshlrev_b32_e32 v118, 16, v24
	v_and_b32_e32 v119, 0xffff0000, v24
	v_cndmask_b32_e64 v88, 1.0, 0, vcc
	v_cmp_gt_i32_e32 vcc, 14, v50
	v_pk_fma_f32 v[130:131], v[48:49], v[116:117], 0 op_sel_hi:[0,1,0]
	s_waitcnt vmcnt(8)
	v_lshlrev_b32_e32 v120, 16, v40
	v_cndmask_b32_e64 v84, 1.0, 0, vcc
	v_cmp_gt_i32_e32 vcc, 15, v50
	v_and_b32_e32 v121, 0xffff0000, v40
	v_pk_fma_f32 v[118:119], v[52:53], v[118:119], v[130:131] op_sel_hi:[0,1,1]
	v_cndmask_b32_e64 v78, 1.0, 0, vcc
	v_div_scale_f32 v63, vcc, 1.0, v51, 1.0
	v_mul_f32_e32 v65, v63, v59
	v_fma_f32 v71, -v55, v65, v63
	v_fmac_f32_e32 v65, v71, v59
	v_fma_f32 v55, -v55, v65, v63
	v_div_fmas_f32 v55, v55, v59, v65
	s_waitcnt vmcnt(7)
	v_lshlrev_b32_e32 v122, 16, v32
	v_and_b32_e32 v123, 0xffff0000, v32
	v_pk_fma_f32 v[118:119], v[54:55], v[120:121], v[118:119] op_sel_hi:[0,1,1]
	s_waitcnt vmcnt(6)
	v_lshlrev_b32_e32 v124, 16, v44
	v_and_b32_e32 v125, 0xffff0000, v44
	v_pk_fma_f32 v[118:119], v[56:57], v[122:123], v[118:119] op_sel_hi:[0,1,1]
	s_waitcnt vmcnt(5)
	v_lshlrev_b32_e32 v126, 16, v36
	v_and_b32_e32 v127, 0xffff0000, v36
	v_pk_fma_f32 v[118:119], v[58:59], v[124:125], v[118:119] op_sel_hi:[0,1,1]
	v_lshlrev_b32_e32 v128, 16, v0
	v_and_b32_e32 v129, 0xffff0000, v0
	v_pk_fma_f32 v[118:119], v[60:61], v[126:127], v[118:119] op_sel_hi:[0,1,1]
	v_pk_fma_f32 v[118:119], v[62:63], v[128:129], v[118:119] op_sel_hi:[0,1,1]
	v_pk_fma_f32 v[96:97], v[64:65], v[96:97], v[118:119] op_sel_hi:[0,1,1]
	v_pk_fma_f32 v[96:97], v[70:71], v[100:101], v[96:97] op_sel_hi:[0,1,1]
	v_pk_fma_f32 v[96:97], v[74:75], v[104:105], v[96:97] op_sel_hi:[0,1,1]
	v_pk_fma_f32 v[96:97], v[86:87], v[110:111], v[96:97] op_sel_hi:[0,1,1]
	s_waitcnt vmcnt(4)
	v_lshlrev_b32_e32 v100, 16, v4
	v_and_b32_e32 v101, 0xffff0000, v4
	v_pk_fma_f32 v[96:97], v[80:81], v[100:101], v[96:97] op_sel_hi:[0,1,1]
	s_waitcnt vmcnt(3)
	v_lshlrev_b32_e32 v100, 16, v12
	v_and_b32_e32 v101, 0xffff0000, v12
	v_pk_fma_f32 v[96:97], v[76:77], v[100:101], v[96:97] op_sel_hi:[0,1,1]
	s_waitcnt vmcnt(2)
	v_lshlrev_b32_e32 v100, 16, v8
	v_and_b32_e32 v101, 0xffff0000, v8
	v_pk_fma_f32 v[96:97], v[88:89], v[100:101], v[96:97] op_sel_hi:[0,1,1]
	s_waitcnt vmcnt(1)
	v_lshlrev_b32_e32 v100, 16, v20
	v_and_b32_e32 v101, 0xffff0000, v20
	v_pk_fma_f32 v[96:97], v[84:85], v[100:101], v[96:97] op_sel_hi:[0,1,1]
	s_waitcnt vmcnt(0)
	v_lshlrev_b32_e32 v100, 16, v16
	v_and_b32_e32 v101, 0xffff0000, v16
	v_lshlrev_b32_e32 v28, 16, v29
	v_and_b32_e32 v29, 0xffff0000, v29
	v_pk_fma_f32 v[96:97], v[78:79], v[100:101], v[96:97] op_sel_hi:[0,1,1]
	v_lshlrev_b32_e32 v24, 16, v25
	v_and_b32_e32 v25, 0xffff0000, v25
	v_pk_fma_f32 v[100:101], v[48:49], v[28:29], 0 op_sel_hi:[0,1,0]
	v_lshlrev_b32_e32 v40, 16, v41
	v_and_b32_e32 v41, 0xffff0000, v41
	v_pk_fma_f32 v[24:25], v[52:53], v[24:25], v[100:101] op_sel_hi:[0,1,1]
	v_lshlrev_b32_e32 v32, 16, v33
	v_and_b32_e32 v33, 0xffff0000, v33
	v_pk_fma_f32 v[24:25], v[54:55], v[40:41], v[24:25] op_sel_hi:[0,1,1]
	v_lshlrev_b32_e32 v44, 16, v45
	v_and_b32_e32 v45, 0xffff0000, v45
	v_pk_fma_f32 v[24:25], v[56:57], v[32:33], v[24:25] op_sel_hi:[0,1,1]
	v_lshlrev_b32_e32 v36, 16, v37
	v_and_b32_e32 v37, 0xffff0000, v37
	v_pk_fma_f32 v[24:25], v[58:59], v[44:45], v[24:25] op_sel_hi:[0,1,1]
	v_lshlrev_b32_e32 v0, 16, v1
	v_and_b32_e32 v1, 0xffff0000, v1
	v_pk_fma_f32 v[24:25], v[60:61], v[36:37], v[24:25] op_sel_hi:[0,1,1]
	v_and_b32_e32 v99, 0xffff0000, v67
	v_pk_fma_f32 v[0:1], v[62:63], v[0:1], v[24:25] op_sel_hi:[0,1,1]
	v_pk_fma_f32 v[0:1], v[64:65], v[98:99], v[0:1] op_sel_hi:[0,1,1]
	v_lshlrev_b32_e32 v106, 16, v75
	v_and_b32_e32 v107, 0xffff0000, v75
	v_pk_fma_f32 v[0:1], v[70:71], v[102:103], v[0:1] op_sel_hi:[0,1,1]
	v_lshlrev_b32_e32 v112, 16, v79
	v_and_b32_e32 v113, 0xffff0000, v79
	v_pk_fma_f32 v[0:1], v[74:75], v[106:107], v[0:1] op_sel_hi:[0,1,1]
	v_pk_fma_f32 v[0:1], v[86:87], v[112:113], v[0:1] op_sel_hi:[0,1,1]
	v_lshlrev_b32_e32 v4, 16, v5
	v_and_b32_e32 v5, 0xffff0000, v5
	v_pk_fma_f32 v[0:1], v[80:81], v[4:5], v[0:1] op_sel_hi:[0,1,1]
	v_lshlrev_b32_e32 v4, 16, v13
	v_and_b32_e32 v5, 0xffff0000, v13
	v_pk_fma_f32 v[0:1], v[76:77], v[4:5], v[0:1] op_sel_hi:[0,1,1]
	v_lshlrev_b32_e32 v4, 16, v9
	v_and_b32_e32 v5, 0xffff0000, v9
	v_pk_fma_f32 v[0:1], v[88:89], v[4:5], v[0:1] op_sel_hi:[0,1,1]
	v_lshlrev_b32_e32 v4, 16, v21
	v_and_b32_e32 v5, 0xffff0000, v21
	v_pk_fma_f32 v[0:1], v[84:85], v[4:5], v[0:1] op_sel_hi:[0,1,1]
	v_lshlrev_b32_e32 v4, 16, v17
	v_and_b32_e32 v5, 0xffff0000, v17
	v_div_fixup_f32 v90, v55, v51, 1.0
	v_pk_fma_f32 v[0:1], v[78:79], v[4:5], v[0:1] op_sel_hi:[0,1,1]
	v_pk_fma_f32 v[4:5], v[90:91], v[0:1], v[28:29] op_sel_hi:[0,1,1] neg_lo:[0,0,1] neg_hi:[0,0,1]
	v_lshlrev_b32_e32 v0, 16, v30
	v_and_b32_e32 v1, 0xffff0000, v30
	v_lshlrev_b32_e32 v8, 16, v26
	v_and_b32_e32 v9, 0xffff0000, v26
	v_pk_fma_f32 v[32:33], v[48:49], v[0:1], 0 op_sel_hi:[0,1,0]
	v_lshlrev_b32_e32 v12, 16, v42
	v_and_b32_e32 v13, 0xffff0000, v42
	v_pk_fma_f32 v[8:9], v[52:53], v[8:9], v[32:33] op_sel_hi:[0,1,1]
	v_lshlrev_b32_e32 v16, 16, v34
	v_and_b32_e32 v17, 0xffff0000, v34
	v_pk_fma_f32 v[8:9], v[54:55], v[12:13], v[8:9] op_sel_hi:[0,1,1]
	v_lshlrev_b32_e32 v20, 16, v46
	v_and_b32_e32 v21, 0xffff0000, v46
	v_pk_fma_f32 v[8:9], v[56:57], v[16:17], v[8:9] op_sel_hi:[0,1,1]
	v_lshlrev_b32_e32 v24, 16, v38
	v_and_b32_e32 v25, 0xffff0000, v38
	v_pk_fma_f32 v[8:9], v[58:59], v[20:21], v[8:9] op_sel_hi:[0,1,1]
	v_lshlrev_b32_e32 v28, 16, v2
	v_and_b32_e32 v29, 0xffff0000, v2
	v_pk_fma_f32 v[8:9], v[60:61], v[24:25], v[8:9] op_sel_hi:[0,1,1]
	v_lshlrev_b32_e32 v92, 16, v68
	v_and_b32_e32 v93, 0xffff0000, v68
	v_pk_fma_f32 v[8:9], v[62:63], v[28:29], v[8:9] op_sel_hi:[0,1,1]
	v_lshlrev_b32_e32 v94, 16, v72
	v_and_b32_e32 v95, 0xffff0000, v72
	v_pk_fma_f32 v[8:9], v[64:65], v[92:93], v[8:9] op_sel_hi:[0,1,1]
	v_pk_fma_f32 v[8:9], v[70:71], v[94:95], v[8:9] op_sel_hi:[0,1,1]
	v_pk_fma_f32 v[8:9], v[74:75], v[108:109], v[8:9] op_sel_hi:[0,1,1]
	v_pk_fma_f32 v[8:9], v[86:87], v[114:115], v[8:9] op_sel_hi:[0,1,1]
	v_lshlrev_b32_e32 v12, 16, v6
	v_and_b32_e32 v13, 0xffff0000, v6
	v_pk_fma_f32 v[8:9], v[80:81], v[12:13], v[8:9] op_sel_hi:[0,1,1]
	v_lshlrev_b32_e32 v12, 16, v14
	v_and_b32_e32 v13, 0xffff0000, v14
	v_pk_fma_f32 v[8:9], v[76:77], v[12:13], v[8:9] op_sel_hi:[0,1,1]
	v_lshlrev_b32_e32 v12, 16, v10
	v_and_b32_e32 v13, 0xffff0000, v10
	v_pk_fma_f32 v[8:9], v[88:89], v[12:13], v[8:9] op_sel_hi:[0,1,1]
	v_lshlrev_b32_e32 v12, 16, v22
	v_and_b32_e32 v13, 0xffff0000, v22
	v_pk_fma_f32 v[8:9], v[84:85], v[12:13], v[8:9] op_sel_hi:[0,1,1]
	v_lshlrev_b32_e32 v12, 16, v18
	v_and_b32_e32 v13, 0xffff0000, v18
	v_pk_fma_f32 v[8:9], v[78:79], v[12:13], v[8:9] op_sel_hi:[0,1,1]
	v_pk_fma_f32 v[8:9], v[90:91], v[8:9], v[0:1] op_sel_hi:[0,1,1] neg_lo:[0,0,1] neg_hi:[0,0,1]
	v_lshlrev_b32_e32 v0, 16, v31
	v_and_b32_e32 v1, 0xffff0000, v31
	v_lshlrev_b32_e32 v12, 16, v27
	v_and_b32_e32 v13, 0xffff0000, v27
	v_pk_fma_f32 v[28:29], v[48:49], v[0:1], 0 op_sel_hi:[0,1,0]
	v_lshlrev_b32_e32 v16, 16, v43
	v_and_b32_e32 v17, 0xffff0000, v43
	v_pk_fma_f32 v[12:13], v[52:53], v[12:13], v[28:29] op_sel_hi:[0,1,1]
	v_lshlrev_b32_e32 v20, 16, v35
	v_and_b32_e32 v21, 0xffff0000, v35
	v_pk_fma_f32 v[12:13], v[54:55], v[16:17], v[12:13] op_sel_hi:[0,1,1]
	v_lshlrev_b32_e32 v24, 16, v47
	v_and_b32_e32 v25, 0xffff0000, v47
	v_pk_fma_f32 v[12:13], v[56:57], v[20:21], v[12:13] op_sel_hi:[0,1,1]
	v_lshlrev_b32_e32 v26, 16, v39
	v_and_b32_e32 v27, 0xffff0000, v39
	v_pk_fma_f32 v[12:13], v[58:59], v[24:25], v[12:13] op_sel_hi:[0,1,1]
	v_lshlrev_b32_e32 v2, 16, v3
	v_and_b32_e32 v3, 0xffff0000, v3
	v_pk_fma_f32 v[12:13], v[60:61], v[26:27], v[12:13] op_sel_hi:[0,1,1]
	v_lshlrev_b32_e32 v66, 16, v69
	v_and_b32_e32 v67, 0xffff0000, v69
	v_pk_fma_f32 v[2:3], v[62:63], v[2:3], v[12:13] op_sel_hi:[0,1,1]
	v_lshlrev_b32_e32 v68, 16, v73
	v_and_b32_e32 v69, 0xffff0000, v73
	v_pk_fma_f32 v[2:3], v[64:65], v[66:67], v[2:3] op_sel_hi:[0,1,1]
	v_lshlrev_b32_e32 v72, 16, v77
	v_and_b32_e32 v73, 0xffff0000, v77
	v_pk_fma_f32 v[2:3], v[70:71], v[68:69], v[2:3] op_sel_hi:[0,1,1]
	v_lshlrev_b32_e32 v82, 16, v81
	v_and_b32_e32 v83, 0xffff0000, v81
	v_pk_fma_f32 v[2:3], v[74:75], v[72:73], v[2:3] op_sel_hi:[0,1,1]
	v_pk_fma_f32 v[2:3], v[86:87], v[82:83], v[2:3] op_sel_hi:[0,1,1]
	v_lshlrev_b32_e32 v6, 16, v7
	v_and_b32_e32 v7, 0xffff0000, v7
	v_pk_fma_f32 v[2:3], v[80:81], v[6:7], v[2:3] op_sel_hi:[0,1,1]
	v_lshlrev_b32_e32 v6, 16, v15
	v_and_b32_e32 v7, 0xffff0000, v15
	v_pk_fma_f32 v[2:3], v[76:77], v[6:7], v[2:3] op_sel_hi:[0,1,1]
	v_lshlrev_b32_e32 v6, 16, v11
	v_and_b32_e32 v7, 0xffff0000, v11
	v_pk_fma_f32 v[2:3], v[88:89], v[6:7], v[2:3] op_sel_hi:[0,1,1]
	v_lshlrev_b32_e32 v6, 16, v23
	v_and_b32_e32 v7, 0xffff0000, v23
	v_pk_fma_f32 v[2:3], v[84:85], v[6:7], v[2:3] op_sel_hi:[0,1,1]
	v_lshlrev_b32_e32 v6, 16, v19
	v_and_b32_e32 v7, 0xffff0000, v19
	v_pk_fma_f32 v[2:3], v[78:79], v[6:7], v[2:3] op_sel_hi:[0,1,1]
	v_ashrrev_i32_e32 v51, 31, v50
	v_pk_fma_f32 v[6:7], v[90:91], v[2:3], v[0:1] op_sel_hi:[0,1,1] neg_lo:[0,0,1] neg_hi:[0,0,1]
	v_cvt_pk_bf16_f32 v1, v4, v5
	v_lshlrev_b64 v[4:5], 9, v[50:51]
	v_pk_fma_f32 v[96:97], v[90:91], v[96:97], v[116:117] op_sel_hi:[0,1,1] neg_lo:[0,0,1] neg_hi:[0,0,1]
	v_lshl_add_u64 v[4:5], s[38:39], 0, v[4:5]
	v_cvt_pk_bf16_f32 v0, v96, v97
	v_cvt_pk_bf16_f32 v2, v8, v9
	v_cvt_pk_bf16_f32 v3, v6, v7
	v_lshl_add_u64 v[10:11], v[4:5], 0, s[12:13]

.LBB0_919:
	v_lshl_add_u32 v156, s70, 8, v162
	v_lshlrev_b64 v[152:153], 2, v[152:153]
	v_ashrrev_i32_e32 v157, 31, v156
	v_lshl_add_u64 v[154:155], s[36:37], 0, v[152:153]
	v_lshlrev_b64 v[158:159], 12, v[156:157]
	v_or_b32_e32 v186, 16, v156
	v_lshl_add_u64 v[182:183], v[154:155], 0, v[158:159]
	v_ashrrev_i32_e32 v187, 31, v186
	global_load_dwordx4 v[170:173], v[182:183], off
	global_load_dwordx4 v[174:177], v[182:183], off offset:64
	global_load_dwordx4 v[178:181], v[182:183], off offset:512
	s_nop 0
	global_load_dwordx4 v[182:185], v[182:183], off offset:576
	v_lshlrev_b64 v[238:239], 12, v[186:187]
	v_or_b32_e32 v202, 32, v156
	v_lshl_add_u64 v[198:199], v[154:155], 0, v[238:239]
	v_ashrrev_i32_e32 v203, 31, v202
	v_or_b32_e32 v222, 48, v156
	global_load_dwordx4 v[186:189], v[198:199], off
	global_load_dwordx4 v[190:193], v[198:199], off offset:64
	global_load_dwordx4 v[194:197], v[198:199], off offset:512
	s_nop 0
	global_load_dwordx4 v[198:201], v[198:199], off offset:576
	v_lshlrev_b64 v[240:241], 12, v[202:203]
	v_ashrrev_i32_e32 v223, 31, v222
	v_lshl_add_u64 v[218:219], v[154:155], 0, v[240:241]
	v_lshlrev_b64 v[242:243], 12, v[222:223]
	global_load_dwordx4 v[202:205], v[218:219], off
	global_load_dwordx4 v[206:209], v[218:219], off offset:64
	global_load_dwordx4 v[214:217], v[218:219], off offset:512
	s_nop 0
	global_load_dwordx4 v[218:221], v[218:219], off offset:576
	v_lshl_add_u64 v[234:235], v[154:155], 0, v[242:243]
	global_load_dwordx4 v[222:225], v[234:235], off
	global_load_dwordx4 v[226:229], v[234:235], off offset:64
	global_load_dwordx4 v[230:233], v[234:235], off offset:512
	s_nop 0
	global_load_dwordx4 v[234:237], v[234:235], off offset:576
	v_lshl_add_u64 v[158:159], s[36:37], 0, v[158:159]
	v_lshl_add_u64 v[158:159], v[158:159], 0, v[152:153]
	s_mov_b64 s[8:9], -1
	s_andn2_b64 vcc, exec, s[6:7]
	s_waitcnt vmcnt(0)
	v_pk_fma_f32 v[142:143], v[142:143], v[70:71], v[172:173]
	v_pk_fma_f32 v[140:141], v[140:141], v[68:69], v[170:171]
	v_pk_fma_f32 v[126:127], v[126:127], v[86:87], v[180:181]
	v_pk_fma_f32 v[124:125], v[124:125], v[84:85], v[178:179]
	global_store_dwordx4 v[158:159], v[124:127], off offset:512 sc1
	v_pk_fma_f32 v[118:119], v[118:119], v[82:83], v[184:185]
	v_pk_fma_f32 v[116:117], v[116:117], v[80:81], v[182:183]
	v_lshl_add_u64 v[124:125], s[36:37], 0, v[238:239]
	v_lshl_add_u64 v[124:125], v[124:125], 0, v[152:153]
	v_pk_fma_f32 v[110:111], v[110:111], v[86:87], v[196:197]
	v_pk_fma_f32 v[108:109], v[108:109], v[84:85], v[194:195]
	global_store_dwordx4 v[124:125], v[108:111], off offset:512 sc1
	v_pk_fma_f32 v[102:103], v[102:103], v[82:83], v[200:201]
	v_pk_fma_f32 v[94:95], v[94:95], v[86:87], v[216:217]
	v_lshl_add_u64 v[108:109], s[36:37], 0, v[240:241]
	v_lshl_add_u64 v[108:109], v[108:109], 0, v[152:153]
	v_pk_fma_f32 v[92:93], v[92:93], v[84:85], v[214:215]
	global_store_dwordx4 v[108:109], v[92:95], off offset:512 sc1
	v_pk_fma_f32 v[74:75], v[74:75], v[82:83], v[236:237]
	v_pk_fma_f32 v[72:73], v[72:73], v[80:81], v[234:235]
	v_lshl_add_u64 v[92:93], s[36:37], 0, v[242:243]
	v_lshl_add_u64 v[92:93], v[92:93], 0, v[152:153]
	v_pk_fma_f32 v[100:101], v[100:101], v[80:81], v[198:199]
	v_pk_fma_f32 v[90:91], v[90:91], v[82:83], v[220:221]
	v_pk_fma_f32 v[88:89], v[88:89], v[80:81], v[218:219]
	global_store_dwordx4 v[92:93], v[72:75], off offset:576 sc1
	v_pk_fma_f32 v[138:139], v[138:139], v[66:67], v[176:177]
	v_pk_fma_f32 v[136:137], v[136:137], v[64:65], v[174:175]
	v_add_u32_e32 v72, 0x80, v156
	global_store_dwordx4 v[158:159], v[116:119], off offset:576 sc1
	global_store_dwordx4 v[124:125], v[100:103], off offset:576 sc1
	global_store_dwordx4 v[108:109], v[88:91], off offset:576 sc1
	v_pk_fma_f32 v[118:119], v[134:135], v[70:71], v[188:189]
	v_pk_fma_f32 v[116:117], v[132:133], v[68:69], v[186:187]
	v_pk_fma_f32 v[102:103], v[122:123], v[70:71], v[204:205]
	v_pk_fma_f32 v[100:101], v[120:121], v[68:69], v[202:203]
	v_pk_fma_f32 v[90:91], v[106:107], v[70:71], v[224:225]
	v_pk_fma_f32 v[88:89], v[104:105], v[68:69], v[222:223]
	v_ashrrev_i32_e32 v73, 31, v72
	global_store_dwordx4 v[158:159], v[140:143], off sc1
	global_store_dwordx4 v[158:159], v[136:139], off offset:64 sc1
	global_store_dwordx4 v[124:125], v[116:119], off sc1
	global_store_dwordx4 v[108:109], v[100:103], off sc1
	global_store_dwordx4 v[92:93], v[88:91], off sc1
	v_pk_fma_f32 v[118:119], v[130:131], v[66:67], v[192:193]
	v_pk_fma_f32 v[116:117], v[128:129], v[64:65], v[190:191]
	v_pk_fma_f32 v[102:103], v[114:115], v[66:67], v[208:209]
	v_pk_fma_f32 v[100:101], v[112:113], v[64:65], v[206:207]
	v_pk_fma_f32 v[90:91], v[98:99], v[66:67], v[228:229]
	v_pk_fma_f32 v[88:89], v[96:97], v[64:65], v[226:227]
	v_pk_fma_f32 v[78:79], v[78:79], v[86:87], v[232:233]
	v_pk_fma_f32 v[76:77], v[76:77], v[84:85], v[230:231]
	v_lshlrev_b64 v[158:159], 12, v[72:73]
	global_store_dwordx4 v[124:125], v[116:119], off offset:64 sc1
	global_store_dwordx4 v[108:109], v[100:103], off offset:64 sc1
	global_store_dwordx4 v[92:93], v[88:91], off offset:64 sc1
	global_store_dwordx4 v[92:93], v[76:79], off offset:512 sc1
	v_lshl_add_u64 v[72:73], v[154:155], 0, v[158:159]
	global_load_dwordx4 v[124:127], v[72:73], off
	global_load_dwordx4 v[120:123], v[72:73], off offset:64
	global_load_dwordx4 v[112:115], v[72:73], off offset:512
	global_load_dwordx4 v[100:103], v[72:73], off offset:576
	v_add_u32_e32 v72, 0x90, v156
	v_ashrrev_i32_e32 v73, 31, v72
	v_lshlrev_b64 v[142:143], 12, v[72:73]
	v_lshl_add_u64 v[72:73], v[154:155], 0, v[142:143]
	global_load_dwordx4 v[116:119], v[72:73], off
	global_load_dwordx4 v[104:107], v[72:73], off offset:64
	global_load_dwordx4 v[96:99], v[72:73], off offset:512
	global_load_dwordx4 v[88:91], v[72:73], off offset:576
	v_add_u32_e32 v72, 0xa0, v156
	v_ashrrev_i32_e32 v73, 31, v72
	v_lshlrev_b64 v[140:141], 12, v[72:73]
	v_add_u32_e32 v128, 0xb0, v156
	v_lshl_add_u64 v[72:73], v[154:155], 0, v[140:141]
	v_ashrrev_i32_e32 v129, 31, v128
	global_load_dwordx4 v[108:111], v[72:73], off
	global_load_dwordx4 v[92:95], v[72:73], off offset:64
	global_load_dwordx4 v[76:79], v[72:73], off offset:512
	s_nop 0
	global_load_dwordx4 v[72:75], v[72:73], off offset:576
	v_lshlrev_b64 v[156:157], 12, v[128:129]
	v_lshl_add_u64 v[132:133], v[154:155], 0, v[156:157]
	global_load_dwordx4 v[128:131], v[132:133], off
	global_load_dwordx4 v[170:173], v[132:133], off offset:64
	global_load_dwordx4 v[136:139], v[132:133], off offset:512
	s_nop 0
	global_load_dwordx4 v[132:135], v[132:133], off offset:576
	s_waitcnt vmcnt(15)
	v_pk_fma_f32 v[60:61], v[60:61], v[68:69], v[124:125]
	v_lshl_add_u64 v[124:125], s[36:37], 0, v[158:159]
	v_lshl_add_u64 v[124:125], v[124:125], 0, v[152:153]
	s_waitcnt vmcnt(13)
	v_pk_fma_f32 v[50:51], v[50:51], v[86:87], v[114:115]
	v_pk_fma_f32 v[48:49], v[48:49], v[84:85], v[112:113]
	global_store_dwordx4 v[124:125], v[48:51], off offset:512 sc1
	s_waitcnt vmcnt(13)
	v_pk_fma_f32 v[42:43], v[42:43], v[82:83], v[102:103]
	s_waitcnt vmcnt(10)
	v_pk_fma_f32 v[34:35], v[34:35], v[86:87], v[98:99]
	v_lshl_add_u64 v[48:49], s[36:37], 0, v[142:143]
	v_lshl_add_u64 v[48:49], v[48:49], 0, v[152:153]
	v_pk_fma_f32 v[32:33], v[32:33], v[84:85], v[96:97]
	global_store_dwordx4 v[48:49], v[32:35], off offset:512 sc1
	v_pk_fma_f32 v[40:41], v[40:41], v[80:81], v[100:101]
	s_waitcnt vmcnt(10)
	v_pk_fma_f32 v[26:27], v[26:27], v[82:83], v[90:91]
	v_lshl_add_u64 v[32:33], s[36:37], 0, v[140:141]
	v_lshl_add_u64 v[32:33], v[32:33], 0, v[152:153]
	s_waitcnt vmcnt(7)
	v_pk_fma_f32 v[18:19], v[18:19], v[86:87], v[78:79]
	v_pk_fma_f32 v[16:17], v[16:17], v[84:85], v[76:77]
	v_pk_fma_f32 v[24:25], v[24:25], v[80:81], v[88:89]
	global_store_dwordx4 v[32:33], v[16:19], off offset:512 sc1
	s_waitcnt vmcnt(7)
	v_pk_fma_f32 v[10:11], v[10:11], v[82:83], v[74:75]
	v_pk_fma_f32 v[8:9], v[8:9], v[80:81], v[72:73]
	v_lshl_add_u64 v[16:17], s[36:37], 0, v[156:157]
	global_store_dwordx4 v[124:125], v[40:43], off offset:576 sc1
	global_store_dwordx4 v[48:49], v[24:27], off offset:576 sc1
	global_store_dwordx4 v[32:33], v[8:11], off offset:576 sc1
	v_pk_fma_f32 v[42:43], v[54:55], v[70:71], v[118:119]
	v_pk_fma_f32 v[40:41], v[52:53], v[68:69], v[116:117]
	v_pk_fma_f32 v[26:27], v[38:39], v[70:71], v[110:111]
	v_pk_fma_f32 v[24:25], v[36:37], v[68:69], v[108:109]
	s_waitcnt vmcnt(9)
	v_pk_fma_f32 v[10:11], v[22:23], v[70:71], v[130:131]
	v_pk_fma_f32 v[8:9], v[20:21], v[68:69], v[128:129]
	v_lshl_add_u64 v[16:17], v[16:17], 0, v[152:153]
	v_pk_fma_f32 v[62:63], v[62:63], v[70:71], v[126:127]
	v_pk_fma_f32 v[58:59], v[58:59], v[66:67], v[122:123]
	v_pk_fma_f32 v[56:57], v[56:57], v[64:65], v[120:121]
	global_store_dwordx4 v[48:49], v[40:43], off sc1
	global_store_dwordx4 v[32:33], v[24:27], off sc1
	global_store_dwordx4 v[16:17], v[8:11], off sc1
	v_pk_fma_f32 v[42:43], v[46:47], v[66:67], v[106:107]
	v_pk_fma_f32 v[40:41], v[44:45], v[64:65], v[104:105]
	v_pk_fma_f32 v[26:27], v[30:31], v[66:67], v[94:95]
	v_pk_fma_f32 v[24:25], v[28:29], v[64:65], v[92:93]
	s_waitcnt vmcnt(11)
	v_pk_fma_f32 v[10:11], v[14:15], v[66:67], v[172:173]
	v_pk_fma_f32 v[8:9], v[12:13], v[64:65], v[170:171]
	s_waitcnt vmcnt(10)
	v_pk_fma_f32 v[6:7], v[6:7], v[86:87], v[138:139]
	v_pk_fma_f32 v[4:5], v[4:5], v[84:85], v[136:137]
	s_waitcnt vmcnt(9)
	v_pk_fma_f32 v[2:3], v[2:3], v[82:83], v[134:135]
	v_pk_fma_f32 v[0:1], v[0:1], v[80:81], v[132:133]
	global_store_dwordx4 v[124:125], v[60:63], off sc1
	global_store_dwordx4 v[124:125], v[56:59], off offset:64 sc1
	global_store_dwordx4 v[48:49], v[40:43], off offset:64 sc1
	global_store_dwordx4 v[32:33], v[24:27], off offset:64 sc1
	global_store_dwordx4 v[16:17], v[8:11], off offset:64 sc1
	global_store_dwordx4 v[16:17], v[4:7], off offset:512 sc1
	global_store_dwordx4 v[16:17], v[0:3], off offset:576 sc1
	s_cbranch_vccnz .LBB0_898
	s_andn2_b64 vcc, exec, s[14:15]
	s_cbranch_vccnz .LBB0_897
	s_barrier
	s_branch .LBB0_897

.LBB0_1054:
	v_lshl_add_u32 v154, s24, 8, v146
	v_lshl_or_b32 v144, s44, 8, v147
	v_ashrrev_i32_e32 v155, 31, v154
	v_ashrrev_i32_e32 v145, 31, v144
	v_lshlrev_b64 v[156:157], 13, v[154:155]
	v_max_f32_e32 v120, v120, v120
	v_max_f32_e32 v121, v121, v121
	v_lshl_add_u64 v[156:157], s[38:39], 0, v[156:157]
	v_lshlrev_b64 v[158:159], 1, v[144:145]
	v_max_f32_e32 v120, 0, v120
	v_max_f32_e32 v121, 0, v121
	v_lshl_add_u64 v[144:145], v[156:157], 0, v[158:159]
	v_pk_mul_f32 v[156:157], v[120:121], v[120:121]
	v_max_f32_e32 v121, v122, v122
	v_max_f32_e32 v124, v124, v124
	v_max_f32_e32 v125, v125, v125
	v_max_f32_e32 v120, v126, v126
	v_max_f32_e32 v122, 0, v121
	v_max_f32_e32 v121, v127, v127
	v_max_f32_e32 v123, v123, v123
	v_max_f32_e32 v124, 0, v124
	v_max_f32_e32 v125, 0, v125
	v_max_f32_e32 v120, 0, v120
	v_max_f32_e32 v121, 0, v121
	v_max_f32_e32 v123, 0, v123
	v_pk_mul_f32 v[124:125], v[124:125], v[124:125]
	v_pk_mul_f32 v[126:127], v[120:121], v[120:121]
	v_pk_mul_f32 v[162:163], v[122:123], v[122:123]
	v_max_f32_e32 v112, v112, v112
	v_max_f32_e32 v113, v113, v113
	v_cvt_pk_bf16_f32 v120, v124, v125
	v_cvt_pk_bf16_f32 v121, v126, v127
	v_cvt_pk_bf16_f32 v122, v156, v157
	v_cvt_pk_bf16_f32 v123, v162, v163
	v_max_f32_e32 v112, 0, v112
	v_max_f32_e32 v113, 0, v113
	global_store_dwordx4 v[144:145], v[120:123], off sc1
	v_max_f32_e32 v116, v116, v116
	v_max_f32_e32 v117, v117, v117
	v_pk_mul_f32 v[120:121], v[112:113], v[112:113]
	v_max_f32_e32 v113, v114, v114
	v_max_f32_e32 v112, v118, v118
	v_max_f32_e32 v114, 0, v113
	v_max_f32_e32 v113, v119, v119
	v_max_f32_e32 v115, v115, v115
	v_max_f32_e32 v116, 0, v116
	v_max_f32_e32 v117, 0, v117
	v_max_f32_e32 v112, 0, v112
	v_max_f32_e32 v113, 0, v113
	v_max_f32_e32 v115, 0, v115
	v_pk_mul_f32 v[116:117], v[116:117], v[116:117]
	v_pk_mul_f32 v[118:119], v[112:113], v[112:113]
	v_pk_mul_f32 v[122:123], v[114:115], v[114:115]
	v_max_f32_e32 v104, v104, v104
	v_max_f32_e32 v105, v105, v105
	v_cvt_pk_bf16_f32 v112, v116, v117
	v_cvt_pk_bf16_f32 v113, v118, v119
	v_cvt_pk_bf16_f32 v114, v120, v121
	v_cvt_pk_bf16_f32 v115, v122, v123
	v_max_f32_e32 v104, 0, v104
	v_max_f32_e32 v105, 0, v105
	global_store_dwordx4 v[144:145], v[112:115], off offset:256 sc1
	v_max_f32_e32 v108, v108, v108
	v_max_f32_e32 v109, v109, v109
	v_or_b32_e32 v112, 16, v154
	v_pk_mul_f32 v[114:115], v[104:105], v[104:105]
	v_max_f32_e32 v105, v106, v106
	v_ashrrev_i32_e32 v113, 31, v112
	v_max_f32_e32 v104, v110, v110
	v_max_f32_e32 v106, 0, v105
	v_max_f32_e32 v105, v111, v111
	v_max_f32_e32 v107, v107, v107
	v_lshlrev_b64 v[112:113], 13, v[112:113]
	v_max_f32_e32 v108, 0, v108
	v_max_f32_e32 v109, 0, v109
	v_max_f32_e32 v104, 0, v104
	v_max_f32_e32 v105, 0, v105
	v_max_f32_e32 v107, 0, v107
	v_lshl_add_u64 v[112:113], s[38:39], 0, v[112:113]
	v_pk_mul_f32 v[108:109], v[108:109], v[108:109]
	v_pk_mul_f32 v[110:111], v[104:105], v[104:105]
	v_pk_mul_f32 v[116:117], v[106:107], v[106:107]
	v_max_f32_e32 v96, v96, v96
	v_max_f32_e32 v97, v97, v97
	v_lshl_add_u64 v[112:113], v[112:113], 0, v[158:159]
	v_cvt_pk_bf16_f32 v104, v108, v109
	v_cvt_pk_bf16_f32 v105, v110, v111
	v_cvt_pk_bf16_f32 v106, v114, v115
	v_cvt_pk_bf16_f32 v107, v116, v117
	v_max_f32_e32 v96, 0, v96
	v_max_f32_e32 v97, 0, v97
	global_store_dwordx4 v[112:113], v[104:107], off sc1
	v_max_f32_e32 v100, v100, v100
	v_max_f32_e32 v101, v101, v101
	v_pk_mul_f32 v[104:105], v[96:97], v[96:97]
	v_max_f32_e32 v97, v98, v98
	v_max_f32_e32 v96, v102, v102
	v_max_f32_e32 v98, 0, v97
	v_max_f32_e32 v97, v103, v103
	v_max_f32_e32 v99, v99, v99
	v_max_f32_e32 v100, 0, v100
	v_max_f32_e32 v101, 0, v101
	v_max_f32_e32 v96, 0, v96
	v_max_f32_e32 v97, 0, v97
	v_max_f32_e32 v99, 0, v99
	v_pk_mul_f32 v[100:101], v[100:101], v[100:101]
	v_pk_mul_f32 v[102:103], v[96:97], v[96:97]
	v_pk_mul_f32 v[106:107], v[98:99], v[98:99]
	v_max_f32_e32 v88, v88, v88
	v_max_f32_e32 v89, v89, v89
	v_cvt_pk_bf16_f32 v96, v100, v101
	v_cvt_pk_bf16_f32 v97, v102, v103
	v_cvt_pk_bf16_f32 v98, v104, v105
	v_cvt_pk_bf16_f32 v99, v106, v107
	v_max_f32_e32 v88, 0, v88
	v_max_f32_e32 v89, 0, v89
	global_store_dwordx4 v[112:113], v[96:99], off offset:256 sc1
	v_max_f32_e32 v92, v92, v92
	v_max_f32_e32 v93, v93, v93
	v_or_b32_e32 v96, 32, v154
	v_pk_mul_f32 v[98:99], v[88:89], v[88:89]
	v_max_f32_e32 v89, v90, v90
	v_ashrrev_i32_e32 v97, 31, v96
	v_max_f32_e32 v88, v94, v94
	v_max_f32_e32 v90, 0, v89
	v_max_f32_e32 v89, v95, v95
	v_max_f32_e32 v91, v91, v91
	v_lshlrev_b64 v[96:97], 13, v[96:97]
	v_max_f32_e32 v92, 0, v92
	v_max_f32_e32 v93, 0, v93
	v_max_f32_e32 v88, 0, v88
	v_max_f32_e32 v89, 0, v89
	v_max_f32_e32 v91, 0, v91
	v_lshl_add_u64 v[96:97], s[38:39], 0, v[96:97]
	v_pk_mul_f32 v[92:93], v[92:93], v[92:93]
	v_pk_mul_f32 v[94:95], v[88:89], v[88:89]
	v_pk_mul_f32 v[100:101], v[90:91], v[90:91]
	v_max_f32_e32 v80, v80, v80
	v_max_f32_e32 v81, v81, v81
	v_lshl_add_u64 v[96:97], v[96:97], 0, v[158:159]
	v_cvt_pk_bf16_f32 v88, v92, v93
	v_cvt_pk_bf16_f32 v89, v94, v95
	v_cvt_pk_bf16_f32 v90, v98, v99
	v_cvt_pk_bf16_f32 v91, v100, v101
	v_max_f32_e32 v80, 0, v80
	v_max_f32_e32 v81, 0, v81
	global_store_dwordx4 v[96:97], v[88:91], off sc1
	v_max_f32_e32 v84, v84, v84
	v_max_f32_e32 v85, v85, v85
	v_pk_mul_f32 v[88:89], v[80:81], v[80:81]
	v_max_f32_e32 v81, v82, v82
	v_max_f32_e32 v80, v86, v86
	v_max_f32_e32 v82, 0, v81
	v_max_f32_e32 v81, v87, v87
	v_max_f32_e32 v83, v83, v83
	v_max_f32_e32 v84, 0, v84
	v_max_f32_e32 v85, 0, v85
	v_max_f32_e32 v80, 0, v80
	v_max_f32_e32 v81, 0, v81
	v_max_f32_e32 v83, 0, v83
	v_pk_mul_f32 v[84:85], v[84:85], v[84:85]
	v_pk_mul_f32 v[86:87], v[80:81], v[80:81]
	v_pk_mul_f32 v[90:91], v[82:83], v[82:83]
	v_max_f32_e32 v72, v72, v72
	v_max_f32_e32 v73, v73, v73
	v_cvt_pk_bf16_f32 v80, v84, v85
	v_cvt_pk_bf16_f32 v81, v86, v87
	v_cvt_pk_bf16_f32 v82, v88, v89
	v_cvt_pk_bf16_f32 v83, v90, v91
	v_max_f32_e32 v72, 0, v72
	v_max_f32_e32 v73, 0, v73
	global_store_dwordx4 v[96:97], v[80:83], off offset:256 sc1
	v_max_f32_e32 v76, v76, v76
	v_max_f32_e32 v77, v77, v77
	v_or_b32_e32 v80, 48, v154
	v_pk_mul_f32 v[82:83], v[72:73], v[72:73]
	v_max_f32_e32 v73, v74, v74
	v_ashrrev_i32_e32 v81, 31, v80
	v_max_f32_e32 v72, v78, v78
	v_max_f32_e32 v74, 0, v73
	v_max_f32_e32 v73, v79, v79
	v_max_f32_e32 v75, v75, v75
	v_lshlrev_b64 v[80:81], 13, v[80:81]
	v_max_f32_e32 v76, 0, v76
	v_max_f32_e32 v77, 0, v77
	v_max_f32_e32 v72, 0, v72
	v_max_f32_e32 v73, 0, v73
	v_max_f32_e32 v75, 0, v75
	v_lshl_add_u64 v[80:81], s[38:39], 0, v[80:81]
	v_pk_mul_f32 v[76:77], v[76:77], v[76:77]
	v_pk_mul_f32 v[78:79], v[72:73], v[72:73]
	v_pk_mul_f32 v[84:85], v[74:75], v[74:75]
	v_max_f32_e32 v64, v64, v64
	v_max_f32_e32 v65, v65, v65
	v_lshl_add_u64 v[80:81], v[80:81], 0, v[158:159]
	v_cvt_pk_bf16_f32 v72, v76, v77
	v_cvt_pk_bf16_f32 v73, v78, v79
	v_cvt_pk_bf16_f32 v74, v82, v83
	v_cvt_pk_bf16_f32 v75, v84, v85
	v_max_f32_e32 v64, 0, v64
	v_max_f32_e32 v65, 0, v65
	global_store_dwordx4 v[80:81], v[72:75], off sc1
	v_max_f32_e32 v68, v68, v68
	v_max_f32_e32 v69, v69, v69
	v_pk_mul_f32 v[72:73], v[64:65], v[64:65]
	v_max_f32_e32 v65, v66, v66
	v_max_f32_e32 v64, v70, v70
	v_max_f32_e32 v66, 0, v65
	v_max_f32_e32 v65, v71, v71
	v_max_f32_e32 v67, v67, v67
	v_max_f32_e32 v68, 0, v68
	v_max_f32_e32 v69, 0, v69
	v_max_f32_e32 v64, 0, v64
	v_max_f32_e32 v65, 0, v65
	v_max_f32_e32 v67, 0, v67
	v_pk_mul_f32 v[68:69], v[68:69], v[68:69]
	v_pk_mul_f32 v[70:71], v[64:65], v[64:65]
	v_pk_mul_f32 v[74:75], v[66:67], v[66:67]
	v_max_f32_e32 v56, v56, v56
	v_max_f32_e32 v57, v57, v57
	v_cvt_pk_bf16_f32 v64, v68, v69
	v_cvt_pk_bf16_f32 v65, v70, v71
	v_cvt_pk_bf16_f32 v66, v72, v73
	v_cvt_pk_bf16_f32 v67, v74, v75
	v_max_f32_e32 v56, 0, v56
	v_max_f32_e32 v57, 0, v57
	global_store_dwordx4 v[80:81], v[64:67], off offset:256 sc1
	v_max_f32_e32 v60, v60, v60
	v_max_f32_e32 v61, v61, v61
	v_pk_mul_f32 v[66:67], v[56:57], v[56:57]
	v_max_f32_e32 v57, v58, v58
	v_max_f32_e32 v60, 0, v60
	v_max_f32_e32 v61, 0, v61
	v_max_f32_e32 v56, v62, v62
	v_max_f32_e32 v58, 0, v57
	v_max_f32_e32 v57, v63, v63
	v_max_f32_e32 v59, v59, v59
	v_pk_mul_f32 v[60:61], v[60:61], v[60:61]
	v_max_f32_e32 v56, 0, v56
	v_max_f32_e32 v57, 0, v57
	v_max_f32_e32 v59, 0, v59
	s_mov_b32 s17, 0x100000
	v_pk_mul_f32 v[62:63], v[56:57], v[56:57]
	v_pk_mul_f32 v[68:69], v[58:59], v[58:59]
	v_cvt_pk_bf16_f32 v56, v60, v61
	v_add_co_u32_e32 v60, vcc, s17, v144
	v_max_f32_e32 v48, v48, v48
	v_max_f32_e32 v49, v49, v49
	v_cvt_pk_bf16_f32 v57, v62, v63
	v_cvt_pk_bf16_f32 v58, v66, v67
	v_cvt_pk_bf16_f32 v59, v68, v69
	v_addc_co_u32_e32 v61, vcc, 0, v145, vcc
	v_max_f32_e32 v48, 0, v48
	v_max_f32_e32 v49, 0, v49
	global_store_dwordx4 v[60:61], v[56:59], off sc1
	v_max_f32_e32 v52, v52, v52
	v_max_f32_e32 v53, v53, v53
	v_pk_mul_f32 v[56:57], v[48:49], v[48:49]
	v_max_f32_e32 v49, v50, v50
	v_max_f32_e32 v48, v54, v54
	v_max_f32_e32 v50, 0, v49
	v_max_f32_e32 v49, v55, v55
	v_max_f32_e32 v51, v51, v51
	v_max_f32_e32 v52, 0, v52
	v_max_f32_e32 v53, 0, v53
	v_max_f32_e32 v48, 0, v48
	v_max_f32_e32 v49, 0, v49
	v_max_f32_e32 v51, 0, v51
	s_mov_b64 s[44:45], 0x100000
	v_pk_mul_f32 v[52:53], v[52:53], v[52:53]
	v_pk_mul_f32 v[54:55], v[48:49], v[48:49]
	v_pk_mul_f32 v[58:59], v[50:51], v[50:51]
	v_max_f32_e32 v40, v40, v40
	v_max_f32_e32 v41, v41, v41
	v_lshl_add_u64 v[64:65], v[144:145], 0, s[44:45]
	v_cvt_pk_bf16_f32 v48, v52, v53
	v_cvt_pk_bf16_f32 v49, v54, v55
	v_cvt_pk_bf16_f32 v50, v56, v57
	v_cvt_pk_bf16_f32 v51, v58, v59
	v_max_f32_e32 v40, 0, v40
	v_max_f32_e32 v41, 0, v41
	global_store_dwordx4 v[64:65], v[48:51], off offset:256 sc1
	v_max_f32_e32 v44, v44, v44
	v_max_f32_e32 v45, v45, v45
	v_pk_mul_f32 v[50:51], v[40:41], v[40:41]
	v_max_f32_e32 v41, v42, v42
	v_max_f32_e32 v44, 0, v44
	v_max_f32_e32 v45, 0, v45
	v_max_f32_e32 v40, v46, v46
	v_max_f32_e32 v42, 0, v41
	v_max_f32_e32 v41, v47, v47
	v_max_f32_e32 v43, v43, v43
	v_pk_mul_f32 v[44:45], v[44:45], v[44:45]
	v_max_f32_e32 v40, 0, v40
	v_max_f32_e32 v41, 0, v41
	v_max_f32_e32 v43, 0, v43
	s_mov_b32 s17, 0x120000
	v_pk_mul_f32 v[46:47], v[40:41], v[40:41]
	v_pk_mul_f32 v[52:53], v[42:43], v[42:43]
	v_cvt_pk_bf16_f32 v40, v44, v45
	v_add_co_u32_e32 v44, vcc, s17, v144
	v_max_f32_e32 v32, v32, v32
	v_max_f32_e32 v33, v33, v33
	v_cvt_pk_bf16_f32 v41, v46, v47
	v_cvt_pk_bf16_f32 v42, v50, v51
	v_cvt_pk_bf16_f32 v43, v52, v53
	v_addc_co_u32_e32 v45, vcc, 0, v145, vcc
	v_max_f32_e32 v32, 0, v32
	v_max_f32_e32 v33, 0, v33
	global_store_dwordx4 v[44:45], v[40:43], off sc1
	v_max_f32_e32 v36, v36, v36
	v_max_f32_e32 v37, v37, v37
	v_pk_mul_f32 v[40:41], v[32:33], v[32:33]
	v_max_f32_e32 v33, v34, v34
	v_max_f32_e32 v32, v38, v38
	v_max_f32_e32 v34, 0, v33
	v_max_f32_e32 v33, v39, v39
	v_max_f32_e32 v35, v35, v35
	v_max_f32_e32 v36, 0, v36
	v_max_f32_e32 v37, 0, v37
	v_max_f32_e32 v32, 0, v32
	v_max_f32_e32 v33, 0, v33
	v_max_f32_e32 v35, 0, v35
	s_mov_b64 s[44:45], 0x120000
	v_pk_mul_f32 v[36:37], v[36:37], v[36:37]
	v_pk_mul_f32 v[38:39], v[32:33], v[32:33]
	v_pk_mul_f32 v[42:43], v[34:35], v[34:35]
	v_max_f32_e32 v24, v24, v24
	v_max_f32_e32 v25, v25, v25
	v_lshl_add_u64 v[48:49], v[144:145], 0, s[44:45]
	v_cvt_pk_bf16_f32 v32, v36, v37
	v_cvt_pk_bf16_f32 v33, v38, v39
	v_cvt_pk_bf16_f32 v34, v40, v41
	v_cvt_pk_bf16_f32 v35, v42, v43
	v_max_f32_e32 v24, 0, v24
	v_max_f32_e32 v25, 0, v25
	global_store_dwordx4 v[48:49], v[32:35], off offset:256 sc1
	v_max_f32_e32 v28, v28, v28
	v_max_f32_e32 v29, v29, v29
	v_pk_mul_f32 v[34:35], v[24:25], v[24:25]
	v_max_f32_e32 v25, v26, v26
	v_max_f32_e32 v28, 0, v28
	v_max_f32_e32 v29, 0, v29
	v_max_f32_e32 v24, v30, v30
	v_max_f32_e32 v26, 0, v25
	v_max_f32_e32 v25, v31, v31
	v_max_f32_e32 v27, v27, v27
	v_pk_mul_f32 v[28:29], v[28:29], v[28:29]
	v_max_f32_e32 v24, 0, v24
	v_max_f32_e32 v25, 0, v25
	v_max_f32_e32 v27, 0, v27
	s_mov_b32 s17, 0x140000
	v_pk_mul_f32 v[30:31], v[24:25], v[24:25]
	v_pk_mul_f32 v[36:37], v[26:27], v[26:27]
	v_cvt_pk_bf16_f32 v24, v28, v29
	v_add_co_u32_e32 v28, vcc, s17, v144
	v_max_f32_e32 v16, v16, v16
	v_max_f32_e32 v17, v17, v17
	v_cvt_pk_bf16_f32 v25, v30, v31
	v_cvt_pk_bf16_f32 v26, v34, v35
	v_cvt_pk_bf16_f32 v27, v36, v37
	v_addc_co_u32_e32 v29, vcc, 0, v145, vcc
	v_max_f32_e32 v16, 0, v16
	v_max_f32_e32 v17, 0, v17
	global_store_dwordx4 v[28:29], v[24:27], off sc1
	v_max_f32_e32 v20, v20, v20
	v_max_f32_e32 v21, v21, v21
	v_pk_mul_f32 v[24:25], v[16:17], v[16:17]
	v_max_f32_e32 v17, v18, v18
	v_max_f32_e32 v16, v22, v22
	v_max_f32_e32 v18, 0, v17
	v_max_f32_e32 v17, v23, v23
	v_max_f32_e32 v19, v19, v19
	v_max_f32_e32 v20, 0, v20
	v_max_f32_e32 v21, 0, v21
	v_max_f32_e32 v16, 0, v16
	v_max_f32_e32 v17, 0, v17
	v_max_f32_e32 v19, 0, v19
	s_mov_b64 s[44:45], 0x140000
	v_pk_mul_f32 v[20:21], v[20:21], v[20:21]
	v_pk_mul_f32 v[22:23], v[16:17], v[16:17]
	v_pk_mul_f32 v[26:27], v[18:19], v[18:19]
	v_max_f32_e32 v8, v8, v8
	v_max_f32_e32 v9, v9, v9
	v_lshl_add_u64 v[32:33], v[144:145], 0, s[44:45]
	v_cvt_pk_bf16_f32 v16, v20, v21
	v_cvt_pk_bf16_f32 v17, v22, v23
	v_cvt_pk_bf16_f32 v18, v24, v25
	v_cvt_pk_bf16_f32 v19, v26, v27
	v_max_f32_e32 v8, 0, v8
	v_max_f32_e32 v9, 0, v9
	global_store_dwordx4 v[32:33], v[16:19], off offset:256 sc1
	v_max_f32_e32 v12, v12, v12
	v_max_f32_e32 v13, v13, v13
	v_pk_mul_f32 v[18:19], v[8:9], v[8:9]
	v_max_f32_e32 v9, v10, v10
	v_max_f32_e32 v12, 0, v12
	v_max_f32_e32 v13, 0, v13
	v_max_f32_e32 v8, v14, v14
	v_max_f32_e32 v10, 0, v9
	v_max_f32_e32 v9, v15, v15
	v_max_f32_e32 v11, v11, v11
	v_pk_mul_f32 v[12:13], v[12:13], v[12:13]
	v_max_f32_e32 v8, 0, v8
	v_max_f32_e32 v9, 0, v9
	v_max_f32_e32 v11, 0, v11
	v_pk_mul_f32 v[14:15], v[8:9], v[8:9]
	v_pk_mul_f32 v[20:21], v[10:11], v[10:11]
	v_cvt_pk_bf16_f32 v8, v12, v13
	v_add_co_u32_e32 v12, vcc, s40, v144
	v_max_f32_e32 v0, v0, v0
	v_max_f32_e32 v1, v1, v1
	v_cvt_pk_bf16_f32 v9, v14, v15
	v_cvt_pk_bf16_f32 v10, v18, v19
	v_cvt_pk_bf16_f32 v11, v20, v21
	v_addc_co_u32_e32 v13, vcc, 0, v145, vcc
	v_max_f32_e32 v0, 0, v0
	v_max_f32_e32 v1, 0, v1
	global_store_dwordx4 v[12:13], v[8:11], off sc1
	v_max_f32_e32 v4, v4, v4
	v_max_f32_e32 v5, v5, v5
	v_pk_mul_f32 v[8:9], v[0:1], v[0:1]
	v_max_f32_e32 v1, v2, v2
	v_max_f32_e32 v0, v6, v6
	v_max_f32_e32 v2, 0, v1
	v_max_f32_e32 v1, v7, v7
	v_max_f32_e32 v3, v3, v3
	v_max_f32_e32 v4, 0, v4
	v_max_f32_e32 v5, 0, v5
	v_max_f32_e32 v0, 0, v0
	v_max_f32_e32 v1, 0, v1
	v_max_f32_e32 v3, 0, v3
	s_mov_b64 s[44:45], 0x160000
	v_pk_mul_f32 v[4:5], v[4:5], v[4:5]
	v_pk_mul_f32 v[6:7], v[0:1], v[0:1]
	v_pk_mul_f32 v[10:11], v[2:3], v[2:3]
	v_lshl_add_u64 v[16:17], v[144:145], 0, s[44:45]
	v_cvt_pk_bf16_f32 v0, v4, v5
	v_cvt_pk_bf16_f32 v1, v6, v7
	v_cvt_pk_bf16_f32 v2, v8, v9
	v_cvt_pk_bf16_f32 v3, v10, v11
	s_andn2_b64 vcc, exec, s[8:9]
	s_mov_b64 s[8:9], -1
	global_store_dwordx4 v[16:17], v[0:3], off offset:256 sc1
	s_cbranch_vccnz .LBB0_1043
	s_andn2_b64 vcc, exec, s[10:11]
	s_cbranch_vccnz .LBB0_1042
	s_barrier
	s_branch .LBB0_1042

.LBB0_1130:
	v_lshl_or_b32 v140, s25, 8, v149
	v_ashrrev_i32_e32 v141, 31, v140
	v_lshl_add_u32 v144, s24, 8, v148
	v_lshlrev_b64 v[140:141], 2, v[140:141]
	v_ashrrev_i32_e32 v145, 31, v144
	v_lshl_add_u64 v[142:143], s[36:37], 0, v[140:141]
	v_lshlrev_b64 v[146:147], 12, v[144:145]
	v_or_b32_e32 v174, 16, v144
	v_lshl_add_u64 v[170:171], v[142:143], 0, v[146:147]
	v_ashrrev_i32_e32 v175, 31, v174
	global_load_dwordx4 v[156:159], v[170:171], off
	global_load_dwordx4 v[162:165], v[170:171], off offset:64
	global_load_dwordx4 v[166:169], v[170:171], off offset:512
	s_nop 0
	global_load_dwordx4 v[170:173], v[170:171], off offset:576
	v_lshlrev_b64 v[226:227], 12, v[174:175]
	v_or_b32_e32 v190, 32, v144
	v_lshl_add_u64 v[186:187], v[142:143], 0, v[226:227]
	v_ashrrev_i32_e32 v191, 31, v190
	v_or_b32_e32 v206, 48, v144
	global_load_dwordx4 v[174:177], v[186:187], off
	global_load_dwordx4 v[178:181], v[186:187], off offset:64
	global_load_dwordx4 v[182:185], v[186:187], off offset:512
	s_nop 0
	global_load_dwordx4 v[186:189], v[186:187], off offset:576
	v_lshlrev_b64 v[228:229], 12, v[190:191]
	v_ashrrev_i32_e32 v207, 31, v206
	v_lshl_add_u64 v[202:203], v[142:143], 0, v[228:229]
	v_lshlrev_b64 v[230:231], 12, v[206:207]
	global_load_dwordx4 v[190:193], v[202:203], off
	global_load_dwordx4 v[194:197], v[202:203], off offset:64
	global_load_dwordx4 v[198:201], v[202:203], off offset:512
	s_nop 0
	global_load_dwordx4 v[202:205], v[202:203], off offset:576
	v_lshl_add_u64 v[222:223], v[142:143], 0, v[230:231]
	global_load_dwordx4 v[206:209], v[222:223], off
	global_load_dwordx4 v[214:217], v[222:223], off offset:64
	global_load_dwordx4 v[218:221], v[222:223], off offset:512
	s_nop 0
	global_load_dwordx4 v[222:225], v[222:223], off offset:576
	v_lshl_add_u64 v[146:147], s[36:37], 0, v[146:147]
	v_lshl_add_u64 v[146:147], v[146:147], 0, v[140:141]
	s_mov_b64 s[24:25], -1
	s_andn2_b64 vcc, exec, s[8:9]
	s_waitcnt vmcnt(0)
	v_pk_add_f32 v[126:127], v[126:127], v[158:159]
	v_pk_add_f32 v[124:125], v[124:125], v[156:157]
	v_pk_add_f32 v[110:111], v[110:111], v[168:169]
	v_pk_add_f32 v[108:109], v[108:109], v[166:167]
	global_store_dwordx4 v[146:147], v[108:111], off offset:512 sc1
	v_pk_add_f32 v[102:103], v[102:103], v[172:173]
	v_pk_add_f32 v[100:101], v[100:101], v[170:171]
	v_lshl_add_u64 v[108:109], s[36:37], 0, v[226:227]
	v_lshl_add_u64 v[108:109], v[108:109], 0, v[140:141]
	v_pk_add_f32 v[94:95], v[94:95], v[184:185]
	v_pk_add_f32 v[92:93], v[92:93], v[182:183]
	global_store_dwordx4 v[108:109], v[92:95], off offset:512 sc1
	v_pk_add_f32 v[86:87], v[86:87], v[188:189]
	v_pk_add_f32 v[78:79], v[78:79], v[200:201]
	v_lshl_add_u64 v[92:93], s[36:37], 0, v[228:229]
	v_lshl_add_u64 v[92:93], v[92:93], 0, v[140:141]
	v_pk_add_f32 v[76:77], v[76:77], v[198:199]
	global_store_dwordx4 v[92:93], v[76:79], off offset:512 sc1
	v_pk_add_f32 v[66:67], v[66:67], v[224:225]
	v_pk_add_f32 v[64:65], v[64:65], v[222:223]
	v_lshl_add_u64 v[76:77], s[36:37], 0, v[230:231]
	v_lshl_add_u64 v[76:77], v[76:77], 0, v[140:141]
	v_pk_add_f32 v[84:85], v[84:85], v[186:187]
	v_pk_add_f32 v[74:75], v[74:75], v[204:205]
	v_pk_add_f32 v[72:73], v[72:73], v[202:203]
	global_store_dwordx4 v[76:77], v[64:67], off offset:576 sc1
	v_pk_add_f32 v[122:123], v[122:123], v[164:165]
	v_pk_add_f32 v[120:121], v[120:121], v[162:163]
	v_add_u32_e32 v64, 0x80, v144
	global_store_dwordx4 v[146:147], v[100:103], off offset:576 sc1
	global_store_dwordx4 v[108:109], v[84:87], off offset:576 sc1
	global_store_dwordx4 v[92:93], v[72:75], off offset:576 sc1
	v_pk_add_f32 v[102:103], v[118:119], v[176:177]
	v_pk_add_f32 v[100:101], v[116:117], v[174:175]
	v_pk_add_f32 v[86:87], v[106:107], v[192:193]
	v_pk_add_f32 v[84:85], v[104:105], v[190:191]
	v_pk_add_f32 v[74:75], v[90:91], v[208:209]
	v_pk_add_f32 v[72:73], v[88:89], v[206:207]
	v_ashrrev_i32_e32 v65, 31, v64
	global_store_dwordx4 v[146:147], v[124:127], off sc1
	global_store_dwordx4 v[146:147], v[120:123], off offset:64 sc1
	global_store_dwordx4 v[108:109], v[100:103], off sc1
	global_store_dwordx4 v[92:93], v[84:87], off sc1
	global_store_dwordx4 v[76:77], v[72:75], off sc1
	v_pk_add_f32 v[102:103], v[114:115], v[180:181]
	v_pk_add_f32 v[100:101], v[112:113], v[178:179]
	v_pk_add_f32 v[86:87], v[98:99], v[196:197]
	v_pk_add_f32 v[84:85], v[96:97], v[194:195]
	v_pk_add_f32 v[74:75], v[82:83], v[216:217]
	v_pk_add_f32 v[72:73], v[80:81], v[214:215]
	v_pk_add_f32 v[70:71], v[70:71], v[220:221]
	v_pk_add_f32 v[68:69], v[68:69], v[218:219]
	v_lshlrev_b64 v[146:147], 12, v[64:65]
	global_store_dwordx4 v[108:109], v[100:103], off offset:64 sc1
	global_store_dwordx4 v[92:93], v[84:87], off offset:64 sc1
	global_store_dwordx4 v[76:77], v[72:75], off offset:64 sc1
	global_store_dwordx4 v[76:77], v[68:71], off offset:512 sc1
	v_lshl_add_u64 v[64:65], v[142:143], 0, v[146:147]
	global_load_dwordx4 v[108:111], v[64:65], off
	global_load_dwordx4 v[104:107], v[64:65], off offset:64
	global_load_dwordx4 v[96:99], v[64:65], off offset:512
	global_load_dwordx4 v[84:87], v[64:65], off offset:576
	v_add_u32_e32 v64, 0x90, v144
	v_ashrrev_i32_e32 v65, 31, v64
	v_lshlrev_b64 v[126:127], 12, v[64:65]
	v_lshl_add_u64 v[64:65], v[142:143], 0, v[126:127]
	global_load_dwordx4 v[100:103], v[64:65], off
	global_load_dwordx4 v[88:91], v[64:65], off offset:64
	global_load_dwordx4 v[80:83], v[64:65], off offset:512
	global_load_dwordx4 v[72:75], v[64:65], off offset:576
	v_add_u32_e32 v64, 0xa0, v144
	v_ashrrev_i32_e32 v65, 31, v64
	v_lshlrev_b64 v[124:125], 12, v[64:65]
	v_add_u32_e32 v112, 0xb0, v144
	v_lshl_add_u64 v[64:65], v[142:143], 0, v[124:125]
	v_ashrrev_i32_e32 v113, 31, v112
	global_load_dwordx4 v[92:95], v[64:65], off
	global_load_dwordx4 v[76:79], v[64:65], off offset:64
	global_load_dwordx4 v[68:71], v[64:65], off offset:512
	s_nop 0
	global_load_dwordx4 v[64:67], v[64:65], off offset:576
	v_lshlrev_b64 v[144:145], 12, v[112:113]
	v_lshl_add_u64 v[116:117], v[142:143], 0, v[144:145]
	global_load_dwordx4 v[112:115], v[116:117], off
	global_load_dwordx4 v[156:159], v[116:117], off offset:64
	global_load_dwordx4 v[120:123], v[116:117], off offset:512
	s_nop 0
	global_load_dwordx4 v[116:119], v[116:117], off offset:576
	s_waitcnt vmcnt(15)
	v_pk_add_f32 v[60:61], v[60:61], v[108:109]
	v_lshl_add_u64 v[108:109], s[36:37], 0, v[146:147]
	v_lshl_add_u64 v[108:109], v[108:109], 0, v[140:141]
	s_waitcnt vmcnt(13)
	v_pk_add_f32 v[50:51], v[50:51], v[98:99]
	v_pk_add_f32 v[48:49], v[48:49], v[96:97]
	global_store_dwordx4 v[108:109], v[48:51], off offset:512 sc1
	s_waitcnt vmcnt(13)
	v_pk_add_f32 v[42:43], v[42:43], v[86:87]
	s_waitcnt vmcnt(10)
	v_pk_add_f32 v[34:35], v[34:35], v[82:83]
	v_lshl_add_u64 v[48:49], s[36:37], 0, v[126:127]
	v_lshl_add_u64 v[48:49], v[48:49], 0, v[140:141]
	v_pk_add_f32 v[32:33], v[32:33], v[80:81]
	global_store_dwordx4 v[48:49], v[32:35], off offset:512 sc1
	v_pk_add_f32 v[40:41], v[40:41], v[84:85]
	s_waitcnt vmcnt(10)
	v_pk_add_f32 v[26:27], v[26:27], v[74:75]
	v_lshl_add_u64 v[32:33], s[36:37], 0, v[124:125]
	v_lshl_add_u64 v[32:33], v[32:33], 0, v[140:141]
	s_waitcnt vmcnt(7)
	v_pk_add_f32 v[18:19], v[18:19], v[70:71]
	v_pk_add_f32 v[16:17], v[16:17], v[68:69]
	v_pk_add_f32 v[24:25], v[24:25], v[72:73]
	global_store_dwordx4 v[32:33], v[16:19], off offset:512 sc1
	s_waitcnt vmcnt(7)
	v_pk_add_f32 v[10:11], v[10:11], v[66:67]
	v_pk_add_f32 v[8:9], v[8:9], v[64:65]
	v_lshl_add_u64 v[16:17], s[36:37], 0, v[144:145]
	global_store_dwordx4 v[108:109], v[40:43], off offset:576 sc1
	global_store_dwordx4 v[48:49], v[24:27], off offset:576 sc1
	global_store_dwordx4 v[32:33], v[8:11], off offset:576 sc1
	v_pk_add_f32 v[42:43], v[54:55], v[102:103]
	v_pk_add_f32 v[40:41], v[52:53], v[100:101]
	v_pk_add_f32 v[26:27], v[38:39], v[94:95]
	v_pk_add_f32 v[24:25], v[36:37], v[92:93]
	s_waitcnt vmcnt(9)
	v_pk_add_f32 v[10:11], v[22:23], v[114:115]
	v_pk_add_f32 v[8:9], v[20:21], v[112:113]
	v_lshl_add_u64 v[16:17], v[16:17], 0, v[140:141]
	v_pk_add_f32 v[62:63], v[62:63], v[110:111]
	v_pk_add_f32 v[58:59], v[58:59], v[106:107]
	v_pk_add_f32 v[56:57], v[56:57], v[104:105]
	global_store_dwordx4 v[48:49], v[40:43], off sc1
	global_store_dwordx4 v[32:33], v[24:27], off sc1
	global_store_dwordx4 v[16:17], v[8:11], off sc1
	v_pk_add_f32 v[42:43], v[46:47], v[90:91]
	v_pk_add_f32 v[40:41], v[44:45], v[88:89]
	v_pk_add_f32 v[26:27], v[30:31], v[78:79]
	v_pk_add_f32 v[24:25], v[28:29], v[76:77]
	s_waitcnt vmcnt(11)
	v_pk_add_f32 v[10:11], v[14:15], v[158:159]
	v_pk_add_f32 v[8:9], v[12:13], v[156:157]
	s_waitcnt vmcnt(10)
	v_pk_add_f32 v[6:7], v[6:7], v[122:123]
	v_pk_add_f32 v[4:5], v[4:5], v[120:121]
	s_waitcnt vmcnt(9)
	v_pk_add_f32 v[2:3], v[2:3], v[118:119]
	v_pk_add_f32 v[0:1], v[0:1], v[116:117]
	global_store_dwordx4 v[108:109], v[60:63], off sc1
	global_store_dwordx4 v[108:109], v[56:59], off offset:64 sc1
	global_store_dwordx4 v[48:49], v[40:43], off offset:64 sc1
	global_store_dwordx4 v[32:33], v[24:27], off offset:64 sc1
	global_store_dwordx4 v[16:17], v[8:11], off offset:64 sc1
	global_store_dwordx4 v[16:17], v[4:7], off offset:512 sc1
	global_store_dwordx4 v[16:17], v[0:3], off offset:576 sc1
	s_cbranch_vccnz .LBB0_1119
	s_andn2_b64 vcc, exec, s[10:11]
	s_cbranch_vccnz .LBB0_1118
	s_barrier
	s_branch .LBB0_1118

.LBB0_1188:
	v_mul_f32_e32 v59, v29, v29
	v_mul_f32_e32 v60, v31, v31
	v_fmac_f32_e32 v59, v28, v28
	v_fmac_f32_e32 v60, v30, v30
	v_add_f32_e32 v59, v59, v60
	v_mul_f32_e32 v60, v25, v25
	v_mul_f32_e32 v61, v27, v27
	v_fmac_f32_e32 v60, v24, v24
	v_fmac_f32_e32 v61, v26, v26
	v_add_f32_e32 v60, v60, v61
	v_add_f32_e32 v59, v59, v60
	v_mul_f32_e32 v60, v21, v21
	v_mul_f32_e32 v61, v23, v23
	v_fmac_f32_e32 v60, v20, v20
	v_fmac_f32_e32 v61, v22, v22
	v_add_f32_e32 v60, v60, v61
	v_add_f32_e32 v59, v60, v59
	v_mul_f32_e32 v60, v17, v17
	v_mul_f32_e32 v61, v19, v19
	v_fmac_f32_e32 v60, v16, v16
	v_fmac_f32_e32 v61, v18, v18
	v_add_f32_e32 v60, v60, v61
	v_add_f32_e32 v59, v60, v59
	ds_bpermute_b32 v60, v52, v59
	v_lshl_add_u64 v[50:51], v[50:51], 0, s[12:13]
	s_waitcnt lgkmcnt(0)
	v_add_f32_e32 v59, v59, v60
	ds_bpermute_b32 v60, v53, v59
	s_waitcnt lgkmcnt(0)
	v_add_f32_e32 v59, v59, v60
	ds_bpermute_b32 v60, v54, v59
	s_waitcnt lgkmcnt(0)
	v_add_f32_e32 v59, v59, v60
	ds_bpermute_b32 v60, v55, v59
	s_waitcnt lgkmcnt(0)
	v_add_f32_e32 v59, v59, v60
	ds_bpermute_b32 v60, v56, v59
	s_waitcnt lgkmcnt(0)
	v_add_f32_e32 v59, v59, v60
	ds_bpermute_b32 v60, v57, v59
	s_waitcnt lgkmcnt(0)
	v_add_f32_e32 v59, v59, v60
	v_fmamk_f32 v59, v59, 0x3a800000, v58
	v_mul_f32_e32 v60, 0x4b800000, v59
	v_cmp_gt_f32_e32 vcc, s0, v59
	s_nop 1
	v_cndmask_b32_e32 v59, v59, v60, vcc
	v_rsq_f32_e32 v59, v59
	s_nop 0
	v_mul_f32_e32 v60, 0x45800000, v59
	v_cndmask_b32_e32 v60, v59, v60, vcc
	v_pk_mul_f32 v[28:29], v[28:29], v[60:61] op_sel_hi:[1,0]
	v_pk_mul_f32 v[30:31], v[30:31], v[60:61] op_sel_hi:[1,0]
	v_pk_mul_f32 v[24:25], v[24:25], v[60:61] op_sel_hi:[1,0]
	v_pk_mul_f32 v[26:27], v[26:27], v[60:61] op_sel_hi:[1,0]
	v_pk_mul_f32 v[20:21], v[20:21], v[60:61] op_sel_hi:[1,0]
	v_pk_mul_f32 v[22:23], v[22:23], v[60:61] op_sel_hi:[1,0]
	v_pk_mul_f32 v[16:17], v[16:17], v[60:61] op_sel_hi:[1,0]
	v_pk_mul_f32 v[18:19], v[18:19], v[60:61] op_sel_hi:[1,0]
	v_pk_mul_f32 v[30:31], v[2:3], v[30:31]
	v_pk_mul_f32 v[28:29], v[0:1], v[28:29]
	v_pk_mul_f32 v[26:27], v[6:7], v[26:27]
	v_pk_mul_f32 v[24:25], v[4:5], v[24:25]
	v_pk_mul_f32 v[22:23], v[10:11], v[22:23]
	v_pk_mul_f32 v[20:21], v[8:9], v[20:21]
	v_pk_mul_f32 v[18:19], v[14:15], v[18:19]
	v_pk_mul_f32 v[16:17], v[12:13], v[16:17]
	v_cvt_pk_bf16_f32 v28, v28, v29
	v_cvt_pk_bf16_f32 v29, v30, v31
	v_cvt_pk_bf16_f32 v24, v24, v25
	v_cvt_pk_bf16_f32 v25, v26, v27
	v_cvt_pk_bf16_f32 v20, v20, v21
	v_cvt_pk_bf16_f32 v21, v22, v23
	v_cvt_pk_bf16_f32 v16, v16, v17
	v_cvt_pk_bf16_f32 v17, v18, v19
	global_store_dwordx2 v[48:49], v[28:29], off sc1
	global_store_dwordx2 v[48:49], v[24:25], off offset:512 sc1
	global_store_dwordx2 v[48:49], v[20:21], off offset:1024 sc1
	global_store_dwordx2 v[48:49], v[16:17], off offset:1536 sc1
	v_lshl_add_u64 v[48:49], v[48:49], 0, s[10:11]
	s_andn2_b64 vcc, exec, s[14:15]
	s_waitcnt vmcnt(7)
	v_mov_b32_e32 v28, v32
	v_mov_b32_e32 v29, v33
	v_mov_b32_e32 v30, v34
	v_mov_b32_e32 v31, v35
	s_waitcnt vmcnt(6)
	v_mov_b32_e32 v24, v36
	v_mov_b32_e32 v25, v37
	v_mov_b32_e32 v26, v38
	v_mov_b32_e32 v27, v39
	s_waitcnt vmcnt(5)
	v_mov_b32_e32 v20, v40
	v_mov_b32_e32 v21, v41
	v_mov_b32_e32 v22, v42
	v_mov_b32_e32 v23, v43
	s_waitcnt vmcnt(4)
	v_mov_b32_e32 v16, v44
	v_mov_b32_e32 v17, v45
	v_mov_b32_e32 v18, v46
	v_mov_b32_e32 v19, v47
	s_cbranch_vccz .LBB0_1191

.LBB0_1193:
	s_or_b64 exec, exec, s[12:13]
	s_waitcnt vmcnt(0)
	ds_write2_b32 v39, v0, v1 offset1:1
	ds_write2_b32 v39, v2, v3 offset0:2 offset1:3
	v_add_u32_e32 v0, 0x420, v39
	ds_write2_b32 v0, v8, v9 offset1:1
	v_add_u32_e32 v0, 0x428, v39
	ds_write2_b32 v0, v10, v11 offset1:1
	v_add_u32_e32 v0, 0x840, v39
	ds_write2_b32 v0, v4, v5 offset1:1
	v_add_u32_e32 v0, 0x848, v39
	ds_write2_b32 v0, v6, v7 offset1:1
	v_add_u32_e32 v0, 0xc60, v39
	ds_write2_b32 v0, v16, v17 offset1:1
	v_add_u32_e32 v0, 0xc68, v39
	ds_write2_b32 v0, v18, v19 offset1:1
	v_add_u32_e32 v0, 0x1080, v39
	ds_write2_b32 v0, v12, v13 offset1:1
	v_add_u32_e32 v0, 0x1088, v39
	ds_write2_b32 v0, v14, v15 offset1:1
	v_add_u32_e32 v0, 0x14a0, v39
	ds_write2_b32 v0, v24, v25 offset1:1
	v_add_u32_e32 v0, 0x14a8, v39
	ds_write2_b32 v0, v26, v27 offset1:1
	v_add_u32_e32 v0, 0x18c0, v39
	ds_write2_b32 v0, v20, v21 offset1:1
	v_add_u32_e32 v0, 0x18c8, v39
	ds_write2_b32 v0, v22, v23 offset1:1
	v_add_u32_e32 v0, 0x1ce0, v39
	ds_write2_b32 v0, v28, v29 offset1:1
	v_add_u32_e32 v0, 0x1ce8, v39
	ds_write2_b32 v0, v30, v31 offset1:1
	s_waitcnt lgkmcnt(0)
	ds_read2_b32 v[4:5], v38 offset0:33 offset1:41
	ds_read2_b32 v[6:7], v38 offset1:8
	ds_read2_b32 v[8:9], v38 offset0:66 offset1:74
	ds_read2_b32 v[10:11], v38 offset0:99 offset1:107
	ds_read2_b32 v[12:13], v38 offset0:132 offset1:140
	ds_read2_b32 v[14:15], v38 offset0:165 offset1:173
	ds_read2_b32 v[16:17], v38 offset0:198 offset1:206
	ds_read2_b32 v[18:19], v38 offset0:231 offset1:239
	v_add_u32_e32 v22, s4, v37
	s_ashr_i32 s11, s10, 31
	v_ashrrev_i32_e32 v23, 31, v22
	v_lshl_add_u64 v[20:21], s[10:11], 1, v[32:33]
	v_lshlrev_b64 v[24:25], 11, v[22:23]
	s_waitcnt lgkmcnt(6)
	v_cvt_pk_bf16_f32 v0, v6, v4
	s_waitcnt lgkmcnt(4)
	v_cvt_pk_bf16_f32 v1, v8, v10
	s_waitcnt lgkmcnt(2)
	v_cvt_pk_bf16_f32 v2, v12, v14
	s_waitcnt lgkmcnt(0)
	v_cvt_pk_bf16_f32 v3, v16, v18
	v_lshl_add_u64 v[24:25], v[20:21], 0, v[24:25]
	v_add_u32_e32 v4, 8, v22
	global_store_dwordx4 v[24:25], v[0:3], off sc1
	s_add_i32 s0, s0, s34
	s_add_i32 s1, s1, s51
	v_cvt_pk_bf16_f32 v0, v7, v5
	v_ashrrev_i32_e32 v5, 31, v4
	v_cvt_pk_bf16_f32 v1, v9, v11
	v_cvt_pk_bf16_f32 v2, v13, v15
	v_cvt_pk_bf16_f32 v3, v17, v19
	v_lshlrev_b64 v[4:5], 11, v[4:5]
	ds_read2_b32 v[6:7], v38 offset0:49 offset1:57
	ds_read2_b32 v[8:9], v38 offset0:16 offset1:24
	ds_read2_b32 v[10:11], v38 offset0:82 offset1:90
	ds_read2_b32 v[12:13], v38 offset0:115 offset1:123
	ds_read2_b32 v[14:15], v38 offset0:148 offset1:156
	ds_read2_b32 v[16:17], v38 offset0:181 offset1:189
	ds_read2_b32 v[18:19], v38 offset0:214 offset1:222
	ds_read2_b32 v[24:25], v38 offset0:247 offset1:255
	v_lshl_add_u64 v[4:5], v[20:21], 0, v[4:5]
	global_store_dwordx4 v[4:5], v[0:3], off sc1
	v_add_u32_e32 v4, 16, v22
	v_ashrrev_i32_e32 v5, 31, v4
	v_lshlrev_b64 v[4:5], 11, v[4:5]
	s_waitcnt lgkmcnt(6)
	v_cvt_pk_bf16_f32 v0, v8, v6
	s_waitcnt lgkmcnt(4)
	v_cvt_pk_bf16_f32 v1, v10, v12
	s_waitcnt lgkmcnt(2)
	v_cvt_pk_bf16_f32 v2, v14, v16
	s_waitcnt lgkmcnt(0)
	v_cvt_pk_bf16_f32 v3, v18, v24
	v_lshl_add_u64 v[4:5], v[20:21], 0, v[4:5]
	global_store_dwordx4 v[4:5], v[0:3], off sc1
	v_add_u32_e32 v4, 24, v22
	v_ashrrev_i32_e32 v5, 31, v4
	v_lshlrev_b64 v[4:5], 11, v[4:5]
	v_cvt_pk_bf16_f32 v0, v9, v7
	v_cvt_pk_bf16_f32 v1, v11, v13
	v_cvt_pk_bf16_f32 v2, v15, v17
	v_cvt_pk_bf16_f32 v3, v19, v25
	v_lshl_add_u64 v[4:5], v[20:21], 0, v[4:5]
	global_store_dwordx4 v[4:5], v[0:3], off sc1
	s_waitcnt lgkmcnt(0)
	s_cmpk_lt_i32 s0, 0x600
	s_cbranch_scc0 .LBB0_1210

.LBB0_1212:
	s_or_b64 exec, exec, s[12:13]
	s_waitcnt vmcnt(0)
	ds_write2_b32 v41, v0, v1 offset1:1
	ds_write2_b32 v41, v2, v3 offset0:2 offset1:3
	v_add_u32_e32 v0, 0x420, v41
	ds_write2_b32 v0, v8, v9 offset1:1
	v_add_u32_e32 v0, 0x428, v41
	ds_write2_b32 v0, v10, v11 offset1:1
	v_add_u32_e32 v0, 0x840, v41
	ds_write2_b32 v0, v4, v5 offset1:1
	v_add_u32_e32 v0, 0x848, v41
	ds_write2_b32 v0, v6, v7 offset1:1
	v_add_u32_e32 v0, 0xc60, v41
	ds_write2_b32 v0, v16, v17 offset1:1
	v_add_u32_e32 v0, 0xc68, v41
	ds_write2_b32 v0, v18, v19 offset1:1
	v_add_u32_e32 v0, 0x1080, v41
	ds_write2_b32 v0, v12, v13 offset1:1
	v_add_u32_e32 v0, 0x1088, v41
	ds_write2_b32 v0, v14, v15 offset1:1
	v_add_u32_e32 v0, 0x14a0, v41
	ds_write2_b32 v0, v24, v25 offset1:1
	v_add_u32_e32 v0, 0x14a8, v41
	ds_write2_b32 v0, v26, v27 offset1:1
	v_add_u32_e32 v0, 0x18c0, v41
	ds_write2_b32 v0, v20, v21 offset1:1
	v_add_u32_e32 v0, 0x18c8, v41
	ds_write2_b32 v0, v22, v23 offset1:1
	v_add_u32_e32 v0, 0x1ce0, v41
	ds_write2_b32 v0, v28, v29 offset1:1
	v_add_u32_e32 v0, 0x1ce8, v41
	ds_write2_b32 v0, v30, v31 offset1:1
	s_waitcnt lgkmcnt(0)
	s_sub_i32 s3, 0, s3
	ds_read2_b32 v[4:5], v40 offset0:33 offset1:41
	ds_read2_b32 v[6:7], v40 offset1:8
	ds_read2_b32 v[8:9], v40 offset0:66 offset1:74
	ds_read2_b32 v[10:11], v40 offset0:99 offset1:107
	ds_read2_b32 v[12:13], v40 offset0:132 offset1:140
	ds_read2_b32 v[14:15], v40 offset0:165 offset1:173
	ds_read2_b32 v[16:17], v40 offset0:198 offset1:206
	ds_read2_b32 v[18:19], v40 offset0:231 offset1:239
	s_add_i32 s3, s3, s1
	v_add_u32_e32 v22, s3, v39
	s_ashr_i32 s11, s10, 31
	v_ashrrev_i32_e32 v23, 31, v22
	v_lshl_add_u64 v[20:21], s[10:11], 1, v[32:33]
	v_lshlrev_b64 v[24:25], 11, v[22:23]
	s_waitcnt lgkmcnt(6)
	v_cvt_pk_bf16_f32 v0, v6, v4
	s_waitcnt lgkmcnt(4)
	v_cvt_pk_bf16_f32 v1, v8, v10
	s_waitcnt lgkmcnt(2)
	v_cvt_pk_bf16_f32 v2, v12, v14
	s_waitcnt lgkmcnt(0)
	v_cvt_pk_bf16_f32 v3, v16, v18
	v_lshl_add_u64 v[24:25], v[20:21], 0, v[24:25]
	v_add_u32_e32 v4, 8, v22
	global_store_dwordx4 v[24:25], v[0:3], off sc1
	s_add_i32 s0, s0, s34
	s_add_i32 s1, s1, s51
	v_cvt_pk_bf16_f32 v0, v7, v5
	v_ashrrev_i32_e32 v5, 31, v4
	v_cvt_pk_bf16_f32 v1, v9, v11
	v_cvt_pk_bf16_f32 v2, v13, v15
	v_cvt_pk_bf16_f32 v3, v17, v19
	v_lshlrev_b64 v[4:5], 11, v[4:5]
	ds_read2_b32 v[6:7], v40 offset0:49 offset1:57
	ds_read2_b32 v[8:9], v40 offset0:16 offset1:24
	ds_read2_b32 v[10:11], v40 offset0:82 offset1:90
	ds_read2_b32 v[12:13], v40 offset0:115 offset1:123
	ds_read2_b32 v[14:15], v40 offset0:148 offset1:156
	ds_read2_b32 v[16:17], v40 offset0:181 offset1:189
	ds_read2_b32 v[18:19], v40 offset0:214 offset1:222
	ds_read2_b32 v[24:25], v40 offset0:247 offset1:255
	v_lshl_add_u64 v[4:5], v[20:21], 0, v[4:5]
	global_store_dwordx4 v[4:5], v[0:3], off sc1
	v_add_u32_e32 v4, 16, v22
	v_ashrrev_i32_e32 v5, 31, v4
	v_lshlrev_b64 v[4:5], 11, v[4:5]
	s_waitcnt lgkmcnt(6)
	v_cvt_pk_bf16_f32 v0, v8, v6
	s_waitcnt lgkmcnt(4)
	v_cvt_pk_bf16_f32 v1, v10, v12
	s_waitcnt lgkmcnt(2)
	v_cvt_pk_bf16_f32 v2, v14, v16
	s_waitcnt lgkmcnt(0)
	v_cvt_pk_bf16_f32 v3, v18, v24
	v_lshl_add_u64 v[4:5], v[20:21], 0, v[4:5]
	global_store_dwordx4 v[4:5], v[0:3], off sc1
	v_add_u32_e32 v4, 24, v22
	v_ashrrev_i32_e32 v5, 31, v4
	v_lshlrev_b64 v[4:5], 11, v[4:5]
	v_cvt_pk_bf16_f32 v0, v9, v7
	v_cvt_pk_bf16_f32 v1, v11, v13
	v_cvt_pk_bf16_f32 v2, v15, v17
	v_cvt_pk_bf16_f32 v3, v19, v25
	v_lshl_add_u64 v[4:5], v[20:21], 0, v[4:5]
	global_store_dwordx4 v[4:5], v[0:3], off sc1
	s_waitcnt lgkmcnt(0)
	s_cmpk_lt_i32 s0, 0x200
	s_cbranch_scc0 .LBB0_1229

.LBB0_1231:
	s_or_b64 exec, exec, s[12:13]
	s_waitcnt vmcnt(0)
	ds_write2_b32 v41, v0, v1 offset1:1
	ds_write2_b32 v41, v2, v3 offset0:2 offset1:3
	v_add_u32_e32 v0, 0x420, v41
	ds_write2_b32 v0, v8, v9 offset1:1
	v_add_u32_e32 v0, 0x428, v41
	ds_write2_b32 v0, v10, v11 offset1:1
	v_add_u32_e32 v0, 0x840, v41
	ds_write2_b32 v0, v4, v5 offset1:1
	v_add_u32_e32 v0, 0x848, v41
	ds_write2_b32 v0, v6, v7 offset1:1
	v_add_u32_e32 v0, 0xc60, v41
	ds_write2_b32 v0, v16, v17 offset1:1
	v_add_u32_e32 v0, 0xc68, v41
	ds_write2_b32 v0, v18, v19 offset1:1
	v_add_u32_e32 v0, 0x1080, v41
	ds_write2_b32 v0, v12, v13 offset1:1
	v_add_u32_e32 v0, 0x1088, v41
	ds_write2_b32 v0, v14, v15 offset1:1
	v_add_u32_e32 v0, 0x14a0, v41
	ds_write2_b32 v0, v24, v25 offset1:1
	v_add_u32_e32 v0, 0x14a8, v41
	ds_write2_b32 v0, v26, v27 offset1:1
	v_add_u32_e32 v0, 0x18c0, v41
	ds_write2_b32 v0, v20, v21 offset1:1
	v_add_u32_e32 v0, 0x18c8, v41
	ds_write2_b32 v0, v22, v23 offset1:1
	v_add_u32_e32 v0, 0x1ce0, v41
	ds_write2_b32 v0, v28, v29 offset1:1
	v_add_u32_e32 v0, 0x1ce8, v41
	ds_write2_b32 v0, v30, v31 offset1:1
	s_waitcnt lgkmcnt(0)
	s_sub_i32 s3, 0, s3
	ds_read2_b32 v[4:5], v40 offset0:33 offset1:41
	ds_read2_b32 v[6:7], v40 offset1:8
	ds_read2_b32 v[8:9], v40 offset0:66 offset1:74
	ds_read2_b32 v[10:11], v40 offset0:99 offset1:107
	ds_read2_b32 v[12:13], v40 offset0:132 offset1:140
	ds_read2_b32 v[14:15], v40 offset0:165 offset1:173
	ds_read2_b32 v[16:17], v40 offset0:198 offset1:206
	ds_read2_b32 v[18:19], v40 offset0:231 offset1:239
	s_add_i32 s3, s3, s1
	v_add_u32_e32 v22, s3, v39
	s_ashr_i32 s11, s10, 31
	v_ashrrev_i32_e32 v23, 31, v22
	v_lshl_add_u64 v[20:21], s[10:11], 1, v[32:33]
	v_lshlrev_b64 v[24:25], 11, v[22:23]
	s_waitcnt lgkmcnt(6)
	v_cvt_pk_bf16_f32 v0, v6, v4
	s_waitcnt lgkmcnt(4)
	v_cvt_pk_bf16_f32 v1, v8, v10
	s_waitcnt lgkmcnt(2)
	v_cvt_pk_bf16_f32 v2, v12, v14
	s_waitcnt lgkmcnt(0)
	v_cvt_pk_bf16_f32 v3, v16, v18
	v_lshl_add_u64 v[24:25], v[20:21], 0, v[24:25]
	v_add_u32_e32 v4, 8, v22
	global_store_dwordx4 v[24:25], v[0:3], off sc1
	s_add_i32 s0, s0, s34
	s_add_i32 s1, s1, s51
	v_cvt_pk_bf16_f32 v0, v7, v5
	v_ashrrev_i32_e32 v5, 31, v4
	v_cvt_pk_bf16_f32 v1, v9, v11
	v_cvt_pk_bf16_f32 v2, v13, v15
	v_cvt_pk_bf16_f32 v3, v17, v19
	v_lshlrev_b64 v[4:5], 11, v[4:5]
	ds_read2_b32 v[6:7], v40 offset0:49 offset1:57
	ds_read2_b32 v[8:9], v40 offset0:16 offset1:24
	ds_read2_b32 v[10:11], v40 offset0:82 offset1:90
	ds_read2_b32 v[12:13], v40 offset0:115 offset1:123
	ds_read2_b32 v[14:15], v40 offset0:148 offset1:156
	ds_read2_b32 v[16:17], v40 offset0:181 offset1:189
	ds_read2_b32 v[18:19], v40 offset0:214 offset1:222
	ds_read2_b32 v[24:25], v40 offset0:247 offset1:255
	v_lshl_add_u64 v[4:5], v[20:21], 0, v[4:5]
	global_store_dwordx4 v[4:5], v[0:3], off sc1
	v_add_u32_e32 v4, 16, v22
	v_ashrrev_i32_e32 v5, 31, v4
	v_lshlrev_b64 v[4:5], 11, v[4:5]
	s_waitcnt lgkmcnt(6)
	v_cvt_pk_bf16_f32 v0, v8, v6
	s_waitcnt lgkmcnt(4)
	v_cvt_pk_bf16_f32 v1, v10, v12
	s_waitcnt lgkmcnt(2)
	v_cvt_pk_bf16_f32 v2, v14, v16
	s_waitcnt lgkmcnt(0)
	v_cvt_pk_bf16_f32 v3, v18, v24
	v_lshl_add_u64 v[4:5], v[20:21], 0, v[4:5]
	global_store_dwordx4 v[4:5], v[0:3], off sc1
	v_add_u32_e32 v4, 24, v22
	v_ashrrev_i32_e32 v5, 31, v4
	v_lshlrev_b64 v[4:5], 11, v[4:5]
	v_cvt_pk_bf16_f32 v0, v9, v7
	v_cvt_pk_bf16_f32 v1, v11, v13
	v_cvt_pk_bf16_f32 v2, v15, v17
	v_cvt_pk_bf16_f32 v3, v19, v25
	v_lshl_add_u64 v[4:5], v[20:21], 0, v[4:5]
	global_store_dwordx4 v[4:5], v[0:3], off sc1
	s_waitcnt lgkmcnt(0)
	s_cmpk_lt_i32 s0, 0x800
	s_cbranch_scc0 .LBB0_1248

.LBB0_1250:
	s_or_b64 exec, exec, s[12:13]
	s_waitcnt vmcnt(0)
	ds_write2_b32 v41, v0, v1 offset1:1
	ds_write2_b32 v41, v2, v3 offset0:2 offset1:3
	v_add_u32_e32 v0, 0x420, v41
	ds_write2_b32 v0, v8, v9 offset1:1
	v_add_u32_e32 v0, 0x428, v41
	ds_write2_b32 v0, v10, v11 offset1:1
	v_add_u32_e32 v0, 0x840, v41
	ds_write2_b32 v0, v4, v5 offset1:1
	v_add_u32_e32 v0, 0x848, v41
	ds_write2_b32 v0, v6, v7 offset1:1
	v_add_u32_e32 v0, 0xc60, v41
	ds_write2_b32 v0, v16, v17 offset1:1
	v_add_u32_e32 v0, 0xc68, v41
	ds_write2_b32 v0, v18, v19 offset1:1
	v_add_u32_e32 v0, 0x1080, v41
	ds_write2_b32 v0, v12, v13 offset1:1
	v_add_u32_e32 v0, 0x1088, v41
	ds_write2_b32 v0, v14, v15 offset1:1
	v_add_u32_e32 v0, 0x14a0, v41
	ds_write2_b32 v0, v24, v25 offset1:1
	v_add_u32_e32 v0, 0x14a8, v41
	ds_write2_b32 v0, v26, v27 offset1:1
	v_add_u32_e32 v0, 0x18c0, v41
	ds_write2_b32 v0, v20, v21 offset1:1
	v_add_u32_e32 v0, 0x18c8, v41
	ds_write2_b32 v0, v22, v23 offset1:1
	v_add_u32_e32 v0, 0x1ce0, v41
	ds_write2_b32 v0, v28, v29 offset1:1
	v_add_u32_e32 v0, 0x1ce8, v41
	ds_write2_b32 v0, v30, v31 offset1:1
	s_waitcnt lgkmcnt(0)
	s_sub_i32 s3, 0, s3
	ds_read2_b32 v[4:5], v40 offset0:33 offset1:41
	ds_read2_b32 v[6:7], v40 offset1:8
	ds_read2_b32 v[8:9], v40 offset0:66 offset1:74
	ds_read2_b32 v[10:11], v40 offset0:99 offset1:107
	ds_read2_b32 v[12:13], v40 offset0:132 offset1:140
	ds_read2_b32 v[14:15], v40 offset0:165 offset1:173
	ds_read2_b32 v[16:17], v40 offset0:198 offset1:206
	ds_read2_b32 v[18:19], v40 offset0:231 offset1:239
	s_add_i32 s3, s3, s1
	v_add_u32_e32 v22, s3, v39
	s_ashr_i32 s11, s10, 31
	v_ashrrev_i32_e32 v23, 31, v22
	v_lshl_add_u64 v[20:21], s[10:11], 1, v[32:33]
	v_lshlrev_b64 v[24:25], 13, v[22:23]
	s_waitcnt lgkmcnt(6)
	v_cvt_pk_bf16_f32 v0, v6, v4
	s_waitcnt lgkmcnt(4)
	v_cvt_pk_bf16_f32 v1, v8, v10
	s_waitcnt lgkmcnt(2)
	v_cvt_pk_bf16_f32 v2, v12, v14
	s_waitcnt lgkmcnt(0)
	v_cvt_pk_bf16_f32 v3, v16, v18
	v_lshl_add_u64 v[24:25], v[20:21], 0, v[24:25]
	v_add_u32_e32 v4, 8, v22
	global_store_dwordx4 v[24:25], v[0:3], off sc1
	s_add_i32 s0, s0, s34
	s_add_i32 s1, s1, s51
	v_cvt_pk_bf16_f32 v0, v7, v5
	v_ashrrev_i32_e32 v5, 31, v4
	v_cvt_pk_bf16_f32 v1, v9, v11
	v_cvt_pk_bf16_f32 v2, v13, v15
	v_cvt_pk_bf16_f32 v3, v17, v19
	v_lshlrev_b64 v[4:5], 13, v[4:5]
	ds_read2_b32 v[6:7], v40 offset0:49 offset1:57
	ds_read2_b32 v[8:9], v40 offset0:16 offset1:24
	ds_read2_b32 v[10:11], v40 offset0:82 offset1:90
	ds_read2_b32 v[12:13], v40 offset0:115 offset1:123
	ds_read2_b32 v[14:15], v40 offset0:148 offset1:156
	ds_read2_b32 v[16:17], v40 offset0:181 offset1:189
	ds_read2_b32 v[18:19], v40 offset0:214 offset1:222
	ds_read2_b32 v[24:25], v40 offset0:247 offset1:255
	v_lshl_add_u64 v[4:5], v[20:21], 0, v[4:5]
	global_store_dwordx4 v[4:5], v[0:3], off sc1
	v_add_u32_e32 v4, 16, v22
	v_ashrrev_i32_e32 v5, 31, v4
	v_lshlrev_b64 v[4:5], 13, v[4:5]
	s_waitcnt lgkmcnt(6)
	v_cvt_pk_bf16_f32 v0, v8, v6
	s_waitcnt lgkmcnt(4)
	v_cvt_pk_bf16_f32 v1, v10, v12
	s_waitcnt lgkmcnt(2)
	v_cvt_pk_bf16_f32 v2, v14, v16
	s_waitcnt lgkmcnt(0)
	v_cvt_pk_bf16_f32 v3, v18, v24
	v_lshl_add_u64 v[4:5], v[20:21], 0, v[4:5]
	global_store_dwordx4 v[4:5], v[0:3], off sc1
	v_add_u32_e32 v4, 24, v22
	v_ashrrev_i32_e32 v5, 31, v4
	v_lshlrev_b64 v[4:5], 13, v[4:5]
	v_cvt_pk_bf16_f32 v0, v9, v7
	v_cvt_pk_bf16_f32 v1, v11, v13
	v_cvt_pk_bf16_f32 v2, v15, v17
	v_cvt_pk_bf16_f32 v3, v19, v25
	v_lshl_add_u64 v[4:5], v[20:21], 0, v[4:5]
	global_store_dwordx4 v[4:5], v[0:3], off sc1
	s_waitcnt lgkmcnt(0)
	s_cmpk_lt_i32 s0, 0x800
	s_cbranch_scc0 .LBB0_1267

.LBB0_1331:
	v_lshl_add_u32 v151, s16, 8, v144
	v_lshl_or_b32 v152, s45, 8, v145
	v_ashrrev_i32_e32 v153, 31, v152
	v_mov_b64_e32 v[154:155], s[38:39]
	v_cvt_pk_bf16_f32 v68, v68, v69
	v_cvt_pk_bf16_f32 v69, v70, v71
	v_cvt_pk_bf16_f32 v70, v64, v65
	v_add_u32_e32 v64, 0x80, v151
	v_mad_i64_i32 v[156:157], s[46:47], v151, s42, v[154:155]
	v_lshlrev_b64 v[152:153], 1, v[152:153]
	v_cvt_pk_bf16_f32 v108, v108, v109
	v_cvt_pk_bf16_f32 v109, v110, v111
	v_cvt_pk_bf16_f32 v110, v104, v105
	v_or_b32_e32 v104, 16, v151
	v_mad_i64_i32 v[64:65], s[46:47], v64, s42, v[154:155]
	v_cvt_pk_bf16_f32 v44, v44, v45
	v_cvt_pk_bf16_f32 v45, v46, v47
	v_cvt_pk_bf16_f32 v46, v40, v41
	v_add_u32_e32 v40, 0x90, v151
	v_lshl_add_u64 v[156:157], v[156:157], 0, v[152:153]
	v_cvt_pk_bf16_f32 v111, v106, v107
	v_mad_i64_i32 v[104:105], s[46:47], v104, s42, v[154:155]
	v_cvt_pk_bf16_f32 v92, v92, v93
	v_cvt_pk_bf16_f32 v93, v94, v95
	v_cvt_pk_bf16_f32 v94, v88, v89
	v_or_b32_e32 v88, 32, v151
	v_lshl_add_u64 v[64:65], v[64:65], 0, v[152:153]
	v_cvt_pk_bf16_f32 v47, v42, v43
	v_mad_i64_i32 v[40:41], s[46:47], v40, s42, v[154:155]
	v_cvt_pk_bf16_f32 v28, v28, v29
	v_cvt_pk_bf16_f32 v29, v30, v31
	v_cvt_pk_bf16_f32 v30, v24, v25
	v_add_u32_e32 v24, 0xa0, v151
	global_store_dwordx4 v[156:157], v[108:111], off offset:256 sc1
	v_cvt_pk_bf16_f32 v95, v90, v91
	v_mad_i64_i32 v[88:89], s[46:47], v88, s42, v[154:155]
	v_lshl_add_u64 v[108:109], v[104:105], 0, v[152:153]
	v_cvt_pk_bf16_f32 v76, v76, v77
	v_cvt_pk_bf16_f32 v77, v78, v79
	v_cvt_pk_bf16_f32 v78, v72, v73
	v_or_b32_e32 v72, 48, v151
	global_store_dwordx4 v[64:65], v[44:47], off offset:256 sc1
	v_cvt_pk_bf16_f32 v31, v26, v27
	v_mad_i64_i32 v[24:25], s[46:47], v24, s42, v[154:155]
	v_lshl_add_u64 v[44:45], v[40:41], 0, v[152:153]
	v_cvt_pk_bf16_f32 v12, v12, v13
	v_cvt_pk_bf16_f32 v13, v14, v15
	v_cvt_pk_bf16_f32 v14, v8, v9
	v_add_u32_e32 v8, 0xb0, v151
	global_store_dwordx4 v[108:109], v[92:95], off offset:256 sc1
	v_cvt_pk_bf16_f32 v79, v74, v75
	v_mad_i64_i32 v[72:73], s[46:47], v72, s42, v[154:155]
	v_lshl_add_u64 v[92:93], v[88:89], 0, v[152:153]
	global_store_dwordx4 v[44:45], v[28:31], off offset:256 sc1
	v_cvt_pk_bf16_f32 v15, v10, v11
	v_mad_i64_i32 v[8:9], s[46:47], v8, s42, v[154:155]
	v_lshl_add_u64 v[28:29], v[24:25], 0, v[152:153]
	v_cvt_pk_bf16_f32 v124, v124, v125
	v_cvt_pk_bf16_f32 v125, v126, v127
	v_cvt_pk_bf16_f32 v126, v120, v121
	v_cvt_pk_bf16_f32 v127, v122, v123
	v_cvt_pk_bf16_f32 v104, v116, v117
	v_cvt_pk_bf16_f32 v105, v118, v119
	v_cvt_pk_bf16_f32 v106, v112, v113
	v_cvt_pk_bf16_f32 v107, v114, v115
	v_cvt_pk_bf16_f32 v88, v100, v101
	v_cvt_pk_bf16_f32 v89, v102, v103
	v_cvt_pk_bf16_f32 v90, v96, v97
	v_cvt_pk_bf16_f32 v91, v98, v99
	global_store_dwordx4 v[92:93], v[76:79], off offset:256 sc1
	v_cvt_pk_bf16_f32 v74, v80, v81
	v_cvt_pk_bf16_f32 v75, v82, v83
	v_lshl_add_u64 v[76:77], v[72:73], 0, v[152:153]
	v_cvt_pk_bf16_f32 v72, v84, v85
	v_cvt_pk_bf16_f32 v73, v86, v87
	v_cvt_pk_bf16_f32 v71, v66, v67
	v_cvt_pk_bf16_f32 v60, v60, v61
	v_cvt_pk_bf16_f32 v61, v62, v63
	v_cvt_pk_bf16_f32 v62, v56, v57
	v_cvt_pk_bf16_f32 v63, v58, v59
	v_cvt_pk_bf16_f32 v40, v52, v53
	v_cvt_pk_bf16_f32 v41, v54, v55
	v_cvt_pk_bf16_f32 v42, v48, v49
	v_cvt_pk_bf16_f32 v43, v50, v51
	v_cvt_pk_bf16_f32 v24, v36, v37
	v_cvt_pk_bf16_f32 v25, v38, v39
	v_cvt_pk_bf16_f32 v26, v32, v33
	v_cvt_pk_bf16_f32 v27, v34, v35
	global_store_dwordx4 v[28:29], v[12:15], off offset:256 sc1
	v_cvt_pk_bf16_f32 v10, v16, v17
	v_cvt_pk_bf16_f32 v11, v18, v19
	v_lshl_add_u64 v[12:13], v[8:9], 0, v[152:153]
	v_cvt_pk_bf16_f32 v8, v20, v21
	v_cvt_pk_bf16_f32 v9, v22, v23
	v_cvt_pk_bf16_f32 v4, v4, v5
	v_cvt_pk_bf16_f32 v5, v6, v7
	v_cvt_pk_bf16_f32 v6, v0, v1
	v_cvt_pk_bf16_f32 v7, v2, v3
	s_andn2_b64 vcc, exec, s[8:9]
	s_mov_b64 s[8:9], -1
	global_store_dwordx4 v[156:157], v[124:127], off sc1
	global_store_dwordx4 v[108:109], v[104:107], off sc1
	global_store_dwordx4 v[92:93], v[88:91], off sc1
	global_store_dwordx4 v[76:77], v[72:75], off sc1
	global_store_dwordx4 v[76:77], v[68:71], off offset:256 sc1
	global_store_dwordx4 v[64:65], v[60:63], off sc1
	global_store_dwordx4 v[44:45], v[40:43], off sc1
	global_store_dwordx4 v[28:29], v[24:27], off sc1
	global_store_dwordx4 v[12:13], v[8:11], off sc1
	global_store_dwordx4 v[12:13], v[4:7], off offset:256 sc1
	s_cbranch_vccnz .LBB0_1324
	s_andn2_b64 vcc, exec, s[10:11]
	s_cbranch_vccnz .LBB0_1323
	s_barrier
	s_branch .LBB0_1323

.LBB0_1393:
	s_or_b64 exec, exec, s[14:15]
	s_movk_i32 s0, 0x1800
	v_mov_b64_e32 v[12:13], s[38:39]
	v_mad_i64_i32 v[12:13], s[0:1], v0, s0, v[12:13]
	v_mov_b32_e32 v3, 0
	v_lshl_add_u64 v[12:13], v[12:13], 0, v[2:3]
	global_load_dwordx4 v[16:19], v[12:13], off
	v_ashrrev_i32_e32 v1, 31, v0
	v_lshlrev_b64 v[0:1], 11, v[0:1]
	v_lshl_add_u64 v[0:1], s[64:65], 0, v[0:1]
	v_lshl_add_u64 v[12:13], v[0:1], 0, v[2:3]
	v_mov_b32_e32 v27, v14
	s_waitcnt vmcnt(0)
	v_lshlrev_b32_e32 v0, 16, v16
	v_and_b32_e32 v1, 0xffff0000, v16
	v_lshlrev_b32_e32 v2, 16, v17
	v_and_b32_e32 v3, 0xffff0000, v17
	v_lshlrev_b32_e32 v16, 16, v18
	v_and_b32_e32 v17, 0xffff0000, v18
	v_lshlrev_b32_e32 v18, 16, v19
	v_and_b32_e32 v19, 0xffff0000, v19
	v_pk_mul_f32 v[0:1], v[4:5], v[0:1]
	v_pk_mul_f32 v[2:3], v[8:9], v[2:3]
	v_pk_mul_f32 v[4:5], v[10:11], v[16:17]
	v_pk_mul_f32 v[6:7], v[6:7], v[18:19]
	v_cvt_pk_bf16_f32 v0, v0, v1
	v_cvt_pk_bf16_f32 v1, v2, v3
	v_cvt_pk_bf16_f32 v2, v4, v5
	v_cvt_pk_bf16_f32 v3, v6, v7
	global_store_dwordx4 v[12:13], v[0:3], off sc1

.LBB0_1396:
	s_or_b64 exec, exec, s[18:19]
	v_mov_b64_e32 v[2:3], s[38:39]
	v_mad_i64_i32 v[2:3], s[4:5], v8, s1, v[2:3]
	v_lshl_add_u64 v[2:3], v[2:3], 0, v[0:1]
	global_load_dwordx4 v[2:5], v[2:3], off
	v_ashrrev_i32_e32 v9, 31, v8
	v_add_u32_e32 v27, s60, v27
	v_lshlrev_b64 v[6:7], 11, v[8:9]
	v_cmp_lt_i32_e32 vcc, s2, v27
	v_lshl_add_u64 v[6:7], s[64:65], 0, v[6:7]
	s_or_b64 s[8:9], vcc, s[8:9]
	v_lshl_add_u64 v[6:7], v[6:7], 0, v[0:1]
	v_add_u32_e32 v26, s0, v26
	s_waitcnt vmcnt(0)
	v_lshlrev_b32_e32 v8, 16, v2
	v_and_b32_e32 v9, 0xffff0000, v2
	v_lshlrev_b32_e32 v2, 16, v3
	v_and_b32_e32 v3, 0xffff0000, v3
	v_lshlrev_b32_e32 v18, 16, v4
	v_and_b32_e32 v19, 0xffff0000, v4
	v_lshlrev_b32_e32 v4, 16, v5
	v_and_b32_e32 v5, 0xffff0000, v5
	v_pk_mul_f32 v[8:9], v[14:15], v[8:9]
	v_pk_mul_f32 v[12:13], v[12:13], v[2:3]
	v_pk_mul_f32 v[14:15], v[16:17], v[18:19]
	v_pk_mul_f32 v[10:11], v[10:11], v[4:5]
	v_cvt_pk_bf16_f32 v2, v8, v9
	v_cvt_pk_bf16_f32 v3, v12, v13
	v_cvt_pk_bf16_f32 v4, v14, v15
	v_cvt_pk_bf16_f32 v5, v10, v11
	global_store_dwordx4 v[6:7], v[2:5], off sc1
	s_andn2_b64 exec, exec, s[8:9]
	s_cbranch_execz .LBB0_1409

.LBB0_1403:
	s_or_b64 exec, exec, s[18:19]
	v_mov_b64_e32 v[10:11], s[38:39]
	v_mad_i64_i32 v[10:11], s[4:5], v8, s1, v[10:11]
	v_lshl_add_u64 v[10:11], v[10:11], 0, v[0:1]
	global_load_dwordx4 v[28:31], v[10:11], off
	v_ashrrev_i32_e32 v9, 31, v8
	v_add_u32_e32 v27, s60, v27
	v_lshlrev_b64 v[32:33], 11, v[8:9]
	v_ashrrev_i32_e32 v8, 7, v27
	v_lshl_add_u64 v[32:33], s[64:65], 0, v[32:33]
	v_mov_b32_e32 v14, v1
	v_mov_b32_e32 v15, v1
	v_mov_b32_e32 v12, v1
	v_mov_b32_e32 v13, v1
	v_mov_b32_e32 v16, v1
	v_mov_b32_e32 v17, v1
	v_mov_b32_e32 v10, v1
	v_cmp_lt_i32_e32 vcc, 1, v8
	v_lshl_add_u64 v[32:33], v[32:33], 0, v[0:1]
	v_mov_b32_e32 v11, v1
	s_waitcnt vmcnt(0)
	v_lshlrev_b32_e32 v34, 16, v28
	v_and_b32_e32 v35, 0xffff0000, v28
	v_lshlrev_b32_e32 v28, 16, v29
	v_and_b32_e32 v29, 0xffff0000, v29
	v_lshlrev_b32_e32 v36, 16, v30
	v_and_b32_e32 v37, 0xffff0000, v30
	v_lshlrev_b32_e32 v30, 16, v31
	v_and_b32_e32 v31, 0xffff0000, v31
	v_pk_mul_f32 v[22:23], v[22:23], v[34:35]
	v_pk_mul_f32 v[20:21], v[20:21], v[28:29]
	v_pk_mul_f32 v[24:25], v[24:25], v[36:37]
	v_pk_mul_f32 v[28:29], v[18:19], v[30:31]
	v_cvt_pk_bf16_f32 v18, v22, v23
	v_cvt_pk_bf16_f32 v19, v20, v21
	v_cvt_pk_bf16_f32 v20, v24, v25
	v_cvt_pk_bf16_f32 v21, v28, v29
	global_store_dwordx4 v[32:33], v[18:21], off sc1
	s_and_saveexec_b64 s[18:19], vcc
	s_cbranch_execz .LBB0_1406
	v_add_u32_e32 v9, -2, v8
	v_mov_b64_e32 v[10:11], s[38:39]
	v_mad_u64_u32 v[10:11], s[4:5], v9, s1, v[10:11]
	v_lshl_add_u64 v[14:15], v[10:11], 0, v[0:1]
	global_load_dwordx4 v[10:13], v[14:15], off offset:2048
	v_add_co_u32_e32 v14, vcc, 0x1000, v14
	s_waitcnt vmcnt(0)
	v_lshlrev_b32_e32 v28, 16, v13
	v_addc_co_u32_e32 v15, vcc, 0, v15, vcc
	global_load_dwordx4 v[14:17], v[14:15], off
	s_nop 0
	global_load_dwordx4 v[18:21], v[2:3], off offset:16
	global_load_dwordx4 v[22:25], v[2:3], off
	v_lshlrev_b32_e32 v30, 16, v10
	v_and_b32_e32 v31, 0xffff0000, v10
	v_lshlrev_b32_e32 v32, 16, v12
	v_and_b32_e32 v33, 0xffff0000, v12
	v_lshlrev_b32_e32 v10, 16, v11
	v_and_b32_e32 v11, 0xffff0000, v11
	v_and_b32_e32 v29, 0xffff0000, v13
	s_waitcnt vmcnt(2)
	v_lshlrev_b32_e32 v12, 16, v17
	v_lshlrev_b32_e32 v34, 16, v14
	v_and_b32_e32 v35, 0xffff0000, v14
	v_lshlrev_b32_e32 v36, 16, v16
	v_and_b32_e32 v37, 0xffff0000, v16
	v_lshlrev_b32_e32 v14, 16, v15
	v_and_b32_e32 v15, 0xffff0000, v15
	v_and_b32_e32 v13, 0xffff0000, v17
	v_pk_mul_f32 v[12:13], v[28:29], v[12:13]
	v_pk_mul_f32 v[14:15], v[10:11], v[14:15]
	v_pk_mul_f32 v[28:29], v[30:31], v[34:35]
	v_pk_mul_f32 v[16:17], v[32:33], v[36:37]
	s_waitcnt vmcnt(1)
	v_pk_fma_f32 v[10:11], v[20:21], v[12:13], 0 op_sel_hi:[1,1,0]
	s_waitcnt vmcnt(0)
	v_pk_fma_f32 v[12:13], v[24:25], v[14:15], 0 op_sel_hi:[1,1,0]
	v_pk_fma_f32 v[16:17], v[18:19], v[16:17], 0 op_sel_hi:[1,1,0]
	v_pk_fma_f32 v[14:15], v[22:23], v[28:29], 0 op_sel_hi:[1,1,0]
	s_or_b64 exec, exec, s[18:19]
	v_cmp_lt_i32_e32 vcc, 0, v8
	s_and_saveexec_b64 s[18:19], vcc
	s_cbranch_execnz .LBB0_1407

.LBB0_1616:
	v_lshl_add_u32 v154, s60, 8, v146
	v_lshl_or_b32 v144, s46, 8, v147
	v_ashrrev_i32_e32 v155, 31, v154
	v_ashrrev_i32_e32 v145, 31, v144
	v_lshlrev_b64 v[156:157], 13, v[154:155]
	v_max_f32_e32 v120, v120, v120
	v_max_f32_e32 v121, v121, v121
	v_lshl_add_u64 v[156:157], s[38:39], 0, v[156:157]
	v_lshlrev_b64 v[158:159], 1, v[144:145]
	v_max_f32_e32 v120, 0, v120
	v_max_f32_e32 v121, 0, v121
	v_lshl_add_u64 v[144:145], v[156:157], 0, v[158:159]
	v_pk_mul_f32 v[156:157], v[120:121], v[120:121]
	v_max_f32_e32 v121, v122, v122
	v_max_f32_e32 v124, v124, v124
	v_max_f32_e32 v125, v125, v125
	v_max_f32_e32 v120, v126, v126
	v_max_f32_e32 v122, 0, v121
	v_max_f32_e32 v121, v127, v127
	v_max_f32_e32 v123, v123, v123
	v_max_f32_e32 v124, 0, v124
	v_max_f32_e32 v125, 0, v125
	v_max_f32_e32 v120, 0, v120
	v_max_f32_e32 v121, 0, v121
	v_max_f32_e32 v123, 0, v123
	v_pk_mul_f32 v[124:125], v[124:125], v[124:125]
	v_pk_mul_f32 v[126:127], v[120:121], v[120:121]
	v_pk_mul_f32 v[162:163], v[122:123], v[122:123]
	v_max_f32_e32 v112, v112, v112
	v_max_f32_e32 v113, v113, v113
	v_cvt_pk_bf16_f32 v120, v124, v125
	v_cvt_pk_bf16_f32 v121, v126, v127
	v_cvt_pk_bf16_f32 v122, v156, v157
	v_cvt_pk_bf16_f32 v123, v162, v163
	v_max_f32_e32 v112, 0, v112
	v_max_f32_e32 v113, 0, v113
	global_store_dwordx4 v[144:145], v[120:123], off sc1
	v_max_f32_e32 v116, v116, v116
	v_max_f32_e32 v117, v117, v117
	v_pk_mul_f32 v[120:121], v[112:113], v[112:113]
	v_max_f32_e32 v113, v114, v114
	v_max_f32_e32 v112, v118, v118
	v_max_f32_e32 v114, 0, v113
	v_max_f32_e32 v113, v119, v119
	v_max_f32_e32 v115, v115, v115
	v_max_f32_e32 v116, 0, v116
	v_max_f32_e32 v117, 0, v117
	v_max_f32_e32 v112, 0, v112
	v_max_f32_e32 v113, 0, v113
	v_max_f32_e32 v115, 0, v115
	v_pk_mul_f32 v[116:117], v[116:117], v[116:117]
	v_pk_mul_f32 v[118:119], v[112:113], v[112:113]
	v_pk_mul_f32 v[122:123], v[114:115], v[114:115]
	v_max_f32_e32 v104, v104, v104
	v_max_f32_e32 v105, v105, v105
	v_cvt_pk_bf16_f32 v112, v116, v117
	v_cvt_pk_bf16_f32 v113, v118, v119
	v_cvt_pk_bf16_f32 v114, v120, v121
	v_cvt_pk_bf16_f32 v115, v122, v123
	v_max_f32_e32 v104, 0, v104
	v_max_f32_e32 v105, 0, v105
	global_store_dwordx4 v[144:145], v[112:115], off offset:256 sc1
	v_max_f32_e32 v108, v108, v108
	v_max_f32_e32 v109, v109, v109
	v_or_b32_e32 v112, 16, v154
	v_pk_mul_f32 v[114:115], v[104:105], v[104:105]
	v_max_f32_e32 v105, v106, v106
	v_ashrrev_i32_e32 v113, 31, v112
	v_max_f32_e32 v104, v110, v110
	v_max_f32_e32 v106, 0, v105
	v_max_f32_e32 v105, v111, v111
	v_max_f32_e32 v107, v107, v107
	v_lshlrev_b64 v[112:113], 13, v[112:113]
	v_max_f32_e32 v108, 0, v108
	v_max_f32_e32 v109, 0, v109
	v_max_f32_e32 v104, 0, v104
	v_max_f32_e32 v105, 0, v105
	v_max_f32_e32 v107, 0, v107
	v_lshl_add_u64 v[112:113], s[38:39], 0, v[112:113]
	v_pk_mul_f32 v[108:109], v[108:109], v[108:109]
	v_pk_mul_f32 v[110:111], v[104:105], v[104:105]
	v_pk_mul_f32 v[116:117], v[106:107], v[106:107]
	v_max_f32_e32 v96, v96, v96
	v_max_f32_e32 v97, v97, v97
	v_lshl_add_u64 v[112:113], v[112:113], 0, v[158:159]
	v_cvt_pk_bf16_f32 v104, v108, v109
	v_cvt_pk_bf16_f32 v105, v110, v111
	v_cvt_pk_bf16_f32 v106, v114, v115
	v_cvt_pk_bf16_f32 v107, v116, v117
	v_max_f32_e32 v96, 0, v96
	v_max_f32_e32 v97, 0, v97
	global_store_dwordx4 v[112:113], v[104:107], off sc1
	v_max_f32_e32 v100, v100, v100
	v_max_f32_e32 v101, v101, v101
	v_pk_mul_f32 v[104:105], v[96:97], v[96:97]
	v_max_f32_e32 v97, v98, v98
	v_max_f32_e32 v96, v102, v102
	v_max_f32_e32 v98, 0, v97
	v_max_f32_e32 v97, v103, v103
	v_max_f32_e32 v99, v99, v99
	v_max_f32_e32 v100, 0, v100
	v_max_f32_e32 v101, 0, v101
	v_max_f32_e32 v96, 0, v96
	v_max_f32_e32 v97, 0, v97
	v_max_f32_e32 v99, 0, v99
	v_pk_mul_f32 v[100:101], v[100:101], v[100:101]
	v_pk_mul_f32 v[102:103], v[96:97], v[96:97]
	v_pk_mul_f32 v[106:107], v[98:99], v[98:99]
	v_max_f32_e32 v88, v88, v88
	v_max_f32_e32 v89, v89, v89
	v_cvt_pk_bf16_f32 v96, v100, v101
	v_cvt_pk_bf16_f32 v97, v102, v103
	v_cvt_pk_bf16_f32 v98, v104, v105
	v_cvt_pk_bf16_f32 v99, v106, v107
	v_max_f32_e32 v88, 0, v88
	v_max_f32_e32 v89, 0, v89
	global_store_dwordx4 v[112:113], v[96:99], off offset:256 sc1
	v_max_f32_e32 v92, v92, v92
	v_max_f32_e32 v93, v93, v93
	v_or_b32_e32 v96, 32, v154
	v_pk_mul_f32 v[98:99], v[88:89], v[88:89]
	v_max_f32_e32 v89, v90, v90
	v_ashrrev_i32_e32 v97, 31, v96
	v_max_f32_e32 v88, v94, v94
	v_max_f32_e32 v90, 0, v89
	v_max_f32_e32 v89, v95, v95
	v_max_f32_e32 v91, v91, v91
	v_lshlrev_b64 v[96:97], 13, v[96:97]
	v_max_f32_e32 v92, 0, v92
	v_max_f32_e32 v93, 0, v93
	v_max_f32_e32 v88, 0, v88
	v_max_f32_e32 v89, 0, v89
	v_max_f32_e32 v91, 0, v91
	v_lshl_add_u64 v[96:97], s[38:39], 0, v[96:97]
	v_pk_mul_f32 v[92:93], v[92:93], v[92:93]
	v_pk_mul_f32 v[94:95], v[88:89], v[88:89]
	v_pk_mul_f32 v[100:101], v[90:91], v[90:91]
	v_max_f32_e32 v80, v80, v80
	v_max_f32_e32 v81, v81, v81
	v_lshl_add_u64 v[96:97], v[96:97], 0, v[158:159]
	v_cvt_pk_bf16_f32 v88, v92, v93
	v_cvt_pk_bf16_f32 v89, v94, v95
	v_cvt_pk_bf16_f32 v90, v98, v99
	v_cvt_pk_bf16_f32 v91, v100, v101
	v_max_f32_e32 v80, 0, v80
	v_max_f32_e32 v81, 0, v81
	global_store_dwordx4 v[96:97], v[88:91], off sc1
	v_max_f32_e32 v84, v84, v84
	v_max_f32_e32 v85, v85, v85
	v_pk_mul_f32 v[88:89], v[80:81], v[80:81]
	v_max_f32_e32 v81, v82, v82
	v_max_f32_e32 v80, v86, v86
	v_max_f32_e32 v82, 0, v81
	v_max_f32_e32 v81, v87, v87
	v_max_f32_e32 v83, v83, v83
	v_max_f32_e32 v84, 0, v84
	v_max_f32_e32 v85, 0, v85
	v_max_f32_e32 v80, 0, v80
	v_max_f32_e32 v81, 0, v81
	v_max_f32_e32 v83, 0, v83
	v_pk_mul_f32 v[84:85], v[84:85], v[84:85]
	v_pk_mul_f32 v[86:87], v[80:81], v[80:81]
	v_pk_mul_f32 v[90:91], v[82:83], v[82:83]
	v_max_f32_e32 v72, v72, v72
	v_max_f32_e32 v73, v73, v73
	v_cvt_pk_bf16_f32 v80, v84, v85
	v_cvt_pk_bf16_f32 v81, v86, v87
	v_cvt_pk_bf16_f32 v82, v88, v89
	v_cvt_pk_bf16_f32 v83, v90, v91
	v_max_f32_e32 v72, 0, v72
	v_max_f32_e32 v73, 0, v73
	global_store_dwordx4 v[96:97], v[80:83], off offset:256 sc1
	v_max_f32_e32 v76, v76, v76
	v_max_f32_e32 v77, v77, v77
	v_or_b32_e32 v80, 48, v154
	v_pk_mul_f32 v[82:83], v[72:73], v[72:73]
	v_max_f32_e32 v73, v74, v74
	v_ashrrev_i32_e32 v81, 31, v80
	v_max_f32_e32 v72, v78, v78
	v_max_f32_e32 v74, 0, v73
	v_max_f32_e32 v73, v79, v79
	v_max_f32_e32 v75, v75, v75
	v_lshlrev_b64 v[80:81], 13, v[80:81]
	v_max_f32_e32 v76, 0, v76
	v_max_f32_e32 v77, 0, v77
	v_max_f32_e32 v72, 0, v72
	v_max_f32_e32 v73, 0, v73
	v_max_f32_e32 v75, 0, v75
	v_lshl_add_u64 v[80:81], s[38:39], 0, v[80:81]
	v_pk_mul_f32 v[76:77], v[76:77], v[76:77]
	v_pk_mul_f32 v[78:79], v[72:73], v[72:73]
	v_pk_mul_f32 v[84:85], v[74:75], v[74:75]
	v_max_f32_e32 v64, v64, v64
	v_max_f32_e32 v65, v65, v65
	v_lshl_add_u64 v[80:81], v[80:81], 0, v[158:159]
	v_cvt_pk_bf16_f32 v72, v76, v77
	v_cvt_pk_bf16_f32 v73, v78, v79
	v_cvt_pk_bf16_f32 v74, v82, v83
	v_cvt_pk_bf16_f32 v75, v84, v85
	v_max_f32_e32 v64, 0, v64
	v_max_f32_e32 v65, 0, v65
	global_store_dwordx4 v[80:81], v[72:75], off sc1
	v_max_f32_e32 v68, v68, v68
	v_max_f32_e32 v69, v69, v69
	v_pk_mul_f32 v[72:73], v[64:65], v[64:65]
	v_max_f32_e32 v65, v66, v66
	v_max_f32_e32 v64, v70, v70
	v_max_f32_e32 v66, 0, v65
	v_max_f32_e32 v65, v71, v71
	v_max_f32_e32 v67, v67, v67
	v_max_f32_e32 v68, 0, v68
	v_max_f32_e32 v69, 0, v69
	v_max_f32_e32 v64, 0, v64
	v_max_f32_e32 v65, 0, v65
	v_max_f32_e32 v67, 0, v67
	v_pk_mul_f32 v[68:69], v[68:69], v[68:69]
	v_pk_mul_f32 v[70:71], v[64:65], v[64:65]
	v_pk_mul_f32 v[74:75], v[66:67], v[66:67]
	v_max_f32_e32 v56, v56, v56
	v_max_f32_e32 v57, v57, v57
	v_cvt_pk_bf16_f32 v64, v68, v69
	v_cvt_pk_bf16_f32 v65, v70, v71
	v_cvt_pk_bf16_f32 v66, v72, v73
	v_cvt_pk_bf16_f32 v67, v74, v75
	v_max_f32_e32 v56, 0, v56
	v_max_f32_e32 v57, 0, v57
	global_store_dwordx4 v[80:81], v[64:67], off offset:256 sc1
	v_max_f32_e32 v60, v60, v60
	v_max_f32_e32 v61, v61, v61
	v_pk_mul_f32 v[66:67], v[56:57], v[56:57]
	v_max_f32_e32 v57, v58, v58
	v_max_f32_e32 v60, 0, v60
	v_max_f32_e32 v61, 0, v61
	v_max_f32_e32 v56, v62, v62
	v_max_f32_e32 v58, 0, v57
	v_max_f32_e32 v57, v63, v63
	v_max_f32_e32 v59, v59, v59
	v_pk_mul_f32 v[60:61], v[60:61], v[60:61]
	v_max_f32_e32 v56, 0, v56
	v_max_f32_e32 v57, 0, v57
	v_max_f32_e32 v59, 0, v59
	s_mov_b32 s21, 0x100000
	v_pk_mul_f32 v[62:63], v[56:57], v[56:57]
	v_pk_mul_f32 v[68:69], v[58:59], v[58:59]
	v_cvt_pk_bf16_f32 v56, v60, v61
	v_add_co_u32_e32 v60, vcc, s21, v144
	v_max_f32_e32 v48, v48, v48
	v_max_f32_e32 v49, v49, v49
	v_cvt_pk_bf16_f32 v57, v62, v63
	v_cvt_pk_bf16_f32 v58, v66, v67
	v_cvt_pk_bf16_f32 v59, v68, v69
	v_addc_co_u32_e32 v61, vcc, 0, v145, vcc
	v_max_f32_e32 v48, 0, v48
	v_max_f32_e32 v49, 0, v49
	global_store_dwordx4 v[60:61], v[56:59], off sc1
	v_max_f32_e32 v52, v52, v52
	v_max_f32_e32 v53, v53, v53
	v_pk_mul_f32 v[56:57], v[48:49], v[48:49]
	v_max_f32_e32 v49, v50, v50
	v_max_f32_e32 v48, v54, v54
	v_max_f32_e32 v50, 0, v49
	v_max_f32_e32 v49, v55, v55
	v_max_f32_e32 v51, v51, v51
	v_max_f32_e32 v52, 0, v52
	v_max_f32_e32 v53, 0, v53
	v_max_f32_e32 v48, 0, v48
	v_max_f32_e32 v49, 0, v49
	v_max_f32_e32 v51, 0, v51
	s_mov_b64 s[46:47], 0x100000
	v_pk_mul_f32 v[52:53], v[52:53], v[52:53]
	v_pk_mul_f32 v[54:55], v[48:49], v[48:49]
	v_pk_mul_f32 v[58:59], v[50:51], v[50:51]
	v_max_f32_e32 v40, v40, v40
	v_max_f32_e32 v41, v41, v41
	v_lshl_add_u64 v[64:65], v[144:145], 0, s[46:47]
	v_cvt_pk_bf16_f32 v48, v52, v53
	v_cvt_pk_bf16_f32 v49, v54, v55
	v_cvt_pk_bf16_f32 v50, v56, v57
	v_cvt_pk_bf16_f32 v51, v58, v59
	v_max_f32_e32 v40, 0, v40
	v_max_f32_e32 v41, 0, v41
	global_store_dwordx4 v[64:65], v[48:51], off offset:256 sc1
	v_max_f32_e32 v44, v44, v44
	v_max_f32_e32 v45, v45, v45
	v_pk_mul_f32 v[50:51], v[40:41], v[40:41]
	v_max_f32_e32 v41, v42, v42
	v_max_f32_e32 v44, 0, v44
	v_max_f32_e32 v45, 0, v45
	v_max_f32_e32 v40, v46, v46
	v_max_f32_e32 v42, 0, v41
	v_max_f32_e32 v41, v47, v47
	v_max_f32_e32 v43, v43, v43
	v_pk_mul_f32 v[44:45], v[44:45], v[44:45]
	v_max_f32_e32 v40, 0, v40
	v_max_f32_e32 v41, 0, v41
	v_max_f32_e32 v43, 0, v43
	s_mov_b32 s21, 0x120000
	v_pk_mul_f32 v[46:47], v[40:41], v[40:41]
	v_pk_mul_f32 v[52:53], v[42:43], v[42:43]
	v_cvt_pk_bf16_f32 v40, v44, v45
	v_add_co_u32_e32 v44, vcc, s21, v144
	v_max_f32_e32 v32, v32, v32
	v_max_f32_e32 v33, v33, v33
	v_cvt_pk_bf16_f32 v41, v46, v47
	v_cvt_pk_bf16_f32 v42, v50, v51
	v_cvt_pk_bf16_f32 v43, v52, v53
	v_addc_co_u32_e32 v45, vcc, 0, v145, vcc
	v_max_f32_e32 v32, 0, v32
	v_max_f32_e32 v33, 0, v33
	global_store_dwordx4 v[44:45], v[40:43], off sc1
	v_max_f32_e32 v36, v36, v36
	v_max_f32_e32 v37, v37, v37
	v_pk_mul_f32 v[40:41], v[32:33], v[32:33]
	v_max_f32_e32 v33, v34, v34
	v_max_f32_e32 v32, v38, v38
	v_max_f32_e32 v34, 0, v33
	v_max_f32_e32 v33, v39, v39
	v_max_f32_e32 v35, v35, v35
	v_max_f32_e32 v36, 0, v36
	v_max_f32_e32 v37, 0, v37
	v_max_f32_e32 v32, 0, v32
	v_max_f32_e32 v33, 0, v33
	v_max_f32_e32 v35, 0, v35
	s_mov_b64 s[46:47], 0x120000
	v_pk_mul_f32 v[36:37], v[36:37], v[36:37]
	v_pk_mul_f32 v[38:39], v[32:33], v[32:33]
	v_pk_mul_f32 v[42:43], v[34:35], v[34:35]
	v_max_f32_e32 v24, v24, v24
	v_max_f32_e32 v25, v25, v25
	v_lshl_add_u64 v[48:49], v[144:145], 0, s[46:47]
	v_cvt_pk_bf16_f32 v32, v36, v37
	v_cvt_pk_bf16_f32 v33, v38, v39
	v_cvt_pk_bf16_f32 v34, v40, v41
	v_cvt_pk_bf16_f32 v35, v42, v43
	v_max_f32_e32 v24, 0, v24
	v_max_f32_e32 v25, 0, v25
	global_store_dwordx4 v[48:49], v[32:35], off offset:256 sc1
	v_max_f32_e32 v28, v28, v28
	v_max_f32_e32 v29, v29, v29
	v_pk_mul_f32 v[34:35], v[24:25], v[24:25]
	v_max_f32_e32 v25, v26, v26
	v_max_f32_e32 v28, 0, v28
	v_max_f32_e32 v29, 0, v29
	v_max_f32_e32 v24, v30, v30
	v_max_f32_e32 v26, 0, v25
	v_max_f32_e32 v25, v31, v31
	v_max_f32_e32 v27, v27, v27
	v_pk_mul_f32 v[28:29], v[28:29], v[28:29]
	v_max_f32_e32 v24, 0, v24
	v_max_f32_e32 v25, 0, v25
	v_max_f32_e32 v27, 0, v27
	v_pk_mul_f32 v[30:31], v[24:25], v[24:25]
	v_pk_mul_f32 v[36:37], v[26:27], v[26:27]
	v_cvt_pk_bf16_f32 v24, v28, v29
	v_add_co_u32_e32 v28, vcc, s42, v144
	v_max_f32_e32 v16, v16, v16
	v_max_f32_e32 v17, v17, v17
	v_cvt_pk_bf16_f32 v25, v30, v31
	v_cvt_pk_bf16_f32 v26, v34, v35
	v_cvt_pk_bf16_f32 v27, v36, v37
	v_addc_co_u32_e32 v29, vcc, 0, v145, vcc
	v_max_f32_e32 v16, 0, v16
	v_max_f32_e32 v17, 0, v17
	global_store_dwordx4 v[28:29], v[24:27], off sc1
	v_max_f32_e32 v20, v20, v20
	v_max_f32_e32 v21, v21, v21
	v_pk_mul_f32 v[24:25], v[16:17], v[16:17]
	v_max_f32_e32 v17, v18, v18
	v_max_f32_e32 v16, v22, v22
	v_max_f32_e32 v18, 0, v17
	v_max_f32_e32 v17, v23, v23
	v_max_f32_e32 v19, v19, v19
	v_max_f32_e32 v20, 0, v20
	v_max_f32_e32 v21, 0, v21
	v_max_f32_e32 v16, 0, v16
	v_max_f32_e32 v17, 0, v17
	v_max_f32_e32 v19, 0, v19
	v_pk_mul_f32 v[20:21], v[20:21], v[20:21]
	v_pk_mul_f32 v[22:23], v[16:17], v[16:17]
	v_pk_mul_f32 v[26:27], v[18:19], v[18:19]
	v_max_f32_e32 v8, v8, v8
	v_max_f32_e32 v9, v9, v9
	v_lshl_add_u64 v[32:33], v[144:145], 0, s[16:17]
	v_cvt_pk_bf16_f32 v16, v20, v21
	v_cvt_pk_bf16_f32 v17, v22, v23
	v_cvt_pk_bf16_f32 v18, v24, v25
	v_cvt_pk_bf16_f32 v19, v26, v27
	v_max_f32_e32 v8, 0, v8
	v_max_f32_e32 v9, 0, v9
	global_store_dwordx4 v[32:33], v[16:19], off offset:256 sc1
	v_max_f32_e32 v12, v12, v12
	v_max_f32_e32 v13, v13, v13
	v_pk_mul_f32 v[18:19], v[8:9], v[8:9]
	v_max_f32_e32 v9, v10, v10
	v_max_f32_e32 v12, 0, v12
	v_max_f32_e32 v13, 0, v13
	v_max_f32_e32 v8, v14, v14
	v_max_f32_e32 v10, 0, v9
	v_max_f32_e32 v9, v15, v15
	v_max_f32_e32 v11, v11, v11
	v_pk_mul_f32 v[12:13], v[12:13], v[12:13]
	v_max_f32_e32 v8, 0, v8
	v_max_f32_e32 v9, 0, v9
	v_max_f32_e32 v11, 0, v11
	v_pk_mul_f32 v[14:15], v[8:9], v[8:9]
	v_pk_mul_f32 v[20:21], v[10:11], v[10:11]
	v_cvt_pk_bf16_f32 v8, v12, v13
	v_add_co_u32_e32 v12, vcc, s43, v144
	v_max_f32_e32 v0, v0, v0
	v_max_f32_e32 v1, v1, v1
	v_cvt_pk_bf16_f32 v9, v14, v15
	v_cvt_pk_bf16_f32 v10, v18, v19
	v_cvt_pk_bf16_f32 v11, v20, v21
	v_addc_co_u32_e32 v13, vcc, 0, v145, vcc
	v_max_f32_e32 v0, 0, v0
	v_max_f32_e32 v1, 0, v1
	global_store_dwordx4 v[12:13], v[8:11], off sc1
	v_max_f32_e32 v4, v4, v4
	v_max_f32_e32 v5, v5, v5
	v_pk_mul_f32 v[8:9], v[0:1], v[0:1]
	v_max_f32_e32 v1, v2, v2
	v_max_f32_e32 v0, v6, v6
	v_max_f32_e32 v2, 0, v1
	v_max_f32_e32 v1, v7, v7
	v_max_f32_e32 v3, v3, v3
	v_max_f32_e32 v4, 0, v4
	v_max_f32_e32 v5, 0, v5
	v_max_f32_e32 v0, 0, v0
	v_max_f32_e32 v1, 0, v1
	v_max_f32_e32 v3, 0, v3
	v_pk_mul_f32 v[4:5], v[4:5], v[4:5]
	v_pk_mul_f32 v[6:7], v[0:1], v[0:1]
	v_pk_mul_f32 v[10:11], v[2:3], v[2:3]
	v_lshl_add_u64 v[16:17], v[144:145], 0, s[18:19]
	v_cvt_pk_bf16_f32 v0, v4, v5
	v_cvt_pk_bf16_f32 v1, v6, v7
	v_cvt_pk_bf16_f32 v2, v8, v9
	v_cvt_pk_bf16_f32 v3, v10, v11
	s_andn2_b64 vcc, exec, s[8:9]
	s_mov_b64 s[8:9], -1
	global_store_dwordx4 v[16:17], v[0:3], off offset:256 sc1
	s_cbranch_vccnz .LBB0_1605
	s_andn2_b64 vcc, exec, s[10:11]
	s_cbranch_vccnz .LBB0_1604
	s_barrier
	s_branch .LBB0_1604

.LBB0_1755:
	s_or_b64 exec, exec, s[12:13]
	s_waitcnt vmcnt(0)
	ds_write2_b32 v39, v0, v1 offset1:1
	ds_write2_b32 v39, v2, v3 offset0:2 offset1:3
	v_add_u32_e32 v0, 0x420, v39
	ds_write2_b32 v0, v8, v9 offset1:1
	v_add_u32_e32 v0, 0x428, v39
	ds_write2_b32 v0, v10, v11 offset1:1
	v_add_u32_e32 v0, 0x840, v39
	ds_write2_b32 v0, v4, v5 offset1:1
	v_add_u32_e32 v0, 0x848, v39
	ds_write2_b32 v0, v6, v7 offset1:1
	v_add_u32_e32 v0, 0xc60, v39
	ds_write2_b32 v0, v16, v17 offset1:1
	v_add_u32_e32 v0, 0xc68, v39
	ds_write2_b32 v0, v18, v19 offset1:1
	v_add_u32_e32 v0, 0x1080, v39
	ds_write2_b32 v0, v12, v13 offset1:1
	v_add_u32_e32 v0, 0x1088, v39
	ds_write2_b32 v0, v14, v15 offset1:1
	v_add_u32_e32 v0, 0x14a0, v39
	ds_write2_b32 v0, v24, v25 offset1:1
	v_add_u32_e32 v0, 0x14a8, v39
	ds_write2_b32 v0, v26, v27 offset1:1
	v_add_u32_e32 v0, 0x18c0, v39
	ds_write2_b32 v0, v20, v21 offset1:1
	v_add_u32_e32 v0, 0x18c8, v39
	ds_write2_b32 v0, v22, v23 offset1:1
	v_add_u32_e32 v0, 0x1ce0, v39
	ds_write2_b32 v0, v28, v29 offset1:1
	v_add_u32_e32 v0, 0x1ce8, v39
	ds_write2_b32 v0, v30, v31 offset1:1
	s_waitcnt lgkmcnt(0)
	ds_read2_b32 v[4:5], v38 offset0:33 offset1:41
	ds_read2_b32 v[6:7], v38 offset1:8
	ds_read2_b32 v[8:9], v38 offset0:66 offset1:74
	ds_read2_b32 v[10:11], v38 offset0:99 offset1:107
	ds_read2_b32 v[12:13], v38 offset0:132 offset1:140
	ds_read2_b32 v[14:15], v38 offset0:165 offset1:173
	ds_read2_b32 v[16:17], v38 offset0:198 offset1:206
	ds_read2_b32 v[18:19], v38 offset0:231 offset1:239
	v_add_u32_e32 v22, s4, v37
	s_ashr_i32 s11, s10, 31
	v_ashrrev_i32_e32 v23, 31, v22
	v_lshl_add_u64 v[20:21], s[10:11], 1, v[32:33]
	v_lshlrev_b64 v[24:25], 11, v[22:23]
	s_waitcnt lgkmcnt(6)
	v_cvt_pk_bf16_f32 v0, v6, v4
	s_waitcnt lgkmcnt(4)
	v_cvt_pk_bf16_f32 v1, v8, v10
	s_waitcnt lgkmcnt(2)
	v_cvt_pk_bf16_f32 v2, v12, v14
	s_waitcnt lgkmcnt(0)
	v_cvt_pk_bf16_f32 v3, v16, v18
	v_lshl_add_u64 v[24:25], v[20:21], 0, v[24:25]
	v_add_u32_e32 v4, 8, v22
	global_store_dwordx4 v[24:25], v[0:3], off sc1
	s_add_i32 s0, s0, s34
	s_add_i32 s1, s1, s51
	v_cvt_pk_bf16_f32 v0, v7, v5
	v_ashrrev_i32_e32 v5, 31, v4
	v_cvt_pk_bf16_f32 v1, v9, v11
	v_cvt_pk_bf16_f32 v2, v13, v15
	v_cvt_pk_bf16_f32 v3, v17, v19
	v_lshlrev_b64 v[4:5], 11, v[4:5]
	ds_read2_b32 v[6:7], v38 offset0:49 offset1:57
	ds_read2_b32 v[8:9], v38 offset0:16 offset1:24
	ds_read2_b32 v[10:11], v38 offset0:82 offset1:90
	ds_read2_b32 v[12:13], v38 offset0:115 offset1:123
	ds_read2_b32 v[14:15], v38 offset0:148 offset1:156
	ds_read2_b32 v[16:17], v38 offset0:181 offset1:189
	ds_read2_b32 v[18:19], v38 offset0:214 offset1:222
	ds_read2_b32 v[24:25], v38 offset0:247 offset1:255
	v_lshl_add_u64 v[4:5], v[20:21], 0, v[4:5]
	global_store_dwordx4 v[4:5], v[0:3], off sc1
	v_add_u32_e32 v4, 16, v22
	v_ashrrev_i32_e32 v5, 31, v4
	v_lshlrev_b64 v[4:5], 11, v[4:5]
	s_waitcnt lgkmcnt(6)
	v_cvt_pk_bf16_f32 v0, v8, v6
	s_waitcnt lgkmcnt(4)
	v_cvt_pk_bf16_f32 v1, v10, v12
	s_waitcnt lgkmcnt(2)
	v_cvt_pk_bf16_f32 v2, v14, v16
	s_waitcnt lgkmcnt(0)
	v_cvt_pk_bf16_f32 v3, v18, v24
	v_lshl_add_u64 v[4:5], v[20:21], 0, v[4:5]
	global_store_dwordx4 v[4:5], v[0:3], off sc1
	v_add_u32_e32 v4, 24, v22
	v_ashrrev_i32_e32 v5, 31, v4
	v_lshlrev_b64 v[4:5], 11, v[4:5]
	v_cvt_pk_bf16_f32 v0, v9, v7
	v_cvt_pk_bf16_f32 v1, v11, v13
	v_cvt_pk_bf16_f32 v2, v15, v17
	v_cvt_pk_bf16_f32 v3, v19, v25
	v_lshl_add_u64 v[4:5], v[20:21], 0, v[4:5]
	global_store_dwordx4 v[4:5], v[0:3], off sc1
	s_waitcnt lgkmcnt(0)
	s_cmpk_lt_i32 s0, 0x580
	s_cbranch_scc0 .LBB0_1772

.LBB0_1794:
	s_or_b64 exec, exec, s[12:13]
	s_waitcnt vmcnt(0)
	ds_write2_b32 v41, v0, v1 offset1:1
	ds_write2_b32 v41, v2, v3 offset0:2 offset1:3
	v_add_u32_e32 v0, 0x420, v41
	ds_write2_b32 v0, v8, v9 offset1:1
	v_add_u32_e32 v0, 0x428, v41
	ds_write2_b32 v0, v10, v11 offset1:1
	v_add_u32_e32 v0, 0x840, v41
	ds_write2_b32 v0, v4, v5 offset1:1
	v_add_u32_e32 v0, 0x848, v41
	ds_write2_b32 v0, v6, v7 offset1:1
	v_add_u32_e32 v0, 0xc60, v41
	ds_write2_b32 v0, v16, v17 offset1:1
	v_add_u32_e32 v0, 0xc68, v41
	ds_write2_b32 v0, v18, v19 offset1:1
	v_add_u32_e32 v0, 0x1080, v41
	ds_write2_b32 v0, v12, v13 offset1:1
	v_add_u32_e32 v0, 0x1088, v41
	ds_write2_b32 v0, v14, v15 offset1:1
	v_add_u32_e32 v0, 0x14a0, v41
	ds_write2_b32 v0, v24, v25 offset1:1
	v_add_u32_e32 v0, 0x14a8, v41
	ds_write2_b32 v0, v26, v27 offset1:1
	v_add_u32_e32 v0, 0x18c0, v41
	ds_write2_b32 v0, v20, v21 offset1:1
	v_add_u32_e32 v0, 0x18c8, v41
	ds_write2_b32 v0, v22, v23 offset1:1
	v_add_u32_e32 v0, 0x1ce0, v41
	ds_write2_b32 v0, v28, v29 offset1:1
	v_add_u32_e32 v0, 0x1ce8, v41
	ds_write2_b32 v0, v30, v31 offset1:1
	s_waitcnt lgkmcnt(0)
	s_sub_i32 s3, 0, s3
	ds_read2_b32 v[4:5], v40 offset0:33 offset1:41
	ds_read2_b32 v[6:7], v40 offset1:8
	ds_read2_b32 v[8:9], v40 offset0:66 offset1:74
	ds_read2_b32 v[10:11], v40 offset0:99 offset1:107
	ds_read2_b32 v[12:13], v40 offset0:132 offset1:140
	ds_read2_b32 v[14:15], v40 offset0:165 offset1:173
	ds_read2_b32 v[16:17], v40 offset0:198 offset1:206
	ds_read2_b32 v[18:19], v40 offset0:231 offset1:239
	s_add_i32 s3, s3, s1
	v_add_u32_e32 v22, s3, v39
	s_ashr_i32 s11, s10, 31
	v_ashrrev_i32_e32 v23, 31, v22
	v_lshl_add_u64 v[20:21], s[10:11], 1, v[32:33]
	v_lshlrev_b64 v[24:25], 12, v[22:23]
	s_waitcnt lgkmcnt(6)
	v_cvt_pk_bf16_f32 v0, v6, v4
	s_waitcnt lgkmcnt(4)
	v_cvt_pk_bf16_f32 v1, v8, v10
	s_waitcnt lgkmcnt(2)
	v_cvt_pk_bf16_f32 v2, v12, v14
	s_waitcnt lgkmcnt(0)
	v_cvt_pk_bf16_f32 v3, v16, v18
	v_lshl_add_u64 v[24:25], v[20:21], 0, v[24:25]
	v_add_u32_e32 v4, 8, v22
	global_store_dwordx4 v[24:25], v[0:3], off sc1
	s_add_i32 s0, s0, s34
	s_add_i32 s1, s1, s51
	v_cvt_pk_bf16_f32 v0, v7, v5
	v_ashrrev_i32_e32 v5, 31, v4
	v_cvt_pk_bf16_f32 v1, v9, v11
	v_cvt_pk_bf16_f32 v2, v13, v15
	v_cvt_pk_bf16_f32 v3, v17, v19
	v_lshlrev_b64 v[4:5], 12, v[4:5]
	ds_read2_b32 v[6:7], v40 offset0:49 offset1:57
	ds_read2_b32 v[8:9], v40 offset0:16 offset1:24
	ds_read2_b32 v[10:11], v40 offset0:82 offset1:90
	ds_read2_b32 v[12:13], v40 offset0:115 offset1:123
	ds_read2_b32 v[14:15], v40 offset0:148 offset1:156
	ds_read2_b32 v[16:17], v40 offset0:181 offset1:189
	ds_read2_b32 v[18:19], v40 offset0:214 offset1:222
	ds_read2_b32 v[24:25], v40 offset0:247 offset1:255
	v_lshl_add_u64 v[4:5], v[20:21], 0, v[4:5]
	global_store_dwordx4 v[4:5], v[0:3], off sc1
	v_add_u32_e32 v4, 16, v22
	v_ashrrev_i32_e32 v5, 31, v4
	v_lshlrev_b64 v[4:5], 12, v[4:5]
	s_waitcnt lgkmcnt(6)
	v_cvt_pk_bf16_f32 v0, v8, v6
	s_waitcnt lgkmcnt(4)
	v_cvt_pk_bf16_f32 v1, v10, v12
	s_waitcnt lgkmcnt(2)
	v_cvt_pk_bf16_f32 v2, v14, v16
	s_waitcnt lgkmcnt(0)
	v_cvt_pk_bf16_f32 v3, v18, v24
	v_lshl_add_u64 v[4:5], v[20:21], 0, v[4:5]
	global_store_dwordx4 v[4:5], v[0:3], off sc1
	v_add_u32_e32 v4, 24, v22
	v_ashrrev_i32_e32 v5, 31, v4
	v_lshlrev_b64 v[4:5], 12, v[4:5]
	v_cvt_pk_bf16_f32 v0, v9, v7
	v_cvt_pk_bf16_f32 v1, v11, v13
	v_cvt_pk_bf16_f32 v2, v15, v17
	v_cvt_pk_bf16_f32 v3, v19, v25
	v_lshl_add_u64 v[4:5], v[20:21], 0, v[4:5]
	global_store_dwordx4 v[4:5], v[0:3], off sc1
	s_waitcnt lgkmcnt(0)
	s_cmpk_lt_i32 s0, 0x100
	s_cbranch_scc0 .LBB0_1811

.LBB0_1832:
	s_or_b64 exec, exec, s[12:13]
	s_waitcnt vmcnt(0)
	ds_write2_b32 v41, v0, v1 offset1:1
	ds_write2_b32 v41, v2, v3 offset0:2 offset1:3
	v_add_u32_e32 v0, 0x420, v41
	ds_write2_b32 v0, v8, v9 offset1:1
	v_add_u32_e32 v0, 0x428, v41
	ds_write2_b32 v0, v10, v11 offset1:1
	v_add_u32_e32 v0, 0x840, v41
	ds_write2_b32 v0, v4, v5 offset1:1
	v_add_u32_e32 v0, 0x848, v41
	ds_write2_b32 v0, v6, v7 offset1:1
	v_add_u32_e32 v0, 0xc60, v41
	ds_write2_b32 v0, v16, v17 offset1:1
	v_add_u32_e32 v0, 0xc68, v41
	ds_write2_b32 v0, v18, v19 offset1:1
	v_add_u32_e32 v0, 0x1080, v41
	ds_write2_b32 v0, v12, v13 offset1:1
	v_add_u32_e32 v0, 0x1088, v41
	ds_write2_b32 v0, v14, v15 offset1:1
	v_add_u32_e32 v0, 0x14a0, v41
	ds_write2_b32 v0, v24, v25 offset1:1
	v_add_u32_e32 v0, 0x14a8, v41
	ds_write2_b32 v0, v26, v27 offset1:1
	v_add_u32_e32 v0, 0x18c0, v41
	ds_write2_b32 v0, v20, v21 offset1:1
	v_add_u32_e32 v0, 0x18c8, v41
	ds_write2_b32 v0, v22, v23 offset1:1
	v_add_u32_e32 v0, 0x1ce0, v41
	ds_write2_b32 v0, v28, v29 offset1:1
	v_add_u32_e32 v0, 0x1ce8, v41
	ds_write2_b32 v0, v30, v31 offset1:1
	s_waitcnt lgkmcnt(0)
	s_sub_i32 s2, 0, s2
	ds_read2_b32 v[4:5], v40 offset0:33 offset1:41
	ds_read2_b32 v[6:7], v40 offset1:8
	ds_read2_b32 v[8:9], v40 offset0:66 offset1:74
	ds_read2_b32 v[10:11], v40 offset0:99 offset1:107
	ds_read2_b32 v[12:13], v40 offset0:132 offset1:140
	ds_read2_b32 v[14:15], v40 offset0:165 offset1:173
	ds_read2_b32 v[16:17], v40 offset0:198 offset1:206
	ds_read2_b32 v[18:19], v40 offset0:231 offset1:239
	s_add_i32 s2, s2, s1
	v_add_u32_e32 v22, s2, v39
	s_ashr_i32 s11, s10, 31
	v_ashrrev_i32_e32 v23, 31, v22
	v_lshl_add_u64 v[20:21], s[10:11], 1, v[32:33]
	v_lshlrev_b64 v[24:25], 9, v[22:23]
	s_waitcnt lgkmcnt(6)
	v_cvt_pk_bf16_f32 v0, v6, v4
	s_waitcnt lgkmcnt(4)
	v_cvt_pk_bf16_f32 v1, v8, v10
	s_waitcnt lgkmcnt(2)
	v_cvt_pk_bf16_f32 v2, v12, v14
	s_waitcnt lgkmcnt(0)
	v_cvt_pk_bf16_f32 v3, v16, v18
	v_lshl_add_u64 v[24:25], v[20:21], 0, v[24:25]
	v_add_u32_e32 v4, 8, v22
	global_store_dwordx4 v[24:25], v[0:3], off sc1
	s_add_i32 s0, s0, s34
	s_add_i32 s1, s1, s51
	v_cvt_pk_bf16_f32 v0, v7, v5
	v_ashrrev_i32_e32 v5, 31, v4
	v_cvt_pk_bf16_f32 v1, v9, v11
	v_cvt_pk_bf16_f32 v2, v13, v15
	v_cvt_pk_bf16_f32 v3, v17, v19
	v_lshlrev_b64 v[4:5], 9, v[4:5]
	ds_read2_b32 v[6:7], v40 offset0:49 offset1:57
	ds_read2_b32 v[8:9], v40 offset0:16 offset1:24
	ds_read2_b32 v[10:11], v40 offset0:82 offset1:90
	ds_read2_b32 v[12:13], v40 offset0:115 offset1:123
	ds_read2_b32 v[14:15], v40 offset0:148 offset1:156
	ds_read2_b32 v[16:17], v40 offset0:181 offset1:189
	ds_read2_b32 v[18:19], v40 offset0:214 offset1:222
	ds_read2_b32 v[24:25], v40 offset0:247 offset1:255
	v_lshl_add_u64 v[4:5], v[20:21], 0, v[4:5]
	global_store_dwordx4 v[4:5], v[0:3], off sc1
	v_add_u32_e32 v4, 16, v22
	v_ashrrev_i32_e32 v5, 31, v4
	v_lshlrev_b64 v[4:5], 9, v[4:5]
	s_waitcnt lgkmcnt(6)
	v_cvt_pk_bf16_f32 v0, v8, v6
	s_waitcnt lgkmcnt(4)
	v_cvt_pk_bf16_f32 v1, v10, v12
	s_waitcnt lgkmcnt(2)
	v_cvt_pk_bf16_f32 v2, v14, v16
	s_waitcnt lgkmcnt(0)
	v_cvt_pk_bf16_f32 v3, v18, v24
	v_lshl_add_u64 v[4:5], v[20:21], 0, v[4:5]
	global_store_dwordx4 v[4:5], v[0:3], off sc1
	v_add_u32_e32 v4, 24, v22
	v_ashrrev_i32_e32 v5, 31, v4
	v_lshlrev_b64 v[4:5], 9, v[4:5]
	v_cvt_pk_bf16_f32 v0, v9, v7
	v_cvt_pk_bf16_f32 v1, v11, v13
	v_cvt_pk_bf16_f32 v2, v15, v17
	v_cvt_pk_bf16_f32 v3, v19, v25
	v_lshl_add_u64 v[4:5], v[20:21], 0, v[4:5]
	global_store_dwordx4 v[4:5], v[0:3], off sc1
	s_waitcnt lgkmcnt(0)
	s_cmp_lt_i32 s0, 32
	s_cbranch_scc0 .LBB0_1849

.LBB0_1982:
	s_and_b64 vcc, exec, s[10:11]
	s_cbranch_vccz .LBB0_2367
	s_and_saveexec_b64 s[10:11], s[70:71]
	s_cbranch_execz .LBB0_1985
	v_mul_f32_e32 v64, 0xbfb8aa3b, v60
	v_rndne_f32_e32 v65, v64
	v_sub_f32_e32 v66, v64, v65
	v_fma_f32 v64, v60, s44, -v64
	v_fmac_f32_e32 v64, 0xb2a5705f, v60
	v_add_f32_e32 v64, v66, v64
	v_exp_f32_e32 v64, v64
	v_cvt_i32_f32_e32 v65, v65
	v_cmp_nlt_f32_e32 vcc, s45, v60
	v_ldexp_f32 v64, v64, v65
	s_nop 0
	v_cndmask_b32_e32 v64, 0, v64, vcc
	v_cmp_ngt_f32_e32 vcc, s46, v60
	s_nop 1
	v_cndmask_b32_e32 v60, v219, v64, vcc
	v_mul_f32_e32 v64, 0xbfb8aa3b, v61
	v_rndne_f32_e32 v65, v64
	v_sub_f32_e32 v66, v64, v65
	v_fma_f32 v64, v61, s44, -v64
	v_fmac_f32_e32 v64, 0xb2a5705f, v61
	v_add_f32_e32 v64, v66, v64
	v_exp_f32_e32 v64, v64
	v_cvt_i32_f32_e32 v65, v65
	v_cmp_nlt_f32_e32 vcc, s45, v61
	v_ldexp_f32 v64, v64, v65
	s_nop 0
	v_cndmask_b32_e32 v64, 0, v64, vcc
	v_cmp_ngt_f32_e32 vcc, s46, v61
	s_nop 1
	v_cndmask_b32_e32 v61, v219, v64, vcc
	v_mul_f32_e32 v64, 0xbfb8aa3b, v62
	v_rndne_f32_e32 v65, v64
	v_sub_f32_e32 v66, v64, v65
	v_fma_f32 v64, v62, s44, -v64
	v_fmac_f32_e32 v64, 0xb2a5705f, v62
	v_add_f32_e32 v64, v66, v64
	v_exp_f32_e32 v64, v64
	v_cvt_i32_f32_e32 v65, v65
	v_cmp_nlt_f32_e32 vcc, s45, v62
	v_pk_add_f32 v[60:61], v[60:61], 1.0 op_sel_hi:[1,0]
	v_ldexp_f32 v64, v64, v65
	v_cndmask_b32_e32 v64, 0, v64, vcc
	v_cmp_ngt_f32_e32 vcc, s46, v62
	s_nop 1
	v_cndmask_b32_e32 v62, v219, v64, vcc
	v_mul_f32_e32 v64, 0xbfb8aa3b, v63
	v_rndne_f32_e32 v65, v64
	v_sub_f32_e32 v66, v64, v65
	v_fma_f32 v64, v63, s44, -v64
	v_fmac_f32_e32 v64, 0xb2a5705f, v63
	v_add_f32_e32 v64, v66, v64
	v_exp_f32_e32 v64, v64
	v_cvt_i32_f32_e32 v65, v65
	v_cmp_nlt_f32_e32 vcc, s45, v63
	v_ldexp_f32 v64, v64, v65
	s_nop 0
	v_cndmask_b32_e32 v64, 0, v64, vcc
	v_cmp_ngt_f32_e32 vcc, s46, v63
	s_nop 1
	v_cndmask_b32_e32 v63, v219, v64, vcc
	v_pk_add_f32 v[62:63], v[62:63], 1.0 op_sel_hi:[1,0]
	s_nop 0
	v_div_scale_f32 v64, s[12:13], v63, v63, 1.0
	v_rcp_f32_e32 v65, v64
	s_nop 0
	v_fma_f32 v66, -v64, v65, 1.0
	v_fmac_f32_e32 v65, v66, v65
	v_div_scale_f32 v66, vcc, 1.0, v63, 1.0
	v_mul_f32_e32 v67, v66, v65
	v_fma_f32 v68, -v64, v67, v66
	v_fmac_f32_e32 v67, v68, v65
	v_fma_f32 v64, -v64, v67, v66
	v_div_fmas_f32 v64, v64, v65, v67
	v_div_fixup_f32 v65, v64, v63, 1.0
	v_div_scale_f32 v63, s[12:13], v62, v62, 1.0
	v_rcp_f32_e32 v64, v63
	s_nop 0
	v_fma_f32 v66, -v63, v64, 1.0
	v_fmac_f32_e32 v64, v66, v64
	v_div_scale_f32 v66, vcc, 1.0, v62, 1.0
	v_mul_f32_e32 v67, v66, v64
	v_fma_f32 v68, -v63, v67, v66
	v_fmac_f32_e32 v67, v68, v64
	v_fma_f32 v63, -v63, v67, v66
	v_div_fmas_f32 v63, v63, v64, v67
	v_div_fixup_f32 v64, v63, v62, 1.0
	v_div_scale_f32 v62, s[12:13], v61, v61, 1.0
	v_rcp_f32_e32 v63, v62
	s_nop 0
	v_fma_f32 v66, -v62, v63, 1.0
	v_fmac_f32_e32 v63, v66, v63
	v_div_scale_f32 v66, vcc, 1.0, v61, 1.0
	v_mul_f32_e32 v67, v66, v63
	v_fma_f32 v68, -v62, v67, v66
	v_fmac_f32_e32 v67, v68, v63
	v_fma_f32 v62, -v62, v67, v66
	v_div_fmas_f32 v62, v62, v63, v67
	v_div_fixup_f32 v63, v62, v61, 1.0
	v_div_scale_f32 v61, s[12:13], v60, v60, 1.0
	v_rcp_f32_e32 v62, v61
	s_nop 0
	v_fma_f32 v66, -v61, v62, 1.0
	v_fmac_f32_e32 v62, v66, v62
	v_div_scale_f32 v66, vcc, 1.0, v60, 1.0
	v_mul_f32_e32 v67, v66, v62
	v_fma_f32 v68, -v61, v67, v66
	v_fmac_f32_e32 v67, v68, v62
	v_fma_f32 v61, -v61, v67, v66
	v_div_fmas_f32 v61, v61, v62, v67
	v_div_fixup_f32 v62, v61, v60, 1.0
	v_mad_i64_i32 v[60:61], s[12:13], v200, s5, v[190:191]
	global_store_dwordx4 v[60:61], v[62:65], off sc1
	v_cmp_nlt_f32_e32 vcc, s45, v56
	s_nop 0
	v_mul_f32_e32 v62, 0xbfb8aa3b, v56
	v_rndne_f32_e32 v63, v62
	v_sub_f32_e32 v64, v62, v63
	v_fma_f32 v62, v56, s44, -v62
	v_fmac_f32_e32 v62, 0xb2a5705f, v56
	v_add_f32_e32 v62, v64, v62
	v_exp_f32_e32 v62, v62
	v_cvt_i32_f32_e32 v63, v63
	v_ldexp_f32 v62, v62, v63
	v_cndmask_b32_e32 v62, 0, v62, vcc
	v_cmp_ngt_f32_e32 vcc, s46, v56
	s_nop 1
	v_cndmask_b32_e32 v56, v219, v62, vcc
	v_mul_f32_e32 v62, 0xbfb8aa3b, v57
	v_rndne_f32_e32 v63, v62
	v_sub_f32_e32 v64, v62, v63
	v_fma_f32 v62, v57, s44, -v62
	v_fmac_f32_e32 v62, 0xb2a5705f, v57
	v_add_f32_e32 v62, v64, v62
	v_exp_f32_e32 v62, v62
	v_cvt_i32_f32_e32 v63, v63
	v_cmp_nlt_f32_e32 vcc, s45, v57
	v_ldexp_f32 v62, v62, v63
	s_nop 0
	v_cndmask_b32_e32 v62, 0, v62, vcc
	v_cmp_ngt_f32_e32 vcc, s46, v57
	s_nop 1
	v_cndmask_b32_e32 v57, v219, v62, vcc
	v_mul_f32_e32 v62, 0xbfb8aa3b, v58
	v_rndne_f32_e32 v63, v62
	v_sub_f32_e32 v64, v62, v63
	v_fma_f32 v62, v58, s44, -v62
	v_fmac_f32_e32 v62, 0xb2a5705f, v58
	v_add_f32_e32 v62, v64, v62
	v_exp_f32_e32 v62, v62
	v_cvt_i32_f32_e32 v63, v63
	v_cmp_nlt_f32_e32 vcc, s45, v58
	v_pk_add_f32 v[56:57], v[56:57], 1.0 op_sel_hi:[1,0]
	v_ldexp_f32 v62, v62, v63
	v_cndmask_b32_e32 v62, 0, v62, vcc
	v_cmp_ngt_f32_e32 vcc, s46, v58
	s_nop 1
	v_cndmask_b32_e32 v58, v219, v62, vcc
	v_mul_f32_e32 v62, 0xbfb8aa3b, v59
	v_rndne_f32_e32 v63, v62
	v_sub_f32_e32 v64, v62, v63
	v_fma_f32 v62, v59, s44, -v62
	v_fmac_f32_e32 v62, 0xb2a5705f, v59
	v_add_f32_e32 v62, v64, v62
	v_exp_f32_e32 v62, v62
	v_cvt_i32_f32_e32 v63, v63
	v_cmp_nlt_f32_e32 vcc, s45, v59
	v_ldexp_f32 v62, v62, v63
	s_nop 0
	v_cndmask_b32_e32 v62, 0, v62, vcc
	v_cmp_ngt_f32_e32 vcc, s46, v59
	s_nop 1
	v_cndmask_b32_e32 v59, v219, v62, vcc
	v_pk_add_f32 v[58:59], v[58:59], 1.0 op_sel_hi:[1,0]
	s_nop 0
	v_div_scale_f32 v62, s[12:13], v59, v59, 1.0
	v_rcp_f32_e32 v63, v62
	s_nop 0
	v_fma_f32 v64, -v62, v63, 1.0
	v_fmac_f32_e32 v63, v64, v63
	v_div_scale_f32 v64, vcc, 1.0, v59, 1.0
	v_mul_f32_e32 v65, v64, v63
	v_fma_f32 v66, -v62, v65, v64
	v_fmac_f32_e32 v65, v66, v63
	v_fma_f32 v62, -v62, v65, v64
	v_div_fmas_f32 v62, v62, v63, v65
	v_div_fixup_f32 v59, v62, v59, 1.0
	v_div_scale_f32 v62, s[12:13], v58, v58, 1.0
	v_rcp_f32_e32 v63, v62
	s_nop 0
	v_fma_f32 v64, -v62, v63, 1.0
	v_fmac_f32_e32 v63, v64, v63
	v_div_scale_f32 v64, vcc, 1.0, v58, 1.0
	v_mul_f32_e32 v65, v64, v63
	v_fma_f32 v66, -v62, v65, v64
	v_fmac_f32_e32 v65, v66, v63
	v_fma_f32 v62, -v62, v65, v64
	v_div_fmas_f32 v62, v62, v63, v65
	v_div_fixup_f32 v58, v62, v58, 1.0
	v_div_scale_f32 v62, s[12:13], v57, v57, 1.0
	v_rcp_f32_e32 v63, v62
	s_nop 0
	v_fma_f32 v64, -v62, v63, 1.0
	v_fmac_f32_e32 v63, v64, v63
	v_div_scale_f32 v64, vcc, 1.0, v57, 1.0
	v_mul_f32_e32 v65, v64, v63
	v_fma_f32 v66, -v62, v65, v64
	v_fmac_f32_e32 v65, v66, v63
	v_fma_f32 v62, -v62, v65, v64
	v_div_fmas_f32 v62, v62, v63, v65
	v_div_fixup_f32 v57, v62, v57, 1.0
	v_div_scale_f32 v62, s[12:13], v56, v56, 1.0
	v_rcp_f32_e32 v63, v62
	s_nop 0
	v_fma_f32 v64, -v62, v63, 1.0
	v_fmac_f32_e32 v63, v64, v63
	v_div_scale_f32 v64, vcc, 1.0, v56, 1.0
	v_mul_f32_e32 v65, v64, v63
	v_fma_f32 v66, -v62, v65, v64
	v_fmac_f32_e32 v65, v66, v63
	v_fma_f32 v62, -v62, v65, v64
	v_div_fmas_f32 v62, v62, v63, v65
	v_div_fixup_f32 v56, v62, v56, 1.0
	global_store_dwordx4 v[60:61], v[56:59], off offset:16 sc1
	v_cmp_nlt_f32_e32 vcc, s45, v52
	s_nop 0
	v_mul_f32_e32 v56, 0xbfb8aa3b, v52
	v_rndne_f32_e32 v57, v56
	v_sub_f32_e32 v59, v56, v57
	v_fma_f32 v56, v52, s44, -v56
	v_fmac_f32_e32 v56, 0xb2a5705f, v52
	v_add_f32_e32 v56, v59, v56
	v_exp_f32_e32 v56, v56
	v_cvt_i32_f32_e32 v57, v57
	v_or_b32_e32 v58, 16, v200
	v_ldexp_f32 v56, v56, v57
	v_cndmask_b32_e32 v56, 0, v56, vcc
	v_cmp_ngt_f32_e32 vcc, s46, v52
	s_nop 1
	v_cndmask_b32_e32 v52, v219, v56, vcc
	v_mul_f32_e32 v56, 0xbfb8aa3b, v53
	v_rndne_f32_e32 v57, v56
	v_sub_f32_e32 v59, v56, v57
	v_fma_f32 v56, v53, s44, -v56
	v_fmac_f32_e32 v56, 0xb2a5705f, v53
	v_add_f32_e32 v56, v59, v56
	v_exp_f32_e32 v56, v56
	v_cvt_i32_f32_e32 v57, v57
	v_cmp_nlt_f32_e32 vcc, s45, v53
	v_ldexp_f32 v56, v56, v57
	s_nop 0
	v_cndmask_b32_e32 v56, 0, v56, vcc
	v_cmp_ngt_f32_e32 vcc, s46, v53
	s_nop 1
	v_cndmask_b32_e32 v53, v219, v56, vcc
	v_mul_f32_e32 v56, 0xbfb8aa3b, v54
	v_rndne_f32_e32 v57, v56
	v_sub_f32_e32 v59, v56, v57
	v_fma_f32 v56, v54, s44, -v56
	v_fmac_f32_e32 v56, 0xb2a5705f, v54
	v_add_f32_e32 v56, v59, v56
	v_exp_f32_e32 v56, v56
	v_cvt_i32_f32_e32 v57, v57
	v_cmp_nlt_f32_e32 vcc, s45, v54
	v_pk_add_f32 v[52:53], v[52:53], 1.0 op_sel_hi:[1,0]
	v_ldexp_f32 v56, v56, v57
	v_cndmask_b32_e32 v56, 0, v56, vcc
	v_cmp_ngt_f32_e32 vcc, s46, v54
	s_nop 1
	v_cndmask_b32_e32 v54, v219, v56, vcc
	v_mul_f32_e32 v56, 0xbfb8aa3b, v55
	v_rndne_f32_e32 v57, v56
	v_sub_f32_e32 v59, v56, v57
	v_fma_f32 v56, v55, s44, -v56
	v_fmac_f32_e32 v56, 0xb2a5705f, v55
	v_add_f32_e32 v56, v59, v56
	v_exp_f32_e32 v56, v56
	v_cvt_i32_f32_e32 v57, v57
	v_cmp_nlt_f32_e32 vcc, s45, v55
	v_ldexp_f32 v56, v56, v57
	s_nop 0
	v_cndmask_b32_e32 v56, 0, v56, vcc
	v_cmp_ngt_f32_e32 vcc, s46, v55
	s_nop 1
	v_cndmask_b32_e32 v55, v219, v56, vcc
	v_pk_add_f32 v[54:55], v[54:55], 1.0 op_sel_hi:[1,0]
	s_nop 0
	v_div_scale_f32 v56, s[12:13], v55, v55, 1.0
	v_rcp_f32_e32 v57, v56
	s_nop 0
	v_fma_f32 v59, -v56, v57, 1.0
	v_fmac_f32_e32 v57, v59, v57
	v_div_scale_f32 v59, vcc, 1.0, v55, 1.0
	v_mul_f32_e32 v60, v59, v57
	v_fma_f32 v61, -v56, v60, v59
	v_fmac_f32_e32 v60, v61, v57
	v_fma_f32 v56, -v56, v60, v59
	v_div_fmas_f32 v56, v56, v57, v60
	v_div_fixup_f32 v57, v56, v55, 1.0
	v_div_scale_f32 v55, s[12:13], v54, v54, 1.0
	v_rcp_f32_e32 v56, v55
	s_nop 0
	v_fma_f32 v59, -v55, v56, 1.0
	v_fmac_f32_e32 v56, v59, v56
	v_div_scale_f32 v59, vcc, 1.0, v54, 1.0
	v_mul_f32_e32 v60, v59, v56
	v_fma_f32 v61, -v55, v60, v59
	v_fmac_f32_e32 v60, v61, v56
	v_fma_f32 v55, -v55, v60, v59
	v_div_fmas_f32 v55, v55, v56, v60
	v_div_fixup_f32 v56, v55, v54, 1.0
	v_div_scale_f32 v54, s[12:13], v53, v53, 1.0
	v_rcp_f32_e32 v55, v54
	s_nop 0
	v_fma_f32 v59, -v54, v55, 1.0
	v_fmac_f32_e32 v55, v59, v55
	v_div_scale_f32 v59, vcc, 1.0, v53, 1.0
	v_mul_f32_e32 v60, v59, v55
	v_fma_f32 v61, -v54, v60, v59
	v_fmac_f32_e32 v60, v61, v55
	v_fma_f32 v54, -v54, v60, v59
	v_div_fmas_f32 v54, v54, v55, v60
	v_div_fixup_f32 v55, v54, v53, 1.0
	v_div_scale_f32 v53, s[12:13], v52, v52, 1.0
	v_rcp_f32_e32 v54, v53
	s_nop 0
	v_fma_f32 v59, -v53, v54, 1.0
	v_fmac_f32_e32 v54, v59, v54
	v_div_scale_f32 v59, vcc, 1.0, v52, 1.0
	v_mul_f32_e32 v60, v59, v54
	v_fma_f32 v61, -v53, v60, v59
	v_fmac_f32_e32 v60, v61, v54
	v_fma_f32 v53, -v53, v60, v59
	v_div_fmas_f32 v53, v53, v54, v60
	v_div_fixup_f32 v54, v53, v52, 1.0
	v_mad_i64_i32 v[52:53], s[12:13], v58, s5, v[190:191]
	global_store_dwordx4 v[52:53], v[54:57], off sc1
	v_cmp_nlt_f32_e32 vcc, s45, v48
	s_nop 0
	v_mul_f32_e32 v54, 0xbfb8aa3b, v48
	v_rndne_f32_e32 v55, v54
	v_sub_f32_e32 v56, v54, v55
	v_fma_f32 v54, v48, s44, -v54
	v_fmac_f32_e32 v54, 0xb2a5705f, v48
	v_add_f32_e32 v54, v56, v54
	v_exp_f32_e32 v54, v54
	v_cvt_i32_f32_e32 v55, v55
	v_ldexp_f32 v54, v54, v55
	v_cndmask_b32_e32 v54, 0, v54, vcc
	v_cmp_ngt_f32_e32 vcc, s46, v48
	s_nop 1
	v_cndmask_b32_e32 v48, v219, v54, vcc
	v_mul_f32_e32 v54, 0xbfb8aa3b, v49
	v_rndne_f32_e32 v55, v54
	v_sub_f32_e32 v56, v54, v55
	v_fma_f32 v54, v49, s44, -v54
	v_fmac_f32_e32 v54, 0xb2a5705f, v49
	v_add_f32_e32 v54, v56, v54
	v_exp_f32_e32 v54, v54
	v_cvt_i32_f32_e32 v55, v55
	v_cmp_nlt_f32_e32 vcc, s45, v49
	v_ldexp_f32 v54, v54, v55
	s_nop 0
	v_cndmask_b32_e32 v54, 0, v54, vcc
	v_cmp_ngt_f32_e32 vcc, s46, v49
	s_nop 1
	v_cndmask_b32_e32 v49, v219, v54, vcc
	v_mul_f32_e32 v54, 0xbfb8aa3b, v50
	v_rndne_f32_e32 v55, v54
	v_sub_f32_e32 v56, v54, v55
	v_fma_f32 v54, v50, s44, -v54
	v_fmac_f32_e32 v54, 0xb2a5705f, v50
	v_add_f32_e32 v54, v56, v54
	v_exp_f32_e32 v54, v54
	v_cvt_i32_f32_e32 v55, v55
	v_cmp_nlt_f32_e32 vcc, s45, v50
	v_pk_add_f32 v[48:49], v[48:49], 1.0 op_sel_hi:[1,0]
	v_ldexp_f32 v54, v54, v55
	v_cndmask_b32_e32 v54, 0, v54, vcc
	v_cmp_ngt_f32_e32 vcc, s46, v50
	s_nop 1
	v_cndmask_b32_e32 v50, v219, v54, vcc
	v_mul_f32_e32 v54, 0xbfb8aa3b, v51
	v_rndne_f32_e32 v55, v54
	v_sub_f32_e32 v56, v54, v55
	v_fma_f32 v54, v51, s44, -v54
	v_fmac_f32_e32 v54, 0xb2a5705f, v51
	v_add_f32_e32 v54, v56, v54
	v_exp_f32_e32 v54, v54
	v_cvt_i32_f32_e32 v55, v55
	v_cmp_nlt_f32_e32 vcc, s45, v51
	v_ldexp_f32 v54, v54, v55
	s_nop 0
	v_cndmask_b32_e32 v54, 0, v54, vcc
	v_cmp_ngt_f32_e32 vcc, s46, v51
	s_nop 1
	v_cndmask_b32_e32 v51, v219, v54, vcc
	v_pk_add_f32 v[50:51], v[50:51], 1.0 op_sel_hi:[1,0]
	s_nop 0
	v_div_scale_f32 v54, s[12:13], v51, v51, 1.0
	v_rcp_f32_e32 v55, v54
	s_nop 0
	v_fma_f32 v56, -v54, v55, 1.0
	v_fmac_f32_e32 v55, v56, v55
	v_div_scale_f32 v56, vcc, 1.0, v51, 1.0
	v_mul_f32_e32 v57, v56, v55
	v_fma_f32 v58, -v54, v57, v56
	v_fmac_f32_e32 v57, v58, v55
	v_fma_f32 v54, -v54, v57, v56
	v_div_fmas_f32 v54, v54, v55, v57
	v_div_fixup_f32 v51, v54, v51, 1.0
	v_div_scale_f32 v54, s[12:13], v50, v50, 1.0
	v_rcp_f32_e32 v55, v54
	s_nop 0
	v_fma_f32 v56, -v54, v55, 1.0
	v_fmac_f32_e32 v55, v56, v55
	v_div_scale_f32 v56, vcc, 1.0, v50, 1.0
	v_mul_f32_e32 v57, v56, v55
	v_fma_f32 v58, -v54, v57, v56
	v_fmac_f32_e32 v57, v58, v55
	v_fma_f32 v54, -v54, v57, v56
	v_div_fmas_f32 v54, v54, v55, v57
	v_div_fixup_f32 v50, v54, v50, 1.0
	v_div_scale_f32 v54, s[12:13], v49, v49, 1.0
	v_rcp_f32_e32 v55, v54
	s_nop 0
	v_fma_f32 v56, -v54, v55, 1.0
	v_fmac_f32_e32 v55, v56, v55
	v_div_scale_f32 v56, vcc, 1.0, v49, 1.0
	v_mul_f32_e32 v57, v56, v55
	v_fma_f32 v58, -v54, v57, v56
	v_fmac_f32_e32 v57, v58, v55
	v_fma_f32 v54, -v54, v57, v56
	v_div_fmas_f32 v54, v54, v55, v57
	v_div_fixup_f32 v49, v54, v49, 1.0
	v_div_scale_f32 v54, s[12:13], v48, v48, 1.0
	v_rcp_f32_e32 v55, v54
	s_nop 0
	v_fma_f32 v56, -v54, v55, 1.0
	v_fmac_f32_e32 v55, v56, v55
	v_div_scale_f32 v56, vcc, 1.0, v48, 1.0
	v_mul_f32_e32 v57, v56, v55
	v_fma_f32 v58, -v54, v57, v56
	v_fmac_f32_e32 v57, v58, v55
	v_fma_f32 v54, -v54, v57, v56
	v_div_fmas_f32 v54, v54, v55, v57
	v_div_fixup_f32 v48, v54, v48, 1.0
	global_store_dwordx4 v[52:53], v[48:51], off offset:16 sc1
	v_cmp_nlt_f32_e32 vcc, s45, v44
	s_nop 0
	v_mul_f32_e32 v48, 0xbfb8aa3b, v44
	v_rndne_f32_e32 v49, v48
	v_sub_f32_e32 v51, v48, v49
	v_fma_f32 v48, v44, s44, -v48
	v_fmac_f32_e32 v48, 0xb2a5705f, v44
	v_add_f32_e32 v48, v51, v48
	v_exp_f32_e32 v48, v48
	v_cvt_i32_f32_e32 v49, v49
	v_or_b32_e32 v50, 32, v200
	v_ldexp_f32 v48, v48, v49
	v_cndmask_b32_e32 v48, 0, v48, vcc
	v_cmp_ngt_f32_e32 vcc, s46, v44
	s_nop 1
	v_cndmask_b32_e32 v44, v219, v48, vcc
	v_mul_f32_e32 v48, 0xbfb8aa3b, v45
	v_rndne_f32_e32 v49, v48
	v_sub_f32_e32 v51, v48, v49
	v_fma_f32 v48, v45, s44, -v48
	v_fmac_f32_e32 v48, 0xb2a5705f, v45
	v_add_f32_e32 v48, v51, v48
	v_exp_f32_e32 v48, v48
	v_cvt_i32_f32_e32 v49, v49
	v_cmp_nlt_f32_e32 vcc, s45, v45
	v_ldexp_f32 v48, v48, v49
	s_nop 0
	v_cndmask_b32_e32 v48, 0, v48, vcc
	v_cmp_ngt_f32_e32 vcc, s46, v45
	s_nop 1
	v_cndmask_b32_e32 v45, v219, v48, vcc
	v_mul_f32_e32 v48, 0xbfb8aa3b, v46
	v_rndne_f32_e32 v49, v48
	v_sub_f32_e32 v51, v48, v49
	v_fma_f32 v48, v46, s44, -v48
	v_fmac_f32_e32 v48, 0xb2a5705f, v46
	v_add_f32_e32 v48, v51, v48
	v_exp_f32_e32 v48, v48
	v_cvt_i32_f32_e32 v49, v49
	v_cmp_nlt_f32_e32 vcc, s45, v46
	v_pk_add_f32 v[44:45], v[44:45], 1.0 op_sel_hi:[1,0]
	v_ldexp_f32 v48, v48, v49
	v_cndmask_b32_e32 v48, 0, v48, vcc
	v_cmp_ngt_f32_e32 vcc, s46, v46
	s_nop 1
	v_cndmask_b32_e32 v46, v219, v48, vcc
	v_mul_f32_e32 v48, 0xbfb8aa3b, v47
	v_rndne_f32_e32 v49, v48
	v_sub_f32_e32 v51, v48, v49
	v_fma_f32 v48, v47, s44, -v48
	v_fmac_f32_e32 v48, 0xb2a5705f, v47
	v_add_f32_e32 v48, v51, v48
	v_exp_f32_e32 v48, v48
	v_cvt_i32_f32_e32 v49, v49
	v_cmp_nlt_f32_e32 vcc, s45, v47
	v_ldexp_f32 v48, v48, v49
	s_nop 0
	v_cndmask_b32_e32 v48, 0, v48, vcc
	v_cmp_ngt_f32_e32 vcc, s46, v47
	s_nop 1
	v_cndmask_b32_e32 v47, v219, v48, vcc
	v_pk_add_f32 v[46:47], v[46:47], 1.0 op_sel_hi:[1,0]
	s_nop 0
	v_div_scale_f32 v48, s[12:13], v47, v47, 1.0
	v_rcp_f32_e32 v49, v48
	s_nop 0
	v_fma_f32 v51, -v48, v49, 1.0
	v_fmac_f32_e32 v49, v51, v49
	v_div_scale_f32 v51, vcc, 1.0, v47, 1.0
	v_mul_f32_e32 v52, v51, v49
	v_fma_f32 v53, -v48, v52, v51
	v_fmac_f32_e32 v52, v53, v49
	v_fma_f32 v48, -v48, v52, v51
	v_div_fmas_f32 v48, v48, v49, v52
	v_div_fixup_f32 v49, v48, v47, 1.0
	v_div_scale_f32 v47, s[12:13], v46, v46, 1.0
	v_rcp_f32_e32 v48, v47
	s_nop 0
	v_fma_f32 v51, -v47, v48, 1.0
	v_fmac_f32_e32 v48, v51, v48
	v_div_scale_f32 v51, vcc, 1.0, v46, 1.0
	v_mul_f32_e32 v52, v51, v48
	v_fma_f32 v53, -v47, v52, v51
	v_fmac_f32_e32 v52, v53, v48
	v_fma_f32 v47, -v47, v52, v51
	v_div_fmas_f32 v47, v47, v48, v52
	v_div_fixup_f32 v48, v47, v46, 1.0
	v_div_scale_f32 v46, s[12:13], v45, v45, 1.0
	v_rcp_f32_e32 v47, v46
	s_nop 0
	v_fma_f32 v51, -v46, v47, 1.0
	v_fmac_f32_e32 v47, v51, v47
	v_div_scale_f32 v51, vcc, 1.0, v45, 1.0
	v_mul_f32_e32 v52, v51, v47
	v_fma_f32 v53, -v46, v52, v51
	v_fmac_f32_e32 v52, v53, v47
	v_fma_f32 v46, -v46, v52, v51
	v_div_fmas_f32 v46, v46, v47, v52
	v_div_fixup_f32 v47, v46, v45, 1.0
	v_div_scale_f32 v45, s[12:13], v44, v44, 1.0
	v_rcp_f32_e32 v46, v45
	s_nop 0
	v_fma_f32 v51, -v45, v46, 1.0
	v_fmac_f32_e32 v46, v51, v46
	v_div_scale_f32 v51, vcc, 1.0, v44, 1.0
	v_mul_f32_e32 v52, v51, v46
	v_fma_f32 v53, -v45, v52, v51
	v_fmac_f32_e32 v52, v53, v46
	v_fma_f32 v45, -v45, v52, v51
	v_div_fmas_f32 v45, v45, v46, v52
	v_div_fixup_f32 v46, v45, v44, 1.0
	v_mad_i64_i32 v[44:45], s[12:13], v50, s5, v[190:191]
	global_store_dwordx4 v[44:45], v[46:49], off sc1
	v_cmp_nlt_f32_e32 vcc, s45, v40
	s_nop 0
	v_mul_f32_e32 v46, 0xbfb8aa3b, v40
	v_rndne_f32_e32 v47, v46
	v_sub_f32_e32 v48, v46, v47
	v_fma_f32 v46, v40, s44, -v46
	v_fmac_f32_e32 v46, 0xb2a5705f, v40
	v_add_f32_e32 v46, v48, v46
	v_exp_f32_e32 v46, v46
	v_cvt_i32_f32_e32 v47, v47
	v_ldexp_f32 v46, v46, v47
	v_cndmask_b32_e32 v46, 0, v46, vcc
	v_cmp_ngt_f32_e32 vcc, s46, v40
	s_nop 1
	v_cndmask_b32_e32 v40, v219, v46, vcc
	v_mul_f32_e32 v46, 0xbfb8aa3b, v41
	v_rndne_f32_e32 v47, v46
	v_sub_f32_e32 v48, v46, v47
	v_fma_f32 v46, v41, s44, -v46
	v_fmac_f32_e32 v46, 0xb2a5705f, v41
	v_add_f32_e32 v46, v48, v46
	v_exp_f32_e32 v46, v46
	v_cvt_i32_f32_e32 v47, v47
	v_cmp_nlt_f32_e32 vcc, s45, v41
	v_ldexp_f32 v46, v46, v47
	s_nop 0
	v_cndmask_b32_e32 v46, 0, v46, vcc
	v_cmp_ngt_f32_e32 vcc, s46, v41
	s_nop 1
	v_cndmask_b32_e32 v41, v219, v46, vcc
	v_mul_f32_e32 v46, 0xbfb8aa3b, v42
	v_rndne_f32_e32 v47, v46
	v_sub_f32_e32 v48, v46, v47
	v_fma_f32 v46, v42, s44, -v46
	v_fmac_f32_e32 v46, 0xb2a5705f, v42
	v_add_f32_e32 v46, v48, v46
	v_exp_f32_e32 v46, v46
	v_cvt_i32_f32_e32 v47, v47
	v_cmp_nlt_f32_e32 vcc, s45, v42
	v_pk_add_f32 v[40:41], v[40:41], 1.0 op_sel_hi:[1,0]
	v_ldexp_f32 v46, v46, v47
	v_cndmask_b32_e32 v46, 0, v46, vcc
	v_cmp_ngt_f32_e32 vcc, s46, v42
	s_nop 1
	v_cndmask_b32_e32 v42, v219, v46, vcc
	v_mul_f32_e32 v46, 0xbfb8aa3b, v43
	v_rndne_f32_e32 v47, v46
	v_sub_f32_e32 v48, v46, v47
	v_fma_f32 v46, v43, s44, -v46
	v_fmac_f32_e32 v46, 0xb2a5705f, v43
	v_add_f32_e32 v46, v48, v46
	v_exp_f32_e32 v46, v46
	v_cvt_i32_f32_e32 v47, v47
	v_cmp_nlt_f32_e32 vcc, s45, v43
	v_ldexp_f32 v46, v46, v47
	s_nop 0
	v_cndmask_b32_e32 v46, 0, v46, vcc
	v_cmp_ngt_f32_e32 vcc, s46, v43
	s_nop 1
	v_cndmask_b32_e32 v43, v219, v46, vcc
	v_pk_add_f32 v[42:43], v[42:43], 1.0 op_sel_hi:[1,0]
	s_nop 0
	v_div_scale_f32 v46, s[12:13], v43, v43, 1.0
	v_rcp_f32_e32 v47, v46
	s_nop 0
	v_fma_f32 v48, -v46, v47, 1.0
	v_fmac_f32_e32 v47, v48, v47
	v_div_scale_f32 v48, vcc, 1.0, v43, 1.0
	v_mul_f32_e32 v49, v48, v47
	v_fma_f32 v50, -v46, v49, v48
	v_fmac_f32_e32 v49, v50, v47
	v_fma_f32 v46, -v46, v49, v48
	v_div_fmas_f32 v46, v46, v47, v49
	v_div_fixup_f32 v43, v46, v43, 1.0
	v_div_scale_f32 v46, s[12:13], v42, v42, 1.0
	v_rcp_f32_e32 v47, v46
	s_nop 0
	v_fma_f32 v48, -v46, v47, 1.0
	v_fmac_f32_e32 v47, v48, v47
	v_div_scale_f32 v48, vcc, 1.0, v42, 1.0
	v_mul_f32_e32 v49, v48, v47
	v_fma_f32 v50, -v46, v49, v48
	v_fmac_f32_e32 v49, v50, v47
	v_fma_f32 v46, -v46, v49, v48
	v_div_fmas_f32 v46, v46, v47, v49
	v_div_fixup_f32 v42, v46, v42, 1.0
	v_div_scale_f32 v46, s[12:13], v41, v41, 1.0
	v_rcp_f32_e32 v47, v46
	s_nop 0
	v_fma_f32 v48, -v46, v47, 1.0
	v_fmac_f32_e32 v47, v48, v47
	v_div_scale_f32 v48, vcc, 1.0, v41, 1.0
	v_mul_f32_e32 v49, v48, v47
	v_fma_f32 v50, -v46, v49, v48
	v_fmac_f32_e32 v49, v50, v47
	v_fma_f32 v46, -v46, v49, v48
	v_div_fmas_f32 v46, v46, v47, v49
	v_div_fixup_f32 v41, v46, v41, 1.0
	v_div_scale_f32 v46, s[12:13], v40, v40, 1.0
	v_rcp_f32_e32 v47, v46
	s_nop 0
	v_fma_f32 v48, -v46, v47, 1.0
	v_fmac_f32_e32 v47, v48, v47
	v_div_scale_f32 v48, vcc, 1.0, v40, 1.0
	v_mul_f32_e32 v49, v48, v47
	v_fma_f32 v50, -v46, v49, v48
	v_fmac_f32_e32 v49, v50, v47
	v_fma_f32 v46, -v46, v49, v48
	v_div_fmas_f32 v46, v46, v47, v49
	v_div_fixup_f32 v40, v46, v40, 1.0
	global_store_dwordx4 v[44:45], v[40:43], off offset:16 sc1
	v_cmp_nlt_f32_e32 vcc, s45, v36
	s_nop 0
	v_mul_f32_e32 v40, 0xbfb8aa3b, v36
	v_rndne_f32_e32 v41, v40
	v_sub_f32_e32 v43, v40, v41
	v_fma_f32 v40, v36, s44, -v40
	v_fmac_f32_e32 v40, 0xb2a5705f, v36
	v_add_f32_e32 v40, v43, v40
	v_exp_f32_e32 v40, v40
	v_cvt_i32_f32_e32 v41, v41
	v_or_b32_e32 v42, 48, v200
	v_ldexp_f32 v40, v40, v41
	v_cndmask_b32_e32 v40, 0, v40, vcc
	v_cmp_ngt_f32_e32 vcc, s46, v36
	s_nop 1
	v_cndmask_b32_e32 v36, v219, v40, vcc
	v_mul_f32_e32 v40, 0xbfb8aa3b, v37
	v_rndne_f32_e32 v41, v40
	v_sub_f32_e32 v43, v40, v41
	v_fma_f32 v40, v37, s44, -v40
	v_fmac_f32_e32 v40, 0xb2a5705f, v37
	v_add_f32_e32 v40, v43, v40
	v_exp_f32_e32 v40, v40
	v_cvt_i32_f32_e32 v41, v41
	v_cmp_nlt_f32_e32 vcc, s45, v37
	v_ldexp_f32 v40, v40, v41
	s_nop 0
	v_cndmask_b32_e32 v40, 0, v40, vcc
	v_cmp_ngt_f32_e32 vcc, s46, v37
	s_nop 1
	v_cndmask_b32_e32 v37, v219, v40, vcc
	v_mul_f32_e32 v40, 0xbfb8aa3b, v38
	v_rndne_f32_e32 v41, v40
	v_sub_f32_e32 v43, v40, v41
	v_fma_f32 v40, v38, s44, -v40
	v_fmac_f32_e32 v40, 0xb2a5705f, v38
	v_add_f32_e32 v40, v43, v40
	v_exp_f32_e32 v40, v40
	v_cvt_i32_f32_e32 v41, v41
	v_cmp_nlt_f32_e32 vcc, s45, v38
	v_pk_add_f32 v[36:37], v[36:37], 1.0 op_sel_hi:[1,0]
	v_ldexp_f32 v40, v40, v41
	v_cndmask_b32_e32 v40, 0, v40, vcc
	v_cmp_ngt_f32_e32 vcc, s46, v38
	s_nop 1
	v_cndmask_b32_e32 v38, v219, v40, vcc
	v_mul_f32_e32 v40, 0xbfb8aa3b, v39
	v_rndne_f32_e32 v41, v40
	v_sub_f32_e32 v43, v40, v41
	v_fma_f32 v40, v39, s44, -v40
	v_fmac_f32_e32 v40, 0xb2a5705f, v39
	v_add_f32_e32 v40, v43, v40
	v_exp_f32_e32 v40, v40
	v_cvt_i32_f32_e32 v41, v41
	v_cmp_nlt_f32_e32 vcc, s45, v39
	v_ldexp_f32 v40, v40, v41
	s_nop 0
	v_cndmask_b32_e32 v40, 0, v40, vcc
	v_cmp_ngt_f32_e32 vcc, s46, v39
	s_nop 1
	v_cndmask_b32_e32 v39, v219, v40, vcc
	v_pk_add_f32 v[38:39], v[38:39], 1.0 op_sel_hi:[1,0]
	s_nop 0
	v_div_scale_f32 v40, s[12:13], v39, v39, 1.0
	v_rcp_f32_e32 v41, v40
	s_nop 0
	v_fma_f32 v43, -v40, v41, 1.0
	v_fmac_f32_e32 v41, v43, v41
	v_div_scale_f32 v43, vcc, 1.0, v39, 1.0
	v_mul_f32_e32 v44, v43, v41
	v_fma_f32 v45, -v40, v44, v43
	v_fmac_f32_e32 v44, v45, v41
	v_fma_f32 v40, -v40, v44, v43
	v_div_fmas_f32 v40, v40, v41, v44
	v_div_fixup_f32 v41, v40, v39, 1.0
	v_div_scale_f32 v39, s[12:13], v38, v38, 1.0
	v_rcp_f32_e32 v40, v39
	s_nop 0
	v_fma_f32 v43, -v39, v40, 1.0
	v_fmac_f32_e32 v40, v43, v40
	v_div_scale_f32 v43, vcc, 1.0, v38, 1.0
	v_mul_f32_e32 v44, v43, v40
	v_fma_f32 v45, -v39, v44, v43
	v_fmac_f32_e32 v44, v45, v40
	v_fma_f32 v39, -v39, v44, v43
	v_div_fmas_f32 v39, v39, v40, v44
	v_div_fixup_f32 v40, v39, v38, 1.0
	v_div_scale_f32 v38, s[12:13], v37, v37, 1.0
	v_rcp_f32_e32 v39, v38
	s_nop 0
	v_fma_f32 v43, -v38, v39, 1.0
	v_fmac_f32_e32 v39, v43, v39
	v_div_scale_f32 v43, vcc, 1.0, v37, 1.0
	v_mul_f32_e32 v44, v43, v39
	v_fma_f32 v45, -v38, v44, v43
	v_fmac_f32_e32 v44, v45, v39
	v_fma_f32 v38, -v38, v44, v43
	v_div_fmas_f32 v38, v38, v39, v44
	v_div_fixup_f32 v39, v38, v37, 1.0
	v_div_scale_f32 v37, s[12:13], v36, v36, 1.0
	v_rcp_f32_e32 v38, v37
	s_nop 0
	v_fma_f32 v43, -v37, v38, 1.0
	v_fmac_f32_e32 v38, v43, v38
	v_div_scale_f32 v43, vcc, 1.0, v36, 1.0
	v_mul_f32_e32 v44, v43, v38
	v_fma_f32 v45, -v37, v44, v43
	v_fmac_f32_e32 v44, v45, v38
	v_fma_f32 v37, -v37, v44, v43
	v_div_fmas_f32 v37, v37, v38, v44
	v_div_fixup_f32 v38, v37, v36, 1.0
	v_mad_i64_i32 v[36:37], s[12:13], v42, s5, v[190:191]
	global_store_dwordx4 v[36:37], v[38:41], off sc1
	v_cmp_nlt_f32_e32 vcc, s45, v32
	s_nop 0
	v_mul_f32_e32 v38, 0xbfb8aa3b, v32
	v_rndne_f32_e32 v39, v38
	v_sub_f32_e32 v40, v38, v39
	v_fma_f32 v38, v32, s44, -v38
	v_fmac_f32_e32 v38, 0xb2a5705f, v32
	v_add_f32_e32 v38, v40, v38
	v_exp_f32_e32 v38, v38
	v_cvt_i32_f32_e32 v39, v39
	v_ldexp_f32 v38, v38, v39
	v_cndmask_b32_e32 v38, 0, v38, vcc
	v_cmp_ngt_f32_e32 vcc, s46, v32
	s_nop 1
	v_cndmask_b32_e32 v32, v219, v38, vcc
	v_mul_f32_e32 v38, 0xbfb8aa3b, v33
	v_rndne_f32_e32 v39, v38
	v_sub_f32_e32 v40, v38, v39
	v_fma_f32 v38, v33, s44, -v38
	v_fmac_f32_e32 v38, 0xb2a5705f, v33
	v_add_f32_e32 v38, v40, v38
	v_exp_f32_e32 v38, v38
	v_cvt_i32_f32_e32 v39, v39
	v_cmp_nlt_f32_e32 vcc, s45, v33
	v_ldexp_f32 v38, v38, v39
	s_nop 0
	v_cndmask_b32_e32 v38, 0, v38, vcc
	v_cmp_ngt_f32_e32 vcc, s46, v33
	s_nop 1
	v_cndmask_b32_e32 v33, v219, v38, vcc
	v_mul_f32_e32 v38, 0xbfb8aa3b, v34
	v_rndne_f32_e32 v39, v38
	v_sub_f32_e32 v40, v38, v39
	v_fma_f32 v38, v34, s44, -v38
	v_fmac_f32_e32 v38, 0xb2a5705f, v34
	v_add_f32_e32 v38, v40, v38
	v_exp_f32_e32 v38, v38
	v_cvt_i32_f32_e32 v39, v39
	v_cmp_nlt_f32_e32 vcc, s45, v34
	v_pk_add_f32 v[32:33], v[32:33], 1.0 op_sel_hi:[1,0]
	v_ldexp_f32 v38, v38, v39
	v_cndmask_b32_e32 v38, 0, v38, vcc
	v_cmp_ngt_f32_e32 vcc, s46, v34
	s_nop 1
	v_cndmask_b32_e32 v34, v219, v38, vcc
	v_mul_f32_e32 v38, 0xbfb8aa3b, v35
	v_rndne_f32_e32 v39, v38
	v_sub_f32_e32 v40, v38, v39
	v_fma_f32 v38, v35, s44, -v38
	v_fmac_f32_e32 v38, 0xb2a5705f, v35
	v_add_f32_e32 v38, v40, v38
	v_exp_f32_e32 v38, v38
	v_cvt_i32_f32_e32 v39, v39
	v_cmp_nlt_f32_e32 vcc, s45, v35
	v_ldexp_f32 v38, v38, v39
	s_nop 0
	v_cndmask_b32_e32 v38, 0, v38, vcc
	v_cmp_ngt_f32_e32 vcc, s46, v35
	s_nop 1
	v_cndmask_b32_e32 v35, v219, v38, vcc
	v_pk_add_f32 v[34:35], v[34:35], 1.0 op_sel_hi:[1,0]
	s_nop 0
	v_div_scale_f32 v38, s[12:13], v35, v35, 1.0
	v_rcp_f32_e32 v39, v38
	s_nop 0
	v_fma_f32 v40, -v38, v39, 1.0
	v_fmac_f32_e32 v39, v40, v39
	v_div_scale_f32 v40, vcc, 1.0, v35, 1.0
	v_mul_f32_e32 v41, v40, v39
	v_fma_f32 v42, -v38, v41, v40
	v_fmac_f32_e32 v41, v42, v39
	v_fma_f32 v38, -v38, v41, v40
	v_div_fmas_f32 v38, v38, v39, v41
	v_div_fixup_f32 v35, v38, v35, 1.0
	v_div_scale_f32 v38, s[12:13], v34, v34, 1.0
	v_rcp_f32_e32 v39, v38
	s_nop 0
	v_fma_f32 v40, -v38, v39, 1.0
	v_fmac_f32_e32 v39, v40, v39
	v_div_scale_f32 v40, vcc, 1.0, v34, 1.0
	v_mul_f32_e32 v41, v40, v39
	v_fma_f32 v42, -v38, v41, v40
	v_fmac_f32_e32 v41, v42, v39
	v_fma_f32 v38, -v38, v41, v40
	v_div_fmas_f32 v38, v38, v39, v41
	v_div_fixup_f32 v34, v38, v34, 1.0
	v_div_scale_f32 v38, s[12:13], v33, v33, 1.0
	v_rcp_f32_e32 v39, v38
	s_nop 0
	v_fma_f32 v40, -v38, v39, 1.0
	v_fmac_f32_e32 v39, v40, v39
	v_div_scale_f32 v40, vcc, 1.0, v33, 1.0
	v_mul_f32_e32 v41, v40, v39
	v_fma_f32 v42, -v38, v41, v40
	v_fmac_f32_e32 v41, v42, v39
	v_fma_f32 v38, -v38, v41, v40
	v_div_fmas_f32 v38, v38, v39, v41
	v_div_fixup_f32 v33, v38, v33, 1.0
	v_div_scale_f32 v38, s[12:13], v32, v32, 1.0
	v_rcp_f32_e32 v39, v38
	s_nop 0
	v_fma_f32 v40, -v38, v39, 1.0
	v_fmac_f32_e32 v39, v40, v39
	v_div_scale_f32 v40, vcc, 1.0, v32, 1.0
	v_mul_f32_e32 v41, v40, v39
	v_fma_f32 v42, -v38, v41, v40
	v_fmac_f32_e32 v41, v42, v39
	v_fma_f32 v38, -v38, v41, v40
	v_div_fmas_f32 v38, v38, v39, v41
	v_div_fixup_f32 v32, v38, v32, 1.0
	global_store_dwordx4 v[36:37], v[32:35], off offset:16 sc1
	v_cmp_nlt_f32_e32 vcc, s45, v28
	s_nop 0
	v_mul_f32_e32 v32, 0xbfb8aa3b, v28
	v_rndne_f32_e32 v33, v32
	v_sub_f32_e32 v35, v32, v33
	v_fma_f32 v32, v28, s44, -v32
	v_fmac_f32_e32 v32, 0xb2a5705f, v28
	v_add_f32_e32 v32, v35, v32
	v_exp_f32_e32 v32, v32
	v_cvt_i32_f32_e32 v33, v33
	v_add_u32_e32 v34, 0x80, v200
	v_ldexp_f32 v32, v32, v33
	v_cndmask_b32_e32 v32, 0, v32, vcc
	v_cmp_ngt_f32_e32 vcc, s46, v28
	s_nop 1
	v_cndmask_b32_e32 v28, v219, v32, vcc
	v_mul_f32_e32 v32, 0xbfb8aa3b, v29
	v_rndne_f32_e32 v33, v32
	v_sub_f32_e32 v35, v32, v33
	v_fma_f32 v32, v29, s44, -v32
	v_fmac_f32_e32 v32, 0xb2a5705f, v29
	v_add_f32_e32 v32, v35, v32
	v_exp_f32_e32 v32, v32
	v_cvt_i32_f32_e32 v33, v33
	v_cmp_nlt_f32_e32 vcc, s45, v29
	v_ldexp_f32 v32, v32, v33
	s_nop 0
	v_cndmask_b32_e32 v32, 0, v32, vcc
	v_cmp_ngt_f32_e32 vcc, s46, v29
	s_nop 1
	v_cndmask_b32_e32 v29, v219, v32, vcc
	v_mul_f32_e32 v32, 0xbfb8aa3b, v30
	v_rndne_f32_e32 v33, v32
	v_sub_f32_e32 v35, v32, v33
	v_fma_f32 v32, v30, s44, -v32
	v_fmac_f32_e32 v32, 0xb2a5705f, v30
	v_add_f32_e32 v32, v35, v32
	v_exp_f32_e32 v32, v32
	v_cvt_i32_f32_e32 v33, v33
	v_cmp_nlt_f32_e32 vcc, s45, v30
	v_pk_add_f32 v[28:29], v[28:29], 1.0 op_sel_hi:[1,0]
	v_ldexp_f32 v32, v32, v33
	v_cndmask_b32_e32 v32, 0, v32, vcc
	v_cmp_ngt_f32_e32 vcc, s46, v30
	s_nop 1
	v_cndmask_b32_e32 v30, v219, v32, vcc
	v_mul_f32_e32 v32, 0xbfb8aa3b, v31
	v_rndne_f32_e32 v33, v32
	v_sub_f32_e32 v35, v32, v33
	v_fma_f32 v32, v31, s44, -v32
	v_fmac_f32_e32 v32, 0xb2a5705f, v31
	v_add_f32_e32 v32, v35, v32
	v_exp_f32_e32 v32, v32
	v_cvt_i32_f32_e32 v33, v33
	v_cmp_nlt_f32_e32 vcc, s45, v31
	v_ldexp_f32 v32, v32, v33
	s_nop 0
	v_cndmask_b32_e32 v32, 0, v32, vcc
	v_cmp_ngt_f32_e32 vcc, s46, v31
	s_nop 1
	v_cndmask_b32_e32 v31, v219, v32, vcc
	v_pk_add_f32 v[30:31], v[30:31], 1.0 op_sel_hi:[1,0]
	s_nop 0
	v_div_scale_f32 v32, s[12:13], v31, v31, 1.0
	v_rcp_f32_e32 v33, v32
	s_nop 0
	v_fma_f32 v35, -v32, v33, 1.0
	v_fmac_f32_e32 v33, v35, v33
	v_div_scale_f32 v35, vcc, 1.0, v31, 1.0
	v_mul_f32_e32 v36, v35, v33
	v_fma_f32 v37, -v32, v36, v35
	v_fmac_f32_e32 v36, v37, v33
	v_fma_f32 v32, -v32, v36, v35
	v_div_fmas_f32 v32, v32, v33, v36
	v_div_fixup_f32 v33, v32, v31, 1.0
	v_div_scale_f32 v31, s[12:13], v30, v30, 1.0
	v_rcp_f32_e32 v32, v31
	s_nop 0
	v_fma_f32 v35, -v31, v32, 1.0
	v_fmac_f32_e32 v32, v35, v32
	v_div_scale_f32 v35, vcc, 1.0, v30, 1.0
	v_mul_f32_e32 v36, v35, v32
	v_fma_f32 v37, -v31, v36, v35
	v_fmac_f32_e32 v36, v37, v32
	v_fma_f32 v31, -v31, v36, v35
	v_div_fmas_f32 v31, v31, v32, v36
	v_div_fixup_f32 v32, v31, v30, 1.0
	v_div_scale_f32 v30, s[12:13], v29, v29, 1.0
	v_rcp_f32_e32 v31, v30
	s_nop 0
	v_fma_f32 v35, -v30, v31, 1.0
	v_fmac_f32_e32 v31, v35, v31
	v_div_scale_f32 v35, vcc, 1.0, v29, 1.0
	v_mul_f32_e32 v36, v35, v31
	v_fma_f32 v37, -v30, v36, v35
	v_fmac_f32_e32 v36, v37, v31
	v_fma_f32 v30, -v30, v36, v35
	v_div_fmas_f32 v30, v30, v31, v36
	v_div_fixup_f32 v31, v30, v29, 1.0
	v_div_scale_f32 v29, s[12:13], v28, v28, 1.0
	v_rcp_f32_e32 v30, v29
	s_nop 0
	v_fma_f32 v35, -v29, v30, 1.0
	v_fmac_f32_e32 v30, v35, v30
	v_div_scale_f32 v35, vcc, 1.0, v28, 1.0
	v_mul_f32_e32 v36, v35, v30
	v_fma_f32 v37, -v29, v36, v35
	v_fmac_f32_e32 v36, v37, v30
	v_fma_f32 v29, -v29, v36, v35
	v_div_fmas_f32 v29, v29, v30, v36
	v_div_fixup_f32 v30, v29, v28, 1.0
	v_mad_i64_i32 v[28:29], s[12:13], v34, s5, v[190:191]
	global_store_dwordx4 v[28:29], v[30:33], off sc1
	v_cmp_nlt_f32_e32 vcc, s45, v24
	s_nop 0
	v_mul_f32_e32 v30, 0xbfb8aa3b, v24
	v_rndne_f32_e32 v31, v30
	v_sub_f32_e32 v32, v30, v31
	v_fma_f32 v30, v24, s44, -v30
	v_fmac_f32_e32 v30, 0xb2a5705f, v24
	v_add_f32_e32 v30, v32, v30
	v_exp_f32_e32 v30, v30
	v_cvt_i32_f32_e32 v31, v31
	v_ldexp_f32 v30, v30, v31
	v_cndmask_b32_e32 v30, 0, v30, vcc
	v_cmp_ngt_f32_e32 vcc, s46, v24
	s_nop 1
	v_cndmask_b32_e32 v24, v219, v30, vcc
	v_mul_f32_e32 v30, 0xbfb8aa3b, v25
	v_rndne_f32_e32 v31, v30
	v_sub_f32_e32 v32, v30, v31
	v_fma_f32 v30, v25, s44, -v30
	v_fmac_f32_e32 v30, 0xb2a5705f, v25
	v_add_f32_e32 v30, v32, v30
	v_exp_f32_e32 v30, v30
	v_cvt_i32_f32_e32 v31, v31
	v_cmp_nlt_f32_e32 vcc, s45, v25
	v_ldexp_f32 v30, v30, v31
	s_nop 0
	v_cndmask_b32_e32 v30, 0, v30, vcc
	v_cmp_ngt_f32_e32 vcc, s46, v25
	s_nop 1
	v_cndmask_b32_e32 v25, v219, v30, vcc
	v_mul_f32_e32 v30, 0xbfb8aa3b, v26
	v_rndne_f32_e32 v31, v30
	v_sub_f32_e32 v32, v30, v31
	v_fma_f32 v30, v26, s44, -v30
	v_fmac_f32_e32 v30, 0xb2a5705f, v26
	v_add_f32_e32 v30, v32, v30
	v_exp_f32_e32 v30, v30
	v_cvt_i32_f32_e32 v31, v31
	v_cmp_nlt_f32_e32 vcc, s45, v26
	v_pk_add_f32 v[24:25], v[24:25], 1.0 op_sel_hi:[1,0]
	v_ldexp_f32 v30, v30, v31
	v_cndmask_b32_e32 v30, 0, v30, vcc
	v_cmp_ngt_f32_e32 vcc, s46, v26
	s_nop 1
	v_cndmask_b32_e32 v26, v219, v30, vcc
	v_mul_f32_e32 v30, 0xbfb8aa3b, v27
	v_rndne_f32_e32 v31, v30
	v_sub_f32_e32 v32, v30, v31
	v_fma_f32 v30, v27, s44, -v30
	v_fmac_f32_e32 v30, 0xb2a5705f, v27
	v_add_f32_e32 v30, v32, v30
	v_exp_f32_e32 v30, v30
	v_cvt_i32_f32_e32 v31, v31
	v_cmp_nlt_f32_e32 vcc, s45, v27
	v_ldexp_f32 v30, v30, v31
	s_nop 0
	v_cndmask_b32_e32 v30, 0, v30, vcc
	v_cmp_ngt_f32_e32 vcc, s46, v27
	s_nop 1
	v_cndmask_b32_e32 v27, v219, v30, vcc
	v_pk_add_f32 v[26:27], v[26:27], 1.0 op_sel_hi:[1,0]
	s_nop 0
	v_div_scale_f32 v30, s[12:13], v27, v27, 1.0
	v_rcp_f32_e32 v31, v30
	s_nop 0
	v_fma_f32 v32, -v30, v31, 1.0
	v_fmac_f32_e32 v31, v32, v31
	v_div_scale_f32 v32, vcc, 1.0, v27, 1.0
	v_mul_f32_e32 v33, v32, v31
	v_fma_f32 v34, -v30, v33, v32
	v_fmac_f32_e32 v33, v34, v31
	v_fma_f32 v30, -v30, v33, v32
	v_div_fmas_f32 v30, v30, v31, v33
	v_div_fixup_f32 v27, v30, v27, 1.0
	v_div_scale_f32 v30, s[12:13], v26, v26, 1.0
	v_rcp_f32_e32 v31, v30
	s_nop 0
	v_fma_f32 v32, -v30, v31, 1.0
	v_fmac_f32_e32 v31, v32, v31
	v_div_scale_f32 v32, vcc, 1.0, v26, 1.0
	v_mul_f32_e32 v33, v32, v31
	v_fma_f32 v34, -v30, v33, v32
	v_fmac_f32_e32 v33, v34, v31
	v_fma_f32 v30, -v30, v33, v32
	v_div_fmas_f32 v30, v30, v31, v33
	v_div_fixup_f32 v26, v30, v26, 1.0
	v_div_scale_f32 v30, s[12:13], v25, v25, 1.0
	v_rcp_f32_e32 v31, v30
	s_nop 0
	v_fma_f32 v32, -v30, v31, 1.0
	v_fmac_f32_e32 v31, v32, v31
	v_div_scale_f32 v32, vcc, 1.0, v25, 1.0
	v_mul_f32_e32 v33, v32, v31
	v_fma_f32 v34, -v30, v33, v32
	v_fmac_f32_e32 v33, v34, v31
	v_fma_f32 v30, -v30, v33, v32
	v_div_fmas_f32 v30, v30, v31, v33
	v_div_fixup_f32 v25, v30, v25, 1.0
	v_div_scale_f32 v30, s[12:13], v24, v24, 1.0
	v_rcp_f32_e32 v31, v30
	s_nop 0
	v_fma_f32 v32, -v30, v31, 1.0
	v_fmac_f32_e32 v31, v32, v31
	v_div_scale_f32 v32, vcc, 1.0, v24, 1.0
	v_mul_f32_e32 v33, v32, v31
	v_fma_f32 v34, -v30, v33, v32
	v_fmac_f32_e32 v33, v34, v31
	v_fma_f32 v30, -v30, v33, v32
	v_div_fmas_f32 v30, v30, v31, v33
	v_div_fixup_f32 v24, v30, v24, 1.0
	global_store_dwordx4 v[28:29], v[24:27], off offset:16 sc1
	v_cmp_nlt_f32_e32 vcc, s45, v20
	s_nop 0
	v_mul_f32_e32 v24, 0xbfb8aa3b, v20
	v_rndne_f32_e32 v25, v24
	v_sub_f32_e32 v27, v24, v25
	v_fma_f32 v24, v20, s44, -v24
	v_fmac_f32_e32 v24, 0xb2a5705f, v20
	v_add_f32_e32 v24, v27, v24
	v_exp_f32_e32 v24, v24
	v_cvt_i32_f32_e32 v25, v25
	v_add_u32_e32 v26, 0x90, v200
	v_ldexp_f32 v24, v24, v25
	v_cndmask_b32_e32 v24, 0, v24, vcc
	v_cmp_ngt_f32_e32 vcc, s46, v20
	s_nop 1
	v_cndmask_b32_e32 v20, v219, v24, vcc
	v_mul_f32_e32 v24, 0xbfb8aa3b, v21
	v_rndne_f32_e32 v25, v24
	v_sub_f32_e32 v27, v24, v25
	v_fma_f32 v24, v21, s44, -v24
	v_fmac_f32_e32 v24, 0xb2a5705f, v21
	v_add_f32_e32 v24, v27, v24
	v_exp_f32_e32 v24, v24
	v_cvt_i32_f32_e32 v25, v25
	v_cmp_nlt_f32_e32 vcc, s45, v21
	v_ldexp_f32 v24, v24, v25
	s_nop 0
	v_cndmask_b32_e32 v24, 0, v24, vcc
	v_cmp_ngt_f32_e32 vcc, s46, v21
	s_nop 1
	v_cndmask_b32_e32 v21, v219, v24, vcc
	v_mul_f32_e32 v24, 0xbfb8aa3b, v22
	v_rndne_f32_e32 v25, v24
	v_sub_f32_e32 v27, v24, v25
	v_fma_f32 v24, v22, s44, -v24
	v_fmac_f32_e32 v24, 0xb2a5705f, v22
	v_add_f32_e32 v24, v27, v24
	v_exp_f32_e32 v24, v24
	v_cvt_i32_f32_e32 v25, v25
	v_cmp_nlt_f32_e32 vcc, s45, v22
	v_pk_add_f32 v[20:21], v[20:21], 1.0 op_sel_hi:[1,0]
	v_ldexp_f32 v24, v24, v25
	v_cndmask_b32_e32 v24, 0, v24, vcc
	v_cmp_ngt_f32_e32 vcc, s46, v22
	s_nop 1
	v_cndmask_b32_e32 v22, v219, v24, vcc
	v_mul_f32_e32 v24, 0xbfb8aa3b, v23
	v_rndne_f32_e32 v25, v24
	v_sub_f32_e32 v27, v24, v25
	v_fma_f32 v24, v23, s44, -v24
	v_fmac_f32_e32 v24, 0xb2a5705f, v23
	v_add_f32_e32 v24, v27, v24
	v_exp_f32_e32 v24, v24
	v_cvt_i32_f32_e32 v25, v25
	v_cmp_nlt_f32_e32 vcc, s45, v23
	v_ldexp_f32 v24, v24, v25
	s_nop 0
	v_cndmask_b32_e32 v24, 0, v24, vcc
	v_cmp_ngt_f32_e32 vcc, s46, v23
	s_nop 1
	v_cndmask_b32_e32 v23, v219, v24, vcc
	v_pk_add_f32 v[22:23], v[22:23], 1.0 op_sel_hi:[1,0]
	s_nop 0
	v_div_scale_f32 v24, s[12:13], v23, v23, 1.0
	v_rcp_f32_e32 v25, v24
	s_nop 0
	v_fma_f32 v27, -v24, v25, 1.0
	v_fmac_f32_e32 v25, v27, v25
	v_div_scale_f32 v27, vcc, 1.0, v23, 1.0
	v_mul_f32_e32 v28, v27, v25
	v_fma_f32 v29, -v24, v28, v27
	v_fmac_f32_e32 v28, v29, v25
	v_fma_f32 v24, -v24, v28, v27
	v_div_fmas_f32 v24, v24, v25, v28
	v_div_fixup_f32 v25, v24, v23, 1.0
	v_div_scale_f32 v23, s[12:13], v22, v22, 1.0
	v_rcp_f32_e32 v24, v23
	s_nop 0
	v_fma_f32 v27, -v23, v24, 1.0
	v_fmac_f32_e32 v24, v27, v24
	v_div_scale_f32 v27, vcc, 1.0, v22, 1.0
	v_mul_f32_e32 v28, v27, v24
	v_fma_f32 v29, -v23, v28, v27
	v_fmac_f32_e32 v28, v29, v24
	v_fma_f32 v23, -v23, v28, v27
	v_div_fmas_f32 v23, v23, v24, v28
	v_div_fixup_f32 v24, v23, v22, 1.0
	v_div_scale_f32 v22, s[12:13], v21, v21, 1.0
	v_rcp_f32_e32 v23, v22
	s_nop 0
	v_fma_f32 v27, -v22, v23, 1.0
	v_fmac_f32_e32 v23, v27, v23
	v_div_scale_f32 v27, vcc, 1.0, v21, 1.0
	v_mul_f32_e32 v28, v27, v23
	v_fma_f32 v29, -v22, v28, v27
	v_fmac_f32_e32 v28, v29, v23
	v_fma_f32 v22, -v22, v28, v27
	v_div_fmas_f32 v22, v22, v23, v28
	v_div_fixup_f32 v23, v22, v21, 1.0
	v_div_scale_f32 v21, s[12:13], v20, v20, 1.0
	v_rcp_f32_e32 v22, v21
	s_nop 0
	v_fma_f32 v27, -v21, v22, 1.0
	v_fmac_f32_e32 v22, v27, v22
	v_div_scale_f32 v27, vcc, 1.0, v20, 1.0
	v_mul_f32_e32 v28, v27, v22
	v_fma_f32 v29, -v21, v28, v27
	v_fmac_f32_e32 v28, v29, v22
	v_fma_f32 v21, -v21, v28, v27
	v_div_fmas_f32 v21, v21, v22, v28
	v_div_fixup_f32 v22, v21, v20, 1.0
	v_mad_i64_i32 v[20:21], s[12:13], v26, s5, v[190:191]
	global_store_dwordx4 v[20:21], v[22:25], off sc1
	v_cmp_nlt_f32_e32 vcc, s45, v16
	s_nop 0
	v_mul_f32_e32 v22, 0xbfb8aa3b, v16
	v_rndne_f32_e32 v23, v22
	v_sub_f32_e32 v24, v22, v23
	v_fma_f32 v22, v16, s44, -v22
	v_fmac_f32_e32 v22, 0xb2a5705f, v16
	v_add_f32_e32 v22, v24, v22
	v_exp_f32_e32 v22, v22
	v_cvt_i32_f32_e32 v23, v23
	v_ldexp_f32 v22, v22, v23
	v_cndmask_b32_e32 v22, 0, v22, vcc
	v_cmp_ngt_f32_e32 vcc, s46, v16
	s_nop 1
	v_cndmask_b32_e32 v16, v219, v22, vcc
	v_mul_f32_e32 v22, 0xbfb8aa3b, v17
	v_rndne_f32_e32 v23, v22
	v_sub_f32_e32 v24, v22, v23
	v_fma_f32 v22, v17, s44, -v22
	v_fmac_f32_e32 v22, 0xb2a5705f, v17
	v_add_f32_e32 v22, v24, v22
	v_exp_f32_e32 v22, v22
	v_cvt_i32_f32_e32 v23, v23
	v_cmp_nlt_f32_e32 vcc, s45, v17
	v_ldexp_f32 v22, v22, v23
	s_nop 0
	v_cndmask_b32_e32 v22, 0, v22, vcc
	v_cmp_ngt_f32_e32 vcc, s46, v17
	s_nop 1
	v_cndmask_b32_e32 v17, v219, v22, vcc
	v_mul_f32_e32 v22, 0xbfb8aa3b, v18
	v_rndne_f32_e32 v23, v22
	v_sub_f32_e32 v24, v22, v23
	v_fma_f32 v22, v18, s44, -v22
	v_fmac_f32_e32 v22, 0xb2a5705f, v18
	v_add_f32_e32 v22, v24, v22
	v_exp_f32_e32 v22, v22
	v_cvt_i32_f32_e32 v23, v23
	v_cmp_nlt_f32_e32 vcc, s45, v18
	v_pk_add_f32 v[16:17], v[16:17], 1.0 op_sel_hi:[1,0]
	v_ldexp_f32 v22, v22, v23
	v_cndmask_b32_e32 v22, 0, v22, vcc
	v_cmp_ngt_f32_e32 vcc, s46, v18
	s_nop 1
	v_cndmask_b32_e32 v18, v219, v22, vcc
	v_mul_f32_e32 v22, 0xbfb8aa3b, v19
	v_rndne_f32_e32 v23, v22
	v_sub_f32_e32 v24, v22, v23
	v_fma_f32 v22, v19, s44, -v22
	v_fmac_f32_e32 v22, 0xb2a5705f, v19
	v_add_f32_e32 v22, v24, v22
	v_exp_f32_e32 v22, v22
	v_cvt_i32_f32_e32 v23, v23
	v_cmp_nlt_f32_e32 vcc, s45, v19
	v_ldexp_f32 v22, v22, v23
	s_nop 0
	v_cndmask_b32_e32 v22, 0, v22, vcc
	v_cmp_ngt_f32_e32 vcc, s46, v19
	s_nop 1
	v_cndmask_b32_e32 v19, v219, v22, vcc
	v_pk_add_f32 v[18:19], v[18:19], 1.0 op_sel_hi:[1,0]
	s_nop 0
	v_div_scale_f32 v22, s[12:13], v19, v19, 1.0
	v_rcp_f32_e32 v23, v22
	s_nop 0
	v_fma_f32 v24, -v22, v23, 1.0
	v_fmac_f32_e32 v23, v24, v23
	v_div_scale_f32 v24, vcc, 1.0, v19, 1.0
	v_mul_f32_e32 v25, v24, v23
	v_fma_f32 v26, -v22, v25, v24
	v_fmac_f32_e32 v25, v26, v23
	v_fma_f32 v22, -v22, v25, v24
	v_div_fmas_f32 v22, v22, v23, v25
	v_div_fixup_f32 v19, v22, v19, 1.0
	v_div_scale_f32 v22, s[12:13], v18, v18, 1.0
	v_rcp_f32_e32 v23, v22
	s_nop 0
	v_fma_f32 v24, -v22, v23, 1.0
	v_fmac_f32_e32 v23, v24, v23
	v_div_scale_f32 v24, vcc, 1.0, v18, 1.0
	v_mul_f32_e32 v25, v24, v23
	v_fma_f32 v26, -v22, v25, v24
	v_fmac_f32_e32 v25, v26, v23
	v_fma_f32 v22, -v22, v25, v24
	v_div_fmas_f32 v22, v22, v23, v25
	v_div_fixup_f32 v18, v22, v18, 1.0
	v_div_scale_f32 v22, s[12:13], v17, v17, 1.0
	v_rcp_f32_e32 v23, v22
	s_nop 0
	v_fma_f32 v24, -v22, v23, 1.0
	v_fmac_f32_e32 v23, v24, v23
	v_div_scale_f32 v24, vcc, 1.0, v17, 1.0
	v_mul_f32_e32 v25, v24, v23
	v_fma_f32 v26, -v22, v25, v24
	v_fmac_f32_e32 v25, v26, v23
	v_fma_f32 v22, -v22, v25, v24
	v_div_fmas_f32 v22, v22, v23, v25
	v_div_fixup_f32 v17, v22, v17, 1.0
	v_div_scale_f32 v22, s[12:13], v16, v16, 1.0
	v_rcp_f32_e32 v23, v22
	s_nop 0
	v_fma_f32 v24, -v22, v23, 1.0
	v_fmac_f32_e32 v23, v24, v23
	v_div_scale_f32 v24, vcc, 1.0, v16, 1.0
	v_mul_f32_e32 v25, v24, v23
	v_fma_f32 v26, -v22, v25, v24
	v_fmac_f32_e32 v25, v26, v23
	v_fma_f32 v22, -v22, v25, v24
	v_div_fmas_f32 v22, v22, v23, v25
	v_div_fixup_f32 v16, v22, v16, 1.0
	global_store_dwordx4 v[20:21], v[16:19], off offset:16 sc1
	v_cmp_nlt_f32_e32 vcc, s45, v12
	s_nop 0
	v_mul_f32_e32 v16, 0xbfb8aa3b, v12
	v_rndne_f32_e32 v17, v16
	v_sub_f32_e32 v19, v16, v17
	v_fma_f32 v16, v12, s44, -v16
	v_fmac_f32_e32 v16, 0xb2a5705f, v12
	v_add_f32_e32 v16, v19, v16
	v_exp_f32_e32 v16, v16
	v_cvt_i32_f32_e32 v17, v17
	v_add_u32_e32 v18, 0xa0, v200
	v_ldexp_f32 v16, v16, v17
	v_cndmask_b32_e32 v16, 0, v16, vcc
	v_cmp_ngt_f32_e32 vcc, s46, v12
	s_nop 1
	v_cndmask_b32_e32 v12, v219, v16, vcc
	v_mul_f32_e32 v16, 0xbfb8aa3b, v13
	v_rndne_f32_e32 v17, v16
	v_sub_f32_e32 v19, v16, v17
	v_fma_f32 v16, v13, s44, -v16
	v_fmac_f32_e32 v16, 0xb2a5705f, v13
	v_add_f32_e32 v16, v19, v16
	v_exp_f32_e32 v16, v16
	v_cvt_i32_f32_e32 v17, v17
	v_cmp_nlt_f32_e32 vcc, s45, v13
	v_ldexp_f32 v16, v16, v17
	s_nop 0
	v_cndmask_b32_e32 v16, 0, v16, vcc
	v_cmp_ngt_f32_e32 vcc, s46, v13
	s_nop 1
	v_cndmask_b32_e32 v13, v219, v16, vcc
	v_mul_f32_e32 v16, 0xbfb8aa3b, v14
	v_rndne_f32_e32 v17, v16
	v_sub_f32_e32 v19, v16, v17
	v_fma_f32 v16, v14, s44, -v16
	v_fmac_f32_e32 v16, 0xb2a5705f, v14
	v_add_f32_e32 v16, v19, v16
	v_exp_f32_e32 v16, v16
	v_cvt_i32_f32_e32 v17, v17
	v_cmp_nlt_f32_e32 vcc, s45, v14
	v_pk_add_f32 v[12:13], v[12:13], 1.0 op_sel_hi:[1,0]
	v_ldexp_f32 v16, v16, v17
	v_cndmask_b32_e32 v16, 0, v16, vcc
	v_cmp_ngt_f32_e32 vcc, s46, v14
	s_nop 1
	v_cndmask_b32_e32 v14, v219, v16, vcc
	v_mul_f32_e32 v16, 0xbfb8aa3b, v15
	v_rndne_f32_e32 v17, v16
	v_sub_f32_e32 v19, v16, v17
	v_fma_f32 v16, v15, s44, -v16
	v_fmac_f32_e32 v16, 0xb2a5705f, v15
	v_add_f32_e32 v16, v19, v16
	v_exp_f32_e32 v16, v16
	v_cvt_i32_f32_e32 v17, v17
	v_cmp_nlt_f32_e32 vcc, s45, v15
	v_ldexp_f32 v16, v16, v17
	s_nop 0
	v_cndmask_b32_e32 v16, 0, v16, vcc
	v_cmp_ngt_f32_e32 vcc, s46, v15
	s_nop 1
	v_cndmask_b32_e32 v15, v219, v16, vcc
	v_pk_add_f32 v[14:15], v[14:15], 1.0 op_sel_hi:[1,0]
	s_nop 0
	v_div_scale_f32 v16, s[12:13], v15, v15, 1.0
	v_rcp_f32_e32 v17, v16
	s_nop 0
	v_fma_f32 v19, -v16, v17, 1.0
	v_fmac_f32_e32 v17, v19, v17
	v_div_scale_f32 v19, vcc, 1.0, v15, 1.0
	v_mul_f32_e32 v20, v19, v17
	v_fma_f32 v21, -v16, v20, v19
	v_fmac_f32_e32 v20, v21, v17
	v_fma_f32 v16, -v16, v20, v19
	v_div_fmas_f32 v16, v16, v17, v20
	v_div_fixup_f32 v17, v16, v15, 1.0
	v_div_scale_f32 v15, s[12:13], v14, v14, 1.0
	v_rcp_f32_e32 v16, v15
	s_nop 0
	v_fma_f32 v19, -v15, v16, 1.0
	v_fmac_f32_e32 v16, v19, v16
	v_div_scale_f32 v19, vcc, 1.0, v14, 1.0
	v_mul_f32_e32 v20, v19, v16
	v_fma_f32 v21, -v15, v20, v19
	v_fmac_f32_e32 v20, v21, v16
	v_fma_f32 v15, -v15, v20, v19
	v_div_fmas_f32 v15, v15, v16, v20
	v_div_fixup_f32 v16, v15, v14, 1.0
	v_div_scale_f32 v14, s[12:13], v13, v13, 1.0
	v_rcp_f32_e32 v15, v14
	s_nop 0
	v_fma_f32 v19, -v14, v15, 1.0
	v_fmac_f32_e32 v15, v19, v15
	v_div_scale_f32 v19, vcc, 1.0, v13, 1.0
	v_mul_f32_e32 v20, v19, v15
	v_fma_f32 v21, -v14, v20, v19
	v_fmac_f32_e32 v20, v21, v15
	v_fma_f32 v14, -v14, v20, v19
	v_div_fmas_f32 v14, v14, v15, v20
	v_div_fixup_f32 v15, v14, v13, 1.0
	v_div_scale_f32 v13, s[12:13], v12, v12, 1.0
	v_rcp_f32_e32 v14, v13
	s_nop 0
	v_fma_f32 v19, -v13, v14, 1.0
	v_fmac_f32_e32 v14, v19, v14
	v_div_scale_f32 v19, vcc, 1.0, v12, 1.0
	v_mul_f32_e32 v20, v19, v14
	v_fma_f32 v21, -v13, v20, v19
	v_fmac_f32_e32 v20, v21, v14
	v_fma_f32 v13, -v13, v20, v19
	v_div_fmas_f32 v13, v13, v14, v20
	v_div_fixup_f32 v14, v13, v12, 1.0
	v_mad_i64_i32 v[12:13], s[12:13], v18, s5, v[190:191]
	global_store_dwordx4 v[12:13], v[14:17], off sc1
	v_cmp_nlt_f32_e32 vcc, s45, v8
	s_nop 0
	v_mul_f32_e32 v14, 0xbfb8aa3b, v8
	v_rndne_f32_e32 v15, v14
	v_sub_f32_e32 v16, v14, v15
	v_fma_f32 v14, v8, s44, -v14
	v_fmac_f32_e32 v14, 0xb2a5705f, v8
	v_add_f32_e32 v14, v16, v14
	v_exp_f32_e32 v14, v14
	v_cvt_i32_f32_e32 v15, v15
	v_ldexp_f32 v14, v14, v15
	v_cndmask_b32_e32 v14, 0, v14, vcc
	v_cmp_ngt_f32_e32 vcc, s46, v8
	s_nop 1
	v_cndmask_b32_e32 v8, v219, v14, vcc
	v_mul_f32_e32 v14, 0xbfb8aa3b, v9
	v_rndne_f32_e32 v15, v14
	v_sub_f32_e32 v16, v14, v15
	v_fma_f32 v14, v9, s44, -v14
	v_fmac_f32_e32 v14, 0xb2a5705f, v9
	v_add_f32_e32 v14, v16, v14
	v_exp_f32_e32 v14, v14
	v_cvt_i32_f32_e32 v15, v15
	v_cmp_nlt_f32_e32 vcc, s45, v9
	v_ldexp_f32 v14, v14, v15
	s_nop 0
	v_cndmask_b32_e32 v14, 0, v14, vcc
	v_cmp_ngt_f32_e32 vcc, s46, v9
	s_nop 1
	v_cndmask_b32_e32 v9, v219, v14, vcc
	v_mul_f32_e32 v14, 0xbfb8aa3b, v10
	v_rndne_f32_e32 v15, v14
	v_sub_f32_e32 v16, v14, v15
	v_fma_f32 v14, v10, s44, -v14
	v_fmac_f32_e32 v14, 0xb2a5705f, v10
	v_add_f32_e32 v14, v16, v14
	v_exp_f32_e32 v14, v14
	v_cvt_i32_f32_e32 v15, v15
	v_cmp_nlt_f32_e32 vcc, s45, v10
	v_pk_add_f32 v[8:9], v[8:9], 1.0 op_sel_hi:[1,0]
	v_ldexp_f32 v14, v14, v15
	v_cndmask_b32_e32 v14, 0, v14, vcc
	v_cmp_ngt_f32_e32 vcc, s46, v10
	s_nop 1
	v_cndmask_b32_e32 v10, v219, v14, vcc
	v_mul_f32_e32 v14, 0xbfb8aa3b, v11
	v_rndne_f32_e32 v15, v14
	v_sub_f32_e32 v16, v14, v15
	v_fma_f32 v14, v11, s44, -v14
	v_fmac_f32_e32 v14, 0xb2a5705f, v11
	v_add_f32_e32 v14, v16, v14
	v_exp_f32_e32 v14, v14
	v_cvt_i32_f32_e32 v15, v15
	v_cmp_nlt_f32_e32 vcc, s45, v11
	v_ldexp_f32 v14, v14, v15
	s_nop 0
	v_cndmask_b32_e32 v14, 0, v14, vcc
	v_cmp_ngt_f32_e32 vcc, s46, v11
	s_nop 1
	v_cndmask_b32_e32 v11, v219, v14, vcc
	v_pk_add_f32 v[10:11], v[10:11], 1.0 op_sel_hi:[1,0]
	s_nop 0
	v_div_scale_f32 v14, s[12:13], v11, v11, 1.0
	v_rcp_f32_e32 v15, v14
	s_nop 0
	v_fma_f32 v16, -v14, v15, 1.0
	v_fmac_f32_e32 v15, v16, v15
	v_div_scale_f32 v16, vcc, 1.0, v11, 1.0
	v_mul_f32_e32 v17, v16, v15
	v_fma_f32 v18, -v14, v17, v16
	v_fmac_f32_e32 v17, v18, v15
	v_fma_f32 v14, -v14, v17, v16
	v_div_fmas_f32 v14, v14, v15, v17
	v_div_fixup_f32 v11, v14, v11, 1.0
	v_div_scale_f32 v14, s[12:13], v10, v10, 1.0
	v_rcp_f32_e32 v15, v14
	s_nop 0
	v_fma_f32 v16, -v14, v15, 1.0
	v_fmac_f32_e32 v15, v16, v15
	v_div_scale_f32 v16, vcc, 1.0, v10, 1.0
	v_mul_f32_e32 v17, v16, v15
	v_fma_f32 v18, -v14, v17, v16
	v_fmac_f32_e32 v17, v18, v15
	v_fma_f32 v14, -v14, v17, v16
	v_div_fmas_f32 v14, v14, v15, v17
	v_div_fixup_f32 v10, v14, v10, 1.0
	v_div_scale_f32 v14, s[12:13], v9, v9, 1.0
	v_rcp_f32_e32 v15, v14
	s_nop 0
	v_fma_f32 v16, -v14, v15, 1.0
	v_fmac_f32_e32 v15, v16, v15
	v_div_scale_f32 v16, vcc, 1.0, v9, 1.0
	v_mul_f32_e32 v17, v16, v15
	v_fma_f32 v18, -v14, v17, v16
	v_fmac_f32_e32 v17, v18, v15
	v_fma_f32 v14, -v14, v17, v16
	v_div_fmas_f32 v14, v14, v15, v17
	v_div_fixup_f32 v9, v14, v9, 1.0
	v_div_scale_f32 v14, s[12:13], v8, v8, 1.0
	v_rcp_f32_e32 v15, v14
	s_nop 0
	v_fma_f32 v16, -v14, v15, 1.0
	v_fmac_f32_e32 v15, v16, v15
	v_div_scale_f32 v16, vcc, 1.0, v8, 1.0
	v_mul_f32_e32 v17, v16, v15
	v_fma_f32 v18, -v14, v17, v16
	v_fmac_f32_e32 v17, v18, v15
	v_fma_f32 v14, -v14, v17, v16
	v_div_fmas_f32 v14, v14, v15, v17
	v_div_fixup_f32 v8, v14, v8, 1.0
	global_store_dwordx4 v[12:13], v[8:11], off offset:16 sc1
	v_cmp_nlt_f32_e32 vcc, s45, v4
	s_nop 0
	v_mul_f32_e32 v8, 0xbfb8aa3b, v4
	v_rndne_f32_e32 v9, v8
	v_sub_f32_e32 v11, v8, v9
	v_fma_f32 v8, v4, s44, -v8
	v_fmac_f32_e32 v8, 0xb2a5705f, v4
	v_add_f32_e32 v8, v11, v8
	v_exp_f32_e32 v8, v8
	v_cvt_i32_f32_e32 v9, v9
	v_add_u32_e32 v10, 0xb0, v200
	v_ldexp_f32 v8, v8, v9
	v_cndmask_b32_e32 v8, 0, v8, vcc
	v_cmp_ngt_f32_e32 vcc, s46, v4
	s_nop 1
	v_cndmask_b32_e32 v4, v219, v8, vcc
	v_mul_f32_e32 v8, 0xbfb8aa3b, v5
	v_rndne_f32_e32 v9, v8
	v_sub_f32_e32 v11, v8, v9
	v_fma_f32 v8, v5, s44, -v8
	v_fmac_f32_e32 v8, 0xb2a5705f, v5
	v_add_f32_e32 v8, v11, v8
	v_exp_f32_e32 v8, v8
	v_cvt_i32_f32_e32 v9, v9
	v_cmp_nlt_f32_e32 vcc, s45, v5
	v_ldexp_f32 v8, v8, v9
	s_nop 0
	v_cndmask_b32_e32 v8, 0, v8, vcc
	v_cmp_ngt_f32_e32 vcc, s46, v5
	s_nop 1
	v_cndmask_b32_e32 v5, v219, v8, vcc
	v_mul_f32_e32 v8, 0xbfb8aa3b, v6
	v_rndne_f32_e32 v9, v8
	v_sub_f32_e32 v11, v8, v9
	v_fma_f32 v8, v6, s44, -v8
	v_fmac_f32_e32 v8, 0xb2a5705f, v6
	v_add_f32_e32 v8, v11, v8
	v_exp_f32_e32 v8, v8
	v_cvt_i32_f32_e32 v9, v9
	v_cmp_nlt_f32_e32 vcc, s45, v6
	v_pk_add_f32 v[4:5], v[4:5], 1.0 op_sel_hi:[1,0]
	v_ldexp_f32 v8, v8, v9
	v_cndmask_b32_e32 v8, 0, v8, vcc
	v_cmp_ngt_f32_e32 vcc, s46, v6
	s_nop 1
	v_cndmask_b32_e32 v6, v219, v8, vcc
	v_mul_f32_e32 v8, 0xbfb8aa3b, v7
	v_rndne_f32_e32 v9, v8
	v_sub_f32_e32 v11, v8, v9
	v_fma_f32 v8, v7, s44, -v8
	v_fmac_f32_e32 v8, 0xb2a5705f, v7
	v_add_f32_e32 v8, v11, v8
	v_exp_f32_e32 v8, v8
	v_cvt_i32_f32_e32 v9, v9
	v_cmp_nlt_f32_e32 vcc, s45, v7
	v_ldexp_f32 v8, v8, v9
	s_nop 0
	v_cndmask_b32_e32 v8, 0, v8, vcc
	v_cmp_ngt_f32_e32 vcc, s46, v7
	s_nop 1
	v_cndmask_b32_e32 v7, v219, v8, vcc
	v_pk_add_f32 v[6:7], v[6:7], 1.0 op_sel_hi:[1,0]
	s_nop 0
	v_div_scale_f32 v8, s[12:13], v7, v7, 1.0
	v_rcp_f32_e32 v9, v8
	s_nop 0
	v_fma_f32 v11, -v8, v9, 1.0
	v_fmac_f32_e32 v9, v11, v9
	v_div_scale_f32 v11, vcc, 1.0, v7, 1.0
	v_mul_f32_e32 v12, v11, v9
	v_fma_f32 v13, -v8, v12, v11
	v_fmac_f32_e32 v12, v13, v9
	v_fma_f32 v8, -v8, v12, v11
	v_div_fmas_f32 v8, v8, v9, v12
	v_div_fixup_f32 v9, v8, v7, 1.0
	v_div_scale_f32 v7, s[12:13], v6, v6, 1.0
	v_rcp_f32_e32 v8, v7
	s_nop 0
	v_fma_f32 v11, -v7, v8, 1.0
	v_fmac_f32_e32 v8, v11, v8
	v_div_scale_f32 v11, vcc, 1.0, v6, 1.0
	v_mul_f32_e32 v12, v11, v8
	v_fma_f32 v13, -v7, v12, v11
	v_fmac_f32_e32 v12, v13, v8
	v_fma_f32 v7, -v7, v12, v11
	v_div_fmas_f32 v7, v7, v8, v12
	v_div_fixup_f32 v8, v7, v6, 1.0
	v_div_scale_f32 v6, s[12:13], v5, v5, 1.0
	v_rcp_f32_e32 v7, v6
	s_nop 0
	v_fma_f32 v11, -v6, v7, 1.0
	v_fmac_f32_e32 v7, v11, v7
	v_div_scale_f32 v11, vcc, 1.0, v5, 1.0
	v_mul_f32_e32 v12, v11, v7
	v_fma_f32 v13, -v6, v12, v11
	v_fmac_f32_e32 v12, v13, v7
	v_fma_f32 v6, -v6, v12, v11
	v_div_fmas_f32 v6, v6, v7, v12
	v_div_fixup_f32 v7, v6, v5, 1.0
	v_div_scale_f32 v5, s[12:13], v4, v4, 1.0
	v_rcp_f32_e32 v6, v5
	s_nop 0
	v_fma_f32 v11, -v5, v6, 1.0
	v_fmac_f32_e32 v6, v11, v6
	v_div_scale_f32 v11, vcc, 1.0, v4, 1.0
	v_mul_f32_e32 v12, v11, v6
	v_fma_f32 v13, -v5, v12, v11
	v_fmac_f32_e32 v12, v13, v6
	v_fma_f32 v5, -v5, v12, v11
	v_div_fmas_f32 v5, v5, v6, v12
	v_div_fixup_f32 v6, v5, v4, 1.0
	v_mad_i64_i32 v[4:5], s[12:13], v10, s5, v[190:191]
	global_store_dwordx4 v[4:5], v[6:9], off sc1
	v_cmp_nlt_f32_e32 vcc, s45, v0
	s_nop 0
	v_mul_f32_e32 v6, 0xbfb8aa3b, v0
	v_rndne_f32_e32 v7, v6
	v_sub_f32_e32 v8, v6, v7
	v_fma_f32 v6, v0, s44, -v6
	v_fmac_f32_e32 v6, 0xb2a5705f, v0
	v_add_f32_e32 v6, v8, v6
	v_exp_f32_e32 v6, v6
	v_cvt_i32_f32_e32 v7, v7
	v_ldexp_f32 v6, v6, v7
	v_cndmask_b32_e32 v6, 0, v6, vcc
	v_cmp_ngt_f32_e32 vcc, s46, v0
	s_nop 1
	v_cndmask_b32_e32 v0, v219, v6, vcc
	v_mul_f32_e32 v6, 0xbfb8aa3b, v1
	v_rndne_f32_e32 v7, v6
	v_sub_f32_e32 v8, v6, v7
	v_fma_f32 v6, v1, s44, -v6
	v_fmac_f32_e32 v6, 0xb2a5705f, v1
	v_add_f32_e32 v6, v8, v6
	v_exp_f32_e32 v6, v6
	v_cvt_i32_f32_e32 v7, v7
	v_cmp_nlt_f32_e32 vcc, s45, v1
	v_ldexp_f32 v6, v6, v7
	s_nop 0
	v_cndmask_b32_e32 v6, 0, v6, vcc
	v_cmp_ngt_f32_e32 vcc, s46, v1
	s_nop 1
	v_cndmask_b32_e32 v1, v219, v6, vcc
	v_mul_f32_e32 v6, 0xbfb8aa3b, v2
	v_rndne_f32_e32 v7, v6
	v_sub_f32_e32 v8, v6, v7
	v_fma_f32 v6, v2, s44, -v6
	v_fmac_f32_e32 v6, 0xb2a5705f, v2
	v_add_f32_e32 v6, v8, v6
	v_exp_f32_e32 v6, v6
	v_cvt_i32_f32_e32 v7, v7
	v_cmp_nlt_f32_e32 vcc, s45, v2
	v_pk_add_f32 v[0:1], v[0:1], 1.0 op_sel_hi:[1,0]
	v_ldexp_f32 v6, v6, v7
	v_cndmask_b32_e32 v6, 0, v6, vcc
	v_cmp_ngt_f32_e32 vcc, s46, v2
	s_nop 1
	v_cndmask_b32_e32 v2, v219, v6, vcc
	v_mul_f32_e32 v6, 0xbfb8aa3b, v3
	v_rndne_f32_e32 v7, v6
	v_sub_f32_e32 v8, v6, v7
	v_fma_f32 v6, v3, s44, -v6
	v_fmac_f32_e32 v6, 0xb2a5705f, v3
	v_add_f32_e32 v6, v8, v6
	v_exp_f32_e32 v6, v6
	v_cvt_i32_f32_e32 v7, v7
	v_cmp_nlt_f32_e32 vcc, s45, v3
	v_ldexp_f32 v6, v6, v7
	s_nop 0
	v_cndmask_b32_e32 v6, 0, v6, vcc
	v_cmp_ngt_f32_e32 vcc, s46, v3
	s_nop 1
	v_cndmask_b32_e32 v3, v219, v6, vcc
	v_pk_add_f32 v[2:3], v[2:3], 1.0 op_sel_hi:[1,0]
	s_nop 0
	v_div_scale_f32 v6, s[12:13], v3, v3, 1.0
	v_rcp_f32_e32 v7, v6
	s_nop 0
	v_fma_f32 v8, -v6, v7, 1.0
	v_fmac_f32_e32 v7, v8, v7
	v_div_scale_f32 v8, vcc, 1.0, v3, 1.0
	v_mul_f32_e32 v9, v8, v7
	v_fma_f32 v10, -v6, v9, v8
	v_fmac_f32_e32 v9, v10, v7
	v_fma_f32 v6, -v6, v9, v8
	v_div_fmas_f32 v6, v6, v7, v9
	v_div_fixup_f32 v3, v6, v3, 1.0
	v_div_scale_f32 v6, s[12:13], v2, v2, 1.0
	v_rcp_f32_e32 v7, v6
	s_nop 0
	v_fma_f32 v8, -v6, v7, 1.0
	v_fmac_f32_e32 v7, v8, v7
	v_div_scale_f32 v8, vcc, 1.0, v2, 1.0
	v_mul_f32_e32 v9, v8, v7
	v_fma_f32 v10, -v6, v9, v8
	v_fmac_f32_e32 v9, v10, v7
	v_fma_f32 v6, -v6, v9, v8
	v_div_fmas_f32 v6, v6, v7, v9
	v_div_fixup_f32 v2, v6, v2, 1.0
	v_div_scale_f32 v6, s[12:13], v1, v1, 1.0
	v_rcp_f32_e32 v7, v6
	s_nop 0
	v_fma_f32 v8, -v6, v7, 1.0
	v_fmac_f32_e32 v7, v8, v7
	v_div_scale_f32 v8, vcc, 1.0, v1, 1.0
	v_mul_f32_e32 v9, v8, v7
	v_fma_f32 v10, -v6, v9, v8
	v_fmac_f32_e32 v9, v10, v7
	v_fma_f32 v6, -v6, v9, v8
	v_div_fmas_f32 v6, v6, v7, v9
	v_div_fixup_f32 v1, v6, v1, 1.0
	v_div_scale_f32 v6, s[12:13], v0, v0, 1.0
	v_rcp_f32_e32 v7, v6
	s_nop 0
	v_fma_f32 v8, -v6, v7, 1.0
	v_fmac_f32_e32 v7, v8, v7
	v_div_scale_f32 v8, vcc, 1.0, v0, 1.0
	v_mul_f32_e32 v9, v8, v7
	v_fma_f32 v10, -v6, v9, v8
	v_fmac_f32_e32 v9, v10, v7
	v_fma_f32 v6, -v6, v9, v8
	v_div_fmas_f32 v6, v6, v7, v9
	v_div_fixup_f32 v0, v6, v0, 1.0
	global_store_dwordx4 v[4:5], v[0:3], off offset:16 sc1

.LBB0_2007:
	s_add_u32 s12, s28, s53
	s_addc_u32 s13, s29, s51
	v_lshlrev_b64 v[158:159], 7, v[152:153]
	v_lshl_add_u64 v[158:159], s[12:13], 0, v[158:159]
	v_lshlrev_b32_e32 v170, 1, v174
	v_cvt_pk_bf16_f32 v154, v144, v145
	v_cvt_pk_bf16_f32 v155, v146, v147
	v_cvt_pk_bf16_f32 v156, v150, v151
	v_cvt_pk_bf16_f32 v157, v148, v149
	v_lshl_add_u64 v[158:159], v[158:159], 0, v[170:171]
	global_store_dwordx4 v[158:159], v[154:157], off sc1
	s_cbranch_execz .LBB0_2011
	s_branch .LBB0_2012

.LBB0_2011:
	v_mov_b32_e32 v154, 0
	v_mov_b32_e32 v155, 0
	v_cvt_pk_fp8_f32 v154, v144, v145
	v_cvt_pk_fp8_f32 v155, v150, v151
	v_lshlrev_b64 v[152:153], 6, v[152:153]
	v_lshl_add_u64 v[152:153], v[180:181], 0, v[152:153]
	v_cvt_pk_fp8_f32 v154, v146, v147 op_sel:[0,0,1]
	v_cvt_pk_fp8_f32 v155, v148, v149 op_sel:[0,0,1]
	global_store_dwordx2 v[152:153], v[154:155], off sc1

.LBB0_2013:
	v_lshlrev_b64 v[152:153], 11, v[200:201]
	s_lshl_b32 s82, s80, 8
	s_ashr_i32 s83, s82, 31
	v_lshl_add_u64 v[152:153], s[38:39], 0, v[152:153]
	s_and_b64 vcc, exec, s[12:13]
	v_lshl_add_u64 v[204:205], s[82:83], 1, v[152:153]
	s_cbranch_vccz .LBB0_2015
	v_cvt_pk_bf16_f32 v144, v144, v145
	v_cvt_pk_bf16_f32 v145, v146, v147
	v_cvt_pk_bf16_f32 v146, v150, v151
	v_cvt_pk_bf16_f32 v147, v148, v149
	v_lshl_add_u64 v[148:149], v[172:173], 1, v[204:205]
	global_store_dwordx4 v[148:149], v[144:147], off sc1

.LBB0_2029:
	s_add_u32 s60, s28, s53
	s_addc_u32 s61, s29, s51
	v_lshlrev_b64 v[134:135], 7, v[128:129]
	v_lshl_add_u64 v[134:135], s[60:61], 0, v[134:135]
	v_lshlrev_b32_e32 v170, 1, v176
	v_cvt_pk_bf16_f32 v130, v124, v125
	v_cvt_pk_bf16_f32 v131, v126, v127
	v_cvt_pk_bf16_f32 v132, v120, v121
	v_cvt_pk_bf16_f32 v133, v122, v123
	v_lshl_add_u64 v[134:135], v[134:135], 0, v[170:171]
	global_store_dwordx4 v[134:135], v[130:133], off sc1
	s_cbranch_execz .LBB0_2036
	s_branch .LBB0_2037
.LBB0_2030:
	s_and_b64 vcc, exec, s[84:85]
	s_cbranch_vccz .LBB0_2038
	v_cvt_pk_bf16_f32 v124, v124, v125
	v_cvt_pk_bf16_f32 v125, v126, v127
	v_cvt_pk_bf16_f32 v126, v120, v121
	v_cvt_pk_bf16_f32 v127, v122, v123
	v_lshl_add_u64 v[120:121], v[172:173], 1, v[204:205]
	global_store_dwordx4 v[120:121], v[124:127], off offset:256 sc1
	v_or_b32_e32 v152, 16, v200
	s_and_b64 vcc, exec, s[10:11]
	v_ashrrev_i32_e32 v153, 31, v152
	s_cbranch_vccz .LBB0_2039

.LBB0_2036:
	v_mov_b32_e32 v130, v171
	v_mov_b32_e32 v131, v171
	v_cvt_pk_fp8_f32 v130, v124, v125
	v_cvt_pk_fp8_f32 v131, v120, v121
	v_lshlrev_b64 v[128:129], 6, v[128:129]
	v_lshl_add_u64 v[128:129], v[184:185], 0, v[128:129]
	v_cvt_pk_fp8_f32 v130, v126, v127 op_sel:[0,0,1]
	v_cvt_pk_fp8_f32 v131, v122, v123 op_sel:[0,0,1]
	global_store_dwordx2 v[128:129], v[130:131], off sc1

.LBB0_2054:
	s_add_u32 s60, s28, s53
	s_addc_u32 s61, s29, s51
	s_waitcnt lgkmcnt(0)
	v_lshlrev_b64 v[150:151], 7, v[144:145]
	v_lshl_add_u64 v[150:151], s[60:61], 0, v[150:151]
	v_lshlrev_b32_e32 v170, 1, v174
	v_cvt_pk_bf16_f32 v146, v136, v137
	v_cvt_pk_bf16_f32 v147, v138, v139
	v_cvt_pk_bf16_f32 v148, v142, v143
	v_cvt_pk_bf16_f32 v149, v140, v141
	v_lshl_add_u64 v[150:151], v[150:151], 0, v[170:171]
	global_store_dwordx4 v[150:151], v[146:149], off sc1
	s_cbranch_execz .LBB0_2058
	s_branch .LBB0_2059

.LBB0_2058:
	v_mov_b32_e32 v146, v171
	v_mov_b32_e32 v147, v171
	v_cvt_pk_fp8_f32 v146, v136, v137
	v_cvt_pk_fp8_f32 v147, v142, v143
	v_lshlrev_b64 v[144:145], 6, v[144:145]
	v_lshl_add_u64 v[144:145], v[180:181], 0, v[144:145]
	v_cvt_pk_fp8_f32 v146, v138, v139 op_sel:[0,0,1]
	v_cvt_pk_fp8_f32 v147, v140, v141 op_sel:[0,0,1]
	global_store_dwordx2 v[144:145], v[146:147], off sc1

.LBB0_2060:
	v_lshlrev_b64 v[144:145], 11, v[152:153]
	v_lshl_add_u64 v[144:145], s[38:39], 0, v[144:145]
	s_and_b64 vcc, exec, s[84:85]
	s_waitcnt lgkmcnt(1)
	v_lshl_add_u64 v[154:155], s[82:83], 1, v[144:145]
	s_cbranch_vccz .LBB0_2062
	v_cvt_pk_bf16_f32 v136, v136, v137
	v_cvt_pk_bf16_f32 v137, v138, v139
	v_cvt_pk_bf16_f32 v138, v142, v143
	v_cvt_pk_bf16_f32 v139, v140, v141
	v_lshl_add_u64 v[140:141], v[172:173], 1, v[154:155]
	global_store_dwordx4 v[140:141], v[136:139], off sc1

.LBB0_2076:
	s_add_u32 s60, s28, s53
	s_addc_u32 s61, s29, s51
	s_waitcnt vmcnt(1)
	v_lshlrev_b64 v[126:127], 7, v[120:121]
	v_lshl_add_u64 v[126:127], s[60:61], 0, v[126:127]
	v_lshlrev_b32_e32 v170, 1, v176
	v_cvt_pk_bf16_f32 v122, v116, v117
	v_cvt_pk_bf16_f32 v123, v118, v119
	v_cvt_pk_bf16_f32 v124, v112, v113
	v_cvt_pk_bf16_f32 v125, v114, v115
	v_lshl_add_u64 v[126:127], v[126:127], 0, v[170:171]
	global_store_dwordx4 v[126:127], v[122:125], off sc1
	s_cbranch_execz .LBB0_2083
	s_branch .LBB0_2084
.LBB0_2077:
	s_and_b64 vcc, exec, s[84:85]
	s_cbranch_vccz .LBB0_2085
	v_cvt_pk_bf16_f32 v116, v116, v117
	v_cvt_pk_bf16_f32 v117, v118, v119
	v_cvt_pk_bf16_f32 v118, v112, v113
	v_cvt_pk_bf16_f32 v119, v114, v115
	v_lshl_add_u64 v[112:113], v[172:173], 1, v[154:155]
	global_store_dwordx4 v[112:113], v[116:119], off offset:256 sc1
	v_or_b32_e32 v144, 32, v200
	s_and_b64 vcc, exec, s[10:11]
	v_ashrrev_i32_e32 v145, 31, v144
	s_cbranch_vccz .LBB0_2086

.LBB0_2083:
	v_mov_b32_e32 v122, v171
	v_mov_b32_e32 v123, v171
	v_cvt_pk_fp8_f32 v122, v116, v117
	v_cvt_pk_fp8_f32 v123, v112, v113
	v_lshlrev_b64 v[120:121], 6, v[120:121]
	v_lshl_add_u64 v[120:121], v[184:185], 0, v[120:121]
	v_cvt_pk_fp8_f32 v122, v118, v119 op_sel:[0,0,1]
	v_cvt_pk_fp8_f32 v123, v114, v115 op_sel:[0,0,1]
	global_store_dwordx2 v[120:121], v[122:123], off sc1

.LBB0_2101:
	s_add_u32 s60, s28, s53
	s_addc_u32 s61, s29, s51
	s_waitcnt lgkmcnt(0)
	v_lshlrev_b64 v[142:143], 7, v[136:137]
	v_lshl_add_u64 v[142:143], s[60:61], 0, v[142:143]
	v_lshlrev_b32_e32 v170, 1, v174
	v_cvt_pk_bf16_f32 v138, v128, v129
	v_cvt_pk_bf16_f32 v139, v130, v131
	v_cvt_pk_bf16_f32 v140, v134, v135
	v_cvt_pk_bf16_f32 v141, v132, v133
	v_lshl_add_u64 v[142:143], v[142:143], 0, v[170:171]
	global_store_dwordx4 v[142:143], v[138:141], off sc1
	s_cbranch_execz .LBB0_2105
	s_branch .LBB0_2106

.LBB0_2105:
	v_mov_b32_e32 v138, v171
	v_mov_b32_e32 v139, v171
	v_cvt_pk_fp8_f32 v138, v128, v129
	v_cvt_pk_fp8_f32 v139, v134, v135
	v_lshlrev_b64 v[136:137], 6, v[136:137]
	v_lshl_add_u64 v[136:137], v[180:181], 0, v[136:137]
	v_cvt_pk_fp8_f32 v138, v130, v131 op_sel:[0,0,1]
	v_cvt_pk_fp8_f32 v139, v132, v133 op_sel:[0,0,1]
	global_store_dwordx2 v[136:137], v[138:139], off sc1

.LBB0_2107:
	v_lshlrev_b64 v[136:137], 11, v[144:145]
	v_lshl_add_u64 v[136:137], s[38:39], 0, v[136:137]
	s_and_b64 vcc, exec, s[84:85]
	s_waitcnt lgkmcnt(1)
	v_lshl_add_u64 v[146:147], s[82:83], 1, v[136:137]
	s_cbranch_vccz .LBB0_2109
	v_cvt_pk_bf16_f32 v128, v128, v129
	v_cvt_pk_bf16_f32 v129, v130, v131
	v_cvt_pk_bf16_f32 v130, v134, v135
	v_cvt_pk_bf16_f32 v131, v132, v133
	v_lshl_add_u64 v[132:133], v[172:173], 1, v[146:147]
	global_store_dwordx4 v[132:133], v[128:131], off sc1

.LBB0_2123:
	s_add_u32 s60, s28, s53
	s_addc_u32 s61, s29, s51
	v_lshlrev_b64 v[118:119], 7, v[112:113]
	v_lshl_add_u64 v[118:119], s[60:61], 0, v[118:119]
	v_lshlrev_b32_e32 v170, 1, v176
	v_cvt_pk_bf16_f32 v114, v108, v109
	v_cvt_pk_bf16_f32 v115, v110, v111
	v_cvt_pk_bf16_f32 v116, v104, v105
	v_cvt_pk_bf16_f32 v117, v106, v107
	v_lshl_add_u64 v[118:119], v[118:119], 0, v[170:171]
	global_store_dwordx4 v[118:119], v[114:117], off sc1
	s_cbranch_execz .LBB0_2130
	s_branch .LBB0_2131
.LBB0_2124:
	s_and_b64 vcc, exec, s[84:85]
	s_cbranch_vccz .LBB0_2132
	v_cvt_pk_bf16_f32 v108, v108, v109
	v_cvt_pk_bf16_f32 v109, v110, v111
	v_cvt_pk_bf16_f32 v110, v104, v105
	v_cvt_pk_bf16_f32 v111, v106, v107
	v_lshl_add_u64 v[104:105], v[172:173], 1, v[146:147]
	global_store_dwordx4 v[104:105], v[108:111], off offset:256 sc1
	v_or_b32_e32 v136, 48, v200
	s_and_b64 vcc, exec, s[10:11]
	v_ashrrev_i32_e32 v137, 31, v136
	s_cbranch_vccz .LBB0_2133

.LBB0_2130:
	v_mov_b32_e32 v114, v171
	v_mov_b32_e32 v115, v171
	v_cvt_pk_fp8_f32 v114, v108, v109
	v_cvt_pk_fp8_f32 v115, v104, v105
	v_lshlrev_b64 v[112:113], 6, v[112:113]
	v_lshl_add_u64 v[112:113], v[184:185], 0, v[112:113]
	v_cvt_pk_fp8_f32 v114, v110, v111 op_sel:[0,0,1]
	v_cvt_pk_fp8_f32 v115, v106, v107 op_sel:[0,0,1]
	global_store_dwordx2 v[112:113], v[114:115], off sc1

.LBB0_2148:
	s_add_u32 s60, s28, s53
	s_addc_u32 s61, s29, s51
	s_waitcnt lgkmcnt(0)
	v_lshlrev_b64 v[134:135], 7, v[128:129]
	v_lshl_add_u64 v[134:135], s[60:61], 0, v[134:135]
	v_lshlrev_b32_e32 v170, 1, v174
	v_cvt_pk_bf16_f32 v130, v120, v121
	v_cvt_pk_bf16_f32 v131, v122, v123
	v_cvt_pk_bf16_f32 v132, v126, v127
	v_cvt_pk_bf16_f32 v133, v124, v125
	v_lshl_add_u64 v[134:135], v[134:135], 0, v[170:171]
	global_store_dwordx4 v[134:135], v[130:133], off sc1
	s_cbranch_execz .LBB0_2152
	s_branch .LBB0_2153

.LBB0_2152:
	v_mov_b32_e32 v130, v171
	v_mov_b32_e32 v131, v171
	v_cvt_pk_fp8_f32 v130, v120, v121
	v_cvt_pk_fp8_f32 v131, v126, v127
	v_lshlrev_b64 v[128:129], 6, v[128:129]
	v_lshl_add_u64 v[128:129], v[180:181], 0, v[128:129]
	v_cvt_pk_fp8_f32 v130, v122, v123 op_sel:[0,0,1]
	v_cvt_pk_fp8_f32 v131, v124, v125 op_sel:[0,0,1]
	global_store_dwordx2 v[128:129], v[130:131], off sc1

.LBB0_2154:
	v_lshlrev_b64 v[128:129], 11, v[136:137]
	v_lshl_add_u64 v[128:129], s[38:39], 0, v[128:129]
	s_and_b64 vcc, exec, s[84:85]
	s_waitcnt lgkmcnt(1)
	v_lshl_add_u64 v[138:139], s[82:83], 1, v[128:129]
	s_cbranch_vccz .LBB0_2156
	v_cvt_pk_bf16_f32 v120, v120, v121
	v_cvt_pk_bf16_f32 v121, v122, v123
	v_cvt_pk_bf16_f32 v122, v126, v127
	v_cvt_pk_bf16_f32 v123, v124, v125
	v_lshl_add_u64 v[124:125], v[172:173], 1, v[138:139]
	global_store_dwordx4 v[124:125], v[120:123], off sc1

.LBB0_2170:
	s_add_u32 s58, s28, s53
	s_addc_u32 s59, s29, s51
	s_waitcnt vmcnt(1)
	v_lshlrev_b64 v[110:111], 7, v[104:105]
	v_lshl_add_u64 v[110:111], s[58:59], 0, v[110:111]
	v_lshlrev_b32_e32 v170, 1, v176
	v_cvt_pk_bf16_f32 v106, v100, v101
	v_cvt_pk_bf16_f32 v107, v102, v103
	v_cvt_pk_bf16_f32 v108, v96, v97
	v_cvt_pk_bf16_f32 v109, v98, v99
	v_lshl_add_u64 v[110:111], v[110:111], 0, v[170:171]
	global_store_dwordx4 v[110:111], v[106:109], off sc1
	s_cbranch_execz .LBB0_2177
	s_branch .LBB0_2178
.LBB0_2171:
	s_and_b64 vcc, exec, s[84:85]
	s_cbranch_vccz .LBB0_2179
	v_cvt_pk_bf16_f32 v100, v100, v101
	v_cvt_pk_bf16_f32 v101, v102, v103
	v_cvt_pk_bf16_f32 v102, v96, v97
	v_cvt_pk_bf16_f32 v103, v98, v99
	v_lshl_add_u64 v[96:97], v[172:173], 1, v[138:139]
	global_store_dwordx4 v[96:97], v[100:103], off offset:256 sc1
	v_add_u32_e32 v128, 0x80, v200
	s_and_b64 vcc, exec, s[10:11]
	v_ashrrev_i32_e32 v129, 31, v128
	s_cbranch_vccz .LBB0_2180

.LBB0_2177:
	v_mov_b32_e32 v106, v171
	v_mov_b32_e32 v107, v171
	v_cvt_pk_fp8_f32 v106, v100, v101
	v_cvt_pk_fp8_f32 v107, v96, v97
	v_lshlrev_b64 v[104:105], 6, v[104:105]
	v_lshl_add_u64 v[104:105], v[184:185], 0, v[104:105]
	v_cvt_pk_fp8_f32 v106, v102, v103 op_sel:[0,0,1]
	v_cvt_pk_fp8_f32 v107, v98, v99 op_sel:[0,0,1]
	global_store_dwordx2 v[104:105], v[106:107], off sc1

.LBB0_2195:
	s_add_u32 s58, s28, s53
	s_addc_u32 s59, s29, s51
	s_waitcnt lgkmcnt(0)
	v_lshlrev_b64 v[126:127], 7, v[120:121]
	v_lshl_add_u64 v[126:127], s[58:59], 0, v[126:127]
	v_lshlrev_b32_e32 v170, 1, v174
	v_cvt_pk_bf16_f32 v122, v112, v113
	v_cvt_pk_bf16_f32 v123, v114, v115
	v_cvt_pk_bf16_f32 v124, v118, v119
	v_cvt_pk_bf16_f32 v125, v116, v117
	v_lshl_add_u64 v[126:127], v[126:127], 0, v[170:171]
	global_store_dwordx4 v[126:127], v[122:125], off sc1
	s_cbranch_execz .LBB0_2199
	s_branch .LBB0_2200

.LBB0_2199:
	v_mov_b32_e32 v122, v171
	v_mov_b32_e32 v123, v171
	v_cvt_pk_fp8_f32 v122, v112, v113
	v_cvt_pk_fp8_f32 v123, v118, v119
	v_lshlrev_b64 v[120:121], 6, v[120:121]
	v_lshl_add_u64 v[120:121], v[180:181], 0, v[120:121]
	v_cvt_pk_fp8_f32 v122, v114, v115 op_sel:[0,0,1]
	v_cvt_pk_fp8_f32 v123, v116, v117 op_sel:[0,0,1]
	global_store_dwordx2 v[120:121], v[122:123], off sc1

.LBB0_2201:
	v_lshlrev_b64 v[120:121], 11, v[128:129]
	v_lshl_add_u64 v[120:121], s[38:39], 0, v[120:121]
	s_and_b64 vcc, exec, s[84:85]
	s_waitcnt lgkmcnt(1)
	v_lshl_add_u64 v[130:131], s[82:83], 1, v[120:121]
	s_cbranch_vccz .LBB0_2203
	v_cvt_pk_bf16_f32 v112, v112, v113
	v_cvt_pk_bf16_f32 v113, v114, v115
	v_cvt_pk_bf16_f32 v114, v118, v119
	v_cvt_pk_bf16_f32 v115, v116, v117
	v_lshl_add_u64 v[116:117], v[172:173], 1, v[130:131]
	global_store_dwordx4 v[116:117], v[112:115], off sc1

.LBB0_2217:
	s_add_u32 s58, s28, s53
	s_addc_u32 s59, s29, s51
	v_lshlrev_b64 v[102:103], 7, v[96:97]
	v_lshl_add_u64 v[102:103], s[58:59], 0, v[102:103]
	v_lshlrev_b32_e32 v170, 1, v176
	v_cvt_pk_bf16_f32 v98, v92, v93
	v_cvt_pk_bf16_f32 v99, v94, v95
	v_cvt_pk_bf16_f32 v100, v88, v89
	v_cvt_pk_bf16_f32 v101, v90, v91
	v_lshl_add_u64 v[102:103], v[102:103], 0, v[170:171]
	global_store_dwordx4 v[102:103], v[98:101], off sc1
	s_cbranch_execz .LBB0_2224
	s_branch .LBB0_2225
.LBB0_2218:
	s_and_b64 vcc, exec, s[84:85]
	s_cbranch_vccz .LBB0_2226
	v_cvt_pk_bf16_f32 v92, v92, v93
	v_cvt_pk_bf16_f32 v93, v94, v95
	v_cvt_pk_bf16_f32 v94, v88, v89
	v_cvt_pk_bf16_f32 v95, v90, v91
	v_lshl_add_u64 v[88:89], v[172:173], 1, v[130:131]
	global_store_dwordx4 v[88:89], v[92:95], off offset:256 sc1
	v_add_u32_e32 v120, 0x90, v200
	s_and_b64 vcc, exec, s[10:11]
	v_ashrrev_i32_e32 v121, 31, v120
	s_cbranch_vccz .LBB0_2227

.LBB0_2224:
	v_mov_b32_e32 v98, v171
	v_mov_b32_e32 v99, v171
	v_cvt_pk_fp8_f32 v98, v92, v93
	v_cvt_pk_fp8_f32 v99, v88, v89
	v_lshlrev_b64 v[96:97], 6, v[96:97]
	v_lshl_add_u64 v[96:97], v[184:185], 0, v[96:97]
	v_cvt_pk_fp8_f32 v98, v94, v95 op_sel:[0,0,1]
	v_cvt_pk_fp8_f32 v99, v90, v91 op_sel:[0,0,1]
	global_store_dwordx2 v[96:97], v[98:99], off sc1

.LBB0_2242:
	s_add_u32 s58, s28, s53
	s_addc_u32 s59, s29, s51
	s_waitcnt lgkmcnt(0)
	v_lshlrev_b64 v[118:119], 7, v[112:113]
	v_lshl_add_u64 v[118:119], s[58:59], 0, v[118:119]
	v_lshlrev_b32_e32 v170, 1, v174
	v_cvt_pk_bf16_f32 v114, v104, v105
	v_cvt_pk_bf16_f32 v115, v106, v107
	v_cvt_pk_bf16_f32 v116, v110, v111
	v_cvt_pk_bf16_f32 v117, v108, v109
	v_lshl_add_u64 v[118:119], v[118:119], 0, v[170:171]
	global_store_dwordx4 v[118:119], v[114:117], off sc1
	s_cbranch_execz .LBB0_2246
	s_branch .LBB0_2247

.LBB0_2246:
	v_mov_b32_e32 v114, v171
	v_mov_b32_e32 v115, v171
	v_cvt_pk_fp8_f32 v114, v104, v105
	v_cvt_pk_fp8_f32 v115, v110, v111
	v_lshlrev_b64 v[112:113], 6, v[112:113]
	v_lshl_add_u64 v[112:113], v[180:181], 0, v[112:113]
	v_cvt_pk_fp8_f32 v114, v106, v107 op_sel:[0,0,1]
	v_cvt_pk_fp8_f32 v115, v108, v109 op_sel:[0,0,1]
	global_store_dwordx2 v[112:113], v[114:115], off sc1

.LBB0_2248:
	v_lshlrev_b64 v[112:113], 11, v[120:121]
	v_lshl_add_u64 v[112:113], s[38:39], 0, v[112:113]
	s_and_b64 vcc, exec, s[84:85]
	s_waitcnt lgkmcnt(1)
	v_lshl_add_u64 v[122:123], s[82:83], 1, v[112:113]
	s_cbranch_vccz .LBB0_2250
	v_cvt_pk_bf16_f32 v104, v104, v105
	v_cvt_pk_bf16_f32 v105, v106, v107
	v_cvt_pk_bf16_f32 v106, v110, v111
	v_cvt_pk_bf16_f32 v107, v108, v109
	v_lshl_add_u64 v[108:109], v[172:173], 1, v[122:123]
	global_store_dwordx4 v[108:109], v[104:107], off sc1

.LBB0_2264:
	s_add_u32 s58, s28, s53
	s_addc_u32 s59, s29, s51
	s_waitcnt vmcnt(1)
	v_lshlrev_b64 v[94:95], 7, v[88:89]
	v_lshl_add_u64 v[94:95], s[58:59], 0, v[94:95]
	v_lshlrev_b32_e32 v170, 1, v176
	v_cvt_pk_bf16_f32 v90, v84, v85
	v_cvt_pk_bf16_f32 v91, v86, v87
	v_cvt_pk_bf16_f32 v92, v80, v81
	v_cvt_pk_bf16_f32 v93, v82, v83
	v_lshl_add_u64 v[94:95], v[94:95], 0, v[170:171]
	global_store_dwordx4 v[94:95], v[90:93], off sc1
	s_cbranch_execz .LBB0_2271
	s_branch .LBB0_2272
.LBB0_2265:
	s_and_b64 vcc, exec, s[84:85]
	s_cbranch_vccz .LBB0_2273
	v_cvt_pk_bf16_f32 v84, v84, v85
	v_cvt_pk_bf16_f32 v85, v86, v87
	v_cvt_pk_bf16_f32 v86, v80, v81
	v_cvt_pk_bf16_f32 v87, v82, v83
	v_lshl_add_u64 v[80:81], v[172:173], 1, v[122:123]
	global_store_dwordx4 v[80:81], v[84:87], off offset:256 sc1
	v_add_u32_e32 v112, 0xa0, v200
	s_and_b64 vcc, exec, s[10:11]
	v_ashrrev_i32_e32 v113, 31, v112
	s_cbranch_vccz .LBB0_2274

.LBB0_2271:
	v_mov_b32_e32 v90, v171
	v_mov_b32_e32 v91, v171
	v_cvt_pk_fp8_f32 v90, v84, v85
	v_cvt_pk_fp8_f32 v91, v80, v81
	v_lshlrev_b64 v[88:89], 6, v[88:89]
	v_lshl_add_u64 v[88:89], v[184:185], 0, v[88:89]
	v_cvt_pk_fp8_f32 v90, v86, v87 op_sel:[0,0,1]
	v_cvt_pk_fp8_f32 v91, v82, v83 op_sel:[0,0,1]
	global_store_dwordx2 v[88:89], v[90:91], off sc1

.LBB0_2289:
	s_add_u32 s58, s28, s53
	s_addc_u32 s59, s29, s51
	s_waitcnt lgkmcnt(0)
	v_lshlrev_b64 v[110:111], 7, v[104:105]
	v_lshl_add_u64 v[110:111], s[58:59], 0, v[110:111]
	v_lshlrev_b32_e32 v170, 1, v174
	v_cvt_pk_bf16_f32 v106, v96, v97
	v_cvt_pk_bf16_f32 v107, v98, v99
	v_cvt_pk_bf16_f32 v108, v102, v103
	v_cvt_pk_bf16_f32 v109, v100, v101
	v_lshl_add_u64 v[110:111], v[110:111], 0, v[170:171]
	global_store_dwordx4 v[110:111], v[106:109], off sc1
	s_cbranch_execz .LBB0_2293
	s_branch .LBB0_2294

.LBB0_2293:
	v_mov_b32_e32 v106, v171
	v_mov_b32_e32 v107, v171
	v_cvt_pk_fp8_f32 v106, v96, v97
	v_cvt_pk_fp8_f32 v107, v102, v103
	v_lshlrev_b64 v[104:105], 6, v[104:105]
	v_lshl_add_u64 v[104:105], v[180:181], 0, v[104:105]
	v_cvt_pk_fp8_f32 v106, v98, v99 op_sel:[0,0,1]
	v_cvt_pk_fp8_f32 v107, v100, v101 op_sel:[0,0,1]
	global_store_dwordx2 v[104:105], v[106:107], off sc1

.LBB0_2295:
	v_lshlrev_b64 v[104:105], 11, v[112:113]
	v_lshl_add_u64 v[104:105], s[38:39], 0, v[104:105]
	s_and_b64 vcc, exec, s[84:85]
	s_waitcnt lgkmcnt(1)
	v_lshl_add_u64 v[114:115], s[82:83], 1, v[104:105]
	s_cbranch_vccz .LBB0_2297
	v_cvt_pk_bf16_f32 v96, v96, v97
	v_cvt_pk_bf16_f32 v97, v98, v99
	v_cvt_pk_bf16_f32 v98, v102, v103
	v_cvt_pk_bf16_f32 v99, v100, v101
	v_lshl_add_u64 v[100:101], v[172:173], 1, v[114:115]
	global_store_dwordx4 v[100:101], v[96:99], off sc1

.LBB0_2311:
	s_add_u32 s58, s28, s53
	s_addc_u32 s59, s29, s51
	v_lshlrev_b64 v[86:87], 7, v[80:81]
	v_lshl_add_u64 v[86:87], s[58:59], 0, v[86:87]
	v_lshlrev_b32_e32 v170, 1, v176
	v_cvt_pk_bf16_f32 v82, v76, v77
	v_cvt_pk_bf16_f32 v83, v78, v79
	v_cvt_pk_bf16_f32 v84, v72, v73
	v_cvt_pk_bf16_f32 v85, v74, v75
	v_lshl_add_u64 v[86:87], v[86:87], 0, v[170:171]
	global_store_dwordx4 v[86:87], v[82:85], off sc1
	s_cbranch_execz .LBB0_2318
	s_branch .LBB0_2319
.LBB0_2312:
	s_and_b64 vcc, exec, s[84:85]
	s_cbranch_vccz .LBB0_2320
	v_cvt_pk_bf16_f32 v76, v76, v77
	v_cvt_pk_bf16_f32 v77, v78, v79
	v_cvt_pk_bf16_f32 v78, v72, v73
	v_cvt_pk_bf16_f32 v79, v74, v75
	v_lshl_add_u64 v[72:73], v[172:173], 1, v[114:115]
	global_store_dwordx4 v[72:73], v[76:79], off offset:256 sc1
	v_add_u32_e32 v104, 0xb0, v200
	s_and_b64 vcc, exec, s[10:11]
	v_ashrrev_i32_e32 v105, 31, v104
	s_cbranch_vccz .LBB0_2321

.LBB0_2318:
	v_mov_b32_e32 v82, v171
	v_mov_b32_e32 v83, v171
	v_cvt_pk_fp8_f32 v82, v76, v77
	v_cvt_pk_fp8_f32 v83, v72, v73
	v_lshlrev_b64 v[80:81], 6, v[80:81]
	v_lshl_add_u64 v[80:81], v[184:185], 0, v[80:81]
	v_cvt_pk_fp8_f32 v82, v78, v79 op_sel:[0,0,1]
	v_cvt_pk_fp8_f32 v83, v74, v75 op_sel:[0,0,1]
	global_store_dwordx2 v[80:81], v[82:83], off sc1

.LBB0_2336:
	s_add_u32 s58, s28, s53
	s_addc_u32 s59, s29, s51
	s_waitcnt lgkmcnt(0)
	v_lshlrev_b64 v[102:103], 7, v[96:97]
	v_lshl_add_u64 v[102:103], s[58:59], 0, v[102:103]
	v_lshlrev_b32_e32 v170, 1, v174
	v_cvt_pk_bf16_f32 v98, v88, v89
	v_cvt_pk_bf16_f32 v99, v90, v91
	v_cvt_pk_bf16_f32 v100, v94, v95
	v_cvt_pk_bf16_f32 v101, v92, v93
	v_lshl_add_u64 v[102:103], v[102:103], 0, v[170:171]
	global_store_dwordx4 v[102:103], v[98:101], off sc1
	s_cbranch_execz .LBB0_2340
	s_branch .LBB0_2341

.LBB0_2340:
	v_mov_b32_e32 v98, v171
	v_mov_b32_e32 v99, v171
	v_cvt_pk_fp8_f32 v98, v88, v89
	v_cvt_pk_fp8_f32 v99, v94, v95
	v_lshlrev_b64 v[96:97], 6, v[96:97]
	v_lshl_add_u64 v[96:97], v[180:181], 0, v[96:97]
	v_cvt_pk_fp8_f32 v98, v90, v91 op_sel:[0,0,1]
	v_cvt_pk_fp8_f32 v99, v92, v93 op_sel:[0,0,1]
	global_store_dwordx2 v[96:97], v[98:99], off sc1

.LBB0_2342:
	v_lshlrev_b64 v[96:97], 11, v[104:105]
	v_lshl_add_u64 v[96:97], s[38:39], 0, v[96:97]
	s_and_b64 vcc, exec, s[84:85]
	s_waitcnt lgkmcnt(1)
	v_lshl_add_u64 v[106:107], s[82:83], 1, v[96:97]
	s_cbranch_vccz .LBB0_2344
	v_cvt_pk_bf16_f32 v88, v88, v89
	v_cvt_pk_bf16_f32 v89, v90, v91
	v_cvt_pk_bf16_f32 v90, v94, v95
	v_cvt_pk_bf16_f32 v91, v92, v93
	v_lshl_add_u64 v[92:93], v[172:173], 1, v[106:107]
	global_store_dwordx4 v[92:93], v[88:91], off sc1

.LBB0_2358:
	s_add_u32 s10, s28, s53
	s_addc_u32 s11, s29, s51
	s_waitcnt vmcnt(1)
	v_lshlrev_b64 v[78:79], 7, v[72:73]
	v_lshl_add_u64 v[78:79], s[10:11], 0, v[78:79]
	v_lshlrev_b32_e32 v170, 1, v176
	v_cvt_pk_bf16_f32 v74, v68, v69
	v_cvt_pk_bf16_f32 v75, v70, v71
	v_cvt_pk_bf16_f32 v76, v64, v65
	v_cvt_pk_bf16_f32 v77, v66, v67
	v_lshl_add_u64 v[78:79], v[78:79], 0, v[170:171]
	global_store_dwordx4 v[78:79], v[74:77], off sc1
	s_cbranch_execz .LBB0_2362
	s_branch .LBB0_2363

.LBB0_2362:
	v_mov_b32_e32 v74, v171
	v_mov_b32_e32 v75, v171
	v_cvt_pk_fp8_f32 v74, v68, v69
	v_cvt_pk_fp8_f32 v75, v64, v65
	v_lshlrev_b64 v[72:73], 6, v[72:73]
	v_lshl_add_u64 v[72:73], v[184:185], 0, v[72:73]
	v_cvt_pk_fp8_f32 v74, v70, v71 op_sel:[0,0,1]
	v_cvt_pk_fp8_f32 v75, v66, v67 op_sel:[0,0,1]
	global_store_dwordx2 v[72:73], v[74:75], off sc1

.LBB0_2364:
	s_and_b64 vcc, exec, s[10:11]
	s_cbranch_vccz .LBB0_2366
	v_cvt_pk_bf16_f32 v68, v68, v69
	v_cvt_pk_bf16_f32 v69, v70, v71
	v_cvt_pk_bf16_f32 v70, v64, v65
	v_cvt_pk_bf16_f32 v71, v66, v67
	v_lshl_add_u64 v[64:65], v[172:173], 1, v[106:107]
	global_store_dwordx4 v[64:65], v[68:71], off offset:256 sc1

.LBB0_2375:
	s_or_b64 exec, exec, s[20:21]
	s_waitcnt vmcnt(0)
	ds_write2_b32 v41, v0, v1 offset1:1
	ds_write2_b32 v41, v2, v3 offset0:2 offset1:3
	v_add_u32_e32 v0, 0x420, v41
	ds_write2_b32 v0, v8, v9 offset1:1
	v_add_u32_e32 v0, 0x428, v41
	ds_write2_b32 v0, v10, v11 offset1:1
	v_add_u32_e32 v0, 0x840, v41
	ds_write2_b32 v0, v4, v5 offset1:1
	v_add_u32_e32 v0, 0x848, v41
	ds_write2_b32 v0, v6, v7 offset1:1
	v_add_u32_e32 v0, 0xc60, v41
	ds_write2_b32 v0, v16, v17 offset1:1
	v_add_u32_e32 v0, 0xc68, v41
	ds_write2_b32 v0, v18, v19 offset1:1
	v_add_u32_e32 v0, 0x1080, v41
	ds_write2_b32 v0, v12, v13 offset1:1
	v_add_u32_e32 v0, 0x1088, v41
	ds_write2_b32 v0, v14, v15 offset1:1
	v_add_u32_e32 v0, 0x14a0, v41
	ds_write2_b32 v0, v24, v25 offset1:1
	v_add_u32_e32 v0, 0x14a8, v41
	ds_write2_b32 v0, v26, v27 offset1:1
	v_add_u32_e32 v0, 0x18c0, v41
	ds_write2_b32 v0, v20, v21 offset1:1
	v_add_u32_e32 v0, 0x18c8, v41
	ds_write2_b32 v0, v22, v23 offset1:1
	v_add_u32_e32 v0, 0x1ce0, v41
	ds_write2_b32 v0, v28, v29 offset1:1
	v_add_u32_e32 v0, 0x1ce8, v41
	ds_write2_b32 v0, v30, v31 offset1:1
	s_waitcnt lgkmcnt(0)
	s_sub_i32 s4, 0, s4
	ds_read2_b32 v[4:5], v40 offset0:33 offset1:41
	ds_read2_b32 v[6:7], v40 offset1:8
	ds_read2_b32 v[8:9], v40 offset0:66 offset1:74
	ds_read2_b32 v[10:11], v40 offset0:99 offset1:107
	ds_read2_b32 v[12:13], v40 offset0:132 offset1:140
	ds_read2_b32 v[14:15], v40 offset0:165 offset1:173
	ds_read2_b32 v[16:17], v40 offset0:198 offset1:206
	ds_read2_b32 v[18:19], v40 offset0:231 offset1:239
	s_add_i32 s4, s4, s2
	v_add_u32_e32 v22, s4, v39
	s_ashr_i32 s13, s12, 31
	v_ashrrev_i32_e32 v23, 31, v22
	v_lshl_add_u64 v[20:21], s[12:13], 1, v[32:33]
	v_lshlrev_b64 v[24:25], 11, v[22:23]
	s_waitcnt lgkmcnt(6)
	v_cvt_pk_bf16_f32 v0, v6, v4
	s_waitcnt lgkmcnt(4)
	v_cvt_pk_bf16_f32 v1, v8, v10
	s_waitcnt lgkmcnt(2)
	v_cvt_pk_bf16_f32 v2, v12, v14
	s_waitcnt lgkmcnt(0)
	v_cvt_pk_bf16_f32 v3, v16, v18
	v_lshl_add_u64 v[24:25], v[20:21], 0, v[24:25]
	v_add_u32_e32 v4, 8, v22
	global_store_dwordx4 v[24:25], v[0:3], off sc1
	s_add_i32 s4, s1, 0x200
	s_addk_i32 s2, 0x4000
	v_cvt_pk_bf16_f32 v0, v7, v5
	v_ashrrev_i32_e32 v5, 31, v4
	v_cvt_pk_bf16_f32 v1, v9, v11
	v_cvt_pk_bf16_f32 v2, v13, v15
	v_cvt_pk_bf16_f32 v3, v17, v19
	v_lshlrev_b64 v[4:5], 11, v[4:5]
	ds_read2_b32 v[6:7], v40 offset0:49 offset1:57
	ds_read2_b32 v[8:9], v40 offset0:16 offset1:24
	ds_read2_b32 v[10:11], v40 offset0:82 offset1:90
	ds_read2_b32 v[12:13], v40 offset0:115 offset1:123
	ds_read2_b32 v[14:15], v40 offset0:148 offset1:156
	ds_read2_b32 v[16:17], v40 offset0:181 offset1:189
	ds_read2_b32 v[18:19], v40 offset0:214 offset1:222
	ds_read2_b32 v[24:25], v40 offset0:247 offset1:255
	v_lshl_add_u64 v[4:5], v[20:21], 0, v[4:5]
	global_store_dwordx4 v[4:5], v[0:3], off sc1
	v_add_u32_e32 v4, 16, v22
	v_ashrrev_i32_e32 v5, 31, v4
	v_lshlrev_b64 v[4:5], 11, v[4:5]
	s_waitcnt lgkmcnt(6)
	v_cvt_pk_bf16_f32 v0, v8, v6
	s_waitcnt lgkmcnt(4)
	v_cvt_pk_bf16_f32 v1, v10, v12
	s_waitcnt lgkmcnt(2)
	v_cvt_pk_bf16_f32 v2, v14, v16
	s_waitcnt lgkmcnt(0)
	v_cvt_pk_bf16_f32 v3, v18, v24
	v_lshl_add_u64 v[4:5], v[20:21], 0, v[4:5]
	global_store_dwordx4 v[4:5], v[0:3], off sc1
	v_add_u32_e32 v4, 24, v22
	v_ashrrev_i32_e32 v5, 31, v4
	v_lshlrev_b64 v[4:5], 11, v[4:5]
	v_cvt_pk_bf16_f32 v0, v9, v7
	v_cvt_pk_bf16_f32 v1, v11, v13
	v_cvt_pk_bf16_f32 v2, v15, v17
	v_cvt_pk_bf16_f32 v3, v19, v25
	v_lshl_add_u64 v[4:5], v[20:21], 0, v[4:5]
	global_store_dwordx4 v[4:5], v[0:3], off sc1
	s_waitcnt lgkmcnt(0)
	s_cmp_lt_i32 s1, 0
	s_mov_b32 s1, s4
	s_cbranch_scc0 .LBB0_2392

.LBB0_2394:
	s_or_b64 exec, exec, s[20:21]
	s_waitcnt vmcnt(0)
	ds_write2_b32 v41, v0, v1 offset1:1
	ds_write2_b32 v41, v2, v3 offset0:2 offset1:3
	v_add_u32_e32 v0, 0x420, v41
	ds_write2_b32 v0, v8, v9 offset1:1
	v_add_u32_e32 v0, 0x428, v41
	ds_write2_b32 v0, v10, v11 offset1:1
	v_add_u32_e32 v0, 0x840, v41
	ds_write2_b32 v0, v4, v5 offset1:1
	v_add_u32_e32 v0, 0x848, v41
	ds_write2_b32 v0, v6, v7 offset1:1
	v_add_u32_e32 v0, 0xc60, v41
	ds_write2_b32 v0, v16, v17 offset1:1
	v_add_u32_e32 v0, 0xc68, v41
	ds_write2_b32 v0, v18, v19 offset1:1
	v_add_u32_e32 v0, 0x1080, v41
	ds_write2_b32 v0, v12, v13 offset1:1
	v_add_u32_e32 v0, 0x1088, v41
	ds_write2_b32 v0, v14, v15 offset1:1
	v_add_u32_e32 v0, 0x14a0, v41
	ds_write2_b32 v0, v24, v25 offset1:1
	v_add_u32_e32 v0, 0x14a8, v41
	ds_write2_b32 v0, v26, v27 offset1:1
	v_add_u32_e32 v0, 0x18c0, v41
	ds_write2_b32 v0, v20, v21 offset1:1
	v_add_u32_e32 v0, 0x18c8, v41
	ds_write2_b32 v0, v22, v23 offset1:1
	v_add_u32_e32 v0, 0x1ce0, v41
	ds_write2_b32 v0, v28, v29 offset1:1
	v_add_u32_e32 v0, 0x1ce8, v41
	ds_write2_b32 v0, v30, v31 offset1:1
	s_waitcnt lgkmcnt(0)
	s_sub_i32 s4, 0, s4
	ds_read2_b32 v[4:5], v40 offset0:33 offset1:41
	ds_read2_b32 v[6:7], v40 offset1:8
	ds_read2_b32 v[8:9], v40 offset0:66 offset1:74
	ds_read2_b32 v[10:11], v40 offset0:99 offset1:107
	ds_read2_b32 v[12:13], v40 offset0:132 offset1:140
	ds_read2_b32 v[14:15], v40 offset0:165 offset1:173
	ds_read2_b32 v[16:17], v40 offset0:198 offset1:206
	ds_read2_b32 v[18:19], v40 offset0:231 offset1:239
	s_add_i32 s4, s4, s2
	v_add_u32_e32 v22, s4, v39
	s_ashr_i32 s13, s12, 31
	v_ashrrev_i32_e32 v23, 31, v22
	v_lshl_add_u64 v[20:21], s[12:13], 1, v[32:33]
	v_lshlrev_b64 v[24:25], 12, v[22:23]
	s_waitcnt lgkmcnt(6)
	v_cvt_pk_bf16_f32 v0, v6, v4
	s_waitcnt lgkmcnt(4)
	v_cvt_pk_bf16_f32 v1, v8, v10
	s_waitcnt lgkmcnt(2)
	v_cvt_pk_bf16_f32 v2, v12, v14
	s_waitcnt lgkmcnt(0)
	v_cvt_pk_bf16_f32 v3, v16, v18
	v_lshl_add_u64 v[24:25], v[20:21], 0, v[24:25]
	v_add_u32_e32 v4, 8, v22
	global_store_dwordx4 v[24:25], v[0:3], off sc1
	s_add_i32 s4, s1, 0x200
	s_addk_i32 s2, 0x4000
	v_cvt_pk_bf16_f32 v0, v7, v5
	v_ashrrev_i32_e32 v5, 31, v4
	v_cvt_pk_bf16_f32 v1, v9, v11
	v_cvt_pk_bf16_f32 v2, v13, v15
	v_cvt_pk_bf16_f32 v3, v17, v19
	v_lshlrev_b64 v[4:5], 12, v[4:5]
	ds_read2_b32 v[6:7], v40 offset0:49 offset1:57
	ds_read2_b32 v[8:9], v40 offset0:16 offset1:24
	ds_read2_b32 v[10:11], v40 offset0:82 offset1:90
	ds_read2_b32 v[12:13], v40 offset0:115 offset1:123
	ds_read2_b32 v[14:15], v40 offset0:148 offset1:156
	ds_read2_b32 v[16:17], v40 offset0:181 offset1:189
	ds_read2_b32 v[18:19], v40 offset0:214 offset1:222
	ds_read2_b32 v[24:25], v40 offset0:247 offset1:255
	v_lshl_add_u64 v[4:5], v[20:21], 0, v[4:5]
	global_store_dwordx4 v[4:5], v[0:3], off sc1
	v_add_u32_e32 v4, 16, v22
	v_ashrrev_i32_e32 v5, 31, v4
	v_lshlrev_b64 v[4:5], 12, v[4:5]
	s_waitcnt lgkmcnt(6)
	v_cvt_pk_bf16_f32 v0, v8, v6
	s_waitcnt lgkmcnt(4)
	v_cvt_pk_bf16_f32 v1, v10, v12
	s_waitcnt lgkmcnt(2)
	v_cvt_pk_bf16_f32 v2, v14, v16
	s_waitcnt lgkmcnt(0)
	v_cvt_pk_bf16_f32 v3, v18, v24
	v_lshl_add_u64 v[4:5], v[20:21], 0, v[4:5]
	global_store_dwordx4 v[4:5], v[0:3], off sc1
	v_add_u32_e32 v4, 24, v22
	v_ashrrev_i32_e32 v5, 31, v4
	v_lshlrev_b64 v[4:5], 12, v[4:5]
	v_cvt_pk_bf16_f32 v0, v9, v7
	v_cvt_pk_bf16_f32 v1, v11, v13
	v_cvt_pk_bf16_f32 v2, v15, v17
	v_cvt_pk_bf16_f32 v3, v19, v25
	v_lshl_add_u64 v[4:5], v[20:21], 0, v[4:5]
	global_store_dwordx4 v[4:5], v[0:3], off sc1
	s_waitcnt lgkmcnt(0)
	s_cmpk_lt_i32 s1, 0xff00
	s_mov_b32 s1, s4
	s_cbranch_scc0 .LBB0_2411

.LBB0_2432:
	s_or_b64 exec, exec, s[20:21]
	s_waitcnt vmcnt(0)
	ds_write2_b32 v41, v0, v1 offset1:1
	ds_write2_b32 v41, v2, v3 offset0:2 offset1:3
	v_add_u32_e32 v0, 0x420, v41
	ds_write2_b32 v0, v8, v9 offset1:1
	v_add_u32_e32 v0, 0x428, v41
	ds_write2_b32 v0, v10, v11 offset1:1
	v_add_u32_e32 v0, 0x840, v41
	ds_write2_b32 v0, v4, v5 offset1:1
	v_add_u32_e32 v0, 0x848, v41
	ds_write2_b32 v0, v6, v7 offset1:1
	v_add_u32_e32 v0, 0xc60, v41
	ds_write2_b32 v0, v16, v17 offset1:1
	v_add_u32_e32 v0, 0xc68, v41
	ds_write2_b32 v0, v18, v19 offset1:1
	v_add_u32_e32 v0, 0x1080, v41
	ds_write2_b32 v0, v12, v13 offset1:1
	v_add_u32_e32 v0, 0x1088, v41
	ds_write2_b32 v0, v14, v15 offset1:1
	v_add_u32_e32 v0, 0x14a0, v41
	ds_write2_b32 v0, v24, v25 offset1:1
	v_add_u32_e32 v0, 0x14a8, v41
	ds_write2_b32 v0, v26, v27 offset1:1
	v_add_u32_e32 v0, 0x18c0, v41
	ds_write2_b32 v0, v20, v21 offset1:1
	v_add_u32_e32 v0, 0x18c8, v41
	ds_write2_b32 v0, v22, v23 offset1:1
	v_add_u32_e32 v0, 0x1ce0, v41
	ds_write2_b32 v0, v28, v29 offset1:1
	v_add_u32_e32 v0, 0x1ce8, v41
	ds_write2_b32 v0, v30, v31 offset1:1
	s_waitcnt lgkmcnt(0)
	s_sub_i32 s3, 0, s3
	ds_read2_b32 v[4:5], v40 offset0:33 offset1:41
	ds_read2_b32 v[6:7], v40 offset1:8
	ds_read2_b32 v[8:9], v40 offset0:66 offset1:74
	ds_read2_b32 v[10:11], v40 offset0:99 offset1:107
	ds_read2_b32 v[12:13], v40 offset0:132 offset1:140
	ds_read2_b32 v[14:15], v40 offset0:165 offset1:173
	ds_read2_b32 v[16:17], v40 offset0:198 offset1:206
	ds_read2_b32 v[18:19], v40 offset0:231 offset1:239
	s_add_i32 s3, s3, s2
	v_add_u32_e32 v22, s3, v39
	s_ashr_i32 s13, s12, 31
	v_ashrrev_i32_e32 v23, 31, v22
	v_lshl_add_u64 v[20:21], s[12:13], 1, v[32:33]
	v_lshlrev_b64 v[24:25], 9, v[22:23]
	s_waitcnt lgkmcnt(6)
	v_cvt_pk_bf16_f32 v0, v6, v4
	s_waitcnt lgkmcnt(4)
	v_cvt_pk_bf16_f32 v1, v8, v10
	s_waitcnt lgkmcnt(2)
	v_cvt_pk_bf16_f32 v2, v12, v14
	s_waitcnt lgkmcnt(0)
	v_cvt_pk_bf16_f32 v3, v16, v18
	v_lshl_add_u64 v[24:25], v[20:21], 0, v[24:25]
	v_add_u32_e32 v4, 8, v22
	global_store_dwordx4 v[24:25], v[0:3], off sc1
	s_add_i32 s3, s1, 0x200
	s_addk_i32 s2, 0x4000
	v_cvt_pk_bf16_f32 v0, v7, v5
	v_ashrrev_i32_e32 v5, 31, v4
	v_cvt_pk_bf16_f32 v1, v9, v11
	v_cvt_pk_bf16_f32 v2, v13, v15
	v_cvt_pk_bf16_f32 v3, v17, v19
	v_lshlrev_b64 v[4:5], 9, v[4:5]
	ds_read2_b32 v[6:7], v40 offset0:49 offset1:57
	ds_read2_b32 v[8:9], v40 offset0:16 offset1:24
	ds_read2_b32 v[10:11], v40 offset0:82 offset1:90
	ds_read2_b32 v[12:13], v40 offset0:115 offset1:123
	ds_read2_b32 v[14:15], v40 offset0:148 offset1:156
	ds_read2_b32 v[16:17], v40 offset0:181 offset1:189
	ds_read2_b32 v[18:19], v40 offset0:214 offset1:222
	ds_read2_b32 v[24:25], v40 offset0:247 offset1:255
	v_lshl_add_u64 v[4:5], v[20:21], 0, v[4:5]
	global_store_dwordx4 v[4:5], v[0:3], off sc1
	v_add_u32_e32 v4, 16, v22
	v_ashrrev_i32_e32 v5, 31, v4
	v_lshlrev_b64 v[4:5], 9, v[4:5]
	s_waitcnt lgkmcnt(6)
	v_cvt_pk_bf16_f32 v0, v8, v6
	s_waitcnt lgkmcnt(4)
	v_cvt_pk_bf16_f32 v1, v10, v12
	s_waitcnt lgkmcnt(2)
	v_cvt_pk_bf16_f32 v2, v14, v16
	s_waitcnt lgkmcnt(0)
	v_cvt_pk_bf16_f32 v3, v18, v24
	v_lshl_add_u64 v[4:5], v[20:21], 0, v[4:5]
	global_store_dwordx4 v[4:5], v[0:3], off sc1
	v_add_u32_e32 v4, 24, v22
	v_ashrrev_i32_e32 v5, 31, v4
	v_lshlrev_b64 v[4:5], 9, v[4:5]
	v_cvt_pk_bf16_f32 v0, v9, v7
	v_cvt_pk_bf16_f32 v1, v11, v13
	v_cvt_pk_bf16_f32 v2, v15, v17
	v_cvt_pk_bf16_f32 v3, v19, v25
	v_lshl_add_u64 v[4:5], v[20:21], 0, v[4:5]
	global_store_dwordx4 v[4:5], v[0:3], off sc1
	s_waitcnt lgkmcnt(0)
	s_cmpk_lt_i32 s1, 0xfe20
	s_mov_b32 s1, s3
	s_cbranch_scc0 .LBB0_2449

.LBB0_2451:
	s_or_b64 exec, exec, s[20:21]
	s_waitcnt vmcnt(0)
	ds_write2_b32 v41, v0, v1 offset1:1
	ds_write2_b32 v41, v2, v3 offset0:2 offset1:3
	v_add_u32_e32 v0, 0x420, v41
	ds_write2_b32 v0, v8, v9 offset1:1
	v_add_u32_e32 v0, 0x428, v41
	ds_write2_b32 v0, v10, v11 offset1:1
	v_add_u32_e32 v0, 0x840, v41
	ds_write2_b32 v0, v4, v5 offset1:1
	v_add_u32_e32 v0, 0x848, v41
	ds_write2_b32 v0, v6, v7 offset1:1
	v_add_u32_e32 v0, 0xc60, v41
	ds_write2_b32 v0, v16, v17 offset1:1
	v_add_u32_e32 v0, 0xc68, v41
	ds_write2_b32 v0, v18, v19 offset1:1
	v_add_u32_e32 v0, 0x1080, v41
	ds_write2_b32 v0, v12, v13 offset1:1
	v_add_u32_e32 v0, 0x1088, v41
	ds_write2_b32 v0, v14, v15 offset1:1
	v_add_u32_e32 v0, 0x14a0, v41
	ds_write2_b32 v0, v24, v25 offset1:1
	v_add_u32_e32 v0, 0x14a8, v41
	ds_write2_b32 v0, v26, v27 offset1:1
	v_add_u32_e32 v0, 0x18c0, v41
	ds_write2_b32 v0, v20, v21 offset1:1
	v_add_u32_e32 v0, 0x18c8, v41
	ds_write2_b32 v0, v22, v23 offset1:1
	v_add_u32_e32 v0, 0x1ce0, v41
	ds_write2_b32 v0, v28, v29 offset1:1
	v_add_u32_e32 v0, 0x1ce8, v41
	ds_write2_b32 v0, v30, v31 offset1:1
	s_waitcnt lgkmcnt(0)
	s_sub_i32 s2, 0, s2
	ds_read2_b32 v[4:5], v40 offset0:33 offset1:41
	ds_read2_b32 v[6:7], v40 offset1:8
	ds_read2_b32 v[8:9], v40 offset0:66 offset1:74
	ds_read2_b32 v[10:11], v40 offset0:99 offset1:107
	ds_read2_b32 v[12:13], v40 offset0:132 offset1:140
	ds_read2_b32 v[14:15], v40 offset0:165 offset1:173
	ds_read2_b32 v[16:17], v40 offset0:198 offset1:206
	ds_read2_b32 v[18:19], v40 offset0:231 offset1:239
	s_add_i32 s2, s2, s1
	v_add_u32_e32 v22, s2, v39
	s_ashr_i32 s13, s12, 31
	v_ashrrev_i32_e32 v23, 31, v22
	v_lshl_add_u64 v[20:21], s[12:13], 1, v[32:33]
	v_lshlrev_b64 v[24:25], 9, v[22:23]
	s_waitcnt lgkmcnt(6)
	v_cvt_pk_bf16_f32 v0, v6, v4
	s_waitcnt lgkmcnt(4)
	v_cvt_pk_bf16_f32 v1, v8, v10
	s_waitcnt lgkmcnt(2)
	v_cvt_pk_bf16_f32 v2, v12, v14
	s_waitcnt lgkmcnt(0)
	v_cvt_pk_bf16_f32 v3, v16, v18
	v_lshl_add_u64 v[24:25], v[20:21], 0, v[24:25]
	v_add_u32_e32 v4, 8, v22
	global_store_dwordx4 v[24:25], v[0:3], off sc1
	s_add_i32 s2, s0, 0x200
	s_addk_i32 s1, 0x4000
	v_cvt_pk_bf16_f32 v0, v7, v5
	v_ashrrev_i32_e32 v5, 31, v4
	v_cvt_pk_bf16_f32 v1, v9, v11
	v_cvt_pk_bf16_f32 v2, v13, v15
	v_cvt_pk_bf16_f32 v3, v17, v19
	v_lshlrev_b64 v[4:5], 9, v[4:5]
	ds_read2_b32 v[6:7], v40 offset0:49 offset1:57
	ds_read2_b32 v[8:9], v40 offset0:16 offset1:24
	ds_read2_b32 v[10:11], v40 offset0:82 offset1:90
	ds_read2_b32 v[12:13], v40 offset0:115 offset1:123
	ds_read2_b32 v[14:15], v40 offset0:148 offset1:156
	ds_read2_b32 v[16:17], v40 offset0:181 offset1:189
	ds_read2_b32 v[18:19], v40 offset0:214 offset1:222
	ds_read2_b32 v[24:25], v40 offset0:247 offset1:255
	v_lshl_add_u64 v[4:5], v[20:21], 0, v[4:5]
	global_store_dwordx4 v[4:5], v[0:3], off sc1
	v_add_u32_e32 v4, 16, v22
	v_ashrrev_i32_e32 v5, 31, v4
	v_lshlrev_b64 v[4:5], 9, v[4:5]
	s_waitcnt lgkmcnt(6)
	v_cvt_pk_bf16_f32 v0, v8, v6
	s_waitcnt lgkmcnt(4)
	v_cvt_pk_bf16_f32 v1, v10, v12
	s_waitcnt lgkmcnt(2)
	v_cvt_pk_bf16_f32 v2, v14, v16
	s_waitcnt lgkmcnt(0)
	v_cvt_pk_bf16_f32 v3, v18, v24
	v_lshl_add_u64 v[4:5], v[20:21], 0, v[4:5]
	global_store_dwordx4 v[4:5], v[0:3], off sc1
	v_add_u32_e32 v4, 24, v22
	v_ashrrev_i32_e32 v5, 31, v4
	v_lshlrev_b64 v[4:5], 9, v[4:5]
	v_cvt_pk_bf16_f32 v0, v9, v7
	v_cvt_pk_bf16_f32 v1, v11, v13
	v_cvt_pk_bf16_f32 v2, v15, v17
	v_cvt_pk_bf16_f32 v3, v19, v25
	v_lshl_add_u64 v[4:5], v[20:21], 0, v[4:5]
	global_store_dwordx4 v[4:5], v[0:3], off sc1
	s_waitcnt lgkmcnt(0)
	s_cmpk_lt_i32 s0, 0xfe20
	s_mov_b32 s0, s2
	s_cbranch_scc0 .LBB0_2468

.LBB0_2563:
	s_andn2_saveexec_b64 s[74:75], s[74:75]
	v_mul_f32_e32 v162, v159, v159
	v_fmamk_f32 v163, v162, 0xbbbac73d, v153
	v_fmaak_f32 v163, v162, v163, 0xbd5c1c4e
	v_fmaak_f32 v163, v162, v163, 0x3e088382
	v_fmaak_f32 v163, v162, v163, 0xbeaaaa99
	v_mul_f32_e64 v163, |v159|, v163
	v_fma_f32 v162, v162, v163, |v159|
	s_or_b64 exec, exec, s[74:75]
	v_bfi_b32 v157, s45, v158, v157
	v_mul_f32_e32 v126, 0.5, v126
	v_add_f32_e32 v157, 1.0, v157
	v_mul_f32_e32 v157, v126, v157
	v_mul_f32_e32 v126, 0.5, v127
	v_bfi_b32 v127, s45, v129, v128
	v_mul_f32_e32 v124, 0.5, v124
	v_add_f32_e32 v127, 1.0, v127
	v_mul_f32_e32 v127, v124, v127
	v_mul_f32_e32 v124, 0.5, v125
	v_bfi_b32 v125, s45, v131, v130
	v_lshl_add_u32 v128, s72, 8, v148
	v_add_f32_e32 v125, 1.0, v125
	v_ashrrev_i32_e32 v129, 31, v128
	v_mul_f32_e32 v130, v124, v125
	v_lshlrev_b64 v[124:125], 9, v[128:129]
	v_bfi_b32 v129, s45, v162, v159
	v_add_f32_e32 v129, 1.0, v129
	v_mul_f32_e32 v129, v126, v129
	v_lshl_add_u64 v[124:125], s[18:19], 0, v[124:125]
	v_cvt_pk_bf16_f32 v126, v127, v130
	v_cvt_pk_bf16_f32 v127, v157, v129
	v_lshl_add_u64 v[130:131], v[146:147], 1, v[124:125]
	global_store_dwordx2 v[130:131], v[126:127], off sc1
	global_load_dwordx4 v[124:127], v[144:145], off offset:64
	s_waitcnt vmcnt(0)
	v_pk_add_f32 v[120:121], v[120:121], v[124:125]
	s_nop 0
	v_mul_f32_e32 v124, 0x3d372713, v120
	v_mul_f32_e32 v124, v120, v124
	v_fma_f32 v124, v120, v124, v120
	v_mul_f32_e32 v124, 0x3f4c422a, v124
	v_cmp_nlt_f32_e64 s[58:59], |v124|, s40
	s_and_saveexec_b64 s[60:61], s[58:59]
	s_xor_b64 s[72:73], exec, s[60:61]
	s_cbranch_execz .LBB0_2567
	v_add_f32_e64 v125, |v124|, |v124|
	v_mul_f32_e32 v129, 0x3fb8aa3b, v125
	v_rndne_f32_e32 v157, v129
	v_sub_f32_e32 v158, v129, v157
	v_fma_f32 v129, v125, s42, -v129
	v_fmac_f32_e32 v129, 0x32a5705f, v125
	v_add_f32_e32 v129, v158, v129
	v_cvt_i32_f32_e32 v157, v157
	v_exp_f32_e32 v129, v129
	v_cmp_ngt_f32_e32 vcc, s43, v125
	v_ldexp_f32 v129, v129, v157
	s_nop 0
	v_cndmask_b32_e32 v129, 0, v129, vcc
	v_cmp_nlt_f32_e32 vcc, s44, v125
	s_nop 1
	v_cndmask_b32_e32 v125, v156, v129, vcc
	v_add_f32_e32 v125, 1.0, v125
	v_rcp_f32_e32 v125, v125
	s_nop 0
	v_fma_f32 v125, v125, -2.0, 1.0

.LBB0_2579:
	s_andn2_saveexec_b64 s[72:73], s[72:73]
	v_mul_f32_e32 v159, v158, v158
	v_fmamk_f32 v162, v159, 0xbbbac73d, v153
	v_fmaak_f32 v162, v159, v162, 0xbd5c1c4e
	v_fmaak_f32 v162, v159, v162, 0x3e088382
	v_fmaak_f32 v162, v159, v162, 0xbeaaaa99
	v_mul_f32_e64 v162, |v158|, v162
	v_fma_f32 v159, v159, v162, |v158|
	s_or_b64 exec, exec, s[72:73]
	v_bfi_b32 v124, s45, v125, v124
	v_mul_f32_e32 v120, 0.5, v120
	v_add_f32_e32 v124, 1.0, v124
	v_mul_f32_e32 v120, v120, v124
	v_bfi_b32 v124, s45, v127, v126
	v_mul_f32_e32 v121, 0.5, v121
	v_add_f32_e32 v124, 1.0, v124
	v_bfi_b32 v129, s45, v157, v129
	v_mul_f32_e32 v121, v121, v124
	v_bfi_b32 v124, s45, v159, v158
	v_mul_f32_e32 v122, 0.5, v122
	v_add_f32_e32 v129, 1.0, v129
	v_mul_f32_e32 v123, 0.5, v123
	v_add_f32_e32 v124, 1.0, v124
	v_mul_f32_e32 v122, v122, v129
	v_mul_f32_e32 v123, v123, v124
	v_cvt_pk_bf16_f32 v120, v120, v121
	v_cvt_pk_bf16_f32 v121, v122, v123
	global_store_dwordx2 v[130:131], v[120:121], off offset:32 sc1
	global_load_dwordx4 v[120:123], v[144:145], off offset:512
	s_waitcnt vmcnt(0)
	v_pk_add_f32 v[116:117], v[116:117], v[120:121]
	s_nop 0
	v_mul_f32_e32 v120, 0x3d372713, v116
	v_mul_f32_e32 v120, v116, v120
	v_fma_f32 v120, v116, v120, v116
	v_mul_f32_e32 v120, 0x3f4c422a, v120
	v_cmp_nlt_f32_e64 s[58:59], |v120|, s40
	s_and_saveexec_b64 s[60:61], s[58:59]
	s_xor_b64 s[72:73], exec, s[60:61]
	s_cbranch_execz .LBB0_2583
	v_add_f32_e64 v121, |v120|, |v120|
	v_mul_f32_e32 v124, 0x3fb8aa3b, v121
	v_rndne_f32_e32 v125, v124
	v_sub_f32_e32 v126, v124, v125
	v_fma_f32 v124, v121, s42, -v124
	v_fmac_f32_e32 v124, 0x32a5705f, v121
	v_add_f32_e32 v124, v126, v124
	v_cvt_i32_f32_e32 v125, v125
	v_exp_f32_e32 v124, v124
	v_cmp_ngt_f32_e32 vcc, s43, v121
	v_ldexp_f32 v124, v124, v125
	s_nop 0
	v_cndmask_b32_e32 v124, 0, v124, vcc
	v_cmp_nlt_f32_e32 vcc, s44, v121
	s_nop 1
	v_cndmask_b32_e32 v121, v156, v124, vcc
	v_add_f32_e32 v121, 1.0, v121
	v_rcp_f32_e32 v121, v121
	s_nop 0
	v_fma_f32 v121, v121, -2.0, 1.0

.LBB0_2595:
	s_andn2_saveexec_b64 s[72:73], s[72:73]
	v_mul_f32_e32 v127, v126, v126
	v_fmamk_f32 v129, v127, 0xbbbac73d, v153
	v_fmaak_f32 v129, v127, v129, 0xbd5c1c4e
	v_fmaak_f32 v129, v127, v129, 0x3e088382
	v_fmaak_f32 v129, v127, v129, 0xbeaaaa99
	v_mul_f32_e64 v129, |v126|, v129
	v_fma_f32 v127, v127, v129, |v126|
	s_or_b64 exec, exec, s[72:73]
	v_bfi_b32 v120, s45, v121, v120
	v_mul_f32_e32 v116, 0.5, v116
	v_add_f32_e32 v120, 1.0, v120
	v_mul_f32_e32 v116, v116, v120
	v_bfi_b32 v120, s45, v123, v122
	v_mul_f32_e32 v117, 0.5, v117
	v_add_f32_e32 v120, 1.0, v120
	v_bfi_b32 v124, s45, v125, v124
	v_mul_f32_e32 v117, v117, v120
	v_bfi_b32 v120, s45, v127, v126
	v_mul_f32_e32 v118, 0.5, v118
	v_add_f32_e32 v124, 1.0, v124
	v_mul_f32_e32 v119, 0.5, v119
	v_add_f32_e32 v120, 1.0, v120
	v_mul_f32_e32 v118, v118, v124
	v_mul_f32_e32 v119, v119, v120
	v_cvt_pk_bf16_f32 v116, v116, v117
	v_cvt_pk_bf16_f32 v117, v118, v119
	global_store_dwordx2 v[130:131], v[116:117], off offset:256 sc1
	global_load_dwordx4 v[116:119], v[144:145], off offset:576
	s_waitcnt vmcnt(0)
	v_pk_add_f32 v[112:113], v[112:113], v[116:117]
	s_nop 0
	v_mul_f32_e32 v116, 0x3d372713, v112
	v_mul_f32_e32 v116, v112, v116
	v_fma_f32 v116, v112, v116, v112
	v_mul_f32_e32 v116, 0x3f4c422a, v116
	v_cmp_nlt_f32_e64 s[58:59], |v116|, s40
	s_and_saveexec_b64 s[60:61], s[58:59]
	s_xor_b64 s[72:73], exec, s[60:61]
	s_cbranch_execz .LBB0_2599
	v_add_f32_e64 v117, |v116|, |v116|
	v_mul_f32_e32 v120, 0x3fb8aa3b, v117
	v_rndne_f32_e32 v121, v120
	v_sub_f32_e32 v122, v120, v121
	v_fma_f32 v120, v117, s42, -v120
	v_fmac_f32_e32 v120, 0x32a5705f, v117
	v_add_f32_e32 v120, v122, v120
	v_cvt_i32_f32_e32 v121, v121
	v_exp_f32_e32 v120, v120
	v_cmp_ngt_f32_e32 vcc, s43, v117
	v_ldexp_f32 v120, v120, v121
	s_nop 0
	v_cndmask_b32_e32 v120, 0, v120, vcc
	v_cmp_nlt_f32_e32 vcc, s44, v117
	s_nop 1
	v_cndmask_b32_e32 v117, v156, v120, vcc
	v_add_f32_e32 v117, 1.0, v117
	v_rcp_f32_e32 v117, v117
	s_nop 0
	v_fma_f32 v117, v117, -2.0, 1.0

.LBB0_2611:
	s_andn2_saveexec_b64 s[72:73], s[72:73]
	v_mul_f32_e32 v123, v122, v122
	v_fmamk_f32 v124, v123, 0xbbbac73d, v153
	v_fmaak_f32 v124, v123, v124, 0xbd5c1c4e
	v_fmaak_f32 v124, v123, v124, 0x3e088382
	v_fmaak_f32 v124, v123, v124, 0xbeaaaa99
	v_mul_f32_e64 v124, |v122|, v124
	v_fma_f32 v123, v123, v124, |v122|
	s_or_b64 exec, exec, s[72:73]
	v_bfi_b32 v116, s45, v117, v116
	v_mul_f32_e32 v112, 0.5, v112
	v_add_f32_e32 v116, 1.0, v116
	v_mul_f32_e32 v112, v112, v116
	v_bfi_b32 v116, s45, v119, v118
	v_mul_f32_e32 v113, 0.5, v113
	v_add_f32_e32 v116, 1.0, v116
	v_bfi_b32 v120, s45, v121, v120
	v_mul_f32_e32 v113, v113, v116
	v_bfi_b32 v116, s45, v123, v122
	v_mul_f32_e32 v114, 0.5, v114
	v_add_f32_e32 v120, 1.0, v120
	v_mul_f32_e32 v115, 0.5, v115
	v_add_f32_e32 v116, 1.0, v116
	v_mul_f32_e32 v114, v114, v120
	v_mul_f32_e32 v115, v115, v116
	v_cvt_pk_bf16_f32 v112, v112, v113
	v_cvt_pk_bf16_f32 v113, v114, v115
	global_store_dwordx2 v[130:131], v[112:113], off offset:288 sc1
	global_load_dwordx4 v[112:115], v[144:145], off
	s_waitcnt vmcnt(0)
	v_pk_add_f32 v[108:109], v[108:109], v[112:113]
	s_nop 0
	v_mul_f32_e32 v112, 0x3d372713, v108
	v_mul_f32_e32 v112, v108, v112
	v_fma_f32 v112, v108, v112, v108
	v_mul_f32_e32 v112, 0x3f4c422a, v112
	v_cmp_nlt_f32_e64 s[58:59], |v112|, s40
	s_and_saveexec_b64 s[60:61], s[58:59]
	s_xor_b64 s[72:73], exec, s[60:61]
	s_cbranch_execz .LBB0_2615
	v_add_f32_e64 v113, |v112|, |v112|
	v_mul_f32_e32 v116, 0x3fb8aa3b, v113
	v_rndne_f32_e32 v117, v116
	v_sub_f32_e32 v118, v116, v117
	v_fma_f32 v116, v113, s42, -v116
	v_fmac_f32_e32 v116, 0x32a5705f, v113
	v_add_f32_e32 v116, v118, v116
	v_cvt_i32_f32_e32 v117, v117
	v_exp_f32_e32 v116, v116
	v_cmp_ngt_f32_e32 vcc, s43, v113
	v_ldexp_f32 v116, v116, v117
	s_nop 0
	v_cndmask_b32_e32 v116, 0, v116, vcc
	v_cmp_nlt_f32_e32 vcc, s44, v113
	s_nop 1
	v_cndmask_b32_e32 v113, v156, v116, vcc
	v_add_f32_e32 v113, 1.0, v113
	v_rcp_f32_e32 v113, v113
	s_nop 0
	v_fma_f32 v113, v113, -2.0, 1.0

.LBB0_2627:
	s_andn2_saveexec_b64 s[72:73], s[72:73]
	v_mul_f32_e32 v119, v118, v118
	v_fmamk_f32 v120, v119, 0xbbbac73d, v153
	v_fmaak_f32 v120, v119, v120, 0xbd5c1c4e
	v_fmaak_f32 v120, v119, v120, 0x3e088382
	v_fmaak_f32 v120, v119, v120, 0xbeaaaa99
	v_mul_f32_e64 v120, |v118|, v120
	v_fma_f32 v119, v119, v120, |v118|
	s_or_b64 exec, exec, s[72:73]
	v_bfi_b32 v116, s45, v117, v116
	v_mul_f32_e32 v110, 0.5, v110
	v_add_f32_e32 v116, 1.0, v116
	v_mul_f32_e32 v116, v110, v116
	v_mul_f32_e32 v110, 0.5, v111
	v_bfi_b32 v111, s45, v113, v112
	v_mul_f32_e32 v108, 0.5, v108
	v_add_f32_e32 v111, 1.0, v111
	v_mul_f32_e32 v111, v108, v111
	v_mul_f32_e32 v108, 0.5, v109
	v_bfi_b32 v109, s45, v115, v114
	v_add_f32_e32 v109, 1.0, v109
	v_mul_f32_e32 v112, v108, v109
	v_or_b32_e32 v108, 16, v128
	v_ashrrev_i32_e32 v109, 31, v108
	v_bfi_b32 v113, s45, v119, v118
	v_lshlrev_b64 v[108:109], 9, v[108:109]
	v_add_f32_e32 v113, 1.0, v113
	v_mul_f32_e32 v113, v110, v113
	v_lshl_add_u64 v[108:109], s[18:19], 0, v[108:109]
	v_cvt_pk_bf16_f32 v110, v111, v112
	v_cvt_pk_bf16_f32 v111, v116, v113
	v_lshl_add_u64 v[112:113], v[146:147], 1, v[108:109]
	global_store_dwordx2 v[112:113], v[110:111], off sc1
	global_load_dwordx4 v[108:111], v[144:145], off offset:64
	s_waitcnt vmcnt(0)
	v_pk_add_f32 v[104:105], v[104:105], v[108:109]
	s_nop 0
	v_mul_f32_e32 v108, 0x3d372713, v104
	v_mul_f32_e32 v108, v104, v108
	v_fma_f32 v108, v104, v108, v104
	v_mul_f32_e32 v108, 0x3f4c422a, v108
	v_cmp_nlt_f32_e64 s[58:59], |v108|, s40
	s_and_saveexec_b64 s[60:61], s[58:59]
	s_xor_b64 s[72:73], exec, s[60:61]
	s_cbranch_execz .LBB0_2631
	v_add_f32_e64 v109, |v108|, |v108|
	v_mul_f32_e32 v114, 0x3fb8aa3b, v109
	v_rndne_f32_e32 v115, v114
	v_sub_f32_e32 v116, v114, v115
	v_fma_f32 v114, v109, s42, -v114
	v_fmac_f32_e32 v114, 0x32a5705f, v109
	v_add_f32_e32 v114, v116, v114
	v_cvt_i32_f32_e32 v115, v115
	v_exp_f32_e32 v114, v114
	v_cmp_ngt_f32_e32 vcc, s43, v109
	v_ldexp_f32 v114, v114, v115
	s_nop 0
	v_cndmask_b32_e32 v114, 0, v114, vcc
	v_cmp_nlt_f32_e32 vcc, s44, v109
	s_nop 1
	v_cndmask_b32_e32 v109, v156, v114, vcc
	v_add_f32_e32 v109, 1.0, v109
	v_rcp_f32_e32 v109, v109
	s_nop 0
	v_fma_f32 v109, v109, -2.0, 1.0

.LBB0_2643:
	s_andn2_saveexec_b64 s[72:73], s[72:73]
	v_mul_f32_e32 v117, v116, v116
	v_fmamk_f32 v118, v117, 0xbbbac73d, v153
	v_fmaak_f32 v118, v117, v118, 0xbd5c1c4e
	v_fmaak_f32 v118, v117, v118, 0x3e088382
	v_fmaak_f32 v118, v117, v118, 0xbeaaaa99
	v_mul_f32_e64 v118, |v116|, v118
	v_fma_f32 v117, v117, v118, |v116|
	s_or_b64 exec, exec, s[72:73]
	v_bfi_b32 v108, s45, v109, v108
	v_mul_f32_e32 v104, 0.5, v104
	v_add_f32_e32 v108, 1.0, v108
	v_mul_f32_e32 v104, v104, v108
	v_bfi_b32 v108, s45, v111, v110
	v_mul_f32_e32 v105, 0.5, v105
	v_add_f32_e32 v108, 1.0, v108
	v_bfi_b32 v114, s45, v115, v114
	v_mul_f32_e32 v105, v105, v108
	v_bfi_b32 v108, s45, v117, v116
	v_mul_f32_e32 v106, 0.5, v106
	v_add_f32_e32 v114, 1.0, v114
	v_mul_f32_e32 v107, 0.5, v107
	v_add_f32_e32 v108, 1.0, v108
	v_mul_f32_e32 v106, v106, v114
	v_mul_f32_e32 v107, v107, v108
	v_cvt_pk_bf16_f32 v104, v104, v105
	v_cvt_pk_bf16_f32 v105, v106, v107
	global_store_dwordx2 v[112:113], v[104:105], off offset:32 sc1
	global_load_dwordx4 v[104:107], v[144:145], off offset:512
	s_waitcnt vmcnt(0)
	v_pk_add_f32 v[100:101], v[100:101], v[104:105]
	s_nop 0
	v_mul_f32_e32 v104, 0x3d372713, v100
	v_mul_f32_e32 v104, v100, v104
	v_fma_f32 v104, v100, v104, v100
	v_mul_f32_e32 v104, 0x3f4c422a, v104
	v_cmp_nlt_f32_e64 s[58:59], |v104|, s40
	s_and_saveexec_b64 s[60:61], s[58:59]
	s_xor_b64 s[72:73], exec, s[60:61]
	s_cbranch_execz .LBB0_2647
	v_add_f32_e64 v105, |v104|, |v104|
	v_mul_f32_e32 v108, 0x3fb8aa3b, v105
	v_rndne_f32_e32 v109, v108
	v_sub_f32_e32 v110, v108, v109
	v_fma_f32 v108, v105, s42, -v108
	v_fmac_f32_e32 v108, 0x32a5705f, v105
	v_add_f32_e32 v108, v110, v108
	v_cvt_i32_f32_e32 v109, v109
	v_exp_f32_e32 v108, v108
	v_cmp_ngt_f32_e32 vcc, s43, v105
	v_ldexp_f32 v108, v108, v109
	s_nop 0
	v_cndmask_b32_e32 v108, 0, v108, vcc
	v_cmp_nlt_f32_e32 vcc, s44, v105
	s_nop 1
	v_cndmask_b32_e32 v105, v156, v108, vcc
	v_add_f32_e32 v105, 1.0, v105
	v_rcp_f32_e32 v105, v105
	s_nop 0
	v_fma_f32 v105, v105, -2.0, 1.0

.LBB0_2659:
	s_andn2_saveexec_b64 s[72:73], s[72:73]
	v_mul_f32_e32 v111, v110, v110
	v_fmamk_f32 v114, v111, 0xbbbac73d, v153
	v_fmaak_f32 v114, v111, v114, 0xbd5c1c4e
	v_fmaak_f32 v114, v111, v114, 0x3e088382
	v_fmaak_f32 v114, v111, v114, 0xbeaaaa99
	v_mul_f32_e64 v114, |v110|, v114
	v_fma_f32 v111, v111, v114, |v110|
	s_or_b64 exec, exec, s[72:73]
	v_bfi_b32 v104, s45, v105, v104
	v_mul_f32_e32 v100, 0.5, v100
	v_add_f32_e32 v104, 1.0, v104
	v_mul_f32_e32 v100, v100, v104
	v_bfi_b32 v104, s45, v107, v106
	v_mul_f32_e32 v101, 0.5, v101
	v_add_f32_e32 v104, 1.0, v104
	v_bfi_b32 v108, s45, v109, v108
	v_mul_f32_e32 v101, v101, v104
	v_bfi_b32 v104, s45, v111, v110
	v_mul_f32_e32 v102, 0.5, v102
	v_add_f32_e32 v108, 1.0, v108
	v_mul_f32_e32 v103, 0.5, v103
	v_add_f32_e32 v104, 1.0, v104
	v_mul_f32_e32 v102, v102, v108
	v_mul_f32_e32 v103, v103, v104
	v_cvt_pk_bf16_f32 v100, v100, v101
	v_cvt_pk_bf16_f32 v101, v102, v103
	global_store_dwordx2 v[112:113], v[100:101], off offset:256 sc1
	global_load_dwordx4 v[100:103], v[144:145], off offset:576
	s_waitcnt vmcnt(0)
	v_pk_add_f32 v[96:97], v[96:97], v[100:101]
	s_nop 0
	v_mul_f32_e32 v100, 0x3d372713, v96
	v_mul_f32_e32 v100, v96, v100
	v_fma_f32 v100, v96, v100, v96
	v_mul_f32_e32 v100, 0x3f4c422a, v100
	v_cmp_nlt_f32_e64 s[58:59], |v100|, s40
	s_and_saveexec_b64 s[60:61], s[58:59]
	s_xor_b64 s[72:73], exec, s[60:61]
	s_cbranch_execz .LBB0_2663
	v_add_f32_e64 v101, |v100|, |v100|
	v_mul_f32_e32 v104, 0x3fb8aa3b, v101
	v_rndne_f32_e32 v105, v104
	v_sub_f32_e32 v106, v104, v105
	v_fma_f32 v104, v101, s42, -v104
	v_fmac_f32_e32 v104, 0x32a5705f, v101
	v_add_f32_e32 v104, v106, v104
	v_cvt_i32_f32_e32 v105, v105
	v_exp_f32_e32 v104, v104
	v_cmp_ngt_f32_e32 vcc, s43, v101
	v_ldexp_f32 v104, v104, v105
	s_nop 0
	v_cndmask_b32_e32 v104, 0, v104, vcc
	v_cmp_nlt_f32_e32 vcc, s44, v101
	s_nop 1
	v_cndmask_b32_e32 v101, v156, v104, vcc
	v_add_f32_e32 v101, 1.0, v101
	v_rcp_f32_e32 v101, v101
	s_nop 0
	v_fma_f32 v101, v101, -2.0, 1.0

.LBB0_2675:
	s_andn2_saveexec_b64 s[72:73], s[72:73]
	v_mul_f32_e32 v107, v106, v106
	v_fmamk_f32 v108, v107, 0xbbbac73d, v153
	v_fmaak_f32 v108, v107, v108, 0xbd5c1c4e
	v_fmaak_f32 v108, v107, v108, 0x3e088382
	v_fmaak_f32 v108, v107, v108, 0xbeaaaa99
	v_mul_f32_e64 v108, |v106|, v108
	v_fma_f32 v107, v107, v108, |v106|
	s_or_b64 exec, exec, s[72:73]
	v_bfi_b32 v100, s45, v101, v100
	v_mul_f32_e32 v96, 0.5, v96
	v_add_f32_e32 v100, 1.0, v100
	v_mul_f32_e32 v96, v96, v100
	v_bfi_b32 v100, s45, v103, v102
	v_mul_f32_e32 v97, 0.5, v97
	v_add_f32_e32 v100, 1.0, v100
	v_bfi_b32 v104, s45, v105, v104
	v_mul_f32_e32 v97, v97, v100
	v_bfi_b32 v100, s45, v107, v106
	v_mul_f32_e32 v98, 0.5, v98
	v_add_f32_e32 v104, 1.0, v104
	v_mul_f32_e32 v99, 0.5, v99
	v_add_f32_e32 v100, 1.0, v100
	v_mul_f32_e32 v98, v98, v104
	v_mul_f32_e32 v99, v99, v100
	v_cvt_pk_bf16_f32 v96, v96, v97
	v_cvt_pk_bf16_f32 v97, v98, v99
	global_store_dwordx2 v[112:113], v[96:97], off offset:288 sc1
	global_load_dwordx4 v[96:99], v[144:145], off
	s_waitcnt vmcnt(0)
	v_pk_add_f32 v[92:93], v[92:93], v[96:97]
	s_nop 0
	v_mul_f32_e32 v96, 0x3d372713, v92
	v_mul_f32_e32 v96, v92, v96
	v_fma_f32 v96, v92, v96, v92
	v_mul_f32_e32 v96, 0x3f4c422a, v96
	v_cmp_nlt_f32_e64 s[58:59], |v96|, s40
	s_and_saveexec_b64 s[60:61], s[58:59]
	s_xor_b64 s[72:73], exec, s[60:61]
	s_cbranch_execz .LBB0_2679
	v_add_f32_e64 v97, |v96|, |v96|
	v_mul_f32_e32 v100, 0x3fb8aa3b, v97
	v_rndne_f32_e32 v101, v100
	v_sub_f32_e32 v102, v100, v101
	v_fma_f32 v100, v97, s42, -v100
	v_fmac_f32_e32 v100, 0x32a5705f, v97
	v_add_f32_e32 v100, v102, v100
	v_cvt_i32_f32_e32 v101, v101
	v_exp_f32_e32 v100, v100
	v_cmp_ngt_f32_e32 vcc, s43, v97
	v_ldexp_f32 v100, v100, v101
	s_nop 0
	v_cndmask_b32_e32 v100, 0, v100, vcc
	v_cmp_nlt_f32_e32 vcc, s44, v97
	s_nop 1
	v_cndmask_b32_e32 v97, v156, v100, vcc
	v_add_f32_e32 v97, 1.0, v97
	v_rcp_f32_e32 v97, v97
	s_nop 0
	v_fma_f32 v97, v97, -2.0, 1.0

.LBB0_2691:
	s_andn2_saveexec_b64 s[72:73], s[72:73]
	v_mul_f32_e32 v103, v102, v102
	v_fmamk_f32 v104, v103, 0xbbbac73d, v153
	v_fmaak_f32 v104, v103, v104, 0xbd5c1c4e
	v_fmaak_f32 v104, v103, v104, 0x3e088382
	v_fmaak_f32 v104, v103, v104, 0xbeaaaa99
	v_mul_f32_e64 v104, |v102|, v104
	v_fma_f32 v103, v103, v104, |v102|
	s_or_b64 exec, exec, s[72:73]
	v_bfi_b32 v100, s45, v101, v100
	v_mul_f32_e32 v94, 0.5, v94
	v_add_f32_e32 v100, 1.0, v100
	v_mul_f32_e32 v100, v94, v100
	v_mul_f32_e32 v94, 0.5, v95
	v_bfi_b32 v95, s45, v97, v96
	v_mul_f32_e32 v92, 0.5, v92
	v_add_f32_e32 v95, 1.0, v95
	v_mul_f32_e32 v95, v92, v95
	v_mul_f32_e32 v92, 0.5, v93
	v_bfi_b32 v93, s45, v99, v98
	v_add_f32_e32 v93, 1.0, v93
	v_mul_f32_e32 v96, v92, v93
	v_or_b32_e32 v92, 32, v128
	v_ashrrev_i32_e32 v93, 31, v92
	v_bfi_b32 v97, s45, v103, v102
	v_lshlrev_b64 v[92:93], 9, v[92:93]
	v_add_f32_e32 v97, 1.0, v97
	v_mul_f32_e32 v97, v94, v97
	v_lshl_add_u64 v[92:93], s[18:19], 0, v[92:93]
	v_cvt_pk_bf16_f32 v94, v95, v96
	v_cvt_pk_bf16_f32 v95, v100, v97
	v_lshl_add_u64 v[96:97], v[146:147], 1, v[92:93]
	global_store_dwordx2 v[96:97], v[94:95], off sc1
	global_load_dwordx4 v[92:95], v[144:145], off offset:64
	s_waitcnt vmcnt(0)
	v_pk_add_f32 v[88:89], v[88:89], v[92:93]
	s_nop 0
	v_mul_f32_e32 v92, 0x3d372713, v88
	v_mul_f32_e32 v92, v88, v92
	v_fma_f32 v92, v88, v92, v88
	v_mul_f32_e32 v92, 0x3f4c422a, v92
	v_cmp_nlt_f32_e64 s[58:59], |v92|, s40
	s_and_saveexec_b64 s[60:61], s[58:59]
	s_xor_b64 s[72:73], exec, s[60:61]
	s_cbranch_execz .LBB0_2695
	v_add_f32_e64 v93, |v92|, |v92|
	v_mul_f32_e32 v98, 0x3fb8aa3b, v93
	v_rndne_f32_e32 v99, v98
	v_sub_f32_e32 v100, v98, v99
	v_fma_f32 v98, v93, s42, -v98
	v_fmac_f32_e32 v98, 0x32a5705f, v93
	v_add_f32_e32 v98, v100, v98
	v_cvt_i32_f32_e32 v99, v99
	v_exp_f32_e32 v98, v98
	v_cmp_ngt_f32_e32 vcc, s43, v93
	v_ldexp_f32 v98, v98, v99
	s_nop 0
	v_cndmask_b32_e32 v98, 0, v98, vcc
	v_cmp_nlt_f32_e32 vcc, s44, v93
	s_nop 1
	v_cndmask_b32_e32 v93, v156, v98, vcc
	v_add_f32_e32 v93, 1.0, v93
	v_rcp_f32_e32 v93, v93
	s_nop 0
	v_fma_f32 v93, v93, -2.0, 1.0

.LBB0_2707:
	s_andn2_saveexec_b64 s[72:73], s[72:73]
	v_mul_f32_e32 v101, v100, v100
	v_fmamk_f32 v102, v101, 0xbbbac73d, v153
	v_fmaak_f32 v102, v101, v102, 0xbd5c1c4e
	v_fmaak_f32 v102, v101, v102, 0x3e088382
	v_fmaak_f32 v102, v101, v102, 0xbeaaaa99
	v_mul_f32_e64 v102, |v100|, v102
	v_fma_f32 v101, v101, v102, |v100|
	s_or_b64 exec, exec, s[72:73]
	v_bfi_b32 v92, s45, v93, v92
	v_mul_f32_e32 v88, 0.5, v88
	v_add_f32_e32 v92, 1.0, v92
	v_mul_f32_e32 v88, v88, v92
	v_bfi_b32 v92, s45, v95, v94
	v_mul_f32_e32 v89, 0.5, v89
	v_add_f32_e32 v92, 1.0, v92
	v_bfi_b32 v98, s45, v99, v98
	v_mul_f32_e32 v89, v89, v92
	v_bfi_b32 v92, s45, v101, v100
	v_mul_f32_e32 v90, 0.5, v90
	v_add_f32_e32 v98, 1.0, v98
	v_mul_f32_e32 v91, 0.5, v91
	v_add_f32_e32 v92, 1.0, v92
	v_mul_f32_e32 v90, v90, v98
	v_mul_f32_e32 v91, v91, v92
	v_cvt_pk_bf16_f32 v88, v88, v89
	v_cvt_pk_bf16_f32 v89, v90, v91
	global_store_dwordx2 v[96:97], v[88:89], off offset:32 sc1
	global_load_dwordx4 v[88:91], v[144:145], off offset:512
	s_waitcnt vmcnt(0)
	v_pk_add_f32 v[84:85], v[84:85], v[88:89]
	s_nop 0
	v_mul_f32_e32 v88, 0x3d372713, v84
	v_mul_f32_e32 v88, v84, v88
	v_fma_f32 v88, v84, v88, v84
	v_mul_f32_e32 v88, 0x3f4c422a, v88
	v_cmp_nlt_f32_e64 s[58:59], |v88|, s40
	s_and_saveexec_b64 s[60:61], s[58:59]
	s_xor_b64 s[72:73], exec, s[60:61]
	s_cbranch_execz .LBB0_2711
	v_add_f32_e64 v89, |v88|, |v88|
	v_mul_f32_e32 v92, 0x3fb8aa3b, v89
	v_rndne_f32_e32 v93, v92
	v_sub_f32_e32 v94, v92, v93
	v_fma_f32 v92, v89, s42, -v92
	v_fmac_f32_e32 v92, 0x32a5705f, v89
	v_add_f32_e32 v92, v94, v92
	v_cvt_i32_f32_e32 v93, v93
	v_exp_f32_e32 v92, v92
	v_cmp_ngt_f32_e32 vcc, s43, v89
	v_ldexp_f32 v92, v92, v93
	s_nop 0
	v_cndmask_b32_e32 v92, 0, v92, vcc
	v_cmp_nlt_f32_e32 vcc, s44, v89
	s_nop 1
	v_cndmask_b32_e32 v89, v156, v92, vcc
	v_add_f32_e32 v89, 1.0, v89
	v_rcp_f32_e32 v89, v89
	s_nop 0
	v_fma_f32 v89, v89, -2.0, 1.0

.LBB0_2723:
	s_andn2_saveexec_b64 s[72:73], s[72:73]
	v_mul_f32_e32 v95, v94, v94
	v_fmamk_f32 v98, v95, 0xbbbac73d, v153
	v_fmaak_f32 v98, v95, v98, 0xbd5c1c4e
	v_fmaak_f32 v98, v95, v98, 0x3e088382
	v_fmaak_f32 v98, v95, v98, 0xbeaaaa99
	v_mul_f32_e64 v98, |v94|, v98
	v_fma_f32 v95, v95, v98, |v94|
	s_or_b64 exec, exec, s[72:73]
	v_bfi_b32 v88, s45, v89, v88
	v_mul_f32_e32 v84, 0.5, v84
	v_add_f32_e32 v88, 1.0, v88
	v_mul_f32_e32 v84, v84, v88
	v_bfi_b32 v88, s45, v91, v90
	v_mul_f32_e32 v85, 0.5, v85
	v_add_f32_e32 v88, 1.0, v88
	v_bfi_b32 v92, s45, v93, v92
	v_mul_f32_e32 v85, v85, v88
	v_bfi_b32 v88, s45, v95, v94
	v_mul_f32_e32 v86, 0.5, v86
	v_add_f32_e32 v92, 1.0, v92
	v_mul_f32_e32 v87, 0.5, v87
	v_add_f32_e32 v88, 1.0, v88
	v_mul_f32_e32 v86, v86, v92
	v_mul_f32_e32 v87, v87, v88
	v_cvt_pk_bf16_f32 v84, v84, v85
	v_cvt_pk_bf16_f32 v85, v86, v87
	global_store_dwordx2 v[96:97], v[84:85], off offset:256 sc1
	global_load_dwordx4 v[84:87], v[144:145], off offset:576
	s_waitcnt vmcnt(0)
	v_pk_add_f32 v[80:81], v[80:81], v[84:85]
	s_nop 0
	v_mul_f32_e32 v84, 0x3d372713, v80
	v_mul_f32_e32 v84, v80, v84
	v_fma_f32 v84, v80, v84, v80
	v_mul_f32_e32 v84, 0x3f4c422a, v84
	v_cmp_nlt_f32_e64 s[58:59], |v84|, s40
	s_and_saveexec_b64 s[60:61], s[58:59]
	s_xor_b64 s[72:73], exec, s[60:61]
	s_cbranch_execz .LBB0_2727
	v_add_f32_e64 v85, |v84|, |v84|
	v_mul_f32_e32 v88, 0x3fb8aa3b, v85
	v_rndne_f32_e32 v89, v88
	v_sub_f32_e32 v90, v88, v89
	v_fma_f32 v88, v85, s42, -v88
	v_fmac_f32_e32 v88, 0x32a5705f, v85
	v_add_f32_e32 v88, v90, v88
	v_cvt_i32_f32_e32 v89, v89
	v_exp_f32_e32 v88, v88
	v_cmp_ngt_f32_e32 vcc, s43, v85
	v_ldexp_f32 v88, v88, v89
	s_nop 0
	v_cndmask_b32_e32 v88, 0, v88, vcc
	v_cmp_nlt_f32_e32 vcc, s44, v85
	s_nop 1
	v_cndmask_b32_e32 v85, v156, v88, vcc
	v_add_f32_e32 v85, 1.0, v85
	v_rcp_f32_e32 v85, v85
	s_nop 0
	v_fma_f32 v85, v85, -2.0, 1.0

.LBB0_2739:
	s_andn2_saveexec_b64 s[72:73], s[72:73]
	v_mul_f32_e32 v91, v90, v90
	v_fmamk_f32 v92, v91, 0xbbbac73d, v153
	v_fmaak_f32 v92, v91, v92, 0xbd5c1c4e
	v_fmaak_f32 v92, v91, v92, 0x3e088382
	v_fmaak_f32 v92, v91, v92, 0xbeaaaa99
	v_mul_f32_e64 v92, |v90|, v92
	v_fma_f32 v91, v91, v92, |v90|
	s_or_b64 exec, exec, s[72:73]
	v_bfi_b32 v84, s45, v85, v84
	v_mul_f32_e32 v80, 0.5, v80
	v_add_f32_e32 v84, 1.0, v84
	v_mul_f32_e32 v80, v80, v84
	v_bfi_b32 v84, s45, v87, v86
	v_mul_f32_e32 v81, 0.5, v81
	v_add_f32_e32 v84, 1.0, v84
	v_bfi_b32 v88, s45, v89, v88
	v_mul_f32_e32 v81, v81, v84
	v_bfi_b32 v84, s45, v91, v90
	v_mul_f32_e32 v82, 0.5, v82
	v_add_f32_e32 v88, 1.0, v88
	v_mul_f32_e32 v83, 0.5, v83
	v_add_f32_e32 v84, 1.0, v84
	v_mul_f32_e32 v82, v82, v88
	v_mul_f32_e32 v83, v83, v84
	v_cvt_pk_bf16_f32 v80, v80, v81
	v_cvt_pk_bf16_f32 v81, v82, v83
	global_store_dwordx2 v[96:97], v[80:81], off offset:288 sc1
	global_load_dwordx4 v[80:83], v[144:145], off
	s_waitcnt vmcnt(0)
	v_pk_add_f32 v[76:77], v[76:77], v[80:81]
	s_nop 0
	v_mul_f32_e32 v80, 0x3d372713, v76
	v_mul_f32_e32 v80, v76, v80
	v_fma_f32 v80, v76, v80, v76
	v_mul_f32_e32 v80, 0x3f4c422a, v80
	v_cmp_nlt_f32_e64 s[58:59], |v80|, s40
	s_and_saveexec_b64 s[60:61], s[58:59]
	s_xor_b64 s[72:73], exec, s[60:61]
	s_cbranch_execz .LBB0_2743
	v_add_f32_e64 v81, |v80|, |v80|
	v_mul_f32_e32 v84, 0x3fb8aa3b, v81
	v_rndne_f32_e32 v85, v84
	v_sub_f32_e32 v86, v84, v85
	v_fma_f32 v84, v81, s42, -v84
	v_fmac_f32_e32 v84, 0x32a5705f, v81
	v_add_f32_e32 v84, v86, v84
	v_cvt_i32_f32_e32 v85, v85
	v_exp_f32_e32 v84, v84
	v_cmp_ngt_f32_e32 vcc, s43, v81
	v_ldexp_f32 v84, v84, v85
	s_nop 0
	v_cndmask_b32_e32 v84, 0, v84, vcc
	v_cmp_nlt_f32_e32 vcc, s44, v81
	s_nop 1
	v_cndmask_b32_e32 v81, v156, v84, vcc
	v_add_f32_e32 v81, 1.0, v81
	v_rcp_f32_e32 v81, v81
	s_nop 0
	v_fma_f32 v81, v81, -2.0, 1.0

.LBB0_2755:
	s_andn2_saveexec_b64 s[72:73], s[72:73]
	v_mul_f32_e32 v87, v86, v86
	v_fmamk_f32 v88, v87, 0xbbbac73d, v153
	v_fmaak_f32 v88, v87, v88, 0xbd5c1c4e
	v_fmaak_f32 v88, v87, v88, 0x3e088382
	v_fmaak_f32 v88, v87, v88, 0xbeaaaa99
	v_mul_f32_e64 v88, |v86|, v88
	v_fma_f32 v87, v87, v88, |v86|
	s_or_b64 exec, exec, s[72:73]
	v_bfi_b32 v84, s45, v85, v84
	v_mul_f32_e32 v78, 0.5, v78
	v_add_f32_e32 v84, 1.0, v84
	v_mul_f32_e32 v84, v78, v84
	v_mul_f32_e32 v78, 0.5, v79
	v_bfi_b32 v79, s45, v81, v80
	v_mul_f32_e32 v76, 0.5, v76
	v_add_f32_e32 v79, 1.0, v79
	v_mul_f32_e32 v79, v76, v79
	v_mul_f32_e32 v76, 0.5, v77
	v_bfi_b32 v77, s45, v83, v82
	v_add_f32_e32 v77, 1.0, v77
	v_mul_f32_e32 v80, v76, v77
	v_or_b32_e32 v76, 48, v128
	v_ashrrev_i32_e32 v77, 31, v76
	v_bfi_b32 v81, s45, v87, v86
	v_lshlrev_b64 v[76:77], 9, v[76:77]
	v_add_f32_e32 v81, 1.0, v81
	v_mul_f32_e32 v81, v78, v81
	v_lshl_add_u64 v[76:77], s[18:19], 0, v[76:77]
	v_cvt_pk_bf16_f32 v78, v79, v80
	v_cvt_pk_bf16_f32 v79, v84, v81
	v_lshl_add_u64 v[80:81], v[146:147], 1, v[76:77]
	global_store_dwordx2 v[80:81], v[78:79], off sc1
	global_load_dwordx4 v[76:79], v[144:145], off offset:64
	s_waitcnt vmcnt(0)
	v_pk_add_f32 v[72:73], v[72:73], v[76:77]
	s_nop 0
	v_mul_f32_e32 v76, 0x3d372713, v72
	v_mul_f32_e32 v76, v72, v76
	v_fma_f32 v76, v72, v76, v72
	v_mul_f32_e32 v76, 0x3f4c422a, v76
	v_cmp_nlt_f32_e64 s[58:59], |v76|, s40
	s_and_saveexec_b64 s[60:61], s[58:59]
	s_xor_b64 s[72:73], exec, s[60:61]
	s_cbranch_execz .LBB0_2759
	v_add_f32_e64 v77, |v76|, |v76|
	v_mul_f32_e32 v82, 0x3fb8aa3b, v77
	v_rndne_f32_e32 v83, v82
	v_sub_f32_e32 v84, v82, v83
	v_fma_f32 v82, v77, s42, -v82
	v_fmac_f32_e32 v82, 0x32a5705f, v77
	v_add_f32_e32 v82, v84, v82
	v_cvt_i32_f32_e32 v83, v83
	v_exp_f32_e32 v82, v82
	v_cmp_ngt_f32_e32 vcc, s43, v77
	v_ldexp_f32 v82, v82, v83
	s_nop 0
	v_cndmask_b32_e32 v82, 0, v82, vcc
	v_cmp_nlt_f32_e32 vcc, s44, v77
	s_nop 1
	v_cndmask_b32_e32 v77, v156, v82, vcc
	v_add_f32_e32 v77, 1.0, v77
	v_rcp_f32_e32 v77, v77
	s_nop 0
	v_fma_f32 v77, v77, -2.0, 1.0

.LBB0_2771:
	s_andn2_saveexec_b64 s[72:73], s[72:73]
	v_mul_f32_e32 v85, v84, v84
	v_fmamk_f32 v86, v85, 0xbbbac73d, v153
	v_fmaak_f32 v86, v85, v86, 0xbd5c1c4e
	v_fmaak_f32 v86, v85, v86, 0x3e088382
	v_fmaak_f32 v86, v85, v86, 0xbeaaaa99
	v_mul_f32_e64 v86, |v84|, v86
	v_fma_f32 v85, v85, v86, |v84|
	s_or_b64 exec, exec, s[72:73]
	v_bfi_b32 v76, s45, v77, v76
	v_mul_f32_e32 v72, 0.5, v72
	v_add_f32_e32 v76, 1.0, v76
	v_mul_f32_e32 v72, v72, v76
	v_bfi_b32 v76, s45, v79, v78
	v_mul_f32_e32 v73, 0.5, v73
	v_add_f32_e32 v76, 1.0, v76
	v_bfi_b32 v82, s45, v83, v82
	v_mul_f32_e32 v73, v73, v76
	v_bfi_b32 v76, s45, v85, v84
	v_mul_f32_e32 v74, 0.5, v74
	v_add_f32_e32 v82, 1.0, v82
	v_mul_f32_e32 v75, 0.5, v75
	v_add_f32_e32 v76, 1.0, v76
	v_mul_f32_e32 v74, v74, v82
	v_mul_f32_e32 v75, v75, v76
	v_cvt_pk_bf16_f32 v72, v72, v73
	v_cvt_pk_bf16_f32 v73, v74, v75
	global_store_dwordx2 v[80:81], v[72:73], off offset:32 sc1
	global_load_dwordx4 v[72:75], v[144:145], off offset:512
	s_waitcnt vmcnt(0)
	v_pk_add_f32 v[68:69], v[68:69], v[72:73]
	s_nop 0
	v_mul_f32_e32 v72, 0x3d372713, v68
	v_mul_f32_e32 v72, v68, v72
	v_fma_f32 v72, v68, v72, v68
	v_mul_f32_e32 v72, 0x3f4c422a, v72
	v_cmp_nlt_f32_e64 s[58:59], |v72|, s40
	s_and_saveexec_b64 s[60:61], s[58:59]
	s_xor_b64 s[72:73], exec, s[60:61]
	s_cbranch_execz .LBB0_2775
	v_add_f32_e64 v73, |v72|, |v72|
	v_mul_f32_e32 v76, 0x3fb8aa3b, v73
	v_rndne_f32_e32 v77, v76
	v_sub_f32_e32 v78, v76, v77
	v_fma_f32 v76, v73, s42, -v76
	v_fmac_f32_e32 v76, 0x32a5705f, v73
	v_add_f32_e32 v76, v78, v76
	v_cvt_i32_f32_e32 v77, v77
	v_exp_f32_e32 v76, v76
	v_cmp_ngt_f32_e32 vcc, s43, v73
	v_ldexp_f32 v76, v76, v77
	s_nop 0
	v_cndmask_b32_e32 v76, 0, v76, vcc
	v_cmp_nlt_f32_e32 vcc, s44, v73
	s_nop 1
	v_cndmask_b32_e32 v73, v156, v76, vcc
	v_add_f32_e32 v73, 1.0, v73
	v_rcp_f32_e32 v73, v73
	s_nop 0
	v_fma_f32 v73, v73, -2.0, 1.0

.LBB0_2787:
	s_andn2_saveexec_b64 s[72:73], s[72:73]
	v_mul_f32_e32 v79, v78, v78
	v_fmamk_f32 v82, v79, 0xbbbac73d, v153
	v_fmaak_f32 v82, v79, v82, 0xbd5c1c4e
	v_fmaak_f32 v82, v79, v82, 0x3e088382
	v_fmaak_f32 v82, v79, v82, 0xbeaaaa99
	v_mul_f32_e64 v82, |v78|, v82
	v_fma_f32 v79, v79, v82, |v78|
	s_or_b64 exec, exec, s[72:73]
	v_bfi_b32 v72, s45, v73, v72
	v_mul_f32_e32 v68, 0.5, v68
	v_add_f32_e32 v72, 1.0, v72
	v_mul_f32_e32 v68, v68, v72
	v_bfi_b32 v72, s45, v75, v74
	v_mul_f32_e32 v69, 0.5, v69
	v_add_f32_e32 v72, 1.0, v72
	v_bfi_b32 v76, s45, v77, v76
	v_mul_f32_e32 v69, v69, v72
	v_bfi_b32 v72, s45, v79, v78
	v_mul_f32_e32 v70, 0.5, v70
	v_add_f32_e32 v76, 1.0, v76
	v_mul_f32_e32 v71, 0.5, v71
	v_add_f32_e32 v72, 1.0, v72
	v_mul_f32_e32 v70, v70, v76
	v_mul_f32_e32 v71, v71, v72
	v_cvt_pk_bf16_f32 v68, v68, v69
	v_cvt_pk_bf16_f32 v69, v70, v71
	global_store_dwordx2 v[80:81], v[68:69], off offset:256 sc1
	global_load_dwordx4 v[68:71], v[144:145], off offset:576
	s_waitcnt vmcnt(0)
	v_pk_add_f32 v[64:65], v[64:65], v[68:69]
	s_nop 0
	v_mul_f32_e32 v68, 0x3d372713, v64
	v_mul_f32_e32 v68, v64, v68
	v_fma_f32 v68, v64, v68, v64
	v_mul_f32_e32 v68, 0x3f4c422a, v68
	v_cmp_nlt_f32_e64 s[58:59], |v68|, s40
	s_and_saveexec_b64 s[60:61], s[58:59]
	s_xor_b64 s[72:73], exec, s[60:61]
	s_cbranch_execz .LBB0_2791
	v_add_f32_e64 v69, |v68|, |v68|
	v_mul_f32_e32 v72, 0x3fb8aa3b, v69
	v_rndne_f32_e32 v73, v72
	v_sub_f32_e32 v74, v72, v73
	v_fma_f32 v72, v69, s42, -v72
	v_fmac_f32_e32 v72, 0x32a5705f, v69
	v_add_f32_e32 v72, v74, v72
	v_cvt_i32_f32_e32 v73, v73
	v_exp_f32_e32 v72, v72
	v_cmp_ngt_f32_e32 vcc, s43, v69
	v_ldexp_f32 v72, v72, v73
	s_nop 0
	v_cndmask_b32_e32 v72, 0, v72, vcc
	v_cmp_nlt_f32_e32 vcc, s44, v69
	s_nop 1
	v_cndmask_b32_e32 v69, v156, v72, vcc
	v_add_f32_e32 v69, 1.0, v69
	v_rcp_f32_e32 v69, v69
	s_nop 0
	v_fma_f32 v69, v69, -2.0, 1.0

.LBB0_2803:
	s_andn2_saveexec_b64 s[72:73], s[72:73]
	v_mul_f32_e32 v75, v74, v74
	v_fmamk_f32 v76, v75, 0xbbbac73d, v153
	v_fmaak_f32 v76, v75, v76, 0xbd5c1c4e
	v_fmaak_f32 v76, v75, v76, 0x3e088382
	v_fmaak_f32 v76, v75, v76, 0xbeaaaa99
	v_mul_f32_e64 v76, |v74|, v76
	v_fma_f32 v75, v75, v76, |v74|
	s_or_b64 exec, exec, s[72:73]
	v_bfi_b32 v68, s45, v69, v68
	v_mul_f32_e32 v64, 0.5, v64
	v_add_f32_e32 v68, 1.0, v68
	v_mul_f32_e32 v64, v64, v68
	v_bfi_b32 v68, s45, v71, v70
	v_mul_f32_e32 v65, 0.5, v65
	v_add_f32_e32 v68, 1.0, v68
	v_bfi_b32 v72, s45, v73, v72
	v_mul_f32_e32 v65, v65, v68
	v_bfi_b32 v68, s45, v75, v74
	v_mul_f32_e32 v66, 0.5, v66
	v_add_f32_e32 v72, 1.0, v72
	v_mul_f32_e32 v67, 0.5, v67
	v_add_f32_e32 v68, 1.0, v68
	v_mul_f32_e32 v66, v66, v72
	v_mul_f32_e32 v67, v67, v68
	v_cvt_pk_bf16_f32 v64, v64, v65
	v_cvt_pk_bf16_f32 v65, v66, v67
	global_store_dwordx2 v[80:81], v[64:65], off offset:288 sc1
	global_load_dwordx4 v[64:67], v[144:145], off
	s_waitcnt vmcnt(0)
	v_pk_add_f32 v[60:61], v[60:61], v[64:65]
	s_nop 0
	v_mul_f32_e32 v64, 0x3d372713, v60
	v_mul_f32_e32 v64, v60, v64
	v_fma_f32 v64, v60, v64, v60
	v_mul_f32_e32 v64, 0x3f4c422a, v64
	v_cmp_nlt_f32_e64 s[58:59], |v64|, s40
	s_and_saveexec_b64 s[60:61], s[58:59]
	s_xor_b64 s[72:73], exec, s[60:61]
	s_cbranch_execz .LBB0_2807
	v_add_f32_e64 v65, |v64|, |v64|
	v_mul_f32_e32 v68, 0x3fb8aa3b, v65
	v_rndne_f32_e32 v69, v68
	v_sub_f32_e32 v70, v68, v69
	v_fma_f32 v68, v65, s42, -v68
	v_fmac_f32_e32 v68, 0x32a5705f, v65
	v_add_f32_e32 v68, v70, v68
	v_cvt_i32_f32_e32 v69, v69
	v_exp_f32_e32 v68, v68
	v_cmp_ngt_f32_e32 vcc, s43, v65
	v_ldexp_f32 v68, v68, v69
	s_nop 0
	v_cndmask_b32_e32 v68, 0, v68, vcc
	v_cmp_nlt_f32_e32 vcc, s44, v65
	s_nop 1
	v_cndmask_b32_e32 v65, v156, v68, vcc
	v_add_f32_e32 v65, 1.0, v65
	v_rcp_f32_e32 v65, v65
	s_nop 0
	v_fma_f32 v65, v65, -2.0, 1.0

.LBB0_2819:
	s_andn2_saveexec_b64 s[72:73], s[72:73]
	v_mul_f32_e32 v71, v70, v70
	v_fmamk_f32 v72, v71, 0xbbbac73d, v153
	v_fmaak_f32 v72, v71, v72, 0xbd5c1c4e
	v_fmaak_f32 v72, v71, v72, 0x3e088382
	v_fmaak_f32 v72, v71, v72, 0xbeaaaa99
	v_mul_f32_e64 v72, |v70|, v72
	v_fma_f32 v71, v71, v72, |v70|
	s_or_b64 exec, exec, s[72:73]
	v_bfi_b32 v68, s45, v69, v68
	v_mul_f32_e32 v62, 0.5, v62
	v_add_f32_e32 v68, 1.0, v68
	v_mul_f32_e32 v68, v62, v68
	v_mul_f32_e32 v62, 0.5, v63
	v_bfi_b32 v63, s45, v65, v64
	v_mul_f32_e32 v60, 0.5, v60
	v_add_f32_e32 v63, 1.0, v63
	v_mul_f32_e32 v63, v60, v63
	v_mul_f32_e32 v60, 0.5, v61
	v_bfi_b32 v61, s45, v67, v66
	v_add_f32_e32 v61, 1.0, v61
	v_mul_f32_e32 v64, v60, v61
	v_add_u32_e32 v60, 0x80, v128
	v_ashrrev_i32_e32 v61, 31, v60
	v_bfi_b32 v65, s45, v71, v70
	v_lshlrev_b64 v[60:61], 9, v[60:61]
	v_add_f32_e32 v65, 1.0, v65
	v_mul_f32_e32 v65, v62, v65
	v_lshl_add_u64 v[60:61], s[18:19], 0, v[60:61]
	v_cvt_pk_bf16_f32 v62, v63, v64
	v_cvt_pk_bf16_f32 v63, v68, v65
	v_lshl_add_u64 v[64:65], v[146:147], 1, v[60:61]
	global_store_dwordx2 v[64:65], v[62:63], off sc1
	global_load_dwordx4 v[60:63], v[144:145], off offset:64
	s_waitcnt vmcnt(0)
	v_pk_add_f32 v[56:57], v[56:57], v[60:61]
	s_nop 0
	v_mul_f32_e32 v60, 0x3d372713, v56
	v_mul_f32_e32 v60, v56, v60
	v_fma_f32 v60, v56, v60, v56
	v_mul_f32_e32 v60, 0x3f4c422a, v60
	v_cmp_nlt_f32_e64 s[58:59], |v60|, s40
	s_and_saveexec_b64 s[60:61], s[58:59]
	s_xor_b64 s[72:73], exec, s[60:61]
	s_cbranch_execz .LBB0_2823
	v_add_f32_e64 v61, |v60|, |v60|
	v_mul_f32_e32 v66, 0x3fb8aa3b, v61
	v_rndne_f32_e32 v67, v66
	v_sub_f32_e32 v68, v66, v67
	v_fma_f32 v66, v61, s42, -v66
	v_fmac_f32_e32 v66, 0x32a5705f, v61
	v_add_f32_e32 v66, v68, v66
	v_cvt_i32_f32_e32 v67, v67
	v_exp_f32_e32 v66, v66
	v_cmp_ngt_f32_e32 vcc, s43, v61
	v_ldexp_f32 v66, v66, v67
	s_nop 0
	v_cndmask_b32_e32 v66, 0, v66, vcc
	v_cmp_nlt_f32_e32 vcc, s44, v61
	s_nop 1
	v_cndmask_b32_e32 v61, v156, v66, vcc
	v_add_f32_e32 v61, 1.0, v61
	v_rcp_f32_e32 v61, v61
	s_nop 0
	v_fma_f32 v61, v61, -2.0, 1.0

.LBB0_2835:
	s_andn2_saveexec_b64 s[72:73], s[72:73]
	v_mul_f32_e32 v69, v68, v68
	v_fmamk_f32 v70, v69, 0xbbbac73d, v153
	v_fmaak_f32 v70, v69, v70, 0xbd5c1c4e
	v_fmaak_f32 v70, v69, v70, 0x3e088382
	v_fmaak_f32 v70, v69, v70, 0xbeaaaa99
	v_mul_f32_e64 v70, |v68|, v70
	v_fma_f32 v69, v69, v70, |v68|
	s_or_b64 exec, exec, s[72:73]
	v_bfi_b32 v60, s45, v61, v60
	v_mul_f32_e32 v56, 0.5, v56
	v_add_f32_e32 v60, 1.0, v60
	v_mul_f32_e32 v56, v56, v60
	v_bfi_b32 v60, s45, v63, v62
	v_mul_f32_e32 v57, 0.5, v57
	v_add_f32_e32 v60, 1.0, v60
	v_bfi_b32 v66, s45, v67, v66
	v_mul_f32_e32 v57, v57, v60
	v_bfi_b32 v60, s45, v69, v68
	v_mul_f32_e32 v58, 0.5, v58
	v_add_f32_e32 v66, 1.0, v66
	v_mul_f32_e32 v59, 0.5, v59
	v_add_f32_e32 v60, 1.0, v60
	v_mul_f32_e32 v58, v58, v66
	v_mul_f32_e32 v59, v59, v60
	v_cvt_pk_bf16_f32 v56, v56, v57
	v_cvt_pk_bf16_f32 v57, v58, v59
	global_store_dwordx2 v[64:65], v[56:57], off offset:32 sc1
	global_load_dwordx4 v[56:59], v[144:145], off offset:512
	s_waitcnt vmcnt(0)
	v_pk_add_f32 v[52:53], v[52:53], v[56:57]
	s_nop 0
	v_mul_f32_e32 v56, 0x3d372713, v52
	v_mul_f32_e32 v56, v52, v56
	v_fma_f32 v56, v52, v56, v52
	v_mul_f32_e32 v56, 0x3f4c422a, v56
	v_cmp_nlt_f32_e64 s[58:59], |v56|, s40
	s_and_saveexec_b64 s[60:61], s[58:59]
	s_xor_b64 s[72:73], exec, s[60:61]
	s_cbranch_execz .LBB0_2839
	v_add_f32_e64 v57, |v56|, |v56|
	v_mul_f32_e32 v60, 0x3fb8aa3b, v57
	v_rndne_f32_e32 v61, v60
	v_sub_f32_e32 v62, v60, v61
	v_fma_f32 v60, v57, s42, -v60
	v_fmac_f32_e32 v60, 0x32a5705f, v57
	v_add_f32_e32 v60, v62, v60
	v_cvt_i32_f32_e32 v61, v61
	v_exp_f32_e32 v60, v60
	v_cmp_ngt_f32_e32 vcc, s43, v57
	v_ldexp_f32 v60, v60, v61
	s_nop 0
	v_cndmask_b32_e32 v60, 0, v60, vcc
	v_cmp_nlt_f32_e32 vcc, s44, v57
	s_nop 1
	v_cndmask_b32_e32 v57, v156, v60, vcc
	v_add_f32_e32 v57, 1.0, v57
	v_rcp_f32_e32 v57, v57
	s_nop 0
	v_fma_f32 v57, v57, -2.0, 1.0

.LBB0_2851:
	s_andn2_saveexec_b64 s[72:73], s[72:73]
	v_mul_f32_e32 v63, v62, v62
	v_fmamk_f32 v66, v63, 0xbbbac73d, v153
	v_fmaak_f32 v66, v63, v66, 0xbd5c1c4e
	v_fmaak_f32 v66, v63, v66, 0x3e088382
	v_fmaak_f32 v66, v63, v66, 0xbeaaaa99
	v_mul_f32_e64 v66, |v62|, v66
	v_fma_f32 v63, v63, v66, |v62|
	s_or_b64 exec, exec, s[72:73]
	v_bfi_b32 v56, s45, v57, v56
	v_mul_f32_e32 v52, 0.5, v52
	v_add_f32_e32 v56, 1.0, v56
	v_mul_f32_e32 v52, v52, v56
	v_bfi_b32 v56, s45, v59, v58
	v_mul_f32_e32 v53, 0.5, v53
	v_add_f32_e32 v56, 1.0, v56
	v_bfi_b32 v60, s45, v61, v60
	v_mul_f32_e32 v53, v53, v56
	v_bfi_b32 v56, s45, v63, v62
	v_mul_f32_e32 v54, 0.5, v54
	v_add_f32_e32 v60, 1.0, v60
	v_mul_f32_e32 v55, 0.5, v55
	v_add_f32_e32 v56, 1.0, v56
	v_mul_f32_e32 v54, v54, v60
	v_mul_f32_e32 v55, v55, v56
	v_cvt_pk_bf16_f32 v52, v52, v53
	v_cvt_pk_bf16_f32 v53, v54, v55
	global_store_dwordx2 v[64:65], v[52:53], off offset:256 sc1
	global_load_dwordx4 v[52:55], v[144:145], off offset:576
	s_waitcnt vmcnt(0)
	v_pk_add_f32 v[48:49], v[48:49], v[52:53]
	s_nop 0
	v_mul_f32_e32 v52, 0x3d372713, v48
	v_mul_f32_e32 v52, v48, v52
	v_fma_f32 v52, v48, v52, v48
	v_mul_f32_e32 v52, 0x3f4c422a, v52
	v_cmp_nlt_f32_e64 s[58:59], |v52|, s40
	s_and_saveexec_b64 s[60:61], s[58:59]
	s_xor_b64 s[72:73], exec, s[60:61]
	s_cbranch_execz .LBB0_2855
	v_add_f32_e64 v53, |v52|, |v52|
	v_mul_f32_e32 v56, 0x3fb8aa3b, v53
	v_rndne_f32_e32 v57, v56
	v_sub_f32_e32 v58, v56, v57
	v_fma_f32 v56, v53, s42, -v56
	v_fmac_f32_e32 v56, 0x32a5705f, v53
	v_add_f32_e32 v56, v58, v56
	v_cvt_i32_f32_e32 v57, v57
	v_exp_f32_e32 v56, v56
	v_cmp_ngt_f32_e32 vcc, s43, v53
	v_ldexp_f32 v56, v56, v57
	s_nop 0
	v_cndmask_b32_e32 v56, 0, v56, vcc
	v_cmp_nlt_f32_e32 vcc, s44, v53
	s_nop 1
	v_cndmask_b32_e32 v53, v156, v56, vcc
	v_add_f32_e32 v53, 1.0, v53
	v_rcp_f32_e32 v53, v53
	s_nop 0
	v_fma_f32 v53, v53, -2.0, 1.0

.LBB0_2867:
	s_andn2_saveexec_b64 s[72:73], s[72:73]
	v_mul_f32_e32 v59, v58, v58
	v_fmamk_f32 v60, v59, 0xbbbac73d, v153
	v_fmaak_f32 v60, v59, v60, 0xbd5c1c4e
	v_fmaak_f32 v60, v59, v60, 0x3e088382
	v_fmaak_f32 v60, v59, v60, 0xbeaaaa99
	v_mul_f32_e64 v60, |v58|, v60
	v_fma_f32 v59, v59, v60, |v58|
	s_or_b64 exec, exec, s[72:73]
	v_bfi_b32 v52, s45, v53, v52
	v_mul_f32_e32 v48, 0.5, v48
	v_add_f32_e32 v52, 1.0, v52
	v_mul_f32_e32 v48, v48, v52
	v_bfi_b32 v52, s45, v55, v54
	v_mul_f32_e32 v49, 0.5, v49
	v_add_f32_e32 v52, 1.0, v52
	v_bfi_b32 v56, s45, v57, v56
	v_mul_f32_e32 v49, v49, v52
	v_bfi_b32 v52, s45, v59, v58
	v_mul_f32_e32 v50, 0.5, v50
	v_add_f32_e32 v56, 1.0, v56
	v_mul_f32_e32 v51, 0.5, v51
	v_add_f32_e32 v52, 1.0, v52
	v_mul_f32_e32 v50, v50, v56
	v_mul_f32_e32 v51, v51, v52
	v_cvt_pk_bf16_f32 v48, v48, v49
	v_cvt_pk_bf16_f32 v49, v50, v51
	global_store_dwordx2 v[64:65], v[48:49], off offset:288 sc1
	global_load_dwordx4 v[48:51], v[144:145], off
	s_waitcnt vmcnt(0)
	v_pk_add_f32 v[44:45], v[44:45], v[48:49]
	s_nop 0
	v_mul_f32_e32 v48, 0x3d372713, v44
	v_mul_f32_e32 v48, v44, v48
	v_fma_f32 v48, v44, v48, v44
	v_mul_f32_e32 v48, 0x3f4c422a, v48
	v_cmp_nlt_f32_e64 s[58:59], |v48|, s40
	s_and_saveexec_b64 s[60:61], s[58:59]
	s_xor_b64 s[72:73], exec, s[60:61]
	s_cbranch_execz .LBB0_2871
	v_add_f32_e64 v49, |v48|, |v48|
	v_mul_f32_e32 v52, 0x3fb8aa3b, v49
	v_rndne_f32_e32 v53, v52
	v_sub_f32_e32 v54, v52, v53
	v_fma_f32 v52, v49, s42, -v52
	v_fmac_f32_e32 v52, 0x32a5705f, v49
	v_add_f32_e32 v52, v54, v52
	v_cvt_i32_f32_e32 v53, v53
	v_exp_f32_e32 v52, v52
	v_cmp_ngt_f32_e32 vcc, s43, v49
	v_ldexp_f32 v52, v52, v53
	s_nop 0
	v_cndmask_b32_e32 v52, 0, v52, vcc
	v_cmp_nlt_f32_e32 vcc, s44, v49
	s_nop 1
	v_cndmask_b32_e32 v49, v156, v52, vcc
	v_add_f32_e32 v49, 1.0, v49
	v_rcp_f32_e32 v49, v49
	s_nop 0
	v_fma_f32 v49, v49, -2.0, 1.0

.LBB0_2883:
	s_andn2_saveexec_b64 s[72:73], s[72:73]
	v_mul_f32_e32 v55, v54, v54
	v_fmamk_f32 v56, v55, 0xbbbac73d, v153
	v_fmaak_f32 v56, v55, v56, 0xbd5c1c4e
	v_fmaak_f32 v56, v55, v56, 0x3e088382
	v_fmaak_f32 v56, v55, v56, 0xbeaaaa99
	v_mul_f32_e64 v56, |v54|, v56
	v_fma_f32 v55, v55, v56, |v54|
	s_or_b64 exec, exec, s[72:73]
	v_bfi_b32 v52, s45, v53, v52
	v_mul_f32_e32 v46, 0.5, v46
	v_add_f32_e32 v52, 1.0, v52
	v_mul_f32_e32 v52, v46, v52
	v_mul_f32_e32 v46, 0.5, v47
	v_bfi_b32 v47, s45, v49, v48
	v_mul_f32_e32 v44, 0.5, v44
	v_add_f32_e32 v47, 1.0, v47
	v_mul_f32_e32 v47, v44, v47
	v_mul_f32_e32 v44, 0.5, v45
	v_bfi_b32 v45, s45, v51, v50
	v_add_f32_e32 v45, 1.0, v45
	v_mul_f32_e32 v48, v44, v45
	v_add_u32_e32 v44, 0x90, v128
	v_ashrrev_i32_e32 v45, 31, v44
	v_bfi_b32 v49, s45, v55, v54
	v_lshlrev_b64 v[44:45], 9, v[44:45]
	v_add_f32_e32 v49, 1.0, v49
	v_mul_f32_e32 v49, v46, v49
	v_lshl_add_u64 v[44:45], s[18:19], 0, v[44:45]
	v_cvt_pk_bf16_f32 v46, v47, v48
	v_cvt_pk_bf16_f32 v47, v52, v49
	v_lshl_add_u64 v[48:49], v[146:147], 1, v[44:45]
	global_store_dwordx2 v[48:49], v[46:47], off sc1
	global_load_dwordx4 v[44:47], v[144:145], off offset:64
	s_waitcnt vmcnt(0)
	v_pk_add_f32 v[40:41], v[40:41], v[44:45]
	s_nop 0
	v_mul_f32_e32 v44, 0x3d372713, v40
	v_mul_f32_e32 v44, v40, v44
	v_fma_f32 v44, v40, v44, v40
	v_mul_f32_e32 v44, 0x3f4c422a, v44
	v_cmp_nlt_f32_e64 s[58:59], |v44|, s40
	s_and_saveexec_b64 s[60:61], s[58:59]
	s_xor_b64 s[72:73], exec, s[60:61]
	s_cbranch_execz .LBB0_2887
	v_add_f32_e64 v45, |v44|, |v44|
	v_mul_f32_e32 v50, 0x3fb8aa3b, v45
	v_rndne_f32_e32 v51, v50
	v_sub_f32_e32 v52, v50, v51
	v_fma_f32 v50, v45, s42, -v50
	v_fmac_f32_e32 v50, 0x32a5705f, v45
	v_add_f32_e32 v50, v52, v50
	v_cvt_i32_f32_e32 v51, v51
	v_exp_f32_e32 v50, v50
	v_cmp_ngt_f32_e32 vcc, s43, v45
	v_ldexp_f32 v50, v50, v51
	s_nop 0
	v_cndmask_b32_e32 v50, 0, v50, vcc
	v_cmp_nlt_f32_e32 vcc, s44, v45
	s_nop 1
	v_cndmask_b32_e32 v45, v156, v50, vcc
	v_add_f32_e32 v45, 1.0, v45
	v_rcp_f32_e32 v45, v45
	s_nop 0
	v_fma_f32 v45, v45, -2.0, 1.0

.LBB0_2899:
	s_andn2_saveexec_b64 s[72:73], s[72:73]
	v_mul_f32_e32 v53, v52, v52
	v_fmamk_f32 v54, v53, 0xbbbac73d, v153
	v_fmaak_f32 v54, v53, v54, 0xbd5c1c4e
	v_fmaak_f32 v54, v53, v54, 0x3e088382
	v_fmaak_f32 v54, v53, v54, 0xbeaaaa99
	v_mul_f32_e64 v54, |v52|, v54
	v_fma_f32 v53, v53, v54, |v52|
	s_or_b64 exec, exec, s[72:73]
	v_bfi_b32 v44, s45, v45, v44
	v_mul_f32_e32 v40, 0.5, v40
	v_add_f32_e32 v44, 1.0, v44
	v_mul_f32_e32 v40, v40, v44
	v_bfi_b32 v44, s45, v47, v46
	v_mul_f32_e32 v41, 0.5, v41
	v_add_f32_e32 v44, 1.0, v44
	v_bfi_b32 v50, s45, v51, v50
	v_mul_f32_e32 v41, v41, v44
	v_bfi_b32 v44, s45, v53, v52
	v_mul_f32_e32 v42, 0.5, v42
	v_add_f32_e32 v50, 1.0, v50
	v_mul_f32_e32 v43, 0.5, v43
	v_add_f32_e32 v44, 1.0, v44
	v_mul_f32_e32 v42, v42, v50
	v_mul_f32_e32 v43, v43, v44
	v_cvt_pk_bf16_f32 v40, v40, v41
	v_cvt_pk_bf16_f32 v41, v42, v43
	global_store_dwordx2 v[48:49], v[40:41], off offset:32 sc1
	global_load_dwordx4 v[40:43], v[144:145], off offset:512
	s_waitcnt vmcnt(0)
	v_pk_add_f32 v[36:37], v[36:37], v[40:41]
	s_nop 0
	v_mul_f32_e32 v40, 0x3d372713, v36
	v_mul_f32_e32 v40, v36, v40
	v_fma_f32 v40, v36, v40, v36
	v_mul_f32_e32 v40, 0x3f4c422a, v40
	v_cmp_nlt_f32_e64 s[58:59], |v40|, s40
	s_and_saveexec_b64 s[60:61], s[58:59]
	s_xor_b64 s[72:73], exec, s[60:61]
	s_cbranch_execz .LBB0_2903
	v_add_f32_e64 v41, |v40|, |v40|
	v_mul_f32_e32 v44, 0x3fb8aa3b, v41
	v_rndne_f32_e32 v45, v44
	v_sub_f32_e32 v46, v44, v45
	v_fma_f32 v44, v41, s42, -v44
	v_fmac_f32_e32 v44, 0x32a5705f, v41
	v_add_f32_e32 v44, v46, v44
	v_cvt_i32_f32_e32 v45, v45
	v_exp_f32_e32 v44, v44
	v_cmp_ngt_f32_e32 vcc, s43, v41
	v_ldexp_f32 v44, v44, v45
	s_nop 0
	v_cndmask_b32_e32 v44, 0, v44, vcc
	v_cmp_nlt_f32_e32 vcc, s44, v41
	s_nop 1
	v_cndmask_b32_e32 v41, v156, v44, vcc
	v_add_f32_e32 v41, 1.0, v41
	v_rcp_f32_e32 v41, v41
	s_nop 0
	v_fma_f32 v41, v41, -2.0, 1.0

.LBB0_2915:
	s_andn2_saveexec_b64 s[72:73], s[72:73]
	v_mul_f32_e32 v47, v46, v46
	v_fmamk_f32 v50, v47, 0xbbbac73d, v153
	v_fmaak_f32 v50, v47, v50, 0xbd5c1c4e
	v_fmaak_f32 v50, v47, v50, 0x3e088382
	v_fmaak_f32 v50, v47, v50, 0xbeaaaa99
	v_mul_f32_e64 v50, |v46|, v50
	v_fma_f32 v47, v47, v50, |v46|
	s_or_b64 exec, exec, s[72:73]
	v_bfi_b32 v40, s45, v41, v40
	v_mul_f32_e32 v36, 0.5, v36
	v_add_f32_e32 v40, 1.0, v40
	v_mul_f32_e32 v36, v36, v40
	v_bfi_b32 v40, s45, v43, v42
	v_mul_f32_e32 v37, 0.5, v37
	v_add_f32_e32 v40, 1.0, v40
	v_bfi_b32 v44, s45, v45, v44
	v_mul_f32_e32 v37, v37, v40
	v_bfi_b32 v40, s45, v47, v46
	v_mul_f32_e32 v38, 0.5, v38
	v_add_f32_e32 v44, 1.0, v44
	v_mul_f32_e32 v39, 0.5, v39
	v_add_f32_e32 v40, 1.0, v40
	v_mul_f32_e32 v38, v38, v44
	v_mul_f32_e32 v39, v39, v40
	v_cvt_pk_bf16_f32 v36, v36, v37
	v_cvt_pk_bf16_f32 v37, v38, v39
	global_store_dwordx2 v[48:49], v[36:37], off offset:256 sc1
	global_load_dwordx4 v[36:39], v[144:145], off offset:576
	s_waitcnt vmcnt(0)
	v_pk_add_f32 v[32:33], v[32:33], v[36:37]
	s_nop 0
	v_mul_f32_e32 v36, 0x3d372713, v32
	v_mul_f32_e32 v36, v32, v36
	v_fma_f32 v36, v32, v36, v32
	v_mul_f32_e32 v36, 0x3f4c422a, v36
	v_cmp_nlt_f32_e64 s[58:59], |v36|, s40
	s_and_saveexec_b64 s[60:61], s[58:59]
	s_xor_b64 s[72:73], exec, s[60:61]
	s_cbranch_execz .LBB0_2919
	v_add_f32_e64 v37, |v36|, |v36|
	v_mul_f32_e32 v40, 0x3fb8aa3b, v37
	v_rndne_f32_e32 v41, v40
	v_sub_f32_e32 v42, v40, v41
	v_fma_f32 v40, v37, s42, -v40
	v_fmac_f32_e32 v40, 0x32a5705f, v37
	v_add_f32_e32 v40, v42, v40
	v_cvt_i32_f32_e32 v41, v41
	v_exp_f32_e32 v40, v40
	v_cmp_ngt_f32_e32 vcc, s43, v37
	v_ldexp_f32 v40, v40, v41
	s_nop 0
	v_cndmask_b32_e32 v40, 0, v40, vcc
	v_cmp_nlt_f32_e32 vcc, s44, v37
	s_nop 1
	v_cndmask_b32_e32 v37, v156, v40, vcc
	v_add_f32_e32 v37, 1.0, v37
	v_rcp_f32_e32 v37, v37
	s_nop 0
	v_fma_f32 v37, v37, -2.0, 1.0

.LBB0_2931:
	s_andn2_saveexec_b64 s[72:73], s[72:73]
	v_mul_f32_e32 v43, v42, v42
	v_fmamk_f32 v44, v43, 0xbbbac73d, v153
	v_fmaak_f32 v44, v43, v44, 0xbd5c1c4e
	v_fmaak_f32 v44, v43, v44, 0x3e088382
	v_fmaak_f32 v44, v43, v44, 0xbeaaaa99
	v_mul_f32_e64 v44, |v42|, v44
	v_fma_f32 v43, v43, v44, |v42|
	s_or_b64 exec, exec, s[72:73]
	v_bfi_b32 v36, s45, v37, v36
	v_mul_f32_e32 v32, 0.5, v32
	v_add_f32_e32 v36, 1.0, v36
	v_mul_f32_e32 v32, v32, v36
	v_bfi_b32 v36, s45, v39, v38
	v_mul_f32_e32 v33, 0.5, v33
	v_add_f32_e32 v36, 1.0, v36
	v_bfi_b32 v40, s45, v41, v40
	v_mul_f32_e32 v33, v33, v36
	v_bfi_b32 v36, s45, v43, v42
	v_mul_f32_e32 v34, 0.5, v34
	v_add_f32_e32 v40, 1.0, v40
	v_mul_f32_e32 v35, 0.5, v35
	v_add_f32_e32 v36, 1.0, v36
	v_mul_f32_e32 v34, v34, v40
	v_mul_f32_e32 v35, v35, v36
	v_cvt_pk_bf16_f32 v32, v32, v33
	v_cvt_pk_bf16_f32 v33, v34, v35
	global_store_dwordx2 v[48:49], v[32:33], off offset:288 sc1
	global_load_dwordx4 v[32:35], v[144:145], off
	s_waitcnt vmcnt(0)
	v_pk_add_f32 v[28:29], v[28:29], v[32:33]
	s_nop 0
	v_mul_f32_e32 v32, 0x3d372713, v28
	v_mul_f32_e32 v32, v28, v32
	v_fma_f32 v32, v28, v32, v28
	v_mul_f32_e32 v32, 0x3f4c422a, v32
	v_cmp_nlt_f32_e64 s[58:59], |v32|, s40
	s_and_saveexec_b64 s[60:61], s[58:59]
	s_xor_b64 s[72:73], exec, s[60:61]
	s_cbranch_execz .LBB0_2935
	v_add_f32_e64 v33, |v32|, |v32|
	v_mul_f32_e32 v36, 0x3fb8aa3b, v33
	v_rndne_f32_e32 v37, v36
	v_sub_f32_e32 v38, v36, v37
	v_fma_f32 v36, v33, s42, -v36
	v_fmac_f32_e32 v36, 0x32a5705f, v33
	v_add_f32_e32 v36, v38, v36
	v_cvt_i32_f32_e32 v37, v37
	v_exp_f32_e32 v36, v36
	v_cmp_ngt_f32_e32 vcc, s43, v33
	v_ldexp_f32 v36, v36, v37
	s_nop 0
	v_cndmask_b32_e32 v36, 0, v36, vcc
	v_cmp_nlt_f32_e32 vcc, s44, v33
	s_nop 1
	v_cndmask_b32_e32 v33, v156, v36, vcc
	v_add_f32_e32 v33, 1.0, v33
	v_rcp_f32_e32 v33, v33
	s_nop 0
	v_fma_f32 v33, v33, -2.0, 1.0

.LBB0_2947:
	s_andn2_saveexec_b64 s[72:73], s[72:73]
	v_mul_f32_e32 v39, v38, v38
	v_fmamk_f32 v40, v39, 0xbbbac73d, v153
	v_fmaak_f32 v40, v39, v40, 0xbd5c1c4e
	v_fmaak_f32 v40, v39, v40, 0x3e088382
	v_fmaak_f32 v40, v39, v40, 0xbeaaaa99
	v_mul_f32_e64 v40, |v38|, v40
	v_fma_f32 v39, v39, v40, |v38|
	s_or_b64 exec, exec, s[72:73]
	v_bfi_b32 v36, s45, v37, v36
	v_mul_f32_e32 v30, 0.5, v30
	v_add_f32_e32 v36, 1.0, v36
	v_mul_f32_e32 v36, v30, v36
	v_mul_f32_e32 v30, 0.5, v31
	v_bfi_b32 v31, s45, v33, v32
	v_mul_f32_e32 v28, 0.5, v28
	v_add_f32_e32 v31, 1.0, v31
	v_mul_f32_e32 v31, v28, v31
	v_mul_f32_e32 v28, 0.5, v29
	v_bfi_b32 v29, s45, v35, v34
	v_add_f32_e32 v29, 1.0, v29
	v_mul_f32_e32 v32, v28, v29
	v_add_u32_e32 v28, 0xa0, v128
	v_ashrrev_i32_e32 v29, 31, v28
	v_bfi_b32 v33, s45, v39, v38
	v_lshlrev_b64 v[28:29], 9, v[28:29]
	v_add_f32_e32 v33, 1.0, v33
	v_mul_f32_e32 v33, v30, v33
	v_lshl_add_u64 v[28:29], s[18:19], 0, v[28:29]
	v_cvt_pk_bf16_f32 v30, v31, v32
	v_cvt_pk_bf16_f32 v31, v36, v33
	v_lshl_add_u64 v[32:33], v[146:147], 1, v[28:29]
	global_store_dwordx2 v[32:33], v[30:31], off sc1
	global_load_dwordx4 v[28:31], v[144:145], off offset:64
	s_waitcnt vmcnt(0)
	v_pk_add_f32 v[24:25], v[24:25], v[28:29]
	s_nop 0
	v_mul_f32_e32 v28, 0x3d372713, v24
	v_mul_f32_e32 v28, v24, v28
	v_fma_f32 v28, v24, v28, v24
	v_mul_f32_e32 v28, 0x3f4c422a, v28
	v_cmp_nlt_f32_e64 s[58:59], |v28|, s40
	s_and_saveexec_b64 s[60:61], s[58:59]
	s_xor_b64 s[72:73], exec, s[60:61]
	s_cbranch_execz .LBB0_2951
	v_add_f32_e64 v29, |v28|, |v28|
	v_mul_f32_e32 v34, 0x3fb8aa3b, v29
	v_rndne_f32_e32 v35, v34
	v_sub_f32_e32 v36, v34, v35
	v_fma_f32 v34, v29, s42, -v34
	v_fmac_f32_e32 v34, 0x32a5705f, v29
	v_add_f32_e32 v34, v36, v34
	v_cvt_i32_f32_e32 v35, v35
	v_exp_f32_e32 v34, v34
	v_cmp_ngt_f32_e32 vcc, s43, v29
	v_ldexp_f32 v34, v34, v35
	s_nop 0
	v_cndmask_b32_e32 v34, 0, v34, vcc
	v_cmp_nlt_f32_e32 vcc, s44, v29
	s_nop 1
	v_cndmask_b32_e32 v29, v156, v34, vcc
	v_add_f32_e32 v29, 1.0, v29
	v_rcp_f32_e32 v29, v29
	s_nop 0
	v_fma_f32 v29, v29, -2.0, 1.0

.LBB0_2963:
	s_andn2_saveexec_b64 s[72:73], s[72:73]
	v_mul_f32_e32 v37, v36, v36
	v_fmamk_f32 v38, v37, 0xbbbac73d, v153
	v_fmaak_f32 v38, v37, v38, 0xbd5c1c4e
	v_fmaak_f32 v38, v37, v38, 0x3e088382
	v_fmaak_f32 v38, v37, v38, 0xbeaaaa99
	v_mul_f32_e64 v38, |v36|, v38
	v_fma_f32 v37, v37, v38, |v36|
	s_or_b64 exec, exec, s[72:73]
	v_bfi_b32 v28, s45, v29, v28
	v_mul_f32_e32 v24, 0.5, v24
	v_add_f32_e32 v28, 1.0, v28
	v_mul_f32_e32 v24, v24, v28
	v_bfi_b32 v28, s45, v31, v30
	v_mul_f32_e32 v25, 0.5, v25
	v_add_f32_e32 v28, 1.0, v28
	v_bfi_b32 v34, s45, v35, v34
	v_mul_f32_e32 v25, v25, v28
	v_bfi_b32 v28, s45, v37, v36
	v_mul_f32_e32 v26, 0.5, v26
	v_add_f32_e32 v34, 1.0, v34
	v_mul_f32_e32 v27, 0.5, v27
	v_add_f32_e32 v28, 1.0, v28
	v_mul_f32_e32 v26, v26, v34
	v_mul_f32_e32 v27, v27, v28
	v_cvt_pk_bf16_f32 v24, v24, v25
	v_cvt_pk_bf16_f32 v25, v26, v27
	global_store_dwordx2 v[32:33], v[24:25], off offset:32 sc1
	global_load_dwordx4 v[24:27], v[144:145], off offset:512
	s_waitcnt vmcnt(0)
	v_pk_add_f32 v[20:21], v[20:21], v[24:25]
	s_nop 0
	v_mul_f32_e32 v24, 0x3d372713, v20
	v_mul_f32_e32 v24, v20, v24
	v_fma_f32 v24, v20, v24, v20
	v_mul_f32_e32 v24, 0x3f4c422a, v24
	v_cmp_nlt_f32_e64 s[58:59], |v24|, s40
	s_and_saveexec_b64 s[60:61], s[58:59]
	s_xor_b64 s[72:73], exec, s[60:61]
	s_cbranch_execz .LBB0_2967
	v_add_f32_e64 v25, |v24|, |v24|
	v_mul_f32_e32 v28, 0x3fb8aa3b, v25
	v_rndne_f32_e32 v29, v28
	v_sub_f32_e32 v30, v28, v29
	v_fma_f32 v28, v25, s42, -v28
	v_fmac_f32_e32 v28, 0x32a5705f, v25
	v_add_f32_e32 v28, v30, v28
	v_cvt_i32_f32_e32 v29, v29
	v_exp_f32_e32 v28, v28
	v_cmp_ngt_f32_e32 vcc, s43, v25
	v_ldexp_f32 v28, v28, v29
	s_nop 0
	v_cndmask_b32_e32 v28, 0, v28, vcc
	v_cmp_nlt_f32_e32 vcc, s44, v25
	s_nop 1
	v_cndmask_b32_e32 v25, v156, v28, vcc
	v_add_f32_e32 v25, 1.0, v25
	v_rcp_f32_e32 v25, v25
	s_nop 0
	v_fma_f32 v25, v25, -2.0, 1.0

.LBB0_2979:
	s_andn2_saveexec_b64 s[72:73], s[72:73]
	v_mul_f32_e32 v31, v30, v30
	v_fmamk_f32 v34, v31, 0xbbbac73d, v153
	v_fmaak_f32 v34, v31, v34, 0xbd5c1c4e
	v_fmaak_f32 v34, v31, v34, 0x3e088382
	v_fmaak_f32 v34, v31, v34, 0xbeaaaa99
	v_mul_f32_e64 v34, |v30|, v34
	v_fma_f32 v31, v31, v34, |v30|
	s_or_b64 exec, exec, s[72:73]
	v_bfi_b32 v24, s45, v25, v24
	v_mul_f32_e32 v20, 0.5, v20
	v_add_f32_e32 v24, 1.0, v24
	v_mul_f32_e32 v20, v20, v24
	v_bfi_b32 v24, s45, v27, v26
	v_mul_f32_e32 v21, 0.5, v21
	v_add_f32_e32 v24, 1.0, v24
	v_bfi_b32 v28, s45, v29, v28
	v_mul_f32_e32 v21, v21, v24
	v_bfi_b32 v24, s45, v31, v30
	v_mul_f32_e32 v22, 0.5, v22
	v_add_f32_e32 v28, 1.0, v28
	v_mul_f32_e32 v23, 0.5, v23
	v_add_f32_e32 v24, 1.0, v24
	v_mul_f32_e32 v22, v22, v28
	v_mul_f32_e32 v23, v23, v24
	v_cvt_pk_bf16_f32 v20, v20, v21
	v_cvt_pk_bf16_f32 v21, v22, v23
	global_store_dwordx2 v[32:33], v[20:21], off offset:256 sc1
	global_load_dwordx4 v[20:23], v[144:145], off offset:576
	s_waitcnt vmcnt(0)
	v_pk_add_f32 v[16:17], v[16:17], v[20:21]
	s_nop 0
	v_mul_f32_e32 v20, 0x3d372713, v16
	v_mul_f32_e32 v20, v16, v20
	v_fma_f32 v20, v16, v20, v16
	v_mul_f32_e32 v20, 0x3f4c422a, v20
	v_cmp_nlt_f32_e64 s[58:59], |v20|, s40
	s_and_saveexec_b64 s[60:61], s[58:59]
	s_xor_b64 s[72:73], exec, s[60:61]
	s_cbranch_execz .LBB0_2983
	v_add_f32_e64 v21, |v20|, |v20|
	v_mul_f32_e32 v24, 0x3fb8aa3b, v21
	v_rndne_f32_e32 v25, v24
	v_sub_f32_e32 v26, v24, v25
	v_fma_f32 v24, v21, s42, -v24
	v_fmac_f32_e32 v24, 0x32a5705f, v21
	v_add_f32_e32 v24, v26, v24
	v_cvt_i32_f32_e32 v25, v25
	v_exp_f32_e32 v24, v24
	v_cmp_ngt_f32_e32 vcc, s43, v21
	v_ldexp_f32 v24, v24, v25
	s_nop 0
	v_cndmask_b32_e32 v24, 0, v24, vcc
	v_cmp_nlt_f32_e32 vcc, s44, v21
	s_nop 1
	v_cndmask_b32_e32 v21, v156, v24, vcc
	v_add_f32_e32 v21, 1.0, v21
	v_rcp_f32_e32 v21, v21
	s_nop 0
	v_fma_f32 v21, v21, -2.0, 1.0

.LBB0_2995:
	s_andn2_saveexec_b64 s[72:73], s[72:73]
	v_mul_f32_e32 v27, v26, v26
	v_fmamk_f32 v28, v27, 0xbbbac73d, v153
	v_fmaak_f32 v28, v27, v28, 0xbd5c1c4e
	v_fmaak_f32 v28, v27, v28, 0x3e088382
	v_fmaak_f32 v28, v27, v28, 0xbeaaaa99
	v_mul_f32_e64 v28, |v26|, v28
	v_fma_f32 v27, v27, v28, |v26|
	s_or_b64 exec, exec, s[72:73]
	v_bfi_b32 v20, s45, v21, v20
	v_mul_f32_e32 v16, 0.5, v16
	v_add_f32_e32 v20, 1.0, v20
	v_mul_f32_e32 v16, v16, v20
	v_bfi_b32 v20, s45, v23, v22
	v_mul_f32_e32 v17, 0.5, v17
	v_add_f32_e32 v20, 1.0, v20
	v_bfi_b32 v24, s45, v25, v24
	v_mul_f32_e32 v17, v17, v20
	v_bfi_b32 v20, s45, v27, v26
	v_mul_f32_e32 v18, 0.5, v18
	v_add_f32_e32 v24, 1.0, v24
	v_mul_f32_e32 v19, 0.5, v19
	v_add_f32_e32 v20, 1.0, v20
	v_mul_f32_e32 v18, v18, v24
	v_mul_f32_e32 v19, v19, v20
	v_cvt_pk_bf16_f32 v16, v16, v17
	v_cvt_pk_bf16_f32 v17, v18, v19
	global_store_dwordx2 v[32:33], v[16:17], off offset:288 sc1
	global_load_dwordx4 v[16:19], v[144:145], off
	s_waitcnt vmcnt(0)
	v_pk_add_f32 v[12:13], v[12:13], v[16:17]
	s_nop 0
	v_mul_f32_e32 v16, 0x3d372713, v12
	v_mul_f32_e32 v16, v12, v16
	v_fma_f32 v16, v12, v16, v12
	v_mul_f32_e32 v16, 0x3f4c422a, v16
	v_cmp_nlt_f32_e64 s[58:59], |v16|, s40
	s_and_saveexec_b64 s[60:61], s[58:59]
	s_xor_b64 s[72:73], exec, s[60:61]
	s_cbranch_execz .LBB0_2999
	v_add_f32_e64 v17, |v16|, |v16|
	v_mul_f32_e32 v20, 0x3fb8aa3b, v17
	v_rndne_f32_e32 v21, v20
	v_sub_f32_e32 v22, v20, v21
	v_fma_f32 v20, v17, s42, -v20
	v_fmac_f32_e32 v20, 0x32a5705f, v17
	v_add_f32_e32 v20, v22, v20
	v_cvt_i32_f32_e32 v21, v21
	v_exp_f32_e32 v20, v20
	v_cmp_ngt_f32_e32 vcc, s43, v17
	v_ldexp_f32 v20, v20, v21
	s_nop 0
	v_cndmask_b32_e32 v20, 0, v20, vcc
	v_cmp_nlt_f32_e32 vcc, s44, v17
	s_nop 1
	v_cndmask_b32_e32 v17, v156, v20, vcc
	v_add_f32_e32 v17, 1.0, v17
	v_rcp_f32_e32 v17, v17
	s_nop 0
	v_fma_f32 v17, v17, -2.0, 1.0

.LBB0_3011:
	s_andn2_saveexec_b64 s[72:73], s[72:73]
	v_mul_f32_e32 v23, v22, v22
	v_fmamk_f32 v24, v23, 0xbbbac73d, v153
	v_fmaak_f32 v24, v23, v24, 0xbd5c1c4e
	v_fmaak_f32 v24, v23, v24, 0x3e088382
	v_fmaak_f32 v24, v23, v24, 0xbeaaaa99
	v_mul_f32_e64 v24, |v22|, v24
	v_fma_f32 v23, v23, v24, |v22|
	s_or_b64 exec, exec, s[72:73]
	v_bfi_b32 v20, s45, v21, v20
	v_mul_f32_e32 v14, 0.5, v14
	v_add_f32_e32 v20, 1.0, v20
	v_mul_f32_e32 v20, v14, v20
	v_mul_f32_e32 v14, 0.5, v15
	v_bfi_b32 v15, s45, v17, v16
	v_mul_f32_e32 v12, 0.5, v12
	v_add_f32_e32 v15, 1.0, v15
	v_mul_f32_e32 v15, v12, v15
	v_mul_f32_e32 v12, 0.5, v13
	v_bfi_b32 v13, s45, v19, v18
	v_add_f32_e32 v13, 1.0, v13
	v_mul_f32_e32 v16, v12, v13
	v_add_u32_e32 v12, 0xb0, v128
	v_ashrrev_i32_e32 v13, 31, v12
	v_bfi_b32 v17, s45, v23, v22
	v_lshlrev_b64 v[12:13], 9, v[12:13]
	v_add_f32_e32 v17, 1.0, v17
	v_mul_f32_e32 v17, v14, v17
	v_lshl_add_u64 v[12:13], s[18:19], 0, v[12:13]
	v_cvt_pk_bf16_f32 v14, v15, v16
	v_cvt_pk_bf16_f32 v15, v20, v17
	v_lshl_add_u64 v[16:17], v[146:147], 1, v[12:13]
	global_store_dwordx2 v[16:17], v[14:15], off sc1
	global_load_dwordx4 v[12:15], v[144:145], off offset:64
	s_waitcnt vmcnt(0)
	v_pk_add_f32 v[8:9], v[8:9], v[12:13]
	s_nop 0
	v_mul_f32_e32 v12, 0x3d372713, v8
	v_mul_f32_e32 v12, v8, v12
	v_fma_f32 v12, v8, v12, v8
	v_mul_f32_e32 v12, 0x3f4c422a, v12
	v_cmp_nlt_f32_e64 s[58:59], |v12|, s40
	s_and_saveexec_b64 s[60:61], s[58:59]
	s_xor_b64 s[72:73], exec, s[60:61]
	s_cbranch_execz .LBB0_3015
	v_add_f32_e64 v13, |v12|, |v12|
	v_mul_f32_e32 v18, 0x3fb8aa3b, v13
	v_rndne_f32_e32 v19, v18
	v_sub_f32_e32 v20, v18, v19
	v_fma_f32 v18, v13, s42, -v18
	v_fmac_f32_e32 v18, 0x32a5705f, v13
	v_add_f32_e32 v18, v20, v18
	v_cvt_i32_f32_e32 v19, v19
	v_exp_f32_e32 v18, v18
	v_cmp_ngt_f32_e32 vcc, s43, v13
	v_ldexp_f32 v18, v18, v19
	s_nop 0
	v_cndmask_b32_e32 v18, 0, v18, vcc
	v_cmp_nlt_f32_e32 vcc, s44, v13
	s_nop 1
	v_cndmask_b32_e32 v13, v156, v18, vcc
	v_add_f32_e32 v13, 1.0, v13
	v_rcp_f32_e32 v13, v13
	s_nop 0
	v_fma_f32 v13, v13, -2.0, 1.0

.LBB0_3027:
	s_andn2_saveexec_b64 s[72:73], s[72:73]
	v_mul_f32_e32 v21, v20, v20
	v_fmamk_f32 v22, v21, 0xbbbac73d, v153
	v_fmaak_f32 v22, v21, v22, 0xbd5c1c4e
	v_fmaak_f32 v22, v21, v22, 0x3e088382
	v_fmaak_f32 v22, v21, v22, 0xbeaaaa99
	v_mul_f32_e64 v22, |v20|, v22
	v_fma_f32 v21, v21, v22, |v20|
	s_or_b64 exec, exec, s[72:73]
	v_bfi_b32 v12, s45, v13, v12
	v_mul_f32_e32 v8, 0.5, v8
	v_add_f32_e32 v12, 1.0, v12
	v_mul_f32_e32 v8, v8, v12
	v_bfi_b32 v12, s45, v15, v14
	v_mul_f32_e32 v9, 0.5, v9
	v_add_f32_e32 v12, 1.0, v12
	v_bfi_b32 v18, s45, v19, v18
	v_mul_f32_e32 v9, v9, v12
	v_bfi_b32 v12, s45, v21, v20
	v_mul_f32_e32 v10, 0.5, v10
	v_add_f32_e32 v18, 1.0, v18
	v_mul_f32_e32 v11, 0.5, v11
	v_add_f32_e32 v12, 1.0, v12
	v_mul_f32_e32 v10, v10, v18
	v_mul_f32_e32 v11, v11, v12
	v_cvt_pk_bf16_f32 v8, v8, v9
	v_cvt_pk_bf16_f32 v9, v10, v11
	global_store_dwordx2 v[16:17], v[8:9], off offset:32 sc1
	global_load_dwordx4 v[8:11], v[144:145], off offset:512
	s_waitcnt vmcnt(0)
	v_pk_add_f32 v[4:5], v[4:5], v[8:9]
	s_nop 0
	v_mul_f32_e32 v8, 0x3d372713, v4
	v_mul_f32_e32 v8, v4, v8
	v_fma_f32 v8, v4, v8, v4
	v_mul_f32_e32 v8, 0x3f4c422a, v8
	v_cmp_nlt_f32_e64 s[58:59], |v8|, s40
	s_and_saveexec_b64 s[60:61], s[58:59]
	s_xor_b64 s[72:73], exec, s[60:61]
	s_cbranch_execz .LBB0_3031
	v_add_f32_e64 v9, |v8|, |v8|
	v_mul_f32_e32 v12, 0x3fb8aa3b, v9
	v_rndne_f32_e32 v13, v12
	v_sub_f32_e32 v14, v12, v13
	v_fma_f32 v12, v9, s42, -v12
	v_fmac_f32_e32 v12, 0x32a5705f, v9
	v_add_f32_e32 v12, v14, v12
	v_cvt_i32_f32_e32 v13, v13
	v_exp_f32_e32 v12, v12
	v_cmp_ngt_f32_e32 vcc, s43, v9
	v_ldexp_f32 v12, v12, v13
	s_nop 0
	v_cndmask_b32_e32 v12, 0, v12, vcc
	v_cmp_nlt_f32_e32 vcc, s44, v9
	s_nop 1
	v_cndmask_b32_e32 v9, v156, v12, vcc
	v_add_f32_e32 v9, 1.0, v9
	v_rcp_f32_e32 v9, v9
	s_nop 0
	v_fma_f32 v9, v9, -2.0, 1.0

.LBB0_3043:
	s_andn2_saveexec_b64 s[72:73], s[72:73]
	v_mul_f32_e32 v15, v14, v14
	v_fmamk_f32 v18, v15, 0xbbbac73d, v153
	v_fmaak_f32 v18, v15, v18, 0xbd5c1c4e
	v_fmaak_f32 v18, v15, v18, 0x3e088382
	v_fmaak_f32 v18, v15, v18, 0xbeaaaa99
	v_mul_f32_e64 v18, |v14|, v18
	v_fma_f32 v15, v15, v18, |v14|
	s_or_b64 exec, exec, s[72:73]
	v_bfi_b32 v8, s45, v9, v8
	v_mul_f32_e32 v4, 0.5, v4
	v_add_f32_e32 v8, 1.0, v8
	v_mul_f32_e32 v4, v4, v8
	v_bfi_b32 v8, s45, v11, v10
	v_mul_f32_e32 v5, 0.5, v5
	v_add_f32_e32 v8, 1.0, v8
	v_bfi_b32 v12, s45, v13, v12
	v_mul_f32_e32 v5, v5, v8
	v_bfi_b32 v8, s45, v15, v14
	v_mul_f32_e32 v6, 0.5, v6
	v_add_f32_e32 v12, 1.0, v12
	v_mul_f32_e32 v7, 0.5, v7
	v_add_f32_e32 v8, 1.0, v8
	v_mul_f32_e32 v6, v6, v12
	v_mul_f32_e32 v7, v7, v8
	v_cvt_pk_bf16_f32 v4, v4, v5
	v_cvt_pk_bf16_f32 v5, v6, v7
	global_store_dwordx2 v[16:17], v[4:5], off offset:256 sc1
	global_load_dwordx4 v[4:7], v[144:145], off offset:576
	s_waitcnt vmcnt(0)
	v_pk_add_f32 v[0:1], v[0:1], v[4:5]
	s_nop 0
	v_mul_f32_e32 v4, 0x3d372713, v0
	v_mul_f32_e32 v4, v0, v4
	v_fma_f32 v4, v0, v4, v0
	v_mul_f32_e32 v4, 0x3f4c422a, v4
	v_cmp_nlt_f32_e64 s[58:59], |v4|, s40
	s_and_saveexec_b64 s[60:61], s[58:59]
	s_xor_b64 s[72:73], exec, s[60:61]
	s_cbranch_execz .LBB0_3047
	v_add_f32_e64 v5, |v4|, |v4|
	v_mul_f32_e32 v8, 0x3fb8aa3b, v5
	v_rndne_f32_e32 v9, v8
	v_sub_f32_e32 v10, v8, v9
	v_fma_f32 v8, v5, s42, -v8
	v_fmac_f32_e32 v8, 0x32a5705f, v5
	v_add_f32_e32 v8, v10, v8
	v_cvt_i32_f32_e32 v9, v9
	v_exp_f32_e32 v8, v8
	v_cmp_ngt_f32_e32 vcc, s43, v5
	v_ldexp_f32 v8, v8, v9
	s_nop 0
	v_cndmask_b32_e32 v8, 0, v8, vcc
	v_cmp_nlt_f32_e32 vcc, s44, v5
	s_nop 1
	v_cndmask_b32_e32 v5, v156, v8, vcc
	v_add_f32_e32 v5, 1.0, v5
	v_rcp_f32_e32 v5, v5
	s_nop 0
	v_fma_f32 v5, v5, -2.0, 1.0

.LBB0_3059:
	s_andn2_saveexec_b64 s[72:73], s[72:73]
	v_mul_f32_e32 v11, v10, v10
	v_fmamk_f32 v12, v11, 0xbbbac73d, v153
	v_fmaak_f32 v12, v11, v12, 0xbd5c1c4e
	v_fmaak_f32 v12, v11, v12, 0x3e088382
	v_fmaak_f32 v12, v11, v12, 0xbeaaaa99
	v_mul_f32_e64 v12, |v10|, v12
	v_fma_f32 v11, v11, v12, |v10|
	s_or_b64 exec, exec, s[72:73]
	v_bfi_b32 v7, s45, v7, v6
	v_bfi_b32 v6, s45, v5, v4
	v_pk_mul_f32 v[0:1], v[0:1], 0.5 op_sel_hi:[1,0]
	v_pk_add_f32 v[4:5], v[6:7], 1.0 op_sel_hi:[1,0]
	v_pk_mul_f32 v[2:3], v[2:3], 0.5 op_sel_hi:[1,0]
	v_pk_mul_f32 v[0:1], v[0:1], v[4:5]
	v_bfi_b32 v5, s45, v11, v10
	v_bfi_b32 v4, s45, v9, v8
	v_pk_add_f32 v[4:5], v[4:5], 1.0 op_sel_hi:[1,0]
	v_cvt_pk_bf16_f32 v0, v0, v1
	v_pk_mul_f32 v[2:3], v[2:3], v[4:5]
	s_andn2_b64 vcc, exec, s[56:57]
	v_cvt_pk_bf16_f32 v1, v2, v3
	s_mov_b64 s[56:57], -1
	global_store_dwordx2 v[16:17], v[0:1], off offset:288 sc1
	s_cbranch_vccnz .LBB0_2538
	s_andn2_b64 vcc, exec, s[20:21]
	s_cbranch_vccnz .LBB0_2537
	s_barrier
	s_branch .LBB0_2537

.LBB0_3101:
	s_andn2_saveexec_b64 s[76:77], s[76:77]
	v_mul_f32_e32 v162, v159, v159
	v_fmamk_f32 v163, v162, 0xbbbac73d, v153
	v_fmaak_f32 v163, v162, v163, 0xbd5c1c4e
	v_fmaak_f32 v163, v162, v163, 0x3e088382
	v_fmaak_f32 v163, v162, v163, 0xbeaaaa99
	v_mul_f32_e64 v163, |v159|, v163
	v_fma_f32 v162, v162, v163, |v159|
	s_or_b64 exec, exec, s[76:77]
	v_bfi_b32 v157, s48, v158, v157
	v_mul_f32_e32 v126, 0.5, v126
	v_add_f32_e32 v157, 1.0, v157
	v_mul_f32_e32 v157, v126, v157
	v_mul_f32_e32 v126, 0.5, v127
	v_bfi_b32 v127, s48, v129, v128
	v_mul_f32_e32 v124, 0.5, v124
	v_add_f32_e32 v127, 1.0, v127
	v_mul_f32_e32 v127, v124, v127
	v_mul_f32_e32 v124, 0.5, v125
	v_bfi_b32 v125, s48, v131, v130
	v_lshl_add_u32 v128, s74, 8, v148
	v_add_f32_e32 v125, 1.0, v125
	v_ashrrev_i32_e32 v129, 31, v128
	v_mul_f32_e32 v130, v124, v125
	v_lshlrev_b64 v[124:125], 9, v[128:129]
	v_bfi_b32 v129, s48, v162, v159
	v_add_f32_e32 v129, 1.0, v129
	v_mul_f32_e32 v129, v126, v129
	v_lshl_add_u64 v[124:125], s[20:21], 0, v[124:125]
	v_cvt_pk_bf16_f32 v126, v127, v130
	v_cvt_pk_bf16_f32 v127, v157, v129
	v_lshl_add_u64 v[130:131], v[146:147], 1, v[124:125]
	global_store_dwordx2 v[130:131], v[126:127], off sc1
	global_load_dwordx4 v[124:127], v[144:145], off offset:64
	s_waitcnt vmcnt(0)
	v_pk_add_f32 v[120:121], v[120:121], v[124:125]
	s_nop 0
	v_mul_f32_e32 v124, 0x3d372713, v120
	v_mul_f32_e32 v124, v120, v124
	v_fma_f32 v124, v120, v124, v120
	v_mul_f32_e32 v124, 0x3f4c422a, v124
	v_cmp_nlt_f32_e64 s[58:59], |v124|, s44
	s_and_saveexec_b64 s[60:61], s[58:59]
	s_xor_b64 s[74:75], exec, s[60:61]
	s_cbranch_execz .LBB0_3105
	v_add_f32_e64 v125, |v124|, |v124|
	v_mul_f32_e32 v129, 0x3fb8aa3b, v125
	v_rndne_f32_e32 v157, v129
	v_sub_f32_e32 v158, v129, v157
	v_fma_f32 v129, v125, s45, -v129
	v_fmac_f32_e32 v129, 0x32a5705f, v125
	v_add_f32_e32 v129, v158, v129
	v_cvt_i32_f32_e32 v157, v157
	v_exp_f32_e32 v129, v129
	v_cmp_ngt_f32_e32 vcc, s46, v125
	v_ldexp_f32 v129, v129, v157
	s_nop 0
	v_cndmask_b32_e32 v129, 0, v129, vcc
	v_cmp_nlt_f32_e32 vcc, s47, v125
	s_nop 1
	v_cndmask_b32_e32 v125, v156, v129, vcc
	v_add_f32_e32 v125, 1.0, v125
	v_rcp_f32_e32 v125, v125
	s_nop 0
	v_fma_f32 v125, v125, -2.0, 1.0

.LBB0_3117:
	s_andn2_saveexec_b64 s[74:75], s[74:75]
	v_mul_f32_e32 v159, v158, v158
	v_fmamk_f32 v162, v159, 0xbbbac73d, v153
	v_fmaak_f32 v162, v159, v162, 0xbd5c1c4e
	v_fmaak_f32 v162, v159, v162, 0x3e088382
	v_fmaak_f32 v162, v159, v162, 0xbeaaaa99
	v_mul_f32_e64 v162, |v158|, v162
	v_fma_f32 v159, v159, v162, |v158|
	s_or_b64 exec, exec, s[74:75]
	v_bfi_b32 v124, s48, v125, v124
	v_mul_f32_e32 v120, 0.5, v120
	v_add_f32_e32 v124, 1.0, v124
	v_mul_f32_e32 v120, v120, v124
	v_bfi_b32 v124, s48, v127, v126
	v_mul_f32_e32 v121, 0.5, v121
	v_add_f32_e32 v124, 1.0, v124
	v_bfi_b32 v129, s48, v157, v129
	v_mul_f32_e32 v121, v121, v124
	v_bfi_b32 v124, s48, v159, v158
	v_mul_f32_e32 v122, 0.5, v122
	v_add_f32_e32 v129, 1.0, v129
	v_mul_f32_e32 v123, 0.5, v123
	v_add_f32_e32 v124, 1.0, v124
	v_mul_f32_e32 v122, v122, v129
	v_mul_f32_e32 v123, v123, v124
	v_cvt_pk_bf16_f32 v120, v120, v121
	v_cvt_pk_bf16_f32 v121, v122, v123
	global_store_dwordx2 v[130:131], v[120:121], off offset:32 sc1
	global_load_dwordx4 v[120:123], v[144:145], off offset:512
	s_waitcnt vmcnt(0)
	v_pk_add_f32 v[116:117], v[116:117], v[120:121]
	s_nop 0
	v_mul_f32_e32 v120, 0x3d372713, v116
	v_mul_f32_e32 v120, v116, v120
	v_fma_f32 v120, v116, v120, v116
	v_mul_f32_e32 v120, 0x3f4c422a, v120
	v_cmp_nlt_f32_e64 s[58:59], |v120|, s44
	s_and_saveexec_b64 s[60:61], s[58:59]
	s_xor_b64 s[74:75], exec, s[60:61]
	s_cbranch_execz .LBB0_3121
	v_add_f32_e64 v121, |v120|, |v120|
	v_mul_f32_e32 v124, 0x3fb8aa3b, v121
	v_rndne_f32_e32 v125, v124
	v_sub_f32_e32 v126, v124, v125
	v_fma_f32 v124, v121, s45, -v124
	v_fmac_f32_e32 v124, 0x32a5705f, v121
	v_add_f32_e32 v124, v126, v124
	v_cvt_i32_f32_e32 v125, v125
	v_exp_f32_e32 v124, v124
	v_cmp_ngt_f32_e32 vcc, s46, v121
	v_ldexp_f32 v124, v124, v125
	s_nop 0
	v_cndmask_b32_e32 v124, 0, v124, vcc
	v_cmp_nlt_f32_e32 vcc, s47, v121
	s_nop 1
	v_cndmask_b32_e32 v121, v156, v124, vcc
	v_add_f32_e32 v121, 1.0, v121
	v_rcp_f32_e32 v121, v121
	s_nop 0
	v_fma_f32 v121, v121, -2.0, 1.0

.LBB0_3133:
	s_andn2_saveexec_b64 s[74:75], s[74:75]
	v_mul_f32_e32 v127, v126, v126
	v_fmamk_f32 v129, v127, 0xbbbac73d, v153
	v_fmaak_f32 v129, v127, v129, 0xbd5c1c4e
	v_fmaak_f32 v129, v127, v129, 0x3e088382
	v_fmaak_f32 v129, v127, v129, 0xbeaaaa99
	v_mul_f32_e64 v129, |v126|, v129
	v_fma_f32 v127, v127, v129, |v126|
	s_or_b64 exec, exec, s[74:75]
	v_bfi_b32 v120, s48, v121, v120
	v_mul_f32_e32 v116, 0.5, v116
	v_add_f32_e32 v120, 1.0, v120
	v_mul_f32_e32 v116, v116, v120
	v_bfi_b32 v120, s48, v123, v122
	v_mul_f32_e32 v117, 0.5, v117
	v_add_f32_e32 v120, 1.0, v120
	v_bfi_b32 v124, s48, v125, v124
	v_mul_f32_e32 v117, v117, v120
	v_bfi_b32 v120, s48, v127, v126
	v_mul_f32_e32 v118, 0.5, v118
	v_add_f32_e32 v124, 1.0, v124
	v_mul_f32_e32 v119, 0.5, v119
	v_add_f32_e32 v120, 1.0, v120
	v_mul_f32_e32 v118, v118, v124
	v_mul_f32_e32 v119, v119, v120
	v_cvt_pk_bf16_f32 v116, v116, v117
	v_cvt_pk_bf16_f32 v117, v118, v119
	global_store_dwordx2 v[130:131], v[116:117], off offset:256 sc1
	global_load_dwordx4 v[116:119], v[144:145], off offset:576
	s_waitcnt vmcnt(0)
	v_pk_add_f32 v[112:113], v[112:113], v[116:117]
	s_nop 0
	v_mul_f32_e32 v116, 0x3d372713, v112
	v_mul_f32_e32 v116, v112, v116
	v_fma_f32 v116, v112, v116, v112
	v_mul_f32_e32 v116, 0x3f4c422a, v116
	v_cmp_nlt_f32_e64 s[58:59], |v116|, s44
	s_and_saveexec_b64 s[60:61], s[58:59]
	s_xor_b64 s[74:75], exec, s[60:61]
	s_cbranch_execz .LBB0_3137
	v_add_f32_e64 v117, |v116|, |v116|
	v_mul_f32_e32 v120, 0x3fb8aa3b, v117
	v_rndne_f32_e32 v121, v120
	v_sub_f32_e32 v122, v120, v121
	v_fma_f32 v120, v117, s45, -v120
	v_fmac_f32_e32 v120, 0x32a5705f, v117
	v_add_f32_e32 v120, v122, v120
	v_cvt_i32_f32_e32 v121, v121
	v_exp_f32_e32 v120, v120
	v_cmp_ngt_f32_e32 vcc, s46, v117
	v_ldexp_f32 v120, v120, v121
	s_nop 0
	v_cndmask_b32_e32 v120, 0, v120, vcc
	v_cmp_nlt_f32_e32 vcc, s47, v117
	s_nop 1
	v_cndmask_b32_e32 v117, v156, v120, vcc
	v_add_f32_e32 v117, 1.0, v117
	v_rcp_f32_e32 v117, v117
	s_nop 0
	v_fma_f32 v117, v117, -2.0, 1.0

.LBB0_3149:
	s_andn2_saveexec_b64 s[74:75], s[74:75]
	v_mul_f32_e32 v123, v122, v122
	v_fmamk_f32 v124, v123, 0xbbbac73d, v153
	v_fmaak_f32 v124, v123, v124, 0xbd5c1c4e
	v_fmaak_f32 v124, v123, v124, 0x3e088382
	v_fmaak_f32 v124, v123, v124, 0xbeaaaa99
	v_mul_f32_e64 v124, |v122|, v124
	v_fma_f32 v123, v123, v124, |v122|
	s_or_b64 exec, exec, s[74:75]
	v_bfi_b32 v116, s48, v117, v116
	v_mul_f32_e32 v112, 0.5, v112
	v_add_f32_e32 v116, 1.0, v116
	v_mul_f32_e32 v112, v112, v116
	v_bfi_b32 v116, s48, v119, v118
	v_mul_f32_e32 v113, 0.5, v113
	v_add_f32_e32 v116, 1.0, v116
	v_bfi_b32 v120, s48, v121, v120
	v_mul_f32_e32 v113, v113, v116
	v_bfi_b32 v116, s48, v123, v122
	v_mul_f32_e32 v114, 0.5, v114
	v_add_f32_e32 v120, 1.0, v120
	v_mul_f32_e32 v115, 0.5, v115
	v_add_f32_e32 v116, 1.0, v116
	v_mul_f32_e32 v114, v114, v120
	v_mul_f32_e32 v115, v115, v116
	v_cvt_pk_bf16_f32 v112, v112, v113
	v_cvt_pk_bf16_f32 v113, v114, v115
	global_store_dwordx2 v[130:131], v[112:113], off offset:288 sc1
	global_load_dwordx4 v[112:115], v[144:145], off
	s_waitcnt vmcnt(0)
	v_pk_add_f32 v[108:109], v[108:109], v[112:113]
	s_nop 0
	v_mul_f32_e32 v112, 0x3d372713, v108
	v_mul_f32_e32 v112, v108, v112
	v_fma_f32 v112, v108, v112, v108
	v_mul_f32_e32 v112, 0x3f4c422a, v112
	v_cmp_nlt_f32_e64 s[58:59], |v112|, s44
	s_and_saveexec_b64 s[60:61], s[58:59]
	s_xor_b64 s[74:75], exec, s[60:61]
	s_cbranch_execz .LBB0_3153
	v_add_f32_e64 v113, |v112|, |v112|
	v_mul_f32_e32 v116, 0x3fb8aa3b, v113
	v_rndne_f32_e32 v117, v116
	v_sub_f32_e32 v118, v116, v117
	v_fma_f32 v116, v113, s45, -v116
	v_fmac_f32_e32 v116, 0x32a5705f, v113
	v_add_f32_e32 v116, v118, v116
	v_cvt_i32_f32_e32 v117, v117
	v_exp_f32_e32 v116, v116
	v_cmp_ngt_f32_e32 vcc, s46, v113
	v_ldexp_f32 v116, v116, v117
	s_nop 0
	v_cndmask_b32_e32 v116, 0, v116, vcc
	v_cmp_nlt_f32_e32 vcc, s47, v113
	s_nop 1
	v_cndmask_b32_e32 v113, v156, v116, vcc
	v_add_f32_e32 v113, 1.0, v113
	v_rcp_f32_e32 v113, v113
	s_nop 0
	v_fma_f32 v113, v113, -2.0, 1.0

.LBB0_3165:
	s_andn2_saveexec_b64 s[74:75], s[74:75]
	v_mul_f32_e32 v119, v118, v118
	v_fmamk_f32 v120, v119, 0xbbbac73d, v153
	v_fmaak_f32 v120, v119, v120, 0xbd5c1c4e
	v_fmaak_f32 v120, v119, v120, 0x3e088382
	v_fmaak_f32 v120, v119, v120, 0xbeaaaa99
	v_mul_f32_e64 v120, |v118|, v120
	v_fma_f32 v119, v119, v120, |v118|
	s_or_b64 exec, exec, s[74:75]
	v_bfi_b32 v116, s48, v117, v116
	v_mul_f32_e32 v110, 0.5, v110
	v_add_f32_e32 v116, 1.0, v116
	v_mul_f32_e32 v116, v110, v116
	v_mul_f32_e32 v110, 0.5, v111
	v_bfi_b32 v111, s48, v113, v112
	v_mul_f32_e32 v108, 0.5, v108
	v_add_f32_e32 v111, 1.0, v111
	v_mul_f32_e32 v111, v108, v111
	v_mul_f32_e32 v108, 0.5, v109
	v_bfi_b32 v109, s48, v115, v114
	v_add_f32_e32 v109, 1.0, v109
	v_mul_f32_e32 v112, v108, v109
	v_or_b32_e32 v108, 16, v128
	v_ashrrev_i32_e32 v109, 31, v108
	v_bfi_b32 v113, s48, v119, v118
	v_lshlrev_b64 v[108:109], 9, v[108:109]
	v_add_f32_e32 v113, 1.0, v113
	v_mul_f32_e32 v113, v110, v113
	v_lshl_add_u64 v[108:109], s[20:21], 0, v[108:109]
	v_cvt_pk_bf16_f32 v110, v111, v112
	v_cvt_pk_bf16_f32 v111, v116, v113
	v_lshl_add_u64 v[112:113], v[146:147], 1, v[108:109]
	global_store_dwordx2 v[112:113], v[110:111], off sc1
	global_load_dwordx4 v[108:111], v[144:145], off offset:64
	s_waitcnt vmcnt(0)
	v_pk_add_f32 v[104:105], v[104:105], v[108:109]
	s_nop 0
	v_mul_f32_e32 v108, 0x3d372713, v104
	v_mul_f32_e32 v108, v104, v108
	v_fma_f32 v108, v104, v108, v104
	v_mul_f32_e32 v108, 0x3f4c422a, v108
	v_cmp_nlt_f32_e64 s[58:59], |v108|, s44
	s_and_saveexec_b64 s[60:61], s[58:59]
	s_xor_b64 s[74:75], exec, s[60:61]
	s_cbranch_execz .LBB0_3169
	v_add_f32_e64 v109, |v108|, |v108|
	v_mul_f32_e32 v114, 0x3fb8aa3b, v109
	v_rndne_f32_e32 v115, v114
	v_sub_f32_e32 v116, v114, v115
	v_fma_f32 v114, v109, s45, -v114
	v_fmac_f32_e32 v114, 0x32a5705f, v109
	v_add_f32_e32 v114, v116, v114
	v_cvt_i32_f32_e32 v115, v115
	v_exp_f32_e32 v114, v114
	v_cmp_ngt_f32_e32 vcc, s46, v109
	v_ldexp_f32 v114, v114, v115
	s_nop 0
	v_cndmask_b32_e32 v114, 0, v114, vcc
	v_cmp_nlt_f32_e32 vcc, s47, v109
	s_nop 1
	v_cndmask_b32_e32 v109, v156, v114, vcc
	v_add_f32_e32 v109, 1.0, v109
	v_rcp_f32_e32 v109, v109
	s_nop 0
	v_fma_f32 v109, v109, -2.0, 1.0

.LBB0_3181:
	s_andn2_saveexec_b64 s[74:75], s[74:75]
	v_mul_f32_e32 v117, v116, v116
	v_fmamk_f32 v118, v117, 0xbbbac73d, v153
	v_fmaak_f32 v118, v117, v118, 0xbd5c1c4e
	v_fmaak_f32 v118, v117, v118, 0x3e088382
	v_fmaak_f32 v118, v117, v118, 0xbeaaaa99
	v_mul_f32_e64 v118, |v116|, v118
	v_fma_f32 v117, v117, v118, |v116|
	s_or_b64 exec, exec, s[74:75]
	v_bfi_b32 v108, s48, v109, v108
	v_mul_f32_e32 v104, 0.5, v104
	v_add_f32_e32 v108, 1.0, v108
	v_mul_f32_e32 v104, v104, v108
	v_bfi_b32 v108, s48, v111, v110
	v_mul_f32_e32 v105, 0.5, v105
	v_add_f32_e32 v108, 1.0, v108
	v_bfi_b32 v114, s48, v115, v114
	v_mul_f32_e32 v105, v105, v108
	v_bfi_b32 v108, s48, v117, v116
	v_mul_f32_e32 v106, 0.5, v106
	v_add_f32_e32 v114, 1.0, v114
	v_mul_f32_e32 v107, 0.5, v107
	v_add_f32_e32 v108, 1.0, v108
	v_mul_f32_e32 v106, v106, v114
	v_mul_f32_e32 v107, v107, v108
	v_cvt_pk_bf16_f32 v104, v104, v105
	v_cvt_pk_bf16_f32 v105, v106, v107
	global_store_dwordx2 v[112:113], v[104:105], off offset:32 sc1
	global_load_dwordx4 v[104:107], v[144:145], off offset:512
	s_waitcnt vmcnt(0)
	v_pk_add_f32 v[100:101], v[100:101], v[104:105]
	s_nop 0
	v_mul_f32_e32 v104, 0x3d372713, v100
	v_mul_f32_e32 v104, v100, v104
	v_fma_f32 v104, v100, v104, v100
	v_mul_f32_e32 v104, 0x3f4c422a, v104
	v_cmp_nlt_f32_e64 s[58:59], |v104|, s44
	s_and_saveexec_b64 s[60:61], s[58:59]
	s_xor_b64 s[74:75], exec, s[60:61]
	s_cbranch_execz .LBB0_3185
	v_add_f32_e64 v105, |v104|, |v104|
	v_mul_f32_e32 v108, 0x3fb8aa3b, v105
	v_rndne_f32_e32 v109, v108
	v_sub_f32_e32 v110, v108, v109
	v_fma_f32 v108, v105, s45, -v108
	v_fmac_f32_e32 v108, 0x32a5705f, v105
	v_add_f32_e32 v108, v110, v108
	v_cvt_i32_f32_e32 v109, v109
	v_exp_f32_e32 v108, v108
	v_cmp_ngt_f32_e32 vcc, s46, v105
	v_ldexp_f32 v108, v108, v109
	s_nop 0
	v_cndmask_b32_e32 v108, 0, v108, vcc
	v_cmp_nlt_f32_e32 vcc, s47, v105
	s_nop 1
	v_cndmask_b32_e32 v105, v156, v108, vcc
	v_add_f32_e32 v105, 1.0, v105
	v_rcp_f32_e32 v105, v105
	s_nop 0
	v_fma_f32 v105, v105, -2.0, 1.0

.LBB0_3197:
	s_andn2_saveexec_b64 s[74:75], s[74:75]
	v_mul_f32_e32 v111, v110, v110
	v_fmamk_f32 v114, v111, 0xbbbac73d, v153
	v_fmaak_f32 v114, v111, v114, 0xbd5c1c4e
	v_fmaak_f32 v114, v111, v114, 0x3e088382
	v_fmaak_f32 v114, v111, v114, 0xbeaaaa99
	v_mul_f32_e64 v114, |v110|, v114
	v_fma_f32 v111, v111, v114, |v110|
	s_or_b64 exec, exec, s[74:75]
	v_bfi_b32 v104, s48, v105, v104
	v_mul_f32_e32 v100, 0.5, v100
	v_add_f32_e32 v104, 1.0, v104
	v_mul_f32_e32 v100, v100, v104
	v_bfi_b32 v104, s48, v107, v106
	v_mul_f32_e32 v101, 0.5, v101
	v_add_f32_e32 v104, 1.0, v104
	v_bfi_b32 v108, s48, v109, v108
	v_mul_f32_e32 v101, v101, v104
	v_bfi_b32 v104, s48, v111, v110
	v_mul_f32_e32 v102, 0.5, v102
	v_add_f32_e32 v108, 1.0, v108
	v_mul_f32_e32 v103, 0.5, v103
	v_add_f32_e32 v104, 1.0, v104
	v_mul_f32_e32 v102, v102, v108
	v_mul_f32_e32 v103, v103, v104
	v_cvt_pk_bf16_f32 v100, v100, v101
	v_cvt_pk_bf16_f32 v101, v102, v103
	global_store_dwordx2 v[112:113], v[100:101], off offset:256 sc1
	global_load_dwordx4 v[100:103], v[144:145], off offset:576
	s_waitcnt vmcnt(0)
	v_pk_add_f32 v[96:97], v[96:97], v[100:101]
	s_nop 0
	v_mul_f32_e32 v100, 0x3d372713, v96
	v_mul_f32_e32 v100, v96, v100
	v_fma_f32 v100, v96, v100, v96
	v_mul_f32_e32 v100, 0x3f4c422a, v100
	v_cmp_nlt_f32_e64 s[58:59], |v100|, s44
	s_and_saveexec_b64 s[60:61], s[58:59]
	s_xor_b64 s[74:75], exec, s[60:61]
	s_cbranch_execz .LBB0_3201
	v_add_f32_e64 v101, |v100|, |v100|
	v_mul_f32_e32 v104, 0x3fb8aa3b, v101
	v_rndne_f32_e32 v105, v104
	v_sub_f32_e32 v106, v104, v105
	v_fma_f32 v104, v101, s45, -v104
	v_fmac_f32_e32 v104, 0x32a5705f, v101
	v_add_f32_e32 v104, v106, v104
	v_cvt_i32_f32_e32 v105, v105
	v_exp_f32_e32 v104, v104
	v_cmp_ngt_f32_e32 vcc, s46, v101
	v_ldexp_f32 v104, v104, v105
	s_nop 0
	v_cndmask_b32_e32 v104, 0, v104, vcc
	v_cmp_nlt_f32_e32 vcc, s47, v101
	s_nop 1
	v_cndmask_b32_e32 v101, v156, v104, vcc
	v_add_f32_e32 v101, 1.0, v101
	v_rcp_f32_e32 v101, v101
	s_nop 0
	v_fma_f32 v101, v101, -2.0, 1.0

.LBB0_3213:
	s_andn2_saveexec_b64 s[74:75], s[74:75]
	v_mul_f32_e32 v107, v106, v106
	v_fmamk_f32 v108, v107, 0xbbbac73d, v153
	v_fmaak_f32 v108, v107, v108, 0xbd5c1c4e
	v_fmaak_f32 v108, v107, v108, 0x3e088382
	v_fmaak_f32 v108, v107, v108, 0xbeaaaa99
	v_mul_f32_e64 v108, |v106|, v108
	v_fma_f32 v107, v107, v108, |v106|
	s_or_b64 exec, exec, s[74:75]
	v_bfi_b32 v100, s48, v101, v100
	v_mul_f32_e32 v96, 0.5, v96
	v_add_f32_e32 v100, 1.0, v100
	v_mul_f32_e32 v96, v96, v100
	v_bfi_b32 v100, s48, v103, v102
	v_mul_f32_e32 v97, 0.5, v97
	v_add_f32_e32 v100, 1.0, v100
	v_bfi_b32 v104, s48, v105, v104
	v_mul_f32_e32 v97, v97, v100
	v_bfi_b32 v100, s48, v107, v106
	v_mul_f32_e32 v98, 0.5, v98
	v_add_f32_e32 v104, 1.0, v104
	v_mul_f32_e32 v99, 0.5, v99
	v_add_f32_e32 v100, 1.0, v100
	v_mul_f32_e32 v98, v98, v104
	v_mul_f32_e32 v99, v99, v100
	v_cvt_pk_bf16_f32 v96, v96, v97
	v_cvt_pk_bf16_f32 v97, v98, v99
	global_store_dwordx2 v[112:113], v[96:97], off offset:288 sc1
	global_load_dwordx4 v[96:99], v[144:145], off
	s_waitcnt vmcnt(0)
	v_pk_add_f32 v[92:93], v[92:93], v[96:97]
	s_nop 0
	v_mul_f32_e32 v96, 0x3d372713, v92
	v_mul_f32_e32 v96, v92, v96
	v_fma_f32 v96, v92, v96, v92
	v_mul_f32_e32 v96, 0x3f4c422a, v96
	v_cmp_nlt_f32_e64 s[58:59], |v96|, s44
	s_and_saveexec_b64 s[60:61], s[58:59]
	s_xor_b64 s[74:75], exec, s[60:61]
	s_cbranch_execz .LBB0_3217
	v_add_f32_e64 v97, |v96|, |v96|
	v_mul_f32_e32 v100, 0x3fb8aa3b, v97
	v_rndne_f32_e32 v101, v100
	v_sub_f32_e32 v102, v100, v101
	v_fma_f32 v100, v97, s45, -v100
	v_fmac_f32_e32 v100, 0x32a5705f, v97
	v_add_f32_e32 v100, v102, v100
	v_cvt_i32_f32_e32 v101, v101
	v_exp_f32_e32 v100, v100
	v_cmp_ngt_f32_e32 vcc, s46, v97
	v_ldexp_f32 v100, v100, v101
	s_nop 0
	v_cndmask_b32_e32 v100, 0, v100, vcc
	v_cmp_nlt_f32_e32 vcc, s47, v97
	s_nop 1
	v_cndmask_b32_e32 v97, v156, v100, vcc
	v_add_f32_e32 v97, 1.0, v97
	v_rcp_f32_e32 v97, v97
	s_nop 0
	v_fma_f32 v97, v97, -2.0, 1.0

.LBB0_3229:
	s_andn2_saveexec_b64 s[74:75], s[74:75]
	v_mul_f32_e32 v103, v102, v102
	v_fmamk_f32 v104, v103, 0xbbbac73d, v153
	v_fmaak_f32 v104, v103, v104, 0xbd5c1c4e
	v_fmaak_f32 v104, v103, v104, 0x3e088382
	v_fmaak_f32 v104, v103, v104, 0xbeaaaa99
	v_mul_f32_e64 v104, |v102|, v104
	v_fma_f32 v103, v103, v104, |v102|
	s_or_b64 exec, exec, s[74:75]
	v_bfi_b32 v100, s48, v101, v100
	v_mul_f32_e32 v94, 0.5, v94
	v_add_f32_e32 v100, 1.0, v100
	v_mul_f32_e32 v100, v94, v100
	v_mul_f32_e32 v94, 0.5, v95
	v_bfi_b32 v95, s48, v97, v96
	v_mul_f32_e32 v92, 0.5, v92
	v_add_f32_e32 v95, 1.0, v95
	v_mul_f32_e32 v95, v92, v95
	v_mul_f32_e32 v92, 0.5, v93
	v_bfi_b32 v93, s48, v99, v98
	v_add_f32_e32 v93, 1.0, v93
	v_mul_f32_e32 v96, v92, v93
	v_or_b32_e32 v92, 32, v128
	v_ashrrev_i32_e32 v93, 31, v92
	v_bfi_b32 v97, s48, v103, v102
	v_lshlrev_b64 v[92:93], 9, v[92:93]
	v_add_f32_e32 v97, 1.0, v97
	v_mul_f32_e32 v97, v94, v97
	v_lshl_add_u64 v[92:93], s[20:21], 0, v[92:93]
	v_cvt_pk_bf16_f32 v94, v95, v96
	v_cvt_pk_bf16_f32 v95, v100, v97
	v_lshl_add_u64 v[96:97], v[146:147], 1, v[92:93]
	global_store_dwordx2 v[96:97], v[94:95], off sc1
	global_load_dwordx4 v[92:95], v[144:145], off offset:64
	s_waitcnt vmcnt(0)
	v_pk_add_f32 v[88:89], v[88:89], v[92:93]
	s_nop 0
	v_mul_f32_e32 v92, 0x3d372713, v88
	v_mul_f32_e32 v92, v88, v92
	v_fma_f32 v92, v88, v92, v88
	v_mul_f32_e32 v92, 0x3f4c422a, v92
	v_cmp_nlt_f32_e64 s[58:59], |v92|, s44
	s_and_saveexec_b64 s[60:61], s[58:59]
	s_xor_b64 s[74:75], exec, s[60:61]
	s_cbranch_execz .LBB0_3233
	v_add_f32_e64 v93, |v92|, |v92|
	v_mul_f32_e32 v98, 0x3fb8aa3b, v93
	v_rndne_f32_e32 v99, v98
	v_sub_f32_e32 v100, v98, v99
	v_fma_f32 v98, v93, s45, -v98
	v_fmac_f32_e32 v98, 0x32a5705f, v93
	v_add_f32_e32 v98, v100, v98
	v_cvt_i32_f32_e32 v99, v99
	v_exp_f32_e32 v98, v98
	v_cmp_ngt_f32_e32 vcc, s46, v93
	v_ldexp_f32 v98, v98, v99
	s_nop 0
	v_cndmask_b32_e32 v98, 0, v98, vcc
	v_cmp_nlt_f32_e32 vcc, s47, v93
	s_nop 1
	v_cndmask_b32_e32 v93, v156, v98, vcc
	v_add_f32_e32 v93, 1.0, v93
	v_rcp_f32_e32 v93, v93
	s_nop 0
	v_fma_f32 v93, v93, -2.0, 1.0

.LBB0_3245:
	s_andn2_saveexec_b64 s[74:75], s[74:75]
	v_mul_f32_e32 v101, v100, v100
	v_fmamk_f32 v102, v101, 0xbbbac73d, v153
	v_fmaak_f32 v102, v101, v102, 0xbd5c1c4e
	v_fmaak_f32 v102, v101, v102, 0x3e088382
	v_fmaak_f32 v102, v101, v102, 0xbeaaaa99
	v_mul_f32_e64 v102, |v100|, v102
	v_fma_f32 v101, v101, v102, |v100|
	s_or_b64 exec, exec, s[74:75]
	v_bfi_b32 v92, s48, v93, v92
	v_mul_f32_e32 v88, 0.5, v88
	v_add_f32_e32 v92, 1.0, v92
	v_mul_f32_e32 v88, v88, v92
	v_bfi_b32 v92, s48, v95, v94
	v_mul_f32_e32 v89, 0.5, v89
	v_add_f32_e32 v92, 1.0, v92
	v_bfi_b32 v98, s48, v99, v98
	v_mul_f32_e32 v89, v89, v92
	v_bfi_b32 v92, s48, v101, v100
	v_mul_f32_e32 v90, 0.5, v90
	v_add_f32_e32 v98, 1.0, v98
	v_mul_f32_e32 v91, 0.5, v91
	v_add_f32_e32 v92, 1.0, v92
	v_mul_f32_e32 v90, v90, v98
	v_mul_f32_e32 v91, v91, v92
	v_cvt_pk_bf16_f32 v88, v88, v89
	v_cvt_pk_bf16_f32 v89, v90, v91
	global_store_dwordx2 v[96:97], v[88:89], off offset:32 sc1
	global_load_dwordx4 v[88:91], v[144:145], off offset:512
	s_waitcnt vmcnt(0)
	v_pk_add_f32 v[84:85], v[84:85], v[88:89]
	s_nop 0
	v_mul_f32_e32 v88, 0x3d372713, v84
	v_mul_f32_e32 v88, v84, v88
	v_fma_f32 v88, v84, v88, v84
	v_mul_f32_e32 v88, 0x3f4c422a, v88
	v_cmp_nlt_f32_e64 s[58:59], |v88|, s44
	s_and_saveexec_b64 s[60:61], s[58:59]
	s_xor_b64 s[74:75], exec, s[60:61]
	s_cbranch_execz .LBB0_3249
	v_add_f32_e64 v89, |v88|, |v88|
	v_mul_f32_e32 v92, 0x3fb8aa3b, v89
	v_rndne_f32_e32 v93, v92
	v_sub_f32_e32 v94, v92, v93
	v_fma_f32 v92, v89, s45, -v92
	v_fmac_f32_e32 v92, 0x32a5705f, v89
	v_add_f32_e32 v92, v94, v92
	v_cvt_i32_f32_e32 v93, v93
	v_exp_f32_e32 v92, v92
	v_cmp_ngt_f32_e32 vcc, s46, v89
	v_ldexp_f32 v92, v92, v93
	s_nop 0
	v_cndmask_b32_e32 v92, 0, v92, vcc
	v_cmp_nlt_f32_e32 vcc, s47, v89
	s_nop 1
	v_cndmask_b32_e32 v89, v156, v92, vcc
	v_add_f32_e32 v89, 1.0, v89
	v_rcp_f32_e32 v89, v89
	s_nop 0
	v_fma_f32 v89, v89, -2.0, 1.0

.LBB0_3261:
	s_andn2_saveexec_b64 s[74:75], s[74:75]
	v_mul_f32_e32 v95, v94, v94
	v_fmamk_f32 v98, v95, 0xbbbac73d, v153
	v_fmaak_f32 v98, v95, v98, 0xbd5c1c4e
	v_fmaak_f32 v98, v95, v98, 0x3e088382
	v_fmaak_f32 v98, v95, v98, 0xbeaaaa99
	v_mul_f32_e64 v98, |v94|, v98
	v_fma_f32 v95, v95, v98, |v94|
	s_or_b64 exec, exec, s[74:75]
	v_bfi_b32 v88, s48, v89, v88
	v_mul_f32_e32 v84, 0.5, v84
	v_add_f32_e32 v88, 1.0, v88
	v_mul_f32_e32 v84, v84, v88
	v_bfi_b32 v88, s48, v91, v90
	v_mul_f32_e32 v85, 0.5, v85
	v_add_f32_e32 v88, 1.0, v88
	v_bfi_b32 v92, s48, v93, v92
	v_mul_f32_e32 v85, v85, v88
	v_bfi_b32 v88, s48, v95, v94
	v_mul_f32_e32 v86, 0.5, v86
	v_add_f32_e32 v92, 1.0, v92
	v_mul_f32_e32 v87, 0.5, v87
	v_add_f32_e32 v88, 1.0, v88
	v_mul_f32_e32 v86, v86, v92
	v_mul_f32_e32 v87, v87, v88
	v_cvt_pk_bf16_f32 v84, v84, v85
	v_cvt_pk_bf16_f32 v85, v86, v87
	global_store_dwordx2 v[96:97], v[84:85], off offset:256 sc1
	global_load_dwordx4 v[84:87], v[144:145], off offset:576
	s_waitcnt vmcnt(0)
	v_pk_add_f32 v[80:81], v[80:81], v[84:85]
	s_nop 0
	v_mul_f32_e32 v84, 0x3d372713, v80
	v_mul_f32_e32 v84, v80, v84
	v_fma_f32 v84, v80, v84, v80
	v_mul_f32_e32 v84, 0x3f4c422a, v84
	v_cmp_nlt_f32_e64 s[58:59], |v84|, s44
	s_and_saveexec_b64 s[60:61], s[58:59]
	s_xor_b64 s[74:75], exec, s[60:61]
	s_cbranch_execz .LBB0_3265
	v_add_f32_e64 v85, |v84|, |v84|
	v_mul_f32_e32 v88, 0x3fb8aa3b, v85
	v_rndne_f32_e32 v89, v88
	v_sub_f32_e32 v90, v88, v89
	v_fma_f32 v88, v85, s45, -v88
	v_fmac_f32_e32 v88, 0x32a5705f, v85
	v_add_f32_e32 v88, v90, v88
	v_cvt_i32_f32_e32 v89, v89
	v_exp_f32_e32 v88, v88
	v_cmp_ngt_f32_e32 vcc, s46, v85
	v_ldexp_f32 v88, v88, v89
	s_nop 0
	v_cndmask_b32_e32 v88, 0, v88, vcc
	v_cmp_nlt_f32_e32 vcc, s47, v85
	s_nop 1
	v_cndmask_b32_e32 v85, v156, v88, vcc
	v_add_f32_e32 v85, 1.0, v85
	v_rcp_f32_e32 v85, v85
	s_nop 0
	v_fma_f32 v85, v85, -2.0, 1.0

.LBB0_3277:
	s_andn2_saveexec_b64 s[74:75], s[74:75]
	v_mul_f32_e32 v91, v90, v90
	v_fmamk_f32 v92, v91, 0xbbbac73d, v153
	v_fmaak_f32 v92, v91, v92, 0xbd5c1c4e
	v_fmaak_f32 v92, v91, v92, 0x3e088382
	v_fmaak_f32 v92, v91, v92, 0xbeaaaa99
	v_mul_f32_e64 v92, |v90|, v92
	v_fma_f32 v91, v91, v92, |v90|
	s_or_b64 exec, exec, s[74:75]
	v_bfi_b32 v84, s48, v85, v84
	v_mul_f32_e32 v80, 0.5, v80
	v_add_f32_e32 v84, 1.0, v84
	v_mul_f32_e32 v80, v80, v84
	v_bfi_b32 v84, s48, v87, v86
	v_mul_f32_e32 v81, 0.5, v81
	v_add_f32_e32 v84, 1.0, v84
	v_bfi_b32 v88, s48, v89, v88
	v_mul_f32_e32 v81, v81, v84
	v_bfi_b32 v84, s48, v91, v90
	v_mul_f32_e32 v82, 0.5, v82
	v_add_f32_e32 v88, 1.0, v88
	v_mul_f32_e32 v83, 0.5, v83
	v_add_f32_e32 v84, 1.0, v84
	v_mul_f32_e32 v82, v82, v88
	v_mul_f32_e32 v83, v83, v84
	v_cvt_pk_bf16_f32 v80, v80, v81
	v_cvt_pk_bf16_f32 v81, v82, v83
	global_store_dwordx2 v[96:97], v[80:81], off offset:288 sc1
	global_load_dwordx4 v[80:83], v[144:145], off
	s_waitcnt vmcnt(0)
	v_pk_add_f32 v[76:77], v[76:77], v[80:81]
	s_nop 0
	v_mul_f32_e32 v80, 0x3d372713, v76
	v_mul_f32_e32 v80, v76, v80
	v_fma_f32 v80, v76, v80, v76
	v_mul_f32_e32 v80, 0x3f4c422a, v80
	v_cmp_nlt_f32_e64 s[58:59], |v80|, s44
	s_and_saveexec_b64 s[60:61], s[58:59]
	s_xor_b64 s[74:75], exec, s[60:61]
	s_cbranch_execz .LBB0_3281
	v_add_f32_e64 v81, |v80|, |v80|
	v_mul_f32_e32 v84, 0x3fb8aa3b, v81
	v_rndne_f32_e32 v85, v84
	v_sub_f32_e32 v86, v84, v85
	v_fma_f32 v84, v81, s45, -v84
	v_fmac_f32_e32 v84, 0x32a5705f, v81
	v_add_f32_e32 v84, v86, v84
	v_cvt_i32_f32_e32 v85, v85
	v_exp_f32_e32 v84, v84
	v_cmp_ngt_f32_e32 vcc, s46, v81
	v_ldexp_f32 v84, v84, v85
	s_nop 0
	v_cndmask_b32_e32 v84, 0, v84, vcc
	v_cmp_nlt_f32_e32 vcc, s47, v81
	s_nop 1
	v_cndmask_b32_e32 v81, v156, v84, vcc
	v_add_f32_e32 v81, 1.0, v81
	v_rcp_f32_e32 v81, v81
	s_nop 0
	v_fma_f32 v81, v81, -2.0, 1.0

.LBB0_3293:
	s_andn2_saveexec_b64 s[74:75], s[74:75]
	v_mul_f32_e32 v87, v86, v86
	v_fmamk_f32 v88, v87, 0xbbbac73d, v153
	v_fmaak_f32 v88, v87, v88, 0xbd5c1c4e
	v_fmaak_f32 v88, v87, v88, 0x3e088382
	v_fmaak_f32 v88, v87, v88, 0xbeaaaa99
	v_mul_f32_e64 v88, |v86|, v88
	v_fma_f32 v87, v87, v88, |v86|
	s_or_b64 exec, exec, s[74:75]
	v_bfi_b32 v84, s48, v85, v84
	v_mul_f32_e32 v78, 0.5, v78
	v_add_f32_e32 v84, 1.0, v84
	v_mul_f32_e32 v84, v78, v84
	v_mul_f32_e32 v78, 0.5, v79
	v_bfi_b32 v79, s48, v81, v80
	v_mul_f32_e32 v76, 0.5, v76
	v_add_f32_e32 v79, 1.0, v79
	v_mul_f32_e32 v79, v76, v79
	v_mul_f32_e32 v76, 0.5, v77
	v_bfi_b32 v77, s48, v83, v82
	v_add_f32_e32 v77, 1.0, v77
	v_mul_f32_e32 v80, v76, v77
	v_or_b32_e32 v76, 48, v128
	v_ashrrev_i32_e32 v77, 31, v76
	v_bfi_b32 v81, s48, v87, v86
	v_lshlrev_b64 v[76:77], 9, v[76:77]
	v_add_f32_e32 v81, 1.0, v81
	v_mul_f32_e32 v81, v78, v81
	v_lshl_add_u64 v[76:77], s[20:21], 0, v[76:77]
	v_cvt_pk_bf16_f32 v78, v79, v80
	v_cvt_pk_bf16_f32 v79, v84, v81
	v_lshl_add_u64 v[80:81], v[146:147], 1, v[76:77]
	global_store_dwordx2 v[80:81], v[78:79], off sc1
	global_load_dwordx4 v[76:79], v[144:145], off offset:64
	s_waitcnt vmcnt(0)
	v_pk_add_f32 v[72:73], v[72:73], v[76:77]
	s_nop 0
	v_mul_f32_e32 v76, 0x3d372713, v72
	v_mul_f32_e32 v76, v72, v76
	v_fma_f32 v76, v72, v76, v72
	v_mul_f32_e32 v76, 0x3f4c422a, v76
	v_cmp_nlt_f32_e64 s[58:59], |v76|, s44
	s_and_saveexec_b64 s[60:61], s[58:59]
	s_xor_b64 s[74:75], exec, s[60:61]
	s_cbranch_execz .LBB0_3297
	v_add_f32_e64 v77, |v76|, |v76|
	v_mul_f32_e32 v82, 0x3fb8aa3b, v77
	v_rndne_f32_e32 v83, v82
	v_sub_f32_e32 v84, v82, v83
	v_fma_f32 v82, v77, s45, -v82
	v_fmac_f32_e32 v82, 0x32a5705f, v77
	v_add_f32_e32 v82, v84, v82
	v_cvt_i32_f32_e32 v83, v83
	v_exp_f32_e32 v82, v82
	v_cmp_ngt_f32_e32 vcc, s46, v77
	v_ldexp_f32 v82, v82, v83
	s_nop 0
	v_cndmask_b32_e32 v82, 0, v82, vcc
	v_cmp_nlt_f32_e32 vcc, s47, v77
	s_nop 1
	v_cndmask_b32_e32 v77, v156, v82, vcc
	v_add_f32_e32 v77, 1.0, v77
	v_rcp_f32_e32 v77, v77
	s_nop 0
	v_fma_f32 v77, v77, -2.0, 1.0

.LBB0_3309:
	s_andn2_saveexec_b64 s[74:75], s[74:75]
	v_mul_f32_e32 v85, v84, v84
	v_fmamk_f32 v86, v85, 0xbbbac73d, v153
	v_fmaak_f32 v86, v85, v86, 0xbd5c1c4e
	v_fmaak_f32 v86, v85, v86, 0x3e088382
	v_fmaak_f32 v86, v85, v86, 0xbeaaaa99
	v_mul_f32_e64 v86, |v84|, v86
	v_fma_f32 v85, v85, v86, |v84|
	s_or_b64 exec, exec, s[74:75]
	v_bfi_b32 v76, s48, v77, v76
	v_mul_f32_e32 v72, 0.5, v72
	v_add_f32_e32 v76, 1.0, v76
	v_mul_f32_e32 v72, v72, v76
	v_bfi_b32 v76, s48, v79, v78
	v_mul_f32_e32 v73, 0.5, v73
	v_add_f32_e32 v76, 1.0, v76
	v_bfi_b32 v82, s48, v83, v82
	v_mul_f32_e32 v73, v73, v76
	v_bfi_b32 v76, s48, v85, v84
	v_mul_f32_e32 v74, 0.5, v74
	v_add_f32_e32 v82, 1.0, v82
	v_mul_f32_e32 v75, 0.5, v75
	v_add_f32_e32 v76, 1.0, v76
	v_mul_f32_e32 v74, v74, v82
	v_mul_f32_e32 v75, v75, v76
	v_cvt_pk_bf16_f32 v72, v72, v73
	v_cvt_pk_bf16_f32 v73, v74, v75
	global_store_dwordx2 v[80:81], v[72:73], off offset:32 sc1
	global_load_dwordx4 v[72:75], v[144:145], off offset:512
	s_waitcnt vmcnt(0)
	v_pk_add_f32 v[68:69], v[68:69], v[72:73]
	s_nop 0
	v_mul_f32_e32 v72, 0x3d372713, v68
	v_mul_f32_e32 v72, v68, v72
	v_fma_f32 v72, v68, v72, v68
	v_mul_f32_e32 v72, 0x3f4c422a, v72
	v_cmp_nlt_f32_e64 s[58:59], |v72|, s44
	s_and_saveexec_b64 s[60:61], s[58:59]
	s_xor_b64 s[74:75], exec, s[60:61]
	s_cbranch_execz .LBB0_3313
	v_add_f32_e64 v73, |v72|, |v72|
	v_mul_f32_e32 v76, 0x3fb8aa3b, v73
	v_rndne_f32_e32 v77, v76
	v_sub_f32_e32 v78, v76, v77
	v_fma_f32 v76, v73, s45, -v76
	v_fmac_f32_e32 v76, 0x32a5705f, v73
	v_add_f32_e32 v76, v78, v76
	v_cvt_i32_f32_e32 v77, v77
	v_exp_f32_e32 v76, v76
	v_cmp_ngt_f32_e32 vcc, s46, v73
	v_ldexp_f32 v76, v76, v77
	s_nop 0
	v_cndmask_b32_e32 v76, 0, v76, vcc
	v_cmp_nlt_f32_e32 vcc, s47, v73
	s_nop 1
	v_cndmask_b32_e32 v73, v156, v76, vcc
	v_add_f32_e32 v73, 1.0, v73
	v_rcp_f32_e32 v73, v73
	s_nop 0
	v_fma_f32 v73, v73, -2.0, 1.0

.LBB0_3325:
	s_andn2_saveexec_b64 s[74:75], s[74:75]
	v_mul_f32_e32 v79, v78, v78
	v_fmamk_f32 v82, v79, 0xbbbac73d, v153
	v_fmaak_f32 v82, v79, v82, 0xbd5c1c4e
	v_fmaak_f32 v82, v79, v82, 0x3e088382
	v_fmaak_f32 v82, v79, v82, 0xbeaaaa99
	v_mul_f32_e64 v82, |v78|, v82
	v_fma_f32 v79, v79, v82, |v78|
	s_or_b64 exec, exec, s[74:75]
	v_bfi_b32 v72, s48, v73, v72
	v_mul_f32_e32 v68, 0.5, v68
	v_add_f32_e32 v72, 1.0, v72
	v_mul_f32_e32 v68, v68, v72
	v_bfi_b32 v72, s48, v75, v74
	v_mul_f32_e32 v69, 0.5, v69
	v_add_f32_e32 v72, 1.0, v72
	v_bfi_b32 v76, s48, v77, v76
	v_mul_f32_e32 v69, v69, v72
	v_bfi_b32 v72, s48, v79, v78
	v_mul_f32_e32 v70, 0.5, v70
	v_add_f32_e32 v76, 1.0, v76
	v_mul_f32_e32 v71, 0.5, v71
	v_add_f32_e32 v72, 1.0, v72
	v_mul_f32_e32 v70, v70, v76
	v_mul_f32_e32 v71, v71, v72
	v_cvt_pk_bf16_f32 v68, v68, v69
	v_cvt_pk_bf16_f32 v69, v70, v71
	global_store_dwordx2 v[80:81], v[68:69], off offset:256 sc1
	global_load_dwordx4 v[68:71], v[144:145], off offset:576
	s_waitcnt vmcnt(0)
	v_pk_add_f32 v[64:65], v[64:65], v[68:69]
	s_nop 0
	v_mul_f32_e32 v68, 0x3d372713, v64
	v_mul_f32_e32 v68, v64, v68
	v_fma_f32 v68, v64, v68, v64
	v_mul_f32_e32 v68, 0x3f4c422a, v68
	v_cmp_nlt_f32_e64 s[58:59], |v68|, s44
	s_and_saveexec_b64 s[60:61], s[58:59]
	s_xor_b64 s[74:75], exec, s[60:61]
	s_cbranch_execz .LBB0_3329
	v_add_f32_e64 v69, |v68|, |v68|
	v_mul_f32_e32 v72, 0x3fb8aa3b, v69
	v_rndne_f32_e32 v73, v72
	v_sub_f32_e32 v74, v72, v73
	v_fma_f32 v72, v69, s45, -v72
	v_fmac_f32_e32 v72, 0x32a5705f, v69
	v_add_f32_e32 v72, v74, v72
	v_cvt_i32_f32_e32 v73, v73
	v_exp_f32_e32 v72, v72
	v_cmp_ngt_f32_e32 vcc, s46, v69
	v_ldexp_f32 v72, v72, v73
	s_nop 0
	v_cndmask_b32_e32 v72, 0, v72, vcc
	v_cmp_nlt_f32_e32 vcc, s47, v69
	s_nop 1
	v_cndmask_b32_e32 v69, v156, v72, vcc
	v_add_f32_e32 v69, 1.0, v69
	v_rcp_f32_e32 v69, v69
	s_nop 0
	v_fma_f32 v69, v69, -2.0, 1.0

.LBB0_3341:
	s_andn2_saveexec_b64 s[74:75], s[74:75]
	v_mul_f32_e32 v75, v74, v74
	v_fmamk_f32 v76, v75, 0xbbbac73d, v153
	v_fmaak_f32 v76, v75, v76, 0xbd5c1c4e
	v_fmaak_f32 v76, v75, v76, 0x3e088382
	v_fmaak_f32 v76, v75, v76, 0xbeaaaa99
	v_mul_f32_e64 v76, |v74|, v76
	v_fma_f32 v75, v75, v76, |v74|
	s_or_b64 exec, exec, s[74:75]
	v_bfi_b32 v68, s48, v69, v68
	v_mul_f32_e32 v64, 0.5, v64
	v_add_f32_e32 v68, 1.0, v68
	v_mul_f32_e32 v64, v64, v68
	v_bfi_b32 v68, s48, v71, v70
	v_mul_f32_e32 v65, 0.5, v65
	v_add_f32_e32 v68, 1.0, v68
	v_bfi_b32 v72, s48, v73, v72
	v_mul_f32_e32 v65, v65, v68
	v_bfi_b32 v68, s48, v75, v74
	v_mul_f32_e32 v66, 0.5, v66
	v_add_f32_e32 v72, 1.0, v72
	v_mul_f32_e32 v67, 0.5, v67
	v_add_f32_e32 v68, 1.0, v68
	v_mul_f32_e32 v66, v66, v72
	v_mul_f32_e32 v67, v67, v68
	v_cvt_pk_bf16_f32 v64, v64, v65
	v_cvt_pk_bf16_f32 v65, v66, v67
	global_store_dwordx2 v[80:81], v[64:65], off offset:288 sc1
	global_load_dwordx4 v[64:67], v[144:145], off
	s_waitcnt vmcnt(0)
	v_pk_add_f32 v[60:61], v[60:61], v[64:65]
	s_nop 0
	v_mul_f32_e32 v64, 0x3d372713, v60
	v_mul_f32_e32 v64, v60, v64
	v_fma_f32 v64, v60, v64, v60
	v_mul_f32_e32 v64, 0x3f4c422a, v64
	v_cmp_nlt_f32_e64 s[58:59], |v64|, s44
	s_and_saveexec_b64 s[60:61], s[58:59]
	s_xor_b64 s[74:75], exec, s[60:61]
	s_cbranch_execz .LBB0_3345
	v_add_f32_e64 v65, |v64|, |v64|
	v_mul_f32_e32 v68, 0x3fb8aa3b, v65
	v_rndne_f32_e32 v69, v68
	v_sub_f32_e32 v70, v68, v69
	v_fma_f32 v68, v65, s45, -v68
	v_fmac_f32_e32 v68, 0x32a5705f, v65
	v_add_f32_e32 v68, v70, v68
	v_cvt_i32_f32_e32 v69, v69
	v_exp_f32_e32 v68, v68
	v_cmp_ngt_f32_e32 vcc, s46, v65
	v_ldexp_f32 v68, v68, v69
	s_nop 0
	v_cndmask_b32_e32 v68, 0, v68, vcc
	v_cmp_nlt_f32_e32 vcc, s47, v65
	s_nop 1
	v_cndmask_b32_e32 v65, v156, v68, vcc
	v_add_f32_e32 v65, 1.0, v65
	v_rcp_f32_e32 v65, v65
	s_nop 0
	v_fma_f32 v65, v65, -2.0, 1.0

.LBB0_3357:
	s_andn2_saveexec_b64 s[74:75], s[74:75]
	v_mul_f32_e32 v71, v70, v70
	v_fmamk_f32 v72, v71, 0xbbbac73d, v153
	v_fmaak_f32 v72, v71, v72, 0xbd5c1c4e
	v_fmaak_f32 v72, v71, v72, 0x3e088382
	v_fmaak_f32 v72, v71, v72, 0xbeaaaa99
	v_mul_f32_e64 v72, |v70|, v72
	v_fma_f32 v71, v71, v72, |v70|
	s_or_b64 exec, exec, s[74:75]
	v_bfi_b32 v68, s48, v69, v68
	v_mul_f32_e32 v62, 0.5, v62
	v_add_f32_e32 v68, 1.0, v68
	v_mul_f32_e32 v68, v62, v68
	v_mul_f32_e32 v62, 0.5, v63
	v_bfi_b32 v63, s48, v65, v64
	v_mul_f32_e32 v60, 0.5, v60
	v_add_f32_e32 v63, 1.0, v63
	v_mul_f32_e32 v63, v60, v63
	v_mul_f32_e32 v60, 0.5, v61
	v_bfi_b32 v61, s48, v67, v66
	v_add_f32_e32 v61, 1.0, v61
	v_mul_f32_e32 v64, v60, v61
	v_add_u32_e32 v60, 0x80, v128
	v_ashrrev_i32_e32 v61, 31, v60
	v_bfi_b32 v65, s48, v71, v70
	v_lshlrev_b64 v[60:61], 9, v[60:61]
	v_add_f32_e32 v65, 1.0, v65
	v_mul_f32_e32 v65, v62, v65
	v_lshl_add_u64 v[60:61], s[20:21], 0, v[60:61]
	v_cvt_pk_bf16_f32 v62, v63, v64
	v_cvt_pk_bf16_f32 v63, v68, v65
	v_lshl_add_u64 v[64:65], v[146:147], 1, v[60:61]
	global_store_dwordx2 v[64:65], v[62:63], off sc1
	global_load_dwordx4 v[60:63], v[144:145], off offset:64
	s_waitcnt vmcnt(0)
	v_pk_add_f32 v[56:57], v[56:57], v[60:61]
	s_nop 0
	v_mul_f32_e32 v60, 0x3d372713, v56
	v_mul_f32_e32 v60, v56, v60
	v_fma_f32 v60, v56, v60, v56
	v_mul_f32_e32 v60, 0x3f4c422a, v60
	v_cmp_nlt_f32_e64 s[58:59], |v60|, s44
	s_and_saveexec_b64 s[60:61], s[58:59]
	s_xor_b64 s[74:75], exec, s[60:61]
	s_cbranch_execz .LBB0_3361
	v_add_f32_e64 v61, |v60|, |v60|
	v_mul_f32_e32 v66, 0x3fb8aa3b, v61
	v_rndne_f32_e32 v67, v66
	v_sub_f32_e32 v68, v66, v67
	v_fma_f32 v66, v61, s45, -v66
	v_fmac_f32_e32 v66, 0x32a5705f, v61
	v_add_f32_e32 v66, v68, v66
	v_cvt_i32_f32_e32 v67, v67
	v_exp_f32_e32 v66, v66
	v_cmp_ngt_f32_e32 vcc, s46, v61
	v_ldexp_f32 v66, v66, v67
	s_nop 0
	v_cndmask_b32_e32 v66, 0, v66, vcc
	v_cmp_nlt_f32_e32 vcc, s47, v61
	s_nop 1
	v_cndmask_b32_e32 v61, v156, v66, vcc
	v_add_f32_e32 v61, 1.0, v61
	v_rcp_f32_e32 v61, v61
	s_nop 0
	v_fma_f32 v61, v61, -2.0, 1.0

.LBB0_3373:
	s_andn2_saveexec_b64 s[74:75], s[74:75]
	v_mul_f32_e32 v69, v68, v68
	v_fmamk_f32 v70, v69, 0xbbbac73d, v153
	v_fmaak_f32 v70, v69, v70, 0xbd5c1c4e
	v_fmaak_f32 v70, v69, v70, 0x3e088382
	v_fmaak_f32 v70, v69, v70, 0xbeaaaa99
	v_mul_f32_e64 v70, |v68|, v70
	v_fma_f32 v69, v69, v70, |v68|
	s_or_b64 exec, exec, s[74:75]
	v_bfi_b32 v60, s48, v61, v60
	v_mul_f32_e32 v56, 0.5, v56
	v_add_f32_e32 v60, 1.0, v60
	v_mul_f32_e32 v56, v56, v60
	v_bfi_b32 v60, s48, v63, v62
	v_mul_f32_e32 v57, 0.5, v57
	v_add_f32_e32 v60, 1.0, v60
	v_bfi_b32 v66, s48, v67, v66
	v_mul_f32_e32 v57, v57, v60
	v_bfi_b32 v60, s48, v69, v68
	v_mul_f32_e32 v58, 0.5, v58
	v_add_f32_e32 v66, 1.0, v66
	v_mul_f32_e32 v59, 0.5, v59
	v_add_f32_e32 v60, 1.0, v60
	v_mul_f32_e32 v58, v58, v66
	v_mul_f32_e32 v59, v59, v60
	v_cvt_pk_bf16_f32 v56, v56, v57
	v_cvt_pk_bf16_f32 v57, v58, v59
	global_store_dwordx2 v[64:65], v[56:57], off offset:32 sc1
	global_load_dwordx4 v[56:59], v[144:145], off offset:512
	s_waitcnt vmcnt(0)
	v_pk_add_f32 v[52:53], v[52:53], v[56:57]
	s_nop 0
	v_mul_f32_e32 v56, 0x3d372713, v52
	v_mul_f32_e32 v56, v52, v56
	v_fma_f32 v56, v52, v56, v52
	v_mul_f32_e32 v56, 0x3f4c422a, v56
	v_cmp_nlt_f32_e64 s[58:59], |v56|, s44
	s_and_saveexec_b64 s[60:61], s[58:59]
	s_xor_b64 s[74:75], exec, s[60:61]
	s_cbranch_execz .LBB0_3377
	v_add_f32_e64 v57, |v56|, |v56|
	v_mul_f32_e32 v60, 0x3fb8aa3b, v57
	v_rndne_f32_e32 v61, v60
	v_sub_f32_e32 v62, v60, v61
	v_fma_f32 v60, v57, s45, -v60
	v_fmac_f32_e32 v60, 0x32a5705f, v57
	v_add_f32_e32 v60, v62, v60
	v_cvt_i32_f32_e32 v61, v61
	v_exp_f32_e32 v60, v60
	v_cmp_ngt_f32_e32 vcc, s46, v57
	v_ldexp_f32 v60, v60, v61
	s_nop 0
	v_cndmask_b32_e32 v60, 0, v60, vcc
	v_cmp_nlt_f32_e32 vcc, s47, v57
	s_nop 1
	v_cndmask_b32_e32 v57, v156, v60, vcc
	v_add_f32_e32 v57, 1.0, v57
	v_rcp_f32_e32 v57, v57
	s_nop 0
	v_fma_f32 v57, v57, -2.0, 1.0

.LBB0_3389:
	s_andn2_saveexec_b64 s[74:75], s[74:75]
	v_mul_f32_e32 v63, v62, v62
	v_fmamk_f32 v66, v63, 0xbbbac73d, v153
	v_fmaak_f32 v66, v63, v66, 0xbd5c1c4e
	v_fmaak_f32 v66, v63, v66, 0x3e088382
	v_fmaak_f32 v66, v63, v66, 0xbeaaaa99
	v_mul_f32_e64 v66, |v62|, v66
	v_fma_f32 v63, v63, v66, |v62|
	s_or_b64 exec, exec, s[74:75]
	v_bfi_b32 v56, s48, v57, v56
	v_mul_f32_e32 v52, 0.5, v52
	v_add_f32_e32 v56, 1.0, v56
	v_mul_f32_e32 v52, v52, v56
	v_bfi_b32 v56, s48, v59, v58
	v_mul_f32_e32 v53, 0.5, v53
	v_add_f32_e32 v56, 1.0, v56
	v_bfi_b32 v60, s48, v61, v60
	v_mul_f32_e32 v53, v53, v56
	v_bfi_b32 v56, s48, v63, v62
	v_mul_f32_e32 v54, 0.5, v54
	v_add_f32_e32 v60, 1.0, v60
	v_mul_f32_e32 v55, 0.5, v55
	v_add_f32_e32 v56, 1.0, v56
	v_mul_f32_e32 v54, v54, v60
	v_mul_f32_e32 v55, v55, v56
	v_cvt_pk_bf16_f32 v52, v52, v53
	v_cvt_pk_bf16_f32 v53, v54, v55
	global_store_dwordx2 v[64:65], v[52:53], off offset:256 sc1
	global_load_dwordx4 v[52:55], v[144:145], off offset:576
	s_waitcnt vmcnt(0)
	v_pk_add_f32 v[48:49], v[48:49], v[52:53]
	s_nop 0
	v_mul_f32_e32 v52, 0x3d372713, v48
	v_mul_f32_e32 v52, v48, v52
	v_fma_f32 v52, v48, v52, v48
	v_mul_f32_e32 v52, 0x3f4c422a, v52
	v_cmp_nlt_f32_e64 s[58:59], |v52|, s44
	s_and_saveexec_b64 s[60:61], s[58:59]
	s_xor_b64 s[74:75], exec, s[60:61]
	s_cbranch_execz .LBB0_3393
	v_add_f32_e64 v53, |v52|, |v52|
	v_mul_f32_e32 v56, 0x3fb8aa3b, v53
	v_rndne_f32_e32 v57, v56
	v_sub_f32_e32 v58, v56, v57
	v_fma_f32 v56, v53, s45, -v56
	v_fmac_f32_e32 v56, 0x32a5705f, v53
	v_add_f32_e32 v56, v58, v56
	v_cvt_i32_f32_e32 v57, v57
	v_exp_f32_e32 v56, v56
	v_cmp_ngt_f32_e32 vcc, s46, v53
	v_ldexp_f32 v56, v56, v57
	s_nop 0
	v_cndmask_b32_e32 v56, 0, v56, vcc
	v_cmp_nlt_f32_e32 vcc, s47, v53
	s_nop 1
	v_cndmask_b32_e32 v53, v156, v56, vcc
	v_add_f32_e32 v53, 1.0, v53
	v_rcp_f32_e32 v53, v53
	s_nop 0
	v_fma_f32 v53, v53, -2.0, 1.0

.LBB0_3405:
	s_andn2_saveexec_b64 s[74:75], s[74:75]
	v_mul_f32_e32 v59, v58, v58
	v_fmamk_f32 v60, v59, 0xbbbac73d, v153
	v_fmaak_f32 v60, v59, v60, 0xbd5c1c4e
	v_fmaak_f32 v60, v59, v60, 0x3e088382
	v_fmaak_f32 v60, v59, v60, 0xbeaaaa99
	v_mul_f32_e64 v60, |v58|, v60
	v_fma_f32 v59, v59, v60, |v58|
	s_or_b64 exec, exec, s[74:75]
	v_bfi_b32 v52, s48, v53, v52
	v_mul_f32_e32 v48, 0.5, v48
	v_add_f32_e32 v52, 1.0, v52
	v_mul_f32_e32 v48, v48, v52
	v_bfi_b32 v52, s48, v55, v54
	v_mul_f32_e32 v49, 0.5, v49
	v_add_f32_e32 v52, 1.0, v52
	v_bfi_b32 v56, s48, v57, v56
	v_mul_f32_e32 v49, v49, v52
	v_bfi_b32 v52, s48, v59, v58
	v_mul_f32_e32 v50, 0.5, v50
	v_add_f32_e32 v56, 1.0, v56
	v_mul_f32_e32 v51, 0.5, v51
	v_add_f32_e32 v52, 1.0, v52
	v_mul_f32_e32 v50, v50, v56
	v_mul_f32_e32 v51, v51, v52
	v_cvt_pk_bf16_f32 v48, v48, v49
	v_cvt_pk_bf16_f32 v49, v50, v51
	global_store_dwordx2 v[64:65], v[48:49], off offset:288 sc1
	global_load_dwordx4 v[48:51], v[144:145], off
	s_waitcnt vmcnt(0)
	v_pk_add_f32 v[44:45], v[44:45], v[48:49]
	s_nop 0
	v_mul_f32_e32 v48, 0x3d372713, v44
	v_mul_f32_e32 v48, v44, v48
	v_fma_f32 v48, v44, v48, v44
	v_mul_f32_e32 v48, 0x3f4c422a, v48
	v_cmp_nlt_f32_e64 s[58:59], |v48|, s44
	s_and_saveexec_b64 s[60:61], s[58:59]
	s_xor_b64 s[74:75], exec, s[60:61]
	s_cbranch_execz .LBB0_3409
	v_add_f32_e64 v49, |v48|, |v48|
	v_mul_f32_e32 v52, 0x3fb8aa3b, v49
	v_rndne_f32_e32 v53, v52
	v_sub_f32_e32 v54, v52, v53
	v_fma_f32 v52, v49, s45, -v52
	v_fmac_f32_e32 v52, 0x32a5705f, v49
	v_add_f32_e32 v52, v54, v52
	v_cvt_i32_f32_e32 v53, v53
	v_exp_f32_e32 v52, v52
	v_cmp_ngt_f32_e32 vcc, s46, v49
	v_ldexp_f32 v52, v52, v53
	s_nop 0
	v_cndmask_b32_e32 v52, 0, v52, vcc
	v_cmp_nlt_f32_e32 vcc, s47, v49
	s_nop 1
	v_cndmask_b32_e32 v49, v156, v52, vcc
	v_add_f32_e32 v49, 1.0, v49
	v_rcp_f32_e32 v49, v49
	s_nop 0
	v_fma_f32 v49, v49, -2.0, 1.0

.LBB0_3421:
	s_andn2_saveexec_b64 s[74:75], s[74:75]
	v_mul_f32_e32 v55, v54, v54
	v_fmamk_f32 v56, v55, 0xbbbac73d, v153
	v_fmaak_f32 v56, v55, v56, 0xbd5c1c4e
	v_fmaak_f32 v56, v55, v56, 0x3e088382
	v_fmaak_f32 v56, v55, v56, 0xbeaaaa99
	v_mul_f32_e64 v56, |v54|, v56
	v_fma_f32 v55, v55, v56, |v54|
	s_or_b64 exec, exec, s[74:75]
	v_bfi_b32 v52, s48, v53, v52
	v_mul_f32_e32 v46, 0.5, v46
	v_add_f32_e32 v52, 1.0, v52
	v_mul_f32_e32 v52, v46, v52
	v_mul_f32_e32 v46, 0.5, v47
	v_bfi_b32 v47, s48, v49, v48
	v_mul_f32_e32 v44, 0.5, v44
	v_add_f32_e32 v47, 1.0, v47
	v_mul_f32_e32 v47, v44, v47
	v_mul_f32_e32 v44, 0.5, v45
	v_bfi_b32 v45, s48, v51, v50
	v_add_f32_e32 v45, 1.0, v45
	v_mul_f32_e32 v48, v44, v45
	v_add_u32_e32 v44, 0x90, v128
	v_ashrrev_i32_e32 v45, 31, v44
	v_bfi_b32 v49, s48, v55, v54
	v_lshlrev_b64 v[44:45], 9, v[44:45]
	v_add_f32_e32 v49, 1.0, v49
	v_mul_f32_e32 v49, v46, v49
	v_lshl_add_u64 v[44:45], s[20:21], 0, v[44:45]
	v_cvt_pk_bf16_f32 v46, v47, v48
	v_cvt_pk_bf16_f32 v47, v52, v49
	v_lshl_add_u64 v[48:49], v[146:147], 1, v[44:45]
	global_store_dwordx2 v[48:49], v[46:47], off sc1
	global_load_dwordx4 v[44:47], v[144:145], off offset:64
	s_waitcnt vmcnt(0)
	v_pk_add_f32 v[40:41], v[40:41], v[44:45]
	s_nop 0
	v_mul_f32_e32 v44, 0x3d372713, v40
	v_mul_f32_e32 v44, v40, v44
	v_fma_f32 v44, v40, v44, v40
	v_mul_f32_e32 v44, 0x3f4c422a, v44
	v_cmp_nlt_f32_e64 s[58:59], |v44|, s44
	s_and_saveexec_b64 s[60:61], s[58:59]
	s_xor_b64 s[74:75], exec, s[60:61]
	s_cbranch_execz .LBB0_3425
	v_add_f32_e64 v45, |v44|, |v44|
	v_mul_f32_e32 v50, 0x3fb8aa3b, v45
	v_rndne_f32_e32 v51, v50
	v_sub_f32_e32 v52, v50, v51
	v_fma_f32 v50, v45, s45, -v50
	v_fmac_f32_e32 v50, 0x32a5705f, v45
	v_add_f32_e32 v50, v52, v50
	v_cvt_i32_f32_e32 v51, v51
	v_exp_f32_e32 v50, v50
	v_cmp_ngt_f32_e32 vcc, s46, v45
	v_ldexp_f32 v50, v50, v51
	s_nop 0
	v_cndmask_b32_e32 v50, 0, v50, vcc
	v_cmp_nlt_f32_e32 vcc, s47, v45
	s_nop 1
	v_cndmask_b32_e32 v45, v156, v50, vcc
	v_add_f32_e32 v45, 1.0, v45
	v_rcp_f32_e32 v45, v45
	s_nop 0
	v_fma_f32 v45, v45, -2.0, 1.0

.LBB0_3437:
	s_andn2_saveexec_b64 s[74:75], s[74:75]
	v_mul_f32_e32 v53, v52, v52
	v_fmamk_f32 v54, v53, 0xbbbac73d, v153
	v_fmaak_f32 v54, v53, v54, 0xbd5c1c4e
	v_fmaak_f32 v54, v53, v54, 0x3e088382
	v_fmaak_f32 v54, v53, v54, 0xbeaaaa99
	v_mul_f32_e64 v54, |v52|, v54
	v_fma_f32 v53, v53, v54, |v52|
	s_or_b64 exec, exec, s[74:75]
	v_bfi_b32 v44, s48, v45, v44
	v_mul_f32_e32 v40, 0.5, v40
	v_add_f32_e32 v44, 1.0, v44
	v_mul_f32_e32 v40, v40, v44
	v_bfi_b32 v44, s48, v47, v46
	v_mul_f32_e32 v41, 0.5, v41
	v_add_f32_e32 v44, 1.0, v44
	v_bfi_b32 v50, s48, v51, v50
	v_mul_f32_e32 v41, v41, v44
	v_bfi_b32 v44, s48, v53, v52
	v_mul_f32_e32 v42, 0.5, v42
	v_add_f32_e32 v50, 1.0, v50
	v_mul_f32_e32 v43, 0.5, v43
	v_add_f32_e32 v44, 1.0, v44
	v_mul_f32_e32 v42, v42, v50
	v_mul_f32_e32 v43, v43, v44
	v_cvt_pk_bf16_f32 v40, v40, v41
	v_cvt_pk_bf16_f32 v41, v42, v43
	global_store_dwordx2 v[48:49], v[40:41], off offset:32 sc1
	global_load_dwordx4 v[40:43], v[144:145], off offset:512
	s_waitcnt vmcnt(0)
	v_pk_add_f32 v[36:37], v[36:37], v[40:41]
	s_nop 0
	v_mul_f32_e32 v40, 0x3d372713, v36
	v_mul_f32_e32 v40, v36, v40
	v_fma_f32 v40, v36, v40, v36
	v_mul_f32_e32 v40, 0x3f4c422a, v40
	v_cmp_nlt_f32_e64 s[58:59], |v40|, s44
	s_and_saveexec_b64 s[60:61], s[58:59]
	s_xor_b64 s[74:75], exec, s[60:61]
	s_cbranch_execz .LBB0_3441
	v_add_f32_e64 v41, |v40|, |v40|
	v_mul_f32_e32 v44, 0x3fb8aa3b, v41
	v_rndne_f32_e32 v45, v44
	v_sub_f32_e32 v46, v44, v45
	v_fma_f32 v44, v41, s45, -v44
	v_fmac_f32_e32 v44, 0x32a5705f, v41
	v_add_f32_e32 v44, v46, v44
	v_cvt_i32_f32_e32 v45, v45
	v_exp_f32_e32 v44, v44
	v_cmp_ngt_f32_e32 vcc, s46, v41
	v_ldexp_f32 v44, v44, v45
	s_nop 0
	v_cndmask_b32_e32 v44, 0, v44, vcc
	v_cmp_nlt_f32_e32 vcc, s47, v41
	s_nop 1
	v_cndmask_b32_e32 v41, v156, v44, vcc
	v_add_f32_e32 v41, 1.0, v41
	v_rcp_f32_e32 v41, v41
	s_nop 0
	v_fma_f32 v41, v41, -2.0, 1.0

.LBB0_3453:
	s_andn2_saveexec_b64 s[74:75], s[74:75]
	v_mul_f32_e32 v47, v46, v46
	v_fmamk_f32 v50, v47, 0xbbbac73d, v153
	v_fmaak_f32 v50, v47, v50, 0xbd5c1c4e
	v_fmaak_f32 v50, v47, v50, 0x3e088382
	v_fmaak_f32 v50, v47, v50, 0xbeaaaa99
	v_mul_f32_e64 v50, |v46|, v50
	v_fma_f32 v47, v47, v50, |v46|
	s_or_b64 exec, exec, s[74:75]
	v_bfi_b32 v40, s48, v41, v40
	v_mul_f32_e32 v36, 0.5, v36
	v_add_f32_e32 v40, 1.0, v40
	v_mul_f32_e32 v36, v36, v40
	v_bfi_b32 v40, s48, v43, v42
	v_mul_f32_e32 v37, 0.5, v37
	v_add_f32_e32 v40, 1.0, v40
	v_bfi_b32 v44, s48, v45, v44
	v_mul_f32_e32 v37, v37, v40
	v_bfi_b32 v40, s48, v47, v46
	v_mul_f32_e32 v38, 0.5, v38
	v_add_f32_e32 v44, 1.0, v44
	v_mul_f32_e32 v39, 0.5, v39
	v_add_f32_e32 v40, 1.0, v40
	v_mul_f32_e32 v38, v38, v44
	v_mul_f32_e32 v39, v39, v40
	v_cvt_pk_bf16_f32 v36, v36, v37
	v_cvt_pk_bf16_f32 v37, v38, v39
	global_store_dwordx2 v[48:49], v[36:37], off offset:256 sc1
	global_load_dwordx4 v[36:39], v[144:145], off offset:576
	s_waitcnt vmcnt(0)
	v_pk_add_f32 v[32:33], v[32:33], v[36:37]
	s_nop 0
	v_mul_f32_e32 v36, 0x3d372713, v32
	v_mul_f32_e32 v36, v32, v36
	v_fma_f32 v36, v32, v36, v32
	v_mul_f32_e32 v36, 0x3f4c422a, v36
	v_cmp_nlt_f32_e64 s[58:59], |v36|, s44
	s_and_saveexec_b64 s[60:61], s[58:59]
	s_xor_b64 s[74:75], exec, s[60:61]
	s_cbranch_execz .LBB0_3457
	v_add_f32_e64 v37, |v36|, |v36|
	v_mul_f32_e32 v40, 0x3fb8aa3b, v37
	v_rndne_f32_e32 v41, v40
	v_sub_f32_e32 v42, v40, v41
	v_fma_f32 v40, v37, s45, -v40
	v_fmac_f32_e32 v40, 0x32a5705f, v37
	v_add_f32_e32 v40, v42, v40
	v_cvt_i32_f32_e32 v41, v41
	v_exp_f32_e32 v40, v40
	v_cmp_ngt_f32_e32 vcc, s46, v37
	v_ldexp_f32 v40, v40, v41
	s_nop 0
	v_cndmask_b32_e32 v40, 0, v40, vcc
	v_cmp_nlt_f32_e32 vcc, s47, v37
	s_nop 1
	v_cndmask_b32_e32 v37, v156, v40, vcc
	v_add_f32_e32 v37, 1.0, v37
	v_rcp_f32_e32 v37, v37
	s_nop 0
	v_fma_f32 v37, v37, -2.0, 1.0

.LBB0_3469:
	s_andn2_saveexec_b64 s[74:75], s[74:75]
	v_mul_f32_e32 v43, v42, v42
	v_fmamk_f32 v44, v43, 0xbbbac73d, v153
	v_fmaak_f32 v44, v43, v44, 0xbd5c1c4e
	v_fmaak_f32 v44, v43, v44, 0x3e088382
	v_fmaak_f32 v44, v43, v44, 0xbeaaaa99
	v_mul_f32_e64 v44, |v42|, v44
	v_fma_f32 v43, v43, v44, |v42|
	s_or_b64 exec, exec, s[74:75]
	v_bfi_b32 v36, s48, v37, v36
	v_mul_f32_e32 v32, 0.5, v32
	v_add_f32_e32 v36, 1.0, v36
	v_mul_f32_e32 v32, v32, v36
	v_bfi_b32 v36, s48, v39, v38
	v_mul_f32_e32 v33, 0.5, v33
	v_add_f32_e32 v36, 1.0, v36
	v_bfi_b32 v40, s48, v41, v40
	v_mul_f32_e32 v33, v33, v36
	v_bfi_b32 v36, s48, v43, v42
	v_mul_f32_e32 v34, 0.5, v34
	v_add_f32_e32 v40, 1.0, v40
	v_mul_f32_e32 v35, 0.5, v35
	v_add_f32_e32 v36, 1.0, v36
	v_mul_f32_e32 v34, v34, v40
	v_mul_f32_e32 v35, v35, v36
	v_cvt_pk_bf16_f32 v32, v32, v33
	v_cvt_pk_bf16_f32 v33, v34, v35
	global_store_dwordx2 v[48:49], v[32:33], off offset:288 sc1
	global_load_dwordx4 v[32:35], v[144:145], off
	s_waitcnt vmcnt(0)
	v_pk_add_f32 v[28:29], v[28:29], v[32:33]
	s_nop 0
	v_mul_f32_e32 v32, 0x3d372713, v28
	v_mul_f32_e32 v32, v28, v32
	v_fma_f32 v32, v28, v32, v28
	v_mul_f32_e32 v32, 0x3f4c422a, v32
	v_cmp_nlt_f32_e64 s[58:59], |v32|, s44
	s_and_saveexec_b64 s[60:61], s[58:59]
	s_xor_b64 s[74:75], exec, s[60:61]
	s_cbranch_execz .LBB0_3473
	v_add_f32_e64 v33, |v32|, |v32|
	v_mul_f32_e32 v36, 0x3fb8aa3b, v33
	v_rndne_f32_e32 v37, v36
	v_sub_f32_e32 v38, v36, v37
	v_fma_f32 v36, v33, s45, -v36
	v_fmac_f32_e32 v36, 0x32a5705f, v33
	v_add_f32_e32 v36, v38, v36
	v_cvt_i32_f32_e32 v37, v37
	v_exp_f32_e32 v36, v36
	v_cmp_ngt_f32_e32 vcc, s46, v33
	v_ldexp_f32 v36, v36, v37
	s_nop 0
	v_cndmask_b32_e32 v36, 0, v36, vcc
	v_cmp_nlt_f32_e32 vcc, s47, v33
	s_nop 1
	v_cndmask_b32_e32 v33, v156, v36, vcc
	v_add_f32_e32 v33, 1.0, v33
	v_rcp_f32_e32 v33, v33
	s_nop 0
	v_fma_f32 v33, v33, -2.0, 1.0

.LBB0_3485:
	s_andn2_saveexec_b64 s[74:75], s[74:75]
	v_mul_f32_e32 v39, v38, v38
	v_fmamk_f32 v40, v39, 0xbbbac73d, v153
	v_fmaak_f32 v40, v39, v40, 0xbd5c1c4e
	v_fmaak_f32 v40, v39, v40, 0x3e088382
	v_fmaak_f32 v40, v39, v40, 0xbeaaaa99
	v_mul_f32_e64 v40, |v38|, v40
	v_fma_f32 v39, v39, v40, |v38|
	s_or_b64 exec, exec, s[74:75]
	v_bfi_b32 v36, s48, v37, v36
	v_mul_f32_e32 v30, 0.5, v30
	v_add_f32_e32 v36, 1.0, v36
	v_mul_f32_e32 v36, v30, v36
	v_mul_f32_e32 v30, 0.5, v31
	v_bfi_b32 v31, s48, v33, v32
	v_mul_f32_e32 v28, 0.5, v28
	v_add_f32_e32 v31, 1.0, v31
	v_mul_f32_e32 v31, v28, v31
	v_mul_f32_e32 v28, 0.5, v29
	v_bfi_b32 v29, s48, v35, v34
	v_add_f32_e32 v29, 1.0, v29
	v_mul_f32_e32 v32, v28, v29
	v_add_u32_e32 v28, 0xa0, v128
	v_ashrrev_i32_e32 v29, 31, v28
	v_bfi_b32 v33, s48, v39, v38
	v_lshlrev_b64 v[28:29], 9, v[28:29]
	v_add_f32_e32 v33, 1.0, v33
	v_mul_f32_e32 v33, v30, v33
	v_lshl_add_u64 v[28:29], s[20:21], 0, v[28:29]
	v_cvt_pk_bf16_f32 v30, v31, v32
	v_cvt_pk_bf16_f32 v31, v36, v33
	v_lshl_add_u64 v[32:33], v[146:147], 1, v[28:29]
	global_store_dwordx2 v[32:33], v[30:31], off sc1
	global_load_dwordx4 v[28:31], v[144:145], off offset:64
	s_waitcnt vmcnt(0)
	v_pk_add_f32 v[24:25], v[24:25], v[28:29]
	s_nop 0
	v_mul_f32_e32 v28, 0x3d372713, v24
	v_mul_f32_e32 v28, v24, v28
	v_fma_f32 v28, v24, v28, v24
	v_mul_f32_e32 v28, 0x3f4c422a, v28
	v_cmp_nlt_f32_e64 s[58:59], |v28|, s44
	s_and_saveexec_b64 s[60:61], s[58:59]
	s_xor_b64 s[74:75], exec, s[60:61]
	s_cbranch_execz .LBB0_3489
	v_add_f32_e64 v29, |v28|, |v28|
	v_mul_f32_e32 v34, 0x3fb8aa3b, v29
	v_rndne_f32_e32 v35, v34
	v_sub_f32_e32 v36, v34, v35
	v_fma_f32 v34, v29, s45, -v34
	v_fmac_f32_e32 v34, 0x32a5705f, v29
	v_add_f32_e32 v34, v36, v34
	v_cvt_i32_f32_e32 v35, v35
	v_exp_f32_e32 v34, v34
	v_cmp_ngt_f32_e32 vcc, s46, v29
	v_ldexp_f32 v34, v34, v35
	s_nop 0
	v_cndmask_b32_e32 v34, 0, v34, vcc
	v_cmp_nlt_f32_e32 vcc, s47, v29
	s_nop 1
	v_cndmask_b32_e32 v29, v156, v34, vcc
	v_add_f32_e32 v29, 1.0, v29
	v_rcp_f32_e32 v29, v29
	s_nop 0
	v_fma_f32 v29, v29, -2.0, 1.0

.LBB0_3501:
	s_andn2_saveexec_b64 s[74:75], s[74:75]
	v_mul_f32_e32 v37, v36, v36
	v_fmamk_f32 v38, v37, 0xbbbac73d, v153
	v_fmaak_f32 v38, v37, v38, 0xbd5c1c4e
	v_fmaak_f32 v38, v37, v38, 0x3e088382
	v_fmaak_f32 v38, v37, v38, 0xbeaaaa99
	v_mul_f32_e64 v38, |v36|, v38
	v_fma_f32 v37, v37, v38, |v36|
	s_or_b64 exec, exec, s[74:75]
	v_bfi_b32 v28, s48, v29, v28
	v_mul_f32_e32 v24, 0.5, v24
	v_add_f32_e32 v28, 1.0, v28
	v_mul_f32_e32 v24, v24, v28
	v_bfi_b32 v28, s48, v31, v30
	v_mul_f32_e32 v25, 0.5, v25
	v_add_f32_e32 v28, 1.0, v28
	v_bfi_b32 v34, s48, v35, v34
	v_mul_f32_e32 v25, v25, v28
	v_bfi_b32 v28, s48, v37, v36
	v_mul_f32_e32 v26, 0.5, v26
	v_add_f32_e32 v34, 1.0, v34
	v_mul_f32_e32 v27, 0.5, v27
	v_add_f32_e32 v28, 1.0, v28
	v_mul_f32_e32 v26, v26, v34
	v_mul_f32_e32 v27, v27, v28
	v_cvt_pk_bf16_f32 v24, v24, v25
	v_cvt_pk_bf16_f32 v25, v26, v27
	global_store_dwordx2 v[32:33], v[24:25], off offset:32 sc1
	global_load_dwordx4 v[24:27], v[144:145], off offset:512
	s_waitcnt vmcnt(0)
	v_pk_add_f32 v[20:21], v[20:21], v[24:25]
	s_nop 0
	v_mul_f32_e32 v24, 0x3d372713, v20
	v_mul_f32_e32 v24, v20, v24
	v_fma_f32 v24, v20, v24, v20
	v_mul_f32_e32 v24, 0x3f4c422a, v24
	v_cmp_nlt_f32_e64 s[58:59], |v24|, s44
	s_and_saveexec_b64 s[60:61], s[58:59]
	s_xor_b64 s[74:75], exec, s[60:61]
	s_cbranch_execz .LBB0_3505
	v_add_f32_e64 v25, |v24|, |v24|
	v_mul_f32_e32 v28, 0x3fb8aa3b, v25
	v_rndne_f32_e32 v29, v28
	v_sub_f32_e32 v30, v28, v29
	v_fma_f32 v28, v25, s45, -v28
	v_fmac_f32_e32 v28, 0x32a5705f, v25
	v_add_f32_e32 v28, v30, v28
	v_cvt_i32_f32_e32 v29, v29
	v_exp_f32_e32 v28, v28
	v_cmp_ngt_f32_e32 vcc, s46, v25
	v_ldexp_f32 v28, v28, v29
	s_nop 0
	v_cndmask_b32_e32 v28, 0, v28, vcc
	v_cmp_nlt_f32_e32 vcc, s47, v25
	s_nop 1
	v_cndmask_b32_e32 v25, v156, v28, vcc
	v_add_f32_e32 v25, 1.0, v25
	v_rcp_f32_e32 v25, v25
	s_nop 0
	v_fma_f32 v25, v25, -2.0, 1.0

.LBB0_3517:
	s_andn2_saveexec_b64 s[74:75], s[74:75]
	v_mul_f32_e32 v31, v30, v30
	v_fmamk_f32 v34, v31, 0xbbbac73d, v153
	v_fmaak_f32 v34, v31, v34, 0xbd5c1c4e
	v_fmaak_f32 v34, v31, v34, 0x3e088382
	v_fmaak_f32 v34, v31, v34, 0xbeaaaa99
	v_mul_f32_e64 v34, |v30|, v34
	v_fma_f32 v31, v31, v34, |v30|
	s_or_b64 exec, exec, s[74:75]
	v_bfi_b32 v24, s48, v25, v24
	v_mul_f32_e32 v20, 0.5, v20
	v_add_f32_e32 v24, 1.0, v24
	v_mul_f32_e32 v20, v20, v24
	v_bfi_b32 v24, s48, v27, v26
	v_mul_f32_e32 v21, 0.5, v21
	v_add_f32_e32 v24, 1.0, v24
	v_bfi_b32 v28, s48, v29, v28
	v_mul_f32_e32 v21, v21, v24
	v_bfi_b32 v24, s48, v31, v30
	v_mul_f32_e32 v22, 0.5, v22
	v_add_f32_e32 v28, 1.0, v28
	v_mul_f32_e32 v23, 0.5, v23
	v_add_f32_e32 v24, 1.0, v24
	v_mul_f32_e32 v22, v22, v28
	v_mul_f32_e32 v23, v23, v24
	v_cvt_pk_bf16_f32 v20, v20, v21
	v_cvt_pk_bf16_f32 v21, v22, v23
	global_store_dwordx2 v[32:33], v[20:21], off offset:256 sc1
	global_load_dwordx4 v[20:23], v[144:145], off offset:576
	s_waitcnt vmcnt(0)
	v_pk_add_f32 v[16:17], v[16:17], v[20:21]
	s_nop 0
	v_mul_f32_e32 v20, 0x3d372713, v16
	v_mul_f32_e32 v20, v16, v20
	v_fma_f32 v20, v16, v20, v16
	v_mul_f32_e32 v20, 0x3f4c422a, v20
	v_cmp_nlt_f32_e64 s[58:59], |v20|, s44
	s_and_saveexec_b64 s[60:61], s[58:59]
	s_xor_b64 s[74:75], exec, s[60:61]
	s_cbranch_execz .LBB0_3521
	v_add_f32_e64 v21, |v20|, |v20|
	v_mul_f32_e32 v24, 0x3fb8aa3b, v21
	v_rndne_f32_e32 v25, v24
	v_sub_f32_e32 v26, v24, v25
	v_fma_f32 v24, v21, s45, -v24
	v_fmac_f32_e32 v24, 0x32a5705f, v21
	v_add_f32_e32 v24, v26, v24
	v_cvt_i32_f32_e32 v25, v25
	v_exp_f32_e32 v24, v24
	v_cmp_ngt_f32_e32 vcc, s46, v21
	v_ldexp_f32 v24, v24, v25
	s_nop 0
	v_cndmask_b32_e32 v24, 0, v24, vcc
	v_cmp_nlt_f32_e32 vcc, s47, v21
	s_nop 1
	v_cndmask_b32_e32 v21, v156, v24, vcc
	v_add_f32_e32 v21, 1.0, v21
	v_rcp_f32_e32 v21, v21
	s_nop 0
	v_fma_f32 v21, v21, -2.0, 1.0

.LBB0_3533:
	s_andn2_saveexec_b64 s[74:75], s[74:75]
	v_mul_f32_e32 v27, v26, v26
	v_fmamk_f32 v28, v27, 0xbbbac73d, v153
	v_fmaak_f32 v28, v27, v28, 0xbd5c1c4e
	v_fmaak_f32 v28, v27, v28, 0x3e088382
	v_fmaak_f32 v28, v27, v28, 0xbeaaaa99
	v_mul_f32_e64 v28, |v26|, v28
	v_fma_f32 v27, v27, v28, |v26|
	s_or_b64 exec, exec, s[74:75]
	v_bfi_b32 v20, s48, v21, v20
	v_mul_f32_e32 v16, 0.5, v16
	v_add_f32_e32 v20, 1.0, v20
	v_mul_f32_e32 v16, v16, v20
	v_bfi_b32 v20, s48, v23, v22
	v_mul_f32_e32 v17, 0.5, v17
	v_add_f32_e32 v20, 1.0, v20
	v_bfi_b32 v24, s48, v25, v24
	v_mul_f32_e32 v17, v17, v20
	v_bfi_b32 v20, s48, v27, v26
	v_mul_f32_e32 v18, 0.5, v18
	v_add_f32_e32 v24, 1.0, v24
	v_mul_f32_e32 v19, 0.5, v19
	v_add_f32_e32 v20, 1.0, v20
	v_mul_f32_e32 v18, v18, v24
	v_mul_f32_e32 v19, v19, v20
	v_cvt_pk_bf16_f32 v16, v16, v17
	v_cvt_pk_bf16_f32 v17, v18, v19
	global_store_dwordx2 v[32:33], v[16:17], off offset:288 sc1
	global_load_dwordx4 v[16:19], v[144:145], off
	s_waitcnt vmcnt(0)
	v_pk_add_f32 v[12:13], v[12:13], v[16:17]
	s_nop 0
	v_mul_f32_e32 v16, 0x3d372713, v12
	v_mul_f32_e32 v16, v12, v16
	v_fma_f32 v16, v12, v16, v12
	v_mul_f32_e32 v16, 0x3f4c422a, v16
	v_cmp_nlt_f32_e64 s[58:59], |v16|, s44
	s_and_saveexec_b64 s[60:61], s[58:59]
	s_xor_b64 s[74:75], exec, s[60:61]
	s_cbranch_execz .LBB0_3537
	v_add_f32_e64 v17, |v16|, |v16|
	v_mul_f32_e32 v20, 0x3fb8aa3b, v17
	v_rndne_f32_e32 v21, v20
	v_sub_f32_e32 v22, v20, v21
	v_fma_f32 v20, v17, s45, -v20
	v_fmac_f32_e32 v20, 0x32a5705f, v17
	v_add_f32_e32 v20, v22, v20
	v_cvt_i32_f32_e32 v21, v21
	v_exp_f32_e32 v20, v20
	v_cmp_ngt_f32_e32 vcc, s46, v17
	v_ldexp_f32 v20, v20, v21
	s_nop 0
	v_cndmask_b32_e32 v20, 0, v20, vcc
	v_cmp_nlt_f32_e32 vcc, s47, v17
	s_nop 1
	v_cndmask_b32_e32 v17, v156, v20, vcc
	v_add_f32_e32 v17, 1.0, v17
	v_rcp_f32_e32 v17, v17
	s_nop 0
	v_fma_f32 v17, v17, -2.0, 1.0

.LBB0_3549:
	s_andn2_saveexec_b64 s[74:75], s[74:75]
	v_mul_f32_e32 v23, v22, v22
	v_fmamk_f32 v24, v23, 0xbbbac73d, v153
	v_fmaak_f32 v24, v23, v24, 0xbd5c1c4e
	v_fmaak_f32 v24, v23, v24, 0x3e088382
	v_fmaak_f32 v24, v23, v24, 0xbeaaaa99
	v_mul_f32_e64 v24, |v22|, v24
	v_fma_f32 v23, v23, v24, |v22|
	s_or_b64 exec, exec, s[74:75]
	v_bfi_b32 v20, s48, v21, v20
	v_mul_f32_e32 v14, 0.5, v14
	v_add_f32_e32 v20, 1.0, v20
	v_mul_f32_e32 v20, v14, v20
	v_mul_f32_e32 v14, 0.5, v15
	v_bfi_b32 v15, s48, v17, v16
	v_mul_f32_e32 v12, 0.5, v12
	v_add_f32_e32 v15, 1.0, v15
	v_mul_f32_e32 v15, v12, v15
	v_mul_f32_e32 v12, 0.5, v13
	v_bfi_b32 v13, s48, v19, v18
	v_add_f32_e32 v13, 1.0, v13
	v_mul_f32_e32 v16, v12, v13
	v_add_u32_e32 v12, 0xb0, v128
	v_ashrrev_i32_e32 v13, 31, v12
	v_bfi_b32 v17, s48, v23, v22
	v_lshlrev_b64 v[12:13], 9, v[12:13]
	v_add_f32_e32 v17, 1.0, v17
	v_mul_f32_e32 v17, v14, v17
	v_lshl_add_u64 v[12:13], s[20:21], 0, v[12:13]
	v_cvt_pk_bf16_f32 v14, v15, v16
	v_cvt_pk_bf16_f32 v15, v20, v17
	v_lshl_add_u64 v[16:17], v[146:147], 1, v[12:13]
	global_store_dwordx2 v[16:17], v[14:15], off sc1
	global_load_dwordx4 v[12:15], v[144:145], off offset:64
	s_waitcnt vmcnt(0)
	v_pk_add_f32 v[8:9], v[8:9], v[12:13]
	s_nop 0
	v_mul_f32_e32 v12, 0x3d372713, v8
	v_mul_f32_e32 v12, v8, v12
	v_fma_f32 v12, v8, v12, v8
	v_mul_f32_e32 v12, 0x3f4c422a, v12
	v_cmp_nlt_f32_e64 s[58:59], |v12|, s44
	s_and_saveexec_b64 s[60:61], s[58:59]
	s_xor_b64 s[74:75], exec, s[60:61]
	s_cbranch_execz .LBB0_3553
	v_add_f32_e64 v13, |v12|, |v12|
	v_mul_f32_e32 v18, 0x3fb8aa3b, v13
	v_rndne_f32_e32 v19, v18
	v_sub_f32_e32 v20, v18, v19
	v_fma_f32 v18, v13, s45, -v18
	v_fmac_f32_e32 v18, 0x32a5705f, v13
	v_add_f32_e32 v18, v20, v18
	v_cvt_i32_f32_e32 v19, v19
	v_exp_f32_e32 v18, v18
	v_cmp_ngt_f32_e32 vcc, s46, v13
	v_ldexp_f32 v18, v18, v19
	s_nop 0
	v_cndmask_b32_e32 v18, 0, v18, vcc
	v_cmp_nlt_f32_e32 vcc, s47, v13
	s_nop 1
	v_cndmask_b32_e32 v13, v156, v18, vcc
	v_add_f32_e32 v13, 1.0, v13
	v_rcp_f32_e32 v13, v13
	s_nop 0
	v_fma_f32 v13, v13, -2.0, 1.0

.LBB0_3565:
	s_andn2_saveexec_b64 s[74:75], s[74:75]
	v_mul_f32_e32 v21, v20, v20
	v_fmamk_f32 v22, v21, 0xbbbac73d, v153
	v_fmaak_f32 v22, v21, v22, 0xbd5c1c4e
	v_fmaak_f32 v22, v21, v22, 0x3e088382
	v_fmaak_f32 v22, v21, v22, 0xbeaaaa99
	v_mul_f32_e64 v22, |v20|, v22
	v_fma_f32 v21, v21, v22, |v20|
	s_or_b64 exec, exec, s[74:75]
	v_bfi_b32 v12, s48, v13, v12
	v_mul_f32_e32 v8, 0.5, v8
	v_add_f32_e32 v12, 1.0, v12
	v_mul_f32_e32 v8, v8, v12
	v_bfi_b32 v12, s48, v15, v14
	v_mul_f32_e32 v9, 0.5, v9
	v_add_f32_e32 v12, 1.0, v12
	v_bfi_b32 v18, s48, v19, v18
	v_mul_f32_e32 v9, v9, v12
	v_bfi_b32 v12, s48, v21, v20
	v_mul_f32_e32 v10, 0.5, v10
	v_add_f32_e32 v18, 1.0, v18
	v_mul_f32_e32 v11, 0.5, v11
	v_add_f32_e32 v12, 1.0, v12
	v_mul_f32_e32 v10, v10, v18
	v_mul_f32_e32 v11, v11, v12
	v_cvt_pk_bf16_f32 v8, v8, v9
	v_cvt_pk_bf16_f32 v9, v10, v11
	global_store_dwordx2 v[16:17], v[8:9], off offset:32 sc1
	global_load_dwordx4 v[8:11], v[144:145], off offset:512
	s_waitcnt vmcnt(0)
	v_pk_add_f32 v[4:5], v[4:5], v[8:9]
	s_nop 0
	v_mul_f32_e32 v8, 0x3d372713, v4
	v_mul_f32_e32 v8, v4, v8
	v_fma_f32 v8, v4, v8, v4
	v_mul_f32_e32 v8, 0x3f4c422a, v8
	v_cmp_nlt_f32_e64 s[58:59], |v8|, s44
	s_and_saveexec_b64 s[60:61], s[58:59]
	s_xor_b64 s[74:75], exec, s[60:61]
	s_cbranch_execz .LBB0_3569
	v_add_f32_e64 v9, |v8|, |v8|
	v_mul_f32_e32 v12, 0x3fb8aa3b, v9
	v_rndne_f32_e32 v13, v12
	v_sub_f32_e32 v14, v12, v13
	v_fma_f32 v12, v9, s45, -v12
	v_fmac_f32_e32 v12, 0x32a5705f, v9
	v_add_f32_e32 v12, v14, v12
	v_cvt_i32_f32_e32 v13, v13
	v_exp_f32_e32 v12, v12
	v_cmp_ngt_f32_e32 vcc, s46, v9
	v_ldexp_f32 v12, v12, v13
	s_nop 0
	v_cndmask_b32_e32 v12, 0, v12, vcc
	v_cmp_nlt_f32_e32 vcc, s47, v9
	s_nop 1
	v_cndmask_b32_e32 v9, v156, v12, vcc
	v_add_f32_e32 v9, 1.0, v9
	v_rcp_f32_e32 v9, v9
	s_nop 0
	v_fma_f32 v9, v9, -2.0, 1.0

.LBB0_3581:
	s_andn2_saveexec_b64 s[74:75], s[74:75]
	v_mul_f32_e32 v15, v14, v14
	v_fmamk_f32 v18, v15, 0xbbbac73d, v153
	v_fmaak_f32 v18, v15, v18, 0xbd5c1c4e
	v_fmaak_f32 v18, v15, v18, 0x3e088382
	v_fmaak_f32 v18, v15, v18, 0xbeaaaa99
	v_mul_f32_e64 v18, |v14|, v18
	v_fma_f32 v15, v15, v18, |v14|
	s_or_b64 exec, exec, s[74:75]
	v_bfi_b32 v8, s48, v9, v8
	v_mul_f32_e32 v4, 0.5, v4
	v_add_f32_e32 v8, 1.0, v8
	v_mul_f32_e32 v4, v4, v8
	v_bfi_b32 v8, s48, v11, v10
	v_mul_f32_e32 v5, 0.5, v5
	v_add_f32_e32 v8, 1.0, v8
	v_bfi_b32 v12, s48, v13, v12
	v_mul_f32_e32 v5, v5, v8
	v_bfi_b32 v8, s48, v15, v14
	v_mul_f32_e32 v6, 0.5, v6
	v_add_f32_e32 v12, 1.0, v12
	v_mul_f32_e32 v7, 0.5, v7
	v_add_f32_e32 v8, 1.0, v8
	v_mul_f32_e32 v6, v6, v12
	v_mul_f32_e32 v7, v7, v8
	v_cvt_pk_bf16_f32 v4, v4, v5
	v_cvt_pk_bf16_f32 v5, v6, v7
	global_store_dwordx2 v[16:17], v[4:5], off offset:256 sc1
	global_load_dwordx4 v[4:7], v[144:145], off offset:576
	s_waitcnt vmcnt(0)
	v_pk_add_f32 v[0:1], v[0:1], v[4:5]
	s_nop 0
	v_mul_f32_e32 v4, 0x3d372713, v0
	v_mul_f32_e32 v4, v0, v4
	v_fma_f32 v4, v0, v4, v0
	v_mul_f32_e32 v4, 0x3f4c422a, v4
	v_cmp_nlt_f32_e64 s[58:59], |v4|, s44
	s_and_saveexec_b64 s[60:61], s[58:59]
	s_xor_b64 s[74:75], exec, s[60:61]
	s_cbranch_execz .LBB0_3585
	v_add_f32_e64 v5, |v4|, |v4|
	v_mul_f32_e32 v8, 0x3fb8aa3b, v5
	v_rndne_f32_e32 v9, v8
	v_sub_f32_e32 v10, v8, v9
	v_fma_f32 v8, v5, s45, -v8
	v_fmac_f32_e32 v8, 0x32a5705f, v5
	v_add_f32_e32 v8, v10, v8
	v_cvt_i32_f32_e32 v9, v9
	v_exp_f32_e32 v8, v8
	v_cmp_ngt_f32_e32 vcc, s46, v5
	v_ldexp_f32 v8, v8, v9
	s_nop 0
	v_cndmask_b32_e32 v8, 0, v8, vcc
	v_cmp_nlt_f32_e32 vcc, s47, v5
	s_nop 1
	v_cndmask_b32_e32 v5, v156, v8, vcc
	v_add_f32_e32 v5, 1.0, v5
	v_rcp_f32_e32 v5, v5
	s_nop 0
	v_fma_f32 v5, v5, -2.0, 1.0

.LBB0_3597:
	s_andn2_saveexec_b64 s[74:75], s[74:75]
	v_mul_f32_e32 v11, v10, v10
	v_fmamk_f32 v12, v11, 0xbbbac73d, v153
	v_fmaak_f32 v12, v11, v12, 0xbd5c1c4e
	v_fmaak_f32 v12, v11, v12, 0x3e088382
	v_fmaak_f32 v12, v11, v12, 0xbeaaaa99
	v_mul_f32_e64 v12, |v10|, v12
	v_fma_f32 v11, v11, v12, |v10|
	s_or_b64 exec, exec, s[74:75]
	v_bfi_b32 v7, s48, v7, v6
	v_bfi_b32 v6, s48, v5, v4
	v_pk_mul_f32 v[0:1], v[0:1], 0.5 op_sel_hi:[1,0]
	v_pk_add_f32 v[4:5], v[6:7], 1.0 op_sel_hi:[1,0]
	v_pk_mul_f32 v[2:3], v[2:3], 0.5 op_sel_hi:[1,0]
	v_pk_mul_f32 v[0:1], v[0:1], v[4:5]
	v_bfi_b32 v5, s48, v11, v10
	v_bfi_b32 v4, s48, v9, v8
	v_pk_add_f32 v[4:5], v[4:5], 1.0 op_sel_hi:[1,0]
	v_cvt_pk_bf16_f32 v0, v0, v1
	v_pk_mul_f32 v[2:3], v[2:3], v[4:5]
	s_andn2_b64 vcc, exec, s[64:65]
	v_cvt_pk_bf16_f32 v1, v2, v3
	s_mov_b64 s[64:65], -1
	global_store_dwordx2 v[16:17], v[0:1], off offset:288 sc1
	s_cbranch_vccnz .LBB0_3076
	s_andn2_b64 vcc, exec, s[24:25]
	s_cbranch_vccnz .LBB0_3075
	s_barrier
	s_branch .LBB0_3075

.LBB0_3607:
	s_or_b64 exec, exec, s[24:25]
	s_waitcnt vmcnt(0)
	ds_write2_b32 v41, v0, v1 offset1:1
	ds_write2_b32 v41, v2, v3 offset0:2 offset1:3
	v_add_u32_e32 v0, 0x420, v41
	ds_write2_b32 v0, v8, v9 offset1:1
	v_add_u32_e32 v0, 0x428, v41
	ds_write2_b32 v0, v10, v11 offset1:1
	v_add_u32_e32 v0, 0x840, v41
	ds_write2_b32 v0, v4, v5 offset1:1
	v_add_u32_e32 v0, 0x848, v41
	ds_write2_b32 v0, v6, v7 offset1:1
	v_add_u32_e32 v0, 0xc60, v41
	ds_write2_b32 v0, v16, v17 offset1:1
	v_add_u32_e32 v0, 0xc68, v41
	ds_write2_b32 v0, v18, v19 offset1:1
	v_add_u32_e32 v0, 0x1080, v41
	ds_write2_b32 v0, v12, v13 offset1:1
	v_add_u32_e32 v0, 0x1088, v41
	ds_write2_b32 v0, v14, v15 offset1:1
	v_add_u32_e32 v0, 0x14a0, v41
	ds_write2_b32 v0, v24, v25 offset1:1
	v_add_u32_e32 v0, 0x14a8, v41
	ds_write2_b32 v0, v26, v27 offset1:1
	v_add_u32_e32 v0, 0x18c0, v41
	ds_write2_b32 v0, v20, v21 offset1:1
	v_add_u32_e32 v0, 0x18c8, v41
	ds_write2_b32 v0, v22, v23 offset1:1
	v_add_u32_e32 v0, 0x1ce0, v41
	ds_write2_b32 v0, v28, v29 offset1:1
	v_add_u32_e32 v0, 0x1ce8, v41
	ds_write2_b32 v0, v30, v31 offset1:1
	s_waitcnt lgkmcnt(0)
	s_sub_i32 s5, 0, s5
	ds_read2_b32 v[4:5], v40 offset0:33 offset1:41
	ds_read2_b32 v[6:7], v40 offset1:8
	ds_read2_b32 v[8:9], v40 offset0:66 offset1:74
	ds_read2_b32 v[10:11], v40 offset0:99 offset1:107
	ds_read2_b32 v[12:13], v40 offset0:132 offset1:140
	ds_read2_b32 v[14:15], v40 offset0:165 offset1:173
	ds_read2_b32 v[16:17], v40 offset0:198 offset1:206
	ds_read2_b32 v[18:19], v40 offset0:231 offset1:239
	s_add_i32 s5, s5, s3
	v_add_u32_e32 v22, s5, v39
	s_ashr_i32 s23, s22, 31
	v_ashrrev_i32_e32 v23, 31, v22
	v_lshl_add_u64 v[20:21], s[22:23], 1, v[32:33]
	v_lshlrev_b64 v[24:25], 11, v[22:23]
	s_waitcnt lgkmcnt(6)
	v_cvt_pk_bf16_f32 v0, v6, v4
	s_waitcnt lgkmcnt(4)
	v_cvt_pk_bf16_f32 v1, v8, v10
	s_waitcnt lgkmcnt(2)
	v_cvt_pk_bf16_f32 v2, v12, v14
	s_waitcnt lgkmcnt(0)
	v_cvt_pk_bf16_f32 v3, v16, v18
	v_lshl_add_u64 v[24:25], v[20:21], 0, v[24:25]
	v_add_u32_e32 v4, 8, v22
	global_store_dwordx4 v[24:25], v[0:3], off sc1
	s_add_i32 s5, s2, 0x380
	s_addk_i32 s3, 0x7000
	v_cvt_pk_bf16_f32 v0, v7, v5
	v_ashrrev_i32_e32 v5, 31, v4
	v_cvt_pk_bf16_f32 v1, v9, v11
	v_cvt_pk_bf16_f32 v2, v13, v15
	v_cvt_pk_bf16_f32 v3, v17, v19
	v_lshlrev_b64 v[4:5], 11, v[4:5]
	ds_read2_b32 v[6:7], v40 offset0:49 offset1:57
	ds_read2_b32 v[8:9], v40 offset0:16 offset1:24
	ds_read2_b32 v[10:11], v40 offset0:82 offset1:90
	ds_read2_b32 v[12:13], v40 offset0:115 offset1:123
	ds_read2_b32 v[14:15], v40 offset0:148 offset1:156
	ds_read2_b32 v[16:17], v40 offset0:181 offset1:189
	ds_read2_b32 v[18:19], v40 offset0:214 offset1:222
	ds_read2_b32 v[24:25], v40 offset0:247 offset1:255
	v_lshl_add_u64 v[4:5], v[20:21], 0, v[4:5]
	global_store_dwordx4 v[4:5], v[0:3], off sc1
	v_add_u32_e32 v4, 16, v22
	v_ashrrev_i32_e32 v5, 31, v4
	v_lshlrev_b64 v[4:5], 11, v[4:5]
	s_waitcnt lgkmcnt(6)
	v_cvt_pk_bf16_f32 v0, v8, v6
	s_waitcnt lgkmcnt(4)
	v_cvt_pk_bf16_f32 v1, v10, v12
	s_waitcnt lgkmcnt(2)
	v_cvt_pk_bf16_f32 v2, v14, v16
	s_waitcnt lgkmcnt(0)
	v_cvt_pk_bf16_f32 v3, v18, v24
	v_lshl_add_u64 v[4:5], v[20:21], 0, v[4:5]
	global_store_dwordx4 v[4:5], v[0:3], off sc1
	v_add_u32_e32 v4, 24, v22
	v_ashrrev_i32_e32 v5, 31, v4
	v_lshlrev_b64 v[4:5], 11, v[4:5]
	v_cvt_pk_bf16_f32 v0, v9, v7
	v_cvt_pk_bf16_f32 v1, v11, v13
	v_cvt_pk_bf16_f32 v2, v15, v17
	v_cvt_pk_bf16_f32 v3, v19, v25
	v_lshl_add_u64 v[4:5], v[20:21], 0, v[4:5]
	global_store_dwordx4 v[4:5], v[0:3], off sc1
	s_waitcnt lgkmcnt(0)
	s_cmpk_lt_i32 s2, 0x480
	s_mov_b32 s2, s5
	s_cbranch_scc0 .LBB0_3624

.LBB0_3626:
	s_or_b64 exec, exec, s[24:25]
	s_waitcnt vmcnt(0)
	ds_write2_b32 v41, v0, v1 offset1:1
	ds_write2_b32 v41, v2, v3 offset0:2 offset1:3
	v_add_u32_e32 v0, 0x420, v41
	ds_write2_b32 v0, v8, v9 offset1:1
	v_add_u32_e32 v0, 0x428, v41
	ds_write2_b32 v0, v10, v11 offset1:1
	v_add_u32_e32 v0, 0x840, v41
	ds_write2_b32 v0, v4, v5 offset1:1
	v_add_u32_e32 v0, 0x848, v41
	ds_write2_b32 v0, v6, v7 offset1:1
	v_add_u32_e32 v0, 0xc60, v41
	ds_write2_b32 v0, v16, v17 offset1:1
	v_add_u32_e32 v0, 0xc68, v41
	ds_write2_b32 v0, v18, v19 offset1:1
	v_add_u32_e32 v0, 0x1080, v41
	ds_write2_b32 v0, v12, v13 offset1:1
	v_add_u32_e32 v0, 0x1088, v41
	ds_write2_b32 v0, v14, v15 offset1:1
	v_add_u32_e32 v0, 0x14a0, v41
	ds_write2_b32 v0, v24, v25 offset1:1
	v_add_u32_e32 v0, 0x14a8, v41
	ds_write2_b32 v0, v26, v27 offset1:1
	v_add_u32_e32 v0, 0x18c0, v41
	ds_write2_b32 v0, v20, v21 offset1:1
	v_add_u32_e32 v0, 0x18c8, v41
	ds_write2_b32 v0, v22, v23 offset1:1
	v_add_u32_e32 v0, 0x1ce0, v41
	ds_write2_b32 v0, v28, v29 offset1:1
	v_add_u32_e32 v0, 0x1ce8, v41
	ds_write2_b32 v0, v30, v31 offset1:1
	s_waitcnt lgkmcnt(0)
	s_sub_i32 s4, 0, s4
	ds_read2_b32 v[4:5], v40 offset0:33 offset1:41
	ds_read2_b32 v[6:7], v40 offset1:8
	ds_read2_b32 v[8:9], v40 offset0:66 offset1:74
	ds_read2_b32 v[10:11], v40 offset0:99 offset1:107
	ds_read2_b32 v[12:13], v40 offset0:132 offset1:140
	ds_read2_b32 v[14:15], v40 offset0:165 offset1:173
	ds_read2_b32 v[16:17], v40 offset0:198 offset1:206
	ds_read2_b32 v[18:19], v40 offset0:231 offset1:239
	s_add_i32 s4, s4, s2
	v_add_u32_e32 v22, s4, v39
	s_ashr_i32 s23, s22, 31
	v_ashrrev_i32_e32 v23, 31, v22
	v_lshl_add_u64 v[20:21], s[22:23], 1, v[32:33]
	v_lshlrev_b64 v[24:25], 13, v[22:23]
	s_waitcnt lgkmcnt(6)
	v_cvt_pk_bf16_f32 v0, v6, v4
	s_waitcnt lgkmcnt(4)
	v_cvt_pk_bf16_f32 v1, v8, v10
	s_waitcnt lgkmcnt(2)
	v_cvt_pk_bf16_f32 v2, v12, v14
	s_waitcnt lgkmcnt(0)
	v_cvt_pk_bf16_f32 v3, v16, v18
	v_lshl_add_u64 v[24:25], v[20:21], 0, v[24:25]
	v_add_u32_e32 v4, 8, v22
	global_store_dwordx4 v[24:25], v[0:3], off sc1
	s_add_i32 s4, s1, 0x380
	s_addk_i32 s2, 0x7000
	v_cvt_pk_bf16_f32 v0, v7, v5
	v_ashrrev_i32_e32 v5, 31, v4
	v_cvt_pk_bf16_f32 v1, v9, v11
	v_cvt_pk_bf16_f32 v2, v13, v15
	v_cvt_pk_bf16_f32 v3, v17, v19
	v_lshlrev_b64 v[4:5], 13, v[4:5]
	ds_read2_b32 v[6:7], v40 offset0:49 offset1:57
	ds_read2_b32 v[8:9], v40 offset0:16 offset1:24
	ds_read2_b32 v[10:11], v40 offset0:82 offset1:90
	ds_read2_b32 v[12:13], v40 offset0:115 offset1:123
	ds_read2_b32 v[14:15], v40 offset0:148 offset1:156
	ds_read2_b32 v[16:17], v40 offset0:181 offset1:189
	ds_read2_b32 v[18:19], v40 offset0:214 offset1:222
	ds_read2_b32 v[24:25], v40 offset0:247 offset1:255
	v_lshl_add_u64 v[4:5], v[20:21], 0, v[4:5]
	global_store_dwordx4 v[4:5], v[0:3], off sc1
	v_add_u32_e32 v4, 16, v22
	v_ashrrev_i32_e32 v5, 31, v4
	v_lshlrev_b64 v[4:5], 13, v[4:5]
	s_waitcnt lgkmcnt(6)
	v_cvt_pk_bf16_f32 v0, v8, v6
	s_waitcnt lgkmcnt(4)
	v_cvt_pk_bf16_f32 v1, v10, v12
	s_waitcnt lgkmcnt(2)
	v_cvt_pk_bf16_f32 v2, v14, v16
	s_waitcnt lgkmcnt(0)
	v_cvt_pk_bf16_f32 v3, v18, v24
	v_lshl_add_u64 v[4:5], v[20:21], 0, v[4:5]
	global_store_dwordx4 v[4:5], v[0:3], off sc1
	v_add_u32_e32 v4, 24, v22
	v_ashrrev_i32_e32 v5, 31, v4
	v_lshlrev_b64 v[4:5], 13, v[4:5]
	v_cvt_pk_bf16_f32 v0, v9, v7
	v_cvt_pk_bf16_f32 v1, v11, v13
	v_cvt_pk_bf16_f32 v2, v15, v17
	v_cvt_pk_bf16_f32 v3, v19, v25
	v_lshl_add_u64 v[4:5], v[20:21], 0, v[4:5]
	global_store_dwordx4 v[4:5], v[0:3], off sc1
	s_waitcnt lgkmcnt(0)
	s_cmpk_lt_i32 s1, 0x480
	s_mov_b32 s1, s4
	s_cbranch_scc0 .LBB0_3643

.LBB0_3719:
	v_ashrrev_i32_e32 v77, 31, v76
	v_lshlrev_b64 v[84:85], 7, v[76:77]
	v_cvt_pk_bf16_f32 v60, v60, v61
	v_cvt_pk_bf16_f32 v61, v62, v63
	v_lshl_add_u64 v[62:63], v[74:75], 0, v[84:85]
	v_cvt_pk_bf16_f32 v56, v56, v57
	v_cvt_pk_bf16_f32 v57, v58, v59
	global_store_dwordx2 v[62:63], v[56:57], off offset:32 sc1
	s_and_b64 vcc, exec, s[10:11]
	v_or_b32_e32 v56, 16, v76
	global_store_dwordx2 v[62:63], v[60:61], off sc1
	s_cbranch_vccnz .LBB0_3721
	v_lshlrev_b32_e32 v57, 9, v56
	v_and_b32_e32 v68, 0x7be00, v57
	v_lshl_add_u64 v[58:59], v[72:73], 0, v[68:69]
	global_load_dwordx4 v[58:61], v[58:59], off offset:992
	v_lshl_add_u64 v[62:63], v[70:71], 0, v[68:69]
	global_load_dwordx4 v[84:87], v[62:63], off offset:992
	v_and_b32_e32 v62, 64, v211
	v_xor_b32_e32 v57, 32, v211
	v_add_u32_e32 v62, 64, v62
	v_cmp_lt_i32_e32 vcc, v57, v62
	s_nop 1
	v_cndmask_b32_e32 v57, v211, v57, vcc
	v_lshlrev_b32_e32 v57, 2, v57
	ds_bpermute_b32 v62, v57, v52
	ds_bpermute_b32 v63, v57, v53
	ds_bpermute_b32 v88, v57, v54
	ds_bpermute_b32 v89, v57, v55
	s_waitcnt vmcnt(0) lgkmcnt(0)
	v_pk_mul_f32 v[58:59], v[58:59], v[62:63]
	v_pk_mul_f32 v[60:61], v[60:61], v[88:89]
	v_xor_b32_e32 v63, 0x80000000, v58
	v_xor_b32_e32 v57, 0x80000000, v60
	v_xor_b32_e32 v62, 0x80000000, v61
	v_xor_b32_e32 v68, 0x80000000, v59
	v_cndmask_b32_e64 v59, v59, v68, s[8:9]
	v_cndmask_b32_e64 v58, v58, v63, s[8:9]
	v_cndmask_b32_e64 v61, v61, v62, s[8:9]
	v_cndmask_b32_e64 v60, v60, v57, s[8:9]
	v_pk_fma_f32 v[54:55], v[54:55], v[86:87], v[60:61]
	v_pk_fma_f32 v[52:53], v[52:53], v[84:85], v[58:59]
.LBB0_3721:
	v_ashrrev_i32_e32 v57, 31, v56
	v_lshlrev_b64 v[56:57], 7, v[56:57]
	v_cvt_pk_bf16_f32 v52, v52, v53
	v_cvt_pk_bf16_f32 v53, v54, v55
	v_lshl_add_u64 v[54:55], v[74:75], 0, v[56:57]
	v_cvt_pk_bf16_f32 v48, v48, v49
	v_cvt_pk_bf16_f32 v49, v50, v51
	global_store_dwordx2 v[54:55], v[48:49], off offset:32 sc1
	s_and_b64 vcc, exec, s[10:11]
	v_or_b32_e32 v48, 32, v76
	global_store_dwordx2 v[54:55], v[52:53], off sc1
	s_cbranch_vccnz .LBB0_3723
	v_lshlrev_b32_e32 v49, 9, v48
	v_and_b32_e32 v68, 0x7de00, v49
	v_lshl_add_u64 v[50:51], v[72:73], 0, v[68:69]
	global_load_dwordx4 v[50:53], v[50:51], off offset:992
	v_lshl_add_u64 v[54:55], v[70:71], 0, v[68:69]
	global_load_dwordx4 v[54:57], v[54:55], off offset:992
	v_and_b32_e32 v58, 64, v211
	v_xor_b32_e32 v49, 32, v211
	v_add_u32_e32 v58, 64, v58
	v_cmp_lt_i32_e32 vcc, v49, v58
	s_nop 1
	v_cndmask_b32_e32 v49, v211, v49, vcc
	v_lshlrev_b32_e32 v49, 2, v49
	ds_bpermute_b32 v58, v49, v44
	ds_bpermute_b32 v59, v49, v45
	ds_bpermute_b32 v60, v49, v46
	ds_bpermute_b32 v61, v49, v47
	s_waitcnt vmcnt(0) lgkmcnt(0)
	v_pk_mul_f32 v[50:51], v[50:51], v[58:59]
	v_pk_mul_f32 v[52:53], v[52:53], v[60:61]
	v_xor_b32_e32 v59, 0x80000000, v50
	v_xor_b32_e32 v49, 0x80000000, v52
	v_xor_b32_e32 v58, 0x80000000, v53
	v_xor_b32_e32 v60, 0x80000000, v51
	v_cndmask_b32_e64 v51, v51, v60, s[8:9]
	v_cndmask_b32_e64 v50, v50, v59, s[8:9]
	v_cndmask_b32_e64 v53, v53, v58, s[8:9]
	v_cndmask_b32_e64 v52, v52, v49, s[8:9]
	v_pk_fma_f32 v[46:47], v[46:47], v[56:57], v[52:53]
	v_pk_fma_f32 v[44:45], v[44:45], v[54:55], v[50:51]
.LBB0_3723:
	v_ashrrev_i32_e32 v49, 31, v48
	v_lshlrev_b64 v[48:49], 7, v[48:49]
	v_cvt_pk_bf16_f32 v44, v44, v45
	v_cvt_pk_bf16_f32 v45, v46, v47
	v_lshl_add_u64 v[46:47], v[74:75], 0, v[48:49]
	v_cvt_pk_bf16_f32 v40, v40, v41
	v_cvt_pk_bf16_f32 v41, v42, v43
	global_store_dwordx2 v[46:47], v[40:41], off offset:32 sc1
	v_bitop3_b32 v40, v76, s43, 48 bitop3:0xc8
	s_and_b64 vcc, exec, s[10:11]
	v_cmp_eq_u32_e64 s[14:15], s43, v40
	global_store_dwordx2 v[46:47], v[44:45], off sc1
	s_cbranch_vccnz .LBB0_3725
	v_lshl_add_u32 v40, v40, 7, v82
	v_cndmask_b32_e64 v40, v40, v83, s[14:15]
	v_lshlrev_b32_e32 v68, 2, v40
	v_lshl_add_u64 v[40:41], v[72:73], 0, v[68:69]
	global_load_dwordx4 v[40:43], v[40:41], off
	v_lshl_add_u64 v[44:45], v[70:71], 0, v[68:69]
	global_load_dwordx4 v[44:47], v[44:45], off
	v_and_b32_e32 v49, 64, v211
	v_xor_b32_e32 v48, 32, v211
	v_add_u32_e32 v49, 64, v49
	v_cmp_lt_i32_e32 vcc, v48, v49
	s_nop 1
	v_cndmask_b32_e32 v48, v211, v48, vcc
	v_lshlrev_b32_e32 v49, 2, v48
	ds_bpermute_b32 v48, v49, v36
	ds_bpermute_b32 v50, v49, v38
	ds_bpermute_b32 v51, v49, v39
	ds_bpermute_b32 v49, v49, v37
	s_waitcnt vmcnt(0) lgkmcnt(0)
	v_pk_mul_f32 v[42:43], v[42:43], v[50:51]
	v_pk_mul_f32 v[40:41], v[40:41], v[48:49]
	v_xor_b32_e32 v48, 0x80000000, v42
	v_xor_b32_e32 v49, 0x80000000, v43
	v_xor_b32_e32 v50, 0x80000000, v40
	v_xor_b32_e32 v51, 0x80000000, v41
	v_cndmask_b32_e64 v43, v43, v49, s[8:9]
	v_cndmask_b32_e64 v42, v42, v48, s[8:9]
	v_cndmask_b32_e64 v41, v41, v51, s[8:9]
	v_cndmask_b32_e64 v40, v40, v50, s[8:9]
	v_pk_fma_f32 v[38:39], v[38:39], v[46:47], v[42:43]
	v_pk_fma_f32 v[36:37], v[36:37], v[44:45], v[40:41]
.LBB0_3725:
	v_or_b32_e32 v40, 48, v76
	v_ashrrev_i32_e32 v41, 31, v40
	v_lshlrev_b64 v[40:41], 7, v[40:41]
	v_cndmask_b32_e64 v39, v39, 0, s[14:15]
	v_cndmask_b32_e64 v38, v38, 0, s[14:15]
	v_cndmask_b32_e64 v37, v37, 0, s[14:15]
	v_cndmask_b32_e64 v36, v36, 0, s[14:15]
	v_cndmask_b32_e64 v35, v35, 0, s[14:15]
	v_cndmask_b32_e64 v34, v34, 0, s[14:15]
	v_cndmask_b32_e64 v33, v33, 0, s[14:15]
	v_cndmask_b32_e64 v32, v32, 0, s[14:15]
	v_cvt_pk_bf16_f32 v36, v36, v37
	v_cvt_pk_bf16_f32 v37, v38, v39
	v_lshl_add_u64 v[38:39], v[74:75], 0, v[40:41]
	v_cvt_pk_bf16_f32 v32, v32, v33
	v_cvt_pk_bf16_f32 v33, v34, v35
	global_store_dwordx2 v[38:39], v[32:33], off offset:32 sc1
	s_and_b64 vcc, exec, s[10:11]
	v_add_u32_e32 v32, 0x80, v76
	global_store_dwordx2 v[38:39], v[36:37], off sc1
	s_cbranch_vccnz .LBB0_3727
	v_lshlrev_b32_e32 v33, 9, v32
	v_and_b32_e32 v68, 0x79e00, v33
	v_lshl_add_u64 v[34:35], v[72:73], 0, v[68:69]
	global_load_dwordx4 v[34:37], v[34:35], off offset:992
	v_lshl_add_u64 v[38:39], v[70:71], 0, v[68:69]
	global_load_dwordx4 v[38:41], v[38:39], off offset:992
	v_and_b32_e32 v42, 64, v211
	v_xor_b32_e32 v33, 32, v211
	v_add_u32_e32 v42, 64, v42
	v_cmp_lt_i32_e32 vcc, v33, v42
	s_nop 1
	v_cndmask_b32_e32 v33, v211, v33, vcc
	v_lshlrev_b32_e32 v33, 2, v33
	ds_bpermute_b32 v42, v33, v28
	ds_bpermute_b32 v43, v33, v29
	ds_bpermute_b32 v44, v33, v30
	ds_bpermute_b32 v45, v33, v31
	s_waitcnt vmcnt(0) lgkmcnt(0)
	v_pk_mul_f32 v[34:35], v[34:35], v[42:43]
	v_pk_mul_f32 v[36:37], v[36:37], v[44:45]
	v_xor_b32_e32 v43, 0x80000000, v34
	v_xor_b32_e32 v33, 0x80000000, v36
	v_xor_b32_e32 v42, 0x80000000, v37
	v_xor_b32_e32 v44, 0x80000000, v35
	v_cndmask_b32_e64 v35, v35, v44, s[8:9]
	v_cndmask_b32_e64 v34, v34, v43, s[8:9]
	v_cndmask_b32_e64 v37, v37, v42, s[8:9]
	v_cndmask_b32_e64 v36, v36, v33, s[8:9]
	v_pk_fma_f32 v[30:31], v[30:31], v[40:41], v[36:37]
	v_pk_fma_f32 v[28:29], v[28:29], v[38:39], v[34:35]
.LBB0_3727:
	v_ashrrev_i32_e32 v33, 31, v32
	v_lshlrev_b64 v[32:33], 7, v[32:33]
	v_cvt_pk_bf16_f32 v28, v28, v29
	v_cvt_pk_bf16_f32 v29, v30, v31
	v_lshl_add_u64 v[30:31], v[74:75], 0, v[32:33]
	v_cvt_pk_bf16_f32 v24, v24, v25
	v_cvt_pk_bf16_f32 v25, v26, v27
	global_store_dwordx2 v[30:31], v[24:25], off offset:32 sc1
	s_and_b64 vcc, exec, s[10:11]
	v_add_u32_e32 v24, 0x90, v76
	global_store_dwordx2 v[30:31], v[28:29], off sc1
	s_cbranch_vccnz .LBB0_3729
	v_lshlrev_b32_e32 v25, 9, v24
	v_and_b32_e32 v68, 0x7be00, v25
	v_lshl_add_u64 v[26:27], v[72:73], 0, v[68:69]
	global_load_dwordx4 v[26:29], v[26:27], off offset:992
	v_lshl_add_u64 v[30:31], v[70:71], 0, v[68:69]
	global_load_dwordx4 v[30:33], v[30:31], off offset:992
	v_and_b32_e32 v34, 64, v211
	v_xor_b32_e32 v25, 32, v211
	v_add_u32_e32 v34, 64, v34
	v_cmp_lt_i32_e32 vcc, v25, v34
	s_nop 1
	v_cndmask_b32_e32 v25, v211, v25, vcc
	v_lshlrev_b32_e32 v25, 2, v25
	ds_bpermute_b32 v34, v25, v20
	ds_bpermute_b32 v35, v25, v21
	ds_bpermute_b32 v36, v25, v22
	ds_bpermute_b32 v37, v25, v23
	s_waitcnt vmcnt(0) lgkmcnt(0)
	v_pk_mul_f32 v[26:27], v[26:27], v[34:35]
	v_pk_mul_f32 v[28:29], v[28:29], v[36:37]
	v_xor_b32_e32 v35, 0x80000000, v26
	v_xor_b32_e32 v25, 0x80000000, v28
	v_xor_b32_e32 v34, 0x80000000, v29
	v_xor_b32_e32 v36, 0x80000000, v27
	v_cndmask_b32_e64 v27, v27, v36, s[8:9]
	v_cndmask_b32_e64 v26, v26, v35, s[8:9]
	v_cndmask_b32_e64 v29, v29, v34, s[8:9]
	v_cndmask_b32_e64 v28, v28, v25, s[8:9]
	v_pk_fma_f32 v[22:23], v[22:23], v[32:33], v[28:29]
	v_pk_fma_f32 v[20:21], v[20:21], v[30:31], v[26:27]
.LBB0_3729:
	v_ashrrev_i32_e32 v25, 31, v24
	v_lshlrev_b64 v[24:25], 7, v[24:25]
	v_cvt_pk_bf16_f32 v20, v20, v21
	v_cvt_pk_bf16_f32 v21, v22, v23
	v_lshl_add_u64 v[22:23], v[74:75], 0, v[24:25]
	v_cvt_pk_bf16_f32 v16, v16, v17
	v_cvt_pk_bf16_f32 v17, v18, v19
	global_store_dwordx2 v[22:23], v[16:17], off offset:32 sc1
	s_and_b64 vcc, exec, s[10:11]
	v_add_u32_e32 v16, 0xa0, v76
	global_store_dwordx2 v[22:23], v[20:21], off sc1
	s_cbranch_vccnz .LBB0_3731
	v_lshlrev_b32_e32 v17, 9, v16
	v_and_b32_e32 v68, 0x7de00, v17
	v_lshl_add_u64 v[18:19], v[72:73], 0, v[68:69]
	global_load_dwordx4 v[18:21], v[18:19], off offset:992
	v_lshl_add_u64 v[22:23], v[70:71], 0, v[68:69]
	global_load_dwordx4 v[22:25], v[22:23], off offset:992
	v_and_b32_e32 v26, 64, v211
	v_xor_b32_e32 v17, 32, v211
	v_add_u32_e32 v26, 64, v26
	v_cmp_lt_i32_e32 vcc, v17, v26
	s_nop 1
	v_cndmask_b32_e32 v17, v211, v17, vcc
	v_lshlrev_b32_e32 v17, 2, v17
	ds_bpermute_b32 v26, v17, v12
	ds_bpermute_b32 v27, v17, v13
	ds_bpermute_b32 v28, v17, v14
	ds_bpermute_b32 v29, v17, v15
	s_waitcnt vmcnt(0) lgkmcnt(0)
	v_pk_mul_f32 v[18:19], v[18:19], v[26:27]
	v_pk_mul_f32 v[20:21], v[20:21], v[28:29]
	v_xor_b32_e32 v27, 0x80000000, v18
	v_xor_b32_e32 v17, 0x80000000, v20
	v_xor_b32_e32 v26, 0x80000000, v21
	v_xor_b32_e32 v28, 0x80000000, v19
	v_cndmask_b32_e64 v19, v19, v28, s[8:9]
	v_cndmask_b32_e64 v18, v18, v27, s[8:9]
	v_cndmask_b32_e64 v21, v21, v26, s[8:9]
	v_cndmask_b32_e64 v20, v20, v17, s[8:9]
	v_pk_fma_f32 v[14:15], v[14:15], v[24:25], v[20:21]
	v_pk_fma_f32 v[12:13], v[12:13], v[22:23], v[18:19]
.LBB0_3731:
	v_ashrrev_i32_e32 v17, 31, v16
	v_lshlrev_b64 v[16:17], 7, v[16:17]
	v_cvt_pk_bf16_f32 v12, v12, v13
	v_cvt_pk_bf16_f32 v13, v14, v15
	v_lshl_add_u64 v[14:15], v[74:75], 0, v[16:17]
	v_cvt_pk_bf16_f32 v8, v8, v9
	v_cvt_pk_bf16_f32 v9, v10, v11
	global_store_dwordx2 v[14:15], v[8:9], off offset:32 sc1
	v_add_u32_e32 v8, 0xb0, v76
	v_and_b32_e32 v9, 0x3ff, v8
	s_and_b64 vcc, exec, s[10:11]
	v_cmp_eq_u32_e64 s[10:11], s43, v9
	global_store_dwordx2 v[14:15], v[12:13], off sc1
	s_cbranch_vccnz .LBB0_3733
	v_lshl_add_u32 v9, v9, 7, v82
	v_cndmask_b32_e64 v9, v9, v83, s[10:11]
	v_lshlrev_b32_e32 v68, 2, v9
	v_lshl_add_u64 v[10:11], v[72:73], 0, v[68:69]
	global_load_dwordx4 v[10:13], v[10:11], off
	v_lshl_add_u64 v[14:15], v[70:71], 0, v[68:69]
	global_load_dwordx4 v[14:17], v[14:15], off
	v_and_b32_e32 v18, 64, v211
	v_xor_b32_e32 v9, 32, v211
	v_add_u32_e32 v18, 64, v18
	v_cmp_lt_i32_e32 vcc, v9, v18
	s_nop 1
	v_cndmask_b32_e32 v9, v211, v9, vcc
	v_lshlrev_b32_e32 v9, 2, v9
	ds_bpermute_b32 v18, v9, v4
	ds_bpermute_b32 v20, v9, v6
	ds_bpermute_b32 v21, v9, v7
	ds_bpermute_b32 v19, v9, v5
	s_waitcnt vmcnt(0) lgkmcnt(0)
	v_pk_mul_f32 v[12:13], v[12:13], v[20:21]
	v_pk_mul_f32 v[10:11], v[10:11], v[18:19]
	v_xor_b32_e32 v9, 0x80000000, v12
	v_xor_b32_e32 v18, 0x80000000, v13
	v_xor_b32_e32 v19, 0x80000000, v10
	v_xor_b32_e32 v20, 0x80000000, v11
	v_cndmask_b32_e64 v13, v13, v18, s[8:9]
	v_cndmask_b32_e64 v12, v12, v9, s[8:9]
	v_cndmask_b32_e64 v11, v11, v20, s[8:9]
	v_cndmask_b32_e64 v10, v10, v19, s[8:9]
	v_pk_fma_f32 v[6:7], v[6:7], v[16:17], v[12:13]
	v_pk_fma_f32 v[4:5], v[4:5], v[14:15], v[10:11]
.LBB0_3733:
	v_ashrrev_i32_e32 v9, 31, v8
	v_lshlrev_b64 v[8:9], 7, v[8:9]
	v_cndmask_b32_e64 v7, v7, 0, s[10:11]
	v_cndmask_b32_e64 v6, v6, 0, s[10:11]
	v_cndmask_b32_e64 v5, v5, 0, s[10:11]
	v_cndmask_b32_e64 v4, v4, 0, s[10:11]
	v_cndmask_b32_e64 v3, v3, 0, s[10:11]
	v_cndmask_b32_e64 v2, v2, 0, s[10:11]
	v_cndmask_b32_e64 v1, v1, 0, s[10:11]
	v_cndmask_b32_e64 v0, v0, 0, s[10:11]
	v_cvt_pk_bf16_f32 v4, v4, v5
	v_cvt_pk_bf16_f32 v5, v6, v7
	v_lshl_add_u64 v[6:7], v[74:75], 0, v[8:9]
	v_cvt_pk_bf16_f32 v0, v0, v1
	v_cvt_pk_bf16_f32 v1, v2, v3
	global_store_dwordx2 v[6:7], v[4:5], off sc1
	global_store_dwordx2 v[6:7], v[0:1], off offset:32 sc1
	s_andn2_b64 vcc, exec, s[70:71]
	s_mov_b64 s[10:11], -1
	s_cbranch_vccnz .LBB0_3706

.LBB0_3757:
	v_lshl_add_u32 v74, s28, 8, v70
	v_ashrrev_i32_e32 v75, 31, v74
	v_lshlrev_b64 v[76:77], 7, v[74:75]
	v_cvt_pk_bf16_f32 v60, v60, v61
	v_cvt_pk_bf16_f32 v61, v62, v63
	v_lshl_add_u64 v[62:63], v[68:69], 0, v[76:77]
	v_cvt_pk_bf16_f32 v56, v56, v57
	v_cvt_pk_bf16_f32 v57, v58, v59
	global_store_dwordx2 v[62:63], v[56:57], off offset:32 sc1
	v_or_b32_e32 v56, 16, v74
	v_ashrrev_i32_e32 v57, 31, v56
	v_lshlrev_b64 v[56:57], 7, v[56:57]
	v_cvt_pk_bf16_f32 v52, v52, v53
	v_cvt_pk_bf16_f32 v53, v54, v55
	v_lshl_add_u64 v[54:55], v[68:69], 0, v[56:57]
	v_cvt_pk_bf16_f32 v48, v48, v49
	v_cvt_pk_bf16_f32 v49, v50, v51
	global_store_dwordx2 v[54:55], v[48:49], off offset:32 sc1
	v_or_b32_e32 v48, 32, v74
	v_ashrrev_i32_e32 v49, 31, v48
	v_lshlrev_b64 v[48:49], 7, v[48:49]
	v_cvt_pk_bf16_f32 v36, v36, v37
	v_cvt_pk_bf16_f32 v37, v38, v39
	v_lshl_add_u64 v[38:39], v[68:69], 0, v[48:49]
	v_cvt_pk_bf16_f32 v32, v32, v33
	v_cvt_pk_bf16_f32 v33, v34, v35
	global_store_dwordx2 v[38:39], v[32:33], off offset:32 sc1
	v_or_b32_e32 v32, 48, v74
	v_bitop3_b32 v34, v74, s42, 48 bitop3:0xc8
	v_ashrrev_i32_e32 v33, 31, v32
	v_cmp_eq_u32_e32 vcc, s42, v34
	v_lshlrev_b64 v[32:33], 7, v[32:33]
	global_store_dwordx2 v[62:63], v[60:61], off sc1
	v_cndmask_b32_e64 v23, v23, 0, vcc
	v_cndmask_b32_e64 v22, v22, 0, vcc
	v_cndmask_b32_e64 v21, v21, 0, vcc
	v_cndmask_b32_e64 v20, v20, 0, vcc
	v_cndmask_b32_e64 v11, v11, 0, vcc
	v_cndmask_b32_e64 v10, v10, 0, vcc
	v_cndmask_b32_e64 v9, v9, 0, vcc
	v_cndmask_b32_e64 v8, v8, 0, vcc
	v_cvt_pk_bf16_f32 v20, v20, v21
	v_cvt_pk_bf16_f32 v21, v22, v23
	v_lshl_add_u64 v[22:23], v[68:69], 0, v[32:33]
	v_cvt_pk_bf16_f32 v8, v8, v9
	v_cvt_pk_bf16_f32 v9, v10, v11
	global_store_dwordx2 v[22:23], v[8:9], off offset:32 sc1
	v_add_u32_e32 v8, 0x80, v74
	v_ashrrev_i32_e32 v9, 31, v8
	v_lshlrev_b64 v[8:9], 7, v[8:9]
	v_cvt_pk_bf16_f32 v10, v44, v45
	v_cvt_pk_bf16_f32 v11, v46, v47
	v_lshl_add_u64 v[8:9], v[68:69], 0, v[8:9]
	global_store_dwordx2 v[8:9], v[10:11], off sc1
	v_cvt_pk_bf16_f32 v10, v40, v41
	v_cvt_pk_bf16_f32 v11, v42, v43
	global_store_dwordx2 v[8:9], v[10:11], off offset:32 sc1
	v_add_u32_e32 v8, 0x90, v74
	v_ashrrev_i32_e32 v9, 31, v8
	v_lshlrev_b64 v[8:9], 7, v[8:9]
	v_cvt_pk_bf16_f32 v10, v28, v29
	v_cvt_pk_bf16_f32 v11, v30, v31
	v_lshl_add_u64 v[8:9], v[68:69], 0, v[8:9]
	global_store_dwordx2 v[8:9], v[10:11], off sc1
	v_cvt_pk_bf16_f32 v10, v24, v25
	v_cvt_pk_bf16_f32 v11, v26, v27
	global_store_dwordx2 v[8:9], v[10:11], off offset:32 sc1
	v_add_u32_e32 v8, 0xa0, v74
	v_ashrrev_i32_e32 v9, 31, v8
	v_lshlrev_b64 v[8:9], 7, v[8:9]
	v_cvt_pk_bf16_f32 v10, v16, v17
	v_cvt_pk_bf16_f32 v11, v18, v19
	v_lshl_add_u64 v[8:9], v[68:69], 0, v[8:9]
	global_store_dwordx2 v[8:9], v[10:11], off sc1
	v_cvt_pk_bf16_f32 v10, v12, v13
	v_cvt_pk_bf16_f32 v11, v14, v15
	global_store_dwordx2 v[8:9], v[10:11], off offset:32 sc1
	v_add_u32_e32 v8, 0xb0, v74
	v_and_b32_e32 v10, 0x3ff, v8
	v_ashrrev_i32_e32 v9, 31, v8
	v_cmp_eq_u32_e32 vcc, s42, v10
	v_lshlrev_b64 v[8:9], 7, v[8:9]
	global_store_dwordx2 v[54:55], v[52:53], off sc1
	v_cndmask_b32_e64 v7, v7, 0, vcc
	v_cndmask_b32_e64 v6, v6, 0, vcc
	v_cndmask_b32_e64 v5, v5, 0, vcc
	v_cndmask_b32_e64 v4, v4, 0, vcc
	v_cndmask_b32_e64 v3, v3, 0, vcc
	v_cndmask_b32_e64 v2, v2, 0, vcc
	v_cndmask_b32_e64 v1, v1, 0, vcc
	v_cndmask_b32_e64 v0, v0, 0, vcc
	v_cvt_pk_bf16_f32 v4, v4, v5
	v_cvt_pk_bf16_f32 v5, v6, v7
	v_lshl_add_u64 v[6:7], v[68:69], 0, v[8:9]
	v_cvt_pk_bf16_f32 v0, v0, v1
	v_cvt_pk_bf16_f32 v1, v2, v3
	global_store_dwordx2 v[38:39], v[36:37], off sc1
	global_store_dwordx2 v[22:23], v[20:21], off sc1
	global_store_dwordx2 v[6:7], v[4:5], off sc1
	global_store_dwordx2 v[6:7], v[0:1], off offset:32 sc1
	s_andn2_b64 vcc, exec, s[54:55]
	s_mov_b64 s[28:29], -1
	s_cbranch_vccnz .LBB0_3746

.LBB0_3816:
	s_or_b64 exec, exec, s[10:11]
	global_load_dwordx4 v[38:41], v[134:135], off offset:128
	v_lshl_add_u32 v37, v131, 2, s96
	ds_read_b128 v[42:45], v37 offset:32896
	v_lshl_add_u32 v36, v176, 1, s31
	s_waitcnt vmcnt(0) lgkmcnt(0)
	v_div_scale_f32 v1, s[8:9], v42, v42, v38
	v_rcp_f32_e32 v34, v1
	s_nop 0
	v_fma_f32 v35, -v1, v34, 1.0
	v_fmac_f32_e32 v34, v35, v34
	v_div_scale_f32 v35, vcc, v38, v42, v38
	v_mul_f32_e32 v46, v35, v34
	v_fma_f32 v47, -v1, v46, v35
	v_fmac_f32_e32 v46, v47, v34
	v_fma_f32 v1, -v1, v46, v35
	v_div_fmas_f32 v1, v1, v34, v46
	v_add_u32_e32 v34, v36, v186
	ds_read_u16 v35, v34 offset:34816
	v_div_fixup_f32 v1, v1, v42, v38
	v_or_b32_e32 v38, 8, v131
	s_waitcnt lgkmcnt(0)
	v_lshlrev_b32_e32 v35, 16, v35
	v_fmac_f32_e32 v35, v2, v1
	v_cvt_pk_bf16_f32 v2, v35, s0
	ds_write_b16 v34, v2 offset:34816
	ds_read_u16 v2, v34 offset:34880
	s_waitcnt lgkmcnt(0)
	v_lshlrev_b32_e32 v2, 16, v2
	v_fmac_f32_e32 v2, v18, v1
	v_cvt_pk_bf16_f32 v1, v2, s0
	ds_write_b16 v34, v1 offset:34880
	v_div_scale_f32 v1, s[8:9], v43, v43, v39
	v_rcp_f32_e32 v2, v1
	s_nop 0
	v_fma_f32 v18, -v1, v2, 1.0
	v_fmac_f32_e32 v2, v18, v2
	v_div_scale_f32 v18, vcc, v39, v43, v39
	v_mul_f32_e32 v34, v18, v2
	v_fma_f32 v35, -v1, v34, v18
	v_fmac_f32_e32 v34, v35, v2
	v_fma_f32 v1, -v1, v34, v18
	v_div_fmas_f32 v1, v1, v2, v34
	v_div_fixup_f32 v2, v1, v43, v39
	v_lshl_add_u32 v1, v131, 7, v36
	ds_read_u16 v18, v1 offset:34944
	s_waitcnt lgkmcnt(0)
	v_lshlrev_b32_e32 v18, 16, v18
	v_fmac_f32_e32 v18, v3, v2
	v_cvt_pk_bf16_f32 v3, v18, s0
	ds_write_b16 v1, v3 offset:34944
	ds_read_u16 v3, v1 offset:35008
	s_waitcnt lgkmcnt(0)
	v_lshlrev_b32_e32 v3, 16, v3
	v_fmac_f32_e32 v3, v19, v2
	v_cvt_pk_bf16_f32 v2, v3, s0
	ds_write_b16 v1, v2 offset:35008
	v_div_scale_f32 v2, s[8:9], v44, v44, v40
	v_rcp_f32_e32 v3, v2
	s_nop 0
	v_fma_f32 v18, -v2, v3, 1.0
	v_fmac_f32_e32 v3, v18, v3
	v_div_scale_f32 v18, vcc, v40, v44, v40
	v_mul_f32_e32 v19, v18, v3
	v_fma_f32 v34, -v2, v19, v18
	v_fmac_f32_e32 v19, v34, v3
	v_fma_f32 v2, -v2, v19, v18
	v_div_fmas_f32 v2, v2, v3, v19
	ds_read_u16 v3, v1 offset:35072
	v_div_fixup_f32 v2, v2, v44, v40
	v_mov_b64_e32 v[34:35], s[76:77]
	s_waitcnt lgkmcnt(0)
	v_lshlrev_b32_e32 v3, 16, v3
	v_fmac_f32_e32 v3, v4, v2
	v_cvt_pk_bf16_f32 v3, v3, s0
	ds_write_b16 v1, v3 offset:35072
	ds_read_u16 v3, v1 offset:35136
	s_waitcnt lgkmcnt(0)
	v_lshlrev_b32_e32 v3, 16, v3
	v_fmac_f32_e32 v3, v20, v2
	v_cvt_pk_bf16_f32 v2, v3, s0
	ds_write_b16 v1, v2 offset:35136
	v_div_scale_f32 v2, s[8:9], v45, v45, v41
	v_rcp_f32_e32 v3, v2
	s_nop 0
	v_fma_f32 v4, -v2, v3, 1.0
	v_fmac_f32_e32 v3, v4, v3
	v_div_scale_f32 v4, vcc, v41, v45, v41
	v_mul_f32_e32 v18, v4, v3
	v_fma_f32 v19, -v2, v18, v4
	v_fmac_f32_e32 v18, v19, v3
	v_fma_f32 v2, -v2, v18, v4
	v_div_fmas_f32 v2, v2, v3, v18
	ds_read_u16 v3, v1 offset:35200
	v_div_fixup_f32 v2, v2, v45, v41
	s_waitcnt lgkmcnt(0)
	v_lshlrev_b32_e32 v3, 16, v3
	v_fmac_f32_e32 v3, v5, v2
	v_cvt_pk_bf16_f32 v3, v3, s0
	ds_write_b16 v1, v3 offset:35200
	ds_read_u16 v3, v1 offset:35264
	s_waitcnt lgkmcnt(0)
	v_lshlrev_b32_e32 v3, 16, v3
	v_fmac_f32_e32 v3, v21, v2
	v_cvt_pk_bf16_f32 v2, v3, s0
	ds_write_b16 v1, v2 offset:35264
	v_lshrrev_b32_e32 v2, 2, v38
	v_or_b32_e32 v2, s86, v2
	v_mad_u64_u32 v[2:3], s[8:9], v2, s90, v[34:35]
	global_load_dwordx4 v[2:5], v[2:3], off offset:128
	ds_read_b128 v[18:21], v37 offset:32928
	s_waitcnt vmcnt(0) lgkmcnt(0)
	v_div_scale_f32 v39, s[8:9], v18, v18, v2
	v_rcp_f32_e32 v40, v39
	s_nop 0
	v_fma_f32 v41, -v39, v40, 1.0
	v_fmac_f32_e32 v40, v41, v40
	v_div_scale_f32 v41, vcc, v2, v18, v2
	v_mul_f32_e32 v42, v41, v40
	v_fma_f32 v43, -v39, v42, v41
	v_fmac_f32_e32 v42, v43, v40
	v_fma_f32 v39, -v39, v42, v41
	v_div_fmas_f32 v39, v39, v40, v42
	v_div_fixup_f32 v2, v39, v18, v2
	v_lshl_add_u32 v18, v38, 7, v36
	ds_read_u16 v38, v18 offset:34816
	s_waitcnt lgkmcnt(0)
	v_lshlrev_b32_e32 v38, 16, v38
	v_fmac_f32_e32 v38, v6, v2
	v_cvt_pk_bf16_f32 v6, v38, s0
	ds_write_b16 v18, v6 offset:34816
	ds_read_u16 v6, v18 offset:34880
	s_waitcnt lgkmcnt(0)
	v_lshlrev_b32_e32 v6, 16, v6
	v_fmac_f32_e32 v6, v22, v2
	v_cvt_pk_bf16_f32 v2, v6, s0
	ds_write_b16 v18, v2 offset:34880
	v_div_scale_f32 v2, s[8:9], v19, v19, v3
	v_rcp_f32_e32 v6, v2
	s_nop 0
	v_fma_f32 v18, -v2, v6, 1.0
	v_fmac_f32_e32 v6, v18, v6
	v_div_scale_f32 v18, vcc, v3, v19, v3
	v_mul_f32_e32 v22, v18, v6
	v_fma_f32 v38, -v2, v22, v18
	v_fmac_f32_e32 v22, v38, v6
	v_fma_f32 v2, -v2, v22, v18
	v_div_fmas_f32 v2, v2, v6, v22
	v_div_fixup_f32 v2, v2, v19, v3
	ds_read_u16 v3, v1 offset:35968
	s_waitcnt lgkmcnt(0)
	v_lshlrev_b32_e32 v3, 16, v3
	v_fmac_f32_e32 v3, v7, v2
	v_cvt_pk_bf16_f32 v3, v3, s0
	ds_write_b16 v1, v3 offset:35968
	ds_read_u16 v3, v1 offset:36032
	s_waitcnt lgkmcnt(0)
	v_lshlrev_b32_e32 v3, 16, v3
	v_fmac_f32_e32 v3, v23, v2
	v_cvt_pk_bf16_f32 v2, v3, s0
	ds_write_b16 v1, v2 offset:36032
	v_div_scale_f32 v2, s[8:9], v20, v20, v4
	v_rcp_f32_e32 v3, v2
	s_nop 0
	v_fma_f32 v6, -v2, v3, 1.0
	v_fmac_f32_e32 v3, v6, v3
	v_div_scale_f32 v6, vcc, v4, v20, v4
	v_mul_f32_e32 v7, v6, v3
	v_fma_f32 v18, -v2, v7, v6
	v_fmac_f32_e32 v7, v18, v3
	v_fma_f32 v2, -v2, v7, v6
	v_div_fmas_f32 v2, v2, v3, v7
	ds_read_u16 v3, v1 offset:36096
	v_div_fixup_f32 v2, v2, v20, v4
	v_or_b32_e32 v18, 16, v131
	s_waitcnt lgkmcnt(0)
	v_lshlrev_b32_e32 v3, 16, v3
	v_fmac_f32_e32 v3, v8, v2
	v_cvt_pk_bf16_f32 v3, v3, s0
	ds_write_b16 v1, v3 offset:36096
	ds_read_u16 v3, v1 offset:36160
	s_waitcnt lgkmcnt(0)
	v_lshlrev_b32_e32 v3, 16, v3
	v_fmac_f32_e32 v3, v24, v2
	v_cvt_pk_bf16_f32 v2, v3, s0
	ds_write_b16 v1, v2 offset:36160
	v_div_scale_f32 v2, s[8:9], v21, v21, v5
	v_rcp_f32_e32 v3, v2
	s_nop 0
	v_fma_f32 v4, -v2, v3, 1.0
	v_fmac_f32_e32 v3, v4, v3
	v_div_scale_f32 v4, vcc, v5, v21, v5
	v_mul_f32_e32 v6, v4, v3
	v_fma_f32 v7, -v2, v6, v4
	v_fmac_f32_e32 v6, v7, v3
	v_fma_f32 v2, -v2, v6, v4
	v_div_fmas_f32 v2, v2, v3, v6
	ds_read_u16 v3, v1 offset:36224
	v_div_fixup_f32 v2, v2, v21, v5
	s_waitcnt lgkmcnt(0)
	v_lshlrev_b32_e32 v3, 16, v3
	v_fmac_f32_e32 v3, v9, v2
	v_cvt_pk_bf16_f32 v3, v3, s0
	ds_write_b16 v1, v3 offset:36224
	ds_read_u16 v3, v1 offset:36288
	ds_read_b128 v[6:9], v37 offset:32960
	s_waitcnt lgkmcnt(1)
	v_lshlrev_b32_e32 v3, 16, v3
	v_fmac_f32_e32 v3, v25, v2
	v_cvt_pk_bf16_f32 v2, v3, s0
	ds_write_b16 v1, v2 offset:36288
	v_lshrrev_b32_e32 v2, 2, v18
	v_or_b32_e32 v2, s86, v2
	v_mad_u64_u32 v[2:3], s[8:9], v2, s90, v[34:35]
	global_load_dwordx4 v[2:5], v[2:3], off offset:128
	s_waitcnt vmcnt(0) lgkmcnt(1)
	v_div_scale_f32 v19, s[8:9], v6, v6, v2
	v_rcp_f32_e32 v20, v19
	s_nop 0
	v_fma_f32 v21, -v19, v20, 1.0
	v_fmac_f32_e32 v20, v21, v20
	v_div_scale_f32 v21, vcc, v2, v6, v2
	v_mul_f32_e32 v22, v21, v20
	v_fma_f32 v23, -v19, v22, v21
	v_fmac_f32_e32 v22, v23, v20
	v_fma_f32 v19, -v19, v22, v21
	v_div_fmas_f32 v19, v19, v20, v22
	v_div_fixup_f32 v2, v19, v6, v2
	v_lshl_add_u32 v6, v18, 7, v36
	ds_read_u16 v18, v6 offset:34816
	s_waitcnt lgkmcnt(0)
	v_lshlrev_b32_e32 v18, 16, v18
	v_fmac_f32_e32 v18, v10, v2
	v_cvt_pk_bf16_f32 v10, v18, s0
	ds_write_b16 v6, v10 offset:34816
	ds_read_u16 v10, v6 offset:34880
	s_waitcnt lgkmcnt(0)
	v_lshlrev_b32_e32 v10, 16, v10
	v_fmac_f32_e32 v10, v26, v2
	v_cvt_pk_bf16_f32 v2, v10, s0
	ds_write_b16 v6, v2 offset:34880
	v_div_scale_f32 v2, s[8:9], v7, v7, v3
	v_rcp_f32_e32 v6, v2
	s_nop 0
	v_fma_f32 v10, -v2, v6, 1.0
	v_fmac_f32_e32 v6, v10, v6
	v_div_scale_f32 v10, vcc, v3, v7, v3
	v_mul_f32_e32 v18, v10, v6
	v_fma_f32 v19, -v2, v18, v10
	v_fmac_f32_e32 v18, v19, v6
	v_fma_f32 v2, -v2, v18, v10
	v_div_fmas_f32 v2, v2, v6, v18
	v_div_fixup_f32 v2, v2, v7, v3
	ds_read_u16 v3, v1 offset:36992
	s_waitcnt lgkmcnt(0)
	v_lshlrev_b32_e32 v3, 16, v3
	v_fmac_f32_e32 v3, v11, v2
	v_cvt_pk_bf16_f32 v3, v3, s0
	ds_write_b16 v1, v3 offset:36992
	ds_read_u16 v3, v1 offset:37056
	s_waitcnt lgkmcnt(0)
	v_lshlrev_b32_e32 v3, 16, v3
	v_fmac_f32_e32 v3, v27, v2
	v_cvt_pk_bf16_f32 v2, v3, s0
	ds_write_b16 v1, v2 offset:37056
	v_div_scale_f32 v2, s[8:9], v8, v8, v4
	v_rcp_f32_e32 v3, v2
	s_nop 0
	v_fma_f32 v6, -v2, v3, 1.0
	v_fmac_f32_e32 v3, v6, v3
	v_div_scale_f32 v6, vcc, v4, v8, v4
	v_mul_f32_e32 v7, v6, v3
	v_fma_f32 v10, -v2, v7, v6
	v_fmac_f32_e32 v7, v10, v3
	v_fma_f32 v2, -v2, v7, v6
	v_div_fmas_f32 v2, v2, v3, v7
	ds_read_u16 v3, v1 offset:37120
	v_div_fixup_f32 v2, v2, v8, v4
	v_or_b32_e32 v10, 24, v131
	s_waitcnt lgkmcnt(0)
	v_lshlrev_b32_e32 v3, 16, v3
	v_fmac_f32_e32 v3, v12, v2
	v_cvt_pk_bf16_f32 v3, v3, s0
	ds_write_b16 v1, v3 offset:37120
	ds_read_u16 v3, v1 offset:37184
	s_waitcnt lgkmcnt(0)
	v_lshlrev_b32_e32 v3, 16, v3
	v_fmac_f32_e32 v3, v28, v2
	v_cvt_pk_bf16_f32 v2, v3, s0
	ds_write_b16 v1, v2 offset:37184
	v_div_scale_f32 v2, s[8:9], v9, v9, v5
	v_rcp_f32_e32 v3, v2
	s_nop 0
	v_fma_f32 v4, -v2, v3, 1.0
	v_fmac_f32_e32 v3, v4, v3
	v_div_scale_f32 v4, vcc, v5, v9, v5
	v_mul_f32_e32 v6, v4, v3
	v_fma_f32 v7, -v2, v6, v4
	v_fmac_f32_e32 v6, v7, v3
	v_fma_f32 v2, -v2, v6, v4
	v_div_fmas_f32 v2, v2, v3, v6
	ds_read_u16 v3, v1 offset:37248
	v_div_fixup_f32 v2, v2, v9, v5
	ds_read_b128 v[6:9], v37 offset:32992
	s_waitcnt lgkmcnt(1)
	v_lshlrev_b32_e32 v3, 16, v3
	v_fmac_f32_e32 v3, v13, v2
	v_cvt_pk_bf16_f32 v3, v3, s0
	ds_write_b16 v1, v3 offset:37248
	ds_read_u16 v3, v1 offset:37312
	s_waitcnt lgkmcnt(0)
	v_lshlrev_b32_e32 v3, 16, v3
	v_fmac_f32_e32 v3, v29, v2
	v_cvt_pk_bf16_f32 v2, v3, s0
	ds_write_b16 v1, v2 offset:37312
	v_lshrrev_b32_e32 v2, 2, v10
	v_or_b32_e32 v2, s86, v2
	v_mad_u64_u32 v[2:3], s[8:9], v2, s90, v[34:35]
	global_load_dwordx4 v[2:5], v[2:3], off offset:128
	s_waitcnt vmcnt(0)
	v_div_scale_f32 v11, s[8:9], v6, v6, v2
	v_rcp_f32_e32 v12, v11
	s_nop 0
	v_fma_f32 v13, -v11, v12, 1.0
	v_fmac_f32_e32 v12, v13, v12
	v_div_scale_f32 v13, vcc, v2, v6, v2
	v_mul_f32_e32 v18, v13, v12
	v_fma_f32 v19, -v11, v18, v13
	v_fmac_f32_e32 v18, v19, v12
	v_fma_f32 v11, -v11, v18, v13
	v_div_fmas_f32 v11, v11, v12, v18
	v_div_fixup_f32 v2, v11, v6, v2
	v_lshl_add_u32 v6, v10, 7, v36
	ds_read_u16 v10, v6 offset:34816
	s_waitcnt lgkmcnt(0)
	v_lshlrev_b32_e32 v10, 16, v10
	v_fmac_f32_e32 v10, v14, v2
	v_cvt_pk_bf16_f32 v10, v10, s0
	ds_write_b16 v6, v10 offset:34816
	ds_read_u16 v10, v6 offset:34880
	s_waitcnt lgkmcnt(0)
	v_lshlrev_b32_e32 v10, 16, v10
	v_fmac_f32_e32 v10, v30, v2
	v_cvt_pk_bf16_f32 v2, v10, s0
	ds_write_b16 v6, v2 offset:34880
	v_div_scale_f32 v2, s[8:9], v7, v7, v3
	v_rcp_f32_e32 v6, v2
	s_nop 0
	v_fma_f32 v10, -v2, v6, 1.0
	v_fmac_f32_e32 v6, v10, v6
	v_div_scale_f32 v10, vcc, v3, v7, v3
	v_mul_f32_e32 v11, v10, v6
	v_fma_f32 v12, -v2, v11, v10
	v_fmac_f32_e32 v11, v12, v6
	v_fma_f32 v2, -v2, v11, v10
	v_div_fmas_f32 v2, v2, v6, v11
	v_div_fixup_f32 v2, v2, v7, v3
	ds_read_u16 v3, v1 offset:38016
	s_waitcnt lgkmcnt(0)
	v_lshlrev_b32_e32 v3, 16, v3
	v_fmac_f32_e32 v3, v15, v2
	v_cvt_pk_bf16_f32 v3, v3, s0
	ds_write_b16 v1, v3 offset:38016
	ds_read_u16 v3, v1 offset:38080
	s_waitcnt lgkmcnt(0)
	v_lshlrev_b32_e32 v3, 16, v3
	v_fmac_f32_e32 v3, v31, v2
	v_cvt_pk_bf16_f32 v2, v3, s0
	ds_write_b16 v1, v2 offset:38080
	v_div_scale_f32 v2, s[8:9], v8, v8, v4
	v_rcp_f32_e32 v3, v2
	s_nop 0
	v_fma_f32 v6, -v2, v3, 1.0
	v_fmac_f32_e32 v3, v6, v3
	v_div_scale_f32 v6, vcc, v4, v8, v4
	v_mul_f32_e32 v7, v6, v3
	v_fma_f32 v10, -v2, v7, v6
	v_fmac_f32_e32 v7, v10, v3
	v_fma_f32 v2, -v2, v7, v6
	v_div_fmas_f32 v2, v2, v3, v7
	ds_read_u16 v3, v1 offset:38144
	v_div_fixup_f32 v2, v2, v8, v4
	s_waitcnt lgkmcnt(0)
	v_lshlrev_b32_e32 v3, 16, v3
	v_fmac_f32_e32 v3, v16, v2
	v_cvt_pk_bf16_f32 v3, v3, s0
	ds_write_b16 v1, v3 offset:38144
	ds_read_u16 v3, v1 offset:38208
	s_waitcnt lgkmcnt(0)
	v_lshlrev_b32_e32 v3, 16, v3
	v_fmac_f32_e32 v3, v32, v2
	v_cvt_pk_bf16_f32 v2, v3, s0
	ds_write_b16 v1, v2 offset:38208
	v_div_scale_f32 v2, s[8:9], v9, v9, v5
	v_rcp_f32_e32 v3, v2
	v_readlane_b32 s8, v254, 14
	v_readlane_b32 s9, v254, 15
	v_fma_f32 v4, -v2, v3, 1.0
	v_fmac_f32_e32 v3, v4, v3
	v_div_scale_f32 v4, vcc, v5, v9, v5
	v_mul_f32_e32 v6, v4, v3
	v_fma_f32 v7, -v2, v6, v4
	v_fmac_f32_e32 v6, v7, v3
	v_fma_f32 v2, -v2, v6, v4
	v_div_fmas_f32 v2, v2, v3, v6
	ds_read_u16 v3, v1 offset:38272
	v_div_fixup_f32 v2, v2, v9, v5
	v_mov_b32_e32 v5, v0
	v_lshlrev_b64 v[8:9], 11, v[126:127]
	s_waitcnt lgkmcnt(0)
	v_lshlrev_b32_e32 v3, 16, v3
	v_fmac_f32_e32 v3, v17, v2
	v_cvt_pk_bf16_f32 v3, v3, s0
	ds_write_b16 v1, v3 offset:38272
	ds_read_u16 v3, v1 offset:38336
	s_waitcnt lgkmcnt(0)
	v_lshlrev_b32_e32 v3, 16, v3
	v_fmac_f32_e32 v3, v33, v2
	v_cvt_pk_bf16_f32 v2, v3, s0
	ds_write_b16 v1, v2 offset:38336
	v_lshrrev_b32_e32 v1, 3, v175
	v_lshlrev_b32_e32 v2, 1, v129
	v_and_or_b32 v3, v1, 3, s2
	v_and_b32_e32 v2, 0x70, v2
	v_lshlrev_b32_e32 v4, 7, v3
	v_add_u32_e32 v10, s31, v2
	v_lshl_add_u64 v[4:5], s[8:9], 0, v[4:5]
	v_mov_b32_e32 v3, v0
	v_lshl_add_u64 v[2:3], v[4:5], 0, v[2:3]
	v_lshl_add_u32 v4, v1, 7, v10
	ds_read_b128 v[4:7], v4 offset:34816
	v_lshl_add_u64 v[8:9], v[2:3], 0, v[8:9]
	s_mov_b64 s[8:9], 0
	s_waitcnt lgkmcnt(0)
	global_store_dwordx4 v[8:9], v[4:7], off sc1
	v_or_b32_e32 v8, 8, v1
	s_nop 0
	v_lshl_add_u32 v4, v8, 7, v10
	ds_read_b128 v[4:7], v4 offset:34816
	v_lshrrev_b32_e32 v8, 2, v8
	v_or_b32_e32 v8, s86, v8
	v_mov_b32_e32 v9, v0
	v_lshlrev_b64 v[8:9], 11, v[8:9]
	v_lshl_add_u64 v[8:9], v[2:3], 0, v[8:9]
	s_waitcnt lgkmcnt(0)
	global_store_dwordx4 v[8:9], v[4:7], off sc1
	v_or_b32_e32 v8, 16, v1
	v_mov_b32_e32 v9, v0
	v_lshl_add_u32 v4, v8, 7, v10
	ds_read_b128 v[4:7], v4 offset:34816
	v_lshrrev_b32_e32 v8, 2, v8
	v_or_b32_e32 v8, s86, v8
	v_lshlrev_b64 v[8:9], 11, v[8:9]
	v_lshl_add_u64 v[8:9], v[2:3], 0, v[8:9]
	v_or_b32_e32 v1, 24, v1
	s_waitcnt lgkmcnt(0)
	global_store_dwordx4 v[8:9], v[4:7], off sc1
	v_mov_b32_e32 v9, v0
	s_nop 0
	v_lshl_add_u32 v4, v1, 7, v10
	ds_read_b128 v[4:7], v4 offset:34816
	v_lshrrev_b32_e32 v1, 2, v1
	v_or_b32_e32 v8, s86, v1
	v_lshlrev_b64 v[8:9], 11, v[8:9]
	v_lshl_add_u64 v[2:3], v[2:3], 0, v[8:9]
	s_waitcnt lgkmcnt(0)
	global_store_dwordx4 v[2:3], v[4:7], off sc1

.LBB0_4250:
	v_lshl_or_b32 v140, s25, 8, v150
	v_ashrrev_i32_e32 v141, 31, v140
	v_lshl_add_u32 v144, s24, 8, v148
	v_lshlrev_b64 v[140:141], 2, v[140:141]
	v_ashrrev_i32_e32 v145, 31, v144
	v_lshl_add_u64 v[142:143], s[36:37], 0, v[140:141]
	v_lshlrev_b64 v[146:147], 12, v[144:145]
	v_lshl_add_u64 v[166:167], v[142:143], 0, v[146:147]
	global_load_dwordx4 v[156:159], v[166:167], off
	global_load_dwordx4 v[162:165], v[166:167], off offset:64
	global_load_dwordx4 v[170:173], v[166:167], off offset:512
	global_load_dwordx4 v[174:177], v[166:167], off offset:576
	v_or_b32_e32 v166, 16, v144
	v_ashrrev_i32_e32 v167, 31, v166
	v_lshlrev_b64 v[166:167], 12, v[166:167]
	v_or_b32_e32 v194, 32, v144
	v_lshl_add_u64 v[190:191], v[142:143], 0, v[166:167]
	v_ashrrev_i32_e32 v195, 31, v194
	v_or_b32_e32 v212, 48, v144
	global_load_dwordx4 v[178:181], v[190:191], off
	global_load_dwordx4 v[182:185], v[190:191], off offset:64
	global_load_dwordx4 v[186:189], v[190:191], off offset:512
	s_nop 0
	global_load_dwordx4 v[190:193], v[190:191], off offset:576
	v_lshlrev_b64 v[228:229], 12, v[194:195]
	v_ashrrev_i32_e32 v213, 31, v212
	v_lshl_add_u64 v[206:207], v[142:143], 0, v[228:229]
	v_lshlrev_b64 v[230:231], 12, v[212:213]
	global_load_dwordx4 v[194:197], v[206:207], off
	global_load_dwordx4 v[198:201], v[206:207], off offset:64
	global_load_dwordx4 v[202:205], v[206:207], off offset:512
	s_nop 0
	global_load_dwordx4 v[206:209], v[206:207], off offset:576
	v_lshl_add_u64 v[224:225], v[142:143], 0, v[230:231]
	global_load_dwordx4 v[212:215], v[224:225], off
	global_load_dwordx4 v[216:219], v[224:225], off offset:64
	global_load_dwordx4 v[220:223], v[224:225], off offset:512
	s_nop 0
	global_load_dwordx4 v[224:227], v[224:225], off offset:576
	v_lshl_add_u64 v[146:147], s[36:37], 0, v[146:147]
	v_lshl_add_u64 v[146:147], v[146:147], 0, v[140:141]
	s_mov_b64 s[24:25], -1
	s_andn2_b64 vcc, exec, s[8:9]
	s_waitcnt vmcnt(0)
	v_pk_add_f32 v[126:127], v[126:127], v[158:159]
	v_pk_add_f32 v[124:125], v[124:125], v[156:157]
	v_pk_add_f32 v[110:111], v[110:111], v[172:173]
	v_pk_add_f32 v[108:109], v[108:109], v[170:171]
	global_store_dwordx4 v[146:147], v[108:111], off offset:512 sc1
	v_pk_add_f32 v[102:103], v[102:103], v[176:177]
	v_pk_add_f32 v[100:101], v[100:101], v[174:175]
	v_lshl_add_u64 v[108:109], s[36:37], 0, v[166:167]
	v_lshl_add_u64 v[108:109], v[108:109], 0, v[140:141]
	v_pk_add_f32 v[122:123], v[122:123], v[164:165]
	v_pk_add_f32 v[94:95], v[94:95], v[188:189]
	v_pk_add_f32 v[92:93], v[92:93], v[186:187]
	global_store_dwordx4 v[108:109], v[92:95], off offset:512 sc1
	v_pk_add_f32 v[86:87], v[86:87], v[192:193]
	v_pk_add_f32 v[84:85], v[84:85], v[190:191]
	v_lshl_add_u64 v[92:93], s[36:37], 0, v[228:229]
	v_lshl_add_u64 v[92:93], v[92:93], 0, v[140:141]
	v_pk_add_f32 v[78:79], v[78:79], v[204:205]
	v_pk_add_f32 v[76:77], v[76:77], v[202:203]
	global_store_dwordx4 v[92:93], v[76:79], off offset:512 sc1
	v_pk_add_f32 v[66:67], v[66:67], v[226:227]
	v_pk_add_f32 v[64:65], v[64:65], v[224:225]
	v_lshl_add_u64 v[76:77], s[36:37], 0, v[230:231]
	v_lshl_add_u64 v[76:77], v[76:77], 0, v[140:141]
	v_pk_add_f32 v[74:75], v[74:75], v[208:209]
	v_pk_add_f32 v[72:73], v[72:73], v[206:207]
	global_store_dwordx4 v[76:77], v[64:67], off offset:576 sc1
	v_pk_add_f32 v[120:121], v[120:121], v[162:163]
	global_store_dwordx4 v[146:147], v[100:103], off offset:576 sc1
	v_add_u32_e32 v64, 0x80, v144
	global_store_dwordx4 v[108:109], v[84:87], off offset:576 sc1
	v_pk_add_f32 v[102:103], v[118:119], v[180:181]
	v_pk_add_f32 v[100:101], v[116:117], v[178:179]
	v_pk_add_f32 v[86:87], v[106:107], v[196:197]
	v_pk_add_f32 v[84:85], v[104:105], v[194:195]
	global_store_dwordx4 v[92:93], v[72:75], off offset:576 sc1
	v_ashrrev_i32_e32 v65, 31, v64
	global_store_dwordx4 v[146:147], v[124:127], off sc1
	v_pk_add_f32 v[74:75], v[90:91], v[214:215]
	v_pk_add_f32 v[72:73], v[88:89], v[212:213]
	global_store_dwordx4 v[146:147], v[120:123], off offset:64 sc1
	global_store_dwordx4 v[108:109], v[100:103], off sc1
	global_store_dwordx4 v[92:93], v[84:87], off sc1
	global_store_dwordx4 v[76:77], v[72:75], off sc1
	v_pk_add_f32 v[102:103], v[114:115], v[184:185]
	v_pk_add_f32 v[100:101], v[112:113], v[182:183]
	v_pk_add_f32 v[86:87], v[98:99], v[200:201]
	v_pk_add_f32 v[84:85], v[96:97], v[198:199]
	v_pk_add_f32 v[74:75], v[82:83], v[218:219]
	v_pk_add_f32 v[72:73], v[80:81], v[216:217]
	v_pk_add_f32 v[70:71], v[70:71], v[222:223]
	v_pk_add_f32 v[68:69], v[68:69], v[220:221]
	v_lshlrev_b64 v[146:147], 12, v[64:65]
	global_store_dwordx4 v[108:109], v[100:103], off offset:64 sc1
	global_store_dwordx4 v[92:93], v[84:87], off offset:64 sc1
	global_store_dwordx4 v[76:77], v[72:75], off offset:64 sc1
	global_store_dwordx4 v[76:77], v[68:71], off offset:512 sc1
	v_lshl_add_u64 v[64:65], v[142:143], 0, v[146:147]
	global_load_dwordx4 v[108:111], v[64:65], off
	global_load_dwordx4 v[104:107], v[64:65], off offset:64
	global_load_dwordx4 v[96:99], v[64:65], off offset:512
	global_load_dwordx4 v[84:87], v[64:65], off offset:576
	v_add_u32_e32 v64, 0x90, v144
	v_ashrrev_i32_e32 v65, 31, v64
	v_lshlrev_b64 v[126:127], 12, v[64:65]
	v_lshl_add_u64 v[64:65], v[142:143], 0, v[126:127]
	global_load_dwordx4 v[100:103], v[64:65], off
	global_load_dwordx4 v[88:91], v[64:65], off offset:64
	global_load_dwordx4 v[80:83], v[64:65], off offset:512
	global_load_dwordx4 v[72:75], v[64:65], off offset:576
	v_add_u32_e32 v64, 0xa0, v144
	v_ashrrev_i32_e32 v65, 31, v64
	v_lshlrev_b64 v[124:125], 12, v[64:65]
	v_add_u32_e32 v112, 0xb0, v144
	v_lshl_add_u64 v[64:65], v[142:143], 0, v[124:125]
	v_ashrrev_i32_e32 v113, 31, v112
	global_load_dwordx4 v[92:95], v[64:65], off
	global_load_dwordx4 v[76:79], v[64:65], off offset:64
	global_load_dwordx4 v[68:71], v[64:65], off offset:512
	s_nop 0
	global_load_dwordx4 v[64:67], v[64:65], off offset:576
	v_lshlrev_b64 v[144:145], 12, v[112:113]
	v_lshl_add_u64 v[116:117], v[142:143], 0, v[144:145]
	global_load_dwordx4 v[112:115], v[116:117], off
	global_load_dwordx4 v[156:159], v[116:117], off offset:64
	global_load_dwordx4 v[120:123], v[116:117], off offset:512
	s_nop 0
	global_load_dwordx4 v[116:119], v[116:117], off offset:576
	s_waitcnt vmcnt(15)
	v_pk_add_f32 v[60:61], v[60:61], v[108:109]
	v_lshl_add_u64 v[108:109], s[36:37], 0, v[146:147]
	v_lshl_add_u64 v[108:109], v[108:109], 0, v[140:141]
	s_waitcnt vmcnt(13)
	v_pk_add_f32 v[50:51], v[50:51], v[98:99]
	v_pk_add_f32 v[48:49], v[48:49], v[96:97]
	global_store_dwordx4 v[108:109], v[48:51], off offset:512 sc1
	s_waitcnt vmcnt(13)
	v_pk_add_f32 v[42:43], v[42:43], v[86:87]
	s_waitcnt vmcnt(10)
	v_pk_add_f32 v[34:35], v[34:35], v[82:83]
	v_lshl_add_u64 v[48:49], s[36:37], 0, v[126:127]
	v_lshl_add_u64 v[48:49], v[48:49], 0, v[140:141]
	v_pk_add_f32 v[32:33], v[32:33], v[80:81]
	global_store_dwordx4 v[48:49], v[32:35], off offset:512 sc1
	v_pk_add_f32 v[40:41], v[40:41], v[84:85]
	s_waitcnt vmcnt(10)
	v_pk_add_f32 v[26:27], v[26:27], v[74:75]
	v_lshl_add_u64 v[32:33], s[36:37], 0, v[124:125]
	v_lshl_add_u64 v[32:33], v[32:33], 0, v[140:141]
	s_waitcnt vmcnt(7)
	v_pk_add_f32 v[18:19], v[18:19], v[70:71]
	v_pk_add_f32 v[16:17], v[16:17], v[68:69]
	v_pk_add_f32 v[24:25], v[24:25], v[72:73]
	global_store_dwordx4 v[32:33], v[16:19], off offset:512 sc1
	s_waitcnt vmcnt(7)
	v_pk_add_f32 v[10:11], v[10:11], v[66:67]
	v_pk_add_f32 v[8:9], v[8:9], v[64:65]
	v_lshl_add_u64 v[16:17], s[36:37], 0, v[144:145]
	global_store_dwordx4 v[108:109], v[40:43], off offset:576 sc1
	global_store_dwordx4 v[48:49], v[24:27], off offset:576 sc1
	global_store_dwordx4 v[32:33], v[8:11], off offset:576 sc1
	v_pk_add_f32 v[42:43], v[54:55], v[102:103]
	v_pk_add_f32 v[40:41], v[52:53], v[100:101]
	v_pk_add_f32 v[26:27], v[38:39], v[94:95]
	v_pk_add_f32 v[24:25], v[36:37], v[92:93]
	s_waitcnt vmcnt(9)
	v_pk_add_f32 v[10:11], v[22:23], v[114:115]
	v_pk_add_f32 v[8:9], v[20:21], v[112:113]
	v_lshl_add_u64 v[16:17], v[16:17], 0, v[140:141]
	v_pk_add_f32 v[62:63], v[62:63], v[110:111]
	v_pk_add_f32 v[58:59], v[58:59], v[106:107]
	v_pk_add_f32 v[56:57], v[56:57], v[104:105]
	global_store_dwordx4 v[48:49], v[40:43], off sc1
	global_store_dwordx4 v[32:33], v[24:27], off sc1
	global_store_dwordx4 v[16:17], v[8:11], off sc1
	v_pk_add_f32 v[42:43], v[46:47], v[90:91]
	v_pk_add_f32 v[40:41], v[44:45], v[88:89]
	v_pk_add_f32 v[26:27], v[30:31], v[78:79]
	v_pk_add_f32 v[24:25], v[28:29], v[76:77]
	s_waitcnt vmcnt(11)
	v_pk_add_f32 v[10:11], v[14:15], v[158:159]
	v_pk_add_f32 v[8:9], v[12:13], v[156:157]
	s_waitcnt vmcnt(10)
	v_pk_add_f32 v[6:7], v[6:7], v[122:123]
	v_pk_add_f32 v[4:5], v[4:5], v[120:121]
	s_waitcnt vmcnt(9)
	v_pk_add_f32 v[2:3], v[2:3], v[118:119]
	v_pk_add_f32 v[0:1], v[0:1], v[116:117]
	global_store_dwordx4 v[108:109], v[60:63], off sc1
	global_store_dwordx4 v[108:109], v[56:59], off offset:64 sc1
	global_store_dwordx4 v[48:49], v[40:43], off offset:64 sc1
	global_store_dwordx4 v[32:33], v[24:27], off offset:64 sc1
	global_store_dwordx4 v[16:17], v[8:11], off offset:64 sc1
	global_store_dwordx4 v[16:17], v[4:7], off offset:512 sc1
	global_store_dwordx4 v[16:17], v[0:3], off offset:576 sc1
	s_cbranch_vccnz .LBB0_4239
	s_andn2_b64 vcc, exec, s[10:11]
	s_cbranch_vccnz .LBB0_4238
	s_barrier
	s_branch .LBB0_4238

.LBB0_4383:
	v_lshl_add_u32 v154, s50, 8, v146
	v_lshl_or_b32 v144, s51, 8, v147
	v_ashrrev_i32_e32 v155, 31, v154
	v_ashrrev_i32_e32 v145, 31, v144
	v_lshlrev_b64 v[156:157], 13, v[154:155]
	v_max_f32_e32 v120, v120, v120
	v_max_f32_e32 v121, v121, v121
	v_lshl_add_u64 v[156:157], s[38:39], 0, v[156:157]
	v_lshlrev_b64 v[158:159], 1, v[144:145]
	v_max_f32_e32 v120, 0, v120
	v_max_f32_e32 v121, 0, v121
	v_lshl_add_u64 v[144:145], v[156:157], 0, v[158:159]
	v_pk_mul_f32 v[156:157], v[120:121], v[120:121]
	v_max_f32_e32 v121, v122, v122
	v_max_f32_e32 v124, v124, v124
	v_max_f32_e32 v125, v125, v125
	v_max_f32_e32 v120, v126, v126
	v_max_f32_e32 v122, 0, v121
	v_max_f32_e32 v121, v127, v127
	v_max_f32_e32 v123, v123, v123
	v_max_f32_e32 v124, 0, v124
	v_max_f32_e32 v125, 0, v125
	v_max_f32_e32 v120, 0, v120
	v_max_f32_e32 v121, 0, v121
	v_max_f32_e32 v123, 0, v123
	v_pk_mul_f32 v[124:125], v[124:125], v[124:125]
	v_pk_mul_f32 v[126:127], v[120:121], v[120:121]
	v_pk_mul_f32 v[162:163], v[122:123], v[122:123]
	v_max_f32_e32 v112, v112, v112
	v_max_f32_e32 v113, v113, v113
	v_cvt_pk_bf16_f32 v120, v124, v125
	v_cvt_pk_bf16_f32 v121, v126, v127
	v_cvt_pk_bf16_f32 v122, v156, v157
	v_cvt_pk_bf16_f32 v123, v162, v163
	v_max_f32_e32 v112, 0, v112
	v_max_f32_e32 v113, 0, v113
	global_store_dwordx4 v[144:145], v[120:123], off sc1
	v_max_f32_e32 v116, v116, v116
	v_max_f32_e32 v117, v117, v117
	v_pk_mul_f32 v[120:121], v[112:113], v[112:113]
	v_max_f32_e32 v113, v114, v114
	v_max_f32_e32 v112, v118, v118
	v_max_f32_e32 v114, 0, v113
	v_max_f32_e32 v113, v119, v119
	v_max_f32_e32 v115, v115, v115
	v_max_f32_e32 v116, 0, v116
	v_max_f32_e32 v117, 0, v117
	v_max_f32_e32 v112, 0, v112
	v_max_f32_e32 v113, 0, v113
	v_max_f32_e32 v115, 0, v115
	v_pk_mul_f32 v[116:117], v[116:117], v[116:117]
	v_pk_mul_f32 v[118:119], v[112:113], v[112:113]
	v_pk_mul_f32 v[122:123], v[114:115], v[114:115]
	v_max_f32_e32 v104, v104, v104
	v_max_f32_e32 v105, v105, v105
	v_cvt_pk_bf16_f32 v112, v116, v117
	v_cvt_pk_bf16_f32 v113, v118, v119
	v_cvt_pk_bf16_f32 v114, v120, v121
	v_cvt_pk_bf16_f32 v115, v122, v123
	v_max_f32_e32 v104, 0, v104
	v_max_f32_e32 v105, 0, v105
	global_store_dwordx4 v[144:145], v[112:115], off offset:256 sc1
	v_max_f32_e32 v108, v108, v108
	v_max_f32_e32 v109, v109, v109
	v_or_b32_e32 v112, 16, v154
	v_pk_mul_f32 v[114:115], v[104:105], v[104:105]
	v_max_f32_e32 v105, v106, v106
	v_ashrrev_i32_e32 v113, 31, v112
	v_max_f32_e32 v104, v110, v110
	v_max_f32_e32 v106, 0, v105
	v_max_f32_e32 v105, v111, v111
	v_max_f32_e32 v107, v107, v107
	v_lshlrev_b64 v[112:113], 13, v[112:113]
	v_max_f32_e32 v108, 0, v108
	v_max_f32_e32 v109, 0, v109
	v_max_f32_e32 v104, 0, v104
	v_max_f32_e32 v105, 0, v105
	v_max_f32_e32 v107, 0, v107
	v_lshl_add_u64 v[112:113], s[38:39], 0, v[112:113]
	v_pk_mul_f32 v[108:109], v[108:109], v[108:109]
	v_pk_mul_f32 v[110:111], v[104:105], v[104:105]
	v_pk_mul_f32 v[116:117], v[106:107], v[106:107]
	v_max_f32_e32 v96, v96, v96
	v_max_f32_e32 v97, v97, v97
	v_lshl_add_u64 v[112:113], v[112:113], 0, v[158:159]
	v_cvt_pk_bf16_f32 v104, v108, v109
	v_cvt_pk_bf16_f32 v105, v110, v111
	v_cvt_pk_bf16_f32 v106, v114, v115
	v_cvt_pk_bf16_f32 v107, v116, v117
	v_max_f32_e32 v96, 0, v96
	v_max_f32_e32 v97, 0, v97
	global_store_dwordx4 v[112:113], v[104:107], off sc1
	v_max_f32_e32 v100, v100, v100
	v_max_f32_e32 v101, v101, v101
	v_pk_mul_f32 v[104:105], v[96:97], v[96:97]
	v_max_f32_e32 v97, v98, v98
	v_max_f32_e32 v96, v102, v102
	v_max_f32_e32 v98, 0, v97
	v_max_f32_e32 v97, v103, v103
	v_max_f32_e32 v99, v99, v99
	v_max_f32_e32 v100, 0, v100
	v_max_f32_e32 v101, 0, v101
	v_max_f32_e32 v96, 0, v96
	v_max_f32_e32 v97, 0, v97
	v_max_f32_e32 v99, 0, v99
	v_pk_mul_f32 v[100:101], v[100:101], v[100:101]
	v_pk_mul_f32 v[102:103], v[96:97], v[96:97]
	v_pk_mul_f32 v[106:107], v[98:99], v[98:99]
	v_max_f32_e32 v88, v88, v88
	v_max_f32_e32 v89, v89, v89
	v_cvt_pk_bf16_f32 v96, v100, v101
	v_cvt_pk_bf16_f32 v97, v102, v103
	v_cvt_pk_bf16_f32 v98, v104, v105
	v_cvt_pk_bf16_f32 v99, v106, v107
	v_max_f32_e32 v88, 0, v88
	v_max_f32_e32 v89, 0, v89
	global_store_dwordx4 v[112:113], v[96:99], off offset:256 sc1
	v_max_f32_e32 v92, v92, v92
	v_max_f32_e32 v93, v93, v93
	v_or_b32_e32 v96, 32, v154
	v_pk_mul_f32 v[98:99], v[88:89], v[88:89]
	v_max_f32_e32 v89, v90, v90
	v_ashrrev_i32_e32 v97, 31, v96
	v_max_f32_e32 v88, v94, v94
	v_max_f32_e32 v90, 0, v89
	v_max_f32_e32 v89, v95, v95
	v_max_f32_e32 v91, v91, v91
	v_lshlrev_b64 v[96:97], 13, v[96:97]
	v_max_f32_e32 v92, 0, v92
	v_max_f32_e32 v93, 0, v93
	v_max_f32_e32 v88, 0, v88
	v_max_f32_e32 v89, 0, v89
	v_max_f32_e32 v91, 0, v91
	v_lshl_add_u64 v[96:97], s[38:39], 0, v[96:97]
	v_pk_mul_f32 v[92:93], v[92:93], v[92:93]
	v_pk_mul_f32 v[94:95], v[88:89], v[88:89]
	v_pk_mul_f32 v[100:101], v[90:91], v[90:91]
	v_max_f32_e32 v80, v80, v80
	v_max_f32_e32 v81, v81, v81
	v_lshl_add_u64 v[96:97], v[96:97], 0, v[158:159]
	v_cvt_pk_bf16_f32 v88, v92, v93
	v_cvt_pk_bf16_f32 v89, v94, v95
	v_cvt_pk_bf16_f32 v90, v98, v99
	v_cvt_pk_bf16_f32 v91, v100, v101
	v_max_f32_e32 v80, 0, v80
	v_max_f32_e32 v81, 0, v81
	global_store_dwordx4 v[96:97], v[88:91], off sc1
	v_max_f32_e32 v84, v84, v84
	v_max_f32_e32 v85, v85, v85
	v_pk_mul_f32 v[88:89], v[80:81], v[80:81]
	v_max_f32_e32 v81, v82, v82
	v_max_f32_e32 v80, v86, v86
	v_max_f32_e32 v82, 0, v81
	v_max_f32_e32 v81, v87, v87
	v_max_f32_e32 v83, v83, v83
	v_max_f32_e32 v84, 0, v84
	v_max_f32_e32 v85, 0, v85
	v_max_f32_e32 v80, 0, v80
	v_max_f32_e32 v81, 0, v81
	v_max_f32_e32 v83, 0, v83
	v_pk_mul_f32 v[84:85], v[84:85], v[84:85]
	v_pk_mul_f32 v[86:87], v[80:81], v[80:81]
	v_pk_mul_f32 v[90:91], v[82:83], v[82:83]
	v_max_f32_e32 v72, v72, v72
	v_max_f32_e32 v73, v73, v73
	v_cvt_pk_bf16_f32 v80, v84, v85
	v_cvt_pk_bf16_f32 v81, v86, v87
	v_cvt_pk_bf16_f32 v82, v88, v89
	v_cvt_pk_bf16_f32 v83, v90, v91
	v_max_f32_e32 v72, 0, v72
	v_max_f32_e32 v73, 0, v73
	global_store_dwordx4 v[96:97], v[80:83], off offset:256 sc1
	v_max_f32_e32 v76, v76, v76
	v_max_f32_e32 v77, v77, v77
	v_or_b32_e32 v80, 48, v154
	v_pk_mul_f32 v[82:83], v[72:73], v[72:73]
	v_max_f32_e32 v73, v74, v74
	v_ashrrev_i32_e32 v81, 31, v80
	v_max_f32_e32 v72, v78, v78
	v_max_f32_e32 v74, 0, v73
	v_max_f32_e32 v73, v79, v79
	v_max_f32_e32 v75, v75, v75
	v_lshlrev_b64 v[80:81], 13, v[80:81]
	v_max_f32_e32 v76, 0, v76
	v_max_f32_e32 v77, 0, v77
	v_max_f32_e32 v72, 0, v72
	v_max_f32_e32 v73, 0, v73
	v_max_f32_e32 v75, 0, v75
	v_lshl_add_u64 v[80:81], s[38:39], 0, v[80:81]
	v_pk_mul_f32 v[76:77], v[76:77], v[76:77]
	v_pk_mul_f32 v[78:79], v[72:73], v[72:73]
	v_pk_mul_f32 v[84:85], v[74:75], v[74:75]
	v_max_f32_e32 v64, v64, v64
	v_max_f32_e32 v65, v65, v65
	v_lshl_add_u64 v[80:81], v[80:81], 0, v[158:159]
	v_cvt_pk_bf16_f32 v72, v76, v77
	v_cvt_pk_bf16_f32 v73, v78, v79
	v_cvt_pk_bf16_f32 v74, v82, v83
	v_cvt_pk_bf16_f32 v75, v84, v85
	v_max_f32_e32 v64, 0, v64
	v_max_f32_e32 v65, 0, v65
	global_store_dwordx4 v[80:81], v[72:75], off sc1
	v_max_f32_e32 v68, v68, v68
	v_max_f32_e32 v69, v69, v69
	v_pk_mul_f32 v[72:73], v[64:65], v[64:65]
	v_max_f32_e32 v65, v66, v66
	v_max_f32_e32 v64, v70, v70
	v_max_f32_e32 v66, 0, v65
	v_max_f32_e32 v65, v71, v71
	v_max_f32_e32 v67, v67, v67
	v_max_f32_e32 v68, 0, v68
	v_max_f32_e32 v69, 0, v69
	v_max_f32_e32 v64, 0, v64
	v_max_f32_e32 v65, 0, v65
	v_max_f32_e32 v67, 0, v67
	v_pk_mul_f32 v[68:69], v[68:69], v[68:69]
	v_pk_mul_f32 v[70:71], v[64:65], v[64:65]
	v_pk_mul_f32 v[74:75], v[66:67], v[66:67]
	v_max_f32_e32 v56, v56, v56
	v_max_f32_e32 v57, v57, v57
	v_cvt_pk_bf16_f32 v64, v68, v69
	v_cvt_pk_bf16_f32 v65, v70, v71
	v_cvt_pk_bf16_f32 v66, v72, v73
	v_cvt_pk_bf16_f32 v67, v74, v75
	v_max_f32_e32 v56, 0, v56
	v_max_f32_e32 v57, 0, v57
	global_store_dwordx4 v[80:81], v[64:67], off offset:256 sc1
	v_max_f32_e32 v60, v60, v60
	v_max_f32_e32 v61, v61, v61
	v_pk_mul_f32 v[66:67], v[56:57], v[56:57]
	v_max_f32_e32 v57, v58, v58
	v_max_f32_e32 v60, 0, v60
	v_max_f32_e32 v61, 0, v61
	v_max_f32_e32 v56, v62, v62
	v_max_f32_e32 v58, 0, v57
	v_max_f32_e32 v57, v63, v63
	v_max_f32_e32 v59, v59, v59
	v_pk_mul_f32 v[60:61], v[60:61], v[60:61]
	v_max_f32_e32 v56, 0, v56
	v_max_f32_e32 v57, 0, v57
	v_max_f32_e32 v59, 0, v59
	v_pk_mul_f32 v[62:63], v[56:57], v[56:57]
	v_pk_mul_f32 v[68:69], v[58:59], v[58:59]
	v_cvt_pk_bf16_f32 v56, v60, v61
	v_add_co_u32_e32 v60, vcc, s42, v144
	v_max_f32_e32 v48, v48, v48
	v_max_f32_e32 v49, v49, v49
	v_cvt_pk_bf16_f32 v57, v62, v63
	v_cvt_pk_bf16_f32 v58, v66, v67
	v_cvt_pk_bf16_f32 v59, v68, v69
	v_addc_co_u32_e32 v61, vcc, 0, v145, vcc
	v_max_f32_e32 v48, 0, v48
	v_max_f32_e32 v49, 0, v49
	global_store_dwordx4 v[60:61], v[56:59], off sc1
	v_max_f32_e32 v52, v52, v52
	v_max_f32_e32 v53, v53, v53
	v_pk_mul_f32 v[56:57], v[48:49], v[48:49]
	v_max_f32_e32 v49, v50, v50
	v_max_f32_e32 v48, v54, v54
	v_max_f32_e32 v50, 0, v49
	v_max_f32_e32 v49, v55, v55
	v_max_f32_e32 v51, v51, v51
	v_max_f32_e32 v52, 0, v52
	v_max_f32_e32 v53, 0, v53
	v_max_f32_e32 v48, 0, v48
	v_max_f32_e32 v49, 0, v49
	v_max_f32_e32 v51, 0, v51
	v_pk_mul_f32 v[52:53], v[52:53], v[52:53]
	v_pk_mul_f32 v[54:55], v[48:49], v[48:49]
	v_pk_mul_f32 v[58:59], v[50:51], v[50:51]
	v_max_f32_e32 v40, v40, v40
	v_max_f32_e32 v41, v41, v41
	v_lshl_add_u64 v[64:65], v[144:145], 0, s[14:15]
	v_cvt_pk_bf16_f32 v48, v52, v53
	v_cvt_pk_bf16_f32 v49, v54, v55
	v_cvt_pk_bf16_f32 v50, v56, v57
	v_cvt_pk_bf16_f32 v51, v58, v59
	v_max_f32_e32 v40, 0, v40
	v_max_f32_e32 v41, 0, v41
	global_store_dwordx4 v[64:65], v[48:51], off offset:256 sc1
	v_max_f32_e32 v44, v44, v44
	v_max_f32_e32 v45, v45, v45
	v_pk_mul_f32 v[50:51], v[40:41], v[40:41]
	v_max_f32_e32 v41, v42, v42
	v_max_f32_e32 v44, 0, v44
	v_max_f32_e32 v45, 0, v45
	v_max_f32_e32 v40, v46, v46
	v_max_f32_e32 v42, 0, v41
	v_max_f32_e32 v41, v47, v47
	v_max_f32_e32 v43, v43, v43
	v_pk_mul_f32 v[44:45], v[44:45], v[44:45]
	v_max_f32_e32 v40, 0, v40
	v_max_f32_e32 v41, 0, v41
	v_max_f32_e32 v43, 0, v43
	v_pk_mul_f32 v[46:47], v[40:41], v[40:41]
	v_pk_mul_f32 v[52:53], v[42:43], v[42:43]
	v_cvt_pk_bf16_f32 v40, v44, v45
	v_add_co_u32_e32 v44, vcc, s43, v144
	v_max_f32_e32 v32, v32, v32
	v_max_f32_e32 v33, v33, v33
	v_cvt_pk_bf16_f32 v41, v46, v47
	v_cvt_pk_bf16_f32 v42, v50, v51
	v_cvt_pk_bf16_f32 v43, v52, v53
	v_addc_co_u32_e32 v45, vcc, 0, v145, vcc
	v_max_f32_e32 v32, 0, v32
	v_max_f32_e32 v33, 0, v33
	global_store_dwordx4 v[44:45], v[40:43], off sc1
	v_max_f32_e32 v36, v36, v36
	v_max_f32_e32 v37, v37, v37
	v_pk_mul_f32 v[40:41], v[32:33], v[32:33]
	v_max_f32_e32 v33, v34, v34
	v_max_f32_e32 v32, v38, v38
	v_max_f32_e32 v34, 0, v33
	v_max_f32_e32 v33, v39, v39
	v_max_f32_e32 v35, v35, v35
	v_max_f32_e32 v36, 0, v36
	v_max_f32_e32 v37, 0, v37
	v_max_f32_e32 v32, 0, v32
	v_max_f32_e32 v33, 0, v33
	v_max_f32_e32 v35, 0, v35
	v_pk_mul_f32 v[36:37], v[36:37], v[36:37]
	v_pk_mul_f32 v[38:39], v[32:33], v[32:33]
	v_pk_mul_f32 v[42:43], v[34:35], v[34:35]
	v_max_f32_e32 v24, v24, v24
	v_max_f32_e32 v25, v25, v25
	v_lshl_add_u64 v[48:49], v[144:145], 0, s[16:17]
	v_cvt_pk_bf16_f32 v32, v36, v37
	v_cvt_pk_bf16_f32 v33, v38, v39
	v_cvt_pk_bf16_f32 v34, v40, v41
	v_cvt_pk_bf16_f32 v35, v42, v43
	v_max_f32_e32 v24, 0, v24
	v_max_f32_e32 v25, 0, v25
	global_store_dwordx4 v[48:49], v[32:35], off offset:256 sc1
	v_max_f32_e32 v28, v28, v28
	v_max_f32_e32 v29, v29, v29
	v_pk_mul_f32 v[34:35], v[24:25], v[24:25]
	v_max_f32_e32 v25, v26, v26
	v_max_f32_e32 v28, 0, v28
	v_max_f32_e32 v29, 0, v29
	v_max_f32_e32 v24, v30, v30
	v_max_f32_e32 v26, 0, v25
	v_max_f32_e32 v25, v31, v31
	v_max_f32_e32 v27, v27, v27
	v_pk_mul_f32 v[28:29], v[28:29], v[28:29]
	v_max_f32_e32 v24, 0, v24
	v_max_f32_e32 v25, 0, v25
	v_max_f32_e32 v27, 0, v27
	v_pk_mul_f32 v[30:31], v[24:25], v[24:25]
	v_pk_mul_f32 v[36:37], v[26:27], v[26:27]
	v_cvt_pk_bf16_f32 v24, v28, v29
	v_add_co_u32_e32 v28, vcc, s44, v144
	v_max_f32_e32 v16, v16, v16
	v_max_f32_e32 v17, v17, v17
	v_cvt_pk_bf16_f32 v25, v30, v31
	v_cvt_pk_bf16_f32 v26, v34, v35
	v_cvt_pk_bf16_f32 v27, v36, v37
	v_addc_co_u32_e32 v29, vcc, 0, v145, vcc
	v_max_f32_e32 v16, 0, v16
	v_max_f32_e32 v17, 0, v17
	global_store_dwordx4 v[28:29], v[24:27], off sc1
	v_max_f32_e32 v20, v20, v20
	v_max_f32_e32 v21, v21, v21
	v_pk_mul_f32 v[24:25], v[16:17], v[16:17]
	v_max_f32_e32 v17, v18, v18
	v_max_f32_e32 v16, v22, v22
	v_max_f32_e32 v18, 0, v17
	v_max_f32_e32 v17, v23, v23
	v_max_f32_e32 v19, v19, v19
	v_max_f32_e32 v20, 0, v20
	v_max_f32_e32 v21, 0, v21
	v_max_f32_e32 v16, 0, v16
	v_max_f32_e32 v17, 0, v17
	v_max_f32_e32 v19, 0, v19
	v_pk_mul_f32 v[20:21], v[20:21], v[20:21]
	v_pk_mul_f32 v[22:23], v[16:17], v[16:17]
	v_pk_mul_f32 v[26:27], v[18:19], v[18:19]
	v_max_f32_e32 v8, v8, v8
	v_max_f32_e32 v9, v9, v9
	v_lshl_add_u64 v[32:33], v[144:145], 0, s[18:19]
	v_cvt_pk_bf16_f32 v16, v20, v21
	v_cvt_pk_bf16_f32 v17, v22, v23
	v_cvt_pk_bf16_f32 v18, v24, v25
	v_cvt_pk_bf16_f32 v19, v26, v27
	v_max_f32_e32 v8, 0, v8
	v_max_f32_e32 v9, 0, v9
	global_store_dwordx4 v[32:33], v[16:19], off offset:256 sc1
	v_max_f32_e32 v12, v12, v12
	v_max_f32_e32 v13, v13, v13
	v_pk_mul_f32 v[18:19], v[8:9], v[8:9]
	v_max_f32_e32 v9, v10, v10
	v_max_f32_e32 v12, 0, v12
	v_max_f32_e32 v13, 0, v13
	v_max_f32_e32 v8, v14, v14
	v_max_f32_e32 v10, 0, v9
	v_max_f32_e32 v9, v15, v15
	v_max_f32_e32 v11, v11, v11
	v_pk_mul_f32 v[12:13], v[12:13], v[12:13]
	v_max_f32_e32 v8, 0, v8
	v_max_f32_e32 v9, 0, v9
	v_max_f32_e32 v11, 0, v11
	v_pk_mul_f32 v[14:15], v[8:9], v[8:9]
	v_pk_mul_f32 v[20:21], v[10:11], v[10:11]
	v_cvt_pk_bf16_f32 v8, v12, v13
	v_add_co_u32_e32 v12, vcc, s45, v144
	v_max_f32_e32 v0, v0, v0
	v_max_f32_e32 v1, v1, v1
	v_cvt_pk_bf16_f32 v9, v14, v15
	v_cvt_pk_bf16_f32 v10, v18, v19
	v_cvt_pk_bf16_f32 v11, v20, v21
	v_addc_co_u32_e32 v13, vcc, 0, v145, vcc
	v_max_f32_e32 v0, 0, v0
	v_max_f32_e32 v1, 0, v1
	global_store_dwordx4 v[12:13], v[8:11], off sc1
	v_max_f32_e32 v4, v4, v4
	v_max_f32_e32 v5, v5, v5
	v_pk_mul_f32 v[8:9], v[0:1], v[0:1]
	v_max_f32_e32 v1, v2, v2
	v_max_f32_e32 v0, v6, v6
	v_max_f32_e32 v2, 0, v1
	v_max_f32_e32 v1, v7, v7
	v_max_f32_e32 v3, v3, v3
	v_max_f32_e32 v4, 0, v4
	v_max_f32_e32 v5, 0, v5
	v_max_f32_e32 v0, 0, v0
	v_max_f32_e32 v1, 0, v1
	v_max_f32_e32 v3, 0, v3
	v_pk_mul_f32 v[4:5], v[4:5], v[4:5]
	v_pk_mul_f32 v[6:7], v[0:1], v[0:1]
	v_pk_mul_f32 v[10:11], v[2:3], v[2:3]
	v_lshl_add_u64 v[16:17], v[144:145], 0, s[20:21]
	v_cvt_pk_bf16_f32 v0, v4, v5
	v_cvt_pk_bf16_f32 v1, v6, v7
	v_cvt_pk_bf16_f32 v2, v8, v9
	v_cvt_pk_bf16_f32 v3, v10, v11
	s_andn2_b64 vcc, exec, s[6:7]
	s_mov_b64 s[6:7], -1
	global_store_dwordx4 v[16:17], v[0:3], off offset:256 sc1
	s_cbranch_vccnz .LBB0_4372
	s_andn2_b64 vcc, exec, s[8:9]
	s_cbranch_vccnz .LBB0_4371
	s_barrier
	s_branch .LBB0_4371

.LBB0_4459:
	v_lshl_or_b32 v140, s21, 8, v150
	v_ashrrev_i32_e32 v141, 31, v140
	v_lshl_add_u32 v144, s20, 8, v148
	v_lshlrev_b64 v[140:141], 2, v[140:141]
	v_ashrrev_i32_e32 v145, 31, v144
	v_lshl_add_u64 v[142:143], s[36:37], 0, v[140:141]
	v_lshlrev_b64 v[146:147], 12, v[144:145]
	v_lshl_add_u64 v[166:167], v[142:143], 0, v[146:147]
	global_load_dwordx4 v[156:159], v[166:167], off
	global_load_dwordx4 v[162:165], v[166:167], off offset:64
	global_load_dwordx4 v[170:173], v[166:167], off offset:512
	global_load_dwordx4 v[174:177], v[166:167], off offset:576
	v_or_b32_e32 v166, 16, v144
	v_ashrrev_i32_e32 v167, 31, v166
	v_lshlrev_b64 v[166:167], 12, v[166:167]
	v_or_b32_e32 v194, 32, v144
	v_lshl_add_u64 v[190:191], v[142:143], 0, v[166:167]
	v_ashrrev_i32_e32 v195, 31, v194
	v_or_b32_e32 v212, 48, v144
	global_load_dwordx4 v[178:181], v[190:191], off
	global_load_dwordx4 v[182:185], v[190:191], off offset:64
	global_load_dwordx4 v[186:189], v[190:191], off offset:512
	s_nop 0
	global_load_dwordx4 v[190:193], v[190:191], off offset:576
	v_lshlrev_b64 v[228:229], 12, v[194:195]
	v_ashrrev_i32_e32 v213, 31, v212
	v_lshl_add_u64 v[206:207], v[142:143], 0, v[228:229]
	v_lshlrev_b64 v[230:231], 12, v[212:213]
	global_load_dwordx4 v[194:197], v[206:207], off
	global_load_dwordx4 v[198:201], v[206:207], off offset:64
	global_load_dwordx4 v[202:205], v[206:207], off offset:512
	s_nop 0
	global_load_dwordx4 v[206:209], v[206:207], off offset:576
	v_lshl_add_u64 v[224:225], v[142:143], 0, v[230:231]
	global_load_dwordx4 v[212:215], v[224:225], off
	global_load_dwordx4 v[216:219], v[224:225], off offset:64
	global_load_dwordx4 v[220:223], v[224:225], off offset:512
	s_nop 0
	global_load_dwordx4 v[224:227], v[224:225], off offset:576
	v_lshl_add_u64 v[146:147], s[36:37], 0, v[146:147]
	v_lshl_add_u64 v[146:147], v[146:147], 0, v[140:141]
	s_mov_b64 s[20:21], -1
	s_andn2_b64 vcc, exec, s[4:5]
	s_waitcnt vmcnt(0)
	v_pk_add_f32 v[126:127], v[126:127], v[158:159]
	v_pk_add_f32 v[124:125], v[124:125], v[156:157]
	v_pk_add_f32 v[110:111], v[110:111], v[172:173]
	v_pk_add_f32 v[108:109], v[108:109], v[170:171]
	global_store_dwordx4 v[146:147], v[108:111], off offset:512 sc1
	v_pk_add_f32 v[102:103], v[102:103], v[176:177]
	v_pk_add_f32 v[100:101], v[100:101], v[174:175]
	v_lshl_add_u64 v[108:109], s[36:37], 0, v[166:167]
	v_lshl_add_u64 v[108:109], v[108:109], 0, v[140:141]
	v_pk_add_f32 v[122:123], v[122:123], v[164:165]
	v_pk_add_f32 v[94:95], v[94:95], v[188:189]
	v_pk_add_f32 v[92:93], v[92:93], v[186:187]
	global_store_dwordx4 v[108:109], v[92:95], off offset:512 sc1
	v_pk_add_f32 v[86:87], v[86:87], v[192:193]
	v_pk_add_f32 v[84:85], v[84:85], v[190:191]
	v_lshl_add_u64 v[92:93], s[36:37], 0, v[228:229]
	v_lshl_add_u64 v[92:93], v[92:93], 0, v[140:141]
	v_pk_add_f32 v[78:79], v[78:79], v[204:205]
	v_pk_add_f32 v[76:77], v[76:77], v[202:203]
	global_store_dwordx4 v[92:93], v[76:79], off offset:512 sc1
	v_pk_add_f32 v[66:67], v[66:67], v[226:227]
	v_pk_add_f32 v[64:65], v[64:65], v[224:225]
	v_lshl_add_u64 v[76:77], s[36:37], 0, v[230:231]
	v_lshl_add_u64 v[76:77], v[76:77], 0, v[140:141]
	v_pk_add_f32 v[74:75], v[74:75], v[208:209]
	v_pk_add_f32 v[72:73], v[72:73], v[206:207]
	global_store_dwordx4 v[76:77], v[64:67], off offset:576 sc1
	v_pk_add_f32 v[120:121], v[120:121], v[162:163]
	global_store_dwordx4 v[146:147], v[100:103], off offset:576 sc1
	v_add_u32_e32 v64, 0x80, v144
	global_store_dwordx4 v[108:109], v[84:87], off offset:576 sc1
	v_pk_add_f32 v[102:103], v[118:119], v[180:181]
	v_pk_add_f32 v[100:101], v[116:117], v[178:179]
	v_pk_add_f32 v[86:87], v[106:107], v[196:197]
	v_pk_add_f32 v[84:85], v[104:105], v[194:195]
	global_store_dwordx4 v[92:93], v[72:75], off offset:576 sc1
	v_ashrrev_i32_e32 v65, 31, v64
	global_store_dwordx4 v[146:147], v[124:127], off sc1
	v_pk_add_f32 v[74:75], v[90:91], v[214:215]
	v_pk_add_f32 v[72:73], v[88:89], v[212:213]
	global_store_dwordx4 v[146:147], v[120:123], off offset:64 sc1
	global_store_dwordx4 v[108:109], v[100:103], off sc1
	global_store_dwordx4 v[92:93], v[84:87], off sc1
	global_store_dwordx4 v[76:77], v[72:75], off sc1
	v_pk_add_f32 v[102:103], v[114:115], v[184:185]
	v_pk_add_f32 v[100:101], v[112:113], v[182:183]
	v_pk_add_f32 v[86:87], v[98:99], v[200:201]
	v_pk_add_f32 v[84:85], v[96:97], v[198:199]
	v_pk_add_f32 v[74:75], v[82:83], v[218:219]
	v_pk_add_f32 v[72:73], v[80:81], v[216:217]
	v_pk_add_f32 v[70:71], v[70:71], v[222:223]
	v_pk_add_f32 v[68:69], v[68:69], v[220:221]
	v_lshlrev_b64 v[146:147], 12, v[64:65]
	global_store_dwordx4 v[108:109], v[100:103], off offset:64 sc1
	global_store_dwordx4 v[92:93], v[84:87], off offset:64 sc1
	global_store_dwordx4 v[76:77], v[72:75], off offset:64 sc1
	global_store_dwordx4 v[76:77], v[68:71], off offset:512 sc1
	v_lshl_add_u64 v[64:65], v[142:143], 0, v[146:147]
	global_load_dwordx4 v[108:111], v[64:65], off
	global_load_dwordx4 v[104:107], v[64:65], off offset:64
	global_load_dwordx4 v[96:99], v[64:65], off offset:512
	global_load_dwordx4 v[84:87], v[64:65], off offset:576
	v_add_u32_e32 v64, 0x90, v144
	v_ashrrev_i32_e32 v65, 31, v64
	v_lshlrev_b64 v[126:127], 12, v[64:65]
	v_lshl_add_u64 v[64:65], v[142:143], 0, v[126:127]
	global_load_dwordx4 v[100:103], v[64:65], off
	global_load_dwordx4 v[88:91], v[64:65], off offset:64
	global_load_dwordx4 v[80:83], v[64:65], off offset:512
	global_load_dwordx4 v[72:75], v[64:65], off offset:576
	v_add_u32_e32 v64, 0xa0, v144
	v_ashrrev_i32_e32 v65, 31, v64
	v_lshlrev_b64 v[124:125], 12, v[64:65]
	v_add_u32_e32 v112, 0xb0, v144
	v_lshl_add_u64 v[64:65], v[142:143], 0, v[124:125]
	v_ashrrev_i32_e32 v113, 31, v112
	global_load_dwordx4 v[92:95], v[64:65], off
	global_load_dwordx4 v[76:79], v[64:65], off offset:64
	global_load_dwordx4 v[68:71], v[64:65], off offset:512
	s_nop 0
	global_load_dwordx4 v[64:67], v[64:65], off offset:576
	v_lshlrev_b64 v[144:145], 12, v[112:113]
	v_lshl_add_u64 v[116:117], v[142:143], 0, v[144:145]
	global_load_dwordx4 v[112:115], v[116:117], off
	global_load_dwordx4 v[156:159], v[116:117], off offset:64
	global_load_dwordx4 v[120:123], v[116:117], off offset:512
	s_nop 0
	global_load_dwordx4 v[116:119], v[116:117], off offset:576
	s_waitcnt vmcnt(15)
	v_pk_add_f32 v[60:61], v[60:61], v[108:109]
	v_lshl_add_u64 v[108:109], s[36:37], 0, v[146:147]
	v_lshl_add_u64 v[108:109], v[108:109], 0, v[140:141]
	s_waitcnt vmcnt(13)
	v_pk_add_f32 v[50:51], v[50:51], v[98:99]
	v_pk_add_f32 v[48:49], v[48:49], v[96:97]
	global_store_dwordx4 v[108:109], v[48:51], off offset:512 sc1
	s_waitcnt vmcnt(13)
	v_pk_add_f32 v[42:43], v[42:43], v[86:87]
	s_waitcnt vmcnt(10)
	v_pk_add_f32 v[34:35], v[34:35], v[82:83]
	v_lshl_add_u64 v[48:49], s[36:37], 0, v[126:127]
	v_lshl_add_u64 v[48:49], v[48:49], 0, v[140:141]
	v_pk_add_f32 v[32:33], v[32:33], v[80:81]
	global_store_dwordx4 v[48:49], v[32:35], off offset:512 sc1
	v_pk_add_f32 v[40:41], v[40:41], v[84:85]
	s_waitcnt vmcnt(10)
	v_pk_add_f32 v[26:27], v[26:27], v[74:75]
	v_lshl_add_u64 v[32:33], s[36:37], 0, v[124:125]
	v_lshl_add_u64 v[32:33], v[32:33], 0, v[140:141]
	s_waitcnt vmcnt(7)
	v_pk_add_f32 v[18:19], v[18:19], v[70:71]
	v_pk_add_f32 v[16:17], v[16:17], v[68:69]
	v_pk_add_f32 v[24:25], v[24:25], v[72:73]
	global_store_dwordx4 v[32:33], v[16:19], off offset:512 sc1
	s_waitcnt vmcnt(7)
	v_pk_add_f32 v[10:11], v[10:11], v[66:67]
	v_pk_add_f32 v[8:9], v[8:9], v[64:65]
	v_lshl_add_u64 v[16:17], s[36:37], 0, v[144:145]
	global_store_dwordx4 v[108:109], v[40:43], off offset:576 sc1
	global_store_dwordx4 v[48:49], v[24:27], off offset:576 sc1
	global_store_dwordx4 v[32:33], v[8:11], off offset:576 sc1
	v_pk_add_f32 v[42:43], v[54:55], v[102:103]
	v_pk_add_f32 v[40:41], v[52:53], v[100:101]
	v_pk_add_f32 v[26:27], v[38:39], v[94:95]
	v_pk_add_f32 v[24:25], v[36:37], v[92:93]
	s_waitcnt vmcnt(9)
	v_pk_add_f32 v[10:11], v[22:23], v[114:115]
	v_pk_add_f32 v[8:9], v[20:21], v[112:113]
	v_lshl_add_u64 v[16:17], v[16:17], 0, v[140:141]
	v_pk_add_f32 v[62:63], v[62:63], v[110:111]
	v_pk_add_f32 v[58:59], v[58:59], v[106:107]
	v_pk_add_f32 v[56:57], v[56:57], v[104:105]
	global_store_dwordx4 v[48:49], v[40:43], off sc1
	global_store_dwordx4 v[32:33], v[24:27], off sc1
	global_store_dwordx4 v[16:17], v[8:11], off sc1
	v_pk_add_f32 v[42:43], v[46:47], v[90:91]
	v_pk_add_f32 v[40:41], v[44:45], v[88:89]
	v_pk_add_f32 v[26:27], v[30:31], v[78:79]
	v_pk_add_f32 v[24:25], v[28:29], v[76:77]
	s_waitcnt vmcnt(11)
	v_pk_add_f32 v[10:11], v[14:15], v[158:159]
	v_pk_add_f32 v[8:9], v[12:13], v[156:157]
	s_waitcnt vmcnt(10)
	v_pk_add_f32 v[6:7], v[6:7], v[122:123]
	v_pk_add_f32 v[4:5], v[4:5], v[120:121]
	s_waitcnt vmcnt(9)
	v_pk_add_f32 v[2:3], v[2:3], v[118:119]
	v_pk_add_f32 v[0:1], v[0:1], v[116:117]
	global_store_dwordx4 v[108:109], v[60:63], off sc1
	global_store_dwordx4 v[108:109], v[56:59], off offset:64 sc1
	global_store_dwordx4 v[48:49], v[40:43], off offset:64 sc1
	global_store_dwordx4 v[32:33], v[24:27], off offset:64 sc1
	global_store_dwordx4 v[16:17], v[8:11], off offset:64 sc1
	global_store_dwordx4 v[16:17], v[4:7], off offset:512 sc1
	global_store_dwordx4 v[16:17], v[0:3], off offset:576 sc1
	s_cbranch_vccnz .LBB0_4448
	s_andn2_b64 vcc, exec, s[6:7]
	s_cbranch_vccnz .LBB0_4447
	s_barrier
	s_branch .LBB0_4447

.LBB0_4517:
	v_mul_f32_e32 v57, v29, v29
	v_mul_f32_e32 v58, v31, v31
	v_fmac_f32_e32 v57, v28, v28
	v_fmac_f32_e32 v58, v30, v30
	v_add_f32_e32 v57, v57, v58
	v_mul_f32_e32 v58, v25, v25
	v_mul_f32_e32 v59, v27, v27
	v_fmac_f32_e32 v58, v24, v24
	v_fmac_f32_e32 v59, v26, v26
	v_add_f32_e32 v58, v58, v59
	v_add_f32_e32 v57, v57, v58
	v_mul_f32_e32 v58, v21, v21
	v_mul_f32_e32 v59, v23, v23
	v_fmac_f32_e32 v58, v20, v20
	v_fmac_f32_e32 v59, v22, v22
	v_add_f32_e32 v58, v58, v59
	v_add_f32_e32 v57, v58, v57
	v_mul_f32_e32 v58, v17, v17
	v_mul_f32_e32 v59, v19, v19
	v_fmac_f32_e32 v58, v16, v16
	v_fmac_f32_e32 v59, v18, v18
	v_add_f32_e32 v58, v58, v59
	v_add_f32_e32 v57, v58, v57
	ds_bpermute_b32 v58, v50, v57
	s_add_u32 s4, s4, s6
	s_addc_u32 s5, s5, s7
	s_waitcnt lgkmcnt(0)
	v_add_f32_e32 v57, v57, v58
	ds_bpermute_b32 v58, v51, v57
	s_waitcnt lgkmcnt(0)
	v_add_f32_e32 v57, v57, v58
	ds_bpermute_b32 v58, v52, v57
	s_waitcnt lgkmcnt(0)
	v_add_f32_e32 v57, v57, v58
	ds_bpermute_b32 v58, v53, v57
	s_waitcnt lgkmcnt(0)
	v_add_f32_e32 v57, v57, v58
	ds_bpermute_b32 v58, v54, v57
	s_waitcnt lgkmcnt(0)
	v_add_f32_e32 v57, v57, v58
	ds_bpermute_b32 v58, v55, v57
	s_waitcnt lgkmcnt(0)
	v_add_f32_e32 v57, v57, v58
	v_fmamk_f32 v57, v57, 0x3a800000, v56
	v_mul_f32_e32 v58, 0x4b800000, v57
	v_cmp_gt_f32_e32 vcc, s3, v57
	s_nop 1
	v_cndmask_b32_e32 v57, v57, v58, vcc
	v_rsq_f32_e32 v57, v57
	v_lshl_add_u64 v[58:59], s[0:1], 0, v[48:49]
	s_add_u32 s0, s0, s6
	s_addc_u32 s1, s1, s7
	v_mul_f32_e32 v60, 0x45800000, v57
	v_cndmask_b32_e32 v60, v57, v60, vcc
	v_pk_mul_f32 v[28:29], v[28:29], v[60:61] op_sel_hi:[1,0]
	v_pk_mul_f32 v[30:31], v[30:31], v[60:61] op_sel_hi:[1,0]
	v_pk_mul_f32 v[62:63], v[24:25], v[60:61] op_sel_hi:[1,0]
	v_pk_mul_f32 v[64:65], v[26:27], v[60:61] op_sel_hi:[1,0]
	v_pk_mul_f32 v[20:21], v[20:21], v[60:61] op_sel_hi:[1,0]
	v_pk_mul_f32 v[22:23], v[22:23], v[60:61] op_sel_hi:[1,0]
	v_pk_mul_f32 v[16:17], v[16:17], v[60:61] op_sel_hi:[1,0]
	v_pk_mul_f32 v[18:19], v[18:19], v[60:61] op_sel_hi:[1,0]
	v_pk_mul_f32 v[26:27], v[2:3], v[30:31]
	v_pk_mul_f32 v[24:25], v[0:1], v[28:29]
	v_pk_mul_f32 v[30:31], v[6:7], v[64:65]
	v_pk_mul_f32 v[28:29], v[4:5], v[62:63]
	v_pk_mul_f32 v[22:23], v[10:11], v[22:23]
	v_pk_mul_f32 v[20:21], v[8:9], v[20:21]
	v_pk_mul_f32 v[18:19], v[14:15], v[18:19]
	v_pk_mul_f32 v[16:17], v[12:13], v[16:17]
	global_store_dwordx4 v[58:59], v[24:27], off sc1
	global_store_dwordx4 v[58:59], v[28:31], off offset:1024 sc1
	global_store_dwordx4 v[58:59], v[20:23], off offset:2048 sc1
	global_store_dwordx4 v[58:59], v[16:19], off offset:3072 sc1
	s_andn2_b64 vcc, exec, s[8:9]
	s_waitcnt vmcnt(7)
	v_mov_b32_e32 v28, v32
	v_mov_b32_e32 v29, v33
	v_mov_b32_e32 v30, v34
	v_mov_b32_e32 v31, v35
	s_waitcnt vmcnt(6)
	v_mov_b32_e32 v24, v36
	v_mov_b32_e32 v25, v37
	v_mov_b32_e32 v26, v38
	v_mov_b32_e32 v27, v39
	s_waitcnt vmcnt(5)
	v_mov_b32_e32 v20, v40
	v_mov_b32_e32 v21, v41
	v_mov_b32_e32 v22, v42
	v_mov_b32_e32 v23, v43
	s_waitcnt vmcnt(4)
	v_mov_b32_e32 v16, v44
	v_mov_b32_e32 v17, v45
	v_mov_b32_e32 v18, v46
	v_mov_b32_e32 v19, v47
	s_cbranch_vccz .LBB0_4520
